# scan loops: removed conservative post-inline-asm s_nop pads and x+0*x ops, re-padded per wait-state table
# speedup vs baseline: 1.0175x; 1.0175x over previous
.LBB0_333:
	s_and_saveexec_b64 s[8:9], s[38:39]
	s_cbranch_execz .LBB0_335
	s_waitcnt vmcnt(9)
	v_add_f32_e32 v92, v0, v36
	v_min_f32_e32 v96, 0, v92
	v_mul_f32_e64 v92, |v92|, s62
	v_exp_f32_e32 v92, v92
	v_add_f32_e32 v93, v1, v37
	v_add_f32_e32 v94, v2, v38
	v_add_f32_e32 v95, v3, v39
	v_add_f32_e32 v92, 1.0, v92
	v_cmp_gt_f32_e32 vcc, s5, v92
	s_mov_b32 s4, 0xf800000
	s_waitcnt vmcnt(8)
	v_add_f32_e32 v88, v4, v32
	v_cndmask_b32_e64 v97, 0, 32, vcc
	v_ldexp_f32 v92, v92, v97
	v_log_f32_e32 v92, v92
	v_mul_f32_e32 v88, 0xbfb8aa3b, v88
	v_exp_f32_e32 v90, v88
	v_add_f32_e32 v88, v5, v33
	v_mul_f32_e32 v97, 0x3f317217, v92
	v_fma_f32 v97, v92, s76, -v97
	v_fmac_f32_e32 v97, 0x3377d1cf, v92
	v_fmac_f32_e32 v97, 0x3f317217, v92
	v_cmp_lt_f32_e64 s[42:43], |v92|, s77
	v_mul_f32_e32 v88, 0xbfb8aa3b, v88
	v_exp_f32_e32 v91, v88
	v_cndmask_b32_e64 v92, v92, v97, s[42:43]
	v_cndmask_b32_e32 v97, 0, v171, vcc
	v_sub_f32_e32 v92, v92, v97
	v_sub_f32_e32 v92, v96, v92
	v_min_f32_e32 v96, 0, v93
	v_mul_f32_e64 v93, |v93|, s62
	v_exp_f32_e32 v93, v93
	v_add_f32_e32 v92, -0.5, v92
	v_mul_f32_e32 v92, 0x3fb8aa3b, v92
	v_exp_f32_e32 v92, v92
	v_add_f32_e32 v93, 1.0, v93
	v_cmp_gt_f32_e32 vcc, s5, v93
	v_pk_add_f32 v[90:91], v[90:91], 1.0 op_sel_hi:[1,0]
	v_mul_f32_e32 v92, 0xbfb8aa3b, v92
	v_cndmask_b32_e64 v97, 0, 32, vcc
	v_ldexp_f32 v93, v93, v97
	v_log_f32_e32 v93, v93
	v_exp_f32_e32 v92, v92
	v_add_f32_e32 v88, v6, v34
	v_add_f32_e32 v89, v7, v35
	v_mul_f32_e32 v97, 0x3f317217, v93
	v_fma_f32 v97, v93, s76, -v97
	v_fmac_f32_e32 v97, 0x3377d1cf, v93
	v_fmac_f32_e32 v97, 0x3f317217, v93
	v_cmp_lt_f32_e64 s[42:43], |v93|, s77
	v_mul_f32_e32 v88, 0xbfb8aa3b, v88
	v_mul_f32_e32 v89, 0xbfb8aa3b, v89
	v_cndmask_b32_e64 v93, v93, v97, s[42:43]
	v_cndmask_b32_e32 v97, 0, v171, vcc
	v_sub_f32_e32 v93, v93, v97
	v_sub_f32_e32 v93, v96, v93
	v_min_f32_e32 v96, 0, v94
	v_mul_f32_e64 v94, |v94|, s62
	v_exp_f32_e32 v94, v94
	v_add_f32_e32 v93, -0.5, v93
	v_mul_f32_e32 v93, 0x3fb8aa3b, v93
	v_exp_f32_e32 v93, v93
	v_add_f32_e32 v94, 1.0, v94
	v_cmp_gt_f32_e32 vcc, s5, v94
	v_exp_f32_e32 v88, v88
	v_mul_f32_e32 v93, 0xbfb8aa3b, v93
	v_cndmask_b32_e64 v97, 0, 32, vcc
	v_ldexp_f32 v94, v94, v97
	v_log_f32_e32 v94, v94
	v_exp_f32_e32 v93, v93
	v_exp_f32_e32 v89, v89
	v_mul_f32_e32 v97, 0x3f317217, v94
	v_fma_f32 v97, v94, s76, -v97
	v_fmac_f32_e32 v97, 0x3377d1cf, v94
	v_fmac_f32_e32 v97, 0x3f317217, v94
	v_cmp_lt_f32_e64 s[42:43], |v94|, s77
	v_pk_add_f32 v[88:89], v[88:89], 1.0 op_sel_hi:[1,0]
	s_nop 0
	v_cndmask_b32_e64 v94, v94, v97, s[42:43]
	v_cndmask_b32_e32 v97, 0, v171, vcc
	v_sub_f32_e32 v94, v94, v97
	v_sub_f32_e32 v94, v96, v94
	v_min_f32_e32 v96, 0, v95
	v_mul_f32_e64 v95, |v95|, s62
	v_exp_f32_e32 v95, v95
	v_add_f32_e32 v94, -0.5, v94
	v_mul_f32_e32 v94, 0x3fb8aa3b, v94
	v_exp_f32_e32 v94, v94
	v_add_f32_e32 v95, 1.0, v95
	v_cmp_gt_f32_e32 vcc, s5, v95
	v_mul_f32_e32 v94, 0xbfb8aa3b, v94
	s_nop 0
	v_cndmask_b32_e64 v97, 0, 32, vcc
	v_ldexp_f32 v95, v95, v97
	v_log_f32_e32 v95, v95
	v_exp_f32_e32 v94, v94
	v_mul_f32_e32 v97, 0x3f317217, v95
	v_fma_f32 v97, v95, s76, -v97
	v_fmac_f32_e32 v97, 0x3377d1cf, v95
	v_fmac_f32_e32 v97, 0x3f317217, v95
	v_cmp_lt_f32_e64 s[42:43], |v95|, s77
	s_nop 1
	v_cndmask_b32_e64 v95, v95, v97, s[42:43]
	v_cndmask_b32_e32 v97, 0, v171, vcc
	v_sub_f32_e32 v95, v95, v97
	v_sub_f32_e32 v95, v96, v95
	v_add_f32_e32 v95, -0.5, v95
	v_mul_f32_e32 v95, 0x3fb8aa3b, v95
	v_exp_f32_e32 v95, v95
	v_pk_mul_f32 v[96:97], v[10:11], v[26:27]
	v_mul_f32_e32 v95, 0xbfb8aa3b, v95
	v_exp_f32_e32 v95, v95
	v_pk_mul_f32 v[98:99], v[96:97], v[96:97]
	ds_write_b128 v181, v[92:95]
	v_pk_mul_f32 v[92:93], v[8:9], v[24:25]
	v_pk_mul_f32 v[94:95], v[92:93], v[92:93]
	v_add_f32_e32 v94, v95, v94
	v_add_f32_e32 v94, v98, v94
	v_add_f32_e32 v94, v99, v94
	s_nop 1
	v_add_f32_dpp v94, v94, v94 row_ror:8 row_mask:0xf bank_mask:0xf bound_ctrl:1
	s_nop 1
	v_add_f32_dpp v94, v94, v94 row_ror:4 row_mask:0xf bank_mask:0xf bound_ctrl:1
	s_nop 1
	v_add_f32_dpp v94, v94, v94 row_ror:2 row_mask:0xf bank_mask:0xf bound_ctrl:1
	s_nop 1
	v_add_f32_dpp v94, v94, v94 row_ror:1 row_mask:0xf bank_mask:0xf bound_ctrl:1
	v_cmp_gt_f32_e32 vcc, s4, v94
	v_mul_f32_e32 v95, 0x4f800000, v94
	s_nop 0
	v_cndmask_b32_e32 v94, v94, v95, vcc
	v_sqrt_f32_e32 v95, v94
	s_nop 0
	v_add_u32_e32 v98, -1, v95
	v_fma_f32 v99, -v98, v95, v94
	v_cmp_ge_f32_e64 s[42:43], 0, v99
	v_add_u32_e32 v99, 1, v95
	s_nop 0
	v_cndmask_b32_e64 v98, v95, v98, s[42:43]
	v_fma_f32 v95, -v99, v95, v94
	v_cmp_lt_f32_e64 s[42:43], 0, v95
	s_nop 1
	v_cndmask_b32_e64 v95, v98, v99, s[42:43]
	v_mul_f32_e32 v98, 0x37800000, v95
	v_cndmask_b32_e32 v95, v95, v98, vcc
	v_cmp_class_f32_e32 vcc, v94, v160
	s_nop 1
	v_cndmask_b32_e32 v94, v95, v94, vcc
	v_max_f32_e32 v94, 0x2b8cbccc, v94
	v_div_scale_f32 v95, s[22:23], v94, v94, 1.0
	v_rcp_f32_e32 v98, v95
	s_nop 0
	v_fma_f32 v99, -v95, v98, 1.0
	v_fmac_f32_e32 v98, v99, v98
	v_div_scale_f32 v99, vcc, 1.0, v94, 1.0
	v_mul_f32_e32 v100, v99, v98
	v_fma_f32 v101, -v95, v100, v99
	v_fmac_f32_e32 v100, v101, v98
	v_fma_f32 v95, -v95, v100, v99
	v_div_fmas_f32 v95, v95, v98, v100
	v_div_fixup_f32 v94, v95, v94, 1.0
	v_pk_mul_f32 v[98:99], v[92:93], v[94:95] op_sel_hi:[1,0]
	v_pk_mul_f32 v[96:97], v[96:97], v[94:95] op_sel_hi:[1,0]
	v_xor_b32_e32 v93, 0x80000000, v99
	v_xor_b32_e32 v92, 0x80000000, v98
	v_xor_b32_e32 v95, 0x80000000, v97
	v_xor_b32_e32 v94, 0x80000000, v96
	ds_write_b128 v181, v[92:95] offset:4096
	v_div_scale_f32 v92, s[22:23], v91, v91, 1.0
	v_rcp_f32_e32 v93, v92
	s_nop 0
	v_fma_f32 v94, -v92, v93, 1.0
	v_fmac_f32_e32 v93, v94, v93
	v_div_scale_f32 v94, vcc, 1.0, v91, 1.0
	v_mul_f32_e32 v95, v94, v93
	v_fma_f32 v100, -v92, v95, v94
	v_fmac_f32_e32 v95, v100, v93
	v_fma_f32 v92, -v92, v95, v94
	v_div_fmas_f32 v92, v92, v93, v95
	v_div_fixup_f32 v95, v92, v91, 1.0
	v_div_scale_f32 v91, s[22:23], v90, v90, 1.0
	v_rcp_f32_e32 v92, v91
	s_nop 0
	v_fma_f32 v93, -v91, v92, 1.0
	v_fmac_f32_e32 v92, v93, v92
	v_div_scale_f32 v93, vcc, 1.0, v90, 1.0
	v_mul_f32_e32 v94, v93, v92
	v_fma_f32 v100, -v91, v94, v93
	v_fmac_f32_e32 v94, v100, v92
	v_fma_f32 v91, -v91, v94, v93
	v_div_fmas_f32 v91, v91, v92, v94
	v_div_scale_f32 v92, s[22:23], v89, v89, 1.0
	v_rcp_f32_e32 v93, v92
	v_div_fixup_f32 v94, v91, v90, 1.0
	v_pk_mul_f32 v[90:91], v[94:95], v[98:99]
	v_fma_f32 v98, -v92, v93, 1.0
	v_fmac_f32_e32 v93, v98, v93
	v_div_scale_f32 v98, vcc, 1.0, v89, 1.0
	v_mul_f32_e32 v99, v98, v93
	v_fma_f32 v100, -v92, v99, v98
	v_fmac_f32_e32 v99, v100, v93
	v_fma_f32 v92, -v92, v99, v98
	v_div_fmas_f32 v92, v92, v93, v99
	v_div_fixup_f32 v99, v92, v89, 1.0
	v_div_scale_f32 v89, s[22:23], v88, v88, 1.0
	v_rcp_f32_e32 v92, v89
	s_nop 0
	v_fma_f32 v93, -v89, v92, 1.0
	v_fmac_f32_e32 v92, v93, v92
	v_div_scale_f32 v93, vcc, 1.0, v88, 1.0
	v_mul_f32_e32 v98, v93, v92
	v_fma_f32 v100, -v89, v98, v93
	v_fmac_f32_e32 v98, v100, v92
	v_fma_f32 v89, -v89, v98, v93
	v_div_fmas_f32 v89, v89, v92, v98
	v_div_fixup_f32 v98, v89, v88, 1.0
	v_pk_mul_f32 v[92:93], v[98:99], v[96:97]
	ds_write_b128 v181, v[90:93] offset:8192
	v_pk_add_f32 v[88:89], v[94:95], -1.0 op_sel_hi:[1,0]
	v_pk_add_f32 v[90:91], v[98:99], -1.0 op_sel_hi:[1,0]
	v_pk_fma_f32 v[88:89], v[12:13], v[88:89], 1.0 op_sel_hi:[1,1,0]
	v_pk_fma_f32 v[90:91], v[14:15], v[90:91], 1.0 op_sel_hi:[1,1,0]
	v_pk_mul_f32 v[88:89], v[24:25], v[88:89]
	v_pk_mul_f32 v[90:91], v[26:27], v[90:91]
	ds_write_b128 v181, v[88:91] offset:12288
	ds_write_b128 v181, v[20:23] offset:16384

.LBB0_341:
	ds_read_b128 v[96:99], v134
	ds_read_b128 v[92:95], v134 offset:256
	ds_read_b128 v[100:103], v134 offset:4096
	ds_read_b128 v[116:119], v134 offset:4352
	ds_read_b128 v[108:111], v134 offset:8192
	ds_read_b128 v[104:107], v134 offset:8448
	ds_read_b128 v[120:123], v134 offset:12288
	ds_read_b128 v[112:115], v134 offset:12544
	ds_read_b128 v[190:193], v134 offset:16384
	ds_read_b128 v[88:91], v134 offset:16640
	s_waitcnt lgkmcnt(7)
	v_mul_f32 v124, v84, v100
	v_mul_f32 v100, v80, v100
	v_mul_f32 v125, v85, v101
	v_mul_f32 v101, v81, v101
	v_add_u32_e32 v189, 0x5000, v182
	v_fma_f32 v124, v86, v102, v124
	v_fma_f32 v100, v82, v102, v100
	v_fma_f32 v102, v87, v103, v125
	v_fma_f32 v101, v83, v103, v101
	ds_read2_b32 v[126:127], v189 offset0:32 offset1:48
	v_add_f32_e32 v102, v124, v102
	v_add_f32_e32 v103, v100, v101
	ds_read2_b32 v[100:101], v189 offset1:16
	v_add_f32_dpp v102, v102, v102 row_ror:8 row_mask:0xf bank_mask:0xf bound_ctrl:1
	v_add_f32_dpp v103, v103, v103 row_ror:8 row_mask:0xf bank_mask:0xf bound_ctrl:1
	s_waitcnt lgkmcnt(0)
	v_mul_f32 v124, v100, v120
	v_add_u32_e32 v185, 0xb000, v182
	v_add_f32_dpp v102, v102, v102 row_ror:4 row_mask:0xf bank_mask:0xf bound_ctrl:1
	v_add_f32_dpp v103, v103, v103 row_ror:4 row_mask:0xf bank_mask:0xf bound_ctrl:1
	s_nop 0
	v_add_f32_dpp v102, v102, v102 row_ror:2 row_mask:0xf bank_mask:0xf bound_ctrl:1
	v_add_f32_dpp v103, v103, v103 row_ror:2 row_mask:0xf bank_mask:0xf bound_ctrl:1
	s_nop 0
	v_add_f32_dpp v102, v102, v102 row_ror:1 row_mask:0xf bank_mask:0xf bound_ctrl:1
	v_fma_f32 v124, v102, v108, v124
	v_add_f32_dpp v103, v103, v103 row_ror:1 row_mask:0xf bank_mask:0xf bound_ctrl:1
	v_fma_f32 v141, v84, v96, v124
	v_mul_f32 v84, v101, v120
	v_fma_f32 v84, v103, v108, v84
	v_fma_f32 v148, v80, v96, v84
	v_mul_f32 v80, v100, v121
	v_fma_f32 v80, v102, v109, v80
	v_fma_f32 v150, v85, v97, v80
	v_mul_f32 v80, v101, v121
	v_fma_f32 v80, v103, v109, v80
	v_fma_f32 v151, v81, v97, v80
	v_mul_f32 v80, v100, v122
	v_mul_f32 v81, v148, v190
	v_fma_f32 v80, v102, v110, v80
	v_fma_f32 v149, v86, v98, v80
	v_mul_f32 v80, v101, v122
	v_fma_f32 v80, v103, v110, v80
	v_fma_f32 v86, v82, v98, v80
	v_mul_f32 v80, v100, v123
	v_mul_f32 v82, v150, v191
	v_fma_f32 v80, v102, v111, v80
	v_fma_f32 v81, v86, v192, v81
	v_fma_f32 v85, v87, v99, v80
	v_mul_f32 v80, v101, v123
	v_fma_f32 v80, v103, v111, v80
	v_fma_f32 v82, v85, v193, v82
	v_fma_f32 v84, v83, v99, v80
	v_mul_f32 v80, v141, v190
	v_mul_f32 v83, v151, v191
	v_fma_f32 v80, v149, v192, v80
	v_fma_f32 v83, v84, v193, v83
	v_add_f32_e32 v80, v80, v82
	v_add_f32_e32 v82, v81, v83
	v_mov_b32_e32 v81, 0
	v_add_f32_dpp v80, v80, v80 row_ror:8 row_mask:0xf bank_mask:0xf bound_ctrl:1
	v_add_f32_dpp v82, v82, v82 row_ror:8 row_mask:0xf bank_mask:0xf bound_ctrl:1
	v_mov_b32_e32 v83, 0
	v_add_f32_dpp v80, v80, v80 row_ror:4 row_mask:0xf bank_mask:0xf bound_ctrl:1
	v_add_f32_dpp v82, v82, v82 row_ror:4 row_mask:0xf bank_mask:0xf bound_ctrl:1
	s_nop 0
	v_add_f32_dpp v80, v80, v80 row_ror:2 row_mask:0xf bank_mask:0xf bound_ctrl:1
	v_add_f32_dpp v82, v82, v82 row_ror:2 row_mask:0xf bank_mask:0xf bound_ctrl:1
	s_nop 0
	v_mov_b32_dpp v81, v80 row_ror:1 row_mask:0xf bank_mask:0xf
	v_mov_b32_dpp v83, v82 row_ror:1 row_mask:0xf bank_mask:0xf
	s_and_saveexec_b64 s[8:9], s[40:41]
	v_add_f32_e32 v82, v82, v83
	v_add_f32_e32 v80, v80, v81
	ds_write2_b32 v185, v80, v82 offset1:16
	s_or_b64 exec, exec, s[8:9]
	v_mul_f32 v87, v141, v116
	v_mul_f32 v116, v148, v116
	v_mul_f32 v152, v150, v117
	v_mul_f32 v117, v151, v117
	ds_read_b128 v[96:99], v134 offset:512
	ds_read_b128 v[120:123], v134 offset:4608
	ds_read_b128 v[100:103], v134 offset:8704
	ds_read_b128 v[108:111], v134 offset:12800
	ds_read_b128 v[80:83], v134 offset:16896
	ds_read2_b32 v[124:125], v189 offset0:64 offset1:80
	v_fma_f32 v87, v149, v118, v87
	v_fma_f32 v116, v86, v118, v116
	v_fma_f32 v118, v85, v119, v152
	v_fma_f32 v117, v84, v119, v117
	v_add_f32_e32 v87, v87, v118
	v_add_f32_e32 v116, v116, v117
	v_mul_f32 v117, v126, v112
	v_mul_f32 v112, v127, v112
	v_add_f32_dpp v87, v87, v87 row_ror:8 row_mask:0xf bank_mask:0xf bound_ctrl:1
	v_add_f32_dpp v116, v116, v116 row_ror:8 row_mask:0xf bank_mask:0xf bound_ctrl:1
	s_nop 0
	v_add_f32_dpp v87, v87, v87 row_ror:4 row_mask:0xf bank_mask:0xf bound_ctrl:1
	v_add_f32_dpp v116, v116, v116 row_ror:4 row_mask:0xf bank_mask:0xf bound_ctrl:1
	s_nop 0
	v_add_f32_dpp v87, v87, v87 row_ror:2 row_mask:0xf bank_mask:0xf bound_ctrl:1
	v_add_f32_dpp v116, v116, v116 row_ror:2 row_mask:0xf bank_mask:0xf bound_ctrl:1
	s_nop 0
	v_add_f32_dpp v87, v87, v87 row_ror:1 row_mask:0xf bank_mask:0xf bound_ctrl:1
	v_add_f32_dpp v116, v116, v116 row_ror:1 row_mask:0xf bank_mask:0xf bound_ctrl:1
	v_fma_f32 v117, v87, v104, v117
	v_fma_f32 v104, v116, v104, v112
	v_fma_f32 v141, v141, v92, v117
	v_fma_f32 v92, v148, v92, v104
	v_mul_f32 v104, v126, v113
	v_fma_f32 v104, v87, v105, v104
	v_fma_f32 v148, v150, v93, v104
	v_mul_f32 v104, v127, v113
	v_fma_f32 v104, v116, v105, v104
	v_fma_f32 v93, v151, v93, v104
	v_mul_f32 v104, v126, v114
	v_fma_f32 v104, v87, v106, v104
	v_fma_f32 v149, v149, v94, v104
	v_mul_f32 v104, v127, v114
	v_fma_f32 v104, v116, v106, v104
	v_fma_f32 v94, v86, v94, v104
	v_mul_f32 v86, v126, v115
	v_fma_f32 v86, v87, v107, v86
	v_mul_f32 v87, v93, v89
	v_fma_f32 v150, v85, v95, v86
	v_mul_f32 v85, v127, v115
	v_mul_f32 v86, v148, v89
	v_fma_f32 v85, v116, v107, v85
	v_fma_f32 v86, v150, v91, v86
	v_fma_f32 v95, v84, v95, v85
	v_mul_f32 v84, v141, v88
	v_mul_f32 v85, v92, v88
	v_fma_f32 v84, v149, v90, v84
	v_fma_f32 v85, v94, v90, v85
	v_fma_f32 v87, v95, v91, v87
	v_add_f32_e32 v84, v84, v86
	v_add_f32_e32 v86, v85, v87
	v_mov_b32_e32 v85, 0
	v_add_f32_dpp v84, v84, v84 row_ror:8 row_mask:0xf bank_mask:0xf bound_ctrl:1
	v_add_f32_dpp v86, v86, v86 row_ror:8 row_mask:0xf bank_mask:0xf bound_ctrl:1
	v_mov_b32_e32 v87, 0
	v_add_f32_dpp v84, v84, v84 row_ror:4 row_mask:0xf bank_mask:0xf bound_ctrl:1
	v_add_f32_dpp v86, v86, v86 row_ror:4 row_mask:0xf bank_mask:0xf bound_ctrl:1
	s_nop 0
	v_add_f32_dpp v84, v84, v84 row_ror:2 row_mask:0xf bank_mask:0xf bound_ctrl:1
	v_add_f32_dpp v86, v86, v86 row_ror:2 row_mask:0xf bank_mask:0xf bound_ctrl:1
	s_nop 0
	v_mov_b32_dpp v85, v84 row_ror:1 row_mask:0xf bank_mask:0xf
	v_mov_b32_dpp v87, v86 row_ror:1 row_mask:0xf bank_mask:0xf
	s_and_saveexec_b64 s[8:9], s[40:41]
	v_add_f32_e32 v86, v86, v87
	v_add_f32_e32 v84, v84, v85
	ds_write2_b32 v185, v84, v86 offset0:32 offset1:48
	s_or_b64 exec, exec, s[8:9]
	s_waitcnt lgkmcnt(4)
	v_mul_f32 v151, v141, v120
	v_mul_f32 v120, v92, v120
	v_mul_f32 v152, v148, v121
	v_mul_f32 v121, v93, v121
	ds_read_b128 v[88:91], v134 offset:768
	ds_read_b128 v[116:119], v134 offset:4864
	ds_read_b128 v[104:107], v134 offset:8960
	ds_read_b128 v[112:115], v134 offset:13056
	ds_read_b128 v[84:87], v134 offset:17152
	ds_read2_b32 v[126:127], v189 offset0:96 offset1:112
	v_fma_f32 v151, v149, v122, v151
	v_fma_f32 v120, v94, v122, v120
	v_fma_f32 v122, v150, v123, v152
	v_fma_f32 v121, v95, v123, v121
	v_add_f32_e32 v122, v151, v122
	v_add_f32_e32 v120, v120, v121
	s_nop 0
	v_add_f32_dpp v121, v122, v122 row_ror:8 row_mask:0xf bank_mask:0xf bound_ctrl:1
	v_add_f32_dpp v120, v120, v120 row_ror:8 row_mask:0xf bank_mask:0xf bound_ctrl:1
	s_waitcnt lgkmcnt(6)
	v_mul_f32 v122, v124, v108
	v_mul_f32 v108, v125, v108
	v_add_f32_dpp v121, v121, v121 row_ror:4 row_mask:0xf bank_mask:0xf bound_ctrl:1
	v_add_f32_dpp v120, v120, v120 row_ror:4 row_mask:0xf bank_mask:0xf bound_ctrl:1
	s_nop 0
	v_add_f32_dpp v121, v121, v121 row_ror:2 row_mask:0xf bank_mask:0xf bound_ctrl:1
	v_add_f32_dpp v120, v120, v120 row_ror:2 row_mask:0xf bank_mask:0xf bound_ctrl:1
	s_nop 0
	v_add_f32_dpp v121, v121, v121 row_ror:1 row_mask:0xf bank_mask:0xf bound_ctrl:1
	v_add_f32_dpp v120, v120, v120 row_ror:1 row_mask:0xf bank_mask:0xf bound_ctrl:1
	v_fma_f32 v122, v121, v100, v122
	v_fma_f32 v100, v120, v100, v108
	v_fma_f32 v141, v141, v96, v122
	v_fma_f32 v96, v92, v96, v100
	v_mul_f32 v92, v124, v109
	v_fma_f32 v92, v121, v101, v92
	v_fma_f32 v151, v148, v97, v92
	v_mul_f32 v92, v125, v109
	v_fma_f32 v92, v120, v101, v92
	v_fma_f32 v97, v93, v97, v92
	v_mul_f32 v92, v124, v110
	v_mul_f32 v93, v151, v81
	v_fma_f32 v92, v121, v102, v92
	v_mul_f32 v81, v97, v81
	v_fma_f32 v152, v149, v98, v92
	v_mul_f32 v92, v125, v110
	v_fma_f32 v92, v120, v102, v92
	v_fma_f32 v98, v94, v98, v92
	v_mul_f32 v92, v124, v111
	v_fma_f32 v92, v121, v103, v92
	v_fma_f32 v124, v150, v99, v92
	v_mul_f32 v92, v125, v111
	v_fma_f32 v92, v120, v103, v92
	v_fma_f32 v99, v95, v99, v92
	v_mul_f32 v92, v141, v80
	v_mul_f32 v80, v96, v80
	v_fma_f32 v92, v152, v82, v92
	v_fma_f32 v80, v98, v82, v80
	v_fma_f32 v82, v124, v83, v93
	v_fma_f32 v81, v99, v83, v81
	v_add_f32_e32 v82, v92, v82
	v_add_f32_e32 v83, v80, v81
	v_mov_b32_e32 v81, 0
	v_add_f32_dpp v80, v82, v82 row_ror:8 row_mask:0xf bank_mask:0xf bound_ctrl:1
	v_add_f32_dpp v82, v83, v83 row_ror:8 row_mask:0xf bank_mask:0xf bound_ctrl:1
	v_mov_b32_e32 v83, 0
	v_add_f32_dpp v80, v80, v80 row_ror:4 row_mask:0xf bank_mask:0xf bound_ctrl:1
	v_add_f32_dpp v82, v82, v82 row_ror:4 row_mask:0xf bank_mask:0xf bound_ctrl:1
	s_nop 0
	v_add_f32_dpp v80, v80, v80 row_ror:2 row_mask:0xf bank_mask:0xf bound_ctrl:1
	v_add_f32_dpp v82, v82, v82 row_ror:2 row_mask:0xf bank_mask:0xf bound_ctrl:1
	s_nop 0
	v_mov_b32_dpp v81, v80 row_ror:1 row_mask:0xf bank_mask:0xf
	v_mov_b32_dpp v83, v82 row_ror:1 row_mask:0xf bank_mask:0xf
	s_and_saveexec_b64 s[8:9], s[40:41]
	v_add_f32_e32 v82, v82, v83
	v_add_f32_e32 v80, v80, v81
	ds_write2_b32 v185, v80, v82 offset0:64 offset1:80
	s_or_b64 exec, exec, s[8:9]
	s_waitcnt lgkmcnt(4)
	v_mul_f32 v125, v141, v116
	v_mul_f32 v116, v96, v116
	v_mul_f32 v150, v151, v117
	v_mul_f32 v117, v97, v117
	ds_read_b128 v[92:95], v134 offset:1024
	ds_read_b128 v[120:123], v134 offset:5120
	ds_read_b128 v[100:103], v134 offset:9216
	ds_read_b128 v[108:111], v134 offset:13312
	ds_read_b128 v[80:83], v134 offset:17408
	ds_read2_b32 v[148:149], v189 offset0:128 offset1:144
	v_fma_f32 v116, v98, v118, v116
	v_fma_f32 v125, v152, v118, v125
	v_fma_f32 v118, v124, v119, v150
	v_fma_f32 v117, v99, v119, v117
	v_add_f32_e32 v118, v125, v118
	v_add_f32_e32 v116, v116, v117
	s_nop 1
	v_add_f32_dpp v116, v116, v116 row_ror:8 row_mask:0xf bank_mask:0xf bound_ctrl:1
	v_add_f32_dpp v117, v118, v118 row_ror:8 row_mask:0xf bank_mask:0xf bound_ctrl:1
	s_nop 0
	v_add_f32_dpp v116, v116, v116 row_ror:4 row_mask:0xf bank_mask:0xf bound_ctrl:1
	v_add_f32_dpp v117, v117, v117 row_ror:4 row_mask:0xf bank_mask:0xf bound_ctrl:1
	s_nop 0
	v_add_f32_dpp v116, v116, v116 row_ror:2 row_mask:0xf bank_mask:0xf bound_ctrl:1
	v_add_f32_dpp v117, v117, v117 row_ror:2 row_mask:0xf bank_mask:0xf bound_ctrl:1
	s_nop 0
	v_add_f32_dpp v125, v116, v116 row_ror:1 row_mask:0xf bank_mask:0xf bound_ctrl:1
	s_waitcnt lgkmcnt(6)
	v_mul_f32 v116, v126, v112
	v_add_f32_dpp v119, v117, v117 row_ror:1 row_mask:0xf bank_mask:0xf bound_ctrl:1
	v_fma_f32 v116, v119, v104, v116
	v_mul_f32 v112, v127, v112
	v_fma_f32 v116, v141, v88, v116
	v_fma_f32 v104, v125, v104, v112
	v_fma_f32 v88, v96, v88, v104
	v_mul_f32 v96, v126, v113
	v_fma_f32 v96, v119, v105, v96
	v_fma_f32 v117, v151, v89, v96
	v_mul_f32 v96, v127, v113
	v_fma_f32 v96, v125, v105, v96
	v_fma_f32 v89, v97, v89, v96
	v_mul_f32 v96, v126, v114
	v_mul_f32 v97, v117, v85
	v_fma_f32 v96, v119, v106, v96
	v_mul_f32 v85, v89, v85
	v_fma_f32 v118, v152, v90, v96
	v_mul_f32 v96, v127, v114
	v_fma_f32 v96, v125, v106, v96
	v_fma_f32 v90, v98, v90, v96
	v_mul_f32 v96, v126, v115
	v_fma_f32 v96, v119, v107, v96
	v_fma_f32 v119, v124, v91, v96
	v_mul_f32 v96, v127, v115
	v_fma_f32 v96, v125, v107, v96
	v_fma_f32 v91, v99, v91, v96
	v_mul_f32 v96, v116, v84
	v_mul_f32 v84, v88, v84
	v_fma_f32 v96, v118, v86, v96
	v_fma_f32 v84, v90, v86, v84
	v_fma_f32 v86, v119, v87, v97
	v_fma_f32 v85, v91, v87, v85
	v_add_f32_e32 v86, v96, v86
	v_add_f32_e32 v87, v84, v85
	v_mov_b32_e32 v85, 0
	v_add_f32_dpp v84, v86, v86 row_ror:8 row_mask:0xf bank_mask:0xf bound_ctrl:1
	v_add_f32_dpp v86, v87, v87 row_ror:8 row_mask:0xf bank_mask:0xf bound_ctrl:1
	v_mov_b32_e32 v87, 0
	v_add_f32_dpp v84, v84, v84 row_ror:4 row_mask:0xf bank_mask:0xf bound_ctrl:1
	v_add_f32_dpp v86, v86, v86 row_ror:4 row_mask:0xf bank_mask:0xf bound_ctrl:1
	s_nop 0
	v_add_f32_dpp v84, v84, v84 row_ror:2 row_mask:0xf bank_mask:0xf bound_ctrl:1
	v_add_f32_dpp v86, v86, v86 row_ror:2 row_mask:0xf bank_mask:0xf bound_ctrl:1
	s_nop 0
	v_mov_b32_dpp v85, v84 row_ror:1 row_mask:0xf bank_mask:0xf
	v_mov_b32_dpp v87, v86 row_ror:1 row_mask:0xf bank_mask:0xf
	s_and_saveexec_b64 s[8:9], s[40:41]
	v_add_f32_e32 v86, v86, v87
	v_add_f32_e32 v84, v84, v85
	ds_write2_b32 v185, v84, v86 offset0:96 offset1:112
	s_or_b64 exec, exec, s[8:9]
	s_waitcnt lgkmcnt(4)
	v_mul_f32 v141, v116, v120
	v_mul_f32 v120, v88, v120
	v_mul_f32 v152, v117, v121
	v_mul_f32 v121, v89, v121
	ds_read_b128 v[96:99], v134 offset:1280
	ds_read_b128 v[124:127], v134 offset:5376
	ds_read_b128 v[104:107], v134 offset:9472
	ds_read_b128 v[112:115], v134 offset:13568
	ds_read_b128 v[84:87], v134 offset:17664
	ds_read2_b32 v[150:151], v189 offset0:160 offset1:176
	v_fma_f32 v141, v118, v122, v141
	v_fma_f32 v120, v90, v122, v120
	v_fma_f32 v122, v119, v123, v152
	v_fma_f32 v121, v91, v123, v121
	v_add_f32_e32 v122, v141, v122
	v_add_f32_e32 v120, v120, v121
	s_nop 0
	v_add_f32_dpp v121, v122, v122 row_ror:8 row_mask:0xf bank_mask:0xf bound_ctrl:1
	v_add_f32_dpp v120, v120, v120 row_ror:8 row_mask:0xf bank_mask:0xf bound_ctrl:1
	s_waitcnt lgkmcnt(6)
	v_mul_f32 v122, v148, v108
	v_mul_f32 v108, v149, v108
	v_add_f32_dpp v121, v121, v121 row_ror:4 row_mask:0xf bank_mask:0xf bound_ctrl:1
	v_add_f32_dpp v120, v120, v120 row_ror:4 row_mask:0xf bank_mask:0xf bound_ctrl:1
	s_nop 0
	v_add_f32_dpp v121, v121, v121 row_ror:2 row_mask:0xf bank_mask:0xf bound_ctrl:1
	v_add_f32_dpp v120, v120, v120 row_ror:2 row_mask:0xf bank_mask:0xf bound_ctrl:1
	s_nop 0
	v_add_f32_dpp v121, v121, v121 row_ror:1 row_mask:0xf bank_mask:0xf bound_ctrl:1
	v_add_f32_dpp v120, v120, v120 row_ror:1 row_mask:0xf bank_mask:0xf bound_ctrl:1
	v_fma_f32 v122, v121, v100, v122
	v_fma_f32 v100, v120, v100, v108
	v_fma_f32 v141, v116, v92, v122
	v_fma_f32 v92, v88, v92, v100
	v_mul_f32 v88, v148, v109
	v_fma_f32 v88, v121, v101, v88
	v_fma_f32 v152, v117, v93, v88
	v_mul_f32 v88, v149, v109
	v_fma_f32 v88, v120, v101, v88
	v_fma_f32 v93, v89, v93, v88
	v_mul_f32 v88, v148, v110
	v_mul_f32 v89, v152, v81
	v_fma_f32 v88, v121, v102, v88
	v_mul_f32 v81, v93, v81
	v_fma_f32 v153, v118, v94, v88
	v_mul_f32 v88, v149, v110
	v_fma_f32 v88, v120, v102, v88
	v_fma_f32 v94, v90, v94, v88
	v_mul_f32 v88, v148, v111
	v_fma_f32 v88, v121, v103, v88
	v_fma_f32 v186, v119, v95, v88
	v_mul_f32 v88, v149, v111
	v_fma_f32 v88, v120, v103, v88
	v_fma_f32 v95, v91, v95, v88
	v_mul_f32 v88, v141, v80
	v_mul_f32 v80, v92, v80
	v_fma_f32 v88, v153, v82, v88
	v_fma_f32 v80, v94, v82, v80
	v_fma_f32 v82, v186, v83, v89
	v_fma_f32 v81, v95, v83, v81
	v_add_f32_e32 v82, v88, v82
	v_add_f32_e32 v83, v80, v81
	v_mov_b32_e32 v81, 0
	v_add_f32_dpp v80, v82, v82 row_ror:8 row_mask:0xf bank_mask:0xf bound_ctrl:1
	v_add_f32_dpp v82, v83, v83 row_ror:8 row_mask:0xf bank_mask:0xf bound_ctrl:1
	v_mov_b32_e32 v83, 0
	v_add_f32_dpp v80, v80, v80 row_ror:4 row_mask:0xf bank_mask:0xf bound_ctrl:1
	v_add_f32_dpp v82, v82, v82 row_ror:4 row_mask:0xf bank_mask:0xf bound_ctrl:1
	s_nop 0
	v_add_f32_dpp v80, v80, v80 row_ror:2 row_mask:0xf bank_mask:0xf bound_ctrl:1
	v_add_f32_dpp v82, v82, v82 row_ror:2 row_mask:0xf bank_mask:0xf bound_ctrl:1
	s_nop 0
	v_mov_b32_dpp v81, v80 row_ror:1 row_mask:0xf bank_mask:0xf
	v_mov_b32_dpp v83, v82 row_ror:1 row_mask:0xf bank_mask:0xf
	s_and_saveexec_b64 s[8:9], s[40:41]
	v_add_f32_e32 v82, v82, v83
	v_add_f32_e32 v80, v80, v81
	ds_write2_b32 v185, v80, v82 offset0:128 offset1:144
	s_or_b64 exec, exec, s[8:9]
	s_waitcnt lgkmcnt(4)
	v_mul_f32 v80, v141, v124
	v_mul_f32 v82, v152, v125
	v_mul_f32 v81, v92, v124
	v_mul_f32 v83, v93, v125
	ds_read_b128 v[100:103], v134 offset:1536
	ds_read_b128 v[120:123], v134 offset:5632
	ds_read_b128 v[108:111], v134 offset:9728
	ds_read_b128 v[116:119], v134 offset:13824
	ds_read_b128 v[88:91], v134 offset:17920
	ds_read2_b32 v[148:149], v189 offset0:192 offset1:208
	v_fma_f32 v80, v153, v126, v80
	v_fma_f32 v82, v186, v127, v82
	v_fma_f32 v81, v94, v126, v81
	v_fma_f32 v83, v95, v127, v83
	v_add_f32_e32 v80, v80, v82
	v_add_f32_e32 v81, v81, v83
	s_nop 0
	v_add_f32_dpp v80, v80, v80 row_ror:8 row_mask:0xf bank_mask:0xf bound_ctrl:1
	s_waitcnt lgkmcnt(6)
	v_mul_f32 v82, v150, v112
	v_add_f32_dpp v81, v81, v81 row_ror:8 row_mask:0xf bank_mask:0xf bound_ctrl:1
	v_add_f32_dpp v80, v80, v80 row_ror:4 row_mask:0xf bank_mask:0xf bound_ctrl:1
	s_nop 0
	v_add_f32_dpp v81, v81, v81 row_ror:4 row_mask:0xf bank_mask:0xf bound_ctrl:1
	v_add_f32_dpp v80, v80, v80 row_ror:2 row_mask:0xf bank_mask:0xf bound_ctrl:1
	s_nop 0
	v_add_f32_dpp v81, v81, v81 row_ror:2 row_mask:0xf bank_mask:0xf bound_ctrl:1
	v_add_f32_dpp v80, v80, v80 row_ror:1 row_mask:0xf bank_mask:0xf bound_ctrl:1
	v_fma_f32 v82, v80, v104, v82
	v_fma_f32 v126, v141, v96, v82
	v_mul_f32 v82, v151, v112
	v_add_f32_dpp v81, v81, v81 row_ror:1 row_mask:0xf bank_mask:0xf bound_ctrl:1
	v_fma_f32 v82, v81, v104, v82
	v_fma_f32 v127, v92, v96, v82
	v_mul_f32 v82, v150, v113
	v_fma_f32 v82, v80, v105, v82
	v_fma_f32 v141, v152, v97, v82
	v_mul_f32 v82, v151, v113
	v_fma_f32 v82, v81, v105, v82
	v_fma_f32 v152, v93, v97, v82
	v_mul_f32 v82, v150, v114
	v_fma_f32 v82, v80, v106, v82
	v_mul_f32 v83, v152, v85
	v_fma_f32 v153, v153, v98, v82
	v_mul_f32 v82, v151, v114
	v_fma_f32 v82, v81, v106, v82
	v_fma_f32 v187, v94, v98, v82
	v_mul_f32 v82, v150, v115
	v_fma_f32 v80, v80, v107, v82
	v_mul_f32 v82, v141, v85
	v_fma_f32 v186, v186, v99, v80
	v_mul_f32 v80, v151, v115
	v_fma_f32 v80, v81, v107, v80
	v_mul_f32 v81, v127, v84
	v_fma_f32 v82, v186, v87, v82
	v_fma_f32 v151, v95, v99, v80
	v_mul_f32 v80, v126, v84
	v_fma_f32 v81, v187, v86, v81
	v_fma_f32 v80, v153, v86, v80
	v_fma_f32 v83, v151, v87, v83
	v_add_f32_e32 v80, v80, v82
	v_add_f32_e32 v82, v81, v83
	v_mov_b32_e32 v81, 0
	v_add_f32_dpp v80, v80, v80 row_ror:8 row_mask:0xf bank_mask:0xf bound_ctrl:1
	v_add_f32_dpp v82, v82, v82 row_ror:8 row_mask:0xf bank_mask:0xf bound_ctrl:1
	v_mov_b32_e32 v83, 0
	v_add_f32_dpp v80, v80, v80 row_ror:4 row_mask:0xf bank_mask:0xf bound_ctrl:1
	v_add_f32_dpp v82, v82, v82 row_ror:4 row_mask:0xf bank_mask:0xf bound_ctrl:1
	s_nop 0
	v_add_f32_dpp v80, v80, v80 row_ror:2 row_mask:0xf bank_mask:0xf bound_ctrl:1
	v_add_f32_dpp v82, v82, v82 row_ror:2 row_mask:0xf bank_mask:0xf bound_ctrl:1
	s_nop 0
	v_mov_b32_dpp v81, v80 row_ror:1 row_mask:0xf bank_mask:0xf
	v_mov_b32_dpp v83, v82 row_ror:1 row_mask:0xf bank_mask:0xf
	s_and_saveexec_b64 s[8:9], s[40:41]
	v_add_f32_e32 v82, v82, v83
	v_add_f32_e32 v80, v80, v81
	ds_write2_b32 v185, v80, v82 offset0:160 offset1:176
	s_or_b64 exec, exec, s[8:9]
	s_waitcnt lgkmcnt(4)
	v_mul_f32 v84, v126, v120
	v_mul_f32 v86, v141, v121
	v_mul_f32 v85, v127, v120
	v_mul_f32 v87, v152, v121
	ds_read_b128 v[92:95], v134 offset:1792
	ds_read_b128 v[112:115], v134 offset:5888
	ds_read_b128 v[96:99], v134 offset:9984
	ds_read_b128 v[104:107], v134 offset:14080
	ds_read_b128 v[80:83], v134 offset:18176
	ds_read2_b32 v[124:125], v189 offset0:224 offset1:240
	v_fma_f32 v84, v153, v122, v84
	v_fma_f32 v86, v186, v123, v86
	v_fma_f32 v85, v187, v122, v85
	v_fma_f32 v87, v151, v123, v87
	v_add_f32_e32 v84, v84, v86
	v_add_f32_e32 v85, v85, v87
	s_nop 0
	v_add_f32_dpp v84, v84, v84 row_ror:8 row_mask:0xf bank_mask:0xf bound_ctrl:1
	s_waitcnt lgkmcnt(6)
	v_mul_f32 v86, v148, v116
	v_add_f32_dpp v85, v85, v85 row_ror:8 row_mask:0xf bank_mask:0xf bound_ctrl:1
	v_add_f32_dpp v84, v84, v84 row_ror:4 row_mask:0xf bank_mask:0xf bound_ctrl:1
	s_nop 0
	v_add_f32_dpp v85, v85, v85 row_ror:4 row_mask:0xf bank_mask:0xf bound_ctrl:1
	v_add_f32_dpp v84, v84, v84 row_ror:2 row_mask:0xf bank_mask:0xf bound_ctrl:1
	s_nop 0
	v_add_f32_dpp v85, v85, v85 row_ror:2 row_mask:0xf bank_mask:0xf bound_ctrl:1
	v_add_f32_dpp v84, v84, v84 row_ror:1 row_mask:0xf bank_mask:0xf bound_ctrl:1
	v_fma_f32 v86, v84, v108, v86
	v_fma_f32 v120, v126, v100, v86
	v_mul_f32 v86, v149, v116
	v_add_f32_dpp v85, v85, v85 row_ror:1 row_mask:0xf bank_mask:0xf bound_ctrl:1
	v_fma_f32 v86, v85, v108, v86
	v_fma_f32 v121, v127, v100, v86
	v_mul_f32 v86, v148, v117
	v_fma_f32 v86, v84, v109, v86
	v_fma_f32 v126, v141, v101, v86
	v_mul_f32 v86, v149, v117
	v_fma_f32 v86, v85, v109, v86
	v_fma_f32 v127, v152, v101, v86
	v_mul_f32 v86, v148, v118
	v_fma_f32 v86, v84, v110, v86
	v_mul_f32 v87, v127, v89
	v_fma_f32 v141, v153, v102, v86
	v_mul_f32 v86, v149, v118
	v_fma_f32 v86, v85, v110, v86
	v_fma_f32 v150, v187, v102, v86
	v_mul_f32 v86, v148, v119
	v_fma_f32 v84, v84, v111, v86
	v_mul_f32 v86, v126, v89
	v_fma_f32 v148, v186, v103, v84
	v_mul_f32 v84, v149, v119
	v_fma_f32 v84, v85, v111, v84
	v_mul_f32 v85, v121, v88
	v_fma_f32 v86, v148, v91, v86
	v_fma_f32 v149, v151, v103, v84
	v_mul_f32 v84, v120, v88
	v_fma_f32 v85, v150, v90, v85
	v_fma_f32 v84, v141, v90, v84
	v_fma_f32 v87, v149, v91, v87
	v_add_f32_e32 v84, v84, v86
	v_add_f32_e32 v86, v85, v87
	v_mov_b32_e32 v85, 0
	v_add_f32_dpp v84, v84, v84 row_ror:8 row_mask:0xf bank_mask:0xf bound_ctrl:1
	v_add_f32_dpp v86, v86, v86 row_ror:8 row_mask:0xf bank_mask:0xf bound_ctrl:1
	v_mov_b32_e32 v87, 0
	v_add_f32_dpp v84, v84, v84 row_ror:4 row_mask:0xf bank_mask:0xf bound_ctrl:1
	v_add_f32_dpp v86, v86, v86 row_ror:4 row_mask:0xf bank_mask:0xf bound_ctrl:1
	s_nop 0
	v_add_f32_dpp v84, v84, v84 row_ror:2 row_mask:0xf bank_mask:0xf bound_ctrl:1
	v_add_f32_dpp v86, v86, v86 row_ror:2 row_mask:0xf bank_mask:0xf bound_ctrl:1
	s_nop 0
	v_mov_b32_dpp v85, v84 row_ror:1 row_mask:0xf bank_mask:0xf
	v_mov_b32_dpp v87, v86 row_ror:1 row_mask:0xf bank_mask:0xf
	s_and_saveexec_b64 s[8:9], s[40:41]
	v_add_f32_e32 v86, v86, v87
	v_add_f32_e32 v84, v84, v85
	ds_write2_b32 v185, v84, v86 offset0:192 offset1:208
	s_or_b64 exec, exec, s[8:9]
	s_waitcnt lgkmcnt(4)
	v_mul_f32 v151, v120, v112
	v_mul_f32 v112, v121, v112
	v_mul_f32 v152, v126, v113
	v_mul_f32 v113, v127, v113
	ds_read_b128 v[88:91], v134 offset:2048
	ds_read_b128 v[116:119], v134 offset:6144
	ds_read_b128 v[100:103], v134 offset:10240
	ds_read_b128 v[108:111], v134 offset:14336
	ds_read_b128 v[84:87], v134 offset:18432
	v_fma_f32 v151, v141, v114, v151
	v_fma_f32 v112, v150, v114, v112
	v_fma_f32 v114, v148, v115, v152
	v_fma_f32 v113, v149, v115, v113
	v_add_u32_e32 v187, 0x5400, v182
	v_add_f32_e32 v114, v151, v114
	v_add_f32_e32 v112, v112, v113
	ds_read2_b32 v[122:123], v187 offset1:16
	v_add_f32_dpp v113, v114, v114 row_ror:8 row_mask:0xf bank_mask:0xf bound_ctrl:1
	v_add_f32_dpp v112, v112, v112 row_ror:8 row_mask:0xf bank_mask:0xf bound_ctrl:1
	s_waitcnt lgkmcnt(6)
	v_mul_f32 v114, v124, v104
	v_mul_f32 v104, v125, v104
	v_add_f32_dpp v113, v113, v113 row_ror:4 row_mask:0xf bank_mask:0xf bound_ctrl:1
	v_add_f32_dpp v112, v112, v112 row_ror:4 row_mask:0xf bank_mask:0xf bound_ctrl:1
	s_nop 0
	v_add_f32_dpp v113, v113, v113 row_ror:2 row_mask:0xf bank_mask:0xf bound_ctrl:1
	v_add_f32_dpp v112, v112, v112 row_ror:2 row_mask:0xf bank_mask:0xf bound_ctrl:1
	s_nop 0
	v_add_f32_dpp v113, v113, v113 row_ror:1 row_mask:0xf bank_mask:0xf bound_ctrl:1
	v_add_f32_dpp v112, v112, v112 row_ror:1 row_mask:0xf bank_mask:0xf bound_ctrl:1
	v_fma_f32 v114, v113, v96, v114
	v_fma_f32 v96, v112, v96, v104
	v_fma_f32 v151, v120, v92, v114
	v_fma_f32 v152, v121, v92, v96
	v_mul_f32 v92, v124, v105
	v_fma_f32 v92, v113, v97, v92
	v_fma_f32 v126, v126, v93, v92
	v_mul_f32 v92, v125, v105
	v_fma_f32 v92, v112, v97, v92
	v_fma_f32 v127, v127, v93, v92
	v_mul_f32 v92, v124, v106
	v_mul_f32 v93, v126, v81
	v_fma_f32 v92, v113, v98, v92
	v_mul_f32 v81, v127, v81
	v_fma_f32 v141, v141, v94, v92
	v_mul_f32 v92, v125, v106
	v_fma_f32 v92, v112, v98, v92
	v_fma_f32 v150, v150, v94, v92
	v_mul_f32 v92, v124, v107
	v_fma_f32 v92, v113, v99, v92
	v_fma_f32 v153, v148, v95, v92
	v_mul_f32 v92, v125, v107
	v_fma_f32 v92, v112, v99, v92
	v_fma_f32 v186, v149, v95, v92
	v_mul_f32 v92, v151, v80
	v_mul_f32 v80, v152, v80
	v_fma_f32 v92, v141, v82, v92
	v_fma_f32 v80, v150, v82, v80
	v_fma_f32 v82, v153, v83, v93
	v_fma_f32 v81, v186, v83, v81
	v_add_f32_e32 v82, v92, v82
	v_add_f32_e32 v83, v80, v81
	v_mov_b32_e32 v81, 0
	v_add_f32_dpp v80, v82, v82 row_ror:8 row_mask:0xf bank_mask:0xf bound_ctrl:1
	v_add_f32_dpp v82, v83, v83 row_ror:8 row_mask:0xf bank_mask:0xf bound_ctrl:1
	v_mov_b32_e32 v83, 0
	v_add_f32_dpp v80, v80, v80 row_ror:4 row_mask:0xf bank_mask:0xf bound_ctrl:1
	v_add_f32_dpp v82, v82, v82 row_ror:4 row_mask:0xf bank_mask:0xf bound_ctrl:1
	s_nop 0
	v_add_f32_dpp v80, v80, v80 row_ror:2 row_mask:0xf bank_mask:0xf bound_ctrl:1
	v_add_f32_dpp v82, v82, v82 row_ror:2 row_mask:0xf bank_mask:0xf bound_ctrl:1
	s_nop 0
	v_mov_b32_dpp v81, v80 row_ror:1 row_mask:0xf bank_mask:0xf
	v_mov_b32_dpp v83, v82 row_ror:1 row_mask:0xf bank_mask:0xf
	s_and_saveexec_b64 s[8:9], s[40:41]
	v_add_f32_e32 v82, v82, v83
	v_add_f32_e32 v80, v80, v81
	ds_write2_b32 v185, v80, v82 offset0:224 offset1:240
	s_or_b64 exec, exec, s[8:9]
	s_waitcnt lgkmcnt(4)
	v_mul_f32 v124, v151, v116
	v_mul_f32 v116, v152, v116
	v_mul_f32 v125, v126, v117
	v_mul_f32 v117, v127, v117
	ds_read_b128 v[92:95], v134 offset:2304
	ds_read_b128 v[112:115], v134 offset:6400
	ds_read_b128 v[96:99], v134 offset:10496
	ds_read_b128 v[104:107], v134 offset:14592
	ds_read_b128 v[80:83], v134 offset:18688
	ds_read2_b32 v[120:121], v187 offset0:32 offset1:48
	v_fma_f32 v124, v141, v118, v124
	v_fma_f32 v116, v150, v118, v116
	v_fma_f32 v118, v153, v119, v125
	v_fma_f32 v117, v186, v119, v117
	v_add_f32_e32 v118, v124, v118
	v_add_f32_e32 v116, v116, v117
	s_nop 0
	v_add_f32_dpp v117, v118, v118 row_ror:8 row_mask:0xf bank_mask:0xf bound_ctrl:1
	v_add_f32_dpp v116, v116, v116 row_ror:8 row_mask:0xf bank_mask:0xf bound_ctrl:1
	s_waitcnt lgkmcnt(6)
	v_mul_f32 v118, v122, v108
	v_mul_f32 v108, v123, v108
	v_add_f32_dpp v117, v117, v117 row_ror:4 row_mask:0xf bank_mask:0xf bound_ctrl:1
	v_add_f32_dpp v116, v116, v116 row_ror:4 row_mask:0xf bank_mask:0xf bound_ctrl:1
	s_nop 0
	v_add_f32_dpp v117, v117, v117 row_ror:2 row_mask:0xf bank_mask:0xf bound_ctrl:1
	v_add_f32_dpp v116, v116, v116 row_ror:2 row_mask:0xf bank_mask:0xf bound_ctrl:1
	s_nop 0
	v_add_f32_dpp v117, v117, v117 row_ror:1 row_mask:0xf bank_mask:0xf bound_ctrl:1
	v_add_f32_dpp v116, v116, v116 row_ror:1 row_mask:0xf bank_mask:0xf bound_ctrl:1
	v_fma_f32 v118, v117, v100, v118
	v_fma_f32 v100, v116, v100, v108
	v_fma_f32 v124, v151, v88, v118
	v_fma_f32 v125, v152, v88, v100
	v_mul_f32 v88, v122, v109
	v_fma_f32 v88, v117, v101, v88
	v_fma_f32 v126, v126, v89, v88
	v_mul_f32 v88, v123, v109
	v_fma_f32 v88, v116, v101, v88
	v_fma_f32 v127, v127, v89, v88
	v_mul_f32 v88, v122, v110
	v_mul_f32 v89, v126, v85
	v_fma_f32 v88, v117, v102, v88
	v_mul_f32 v85, v127, v85
	v_fma_f32 v141, v141, v90, v88
	v_mul_f32 v88, v123, v110
	v_fma_f32 v88, v116, v102, v88
	v_fma_f32 v148, v150, v90, v88
	v_mul_f32 v88, v122, v111
	v_fma_f32 v88, v117, v103, v88
	v_fma_f32 v149, v153, v91, v88
	v_mul_f32 v88, v123, v111
	v_fma_f32 v88, v116, v103, v88
	v_fma_f32 v150, v186, v91, v88
	v_mul_f32 v88, v124, v84
	v_mul_f32 v84, v125, v84
	v_add_u32_e32 v186, 0xb400, v182
	v_fma_f32 v88, v141, v86, v88
	v_fma_f32 v84, v148, v86, v84
	v_fma_f32 v86, v149, v87, v89
	v_fma_f32 v85, v150, v87, v85
	v_add_f32_e32 v86, v88, v86
	v_add_f32_e32 v87, v84, v85
	v_mov_b32_e32 v85, 0
	v_add_f32_dpp v84, v86, v86 row_ror:8 row_mask:0xf bank_mask:0xf bound_ctrl:1
	v_add_f32_dpp v86, v87, v87 row_ror:8 row_mask:0xf bank_mask:0xf bound_ctrl:1
	v_mov_b32_e32 v87, 0
	v_add_f32_dpp v84, v84, v84 row_ror:4 row_mask:0xf bank_mask:0xf bound_ctrl:1
	v_add_f32_dpp v86, v86, v86 row_ror:4 row_mask:0xf bank_mask:0xf bound_ctrl:1
	s_nop 0
	v_add_f32_dpp v84, v84, v84 row_ror:2 row_mask:0xf bank_mask:0xf bound_ctrl:1
	v_add_f32_dpp v86, v86, v86 row_ror:2 row_mask:0xf bank_mask:0xf bound_ctrl:1
	s_nop 0
	v_mov_b32_dpp v85, v84 row_ror:1 row_mask:0xf bank_mask:0xf
	v_mov_b32_dpp v87, v86 row_ror:1 row_mask:0xf bank_mask:0xf
	s_and_saveexec_b64 s[8:9], s[40:41]
	v_add_f32_e32 v86, v86, v87
	v_add_f32_e32 v84, v84, v85
	ds_write2_b32 v186, v84, v86 offset1:16
	s_or_b64 exec, exec, s[8:9]
	s_waitcnt lgkmcnt(4)
	v_mul_f32 v151, v124, v112
	v_mul_f32 v112, v125, v112
	v_mul_f32 v152, v126, v113
	v_mul_f32 v113, v127, v113
	ds_read_b128 v[88:91], v134 offset:2560
	ds_read_b128 v[116:119], v134 offset:6656
	ds_read_b128 v[100:103], v134 offset:10752
	ds_read_b128 v[108:111], v134 offset:14848
	ds_read_b128 v[84:87], v134 offset:18944
	ds_read2_b32 v[122:123], v187 offset0:64 offset1:80
	v_fma_f32 v151, v141, v114, v151
	v_fma_f32 v112, v148, v114, v112
	v_fma_f32 v114, v149, v115, v152
	v_fma_f32 v113, v150, v115, v113
	v_add_f32_e32 v114, v151, v114
	v_add_f32_e32 v112, v112, v113
	s_nop 0
	v_add_f32_dpp v113, v114, v114 row_ror:8 row_mask:0xf bank_mask:0xf bound_ctrl:1
	v_add_f32_dpp v112, v112, v112 row_ror:8 row_mask:0xf bank_mask:0xf bound_ctrl:1
	s_waitcnt lgkmcnt(6)
	v_mul_f32 v114, v120, v104
	v_mul_f32 v104, v121, v104
	v_add_f32_dpp v113, v113, v113 row_ror:4 row_mask:0xf bank_mask:0xf bound_ctrl:1
	v_add_f32_dpp v112, v112, v112 row_ror:4 row_mask:0xf bank_mask:0xf bound_ctrl:1
	s_nop 0
	v_add_f32_dpp v113, v113, v113 row_ror:2 row_mask:0xf bank_mask:0xf bound_ctrl:1
	v_add_f32_dpp v112, v112, v112 row_ror:2 row_mask:0xf bank_mask:0xf bound_ctrl:1
	s_nop 0
	v_add_f32_dpp v113, v113, v113 row_ror:1 row_mask:0xf bank_mask:0xf bound_ctrl:1
	v_add_f32_dpp v112, v112, v112 row_ror:1 row_mask:0xf bank_mask:0xf bound_ctrl:1
	v_fma_f32 v114, v113, v96, v114
	v_fma_f32 v96, v112, v96, v104
	v_fma_f32 v124, v124, v92, v114
	v_fma_f32 v125, v125, v92, v96
	v_mul_f32 v92, v120, v105
	v_fma_f32 v92, v113, v97, v92
	v_fma_f32 v126, v126, v93, v92
	v_mul_f32 v92, v121, v105
	v_fma_f32 v92, v112, v97, v92
	v_fma_f32 v127, v127, v93, v92
	v_mul_f32 v92, v120, v106
	v_mul_f32 v93, v126, v81
	v_fma_f32 v92, v113, v98, v92
	v_mul_f32 v81, v127, v81
	v_fma_f32 v141, v141, v94, v92
	v_mul_f32 v92, v121, v106
	v_fma_f32 v92, v112, v98, v92
	v_fma_f32 v148, v148, v94, v92
	v_mul_f32 v92, v120, v107
	v_fma_f32 v92, v113, v99, v92
	v_fma_f32 v149, v149, v95, v92
	v_mul_f32 v92, v121, v107
	v_fma_f32 v92, v112, v99, v92
	v_fma_f32 v150, v150, v95, v92
	v_mul_f32 v92, v124, v80
	v_mul_f32 v80, v125, v80
	v_fma_f32 v92, v141, v82, v92
	v_fma_f32 v80, v148, v82, v80
	v_fma_f32 v82, v149, v83, v93
	v_fma_f32 v81, v150, v83, v81
	v_add_f32_e32 v82, v92, v82
	v_add_f32_e32 v83, v80, v81
	v_mov_b32_e32 v81, 0
	v_add_f32_dpp v80, v82, v82 row_ror:8 row_mask:0xf bank_mask:0xf bound_ctrl:1
	v_add_f32_dpp v82, v83, v83 row_ror:8 row_mask:0xf bank_mask:0xf bound_ctrl:1
	v_mov_b32_e32 v83, 0
	v_add_f32_dpp v80, v80, v80 row_ror:4 row_mask:0xf bank_mask:0xf bound_ctrl:1
	v_add_f32_dpp v82, v82, v82 row_ror:4 row_mask:0xf bank_mask:0xf bound_ctrl:1
	s_nop 0
	v_add_f32_dpp v80, v80, v80 row_ror:2 row_mask:0xf bank_mask:0xf bound_ctrl:1
	v_add_f32_dpp v82, v82, v82 row_ror:2 row_mask:0xf bank_mask:0xf bound_ctrl:1
	s_nop 0
	v_mov_b32_dpp v81, v80 row_ror:1 row_mask:0xf bank_mask:0xf
	v_mov_b32_dpp v83, v82 row_ror:1 row_mask:0xf bank_mask:0xf
	s_and_saveexec_b64 s[8:9], s[40:41]
	v_add_f32_e32 v82, v82, v83
	v_add_f32_e32 v80, v80, v81
	ds_write2_b32 v186, v80, v82 offset0:32 offset1:48
	s_or_b64 exec, exec, s[8:9]
	s_waitcnt lgkmcnt(4)
	v_mul_f32 v151, v124, v116
	v_mul_f32 v116, v125, v116
	v_mul_f32 v152, v126, v117
	v_mul_f32 v117, v127, v117
	ds_read_b128 v[92:95], v134 offset:2816
	ds_read_b128 v[112:115], v134 offset:6912
	ds_read_b128 v[96:99], v134 offset:11008
	ds_read_b128 v[104:107], v134 offset:15104
	ds_read_b128 v[80:83], v134 offset:19200
	ds_read2_b32 v[120:121], v187 offset0:96 offset1:112
	v_fma_f32 v151, v141, v118, v151
	v_fma_f32 v116, v148, v118, v116
	v_fma_f32 v118, v149, v119, v152
	v_fma_f32 v117, v150, v119, v117
	v_add_f32_e32 v118, v151, v118
	v_add_f32_e32 v116, v116, v117
	s_nop 0
	v_add_f32_dpp v117, v118, v118 row_ror:8 row_mask:0xf bank_mask:0xf bound_ctrl:1
	v_add_f32_dpp v116, v116, v116 row_ror:8 row_mask:0xf bank_mask:0xf bound_ctrl:1
	s_waitcnt lgkmcnt(6)
	v_mul_f32 v118, v122, v108
	v_mul_f32 v108, v123, v108
	v_add_f32_dpp v117, v117, v117 row_ror:4 row_mask:0xf bank_mask:0xf bound_ctrl:1
	v_add_f32_dpp v116, v116, v116 row_ror:4 row_mask:0xf bank_mask:0xf bound_ctrl:1
	s_nop 0
	v_add_f32_dpp v117, v117, v117 row_ror:2 row_mask:0xf bank_mask:0xf bound_ctrl:1
	v_add_f32_dpp v116, v116, v116 row_ror:2 row_mask:0xf bank_mask:0xf bound_ctrl:1
	s_nop 0
	v_add_f32_dpp v117, v117, v117 row_ror:1 row_mask:0xf bank_mask:0xf bound_ctrl:1
	v_add_f32_dpp v116, v116, v116 row_ror:1 row_mask:0xf bank_mask:0xf bound_ctrl:1
	v_fma_f32 v118, v117, v100, v118
	v_fma_f32 v100, v116, v100, v108
	v_fma_f32 v124, v124, v88, v118
	v_fma_f32 v125, v125, v88, v100
	v_mul_f32 v88, v122, v109
	v_fma_f32 v88, v117, v101, v88
	v_fma_f32 v126, v126, v89, v88
	v_mul_f32 v88, v123, v109
	v_fma_f32 v88, v116, v101, v88
	v_fma_f32 v127, v127, v89, v88
	v_mul_f32 v88, v122, v110
	v_mul_f32 v89, v126, v85
	v_fma_f32 v88, v117, v102, v88
	v_mul_f32 v85, v127, v85
	v_fma_f32 v141, v141, v90, v88
	v_mul_f32 v88, v123, v110
	v_fma_f32 v88, v116, v102, v88
	v_fma_f32 v148, v148, v90, v88
	v_mul_f32 v88, v122, v111
	v_fma_f32 v88, v117, v103, v88
	v_fma_f32 v149, v149, v91, v88
	v_mul_f32 v88, v123, v111
	v_fma_f32 v88, v116, v103, v88
	v_fma_f32 v150, v150, v91, v88
	v_mul_f32 v88, v124, v84
	v_mul_f32 v84, v125, v84
	v_fma_f32 v88, v141, v86, v88
	v_fma_f32 v84, v148, v86, v84
	v_fma_f32 v86, v149, v87, v89
	v_fma_f32 v85, v150, v87, v85
	v_add_f32_e32 v86, v88, v86
	v_add_f32_e32 v87, v84, v85
	v_mov_b32_e32 v85, 0
	v_add_f32_dpp v84, v86, v86 row_ror:8 row_mask:0xf bank_mask:0xf bound_ctrl:1
	v_add_f32_dpp v86, v87, v87 row_ror:8 row_mask:0xf bank_mask:0xf bound_ctrl:1
	v_mov_b32_e32 v87, 0
	v_add_f32_dpp v84, v84, v84 row_ror:4 row_mask:0xf bank_mask:0xf bound_ctrl:1
	v_add_f32_dpp v86, v86, v86 row_ror:4 row_mask:0xf bank_mask:0xf bound_ctrl:1
	s_nop 0
	v_add_f32_dpp v84, v84, v84 row_ror:2 row_mask:0xf bank_mask:0xf bound_ctrl:1
	v_add_f32_dpp v86, v86, v86 row_ror:2 row_mask:0xf bank_mask:0xf bound_ctrl:1
	s_nop 0
	v_mov_b32_dpp v85, v84 row_ror:1 row_mask:0xf bank_mask:0xf
	v_mov_b32_dpp v87, v86 row_ror:1 row_mask:0xf bank_mask:0xf
	s_and_saveexec_b64 s[8:9], s[40:41]
	v_add_f32_e32 v86, v86, v87
	v_add_f32_e32 v84, v84, v85
	ds_write2_b32 v186, v84, v86 offset0:64 offset1:80
	s_or_b64 exec, exec, s[8:9]
	s_waitcnt lgkmcnt(4)
	v_mul_f32 v151, v124, v112
	v_mul_f32 v112, v125, v112
	v_mul_f32 v152, v126, v113
	v_mul_f32 v113, v127, v113
	ds_read_b128 v[88:91], v134 offset:3072
	ds_read_b128 v[116:119], v134 offset:7168
	ds_read_b128 v[100:103], v134 offset:11264
	ds_read_b128 v[108:111], v134 offset:15360
	ds_read_b128 v[84:87], v134 offset:19456
	ds_read2_b32 v[122:123], v187 offset0:128 offset1:144
	v_fma_f32 v151, v141, v114, v151
	v_fma_f32 v112, v148, v114, v112
	v_fma_f32 v114, v149, v115, v152
	v_fma_f32 v113, v150, v115, v113
	v_add_f32_e32 v114, v151, v114
	v_add_f32_e32 v112, v112, v113
	s_nop 0
	v_add_f32_dpp v113, v114, v114 row_ror:8 row_mask:0xf bank_mask:0xf bound_ctrl:1
	v_add_f32_dpp v112, v112, v112 row_ror:8 row_mask:0xf bank_mask:0xf bound_ctrl:1
	s_waitcnt lgkmcnt(6)
	v_mul_f32 v114, v120, v104
	v_mul_f32 v104, v121, v104
	v_add_f32_dpp v113, v113, v113 row_ror:4 row_mask:0xf bank_mask:0xf bound_ctrl:1
	v_add_f32_dpp v112, v112, v112 row_ror:4 row_mask:0xf bank_mask:0xf bound_ctrl:1
	s_nop 0
	v_add_f32_dpp v113, v113, v113 row_ror:2 row_mask:0xf bank_mask:0xf bound_ctrl:1
	v_add_f32_dpp v112, v112, v112 row_ror:2 row_mask:0xf bank_mask:0xf bound_ctrl:1
	s_nop 0
	v_add_f32_dpp v113, v113, v113 row_ror:1 row_mask:0xf bank_mask:0xf bound_ctrl:1
	v_add_f32_dpp v112, v112, v112 row_ror:1 row_mask:0xf bank_mask:0xf bound_ctrl:1
	v_fma_f32 v114, v113, v96, v114
	v_fma_f32 v96, v112, v96, v104
	v_fma_f32 v124, v124, v92, v114
	v_fma_f32 v125, v125, v92, v96
	v_mul_f32 v92, v120, v105
	v_fma_f32 v92, v113, v97, v92
	v_fma_f32 v126, v126, v93, v92
	v_mul_f32 v92, v121, v105
	v_fma_f32 v92, v112, v97, v92
	v_fma_f32 v127, v127, v93, v92
	v_mul_f32 v92, v120, v106
	v_mul_f32 v93, v126, v81
	v_fma_f32 v92, v113, v98, v92
	v_mul_f32 v81, v127, v81
	v_fma_f32 v141, v141, v94, v92
	v_mul_f32 v92, v121, v106
	v_fma_f32 v92, v112, v98, v92
	v_fma_f32 v148, v148, v94, v92
	v_mul_f32 v92, v120, v107
	v_fma_f32 v92, v113, v99, v92
	v_fma_f32 v149, v149, v95, v92
	v_mul_f32 v92, v121, v107
	v_fma_f32 v92, v112, v99, v92
	v_fma_f32 v150, v150, v95, v92
	v_mul_f32 v92, v124, v80
	v_mul_f32 v80, v125, v80
	v_fma_f32 v92, v141, v82, v92
	v_fma_f32 v80, v148, v82, v80
	v_fma_f32 v82, v149, v83, v93
	v_fma_f32 v81, v150, v83, v81
	v_add_f32_e32 v82, v92, v82
	v_add_f32_e32 v83, v80, v81
	v_mov_b32_e32 v81, 0
	v_add_f32_dpp v80, v82, v82 row_ror:8 row_mask:0xf bank_mask:0xf bound_ctrl:1
	v_add_f32_dpp v82, v83, v83 row_ror:8 row_mask:0xf bank_mask:0xf bound_ctrl:1
	v_mov_b32_e32 v83, 0
	v_add_f32_dpp v80, v80, v80 row_ror:4 row_mask:0xf bank_mask:0xf bound_ctrl:1
	v_add_f32_dpp v82, v82, v82 row_ror:4 row_mask:0xf bank_mask:0xf bound_ctrl:1
	s_nop 0
	v_add_f32_dpp v80, v80, v80 row_ror:2 row_mask:0xf bank_mask:0xf bound_ctrl:1
	v_add_f32_dpp v82, v82, v82 row_ror:2 row_mask:0xf bank_mask:0xf bound_ctrl:1
	s_nop 0
	v_mov_b32_dpp v81, v80 row_ror:1 row_mask:0xf bank_mask:0xf
	v_mov_b32_dpp v83, v82 row_ror:1 row_mask:0xf bank_mask:0xf
	s_and_saveexec_b64 s[8:9], s[40:41]
	v_add_f32_e32 v82, v82, v83
	v_add_f32_e32 v80, v80, v81
	ds_write2_b32 v186, v80, v82 offset0:96 offset1:112
	s_or_b64 exec, exec, s[8:9]
	s_waitcnt lgkmcnt(4)
	v_mul_f32 v151, v124, v116
	v_mul_f32 v116, v125, v116
	v_mul_f32 v152, v126, v117
	v_mul_f32 v117, v127, v117
	ds_read_b128 v[92:95], v134 offset:3328
	ds_read_b128 v[112:115], v134 offset:7424
	ds_read_b128 v[96:99], v134 offset:11520
	ds_read_b128 v[104:107], v134 offset:15616
	ds_read_b128 v[80:83], v134 offset:19712
	ds_read2_b32 v[120:121], v187 offset0:160 offset1:176
	v_fma_f32 v151, v141, v118, v151
	v_fma_f32 v116, v148, v118, v116
	v_fma_f32 v118, v149, v119, v152
	v_fma_f32 v117, v150, v119, v117
	v_add_f32_e32 v118, v151, v118
	v_add_f32_e32 v116, v116, v117
	s_nop 0
	v_add_f32_dpp v117, v118, v118 row_ror:8 row_mask:0xf bank_mask:0xf bound_ctrl:1
	v_add_f32_dpp v116, v116, v116 row_ror:8 row_mask:0xf bank_mask:0xf bound_ctrl:1
	s_waitcnt lgkmcnt(6)
	v_mul_f32 v118, v122, v108
	v_mul_f32 v108, v123, v108
	v_add_f32_dpp v117, v117, v117 row_ror:4 row_mask:0xf bank_mask:0xf bound_ctrl:1
	v_add_f32_dpp v116, v116, v116 row_ror:4 row_mask:0xf bank_mask:0xf bound_ctrl:1
	s_nop 0
	v_add_f32_dpp v117, v117, v117 row_ror:2 row_mask:0xf bank_mask:0xf bound_ctrl:1
	v_add_f32_dpp v116, v116, v116 row_ror:2 row_mask:0xf bank_mask:0xf bound_ctrl:1
	s_nop 0
	v_add_f32_dpp v117, v117, v117 row_ror:1 row_mask:0xf bank_mask:0xf bound_ctrl:1
	v_add_f32_dpp v116, v116, v116 row_ror:1 row_mask:0xf bank_mask:0xf bound_ctrl:1
	v_fma_f32 v118, v117, v100, v118
	v_fma_f32 v100, v116, v100, v108
	v_fma_f32 v124, v124, v88, v118
	v_fma_f32 v125, v125, v88, v100
	v_mul_f32 v88, v122, v109
	v_fma_f32 v88, v117, v101, v88
	v_fma_f32 v126, v126, v89, v88
	v_mul_f32 v88, v123, v109
	v_fma_f32 v88, v116, v101, v88
	v_fma_f32 v127, v127, v89, v88
	v_mul_f32 v88, v122, v110
	v_mul_f32 v89, v126, v85
	v_fma_f32 v88, v117, v102, v88
	v_mul_f32 v85, v127, v85
	v_fma_f32 v141, v141, v90, v88
	v_mul_f32 v88, v123, v110
	v_fma_f32 v88, v116, v102, v88
	v_fma_f32 v148, v148, v90, v88
	v_mul_f32 v88, v122, v111
	v_fma_f32 v88, v117, v103, v88
	v_fma_f32 v149, v149, v91, v88
	v_mul_f32 v88, v123, v111
	v_fma_f32 v88, v116, v103, v88
	v_fma_f32 v150, v150, v91, v88
	v_mul_f32 v88, v124, v84
	v_mul_f32 v84, v125, v84
	v_fma_f32 v88, v141, v86, v88
	v_fma_f32 v84, v148, v86, v84
	v_fma_f32 v86, v149, v87, v89
	v_fma_f32 v85, v150, v87, v85
	v_add_f32_e32 v86, v88, v86
	v_add_f32_e32 v87, v84, v85
	v_mov_b32_e32 v85, 0
	v_add_f32_dpp v84, v86, v86 row_ror:8 row_mask:0xf bank_mask:0xf bound_ctrl:1
	v_add_f32_dpp v86, v87, v87 row_ror:8 row_mask:0xf bank_mask:0xf bound_ctrl:1
	v_mov_b32_e32 v87, 0
	v_add_f32_dpp v84, v84, v84 row_ror:4 row_mask:0xf bank_mask:0xf bound_ctrl:1
	v_add_f32_dpp v86, v86, v86 row_ror:4 row_mask:0xf bank_mask:0xf bound_ctrl:1
	s_nop 0
	v_add_f32_dpp v84, v84, v84 row_ror:2 row_mask:0xf bank_mask:0xf bound_ctrl:1
	v_add_f32_dpp v86, v86, v86 row_ror:2 row_mask:0xf bank_mask:0xf bound_ctrl:1
	s_nop 0
	v_mov_b32_dpp v85, v84 row_ror:1 row_mask:0xf bank_mask:0xf
	v_mov_b32_dpp v87, v86 row_ror:1 row_mask:0xf bank_mask:0xf
	s_and_saveexec_b64 s[8:9], s[40:41]
	v_add_f32_e32 v86, v86, v87
	v_add_f32_e32 v84, v84, v85
	ds_write2_b32 v186, v84, v86 offset0:128 offset1:144
	s_or_b64 exec, exec, s[8:9]
	s_waitcnt lgkmcnt(4)
	v_mul_f32 v151, v124, v112
	v_mul_f32 v112, v125, v112
	v_mul_f32 v152, v126, v113
	v_mul_f32 v113, v127, v113
	ds_read_b128 v[88:91], v134 offset:3584
	ds_read_b128 v[116:119], v134 offset:7680
	ds_read_b128 v[100:103], v134 offset:11776
	ds_read_b128 v[108:111], v134 offset:15872
	ds_read_b128 v[84:87], v134 offset:19968
	ds_read2_b32 v[122:123], v187 offset0:192 offset1:208
	v_fma_f32 v151, v141, v114, v151
	v_fma_f32 v112, v148, v114, v112
	v_fma_f32 v114, v149, v115, v152
	v_fma_f32 v113, v150, v115, v113
	v_add_f32_e32 v114, v151, v114
	v_add_f32_e32 v112, v112, v113
	s_nop 0
	v_add_f32_dpp v113, v114, v114 row_ror:8 row_mask:0xf bank_mask:0xf bound_ctrl:1
	v_add_f32_dpp v112, v112, v112 row_ror:8 row_mask:0xf bank_mask:0xf bound_ctrl:1
	s_waitcnt lgkmcnt(6)
	v_mul_f32 v114, v120, v104
	v_mul_f32 v104, v121, v104
	v_add_f32_dpp v113, v113, v113 row_ror:4 row_mask:0xf bank_mask:0xf bound_ctrl:1
	v_add_f32_dpp v112, v112, v112 row_ror:4 row_mask:0xf bank_mask:0xf bound_ctrl:1
	s_nop 0
	v_add_f32_dpp v113, v113, v113 row_ror:2 row_mask:0xf bank_mask:0xf bound_ctrl:1
	v_add_f32_dpp v112, v112, v112 row_ror:2 row_mask:0xf bank_mask:0xf bound_ctrl:1
	s_nop 0
	v_add_f32_dpp v113, v113, v113 row_ror:1 row_mask:0xf bank_mask:0xf bound_ctrl:1
	v_add_f32_dpp v112, v112, v112 row_ror:1 row_mask:0xf bank_mask:0xf bound_ctrl:1
	v_fma_f32 v114, v113, v96, v114
	v_fma_f32 v96, v112, v96, v104
	v_fma_f32 v124, v124, v92, v114
	v_fma_f32 v125, v125, v92, v96
	v_mul_f32 v92, v120, v105
	v_fma_f32 v92, v113, v97, v92
	v_fma_f32 v126, v126, v93, v92
	v_mul_f32 v92, v121, v105
	v_fma_f32 v92, v112, v97, v92
	v_fma_f32 v127, v127, v93, v92
	v_mul_f32 v92, v120, v106
	v_mul_f32 v93, v126, v81
	v_fma_f32 v92, v113, v98, v92
	v_mul_f32 v81, v127, v81
	v_fma_f32 v141, v141, v94, v92
	v_mul_f32 v92, v121, v106
	v_fma_f32 v92, v112, v98, v92
	v_fma_f32 v148, v148, v94, v92
	v_mul_f32 v92, v120, v107
	v_fma_f32 v92, v113, v99, v92
	v_fma_f32 v149, v149, v95, v92
	v_mul_f32 v92, v121, v107
	v_fma_f32 v92, v112, v99, v92
	v_fma_f32 v150, v150, v95, v92
	v_mul_f32 v92, v124, v80
	v_mul_f32 v80, v125, v80
	v_fma_f32 v92, v141, v82, v92
	v_fma_f32 v80, v148, v82, v80
	v_fma_f32 v82, v149, v83, v93
	v_fma_f32 v81, v150, v83, v81
	v_add_f32_e32 v82, v92, v82
	v_add_f32_e32 v83, v80, v81
	v_mov_b32_e32 v81, 0
	v_add_f32_dpp v80, v82, v82 row_ror:8 row_mask:0xf bank_mask:0xf bound_ctrl:1
	v_add_f32_dpp v82, v83, v83 row_ror:8 row_mask:0xf bank_mask:0xf bound_ctrl:1
	v_mov_b32_e32 v83, 0
	v_add_f32_dpp v80, v80, v80 row_ror:4 row_mask:0xf bank_mask:0xf bound_ctrl:1
	v_add_f32_dpp v82, v82, v82 row_ror:4 row_mask:0xf bank_mask:0xf bound_ctrl:1
	s_nop 0
	v_add_f32_dpp v80, v80, v80 row_ror:2 row_mask:0xf bank_mask:0xf bound_ctrl:1
	v_add_f32_dpp v82, v82, v82 row_ror:2 row_mask:0xf bank_mask:0xf bound_ctrl:1
	s_nop 0
	v_mov_b32_dpp v81, v80 row_ror:1 row_mask:0xf bank_mask:0xf
	v_mov_b32_dpp v83, v82 row_ror:1 row_mask:0xf bank_mask:0xf
	s_and_saveexec_b64 s[8:9], s[40:41]
	v_add_f32_e32 v82, v82, v83
	v_add_f32_e32 v80, v80, v81
	ds_write2_b32 v186, v80, v82 offset0:160 offset1:176
	s_or_b64 exec, exec, s[8:9]
	s_waitcnt lgkmcnt(4)
	v_mul_f32 v151, v124, v116
	v_mul_f32 v116, v125, v116
	v_mul_f32 v152, v126, v117
	v_mul_f32 v117, v127, v117
	ds_read_b128 v[92:95], v134 offset:3840
	ds_read_b128 v[112:115], v134 offset:7936
	ds_read_b128 v[96:99], v134 offset:12032
	ds_read_b128 v[104:107], v134 offset:16128
	ds_read_b128 v[80:83], v134 offset:20224
	ds_read2_b32 v[120:121], v187 offset0:224 offset1:240
	v_fma_f32 v116, v148, v118, v116
	v_fma_f32 v151, v141, v118, v151
	v_fma_f32 v118, v149, v119, v152
	v_fma_f32 v117, v150, v119, v117
	v_add_f32_e32 v118, v151, v118
	v_add_f32_e32 v116, v116, v117
	s_nop 1
	v_add_f32_dpp v116, v116, v116 row_ror:8 row_mask:0xf bank_mask:0xf bound_ctrl:1
	v_add_f32_dpp v117, v118, v118 row_ror:8 row_mask:0xf bank_mask:0xf bound_ctrl:1
	s_nop 0
	v_add_f32_dpp v116, v116, v116 row_ror:4 row_mask:0xf bank_mask:0xf bound_ctrl:1
	v_add_f32_dpp v117, v117, v117 row_ror:4 row_mask:0xf bank_mask:0xf bound_ctrl:1
	s_nop 0
	v_add_f32_dpp v116, v116, v116 row_ror:2 row_mask:0xf bank_mask:0xf bound_ctrl:1
	v_add_f32_dpp v117, v117, v117 row_ror:2 row_mask:0xf bank_mask:0xf bound_ctrl:1
	s_nop 0
	v_add_f32_dpp v118, v116, v116 row_ror:1 row_mask:0xf bank_mask:0xf bound_ctrl:1
	s_waitcnt lgkmcnt(6)
	v_mul_f32 v116, v122, v108
	v_add_f32_dpp v117, v117, v117 row_ror:1 row_mask:0xf bank_mask:0xf bound_ctrl:1
	v_fma_f32 v116, v117, v100, v116
	v_mul_f32 v108, v123, v108
	v_fma_f32 v100, v118, v100, v108
	v_fma_f32 v116, v124, v88, v116
	v_mul_f32 v108, v123, v109
	v_fma_f32 v88, v125, v88, v100
	v_mul_f32 v100, v122, v109
	v_fma_f32 v100, v117, v101, v100
	v_fma_f32 v101, v118, v101, v108
	v_mul_f32 v108, v123, v110
	v_fma_f32 v100, v126, v89, v100
	v_fma_f32 v89, v127, v89, v101
	v_mul_f32 v101, v122, v110
	v_fma_f32 v101, v117, v102, v101
	v_fma_f32 v102, v118, v102, v108
	v_mul_f32 v108, v123, v111
	v_fma_f32 v101, v141, v90, v101
	v_fma_f32 v90, v148, v90, v102
	v_mul_f32 v102, v122, v111
	v_fma_f32 v102, v117, v103, v102
	v_fma_f32 v103, v118, v103, v108
	v_mul_f32 v108, v100, v85
	v_mul_f32 v85, v89, v85
	v_fma_f32 v102, v149, v91, v102
	v_fma_f32 v91, v150, v91, v103
	v_mul_f32 v103, v116, v84
	v_mul_f32 v84, v88, v84
	v_fma_f32 v103, v101, v86, v103
	v_fma_f32 v84, v90, v86, v84
	v_fma_f32 v86, v102, v87, v108
	v_fma_f32 v85, v91, v87, v85
	v_add_f32_e32 v86, v103, v86
	v_add_f32_e32 v87, v84, v85
	v_mov_b32_e32 v85, 0
	v_add_f32_dpp v84, v86, v86 row_ror:8 row_mask:0xf bank_mask:0xf bound_ctrl:1
	v_add_f32_dpp v86, v87, v87 row_ror:8 row_mask:0xf bank_mask:0xf bound_ctrl:1
	v_mov_b32_e32 v87, 0
	v_add_f32_dpp v84, v84, v84 row_ror:4 row_mask:0xf bank_mask:0xf bound_ctrl:1
	v_add_f32_dpp v86, v86, v86 row_ror:4 row_mask:0xf bank_mask:0xf bound_ctrl:1
	s_nop 0
	v_add_f32_dpp v84, v84, v84 row_ror:2 row_mask:0xf bank_mask:0xf bound_ctrl:1
	v_add_f32_dpp v86, v86, v86 row_ror:2 row_mask:0xf bank_mask:0xf bound_ctrl:1
	s_nop 0
	v_mov_b32_dpp v85, v84 row_ror:1 row_mask:0xf bank_mask:0xf
	v_mov_b32_dpp v87, v86 row_ror:1 row_mask:0xf bank_mask:0xf
	s_and_saveexec_b64 s[8:9], s[40:41]
	v_add_f32_e32 v86, v86, v87
	v_add_f32_e32 v84, v84, v85
	ds_write2_b32 v186, v84, v86 offset0:192 offset1:208
	s_or_b64 exec, exec, s[8:9]
	s_waitcnt lgkmcnt(4)
	v_mul_f32 v84, v116, v112
	v_mul_f32 v86, v100, v113
	v_mul_f32 v85, v88, v112
	v_mul_f32 v87, v89, v113
	v_fma_f32 v84, v101, v114, v84
	v_fma_f32 v86, v102, v115, v86
	v_fma_f32 v85, v90, v114, v85
	v_fma_f32 v87, v91, v115, v87
	v_add_f32_e32 v84, v84, v86
	v_add_f32_e32 v85, v85, v87
	s_nop 0
	v_add_f32_dpp v84, v84, v84 row_ror:8 row_mask:0xf bank_mask:0xf bound_ctrl:1
	s_waitcnt lgkmcnt(0)
	v_mul_f32 v86, v120, v105
	v_mul_f32 v87, v121, v105
	v_add_f32_dpp v84, v84, v84 row_ror:4 row_mask:0xf bank_mask:0xf bound_ctrl:1
	s_nop 1
	v_add_f32_dpp v84, v84, v84 row_ror:2 row_mask:0xf bank_mask:0xf bound_ctrl:1
	s_nop 1
	v_add_f32_dpp v103, v84, v84 row_ror:1 row_mask:0xf bank_mask:0xf bound_ctrl:1
	v_add_f32_dpp v84, v85, v85 row_ror:8 row_mask:0xf bank_mask:0xf bound_ctrl:1
	v_mul_f32 v85, v121, v104
	v_fma_f32 v86, v103, v97, v86
	v_fma_f32 v86, v100, v93, v86
	v_add_f32_dpp v84, v84, v84 row_ror:4 row_mask:0xf bank_mask:0xf bound_ctrl:1
	s_nop 1
	v_add_f32_dpp v84, v84, v84 row_ror:2 row_mask:0xf bank_mask:0xf bound_ctrl:1
	s_nop 1
	v_add_f32_dpp v108, v84, v84 row_ror:1 row_mask:0xf bank_mask:0xf bound_ctrl:1
	v_fma_f32 v85, v108, v96, v85
	v_mul_f32 v84, v120, v104
	v_fma_f32 v87, v108, v97, v87
	v_fma_f32 v85, v88, v92, v85
	v_mul_f32 v88, v120, v106
	v_fma_f32 v84, v103, v96, v84
	v_fma_f32 v87, v89, v93, v87
	v_mul_f32 v89, v86, v81
	v_fma_f32 v88, v103, v98, v88
	v_fma_f32 v84, v116, v92, v84
	v_mul_f32 v81, v87, v81
	v_fma_f32 v96, v101, v94, v88
	v_mul_f32 v88, v121, v106
	v_fma_f32 v88, v108, v98, v88
	v_fma_f32 v97, v90, v94, v88
	v_mul_f32 v88, v120, v107
	v_fma_f32 v88, v103, v99, v88
	v_fma_f32 v98, v102, v95, v88
	v_mul_f32 v88, v121, v107
	v_fma_f32 v88, v108, v99, v88
	v_fma_f32 v99, v91, v95, v88
	v_mul_f32 v88, v84, v80
	v_mul_f32 v80, v85, v80
	v_fma_f32 v88, v96, v82, v88
	v_fma_f32 v80, v97, v82, v80
	v_fma_f32 v82, v98, v83, v89
	v_fma_f32 v81, v99, v83, v81
	v_add_f32_e32 v82, v88, v82
	v_add_f32_e32 v83, v80, v81
	v_mov_b32_e32 v81, 0
	v_add_f32_dpp v80, v82, v82 row_ror:8 row_mask:0xf bank_mask:0xf bound_ctrl:1
	v_add_f32_dpp v82, v83, v83 row_ror:8 row_mask:0xf bank_mask:0xf bound_ctrl:1
	v_mov_b32_e32 v83, 0
	v_add_f32_dpp v80, v80, v80 row_ror:4 row_mask:0xf bank_mask:0xf bound_ctrl:1
	v_add_f32_dpp v82, v82, v82 row_ror:4 row_mask:0xf bank_mask:0xf bound_ctrl:1
	s_nop 0
	v_add_f32_dpp v80, v80, v80 row_ror:2 row_mask:0xf bank_mask:0xf bound_ctrl:1
	v_add_f32_dpp v82, v82, v82 row_ror:2 row_mask:0xf bank_mask:0xf bound_ctrl:1
	s_nop 0
	v_mov_b32_dpp v81, v80 row_ror:1 row_mask:0xf bank_mask:0xf
	v_mov_b32_dpp v83, v82 row_ror:1 row_mask:0xf bank_mask:0xf
	s_and_saveexec_b64 s[8:9], s[40:41]
	v_add_f32_e32 v82, v82, v83
	v_add_f32_e32 v80, v80, v81
	ds_write2_b32 v186, v80, v82 offset0:224 offset1:240
	s_or_b64 exec, exec, s[8:9]
	s_and_saveexec_b64 s[8:9], s[38:39]
	s_cbranch_execz .LBB0_375
	v_add_f32_e32 v88, v0, v44
	v_min_f32_e32 v92, 0, v88
	v_mul_f32_e64 v88, |v88|, s62
	v_exp_f32_e32 v88, v88
	v_add_f32_e32 v89, v1, v45
	v_add_f32_e32 v90, v2, v46
	v_add_f32_e32 v91, v3, v47
	v_add_f32_e32 v88, 1.0, v88
	v_cmp_gt_f32_e32 vcc, s5, v88
	s_mov_b32 s4, 0xf800000
	v_add_f32_e32 v80, v4, v28
	v_cndmask_b32_e64 v93, 0, 32, vcc
	v_ldexp_f32 v88, v88, v93
	v_log_f32_e32 v88, v88
	v_mul_f32_e32 v80, 0xbfb8aa3b, v80
	v_exp_f32_e32 v82, v80
	v_add_f32_e32 v80, v5, v29
	v_mul_f32_e32 v93, 0x3f317217, v88
	v_fma_f32 v93, v88, s76, -v93
	v_fmac_f32_e32 v93, 0x3377d1cf, v88
	v_fmac_f32_e32 v93, 0x3f317217, v88
	v_cmp_lt_f32_e64 s[42:43], |v88|, s77
	v_mul_f32_e32 v80, 0xbfb8aa3b, v80
	v_exp_f32_e32 v83, v80
	v_cndmask_b32_e64 v88, v88, v93, s[42:43]
	v_cndmask_b32_e32 v93, 0, v171, vcc
	v_sub_f32_e32 v88, v88, v93
	v_sub_f32_e32 v88, v92, v88
	v_min_f32_e32 v92, 0, v89
	v_mul_f32_e64 v89, |v89|, s62
	v_exp_f32_e32 v89, v89
	v_add_f32_e32 v88, -0.5, v88
	v_mul_f32_e32 v88, 0x3fb8aa3b, v88
	v_exp_f32_e32 v88, v88
	v_add_f32_e32 v89, 1.0, v89
	v_cmp_gt_f32_e32 vcc, s5, v89
	v_pk_add_f32 v[82:83], v[82:83], 1.0 op_sel_hi:[1,0]
	v_mul_f32_e32 v88, 0xbfb8aa3b, v88
	v_cndmask_b32_e64 v93, 0, 32, vcc
	v_ldexp_f32 v89, v89, v93
	v_log_f32_e32 v89, v89
	v_exp_f32_e32 v88, v88
	v_add_f32_e32 v80, v6, v30
	v_add_f32_e32 v81, v7, v31
	v_mul_f32_e32 v93, 0x3f317217, v89
	v_fma_f32 v93, v89, s76, -v93
	v_fmac_f32_e32 v93, 0x3377d1cf, v89
	v_fmac_f32_e32 v93, 0x3f317217, v89
	v_cmp_lt_f32_e64 s[42:43], |v89|, s77
	v_mul_f32_e32 v80, 0xbfb8aa3b, v80
	v_mul_f32_e32 v81, 0xbfb8aa3b, v81
	v_cndmask_b32_e64 v89, v89, v93, s[42:43]
	v_cndmask_b32_e32 v93, 0, v171, vcc
	v_sub_f32_e32 v89, v89, v93
	v_sub_f32_e32 v89, v92, v89
	v_min_f32_e32 v92, 0, v90
	v_mul_f32_e64 v90, |v90|, s62
	v_exp_f32_e32 v90, v90
	v_add_f32_e32 v89, -0.5, v89
	v_mul_f32_e32 v89, 0x3fb8aa3b, v89
	v_exp_f32_e32 v89, v89
	v_add_f32_e32 v90, 1.0, v90
	v_cmp_gt_f32_e32 vcc, s5, v90
	v_exp_f32_e32 v80, v80
	v_mul_f32_e32 v89, 0xbfb8aa3b, v89
	v_cndmask_b32_e64 v93, 0, 32, vcc
	v_ldexp_f32 v90, v90, v93
	v_log_f32_e32 v90, v90
	v_exp_f32_e32 v89, v89
	v_exp_f32_e32 v81, v81
	v_mul_f32_e32 v93, 0x3f317217, v90
	v_fma_f32 v93, v90, s76, -v93
	v_fmac_f32_e32 v93, 0x3377d1cf, v90
	v_fmac_f32_e32 v93, 0x3f317217, v90
	v_cmp_lt_f32_e64 s[42:43], |v90|, s77
	v_pk_add_f32 v[80:81], v[80:81], 1.0 op_sel_hi:[1,0]
	s_nop 0
	v_cndmask_b32_e64 v90, v90, v93, s[42:43]
	v_cndmask_b32_e32 v93, 0, v171, vcc
	v_sub_f32_e32 v90, v90, v93
	v_sub_f32_e32 v90, v92, v90
	v_min_f32_e32 v92, 0, v91
	v_mul_f32_e64 v91, |v91|, s62
	v_exp_f32_e32 v91, v91
	v_add_f32_e32 v90, -0.5, v90
	v_mul_f32_e32 v90, 0x3fb8aa3b, v90
	v_exp_f32_e32 v90, v90
	v_add_f32_e32 v91, 1.0, v91
	v_cmp_gt_f32_e32 vcc, s5, v91
	v_mul_f32_e32 v90, 0xbfb8aa3b, v90
	s_nop 0
	v_cndmask_b32_e64 v93, 0, 32, vcc
	v_ldexp_f32 v91, v91, v93
	v_log_f32_e32 v91, v91
	v_exp_f32_e32 v90, v90
	v_mul_f32_e32 v93, 0x3f317217, v91
	v_fma_f32 v93, v91, s76, -v93
	v_fmac_f32_e32 v93, 0x3377d1cf, v91
	v_fmac_f32_e32 v93, 0x3f317217, v91
	v_cmp_lt_f32_e64 s[42:43], |v91|, s77
	s_nop 1
	v_cndmask_b32_e64 v91, v91, v93, s[42:43]
	v_cndmask_b32_e32 v93, 0, v171, vcc
	v_sub_f32_e32 v91, v91, v93
	v_sub_f32_e32 v91, v92, v91
	v_add_f32_e32 v91, -0.5, v91
	v_mul_f32_e32 v91, 0x3fb8aa3b, v91
	v_exp_f32_e32 v91, v91
	v_pk_mul_f32 v[92:93], v[10:11], v[42:43]
	v_mul_f32_e32 v91, 0xbfb8aa3b, v91
	v_exp_f32_e32 v91, v91
	v_pk_mul_f32 v[94:95], v[92:93], v[92:93]
	ds_write_b128 v181, v[88:91] offset:22528
	v_pk_mul_f32 v[88:89], v[8:9], v[40:41]
	v_pk_mul_f32 v[90:91], v[88:89], v[88:89]
	v_add_f32_e32 v90, v91, v90
	v_add_f32_e32 v90, v94, v90
	v_add_f32_e32 v90, v95, v90
	s_nop 1
	v_add_f32_dpp v90, v90, v90 row_ror:8 row_mask:0xf bank_mask:0xf bound_ctrl:1
	s_nop 1
	v_add_f32_dpp v90, v90, v90 row_ror:4 row_mask:0xf bank_mask:0xf bound_ctrl:1
	s_nop 1
	v_add_f32_dpp v90, v90, v90 row_ror:2 row_mask:0xf bank_mask:0xf bound_ctrl:1
	s_nop 1
	v_add_f32_dpp v90, v90, v90 row_ror:1 row_mask:0xf bank_mask:0xf bound_ctrl:1
	v_cmp_gt_f32_e32 vcc, s4, v90
	v_mul_f32_e32 v91, 0x4f800000, v90
	s_nop 0
	v_cndmask_b32_e32 v90, v90, v91, vcc
	v_sqrt_f32_e32 v91, v90
	s_nop 0
	v_add_u32_e32 v94, -1, v91
	v_fma_f32 v95, -v94, v91, v90
	v_cmp_ge_f32_e64 s[42:43], 0, v95
	v_add_u32_e32 v95, 1, v91
	s_nop 0
	v_cndmask_b32_e64 v94, v91, v94, s[42:43]
	v_fma_f32 v91, -v95, v91, v90
	v_cmp_lt_f32_e64 s[42:43], 0, v91
	s_nop 1
	v_cndmask_b32_e64 v91, v94, v95, s[42:43]
	v_mul_f32_e32 v94, 0x37800000, v91
	v_cndmask_b32_e32 v91, v91, v94, vcc
	v_cmp_class_f32_e32 vcc, v90, v160
	s_nop 1
	v_cndmask_b32_e32 v90, v91, v90, vcc
	v_max_f32_e32 v90, 0x2b8cbccc, v90
	v_div_scale_f32 v91, s[22:23], v90, v90, 1.0
	v_rcp_f32_e32 v94, v91
	s_nop 0
	v_fma_f32 v95, -v91, v94, 1.0
	v_fmac_f32_e32 v94, v95, v94
	v_div_scale_f32 v95, vcc, 1.0, v90, 1.0
	v_mul_f32_e32 v100, v95, v94
	v_fma_f32 v101, -v91, v100, v95
	v_fmac_f32_e32 v100, v101, v94
	v_fma_f32 v91, -v91, v100, v95
	v_div_fmas_f32 v91, v91, v94, v100
	v_div_fixup_f32 v90, v91, v90, 1.0
	v_pk_mul_f32 v[94:95], v[88:89], v[90:91] op_sel_hi:[1,0]
	v_pk_mul_f32 v[92:93], v[92:93], v[90:91] op_sel_hi:[1,0]
	v_xor_b32_e32 v89, 0x80000000, v95
	v_xor_b32_e32 v88, 0x80000000, v94
	v_xor_b32_e32 v91, 0x80000000, v93
	v_xor_b32_e32 v90, 0x80000000, v92
	ds_write_b128 v181, v[88:91] offset:26624
	v_div_scale_f32 v88, s[22:23], v83, v83, 1.0
	v_rcp_f32_e32 v89, v88
	s_nop 0
	v_fma_f32 v90, -v88, v89, 1.0
	v_fmac_f32_e32 v89, v90, v89
	v_div_scale_f32 v90, vcc, 1.0, v83, 1.0
	v_mul_f32_e32 v91, v90, v89
	v_fma_f32 v100, -v88, v91, v90
	v_fmac_f32_e32 v91, v100, v89
	v_fma_f32 v88, -v88, v91, v90
	v_div_fmas_f32 v88, v88, v89, v91
	v_div_fixup_f32 v83, v88, v83, 1.0
	v_div_scale_f32 v88, s[22:23], v82, v82, 1.0
	v_rcp_f32_e32 v89, v88
	s_nop 0
	v_fma_f32 v90, -v88, v89, 1.0
	v_fmac_f32_e32 v89, v90, v89
	v_div_scale_f32 v90, vcc, 1.0, v82, 1.0
	v_mul_f32_e32 v91, v90, v89
	v_fma_f32 v100, -v88, v91, v90
	v_fmac_f32_e32 v91, v100, v89
	v_fma_f32 v88, -v88, v91, v90
	v_div_scale_f32 v90, s[22:23], v81, v81, 1.0
	v_div_fmas_f32 v88, v88, v89, v91
	v_rcp_f32_e32 v91, v90
	v_div_fixup_f32 v82, v88, v82, 1.0
	v_pk_mul_f32 v[88:89], v[82:83], v[94:95]
	v_fma_f32 v94, -v90, v91, 1.0
	v_fmac_f32_e32 v91, v94, v91
	v_div_scale_f32 v94, vcc, 1.0, v81, 1.0
	v_mul_f32_e32 v95, v94, v91
	v_fma_f32 v100, -v90, v95, v94
	v_fmac_f32_e32 v95, v100, v91
	v_fma_f32 v90, -v90, v95, v94
	v_div_fmas_f32 v90, v90, v91, v95
	v_div_fixup_f32 v95, v90, v81, 1.0
	v_div_scale_f32 v81, s[22:23], v80, v80, 1.0
	v_rcp_f32_e32 v90, v81
	s_nop 0
	v_fma_f32 v91, -v81, v90, 1.0
	v_fmac_f32_e32 v90, v91, v90
	v_div_scale_f32 v91, vcc, 1.0, v80, 1.0
	v_mul_f32_e32 v94, v91, v90
	v_fma_f32 v100, -v81, v94, v91
	v_fmac_f32_e32 v94, v100, v90
	v_fma_f32 v81, -v81, v94, v91
	v_div_fmas_f32 v81, v81, v90, v94
	v_div_fixup_f32 v94, v81, v80, 1.0
	v_pk_add_f32 v[80:81], v[82:83], -1.0 op_sel_hi:[1,0]
	v_pk_add_f32 v[82:83], v[94:95], -1.0 op_sel_hi:[1,0]
	v_pk_fma_f32 v[80:81], v[12:13], v[80:81], 1.0 op_sel_hi:[1,1,0]
	v_pk_fma_f32 v[82:83], v[14:15], v[82:83], 1.0 op_sel_hi:[1,1,0]
	v_pk_mul_f32 v[90:91], v[94:95], v[92:93]
	v_pk_mul_f32 v[80:81], v[40:41], v[80:81]
	v_pk_mul_f32 v[82:83], v[42:43], v[82:83]
	ds_write_b128 v181, v[88:91] offset:30720
	ds_write_b128 v181, v[80:83] offset:34816
	ds_write_b128 v181, v[16:19] offset:38912

.LBB0_381:
	ds_read2st64_b32 v[80:81], v179 offset0:176 offset1:180
	v_ashrrev_i32_e32 v127, 31, v126
	v_lshlrev_b64 v[82:83], 13, v[126:127]
	v_ashrrev_i32_e32 v125, 31, v124
	v_lshl_add_u64 v[82:83], v[144:145], 0, v[82:83]
	s_waitcnt lgkmcnt(0)
	global_store_dword v[82:83], v80, off
	v_lshlrev_b64 v[82:83], 13, v[124:125]
	v_lshl_add_u64 v[82:83], v[144:145], 0, v[82:83]
	global_store_dword v[82:83], v81, off
	ds_read_b128 v[104:107], v134 offset:22528
	ds_read_b128 v[88:91], v134 offset:22784
	ds_read_b128 v[108:111], v134 offset:26624
	ds_read_b128 v[112:115], v134 offset:26880
	ds_read_b128 v[116:119], v134 offset:30720
	ds_read_b128 v[92:95], v134 offset:30976
	ds_read_b128 v[150:153], v134 offset:34816
	ds_read_b128 v[100:103], v134 offset:35072
	ds_read_b128 v[192:195], v134 offset:38912
	ds_read_b128 v[80:83], v134 offset:39168
	s_waitcnt lgkmcnt(7)
	v_mul_f32 v122, v84, v108
	v_mul_f32 v108, v85, v108
	v_mul_f32 v123, v86, v109
	v_mul_f32 v109, v87, v109
	v_add_u32_e32 v190, 0xa800, v182
	v_fma_f32 v122, v96, v110, v122
	v_fma_f32 v108, v97, v110, v108
	v_fma_f32 v110, v98, v111, v123
	v_fma_f32 v109, v99, v111, v109
	ds_read2_b32 v[120:121], v190 offset0:32 offset1:48
	v_add_f32_e32 v110, v122, v110
	v_add_f32_e32 v111, v108, v109
	s_nop 0
	v_add_f32_dpp v110, v110, v110 row_ror:8 row_mask:0xf bank_mask:0xf bound_ctrl:1
	ds_read2_b32 v[108:109], v190 offset1:16
	v_add_f32_dpp v111, v111, v111 row_ror:8 row_mask:0xf bank_mask:0xf bound_ctrl:1
	v_add_f32_dpp v110, v110, v110 row_ror:4 row_mask:0xf bank_mask:0xf bound_ctrl:1
	s_waitcnt lgkmcnt(0)
	v_mul_f32 v122, v108, v150
	v_add_u32_e32 v188, 0xb800, v182
	v_add_f32_dpp v111, v111, v111 row_ror:4 row_mask:0xf bank_mask:0xf bound_ctrl:1
	v_add_f32_dpp v110, v110, v110 row_ror:2 row_mask:0xf bank_mask:0xf bound_ctrl:1
	s_nop 0
	v_add_f32_dpp v111, v111, v111 row_ror:2 row_mask:0xf bank_mask:0xf bound_ctrl:1
	v_add_f32_dpp v110, v110, v110 row_ror:1 row_mask:0xf bank_mask:0xf bound_ctrl:1
	v_fma_f32 v122, v110, v116, v122
	v_fma_f32 v122, v84, v104, v122
	v_mul_f32 v84, v109, v150
	v_add_f32_dpp v111, v111, v111 row_ror:1 row_mask:0xf bank_mask:0xf bound_ctrl:1
	v_fma_f32 v84, v111, v116, v84
	v_fma_f32 v123, v85, v104, v84
	v_mul_f32 v84, v108, v151
	v_fma_f32 v84, v110, v117, v84
	v_mul_f32 v85, v123, v192
	v_fma_f32 v125, v86, v105, v84
	v_mul_f32 v84, v109, v151
	v_fma_f32 v84, v111, v117, v84
	v_mul_f32 v86, v125, v193
	v_fma_f32 v127, v87, v105, v84
	v_mul_f32 v84, v108, v152
	v_fma_f32 v84, v110, v118, v84
	v_mul_f32 v87, v127, v193
	v_fma_f32 v141, v96, v106, v84
	v_mul_f32 v84, v109, v152
	v_fma_f32 v84, v111, v118, v84
	v_fma_f32 v150, v97, v106, v84
	v_mul_f32 v84, v108, v153
	v_fma_f32 v84, v110, v119, v84
	v_fma_f32 v85, v150, v194, v85
	v_fma_f32 v151, v98, v107, v84
	v_mul_f32 v84, v109, v153
	v_fma_f32 v84, v111, v119, v84
	v_fma_f32 v86, v151, v195, v86
	v_fma_f32 v152, v99, v107, v84
	v_mul_f32 v84, v122, v192
	v_fma_f32 v84, v141, v194, v84
	v_fma_f32 v87, v152, v195, v87
	v_add_f32_e32 v84, v84, v86
	v_add_f32_e32 v86, v85, v87
	v_mov_b32_e32 v85, 0
	v_add_f32_dpp v84, v84, v84 row_ror:8 row_mask:0xf bank_mask:0xf bound_ctrl:1
	v_add_f32_dpp v86, v86, v86 row_ror:8 row_mask:0xf bank_mask:0xf bound_ctrl:1
	v_mov_b32_e32 v87, 0
	v_add_f32_dpp v84, v84, v84 row_ror:4 row_mask:0xf bank_mask:0xf bound_ctrl:1
	v_add_f32_dpp v86, v86, v86 row_ror:4 row_mask:0xf bank_mask:0xf bound_ctrl:1
	s_nop 0
	v_add_f32_dpp v84, v84, v84 row_ror:2 row_mask:0xf bank_mask:0xf bound_ctrl:1
	v_add_f32_dpp v86, v86, v86 row_ror:2 row_mask:0xf bank_mask:0xf bound_ctrl:1
	s_nop 0
	v_mov_b32_dpp v85, v84 row_ror:1 row_mask:0xf bank_mask:0xf
	v_mov_b32_dpp v87, v86 row_ror:1 row_mask:0xf bank_mask:0xf
	s_and_saveexec_b64 s[8:9], s[40:41]
	v_add_f32_e32 v86, v86, v87
	v_add_f32_e32 v84, v84, v85
	ds_write2_b32 v188, v84, v86 offset1:16
	s_or_b64 exec, exec, s[8:9]
	v_mul_f32 v153, v122, v112
	v_mul_f32 v112, v123, v112
	v_mul_f32 v191, v125, v113
	v_mul_f32 v113, v127, v113
	ds_read_b128 v[96:99], v134 offset:23040
	ds_read_b128 v[116:119], v134 offset:27136
	ds_read_b128 v[104:107], v134 offset:31232
	ds_read_b128 v[108:111], v134 offset:35328
	ds_read_b128 v[84:87], v134 offset:39424
	ds_read2_b32 v[148:149], v190 offset0:64 offset1:80
	v_fma_f32 v153, v141, v114, v153
	v_fma_f32 v112, v150, v114, v112
	v_fma_f32 v114, v151, v115, v191
	v_fma_f32 v113, v152, v115, v113
	v_add_f32_e32 v114, v153, v114
	v_add_f32_e32 v112, v112, v113
	s_nop 0
	v_add_f32_dpp v113, v114, v114 row_ror:8 row_mask:0xf bank_mask:0xf bound_ctrl:1
	v_add_f32_dpp v112, v112, v112 row_ror:8 row_mask:0xf bank_mask:0xf bound_ctrl:1
	v_mul_f32 v114, v120, v100
	v_mul_f32 v100, v121, v100
	v_add_f32_dpp v113, v113, v113 row_ror:4 row_mask:0xf bank_mask:0xf bound_ctrl:1
	v_add_f32_dpp v112, v112, v112 row_ror:4 row_mask:0xf bank_mask:0xf bound_ctrl:1
	s_nop 0
	v_add_f32_dpp v113, v113, v113 row_ror:2 row_mask:0xf bank_mask:0xf bound_ctrl:1
	v_add_f32_dpp v112, v112, v112 row_ror:2 row_mask:0xf bank_mask:0xf bound_ctrl:1
	s_nop 0
	v_add_f32_dpp v113, v113, v113 row_ror:1 row_mask:0xf bank_mask:0xf bound_ctrl:1
	v_add_f32_dpp v112, v112, v112 row_ror:1 row_mask:0xf bank_mask:0xf bound_ctrl:1
	v_fma_f32 v114, v113, v92, v114
	v_fma_f32 v92, v112, v92, v100
	v_fma_f32 v153, v122, v88, v114
	v_fma_f32 v92, v123, v88, v92
	v_mul_f32 v88, v120, v101
	v_fma_f32 v88, v113, v93, v88
	v_fma_f32 v125, v125, v89, v88
	v_mul_f32 v88, v121, v101
	v_fma_f32 v88, v112, v93, v88
	v_fma_f32 v93, v127, v89, v88
	v_mul_f32 v88, v120, v102
	v_mul_f32 v89, v125, v81
	v_fma_f32 v88, v113, v94, v88
	v_mul_f32 v81, v93, v81
	v_fma_f32 v127, v141, v90, v88
	v_mul_f32 v88, v121, v102
	v_fma_f32 v88, v112, v94, v88
	v_fma_f32 v94, v150, v90, v88
	v_mul_f32 v88, v120, v103
	v_fma_f32 v88, v113, v95, v88
	v_fma_f32 v141, v151, v91, v88
	v_mul_f32 v88, v121, v103
	v_fma_f32 v88, v112, v95, v88
	v_fma_f32 v95, v152, v91, v88
	v_mul_f32 v88, v153, v80
	v_mul_f32 v80, v92, v80
	v_fma_f32 v88, v127, v82, v88
	v_fma_f32 v80, v94, v82, v80
	v_fma_f32 v82, v141, v83, v89
	v_fma_f32 v81, v95, v83, v81
	v_add_f32_e32 v82, v88, v82
	v_add_f32_e32 v83, v80, v81
	v_mov_b32_e32 v81, 0
	v_add_f32_dpp v80, v82, v82 row_ror:8 row_mask:0xf bank_mask:0xf bound_ctrl:1
	v_add_f32_dpp v82, v83, v83 row_ror:8 row_mask:0xf bank_mask:0xf bound_ctrl:1
	v_mov_b32_e32 v83, 0
	v_add_f32_dpp v80, v80, v80 row_ror:4 row_mask:0xf bank_mask:0xf bound_ctrl:1
	v_add_f32_dpp v82, v82, v82 row_ror:4 row_mask:0xf bank_mask:0xf bound_ctrl:1
	s_nop 0
	v_add_f32_dpp v80, v80, v80 row_ror:2 row_mask:0xf bank_mask:0xf bound_ctrl:1
	v_add_f32_dpp v82, v82, v82 row_ror:2 row_mask:0xf bank_mask:0xf bound_ctrl:1
	s_nop 0
	v_mov_b32_dpp v81, v80 row_ror:1 row_mask:0xf bank_mask:0xf
	v_mov_b32_dpp v83, v82 row_ror:1 row_mask:0xf bank_mask:0xf
	s_and_saveexec_b64 s[8:9], s[40:41]
	v_add_f32_e32 v82, v82, v83
	v_add_f32_e32 v80, v80, v81
	ds_write2_b32 v188, v80, v82 offset0:32 offset1:48
	s_or_b64 exec, exec, s[8:9]
	s_waitcnt lgkmcnt(4)
	v_mul_f32 v152, v153, v116
	v_mul_f32 v116, v92, v116
	v_mul_f32 v191, v125, v117
	v_mul_f32 v117, v93, v117
	ds_read_b128 v[88:91], v134 offset:23296
	ds_read_b128 v[120:123], v134 offset:27392
	ds_read_b128 v[100:103], v134 offset:31488
	ds_read_b128 v[112:115], v134 offset:35584
	ds_read_b128 v[80:83], v134 offset:39680
	ds_read2_b32 v[150:151], v190 offset0:96 offset1:112
	v_fma_f32 v152, v127, v118, v152
	v_fma_f32 v116, v94, v118, v116
	v_fma_f32 v118, v141, v119, v191
	v_fma_f32 v117, v95, v119, v117
	v_add_f32_e32 v118, v152, v118
	v_add_f32_e32 v116, v116, v117
	s_nop 0
	v_add_f32_dpp v117, v118, v118 row_ror:8 row_mask:0xf bank_mask:0xf bound_ctrl:1
	v_add_f32_dpp v116, v116, v116 row_ror:8 row_mask:0xf bank_mask:0xf bound_ctrl:1
	s_waitcnt lgkmcnt(6)
	v_mul_f32 v118, v148, v108
	v_mul_f32 v108, v149, v108
	v_add_f32_dpp v117, v117, v117 row_ror:4 row_mask:0xf bank_mask:0xf bound_ctrl:1
	v_add_f32_dpp v116, v116, v116 row_ror:4 row_mask:0xf bank_mask:0xf bound_ctrl:1
	s_nop 0
	v_add_f32_dpp v117, v117, v117 row_ror:2 row_mask:0xf bank_mask:0xf bound_ctrl:1
	v_add_f32_dpp v116, v116, v116 row_ror:2 row_mask:0xf bank_mask:0xf bound_ctrl:1
	s_nop 0
	v_add_f32_dpp v117, v117, v117 row_ror:1 row_mask:0xf bank_mask:0xf bound_ctrl:1
	v_add_f32_dpp v116, v116, v116 row_ror:1 row_mask:0xf bank_mask:0xf bound_ctrl:1
	v_fma_f32 v118, v117, v104, v118
	v_fma_f32 v104, v116, v104, v108
	v_fma_f32 v108, v92, v96, v104
	v_mul_f32 v92, v148, v109
	v_fma_f32 v152, v153, v96, v118
	v_fma_f32 v92, v117, v105, v92
	v_fma_f32 v125, v125, v97, v92
	v_mul_f32 v92, v149, v109
	v_fma_f32 v92, v116, v105, v92
	v_fma_f32 v109, v93, v97, v92
	v_mul_f32 v92, v148, v110
	v_mul_f32 v93, v125, v85
	v_fma_f32 v92, v117, v106, v92
	v_mul_f32 v85, v109, v85
	v_fma_f32 v127, v127, v98, v92
	v_mul_f32 v92, v149, v110
	v_fma_f32 v92, v116, v106, v92
	v_fma_f32 v110, v94, v98, v92
	v_mul_f32 v92, v148, v111
	v_fma_f32 v92, v117, v107, v92
	v_fma_f32 v141, v141, v99, v92
	v_mul_f32 v92, v149, v111
	v_fma_f32 v92, v116, v107, v92
	v_fma_f32 v111, v95, v99, v92
	v_mul_f32 v92, v152, v84
	v_mul_f32 v84, v108, v84
	v_fma_f32 v92, v127, v86, v92
	v_fma_f32 v84, v110, v86, v84
	v_fma_f32 v86, v141, v87, v93
	v_fma_f32 v85, v111, v87, v85
	v_add_f32_e32 v86, v92, v86
	v_add_f32_e32 v87, v84, v85
	v_mov_b32_e32 v85, 0
	v_add_f32_dpp v84, v86, v86 row_ror:8 row_mask:0xf bank_mask:0xf bound_ctrl:1
	v_add_f32_dpp v86, v87, v87 row_ror:8 row_mask:0xf bank_mask:0xf bound_ctrl:1
	v_mov_b32_e32 v87, 0
	v_add_f32_dpp v84, v84, v84 row_ror:4 row_mask:0xf bank_mask:0xf bound_ctrl:1
	v_add_f32_dpp v86, v86, v86 row_ror:4 row_mask:0xf bank_mask:0xf bound_ctrl:1
	s_nop 0
	v_add_f32_dpp v84, v84, v84 row_ror:2 row_mask:0xf bank_mask:0xf bound_ctrl:1
	v_add_f32_dpp v86, v86, v86 row_ror:2 row_mask:0xf bank_mask:0xf bound_ctrl:1
	s_nop 0
	v_mov_b32_dpp v85, v84 row_ror:1 row_mask:0xf bank_mask:0xf
	v_mov_b32_dpp v87, v86 row_ror:1 row_mask:0xf bank_mask:0xf
	s_and_saveexec_b64 s[8:9], s[40:41]
	v_add_f32_e32 v86, v86, v87
	v_add_f32_e32 v84, v84, v85
	ds_write2_b32 v188, v84, v86 offset0:64 offset1:80
	s_or_b64 exec, exec, s[8:9]
	s_waitcnt lgkmcnt(4)
	v_mul_f32 v153, v152, v120
	v_mul_f32 v120, v108, v120
	v_mul_f32 v191, v125, v121
	v_mul_f32 v121, v109, v121
	ds_read_b128 v[92:95], v134 offset:23552
	ds_read_b128 v[116:119], v134 offset:27648
	ds_read_b128 v[96:99], v134 offset:31744
	ds_read_b128 v[104:107], v134 offset:35840
	ds_read_b128 v[84:87], v134 offset:39936
	ds_read2_b32 v[148:149], v190 offset0:128 offset1:144
	v_fma_f32 v120, v110, v122, v120
	v_fma_f32 v153, v127, v122, v153
	v_fma_f32 v122, v141, v123, v191
	v_fma_f32 v121, v111, v123, v121
	v_add_f32_e32 v122, v153, v122
	v_add_f32_e32 v120, v120, v121
	s_nop 1
	v_add_f32_dpp v120, v120, v120 row_ror:8 row_mask:0xf bank_mask:0xf bound_ctrl:1
	v_add_f32_dpp v121, v122, v122 row_ror:8 row_mask:0xf bank_mask:0xf bound_ctrl:1
	s_nop 0
	v_add_f32_dpp v120, v120, v120 row_ror:4 row_mask:0xf bank_mask:0xf bound_ctrl:1
	v_add_f32_dpp v121, v121, v121 row_ror:4 row_mask:0xf bank_mask:0xf bound_ctrl:1
	s_nop 0
	v_add_f32_dpp v120, v120, v120 row_ror:2 row_mask:0xf bank_mask:0xf bound_ctrl:1
	v_add_f32_dpp v121, v121, v121 row_ror:2 row_mask:0xf bank_mask:0xf bound_ctrl:1
	s_nop 0
	v_add_f32_dpp v191, v120, v120 row_ror:1 row_mask:0xf bank_mask:0xf bound_ctrl:1
	s_waitcnt lgkmcnt(6)
	v_mul_f32 v120, v150, v112
	v_add_f32_dpp v153, v121, v121 row_ror:1 row_mask:0xf bank_mask:0xf bound_ctrl:1
	v_fma_f32 v120, v153, v100, v120
	v_mul_f32 v112, v151, v112
	v_fma_f32 v120, v152, v88, v120
	v_fma_f32 v100, v191, v100, v112
	v_fma_f32 v121, v108, v88, v100
	v_mul_f32 v88, v150, v113
	v_fma_f32 v88, v153, v101, v88
	v_fma_f32 v122, v125, v89, v88
	v_mul_f32 v88, v151, v113
	v_fma_f32 v88, v191, v101, v88
	v_fma_f32 v123, v109, v89, v88
	v_mul_f32 v88, v150, v114
	v_mul_f32 v89, v122, v81
	v_fma_f32 v88, v153, v102, v88
	v_mul_f32 v81, v123, v81
	v_fma_f32 v125, v127, v90, v88
	v_mul_f32 v88, v151, v114
	v_fma_f32 v88, v191, v102, v88
	v_fma_f32 v127, v110, v90, v88
	v_mul_f32 v88, v150, v115
	v_fma_f32 v88, v153, v103, v88
	v_fma_f32 v141, v141, v91, v88
	v_mul_f32 v88, v151, v115
	v_fma_f32 v88, v191, v103, v88
	v_fma_f32 v152, v111, v91, v88
	v_mul_f32 v88, v120, v80
	v_mul_f32 v80, v121, v80
	v_fma_f32 v88, v125, v82, v88
	v_fma_f32 v80, v127, v82, v80
	v_fma_f32 v82, v141, v83, v89
	v_fma_f32 v81, v152, v83, v81
	v_add_f32_e32 v82, v88, v82
	v_add_f32_e32 v83, v80, v81
	v_mov_b32_e32 v81, 0
	v_add_f32_dpp v80, v82, v82 row_ror:8 row_mask:0xf bank_mask:0xf bound_ctrl:1
	v_add_f32_dpp v82, v83, v83 row_ror:8 row_mask:0xf bank_mask:0xf bound_ctrl:1
	v_mov_b32_e32 v83, 0
	v_add_f32_dpp v80, v80, v80 row_ror:4 row_mask:0xf bank_mask:0xf bound_ctrl:1
	v_add_f32_dpp v82, v82, v82 row_ror:4 row_mask:0xf bank_mask:0xf bound_ctrl:1
	s_nop 0
	v_add_f32_dpp v80, v80, v80 row_ror:2 row_mask:0xf bank_mask:0xf bound_ctrl:1
	v_add_f32_dpp v82, v82, v82 row_ror:2 row_mask:0xf bank_mask:0xf bound_ctrl:1
	s_nop 0
	v_mov_b32_dpp v81, v80 row_ror:1 row_mask:0xf bank_mask:0xf
	v_mov_b32_dpp v83, v82 row_ror:1 row_mask:0xf bank_mask:0xf
	s_and_saveexec_b64 s[8:9], s[40:41]
	v_add_f32_e32 v82, v82, v83
	v_add_f32_e32 v80, v80, v81
	ds_write2_b32 v188, v80, v82 offset0:96 offset1:112
	s_or_b64 exec, exec, s[8:9]
	s_waitcnt lgkmcnt(4)
	v_mul_f32 v153, v120, v116
	v_mul_f32 v116, v121, v116
	v_mul_f32 v191, v122, v117
	v_mul_f32 v117, v123, v117
	ds_read_b128 v[88:91], v134 offset:23808
	ds_read_b128 v[112:115], v134 offset:27904
	ds_read_b128 v[100:103], v134 offset:32000
	ds_read_b128 v[108:111], v134 offset:36096
	ds_read_b128 v[80:83], v134 offset:40192
	ds_read2_b32 v[150:151], v190 offset0:160 offset1:176
	v_fma_f32 v116, v127, v118, v116
	v_fma_f32 v153, v125, v118, v153
	v_fma_f32 v118, v141, v119, v191
	v_fma_f32 v117, v152, v119, v117
	v_add_f32_e32 v118, v153, v118
	v_add_f32_e32 v116, v116, v117
	s_nop 1
	v_add_f32_dpp v116, v116, v116 row_ror:8 row_mask:0xf bank_mask:0xf bound_ctrl:1
	v_add_f32_dpp v117, v118, v118 row_ror:8 row_mask:0xf bank_mask:0xf bound_ctrl:1
	s_nop 0
	v_add_f32_dpp v116, v116, v116 row_ror:4 row_mask:0xf bank_mask:0xf bound_ctrl:1
	v_add_f32_dpp v117, v117, v117 row_ror:4 row_mask:0xf bank_mask:0xf bound_ctrl:1
	s_nop 0
	v_add_f32_dpp v116, v116, v116 row_ror:2 row_mask:0xf bank_mask:0xf bound_ctrl:1
	v_add_f32_dpp v117, v117, v117 row_ror:2 row_mask:0xf bank_mask:0xf bound_ctrl:1
	s_nop 0
	v_add_f32_dpp v191, v116, v116 row_ror:1 row_mask:0xf bank_mask:0xf bound_ctrl:1
	s_waitcnt lgkmcnt(6)
	v_mul_f32 v116, v148, v104
	v_add_f32_dpp v153, v117, v117 row_ror:1 row_mask:0xf bank_mask:0xf bound_ctrl:1
	v_fma_f32 v116, v153, v96, v116
	v_mul_f32 v104, v149, v104
	v_fma_f32 v116, v120, v92, v116
	v_fma_f32 v96, v191, v96, v104
	v_fma_f32 v117, v121, v92, v96
	v_mul_f32 v92, v148, v105
	v_fma_f32 v92, v153, v97, v92
	v_fma_f32 v118, v122, v93, v92
	v_mul_f32 v92, v149, v105
	v_fma_f32 v92, v191, v97, v92
	v_fma_f32 v119, v123, v93, v92
	v_mul_f32 v92, v148, v106
	v_mul_f32 v93, v118, v85
	v_fma_f32 v92, v153, v98, v92
	v_mul_f32 v85, v119, v85
	v_fma_f32 v125, v125, v94, v92
	v_mul_f32 v92, v149, v106
	v_fma_f32 v92, v191, v98, v92
	v_fma_f32 v127, v127, v94, v92
	v_mul_f32 v92, v148, v107
	v_fma_f32 v92, v153, v99, v92
	v_fma_f32 v141, v141, v95, v92
	v_mul_f32 v92, v149, v107
	v_fma_f32 v92, v191, v99, v92
	v_fma_f32 v148, v152, v95, v92
	v_mul_f32 v92, v116, v84
	v_mul_f32 v84, v117, v84
	v_fma_f32 v92, v125, v86, v92
	v_fma_f32 v84, v127, v86, v84
	v_fma_f32 v86, v141, v87, v93
	v_fma_f32 v85, v148, v87, v85
	v_add_f32_e32 v86, v92, v86
	v_add_f32_e32 v87, v84, v85
	v_mov_b32_e32 v85, 0
	v_add_f32_dpp v84, v86, v86 row_ror:8 row_mask:0xf bank_mask:0xf bound_ctrl:1
	v_add_f32_dpp v86, v87, v87 row_ror:8 row_mask:0xf bank_mask:0xf bound_ctrl:1
	v_mov_b32_e32 v87, 0
	v_add_f32_dpp v84, v84, v84 row_ror:4 row_mask:0xf bank_mask:0xf bound_ctrl:1
	v_add_f32_dpp v86, v86, v86 row_ror:4 row_mask:0xf bank_mask:0xf bound_ctrl:1
	s_nop 0
	v_add_f32_dpp v84, v84, v84 row_ror:2 row_mask:0xf bank_mask:0xf bound_ctrl:1
	v_add_f32_dpp v86, v86, v86 row_ror:2 row_mask:0xf bank_mask:0xf bound_ctrl:1
	s_nop 0
	v_mov_b32_dpp v85, v84 row_ror:1 row_mask:0xf bank_mask:0xf
	v_mov_b32_dpp v87, v86 row_ror:1 row_mask:0xf bank_mask:0xf
	s_and_saveexec_b64 s[8:9], s[40:41]
	v_add_f32_e32 v86, v86, v87
	v_add_f32_e32 v84, v84, v85
	ds_write2_b32 v188, v84, v86 offset0:128 offset1:144
	s_or_b64 exec, exec, s[8:9]
	s_waitcnt lgkmcnt(4)
	v_mul_f32 v149, v116, v112
	v_mul_f32 v112, v117, v112
	v_mul_f32 v191, v118, v113
	v_mul_f32 v113, v119, v113
	ds_read_b128 v[92:95], v134 offset:24064
	ds_read_b128 v[120:123], v134 offset:28160
	ds_read_b128 v[96:99], v134 offset:32256
	ds_read_b128 v[104:107], v134 offset:36352
	ds_read_b128 v[84:87], v134 offset:40448
	ds_read2_b32 v[152:153], v190 offset0:192 offset1:208
	v_fma_f32 v112, v127, v114, v112
	v_fma_f32 v149, v125, v114, v149
	v_fma_f32 v114, v141, v115, v191
	v_fma_f32 v113, v148, v115, v113
	v_add_f32_e32 v114, v149, v114
	v_add_f32_e32 v112, v112, v113
	s_nop 1
	v_add_f32_dpp v112, v112, v112 row_ror:8 row_mask:0xf bank_mask:0xf bound_ctrl:1
	v_add_f32_dpp v113, v114, v114 row_ror:8 row_mask:0xf bank_mask:0xf bound_ctrl:1
	s_nop 0
	v_add_f32_dpp v112, v112, v112 row_ror:4 row_mask:0xf bank_mask:0xf bound_ctrl:1
	v_add_f32_dpp v113, v113, v113 row_ror:4 row_mask:0xf bank_mask:0xf bound_ctrl:1
	s_nop 0
	v_add_f32_dpp v112, v112, v112 row_ror:2 row_mask:0xf bank_mask:0xf bound_ctrl:1
	v_add_f32_dpp v113, v113, v113 row_ror:2 row_mask:0xf bank_mask:0xf bound_ctrl:1
	s_nop 0
	v_add_f32_dpp v194, v112, v112 row_ror:1 row_mask:0xf bank_mask:0xf bound_ctrl:1
	s_waitcnt lgkmcnt(6)
	v_mul_f32 v112, v150, v108
	v_add_f32_dpp v149, v113, v113 row_ror:1 row_mask:0xf bank_mask:0xf bound_ctrl:1
	v_fma_f32 v112, v149, v100, v112
	v_mul_f32 v108, v151, v108
	v_fma_f32 v112, v116, v88, v112
	v_fma_f32 v100, v194, v100, v108
	v_fma_f32 v113, v117, v88, v100
	v_mul_f32 v88, v150, v109
	v_fma_f32 v88, v149, v101, v88
	v_fma_f32 v114, v118, v89, v88
	v_mul_f32 v88, v151, v109
	v_fma_f32 v88, v194, v101, v88
	v_fma_f32 v115, v119, v89, v88
	v_mul_f32 v88, v150, v110
	v_mul_f32 v89, v114, v81
	v_fma_f32 v88, v149, v102, v88
	v_mul_f32 v81, v115, v81
	v_fma_f32 v191, v125, v90, v88
	v_mul_f32 v88, v151, v110
	v_fma_f32 v88, v194, v102, v88
	v_fma_f32 v192, v127, v90, v88
	v_mul_f32 v88, v150, v111
	v_fma_f32 v88, v149, v103, v88
	v_fma_f32 v193, v141, v91, v88
	v_mul_f32 v88, v151, v111
	v_fma_f32 v88, v194, v103, v88
	v_fma_f32 v194, v148, v91, v88
	v_mul_f32 v88, v112, v80
	v_mul_f32 v80, v113, v80
	v_fma_f32 v88, v191, v82, v88
	v_fma_f32 v80, v192, v82, v80
	v_fma_f32 v82, v193, v83, v89
	v_fma_f32 v81, v194, v83, v81
	v_add_f32_e32 v82, v88, v82
	v_add_f32_e32 v83, v80, v81
	v_mov_b32_e32 v81, 0
	v_add_f32_dpp v80, v82, v82 row_ror:8 row_mask:0xf bank_mask:0xf bound_ctrl:1
	v_add_f32_dpp v82, v83, v83 row_ror:8 row_mask:0xf bank_mask:0xf bound_ctrl:1
	v_mov_b32_e32 v83, 0
	v_add_f32_dpp v80, v80, v80 row_ror:4 row_mask:0xf bank_mask:0xf bound_ctrl:1
	v_add_f32_dpp v82, v82, v82 row_ror:4 row_mask:0xf bank_mask:0xf bound_ctrl:1
	s_nop 0
	v_add_f32_dpp v80, v80, v80 row_ror:2 row_mask:0xf bank_mask:0xf bound_ctrl:1
	v_add_f32_dpp v82, v82, v82 row_ror:2 row_mask:0xf bank_mask:0xf bound_ctrl:1
	s_nop 0
	v_mov_b32_dpp v81, v80 row_ror:1 row_mask:0xf bank_mask:0xf
	v_mov_b32_dpp v83, v82 row_ror:1 row_mask:0xf bank_mask:0xf
	s_and_saveexec_b64 s[8:9], s[40:41]
	v_add_f32_e32 v82, v82, v83
	v_add_f32_e32 v80, v80, v81
	ds_write2_b32 v188, v80, v82 offset0:160 offset1:176
	s_or_b64 exec, exec, s[8:9]
	s_waitcnt lgkmcnt(4)
	v_mul_f32 v125, v112, v120
	v_mul_f32 v120, v113, v120
	v_mul_f32 v127, v114, v121
	v_mul_f32 v121, v115, v121
	ds_read_b128 v[88:91], v134 offset:24320
	ds_read_b128 v[116:119], v134 offset:28416
	ds_read_b128 v[100:103], v134 offset:32512
	ds_read_b128 v[108:111], v134 offset:36608
	ds_read_b128 v[80:83], v134 offset:40704
	ds_read2_b32 v[148:149], v190 offset0:224 offset1:240
	v_fma_f32 v120, v192, v122, v120
	v_fma_f32 v125, v191, v122, v125
	v_fma_f32 v122, v193, v123, v127
	v_fma_f32 v121, v194, v123, v121
	v_add_f32_e32 v122, v125, v122
	v_add_f32_e32 v120, v120, v121
	s_nop 1
	v_add_f32_dpp v120, v120, v120 row_ror:8 row_mask:0xf bank_mask:0xf bound_ctrl:1
	v_add_f32_dpp v121, v122, v122 row_ror:8 row_mask:0xf bank_mask:0xf bound_ctrl:1
	s_nop 0
	v_add_f32_dpp v120, v120, v120 row_ror:4 row_mask:0xf bank_mask:0xf bound_ctrl:1
	v_add_f32_dpp v121, v121, v121 row_ror:4 row_mask:0xf bank_mask:0xf bound_ctrl:1
	s_nop 0
	v_add_f32_dpp v120, v120, v120 row_ror:2 row_mask:0xf bank_mask:0xf bound_ctrl:1
	v_add_f32_dpp v121, v121, v121 row_ror:2 row_mask:0xf bank_mask:0xf bound_ctrl:1
	s_nop 0
	v_add_f32_dpp v123, v120, v120 row_ror:1 row_mask:0xf bank_mask:0xf bound_ctrl:1
	s_waitcnt lgkmcnt(6)
	v_mul_f32 v120, v152, v104
	v_add_f32_dpp v122, v121, v121 row_ror:1 row_mask:0xf bank_mask:0xf bound_ctrl:1
	v_fma_f32 v120, v122, v96, v120
	v_mul_f32 v104, v153, v104
	v_fma_f32 v120, v112, v92, v120
	v_fma_f32 v96, v123, v96, v104
	v_fma_f32 v121, v113, v92, v96
	v_mul_f32 v92, v152, v105
	v_fma_f32 v92, v122, v97, v92
	v_fma_f32 v125, v114, v93, v92
	v_mul_f32 v92, v153, v105
	v_fma_f32 v92, v123, v97, v92
	v_fma_f32 v127, v115, v93, v92
	v_mul_f32 v92, v152, v106
	v_mul_f32 v93, v125, v85
	v_fma_f32 v92, v122, v98, v92
	v_mul_f32 v85, v127, v85
	v_fma_f32 v141, v191, v94, v92
	v_mul_f32 v92, v153, v106
	v_fma_f32 v92, v123, v98, v92
	v_fma_f32 v150, v192, v94, v92
	v_mul_f32 v92, v152, v107
	v_fma_f32 v92, v122, v99, v92
	v_fma_f32 v151, v193, v95, v92
	v_mul_f32 v92, v153, v107
	v_fma_f32 v92, v123, v99, v92
	v_fma_f32 v153, v194, v95, v92
	v_mul_f32 v92, v120, v84
	v_mul_f32 v84, v121, v84
	v_fma_f32 v92, v141, v86, v92
	v_fma_f32 v84, v150, v86, v84
	v_fma_f32 v86, v151, v87, v93
	v_fma_f32 v85, v153, v87, v85
	v_add_f32_e32 v86, v92, v86
	v_add_f32_e32 v87, v84, v85
	v_mov_b32_e32 v85, 0
	v_add_f32_dpp v84, v86, v86 row_ror:8 row_mask:0xf bank_mask:0xf bound_ctrl:1
	v_add_f32_dpp v86, v87, v87 row_ror:8 row_mask:0xf bank_mask:0xf bound_ctrl:1
	v_mov_b32_e32 v87, 0
	v_add_f32_dpp v84, v84, v84 row_ror:4 row_mask:0xf bank_mask:0xf bound_ctrl:1
	v_add_f32_dpp v86, v86, v86 row_ror:4 row_mask:0xf bank_mask:0xf bound_ctrl:1
	s_nop 0
	v_add_f32_dpp v84, v84, v84 row_ror:2 row_mask:0xf bank_mask:0xf bound_ctrl:1
	v_add_f32_dpp v86, v86, v86 row_ror:2 row_mask:0xf bank_mask:0xf bound_ctrl:1
	s_nop 0
	v_mov_b32_dpp v85, v84 row_ror:1 row_mask:0xf bank_mask:0xf
	v_mov_b32_dpp v87, v86 row_ror:1 row_mask:0xf bank_mask:0xf
	s_and_saveexec_b64 s[8:9], s[40:41]
	v_add_f32_e32 v86, v86, v87
	v_add_f32_e32 v84, v84, v85
	ds_write2_b32 v188, v84, v86 offset0:192 offset1:208
	s_or_b64 exec, exec, s[8:9]
	s_waitcnt lgkmcnt(4)
	v_mul_f32 v191, v120, v116
	v_mul_f32 v116, v121, v116
	v_mul_f32 v192, v125, v117
	v_mul_f32 v117, v127, v117
	ds_read_b128 v[112:115], v134 offset:28672
	ds_read_b128 v[96:99], v134 offset:32768
	ds_read_b128 v[104:107], v134 offset:36864
	ds_read_b128 v[92:95], v134 offset:24576
	ds_read_b128 v[84:87], v134 offset:40960
	v_fma_f32 v191, v141, v118, v191
	v_fma_f32 v116, v150, v118, v116
	v_fma_f32 v118, v151, v119, v192
	v_fma_f32 v117, v153, v119, v117
	v_add_u32_e32 v152, 0xac00, v182
	v_add_f32_e32 v118, v191, v118
	v_add_f32_e32 v116, v116, v117
	ds_read2_b32 v[122:123], v152 offset1:16
	v_add_f32_dpp v117, v118, v118 row_ror:8 row_mask:0xf bank_mask:0xf bound_ctrl:1
	v_add_f32_dpp v116, v116, v116 row_ror:8 row_mask:0xf bank_mask:0xf bound_ctrl:1
	s_waitcnt lgkmcnt(6)
	v_mul_f32 v118, v148, v108
	v_mul_f32 v108, v149, v108
	v_add_f32_dpp v117, v117, v117 row_ror:4 row_mask:0xf bank_mask:0xf bound_ctrl:1
	v_add_f32_dpp v116, v116, v116 row_ror:4 row_mask:0xf bank_mask:0xf bound_ctrl:1
	s_nop 0
	v_add_f32_dpp v117, v117, v117 row_ror:2 row_mask:0xf bank_mask:0xf bound_ctrl:1
	v_add_f32_dpp v116, v116, v116 row_ror:2 row_mask:0xf bank_mask:0xf bound_ctrl:1
	s_nop 0
	v_add_f32_dpp v117, v117, v117 row_ror:1 row_mask:0xf bank_mask:0xf bound_ctrl:1
	v_add_f32_dpp v116, v116, v116 row_ror:1 row_mask:0xf bank_mask:0xf bound_ctrl:1
	v_fma_f32 v118, v117, v100, v118
	v_fma_f32 v100, v116, v100, v108
	v_fma_f32 v191, v120, v88, v118
	v_fma_f32 v192, v121, v88, v100
	v_mul_f32 v88, v148, v109
	v_fma_f32 v88, v117, v101, v88
	v_fma_f32 v193, v125, v89, v88
	v_mul_f32 v88, v149, v109
	v_fma_f32 v88, v116, v101, v88
	v_fma_f32 v194, v127, v89, v88
	v_mul_f32 v88, v148, v110
	v_mul_f32 v89, v193, v81
	v_fma_f32 v88, v117, v102, v88
	v_mul_f32 v81, v194, v81
	v_fma_f32 v195, v141, v90, v88
	v_mul_f32 v88, v149, v110
	v_fma_f32 v88, v116, v102, v88
	v_fma_f32 v150, v150, v90, v88
	v_mul_f32 v88, v148, v111
	v_fma_f32 v88, v117, v103, v88
	v_fma_f32 v151, v151, v91, v88
	v_mul_f32 v88, v149, v111
	v_fma_f32 v88, v116, v103, v88
	v_fma_f32 v153, v153, v91, v88
	v_mul_f32 v88, v191, v80
	v_mul_f32 v80, v192, v80
	v_fma_f32 v88, v195, v82, v88
	v_fma_f32 v80, v150, v82, v80
	v_fma_f32 v82, v151, v83, v89
	v_fma_f32 v81, v153, v83, v81
	v_add_f32_e32 v82, v88, v82
	v_add_f32_e32 v83, v80, v81
	v_mov_b32_e32 v81, 0
	v_add_f32_dpp v80, v82, v82 row_ror:8 row_mask:0xf bank_mask:0xf bound_ctrl:1
	v_add_f32_dpp v82, v83, v83 row_ror:8 row_mask:0xf bank_mask:0xf bound_ctrl:1
	v_mov_b32_e32 v83, 0
	v_add_f32_dpp v80, v80, v80 row_ror:4 row_mask:0xf bank_mask:0xf bound_ctrl:1
	v_add_f32_dpp v82, v82, v82 row_ror:4 row_mask:0xf bank_mask:0xf bound_ctrl:1
	s_nop 0
	v_add_f32_dpp v80, v80, v80 row_ror:2 row_mask:0xf bank_mask:0xf bound_ctrl:1
	v_add_f32_dpp v82, v82, v82 row_ror:2 row_mask:0xf bank_mask:0xf bound_ctrl:1
	s_nop 0
	v_mov_b32_dpp v81, v80 row_ror:1 row_mask:0xf bank_mask:0xf
	v_mov_b32_dpp v83, v82 row_ror:1 row_mask:0xf bank_mask:0xf
	s_and_saveexec_b64 s[8:9], s[40:41]
	v_add_f32_e32 v82, v82, v83
	v_add_f32_e32 v80, v80, v81
	ds_write2_b32 v188, v80, v82 offset0:224 offset1:240
	s_or_b64 exec, exec, s[8:9]
	s_waitcnt lgkmcnt(5)
	v_mul_f32 v125, v191, v112
	v_mul_f32 v112, v192, v112
	v_mul_f32 v127, v193, v113
	v_mul_f32 v113, v194, v113
	ds_read_b128 v[116:119], v134 offset:28928
	ds_read_b128 v[100:103], v134 offset:33024
	ds_read_b128 v[108:111], v134 offset:37120
	ds_read_b128 v[88:91], v134 offset:24832
	ds_read_b128 v[80:83], v134 offset:41216
	ds_read2_b32 v[120:121], v152 offset0:32 offset1:48
	v_fma_f32 v125, v195, v114, v125
	v_fma_f32 v112, v150, v114, v112
	v_fma_f32 v114, v151, v115, v127
	v_fma_f32 v113, v153, v115, v113
	v_add_f32_e32 v114, v125, v114
	v_add_f32_e32 v112, v112, v113
	s_nop 0
	v_add_f32_dpp v113, v114, v114 row_ror:8 row_mask:0xf bank_mask:0xf bound_ctrl:1
	v_add_f32_dpp v112, v112, v112 row_ror:8 row_mask:0xf bank_mask:0xf bound_ctrl:1
	s_waitcnt lgkmcnt(6)
	v_mul_f32 v114, v122, v104
	v_mul_f32 v104, v123, v104
	v_add_f32_dpp v113, v113, v113 row_ror:4 row_mask:0xf bank_mask:0xf bound_ctrl:1
	v_add_f32_dpp v112, v112, v112 row_ror:4 row_mask:0xf bank_mask:0xf bound_ctrl:1
	s_nop 0
	v_add_f32_dpp v113, v113, v113 row_ror:2 row_mask:0xf bank_mask:0xf bound_ctrl:1
	v_add_f32_dpp v112, v112, v112 row_ror:2 row_mask:0xf bank_mask:0xf bound_ctrl:1
	s_nop 0
	v_add_f32_dpp v113, v113, v113 row_ror:1 row_mask:0xf bank_mask:0xf bound_ctrl:1
	v_add_f32_dpp v112, v112, v112 row_ror:1 row_mask:0xf bank_mask:0xf bound_ctrl:1
	v_fma_f32 v114, v113, v96, v114
	v_fma_f32 v96, v112, v96, v104
	v_fma_f32 v125, v191, v92, v114
	v_fma_f32 v127, v192, v92, v96
	v_mul_f32 v92, v122, v105
	v_fma_f32 v92, v113, v97, v92
	v_fma_f32 v141, v193, v93, v92
	v_mul_f32 v92, v123, v105
	v_fma_f32 v92, v112, v97, v92
	v_fma_f32 v148, v194, v93, v92
	v_mul_f32 v92, v122, v106
	v_mul_f32 v93, v141, v85
	v_fma_f32 v92, v113, v98, v92
	v_mul_f32 v85, v148, v85
	v_fma_f32 v149, v195, v94, v92
	v_mul_f32 v92, v123, v106
	v_fma_f32 v92, v112, v98, v92
	v_fma_f32 v150, v150, v94, v92
	v_mul_f32 v92, v122, v107
	v_fma_f32 v92, v113, v99, v92
	v_fma_f32 v151, v151, v95, v92
	v_mul_f32 v92, v123, v107
	v_fma_f32 v92, v112, v99, v92
	v_fma_f32 v191, v153, v95, v92
	v_mul_f32 v92, v125, v84
	v_mul_f32 v84, v127, v84
	v_add_u32_e32 v153, 0xbc00, v182
	v_fma_f32 v92, v149, v86, v92
	v_fma_f32 v84, v150, v86, v84
	v_fma_f32 v86, v151, v87, v93
	v_fma_f32 v85, v191, v87, v85
	v_add_f32_e32 v86, v92, v86
	v_add_f32_e32 v87, v84, v85
	v_mov_b32_e32 v85, 0
	v_add_f32_dpp v84, v86, v86 row_ror:8 row_mask:0xf bank_mask:0xf bound_ctrl:1
	v_add_f32_dpp v86, v87, v87 row_ror:8 row_mask:0xf bank_mask:0xf bound_ctrl:1
	v_mov_b32_e32 v87, 0
	v_add_f32_dpp v84, v84, v84 row_ror:4 row_mask:0xf bank_mask:0xf bound_ctrl:1
	v_add_f32_dpp v86, v86, v86 row_ror:4 row_mask:0xf bank_mask:0xf bound_ctrl:1
	s_nop 0
	v_add_f32_dpp v84, v84, v84 row_ror:2 row_mask:0xf bank_mask:0xf bound_ctrl:1
	v_add_f32_dpp v86, v86, v86 row_ror:2 row_mask:0xf bank_mask:0xf bound_ctrl:1
	s_nop 0
	v_mov_b32_dpp v85, v84 row_ror:1 row_mask:0xf bank_mask:0xf
	v_mov_b32_dpp v87, v86 row_ror:1 row_mask:0xf bank_mask:0xf
	s_and_saveexec_b64 s[8:9], s[40:41]
	v_add_f32_e32 v86, v86, v87
	v_add_f32_e32 v84, v84, v85
	ds_write2_b32 v153, v84, v86 offset1:16
	s_or_b64 exec, exec, s[8:9]
	s_waitcnt lgkmcnt(5)
	v_mul_f32 v192, v125, v116
	v_mul_f32 v116, v127, v116
	v_mul_f32 v193, v141, v117
	v_mul_f32 v117, v148, v117
	ds_read_b128 v[112:115], v134 offset:29184
	ds_read_b128 v[96:99], v134 offset:33280
	ds_read_b128 v[104:107], v134 offset:37376
	ds_read_b128 v[92:95], v134 offset:25088
	ds_read_b128 v[84:87], v134 offset:41472
	ds_read2_b32 v[122:123], v152 offset0:64 offset1:80
	v_fma_f32 v192, v149, v118, v192
	v_fma_f32 v116, v150, v118, v116
	v_fma_f32 v118, v151, v119, v193
	v_fma_f32 v117, v191, v119, v117
	v_add_f32_e32 v118, v192, v118
	v_add_f32_e32 v116, v116, v117
	s_nop 0
	v_add_f32_dpp v117, v118, v118 row_ror:8 row_mask:0xf bank_mask:0xf bound_ctrl:1
	v_add_f32_dpp v116, v116, v116 row_ror:8 row_mask:0xf bank_mask:0xf bound_ctrl:1
	s_waitcnt lgkmcnt(6)
	v_mul_f32 v118, v120, v108
	v_mul_f32 v108, v121, v108
	v_add_f32_dpp v117, v117, v117 row_ror:4 row_mask:0xf bank_mask:0xf bound_ctrl:1
	v_add_f32_dpp v116, v116, v116 row_ror:4 row_mask:0xf bank_mask:0xf bound_ctrl:1
	s_nop 0
	v_add_f32_dpp v117, v117, v117 row_ror:2 row_mask:0xf bank_mask:0xf bound_ctrl:1
	v_add_f32_dpp v116, v116, v116 row_ror:2 row_mask:0xf bank_mask:0xf bound_ctrl:1
	s_nop 0
	v_add_f32_dpp v117, v117, v117 row_ror:1 row_mask:0xf bank_mask:0xf bound_ctrl:1
	v_add_f32_dpp v116, v116, v116 row_ror:1 row_mask:0xf bank_mask:0xf bound_ctrl:1
	v_fma_f32 v118, v117, v100, v118
	v_fma_f32 v100, v116, v100, v108
	v_fma_f32 v125, v125, v88, v118
	v_fma_f32 v127, v127, v88, v100
	v_mul_f32 v88, v120, v109
	v_fma_f32 v88, v117, v101, v88
	v_fma_f32 v141, v141, v89, v88
	v_mul_f32 v88, v121, v109
	v_fma_f32 v88, v116, v101, v88
	v_fma_f32 v148, v148, v89, v88
	v_mul_f32 v88, v120, v110
	v_mul_f32 v89, v141, v81
	v_fma_f32 v88, v117, v102, v88
	v_mul_f32 v81, v148, v81
	v_fma_f32 v149, v149, v90, v88
	v_mul_f32 v88, v121, v110
	v_fma_f32 v88, v116, v102, v88
	v_fma_f32 v150, v150, v90, v88
	v_mul_f32 v88, v120, v111
	v_fma_f32 v88, v117, v103, v88
	v_fma_f32 v151, v151, v91, v88
	v_mul_f32 v88, v121, v111
	v_fma_f32 v88, v116, v103, v88
	v_fma_f32 v191, v191, v91, v88
	v_mul_f32 v88, v125, v80
	v_mul_f32 v80, v127, v80
	v_fma_f32 v88, v149, v82, v88
	v_fma_f32 v80, v150, v82, v80
	v_fma_f32 v82, v151, v83, v89
	v_fma_f32 v81, v191, v83, v81
	v_add_f32_e32 v82, v88, v82
	v_add_f32_e32 v83, v80, v81
	v_mov_b32_e32 v81, 0
	v_add_f32_dpp v80, v82, v82 row_ror:8 row_mask:0xf bank_mask:0xf bound_ctrl:1
	v_add_f32_dpp v82, v83, v83 row_ror:8 row_mask:0xf bank_mask:0xf bound_ctrl:1
	v_mov_b32_e32 v83, 0
	v_add_f32_dpp v80, v80, v80 row_ror:4 row_mask:0xf bank_mask:0xf bound_ctrl:1
	v_add_f32_dpp v82, v82, v82 row_ror:4 row_mask:0xf bank_mask:0xf bound_ctrl:1
	s_nop 0
	v_add_f32_dpp v80, v80, v80 row_ror:2 row_mask:0xf bank_mask:0xf bound_ctrl:1
	v_add_f32_dpp v82, v82, v82 row_ror:2 row_mask:0xf bank_mask:0xf bound_ctrl:1
	s_nop 0
	v_mov_b32_dpp v81, v80 row_ror:1 row_mask:0xf bank_mask:0xf
	v_mov_b32_dpp v83, v82 row_ror:1 row_mask:0xf bank_mask:0xf
	s_and_saveexec_b64 s[8:9], s[40:41]
	v_add_f32_e32 v82, v82, v83
	v_add_f32_e32 v80, v80, v81
	ds_write2_b32 v153, v80, v82 offset0:32 offset1:48
	s_or_b64 exec, exec, s[8:9]
	s_waitcnt lgkmcnt(5)
	v_mul_f32 v192, v125, v112
	v_mul_f32 v112, v127, v112
	v_mul_f32 v193, v141, v113
	v_mul_f32 v113, v148, v113
	ds_read_b128 v[116:119], v134 offset:29440
	ds_read_b128 v[100:103], v134 offset:33536
	ds_read_b128 v[108:111], v134 offset:37632
	ds_read_b128 v[88:91], v134 offset:25344
	ds_read_b128 v[80:83], v134 offset:41728
	ds_read2_b32 v[120:121], v152 offset0:96 offset1:112
	v_fma_f32 v192, v149, v114, v192
	v_fma_f32 v112, v150, v114, v112
	v_fma_f32 v114, v151, v115, v193
	v_fma_f32 v113, v191, v115, v113
	v_add_f32_e32 v114, v192, v114
	v_add_f32_e32 v112, v112, v113
	s_nop 0
	v_add_f32_dpp v113, v114, v114 row_ror:8 row_mask:0xf bank_mask:0xf bound_ctrl:1
	v_add_f32_dpp v112, v112, v112 row_ror:8 row_mask:0xf bank_mask:0xf bound_ctrl:1
	s_waitcnt lgkmcnt(6)
	v_mul_f32 v114, v122, v104
	v_mul_f32 v104, v123, v104
	v_add_f32_dpp v113, v113, v113 row_ror:4 row_mask:0xf bank_mask:0xf bound_ctrl:1
	v_add_f32_dpp v112, v112, v112 row_ror:4 row_mask:0xf bank_mask:0xf bound_ctrl:1
	s_nop 0
	v_add_f32_dpp v113, v113, v113 row_ror:2 row_mask:0xf bank_mask:0xf bound_ctrl:1
	v_add_f32_dpp v112, v112, v112 row_ror:2 row_mask:0xf bank_mask:0xf bound_ctrl:1
	s_nop 0
	v_add_f32_dpp v113, v113, v113 row_ror:1 row_mask:0xf bank_mask:0xf bound_ctrl:1
	v_add_f32_dpp v112, v112, v112 row_ror:1 row_mask:0xf bank_mask:0xf bound_ctrl:1
	v_fma_f32 v114, v113, v96, v114
	v_fma_f32 v96, v112, v96, v104
	v_fma_f32 v125, v125, v92, v114
	v_fma_f32 v127, v127, v92, v96
	v_mul_f32 v92, v122, v105
	v_fma_f32 v92, v113, v97, v92
	v_fma_f32 v141, v141, v93, v92
	v_mul_f32 v92, v123, v105
	v_fma_f32 v92, v112, v97, v92
	v_fma_f32 v148, v148, v93, v92
	v_mul_f32 v92, v122, v106
	v_mul_f32 v93, v141, v85
	v_fma_f32 v92, v113, v98, v92
	v_mul_f32 v85, v148, v85
	v_fma_f32 v149, v149, v94, v92
	v_mul_f32 v92, v123, v106
	v_fma_f32 v92, v112, v98, v92
	v_fma_f32 v150, v150, v94, v92
	v_mul_f32 v92, v122, v107
	v_fma_f32 v92, v113, v99, v92
	v_fma_f32 v151, v151, v95, v92
	v_mul_f32 v92, v123, v107
	v_fma_f32 v92, v112, v99, v92
	v_fma_f32 v191, v191, v95, v92
	v_mul_f32 v92, v125, v84
	v_mul_f32 v84, v127, v84
	v_fma_f32 v92, v149, v86, v92
	v_fma_f32 v84, v150, v86, v84
	v_fma_f32 v86, v151, v87, v93
	v_fma_f32 v85, v191, v87, v85
	v_add_f32_e32 v86, v92, v86
	v_add_f32_e32 v87, v84, v85
	v_mov_b32_e32 v85, 0
	v_add_f32_dpp v84, v86, v86 row_ror:8 row_mask:0xf bank_mask:0xf bound_ctrl:1
	v_add_f32_dpp v86, v87, v87 row_ror:8 row_mask:0xf bank_mask:0xf bound_ctrl:1
	v_mov_b32_e32 v87, 0
	v_add_f32_dpp v84, v84, v84 row_ror:4 row_mask:0xf bank_mask:0xf bound_ctrl:1
	v_add_f32_dpp v86, v86, v86 row_ror:4 row_mask:0xf bank_mask:0xf bound_ctrl:1
	s_nop 0
	v_add_f32_dpp v84, v84, v84 row_ror:2 row_mask:0xf bank_mask:0xf bound_ctrl:1
	v_add_f32_dpp v86, v86, v86 row_ror:2 row_mask:0xf bank_mask:0xf bound_ctrl:1
	s_nop 0
	v_mov_b32_dpp v85, v84 row_ror:1 row_mask:0xf bank_mask:0xf
	v_mov_b32_dpp v87, v86 row_ror:1 row_mask:0xf bank_mask:0xf
	s_and_saveexec_b64 s[8:9], s[40:41]
	v_add_f32_e32 v86, v86, v87
	v_add_f32_e32 v84, v84, v85
	ds_write2_b32 v153, v84, v86 offset0:64 offset1:80
	s_or_b64 exec, exec, s[8:9]
	s_waitcnt lgkmcnt(5)
	v_mul_f32 v192, v125, v116
	v_mul_f32 v116, v127, v116
	v_mul_f32 v193, v141, v117
	v_mul_f32 v117, v148, v117
	ds_read_b128 v[112:115], v134 offset:29696
	ds_read_b128 v[96:99], v134 offset:33792
	ds_read_b128 v[104:107], v134 offset:37888
	ds_read_b128 v[92:95], v134 offset:25600
	ds_read_b128 v[84:87], v134 offset:41984
	ds_read2_b32 v[122:123], v152 offset0:128 offset1:144
	v_fma_f32 v192, v149, v118, v192
	v_fma_f32 v116, v150, v118, v116
	v_fma_f32 v118, v151, v119, v193
	v_fma_f32 v117, v191, v119, v117
	v_add_f32_e32 v118, v192, v118
	v_add_f32_e32 v116, v116, v117
	s_nop 0
	v_add_f32_dpp v117, v118, v118 row_ror:8 row_mask:0xf bank_mask:0xf bound_ctrl:1
	v_add_f32_dpp v116, v116, v116 row_ror:8 row_mask:0xf bank_mask:0xf bound_ctrl:1
	s_waitcnt lgkmcnt(6)
	v_mul_f32 v118, v120, v108
	v_mul_f32 v108, v121, v108
	v_add_f32_dpp v117, v117, v117 row_ror:4 row_mask:0xf bank_mask:0xf bound_ctrl:1
	v_add_f32_dpp v116, v116, v116 row_ror:4 row_mask:0xf bank_mask:0xf bound_ctrl:1
	s_nop 0
	v_add_f32_dpp v117, v117, v117 row_ror:2 row_mask:0xf bank_mask:0xf bound_ctrl:1
	v_add_f32_dpp v116, v116, v116 row_ror:2 row_mask:0xf bank_mask:0xf bound_ctrl:1
	s_nop 0
	v_add_f32_dpp v117, v117, v117 row_ror:1 row_mask:0xf bank_mask:0xf bound_ctrl:1
	v_add_f32_dpp v116, v116, v116 row_ror:1 row_mask:0xf bank_mask:0xf bound_ctrl:1
	v_fma_f32 v118, v117, v100, v118
	v_fma_f32 v100, v116, v100, v108
	v_fma_f32 v125, v125, v88, v118
	v_fma_f32 v127, v127, v88, v100
	v_mul_f32 v88, v120, v109
	v_fma_f32 v88, v117, v101, v88
	v_fma_f32 v141, v141, v89, v88
	v_mul_f32 v88, v121, v109
	v_fma_f32 v88, v116, v101, v88
	v_fma_f32 v148, v148, v89, v88
	v_mul_f32 v88, v120, v110
	v_mul_f32 v89, v141, v81
	v_fma_f32 v88, v117, v102, v88
	v_mul_f32 v81, v148, v81
	v_fma_f32 v149, v149, v90, v88
	v_mul_f32 v88, v121, v110
	v_fma_f32 v88, v116, v102, v88
	v_fma_f32 v150, v150, v90, v88
	v_mul_f32 v88, v120, v111
	v_fma_f32 v88, v117, v103, v88
	v_fma_f32 v151, v151, v91, v88
	v_mul_f32 v88, v121, v111
	v_fma_f32 v88, v116, v103, v88
	v_fma_f32 v191, v191, v91, v88
	v_mul_f32 v88, v125, v80
	v_mul_f32 v80, v127, v80
	v_fma_f32 v88, v149, v82, v88
	v_fma_f32 v80, v150, v82, v80
	v_fma_f32 v82, v151, v83, v89
	v_fma_f32 v81, v191, v83, v81
	v_add_f32_e32 v82, v88, v82
	v_add_f32_e32 v83, v80, v81
	v_mov_b32_e32 v81, 0
	v_add_f32_dpp v80, v82, v82 row_ror:8 row_mask:0xf bank_mask:0xf bound_ctrl:1
	v_add_f32_dpp v82, v83, v83 row_ror:8 row_mask:0xf bank_mask:0xf bound_ctrl:1
	v_mov_b32_e32 v83, 0
	v_add_f32_dpp v80, v80, v80 row_ror:4 row_mask:0xf bank_mask:0xf bound_ctrl:1
	v_add_f32_dpp v82, v82, v82 row_ror:4 row_mask:0xf bank_mask:0xf bound_ctrl:1
	s_nop 0
	v_add_f32_dpp v80, v80, v80 row_ror:2 row_mask:0xf bank_mask:0xf bound_ctrl:1
	v_add_f32_dpp v82, v82, v82 row_ror:2 row_mask:0xf bank_mask:0xf bound_ctrl:1
	s_nop 0
	v_mov_b32_dpp v81, v80 row_ror:1 row_mask:0xf bank_mask:0xf
	v_mov_b32_dpp v83, v82 row_ror:1 row_mask:0xf bank_mask:0xf
	s_and_saveexec_b64 s[8:9], s[40:41]
	v_add_f32_e32 v82, v82, v83
	v_add_f32_e32 v80, v80, v81
	ds_write2_b32 v153, v80, v82 offset0:96 offset1:112
	s_or_b64 exec, exec, s[8:9]
	s_waitcnt lgkmcnt(5)
	v_mul_f32 v192, v125, v112
	v_mul_f32 v112, v127, v112
	v_mul_f32 v193, v141, v113
	v_mul_f32 v113, v148, v113
	ds_read_b128 v[116:119], v134 offset:29952
	ds_read_b128 v[100:103], v134 offset:34048
	ds_read_b128 v[108:111], v134 offset:38144
	ds_read_b128 v[88:91], v134 offset:25856
	ds_read_b128 v[80:83], v134 offset:42240
	ds_read2_b32 v[120:121], v152 offset0:160 offset1:176
	v_fma_f32 v192, v149, v114, v192
	v_fma_f32 v112, v150, v114, v112
	v_fma_f32 v114, v151, v115, v193
	v_fma_f32 v113, v191, v115, v113
	v_add_f32_e32 v114, v192, v114
	v_add_f32_e32 v112, v112, v113
	s_nop 0
	v_add_f32_dpp v113, v114, v114 row_ror:8 row_mask:0xf bank_mask:0xf bound_ctrl:1
	v_add_f32_dpp v112, v112, v112 row_ror:8 row_mask:0xf bank_mask:0xf bound_ctrl:1
	s_waitcnt lgkmcnt(6)
	v_mul_f32 v114, v122, v104
	v_mul_f32 v104, v123, v104
	v_add_f32_dpp v113, v113, v113 row_ror:4 row_mask:0xf bank_mask:0xf bound_ctrl:1
	v_add_f32_dpp v112, v112, v112 row_ror:4 row_mask:0xf bank_mask:0xf bound_ctrl:1
	s_nop 0
	v_add_f32_dpp v113, v113, v113 row_ror:2 row_mask:0xf bank_mask:0xf bound_ctrl:1
	v_add_f32_dpp v112, v112, v112 row_ror:2 row_mask:0xf bank_mask:0xf bound_ctrl:1
	s_nop 0
	v_add_f32_dpp v113, v113, v113 row_ror:1 row_mask:0xf bank_mask:0xf bound_ctrl:1
	v_add_f32_dpp v112, v112, v112 row_ror:1 row_mask:0xf bank_mask:0xf bound_ctrl:1
	v_fma_f32 v114, v113, v96, v114
	v_fma_f32 v96, v112, v96, v104
	v_fma_f32 v125, v125, v92, v114
	v_fma_f32 v127, v127, v92, v96
	v_mul_f32 v92, v122, v105
	v_fma_f32 v92, v113, v97, v92
	v_fma_f32 v141, v141, v93, v92
	v_mul_f32 v92, v123, v105
	v_fma_f32 v92, v112, v97, v92
	v_fma_f32 v148, v148, v93, v92
	v_mul_f32 v92, v122, v106
	v_mul_f32 v93, v141, v85
	v_fma_f32 v92, v113, v98, v92
	v_mul_f32 v85, v148, v85
	v_fma_f32 v149, v149, v94, v92
	v_mul_f32 v92, v123, v106
	v_fma_f32 v92, v112, v98, v92
	v_fma_f32 v150, v150, v94, v92
	v_mul_f32 v92, v122, v107
	v_fma_f32 v92, v113, v99, v92
	v_fma_f32 v151, v151, v95, v92
	v_mul_f32 v92, v123, v107
	v_fma_f32 v92, v112, v99, v92
	v_fma_f32 v191, v191, v95, v92
	v_mul_f32 v92, v125, v84
	v_mul_f32 v84, v127, v84
	v_fma_f32 v92, v149, v86, v92
	v_fma_f32 v84, v150, v86, v84
	v_fma_f32 v86, v151, v87, v93
	v_fma_f32 v85, v191, v87, v85
	v_add_f32_e32 v86, v92, v86
	v_add_f32_e32 v87, v84, v85
	v_mov_b32_e32 v85, 0
	v_add_f32_dpp v84, v86, v86 row_ror:8 row_mask:0xf bank_mask:0xf bound_ctrl:1
	v_add_f32_dpp v86, v87, v87 row_ror:8 row_mask:0xf bank_mask:0xf bound_ctrl:1
	v_mov_b32_e32 v87, 0
	v_add_f32_dpp v84, v84, v84 row_ror:4 row_mask:0xf bank_mask:0xf bound_ctrl:1
	v_add_f32_dpp v86, v86, v86 row_ror:4 row_mask:0xf bank_mask:0xf bound_ctrl:1
	s_nop 0
	v_add_f32_dpp v84, v84, v84 row_ror:2 row_mask:0xf bank_mask:0xf bound_ctrl:1
	v_add_f32_dpp v86, v86, v86 row_ror:2 row_mask:0xf bank_mask:0xf bound_ctrl:1
	s_nop 0
	v_mov_b32_dpp v85, v84 row_ror:1 row_mask:0xf bank_mask:0xf
	v_mov_b32_dpp v87, v86 row_ror:1 row_mask:0xf bank_mask:0xf
	s_and_saveexec_b64 s[8:9], s[40:41]
	v_add_f32_e32 v86, v86, v87
	v_add_f32_e32 v84, v84, v85
	ds_write2_b32 v153, v84, v86 offset0:128 offset1:144
	s_or_b64 exec, exec, s[8:9]
	s_waitcnt lgkmcnt(5)
	v_mul_f32 v192, v125, v116
	v_mul_f32 v116, v127, v116
	v_mul_f32 v193, v141, v117
	v_mul_f32 v117, v148, v117
	ds_read_b128 v[112:115], v134 offset:30208
	ds_read_b128 v[96:99], v134 offset:34304
	ds_read_b128 v[104:107], v134 offset:38400
	ds_read_b128 v[92:95], v134 offset:26112
	ds_read_b128 v[84:87], v134 offset:42496
	ds_read2_b32 v[122:123], v152 offset0:192 offset1:208
	v_fma_f32 v192, v149, v118, v192
	v_fma_f32 v116, v150, v118, v116
	v_fma_f32 v118, v151, v119, v193
	v_fma_f32 v117, v191, v119, v117
	v_add_f32_e32 v118, v192, v118
	v_add_f32_e32 v116, v116, v117
	s_nop 0
	v_add_f32_dpp v117, v118, v118 row_ror:8 row_mask:0xf bank_mask:0xf bound_ctrl:1
	v_add_f32_dpp v116, v116, v116 row_ror:8 row_mask:0xf bank_mask:0xf bound_ctrl:1
	s_waitcnt lgkmcnt(6)
	v_mul_f32 v118, v120, v108
	v_mul_f32 v108, v121, v108
	v_add_f32_dpp v117, v117, v117 row_ror:4 row_mask:0xf bank_mask:0xf bound_ctrl:1
	v_add_f32_dpp v116, v116, v116 row_ror:4 row_mask:0xf bank_mask:0xf bound_ctrl:1
	s_nop 0
	v_add_f32_dpp v117, v117, v117 row_ror:2 row_mask:0xf bank_mask:0xf bound_ctrl:1
	v_add_f32_dpp v116, v116, v116 row_ror:2 row_mask:0xf bank_mask:0xf bound_ctrl:1
	s_nop 0
	v_add_f32_dpp v117, v117, v117 row_ror:1 row_mask:0xf bank_mask:0xf bound_ctrl:1
	v_add_f32_dpp v116, v116, v116 row_ror:1 row_mask:0xf bank_mask:0xf bound_ctrl:1
	v_fma_f32 v118, v117, v100, v118
	v_fma_f32 v100, v116, v100, v108
	v_fma_f32 v125, v125, v88, v118
	v_fma_f32 v127, v127, v88, v100
	v_mul_f32 v88, v120, v109
	v_fma_f32 v88, v117, v101, v88
	v_fma_f32 v141, v141, v89, v88
	v_mul_f32 v88, v121, v109
	v_fma_f32 v88, v116, v101, v88
	v_fma_f32 v148, v148, v89, v88
	v_mul_f32 v88, v120, v110
	v_mul_f32 v89, v141, v81
	v_fma_f32 v88, v117, v102, v88
	v_mul_f32 v81, v148, v81
	v_fma_f32 v149, v149, v90, v88
	v_mul_f32 v88, v121, v110
	v_fma_f32 v88, v116, v102, v88
	v_fma_f32 v150, v150, v90, v88
	v_mul_f32 v88, v120, v111
	v_fma_f32 v88, v117, v103, v88
	v_fma_f32 v151, v151, v91, v88
	v_mul_f32 v88, v121, v111
	v_fma_f32 v88, v116, v103, v88
	v_fma_f32 v191, v191, v91, v88
	v_mul_f32 v88, v125, v80
	v_mul_f32 v80, v127, v80
	v_fma_f32 v88, v149, v82, v88
	v_fma_f32 v80, v150, v82, v80
	v_fma_f32 v82, v151, v83, v89
	v_fma_f32 v81, v191, v83, v81
	v_add_f32_e32 v82, v88, v82
	v_add_f32_e32 v83, v80, v81
	v_mov_b32_e32 v81, 0
	v_add_f32_dpp v80, v82, v82 row_ror:8 row_mask:0xf bank_mask:0xf bound_ctrl:1
	v_add_f32_dpp v82, v83, v83 row_ror:8 row_mask:0xf bank_mask:0xf bound_ctrl:1
	v_mov_b32_e32 v83, 0
	v_add_f32_dpp v80, v80, v80 row_ror:4 row_mask:0xf bank_mask:0xf bound_ctrl:1
	v_add_f32_dpp v82, v82, v82 row_ror:4 row_mask:0xf bank_mask:0xf bound_ctrl:1
	s_nop 0
	v_add_f32_dpp v80, v80, v80 row_ror:2 row_mask:0xf bank_mask:0xf bound_ctrl:1
	v_add_f32_dpp v82, v82, v82 row_ror:2 row_mask:0xf bank_mask:0xf bound_ctrl:1
	s_nop 0
	v_mov_b32_dpp v81, v80 row_ror:1 row_mask:0xf bank_mask:0xf
	v_mov_b32_dpp v83, v82 row_ror:1 row_mask:0xf bank_mask:0xf
	s_and_saveexec_b64 s[8:9], s[40:41]
	v_add_f32_e32 v82, v82, v83
	v_add_f32_e32 v80, v80, v81
	ds_write2_b32 v153, v80, v82 offset0:160 offset1:176
	s_or_b64 exec, exec, s[8:9]
	s_waitcnt lgkmcnt(5)
	v_mul_f32 v192, v125, v112
	v_mul_f32 v112, v127, v112
	v_mul_f32 v193, v141, v113
	v_mul_f32 v113, v148, v113
	ds_read_b128 v[116:119], v134 offset:30464
	ds_read_b128 v[100:103], v134 offset:34560
	ds_read_b128 v[108:111], v134 offset:38656
	ds_read_b128 v[88:91], v134 offset:26368
	ds_read_b128 v[80:83], v134 offset:42752
	ds_read2_b32 v[120:121], v152 offset0:224 offset1:240
	v_fma_f32 v112, v150, v114, v112
	v_fma_f32 v192, v149, v114, v192
	v_fma_f32 v114, v151, v115, v193
	v_fma_f32 v113, v191, v115, v113
	v_add_f32_e32 v114, v192, v114
	v_add_f32_e32 v112, v112, v113
	s_nop 1
	v_add_f32_dpp v112, v112, v112 row_ror:8 row_mask:0xf bank_mask:0xf bound_ctrl:1
	v_add_f32_dpp v113, v114, v114 row_ror:8 row_mask:0xf bank_mask:0xf bound_ctrl:1
	s_nop 0
	v_add_f32_dpp v112, v112, v112 row_ror:4 row_mask:0xf bank_mask:0xf bound_ctrl:1
	v_add_f32_dpp v113, v113, v113 row_ror:4 row_mask:0xf bank_mask:0xf bound_ctrl:1
	s_nop 0
	v_add_f32_dpp v112, v112, v112 row_ror:2 row_mask:0xf bank_mask:0xf bound_ctrl:1
	v_add_f32_dpp v113, v113, v113 row_ror:2 row_mask:0xf bank_mask:0xf bound_ctrl:1
	s_nop 0
	v_add_f32_dpp v114, v112, v112 row_ror:1 row_mask:0xf bank_mask:0xf bound_ctrl:1
	s_waitcnt lgkmcnt(6)
	v_mul_f32 v112, v122, v104
	v_add_f32_dpp v113, v113, v113 row_ror:1 row_mask:0xf bank_mask:0xf bound_ctrl:1
	v_fma_f32 v112, v113, v96, v112
	v_mul_f32 v104, v123, v104
	v_fma_f32 v96, v114, v96, v104
	v_fma_f32 v112, v125, v92, v112
	v_mul_f32 v104, v123, v105
	v_fma_f32 v92, v127, v92, v96
	v_mul_f32 v96, v122, v105
	v_fma_f32 v96, v113, v97, v96
	v_fma_f32 v97, v114, v97, v104
	v_mul_f32 v104, v123, v106
	v_fma_f32 v96, v141, v93, v96
	v_fma_f32 v93, v148, v93, v97
	v_mul_f32 v97, v122, v106
	v_fma_f32 v97, v113, v98, v97
	v_fma_f32 v98, v114, v98, v104
	v_mul_f32 v104, v123, v107
	v_fma_f32 v97, v149, v94, v97
	v_fma_f32 v94, v150, v94, v98
	v_mul_f32 v98, v122, v107
	v_fma_f32 v98, v113, v99, v98
	v_fma_f32 v99, v114, v99, v104
	v_mul_f32 v104, v96, v85
	v_mul_f32 v85, v93, v85
	v_fma_f32 v98, v151, v95, v98
	v_fma_f32 v95, v191, v95, v99
	v_mul_f32 v99, v112, v84
	v_mul_f32 v84, v92, v84
	v_fma_f32 v99, v97, v86, v99
	v_fma_f32 v84, v94, v86, v84
	v_fma_f32 v86, v98, v87, v104
	v_fma_f32 v85, v95, v87, v85
	v_add_f32_e32 v86, v99, v86
	v_add_f32_e32 v87, v84, v85
	v_mov_b32_e32 v85, 0
	v_add_f32_dpp v84, v86, v86 row_ror:8 row_mask:0xf bank_mask:0xf bound_ctrl:1
	v_add_f32_dpp v86, v87, v87 row_ror:8 row_mask:0xf bank_mask:0xf bound_ctrl:1
	v_mov_b32_e32 v87, 0
	v_add_f32_dpp v84, v84, v84 row_ror:4 row_mask:0xf bank_mask:0xf bound_ctrl:1
	v_add_f32_dpp v86, v86, v86 row_ror:4 row_mask:0xf bank_mask:0xf bound_ctrl:1
	s_nop 0
	v_add_f32_dpp v84, v84, v84 row_ror:2 row_mask:0xf bank_mask:0xf bound_ctrl:1
	v_add_f32_dpp v86, v86, v86 row_ror:2 row_mask:0xf bank_mask:0xf bound_ctrl:1
	s_nop 0
	v_mov_b32_dpp v85, v84 row_ror:1 row_mask:0xf bank_mask:0xf
	v_mov_b32_dpp v87, v86 row_ror:1 row_mask:0xf bank_mask:0xf
	s_and_saveexec_b64 s[8:9], s[40:41]
	v_add_f32_e32 v86, v86, v87
	v_add_f32_e32 v84, v84, v85
	ds_write2_b32 v153, v84, v86 offset0:192 offset1:208
	s_or_b64 exec, exec, s[8:9]
	s_waitcnt lgkmcnt(5)
	v_mul_f32 v84, v112, v116
	v_mul_f32 v86, v96, v117
	v_mul_f32 v85, v92, v116
	v_mul_f32 v87, v93, v117
	v_fma_f32 v84, v97, v118, v84
	v_fma_f32 v86, v98, v119, v86
	v_fma_f32 v85, v94, v118, v85
	v_fma_f32 v87, v95, v119, v87
	v_add_f32_e32 v84, v84, v86
	v_add_f32_e32 v85, v85, v87
	s_nop 0
	v_add_f32_dpp v84, v84, v84 row_ror:8 row_mask:0xf bank_mask:0xf bound_ctrl:1
	s_waitcnt lgkmcnt(0)
	v_mul_f32 v86, v120, v109
	v_mul_f32 v87, v121, v109
	v_add_f32_dpp v84, v84, v84 row_ror:4 row_mask:0xf bank_mask:0xf bound_ctrl:1
	s_nop 1
	v_add_f32_dpp v84, v84, v84 row_ror:2 row_mask:0xf bank_mask:0xf bound_ctrl:1
	s_nop 1
	v_add_f32_dpp v99, v84, v84 row_ror:1 row_mask:0xf bank_mask:0xf bound_ctrl:1
	v_add_f32_dpp v84, v85, v85 row_ror:8 row_mask:0xf bank_mask:0xf bound_ctrl:1
	v_mul_f32 v85, v121, v108
	v_fma_f32 v86, v99, v101, v86
	v_fma_f32 v86, v96, v89, v86
	v_add_f32_dpp v84, v84, v84 row_ror:4 row_mask:0xf bank_mask:0xf bound_ctrl:1
	s_nop 1
	v_add_f32_dpp v84, v84, v84 row_ror:2 row_mask:0xf bank_mask:0xf bound_ctrl:1
	s_nop 1
	v_add_f32_dpp v104, v84, v84 row_ror:1 row_mask:0xf bank_mask:0xf bound_ctrl:1
	v_mul_f32 v84, v120, v108
	v_fma_f32 v85, v104, v100, v85
	v_fma_f32 v87, v104, v101, v87
	v_fma_f32 v84, v99, v100, v84
	v_fma_f32 v85, v92, v88, v85
	v_fma_f32 v87, v93, v89, v87
	v_mul_f32 v89, v86, v81
	v_fma_f32 v84, v112, v88, v84
	v_mul_f32 v88, v120, v110
	v_mul_f32 v81, v87, v81
	v_fma_f32 v88, v99, v102, v88
	v_fma_f32 v96, v97, v90, v88
	v_mul_f32 v88, v121, v110
	v_fma_f32 v88, v104, v102, v88
	v_fma_f32 v97, v94, v90, v88
	v_mul_f32 v88, v120, v111
	v_fma_f32 v88, v99, v103, v88
	v_fma_f32 v98, v98, v91, v88
	v_mul_f32 v88, v121, v111
	v_fma_f32 v88, v104, v103, v88
	v_fma_f32 v99, v95, v91, v88
	v_mul_f32 v88, v84, v80
	v_mul_f32 v80, v85, v80
	v_fma_f32 v88, v96, v82, v88
	v_fma_f32 v80, v97, v82, v80
	v_fma_f32 v82, v98, v83, v89
	v_fma_f32 v81, v99, v83, v81
	v_add_f32_e32 v82, v88, v82
	v_add_f32_e32 v83, v80, v81
	v_mov_b32_e32 v81, 0
	v_add_f32_dpp v80, v82, v82 row_ror:8 row_mask:0xf bank_mask:0xf bound_ctrl:1
	v_add_f32_dpp v82, v83, v83 row_ror:8 row_mask:0xf bank_mask:0xf bound_ctrl:1
	v_mov_b32_e32 v83, 0
	v_add_f32_dpp v80, v80, v80 row_ror:4 row_mask:0xf bank_mask:0xf bound_ctrl:1
	v_add_f32_dpp v82, v82, v82 row_ror:4 row_mask:0xf bank_mask:0xf bound_ctrl:1
	s_nop 0
	v_add_f32_dpp v80, v80, v80 row_ror:2 row_mask:0xf bank_mask:0xf bound_ctrl:1
	v_add_f32_dpp v82, v82, v82 row_ror:2 row_mask:0xf bank_mask:0xf bound_ctrl:1
	s_nop 0
	v_mov_b32_dpp v81, v80 row_ror:1 row_mask:0xf bank_mask:0xf
	v_mov_b32_dpp v83, v82 row_ror:1 row_mask:0xf bank_mask:0xf
	s_and_saveexec_b64 s[8:9], s[40:41]
	v_add_f32_e32 v82, v82, v83
	v_add_f32_e32 v80, v80, v81
	ds_write2_b32 v153, v80, v82 offset0:224 offset1:240
	s_or_b64 exec, exec, s[8:9]
	s_and_saveexec_b64 s[8:9], s[38:39]
	s_cbranch_execz .LBB0_415
	v_add_f32_e32 v88, v0, v64
	v_min_f32_e32 v92, 0, v88
	v_mul_f32_e64 v88, |v88|, s62
	v_exp_f32_e32 v88, v88
	v_add_f32_e32 v89, v1, v65
	v_add_f32_e32 v90, v2, v66
	v_add_f32_e32 v91, v3, v67
	v_add_f32_e32 v88, 1.0, v88
	v_cmp_gt_f32_e32 vcc, s5, v88
	s_mov_b32 s4, 0xf800000
	v_add_f32_e32 v80, v4, v60
	v_cndmask_b32_e64 v93, 0, 32, vcc
	v_ldexp_f32 v88, v88, v93
	v_log_f32_e32 v88, v88
	v_mul_f32_e32 v80, 0xbfb8aa3b, v80
	v_exp_f32_e32 v82, v80
	v_add_f32_e32 v80, v5, v61
	v_mul_f32_e32 v93, 0x3f317217, v88
	v_fma_f32 v93, v88, s76, -v93
	v_fmac_f32_e32 v93, 0x3377d1cf, v88
	v_fmac_f32_e32 v93, 0x3f317217, v88
	v_cmp_lt_f32_e64 s[42:43], |v88|, s77
	v_mul_f32_e32 v80, 0xbfb8aa3b, v80
	v_exp_f32_e32 v83, v80
	v_cndmask_b32_e64 v88, v88, v93, s[42:43]
	v_cndmask_b32_e32 v93, 0, v171, vcc
	v_sub_f32_e32 v88, v88, v93
	v_sub_f32_e32 v88, v92, v88
	v_min_f32_e32 v92, 0, v89
	v_mul_f32_e64 v89, |v89|, s62
	v_exp_f32_e32 v89, v89
	v_add_f32_e32 v88, -0.5, v88
	v_mul_f32_e32 v88, 0x3fb8aa3b, v88
	v_exp_f32_e32 v88, v88
	v_add_f32_e32 v89, 1.0, v89
	v_cmp_gt_f32_e32 vcc, s5, v89
	v_pk_add_f32 v[82:83], v[82:83], 1.0 op_sel_hi:[1,0]
	v_mul_f32_e32 v88, 0xbfb8aa3b, v88
	v_cndmask_b32_e64 v93, 0, 32, vcc
	v_ldexp_f32 v89, v89, v93
	v_log_f32_e32 v89, v89
	v_exp_f32_e32 v88, v88
	v_add_f32_e32 v80, v6, v62
	v_add_f32_e32 v81, v7, v63
	v_mul_f32_e32 v93, 0x3f317217, v89
	v_fma_f32 v93, v89, s76, -v93
	v_fmac_f32_e32 v93, 0x3377d1cf, v89
	v_fmac_f32_e32 v93, 0x3f317217, v89
	v_cmp_lt_f32_e64 s[42:43], |v89|, s77
	v_mul_f32_e32 v80, 0xbfb8aa3b, v80
	v_mul_f32_e32 v81, 0xbfb8aa3b, v81
	v_cndmask_b32_e64 v89, v89, v93, s[42:43]
	v_cndmask_b32_e32 v93, 0, v171, vcc
	v_sub_f32_e32 v89, v89, v93
	v_sub_f32_e32 v89, v92, v89
	v_min_f32_e32 v92, 0, v90
	v_mul_f32_e64 v90, |v90|, s62
	v_exp_f32_e32 v90, v90
	v_add_f32_e32 v89, -0.5, v89
	v_mul_f32_e32 v89, 0x3fb8aa3b, v89
	v_exp_f32_e32 v89, v89
	v_add_f32_e32 v90, 1.0, v90
	v_cmp_gt_f32_e32 vcc, s5, v90
	v_exp_f32_e32 v80, v80
	v_mul_f32_e32 v89, 0xbfb8aa3b, v89
	v_cndmask_b32_e64 v93, 0, 32, vcc
	v_ldexp_f32 v90, v90, v93
	v_log_f32_e32 v90, v90
	v_exp_f32_e32 v89, v89
	v_exp_f32_e32 v81, v81
	v_mul_f32_e32 v93, 0x3f317217, v90
	v_fma_f32 v93, v90, s76, -v93
	v_fmac_f32_e32 v93, 0x3377d1cf, v90
	v_fmac_f32_e32 v93, 0x3f317217, v90
	v_cmp_lt_f32_e64 s[42:43], |v90|, s77
	v_pk_add_f32 v[80:81], v[80:81], 1.0 op_sel_hi:[1,0]
	s_nop 0
	v_cndmask_b32_e64 v90, v90, v93, s[42:43]
	v_cndmask_b32_e32 v93, 0, v171, vcc
	v_sub_f32_e32 v90, v90, v93
	v_sub_f32_e32 v90, v92, v90
	v_min_f32_e32 v92, 0, v91
	v_mul_f32_e64 v91, |v91|, s62
	v_exp_f32_e32 v91, v91
	v_add_f32_e32 v90, -0.5, v90
	v_mul_f32_e32 v90, 0x3fb8aa3b, v90
	v_exp_f32_e32 v90, v90
	v_add_f32_e32 v91, 1.0, v91
	v_cmp_gt_f32_e32 vcc, s5, v91
	v_mul_f32_e32 v90, 0xbfb8aa3b, v90
	s_nop 0
	v_cndmask_b32_e64 v93, 0, 32, vcc
	v_ldexp_f32 v91, v91, v93
	v_log_f32_e32 v91, v91
	v_exp_f32_e32 v90, v90
	v_mul_f32_e32 v93, 0x3f317217, v91
	v_fma_f32 v93, v91, s76, -v93
	v_fmac_f32_e32 v93, 0x3377d1cf, v91
	v_fmac_f32_e32 v93, 0x3f317217, v91
	v_cmp_lt_f32_e64 s[42:43], |v91|, s77
	s_nop 1
	v_cndmask_b32_e64 v91, v91, v93, s[42:43]
	v_cndmask_b32_e32 v93, 0, v171, vcc
	v_sub_f32_e32 v91, v91, v93
	v_sub_f32_e32 v91, v92, v91
	v_add_f32_e32 v91, -0.5, v91
	v_mul_f32_e32 v91, 0x3fb8aa3b, v91
	v_exp_f32_e32 v91, v91
	v_pk_mul_f32 v[92:93], v[10:11], v[58:59]
	v_mul_f32_e32 v91, 0xbfb8aa3b, v91
	v_exp_f32_e32 v91, v91
	v_pk_mul_f32 v[94:95], v[92:93], v[92:93]
	ds_write_b128 v181, v[88:91]
	v_pk_mul_f32 v[88:89], v[8:9], v[56:57]
	v_pk_mul_f32 v[90:91], v[88:89], v[88:89]
	v_add_f32_e32 v90, v91, v90
	v_add_f32_e32 v90, v94, v90
	v_add_f32_e32 v90, v95, v90
	s_nop 1
	v_add_f32_dpp v90, v90, v90 row_ror:8 row_mask:0xf bank_mask:0xf bound_ctrl:1
	s_nop 1
	v_add_f32_dpp v90, v90, v90 row_ror:4 row_mask:0xf bank_mask:0xf bound_ctrl:1
	s_nop 1
	v_add_f32_dpp v90, v90, v90 row_ror:2 row_mask:0xf bank_mask:0xf bound_ctrl:1
	s_nop 1
	v_add_f32_dpp v90, v90, v90 row_ror:1 row_mask:0xf bank_mask:0xf bound_ctrl:1
	v_cmp_gt_f32_e32 vcc, s4, v90
	v_mul_f32_e32 v91, 0x4f800000, v90
	s_nop 0
	v_cndmask_b32_e32 v90, v90, v91, vcc
	v_sqrt_f32_e32 v91, v90
	s_nop 0
	v_add_u32_e32 v94, -1, v91
	v_fma_f32 v95, -v94, v91, v90
	v_cmp_ge_f32_e64 s[42:43], 0, v95
	v_add_u32_e32 v95, 1, v91
	s_nop 0
	v_cndmask_b32_e64 v94, v91, v94, s[42:43]
	v_fma_f32 v91, -v95, v91, v90
	v_cmp_lt_f32_e64 s[42:43], 0, v91
	s_nop 1
	v_cndmask_b32_e64 v91, v94, v95, s[42:43]
	v_mul_f32_e32 v94, 0x37800000, v91
	v_cndmask_b32_e32 v91, v91, v94, vcc
	v_cmp_class_f32_e32 vcc, v90, v160
	s_nop 1
	v_cndmask_b32_e32 v90, v91, v90, vcc
	v_max_f32_e32 v90, 0x2b8cbccc, v90
	v_div_scale_f32 v91, s[22:23], v90, v90, 1.0
	v_rcp_f32_e32 v94, v91
	s_nop 0
	v_fma_f32 v95, -v91, v94, 1.0
	v_fmac_f32_e32 v94, v95, v94
	v_div_scale_f32 v95, vcc, 1.0, v90, 1.0
	v_mul_f32_e32 v100, v95, v94
	v_fma_f32 v101, -v91, v100, v95
	v_fmac_f32_e32 v100, v101, v94
	v_fma_f32 v91, -v91, v100, v95
	v_div_fmas_f32 v91, v91, v94, v100
	v_div_fixup_f32 v90, v91, v90, 1.0
	v_pk_mul_f32 v[94:95], v[88:89], v[90:91] op_sel_hi:[1,0]
	v_pk_mul_f32 v[92:93], v[92:93], v[90:91] op_sel_hi:[1,0]
	v_xor_b32_e32 v89, 0x80000000, v95
	v_xor_b32_e32 v88, 0x80000000, v94
	v_xor_b32_e32 v91, 0x80000000, v93
	v_xor_b32_e32 v90, 0x80000000, v92
	ds_write_b128 v181, v[88:91] offset:4096
	v_div_scale_f32 v88, s[22:23], v83, v83, 1.0
	v_rcp_f32_e32 v89, v88
	s_nop 0
	v_fma_f32 v90, -v88, v89, 1.0
	v_fmac_f32_e32 v89, v90, v89
	v_div_scale_f32 v90, vcc, 1.0, v83, 1.0
	v_mul_f32_e32 v91, v90, v89
	v_fma_f32 v100, -v88, v91, v90
	v_fmac_f32_e32 v91, v100, v89
	v_fma_f32 v88, -v88, v91, v90
	v_div_fmas_f32 v88, v88, v89, v91
	v_div_fixup_f32 v83, v88, v83, 1.0
	v_div_scale_f32 v88, s[22:23], v82, v82, 1.0
	v_rcp_f32_e32 v89, v88
	s_nop 0
	v_fma_f32 v90, -v88, v89, 1.0
	v_fmac_f32_e32 v89, v90, v89
	v_div_scale_f32 v90, vcc, 1.0, v82, 1.0
	v_mul_f32_e32 v91, v90, v89
	v_fma_f32 v100, -v88, v91, v90
	v_fmac_f32_e32 v91, v100, v89
	v_fma_f32 v88, -v88, v91, v90
	v_div_scale_f32 v90, s[22:23], v81, v81, 1.0
	v_div_fmas_f32 v88, v88, v89, v91
	v_rcp_f32_e32 v91, v90
	v_div_fixup_f32 v82, v88, v82, 1.0
	v_pk_mul_f32 v[88:89], v[82:83], v[94:95]
	v_fma_f32 v94, -v90, v91, 1.0
	v_fmac_f32_e32 v91, v94, v91
	v_div_scale_f32 v94, vcc, 1.0, v81, 1.0
	v_mul_f32_e32 v95, v94, v91
	v_fma_f32 v100, -v90, v95, v94
	v_fmac_f32_e32 v95, v100, v91
	v_fma_f32 v90, -v90, v95, v94
	v_div_fmas_f32 v90, v90, v91, v95
	v_div_fixup_f32 v95, v90, v81, 1.0
	v_div_scale_f32 v81, s[22:23], v80, v80, 1.0
	v_rcp_f32_e32 v90, v81
	s_nop 0
	v_fma_f32 v91, -v81, v90, 1.0
	v_fmac_f32_e32 v90, v91, v90
	v_div_scale_f32 v91, vcc, 1.0, v80, 1.0
	v_mul_f32_e32 v94, v91, v90
	v_fma_f32 v100, -v81, v94, v91
	v_fmac_f32_e32 v94, v100, v90
	v_fma_f32 v81, -v81, v94, v91
	v_div_fmas_f32 v81, v81, v90, v94
	v_div_fixup_f32 v94, v81, v80, 1.0
	v_pk_add_f32 v[80:81], v[82:83], -1.0 op_sel_hi:[1,0]
	v_pk_add_f32 v[82:83], v[94:95], -1.0 op_sel_hi:[1,0]
	v_pk_fma_f32 v[80:81], v[12:13], v[80:81], 1.0 op_sel_hi:[1,1,0]
	v_pk_fma_f32 v[82:83], v[14:15], v[82:83], 1.0 op_sel_hi:[1,1,0]
	v_pk_mul_f32 v[90:91], v[94:95], v[92:93]
	v_pk_mul_f32 v[80:81], v[56:57], v[80:81]
	v_pk_mul_f32 v[82:83], v[58:59], v[82:83]
	ds_write_b128 v181, v[88:91] offset:8192
	ds_write_b128 v181, v[80:83] offset:12288
	ds_write_b128 v181, v[52:55] offset:16384

.LBB0_419:
	ds_read2st64_b32 v[80:81], v179 offset0:184 offset1:188
	v_add_u32_e32 v82, 16, v126
	v_ashrrev_i32_e32 v83, 31, v82
	v_lshlrev_b64 v[82:83], 13, v[82:83]
	v_lshl_add_u64 v[82:83], v[144:145], 0, v[82:83]
	s_waitcnt lgkmcnt(0)
	global_store_dword v[82:83], v80, off
	v_add_u32_e32 v82, 16, v124
	v_ashrrev_i32_e32 v83, 31, v82
	v_lshlrev_b64 v[82:83], 13, v[82:83]
	v_lshl_add_u64 v[82:83], v[144:145], 0, v[82:83]
	global_store_dword v[82:83], v81, off
	ds_read_b128 v[104:107], v134
	ds_read_b128 v[88:91], v134 offset:256
	ds_read_b128 v[108:111], v134 offset:4096
	ds_read_b128 v[112:115], v134 offset:4352
	ds_read_b128 v[116:119], v134 offset:8192
	ds_read_b128 v[92:95], v134 offset:8448
	ds_read_b128 v[192:195], v134 offset:12288
	ds_read_b128 v[100:103], v134 offset:12544
	ds_read_b128 v[196:199], v134 offset:16384
	ds_read_b128 v[80:83], v134 offset:16640
	ds_read2_b32 v[120:121], v189 offset0:32 offset1:48
	s_waitcnt lgkmcnt(8)
	v_mul_f32 v122, v84, v108
	v_mul_f32 v108, v85, v108
	v_mul_f32 v123, v86, v109
	v_mul_f32 v109, v87, v109
	v_fma_f32 v122, v96, v110, v122
	v_fma_f32 v108, v97, v110, v108
	v_fma_f32 v110, v98, v111, v123
	v_fma_f32 v109, v99, v111, v109
	v_add_f32_e32 v110, v122, v110
	v_add_f32_e32 v111, v108, v109
	s_nop 0
	v_add_f32_dpp v110, v110, v110 row_ror:8 row_mask:0xf bank_mask:0xf bound_ctrl:1
	ds_read2_b32 v[108:109], v189 offset1:16
	v_add_f32_dpp v111, v111, v111 row_ror:8 row_mask:0xf bank_mask:0xf bound_ctrl:1
	v_add_f32_dpp v110, v110, v110 row_ror:4 row_mask:0xf bank_mask:0xf bound_ctrl:1
	s_waitcnt lgkmcnt(0)
	v_mul_f32 v122, v108, v192
	v_add_f32_dpp v111, v111, v111 row_ror:4 row_mask:0xf bank_mask:0xf bound_ctrl:1
	v_add_f32_dpp v110, v110, v110 row_ror:2 row_mask:0xf bank_mask:0xf bound_ctrl:1
	s_nop 0
	v_add_f32_dpp v111, v111, v111 row_ror:2 row_mask:0xf bank_mask:0xf bound_ctrl:1
	v_add_f32_dpp v110, v110, v110 row_ror:1 row_mask:0xf bank_mask:0xf bound_ctrl:1
	v_fma_f32 v122, v110, v116, v122
	v_fma_f32 v122, v84, v104, v122
	v_mul_f32 v84, v109, v192
	v_add_f32_dpp v111, v111, v111 row_ror:1 row_mask:0xf bank_mask:0xf bound_ctrl:1
	v_fma_f32 v84, v111, v116, v84
	v_fma_f32 v123, v85, v104, v84
	v_mul_f32 v84, v108, v193
	v_fma_f32 v84, v110, v117, v84
	v_mul_f32 v85, v123, v196
	v_fma_f32 v125, v86, v105, v84
	v_mul_f32 v84, v109, v193
	v_fma_f32 v84, v111, v117, v84
	v_mul_f32 v86, v125, v197
	v_fma_f32 v127, v87, v105, v84
	v_mul_f32 v84, v108, v194
	v_fma_f32 v84, v110, v118, v84
	v_mul_f32 v87, v127, v197
	v_fma_f32 v141, v96, v106, v84
	v_mul_f32 v84, v109, v194
	v_fma_f32 v84, v111, v118, v84
	v_fma_f32 v150, v97, v106, v84
	v_mul_f32 v84, v108, v195
	v_fma_f32 v84, v110, v119, v84
	v_fma_f32 v85, v150, v198, v85
	v_fma_f32 v151, v98, v107, v84
	v_mul_f32 v84, v109, v195
	v_fma_f32 v84, v111, v119, v84
	v_fma_f32 v86, v151, v199, v86
	v_fma_f32 v191, v99, v107, v84
	v_mul_f32 v84, v122, v196
	v_fma_f32 v84, v141, v198, v84
	v_fma_f32 v87, v191, v199, v87
	v_add_f32_e32 v84, v84, v86
	v_add_f32_e32 v86, v85, v87
	v_mov_b32_e32 v85, 0
	v_add_f32_dpp v84, v84, v84 row_ror:8 row_mask:0xf bank_mask:0xf bound_ctrl:1
	v_add_f32_dpp v86, v86, v86 row_ror:8 row_mask:0xf bank_mask:0xf bound_ctrl:1
	v_mov_b32_e32 v87, 0
	v_add_f32_dpp v84, v84, v84 row_ror:4 row_mask:0xf bank_mask:0xf bound_ctrl:1
	v_add_f32_dpp v86, v86, v86 row_ror:4 row_mask:0xf bank_mask:0xf bound_ctrl:1
	s_nop 0
	v_add_f32_dpp v84, v84, v84 row_ror:2 row_mask:0xf bank_mask:0xf bound_ctrl:1
	v_add_f32_dpp v86, v86, v86 row_ror:2 row_mask:0xf bank_mask:0xf bound_ctrl:1
	s_nop 0
	v_mov_b32_dpp v85, v84 row_ror:1 row_mask:0xf bank_mask:0xf
	v_mov_b32_dpp v87, v86 row_ror:1 row_mask:0xf bank_mask:0xf
	s_and_saveexec_b64 s[8:9], s[40:41]
	v_add_f32_e32 v86, v86, v87
	v_add_f32_e32 v84, v84, v85
	ds_write2_b32 v185, v84, v86 offset1:16
	s_or_b64 exec, exec, s[8:9]
	v_mul_f32 v192, v122, v112
	v_mul_f32 v112, v123, v112
	v_mul_f32 v193, v125, v113
	v_mul_f32 v113, v127, v113
	ds_read_b128 v[96:99], v134 offset:512
	ds_read_b128 v[116:119], v134 offset:4608
	ds_read_b128 v[104:107], v134 offset:8704
	ds_read_b128 v[108:111], v134 offset:12800
	ds_read_b128 v[84:87], v134 offset:16896
	ds_read2_b32 v[148:149], v189 offset0:64 offset1:80
	v_fma_f32 v192, v141, v114, v192
	v_fma_f32 v112, v150, v114, v112
	v_fma_f32 v114, v151, v115, v193
	v_fma_f32 v113, v191, v115, v113
	v_add_f32_e32 v114, v192, v114
	v_add_f32_e32 v112, v112, v113
	s_nop 0
	v_add_f32_dpp v113, v114, v114 row_ror:8 row_mask:0xf bank_mask:0xf bound_ctrl:1
	v_add_f32_dpp v112, v112, v112 row_ror:8 row_mask:0xf bank_mask:0xf bound_ctrl:1
	v_mul_f32 v114, v120, v100
	v_mul_f32 v100, v121, v100
	v_add_f32_dpp v113, v113, v113 row_ror:4 row_mask:0xf bank_mask:0xf bound_ctrl:1
	v_add_f32_dpp v112, v112, v112 row_ror:4 row_mask:0xf bank_mask:0xf bound_ctrl:1
	s_nop 0
	v_add_f32_dpp v113, v113, v113 row_ror:2 row_mask:0xf bank_mask:0xf bound_ctrl:1
	v_add_f32_dpp v112, v112, v112 row_ror:2 row_mask:0xf bank_mask:0xf bound_ctrl:1
	s_nop 0
	v_add_f32_dpp v113, v113, v113 row_ror:1 row_mask:0xf bank_mask:0xf bound_ctrl:1
	v_add_f32_dpp v112, v112, v112 row_ror:1 row_mask:0xf bank_mask:0xf bound_ctrl:1
	v_fma_f32 v114, v113, v92, v114
	v_fma_f32 v92, v112, v92, v100
	v_fma_f32 v192, v122, v88, v114
	v_fma_f32 v92, v123, v88, v92
	v_mul_f32 v88, v120, v101
	v_fma_f32 v88, v113, v93, v88
	v_fma_f32 v125, v125, v89, v88
	v_mul_f32 v88, v121, v101
	v_fma_f32 v88, v112, v93, v88
	v_fma_f32 v93, v127, v89, v88
	v_mul_f32 v88, v120, v102
	v_mul_f32 v89, v125, v81
	v_fma_f32 v88, v113, v94, v88
	v_mul_f32 v81, v93, v81
	v_fma_f32 v127, v141, v90, v88
	v_mul_f32 v88, v121, v102
	v_fma_f32 v88, v112, v94, v88
	v_fma_f32 v94, v150, v90, v88
	v_mul_f32 v88, v120, v103
	v_fma_f32 v88, v113, v95, v88
	v_fma_f32 v141, v151, v91, v88
	v_mul_f32 v88, v121, v103
	v_fma_f32 v88, v112, v95, v88
	v_fma_f32 v95, v191, v91, v88
	v_mul_f32 v88, v192, v80
	v_mul_f32 v80, v92, v80
	v_fma_f32 v88, v127, v82, v88
	v_fma_f32 v80, v94, v82, v80
	v_fma_f32 v82, v141, v83, v89
	v_fma_f32 v81, v95, v83, v81
	v_add_f32_e32 v82, v88, v82
	v_add_f32_e32 v83, v80, v81
	v_mov_b32_e32 v81, 0
	v_add_f32_dpp v80, v82, v82 row_ror:8 row_mask:0xf bank_mask:0xf bound_ctrl:1
	v_add_f32_dpp v82, v83, v83 row_ror:8 row_mask:0xf bank_mask:0xf bound_ctrl:1
	v_mov_b32_e32 v83, 0
	v_add_f32_dpp v80, v80, v80 row_ror:4 row_mask:0xf bank_mask:0xf bound_ctrl:1
	v_add_f32_dpp v82, v82, v82 row_ror:4 row_mask:0xf bank_mask:0xf bound_ctrl:1
	s_nop 0
	v_add_f32_dpp v80, v80, v80 row_ror:2 row_mask:0xf bank_mask:0xf bound_ctrl:1
	v_add_f32_dpp v82, v82, v82 row_ror:2 row_mask:0xf bank_mask:0xf bound_ctrl:1
	s_nop 0
	v_mov_b32_dpp v81, v80 row_ror:1 row_mask:0xf bank_mask:0xf
	v_mov_b32_dpp v83, v82 row_ror:1 row_mask:0xf bank_mask:0xf
	s_and_saveexec_b64 s[8:9], s[40:41]
	v_add_f32_e32 v82, v82, v83
	v_add_f32_e32 v80, v80, v81
	ds_write2_b32 v185, v80, v82 offset0:32 offset1:48
	s_or_b64 exec, exec, s[8:9]
	s_waitcnt lgkmcnt(4)
	v_mul_f32 v191, v192, v116
	v_mul_f32 v116, v92, v116
	v_mul_f32 v193, v125, v117
	v_mul_f32 v117, v93, v117
	ds_read_b128 v[88:91], v134 offset:768
	ds_read_b128 v[120:123], v134 offset:4864
	ds_read_b128 v[100:103], v134 offset:8960
	ds_read_b128 v[112:115], v134 offset:13056
	ds_read_b128 v[80:83], v134 offset:17152
	ds_read2_b32 v[150:151], v189 offset0:96 offset1:112
	v_fma_f32 v191, v127, v118, v191
	v_fma_f32 v116, v94, v118, v116
	v_fma_f32 v118, v141, v119, v193
	v_fma_f32 v117, v95, v119, v117
	v_add_f32_e32 v118, v191, v118
	v_add_f32_e32 v116, v116, v117
	s_nop 0
	v_add_f32_dpp v117, v118, v118 row_ror:8 row_mask:0xf bank_mask:0xf bound_ctrl:1
	v_add_f32_dpp v116, v116, v116 row_ror:8 row_mask:0xf bank_mask:0xf bound_ctrl:1
	s_waitcnt lgkmcnt(6)
	v_mul_f32 v118, v148, v108
	v_mul_f32 v108, v149, v108
	v_add_f32_dpp v117, v117, v117 row_ror:4 row_mask:0xf bank_mask:0xf bound_ctrl:1
	v_add_f32_dpp v116, v116, v116 row_ror:4 row_mask:0xf bank_mask:0xf bound_ctrl:1
	s_nop 0
	v_add_f32_dpp v117, v117, v117 row_ror:2 row_mask:0xf bank_mask:0xf bound_ctrl:1
	v_add_f32_dpp v116, v116, v116 row_ror:2 row_mask:0xf bank_mask:0xf bound_ctrl:1
	s_nop 0
	v_add_f32_dpp v117, v117, v117 row_ror:1 row_mask:0xf bank_mask:0xf bound_ctrl:1
	v_add_f32_dpp v116, v116, v116 row_ror:1 row_mask:0xf bank_mask:0xf bound_ctrl:1
	v_fma_f32 v118, v117, v104, v118
	v_fma_f32 v104, v116, v104, v108
	v_fma_f32 v108, v92, v96, v104
	v_mul_f32 v92, v148, v109
	v_fma_f32 v191, v192, v96, v118
	v_fma_f32 v92, v117, v105, v92
	v_fma_f32 v125, v125, v97, v92
	v_mul_f32 v92, v149, v109
	v_fma_f32 v92, v116, v105, v92
	v_fma_f32 v109, v93, v97, v92
	v_mul_f32 v92, v148, v110
	v_mul_f32 v93, v125, v85
	v_fma_f32 v92, v117, v106, v92
	v_mul_f32 v85, v109, v85
	v_fma_f32 v127, v127, v98, v92
	v_mul_f32 v92, v149, v110
	v_fma_f32 v92, v116, v106, v92
	v_fma_f32 v110, v94, v98, v92
	v_mul_f32 v92, v148, v111
	v_fma_f32 v92, v117, v107, v92
	v_fma_f32 v141, v141, v99, v92
	v_mul_f32 v92, v149, v111
	v_fma_f32 v92, v116, v107, v92
	v_fma_f32 v111, v95, v99, v92
	v_mul_f32 v92, v191, v84
	v_mul_f32 v84, v108, v84
	v_fma_f32 v92, v127, v86, v92
	v_fma_f32 v84, v110, v86, v84
	v_fma_f32 v86, v141, v87, v93
	v_fma_f32 v85, v111, v87, v85
	v_add_f32_e32 v86, v92, v86
	v_add_f32_e32 v87, v84, v85
	v_mov_b32_e32 v85, 0
	v_add_f32_dpp v84, v86, v86 row_ror:8 row_mask:0xf bank_mask:0xf bound_ctrl:1
	v_add_f32_dpp v86, v87, v87 row_ror:8 row_mask:0xf bank_mask:0xf bound_ctrl:1
	v_mov_b32_e32 v87, 0
	v_add_f32_dpp v84, v84, v84 row_ror:4 row_mask:0xf bank_mask:0xf bound_ctrl:1
	v_add_f32_dpp v86, v86, v86 row_ror:4 row_mask:0xf bank_mask:0xf bound_ctrl:1
	s_nop 0
	v_add_f32_dpp v84, v84, v84 row_ror:2 row_mask:0xf bank_mask:0xf bound_ctrl:1
	v_add_f32_dpp v86, v86, v86 row_ror:2 row_mask:0xf bank_mask:0xf bound_ctrl:1
	s_nop 0
	v_mov_b32_dpp v85, v84 row_ror:1 row_mask:0xf bank_mask:0xf
	v_mov_b32_dpp v87, v86 row_ror:1 row_mask:0xf bank_mask:0xf
	s_and_saveexec_b64 s[8:9], s[40:41]
	v_add_f32_e32 v86, v86, v87
	v_add_f32_e32 v84, v84, v85
	ds_write2_b32 v185, v84, v86 offset0:64 offset1:80
	s_or_b64 exec, exec, s[8:9]
	s_waitcnt lgkmcnt(4)
	v_mul_f32 v192, v191, v120
	v_mul_f32 v120, v108, v120
	v_mul_f32 v193, v125, v121
	v_mul_f32 v121, v109, v121
	ds_read_b128 v[92:95], v134 offset:1024
	ds_read_b128 v[116:119], v134 offset:5120
	ds_read_b128 v[96:99], v134 offset:9216
	ds_read_b128 v[104:107], v134 offset:13312
	ds_read_b128 v[84:87], v134 offset:17408
	ds_read2_b32 v[148:149], v189 offset0:128 offset1:144
	v_fma_f32 v192, v127, v122, v192
	v_fma_f32 v120, v110, v122, v120
	v_fma_f32 v122, v141, v123, v193
	v_fma_f32 v121, v111, v123, v121
	v_add_f32_e32 v122, v192, v122
	v_add_f32_e32 v120, v120, v121
	s_nop 0
	v_add_f32_dpp v121, v122, v122 row_ror:8 row_mask:0xf bank_mask:0xf bound_ctrl:1
	v_add_f32_dpp v120, v120, v120 row_ror:8 row_mask:0xf bank_mask:0xf bound_ctrl:1
	s_waitcnt lgkmcnt(6)
	v_mul_f32 v122, v150, v112
	v_mul_f32 v112, v151, v112
	v_add_f32_dpp v121, v121, v121 row_ror:4 row_mask:0xf bank_mask:0xf bound_ctrl:1
	v_add_f32_dpp v120, v120, v120 row_ror:4 row_mask:0xf bank_mask:0xf bound_ctrl:1
	s_nop 0
	v_add_f32_dpp v121, v121, v121 row_ror:2 row_mask:0xf bank_mask:0xf bound_ctrl:1
	v_add_f32_dpp v120, v120, v120 row_ror:2 row_mask:0xf bank_mask:0xf bound_ctrl:1
	s_nop 0
	v_add_f32_dpp v121, v121, v121 row_ror:1 row_mask:0xf bank_mask:0xf bound_ctrl:1
	v_fma_f32 v122, v121, v100, v122
	v_add_f32_dpp v120, v120, v120 row_ror:1 row_mask:0xf bank_mask:0xf bound_ctrl:1
	v_fma_f32 v122, v191, v88, v122
	v_fma_f32 v100, v120, v100, v112
	v_fma_f32 v123, v108, v88, v100
	v_mul_f32 v88, v150, v113
	v_fma_f32 v88, v121, v101, v88
	v_fma_f32 v125, v125, v89, v88
	v_mul_f32 v88, v151, v113
	v_fma_f32 v88, v120, v101, v88
	v_fma_f32 v191, v109, v89, v88
	v_mul_f32 v88, v150, v114
	v_mul_f32 v89, v125, v81
	v_fma_f32 v88, v121, v102, v88
	v_mul_f32 v81, v191, v81
	v_fma_f32 v127, v127, v90, v88
	v_mul_f32 v88, v151, v114
	v_fma_f32 v88, v120, v102, v88
	v_fma_f32 v192, v110, v90, v88
	v_mul_f32 v88, v150, v115
	v_fma_f32 v88, v121, v103, v88
	v_fma_f32 v141, v141, v91, v88
	v_mul_f32 v88, v151, v115
	v_fma_f32 v88, v120, v103, v88
	v_fma_f32 v150, v111, v91, v88
	v_mul_f32 v88, v122, v80
	v_mul_f32 v80, v123, v80
	v_fma_f32 v88, v127, v82, v88
	v_fma_f32 v80, v192, v82, v80
	v_fma_f32 v82, v141, v83, v89
	v_fma_f32 v81, v150, v83, v81
	v_add_f32_e32 v82, v88, v82
	v_add_f32_e32 v83, v80, v81
	v_mov_b32_e32 v81, 0
	v_add_f32_dpp v80, v82, v82 row_ror:8 row_mask:0xf bank_mask:0xf bound_ctrl:1
	v_add_f32_dpp v82, v83, v83 row_ror:8 row_mask:0xf bank_mask:0xf bound_ctrl:1
	v_mov_b32_e32 v83, 0
	v_add_f32_dpp v80, v80, v80 row_ror:4 row_mask:0xf bank_mask:0xf bound_ctrl:1
	v_add_f32_dpp v82, v82, v82 row_ror:4 row_mask:0xf bank_mask:0xf bound_ctrl:1
	s_nop 0
	v_add_f32_dpp v80, v80, v80 row_ror:2 row_mask:0xf bank_mask:0xf bound_ctrl:1
	v_add_f32_dpp v82, v82, v82 row_ror:2 row_mask:0xf bank_mask:0xf bound_ctrl:1
	s_nop 0
	v_mov_b32_dpp v81, v80 row_ror:1 row_mask:0xf bank_mask:0xf
	v_mov_b32_dpp v83, v82 row_ror:1 row_mask:0xf bank_mask:0xf
	s_and_saveexec_b64 s[8:9], s[40:41]
	v_add_f32_e32 v82, v82, v83
	v_add_f32_e32 v80, v80, v81
	ds_write2_b32 v185, v80, v82 offset0:96 offset1:112
	s_or_b64 exec, exec, s[8:9]
	s_waitcnt lgkmcnt(4)
	v_mul_f32 v151, v122, v116
	v_mul_f32 v116, v123, v116
	v_mul_f32 v193, v125, v117
	v_mul_f32 v117, v191, v117
	ds_read_b128 v[88:91], v134 offset:1280
	ds_read_b128 v[112:115], v134 offset:5376
	ds_read_b128 v[100:103], v134 offset:9472
	ds_read_b128 v[108:111], v134 offset:13568
	ds_read_b128 v[80:83], v134 offset:17664
	ds_read2_b32 v[120:121], v189 offset0:160 offset1:176
	v_fma_f32 v151, v127, v118, v151
	v_fma_f32 v116, v192, v118, v116
	v_fma_f32 v118, v141, v119, v193
	v_fma_f32 v117, v150, v119, v117
	v_add_f32_e32 v118, v151, v118
	v_add_f32_e32 v116, v116, v117
	s_nop 0
	v_add_f32_dpp v117, v118, v118 row_ror:8 row_mask:0xf bank_mask:0xf bound_ctrl:1
	v_add_f32_dpp v116, v116, v116 row_ror:8 row_mask:0xf bank_mask:0xf bound_ctrl:1
	s_waitcnt lgkmcnt(6)
	v_mul_f32 v118, v148, v104
	v_mul_f32 v104, v149, v104
	v_add_f32_dpp v117, v117, v117 row_ror:4 row_mask:0xf bank_mask:0xf bound_ctrl:1
	v_add_f32_dpp v116, v116, v116 row_ror:4 row_mask:0xf bank_mask:0xf bound_ctrl:1
	s_nop 0
	v_add_f32_dpp v117, v117, v117 row_ror:2 row_mask:0xf bank_mask:0xf bound_ctrl:1
	v_add_f32_dpp v116, v116, v116 row_ror:2 row_mask:0xf bank_mask:0xf bound_ctrl:1
	s_nop 0
	v_add_f32_dpp v117, v117, v117 row_ror:1 row_mask:0xf bank_mask:0xf bound_ctrl:1
	v_add_f32_dpp v116, v116, v116 row_ror:1 row_mask:0xf bank_mask:0xf bound_ctrl:1
	v_fma_f32 v118, v117, v96, v118
	v_fma_f32 v96, v116, v96, v104
	v_fma_f32 v151, v122, v92, v118
	v_fma_f32 v193, v123, v92, v96
	v_mul_f32 v92, v148, v105
	v_fma_f32 v92, v117, v97, v92
	v_fma_f32 v125, v125, v93, v92
	v_mul_f32 v92, v149, v105
	v_fma_f32 v92, v116, v97, v92
	v_fma_f32 v191, v191, v93, v92
	v_mul_f32 v92, v148, v106
	v_mul_f32 v93, v125, v85
	v_fma_f32 v92, v117, v98, v92
	v_mul_f32 v85, v191, v85
	v_fma_f32 v127, v127, v94, v92
	v_mul_f32 v92, v149, v106
	v_fma_f32 v92, v116, v98, v92
	v_fma_f32 v192, v192, v94, v92
	v_mul_f32 v92, v148, v107
	v_fma_f32 v92, v117, v99, v92
	v_fma_f32 v141, v141, v95, v92
	v_mul_f32 v92, v149, v107
	v_fma_f32 v92, v116, v99, v92
	v_fma_f32 v148, v150, v95, v92
	v_mul_f32 v92, v151, v84
	v_mul_f32 v84, v193, v84
	v_fma_f32 v92, v127, v86, v92
	v_fma_f32 v84, v192, v86, v84
	v_fma_f32 v86, v141, v87, v93
	v_fma_f32 v85, v148, v87, v85
	v_add_f32_e32 v86, v92, v86
	v_add_f32_e32 v87, v84, v85
	v_mov_b32_e32 v85, 0
	v_add_f32_dpp v84, v86, v86 row_ror:8 row_mask:0xf bank_mask:0xf bound_ctrl:1
	v_add_f32_dpp v86, v87, v87 row_ror:8 row_mask:0xf bank_mask:0xf bound_ctrl:1
	v_mov_b32_e32 v87, 0
	v_add_f32_dpp v84, v84, v84 row_ror:4 row_mask:0xf bank_mask:0xf bound_ctrl:1
	v_add_f32_dpp v86, v86, v86 row_ror:4 row_mask:0xf bank_mask:0xf bound_ctrl:1
	s_nop 0
	v_add_f32_dpp v84, v84, v84 row_ror:2 row_mask:0xf bank_mask:0xf bound_ctrl:1
	v_add_f32_dpp v86, v86, v86 row_ror:2 row_mask:0xf bank_mask:0xf bound_ctrl:1
	s_nop 0
	v_mov_b32_dpp v85, v84 row_ror:1 row_mask:0xf bank_mask:0xf
	v_mov_b32_dpp v87, v86 row_ror:1 row_mask:0xf bank_mask:0xf
	s_and_saveexec_b64 s[8:9], s[40:41]
	v_add_f32_e32 v86, v86, v87
	v_add_f32_e32 v84, v84, v85
	ds_write2_b32 v185, v84, v86 offset0:128 offset1:144
	s_or_b64 exec, exec, s[8:9]
	s_waitcnt lgkmcnt(4)
	v_mul_f32 v149, v151, v112
	v_mul_f32 v112, v193, v112
	v_mul_f32 v150, v125, v113
	v_mul_f32 v113, v191, v113
	ds_read_b128 v[92:95], v134 offset:1536
	ds_read_b128 v[116:119], v134 offset:5632
	ds_read_b128 v[96:99], v134 offset:9728
	ds_read_b128 v[104:107], v134 offset:13824
	ds_read_b128 v[84:87], v134 offset:17920
	ds_read2_b32 v[122:123], v189 offset0:192 offset1:208
	v_fma_f32 v149, v127, v114, v149
	v_fma_f32 v112, v192, v114, v112
	v_fma_f32 v114, v141, v115, v150
	v_fma_f32 v113, v148, v115, v113
	v_add_f32_e32 v114, v149, v114
	v_add_f32_e32 v112, v112, v113
	s_nop 0
	v_add_f32_dpp v113, v114, v114 row_ror:8 row_mask:0xf bank_mask:0xf bound_ctrl:1
	v_add_f32_dpp v112, v112, v112 row_ror:8 row_mask:0xf bank_mask:0xf bound_ctrl:1
	s_waitcnt lgkmcnt(6)
	v_mul_f32 v114, v120, v108
	v_mul_f32 v108, v121, v108
	v_add_f32_dpp v113, v113, v113 row_ror:4 row_mask:0xf bank_mask:0xf bound_ctrl:1
	v_add_f32_dpp v112, v112, v112 row_ror:4 row_mask:0xf bank_mask:0xf bound_ctrl:1
	s_nop 0
	v_add_f32_dpp v113, v113, v113 row_ror:2 row_mask:0xf bank_mask:0xf bound_ctrl:1
	v_add_f32_dpp v112, v112, v112 row_ror:2 row_mask:0xf bank_mask:0xf bound_ctrl:1
	s_nop 0
	v_add_f32_dpp v113, v113, v113 row_ror:1 row_mask:0xf bank_mask:0xf bound_ctrl:1
	v_add_f32_dpp v112, v112, v112 row_ror:1 row_mask:0xf bank_mask:0xf bound_ctrl:1
	v_fma_f32 v114, v113, v100, v114
	v_fma_f32 v100, v112, v100, v108
	v_fma_f32 v149, v151, v88, v114
	v_fma_f32 v150, v193, v88, v100
	v_mul_f32 v88, v120, v109
	v_fma_f32 v88, v113, v101, v88
	v_fma_f32 v125, v125, v89, v88
	v_mul_f32 v88, v121, v109
	v_fma_f32 v88, v112, v101, v88
	v_fma_f32 v151, v191, v89, v88
	v_mul_f32 v88, v120, v110
	v_mul_f32 v89, v125, v81
	v_fma_f32 v88, v113, v102, v88
	v_mul_f32 v81, v151, v81
	v_fma_f32 v127, v127, v90, v88
	v_mul_f32 v88, v121, v110
	v_fma_f32 v88, v112, v102, v88
	v_fma_f32 v191, v192, v90, v88
	v_mul_f32 v88, v120, v111
	v_fma_f32 v88, v113, v103, v88
	v_fma_f32 v141, v141, v91, v88
	v_mul_f32 v88, v121, v111
	v_fma_f32 v88, v112, v103, v88
	v_fma_f32 v148, v148, v91, v88
	v_mul_f32 v88, v149, v80
	v_mul_f32 v80, v150, v80
	v_fma_f32 v88, v127, v82, v88
	v_fma_f32 v80, v191, v82, v80
	v_fma_f32 v82, v141, v83, v89
	v_fma_f32 v81, v148, v83, v81
	v_add_f32_e32 v82, v88, v82
	v_add_f32_e32 v83, v80, v81
	v_mov_b32_e32 v81, 0
	v_add_f32_dpp v80, v82, v82 row_ror:8 row_mask:0xf bank_mask:0xf bound_ctrl:1
	v_add_f32_dpp v82, v83, v83 row_ror:8 row_mask:0xf bank_mask:0xf bound_ctrl:1
	v_mov_b32_e32 v83, 0
	v_add_f32_dpp v80, v80, v80 row_ror:4 row_mask:0xf bank_mask:0xf bound_ctrl:1
	v_add_f32_dpp v82, v82, v82 row_ror:4 row_mask:0xf bank_mask:0xf bound_ctrl:1
	s_nop 0
	v_add_f32_dpp v80, v80, v80 row_ror:2 row_mask:0xf bank_mask:0xf bound_ctrl:1
	v_add_f32_dpp v82, v82, v82 row_ror:2 row_mask:0xf bank_mask:0xf bound_ctrl:1
	s_nop 0
	v_mov_b32_dpp v81, v80 row_ror:1 row_mask:0xf bank_mask:0xf
	v_mov_b32_dpp v83, v82 row_ror:1 row_mask:0xf bank_mask:0xf
	s_and_saveexec_b64 s[8:9], s[40:41]
	v_add_f32_e32 v82, v82, v83
	v_add_f32_e32 v80, v80, v81
	ds_write2_b32 v185, v80, v82 offset0:160 offset1:176
	s_or_b64 exec, exec, s[8:9]
	ds_read_b128 v[88:91], v134 offset:1792
	ds_read_b128 v[112:115], v134 offset:5888
	ds_read_b128 v[100:103], v134 offset:9984
	ds_read_b128 v[108:111], v134 offset:14080
	ds_read_b128 v[80:83], v134 offset:18176
	ds_read2_b32 v[120:121], v189 offset0:224 offset1:240
	s_waitcnt lgkmcnt(10)
	v_mul_f32 v189, v149, v116
	v_mul_f32 v116, v150, v116
	v_mul_f32 v192, v125, v117
	v_mul_f32 v117, v151, v117
	v_fma_f32 v189, v127, v118, v189
	v_fma_f32 v116, v191, v118, v116
	v_fma_f32 v118, v141, v119, v192
	v_fma_f32 v117, v148, v119, v117
	v_add_f32_e32 v118, v189, v118
	v_add_f32_e32 v116, v116, v117
	s_nop 0
	v_add_f32_dpp v117, v118, v118 row_ror:8 row_mask:0xf bank_mask:0xf bound_ctrl:1
	v_add_f32_dpp v116, v116, v116 row_ror:8 row_mask:0xf bank_mask:0xf bound_ctrl:1
	s_waitcnt lgkmcnt(6)
	v_mul_f32 v118, v122, v104
	v_mul_f32 v104, v123, v104
	v_add_f32_dpp v117, v117, v117 row_ror:4 row_mask:0xf bank_mask:0xf bound_ctrl:1
	v_add_f32_dpp v116, v116, v116 row_ror:4 row_mask:0xf bank_mask:0xf bound_ctrl:1
	s_nop 0
	v_add_f32_dpp v117, v117, v117 row_ror:2 row_mask:0xf bank_mask:0xf bound_ctrl:1
	v_add_f32_dpp v116, v116, v116 row_ror:2 row_mask:0xf bank_mask:0xf bound_ctrl:1
	s_nop 0
	v_add_f32_dpp v117, v117, v117 row_ror:1 row_mask:0xf bank_mask:0xf bound_ctrl:1
	v_add_f32_dpp v116, v116, v116 row_ror:1 row_mask:0xf bank_mask:0xf bound_ctrl:1
	v_fma_f32 v118, v117, v96, v118
	v_fma_f32 v96, v116, v96, v104
	v_fma_f32 v149, v149, v92, v118
	v_fma_f32 v150, v150, v92, v96
	v_mul_f32 v92, v122, v105
	v_fma_f32 v92, v117, v97, v92
	v_fma_f32 v125, v125, v93, v92
	v_mul_f32 v92, v123, v105
	v_fma_f32 v92, v116, v97, v92
	v_fma_f32 v151, v151, v93, v92
	v_mul_f32 v92, v122, v106
	v_mul_f32 v93, v125, v85
	v_fma_f32 v92, v117, v98, v92
	v_mul_f32 v85, v151, v85
	v_fma_f32 v127, v127, v94, v92
	v_mul_f32 v92, v123, v106
	v_fma_f32 v92, v116, v98, v92
	v_fma_f32 v189, v191, v94, v92
	v_mul_f32 v92, v122, v107
	v_fma_f32 v92, v117, v99, v92
	v_fma_f32 v141, v141, v95, v92
	v_mul_f32 v92, v123, v107
	v_fma_f32 v92, v116, v99, v92
	v_fma_f32 v148, v148, v95, v92
	v_mul_f32 v92, v149, v84
	v_mul_f32 v84, v150, v84
	v_fma_f32 v92, v127, v86, v92
	v_fma_f32 v84, v189, v86, v84
	v_fma_f32 v86, v141, v87, v93
	v_fma_f32 v85, v148, v87, v85
	v_add_f32_e32 v86, v92, v86
	v_add_f32_e32 v87, v84, v85
	v_mov_b32_e32 v85, 0
	v_add_f32_dpp v84, v86, v86 row_ror:8 row_mask:0xf bank_mask:0xf bound_ctrl:1
	v_add_f32_dpp v86, v87, v87 row_ror:8 row_mask:0xf bank_mask:0xf bound_ctrl:1
	v_mov_b32_e32 v87, 0
	v_add_f32_dpp v84, v84, v84 row_ror:4 row_mask:0xf bank_mask:0xf bound_ctrl:1
	v_add_f32_dpp v86, v86, v86 row_ror:4 row_mask:0xf bank_mask:0xf bound_ctrl:1
	s_nop 0
	v_add_f32_dpp v84, v84, v84 row_ror:2 row_mask:0xf bank_mask:0xf bound_ctrl:1
	v_add_f32_dpp v86, v86, v86 row_ror:2 row_mask:0xf bank_mask:0xf bound_ctrl:1
	s_nop 0
	v_mov_b32_dpp v85, v84 row_ror:1 row_mask:0xf bank_mask:0xf
	v_mov_b32_dpp v87, v86 row_ror:1 row_mask:0xf bank_mask:0xf
	s_and_saveexec_b64 s[8:9], s[40:41]
	v_add_f32_e32 v86, v86, v87
	v_add_f32_e32 v84, v84, v85
	ds_write2_b32 v185, v84, v86 offset0:192 offset1:208
	s_or_b64 exec, exec, s[8:9]
	s_waitcnt lgkmcnt(4)
	v_mul_f32 v191, v149, v112
	v_mul_f32 v112, v150, v112
	v_mul_f32 v192, v125, v113
	v_mul_f32 v113, v151, v113
	ds_read_b128 v[92:95], v134 offset:2048
	ds_read_b128 v[116:119], v134 offset:6144
	ds_read_b128 v[96:99], v134 offset:10240
	ds_read_b128 v[104:107], v134 offset:14336
	ds_read_b128 v[84:87], v134 offset:18432
	ds_read2_b32 v[122:123], v187 offset1:16
	v_fma_f32 v191, v127, v114, v191
	v_fma_f32 v112, v189, v114, v112
	v_fma_f32 v114, v141, v115, v192
	v_fma_f32 v113, v148, v115, v113
	v_add_f32_e32 v114, v191, v114
	v_add_f32_e32 v112, v112, v113
	s_nop 0
	v_add_f32_dpp v113, v114, v114 row_ror:8 row_mask:0xf bank_mask:0xf bound_ctrl:1
	v_add_f32_dpp v112, v112, v112 row_ror:8 row_mask:0xf bank_mask:0xf bound_ctrl:1
	s_waitcnt lgkmcnt(6)
	v_mul_f32 v114, v120, v108
	v_mul_f32 v108, v121, v108
	v_add_f32_dpp v113, v113, v113 row_ror:4 row_mask:0xf bank_mask:0xf bound_ctrl:1
	v_add_f32_dpp v112, v112, v112 row_ror:4 row_mask:0xf bank_mask:0xf bound_ctrl:1
	s_nop 0
	v_add_f32_dpp v113, v113, v113 row_ror:2 row_mask:0xf bank_mask:0xf bound_ctrl:1
	v_add_f32_dpp v112, v112, v112 row_ror:2 row_mask:0xf bank_mask:0xf bound_ctrl:1
	s_nop 0
	v_add_f32_dpp v113, v113, v113 row_ror:1 row_mask:0xf bank_mask:0xf bound_ctrl:1
	v_add_f32_dpp v112, v112, v112 row_ror:1 row_mask:0xf bank_mask:0xf bound_ctrl:1
	v_fma_f32 v114, v113, v100, v114
	v_fma_f32 v100, v112, v100, v108
	v_fma_f32 v149, v149, v88, v114
	v_fma_f32 v150, v150, v88, v100
	v_mul_f32 v88, v120, v109
	v_fma_f32 v88, v113, v101, v88
	v_fma_f32 v125, v125, v89, v88
	v_mul_f32 v88, v121, v109
	v_fma_f32 v88, v112, v101, v88
	v_fma_f32 v151, v151, v89, v88
	v_mul_f32 v88, v120, v110
	v_mul_f32 v89, v125, v81
	v_fma_f32 v88, v113, v102, v88
	v_mul_f32 v81, v151, v81
	v_fma_f32 v127, v127, v90, v88
	v_mul_f32 v88, v121, v110
	v_fma_f32 v88, v112, v102, v88
	v_fma_f32 v189, v189, v90, v88
	v_mul_f32 v88, v120, v111
	v_fma_f32 v88, v113, v103, v88
	v_fma_f32 v141, v141, v91, v88
	v_mul_f32 v88, v121, v111
	v_fma_f32 v88, v112, v103, v88
	v_fma_f32 v148, v148, v91, v88
	v_mul_f32 v88, v149, v80
	v_mul_f32 v80, v150, v80
	v_fma_f32 v88, v127, v82, v88
	v_fma_f32 v80, v189, v82, v80
	v_fma_f32 v82, v141, v83, v89
	v_fma_f32 v81, v148, v83, v81
	v_add_f32_e32 v82, v88, v82
	v_add_f32_e32 v83, v80, v81
	v_mov_b32_e32 v81, 0
	v_add_f32_dpp v80, v82, v82 row_ror:8 row_mask:0xf bank_mask:0xf bound_ctrl:1
	v_add_f32_dpp v82, v83, v83 row_ror:8 row_mask:0xf bank_mask:0xf bound_ctrl:1
	v_mov_b32_e32 v83, 0
	v_add_f32_dpp v80, v80, v80 row_ror:4 row_mask:0xf bank_mask:0xf bound_ctrl:1
	v_add_f32_dpp v82, v82, v82 row_ror:4 row_mask:0xf bank_mask:0xf bound_ctrl:1
	s_nop 0
	v_add_f32_dpp v80, v80, v80 row_ror:2 row_mask:0xf bank_mask:0xf bound_ctrl:1
	v_add_f32_dpp v82, v82, v82 row_ror:2 row_mask:0xf bank_mask:0xf bound_ctrl:1
	s_nop 0
	v_mov_b32_dpp v81, v80 row_ror:1 row_mask:0xf bank_mask:0xf
	v_mov_b32_dpp v83, v82 row_ror:1 row_mask:0xf bank_mask:0xf
	s_and_saveexec_b64 s[8:9], s[40:41]
	v_add_f32_e32 v82, v82, v83
	v_add_f32_e32 v80, v80, v81
	ds_write2_b32 v185, v80, v82 offset0:224 offset1:240
	s_or_b64 exec, exec, s[8:9]
	s_waitcnt lgkmcnt(4)
	v_mul_f32 v185, v149, v116
	v_mul_f32 v116, v150, v116
	v_mul_f32 v191, v125, v117
	v_mul_f32 v117, v151, v117
	ds_read_b128 v[88:91], v134 offset:2304
	ds_read_b128 v[112:115], v134 offset:6400
	ds_read_b128 v[100:103], v134 offset:10496
	ds_read_b128 v[108:111], v134 offset:14592
	ds_read_b128 v[80:83], v134 offset:18688
	ds_read2_b32 v[120:121], v187 offset0:32 offset1:48
	v_fma_f32 v185, v127, v118, v185
	v_fma_f32 v116, v189, v118, v116
	v_fma_f32 v118, v141, v119, v191
	v_fma_f32 v117, v148, v119, v117
	v_add_f32_e32 v118, v185, v118
	v_add_f32_e32 v116, v116, v117
	s_nop 0
	v_add_f32_dpp v117, v118, v118 row_ror:8 row_mask:0xf bank_mask:0xf bound_ctrl:1
	v_add_f32_dpp v116, v116, v116 row_ror:8 row_mask:0xf bank_mask:0xf bound_ctrl:1
	s_waitcnt lgkmcnt(6)
	v_mul_f32 v118, v122, v104
	v_mul_f32 v104, v123, v104
	v_add_f32_dpp v117, v117, v117 row_ror:4 row_mask:0xf bank_mask:0xf bound_ctrl:1
	v_add_f32_dpp v116, v116, v116 row_ror:4 row_mask:0xf bank_mask:0xf bound_ctrl:1
	s_nop 0
	v_add_f32_dpp v117, v117, v117 row_ror:2 row_mask:0xf bank_mask:0xf bound_ctrl:1
	v_add_f32_dpp v116, v116, v116 row_ror:2 row_mask:0xf bank_mask:0xf bound_ctrl:1
	s_nop 0
	v_add_f32_dpp v117, v117, v117 row_ror:1 row_mask:0xf bank_mask:0xf bound_ctrl:1
	v_add_f32_dpp v116, v116, v116 row_ror:1 row_mask:0xf bank_mask:0xf bound_ctrl:1
	v_fma_f32 v118, v117, v96, v118
	v_fma_f32 v96, v116, v96, v104
	v_fma_f32 v149, v149, v92, v118
	v_fma_f32 v150, v150, v92, v96
	v_mul_f32 v92, v122, v105
	v_fma_f32 v92, v117, v97, v92
	v_fma_f32 v125, v125, v93, v92
	v_mul_f32 v92, v123, v105
	v_fma_f32 v92, v116, v97, v92
	v_fma_f32 v151, v151, v93, v92
	v_mul_f32 v92, v122, v106
	v_mul_f32 v93, v125, v85
	v_fma_f32 v92, v117, v98, v92
	v_mul_f32 v85, v151, v85
	v_fma_f32 v127, v127, v94, v92
	v_mul_f32 v92, v123, v106
	v_fma_f32 v92, v116, v98, v92
	v_fma_f32 v185, v189, v94, v92
	v_mul_f32 v92, v122, v107
	v_fma_f32 v92, v117, v99, v92
	v_fma_f32 v141, v141, v95, v92
	v_mul_f32 v92, v123, v107
	v_fma_f32 v92, v116, v99, v92
	v_fma_f32 v148, v148, v95, v92
	v_mul_f32 v92, v149, v84
	v_mul_f32 v84, v150, v84
	v_fma_f32 v92, v127, v86, v92
	v_fma_f32 v84, v185, v86, v84
	v_fma_f32 v86, v141, v87, v93
	v_fma_f32 v85, v148, v87, v85
	v_add_f32_e32 v86, v92, v86
	v_add_f32_e32 v87, v84, v85
	v_mov_b32_e32 v85, 0
	v_add_f32_dpp v84, v86, v86 row_ror:8 row_mask:0xf bank_mask:0xf bound_ctrl:1
	v_add_f32_dpp v86, v87, v87 row_ror:8 row_mask:0xf bank_mask:0xf bound_ctrl:1
	v_mov_b32_e32 v87, 0
	v_add_f32_dpp v84, v84, v84 row_ror:4 row_mask:0xf bank_mask:0xf bound_ctrl:1
	v_add_f32_dpp v86, v86, v86 row_ror:4 row_mask:0xf bank_mask:0xf bound_ctrl:1
	s_nop 0
	v_add_f32_dpp v84, v84, v84 row_ror:2 row_mask:0xf bank_mask:0xf bound_ctrl:1
	v_add_f32_dpp v86, v86, v86 row_ror:2 row_mask:0xf bank_mask:0xf bound_ctrl:1
	s_nop 0
	v_mov_b32_dpp v85, v84 row_ror:1 row_mask:0xf bank_mask:0xf
	v_mov_b32_dpp v87, v86 row_ror:1 row_mask:0xf bank_mask:0xf
	s_and_saveexec_b64 s[8:9], s[40:41]
	v_add_f32_e32 v86, v86, v87
	v_add_f32_e32 v84, v84, v85
	ds_write2_b32 v186, v84, v86 offset1:16
	s_or_b64 exec, exec, s[8:9]
	s_waitcnt lgkmcnt(4)
	v_mul_f32 v189, v149, v112
	v_mul_f32 v112, v150, v112
	v_mul_f32 v191, v125, v113
	v_mul_f32 v113, v151, v113
	ds_read_b128 v[92:95], v134 offset:2560
	ds_read_b128 v[116:119], v134 offset:6656
	ds_read_b128 v[96:99], v134 offset:10752
	ds_read_b128 v[104:107], v134 offset:14848
	ds_read_b128 v[84:87], v134 offset:18944
	ds_read2_b32 v[122:123], v187 offset0:64 offset1:80
	v_fma_f32 v189, v127, v114, v189
	v_fma_f32 v112, v185, v114, v112
	v_fma_f32 v114, v141, v115, v191
	v_fma_f32 v113, v148, v115, v113
	v_add_f32_e32 v114, v189, v114
	v_add_f32_e32 v112, v112, v113
	s_nop 0
	v_add_f32_dpp v113, v114, v114 row_ror:8 row_mask:0xf bank_mask:0xf bound_ctrl:1
	v_add_f32_dpp v112, v112, v112 row_ror:8 row_mask:0xf bank_mask:0xf bound_ctrl:1
	s_waitcnt lgkmcnt(6)
	v_mul_f32 v114, v120, v108
	v_mul_f32 v108, v121, v108
	v_add_f32_dpp v113, v113, v113 row_ror:4 row_mask:0xf bank_mask:0xf bound_ctrl:1
	v_add_f32_dpp v112, v112, v112 row_ror:4 row_mask:0xf bank_mask:0xf bound_ctrl:1
	s_nop 0
	v_add_f32_dpp v113, v113, v113 row_ror:2 row_mask:0xf bank_mask:0xf bound_ctrl:1
	v_add_f32_dpp v112, v112, v112 row_ror:2 row_mask:0xf bank_mask:0xf bound_ctrl:1
	s_nop 0
	v_add_f32_dpp v113, v113, v113 row_ror:1 row_mask:0xf bank_mask:0xf bound_ctrl:1
	v_add_f32_dpp v112, v112, v112 row_ror:1 row_mask:0xf bank_mask:0xf bound_ctrl:1
	v_fma_f32 v114, v113, v100, v114
	v_fma_f32 v100, v112, v100, v108
	v_fma_f32 v149, v149, v88, v114
	v_fma_f32 v150, v150, v88, v100
	v_mul_f32 v88, v120, v109
	v_fma_f32 v88, v113, v101, v88
	v_fma_f32 v125, v125, v89, v88
	v_mul_f32 v88, v121, v109
	v_fma_f32 v88, v112, v101, v88
	v_fma_f32 v151, v151, v89, v88
	v_mul_f32 v88, v120, v110
	v_mul_f32 v89, v125, v81
	v_fma_f32 v88, v113, v102, v88
	v_mul_f32 v81, v151, v81
	v_fma_f32 v127, v127, v90, v88
	v_mul_f32 v88, v121, v110
	v_fma_f32 v88, v112, v102, v88
	v_fma_f32 v185, v185, v90, v88
	v_mul_f32 v88, v120, v111
	v_fma_f32 v88, v113, v103, v88
	v_fma_f32 v141, v141, v91, v88
	v_mul_f32 v88, v121, v111
	v_fma_f32 v88, v112, v103, v88
	v_fma_f32 v148, v148, v91, v88
	v_mul_f32 v88, v149, v80
	v_mul_f32 v80, v150, v80
	v_fma_f32 v88, v127, v82, v88
	v_fma_f32 v80, v185, v82, v80
	v_fma_f32 v82, v141, v83, v89
	v_fma_f32 v81, v148, v83, v81
	v_add_f32_e32 v82, v88, v82
	v_add_f32_e32 v83, v80, v81
	v_mov_b32_e32 v81, 0
	v_add_f32_dpp v80, v82, v82 row_ror:8 row_mask:0xf bank_mask:0xf bound_ctrl:1
	v_add_f32_dpp v82, v83, v83 row_ror:8 row_mask:0xf bank_mask:0xf bound_ctrl:1
	v_mov_b32_e32 v83, 0
	v_add_f32_dpp v80, v80, v80 row_ror:4 row_mask:0xf bank_mask:0xf bound_ctrl:1
	v_add_f32_dpp v82, v82, v82 row_ror:4 row_mask:0xf bank_mask:0xf bound_ctrl:1
	s_nop 0
	v_add_f32_dpp v80, v80, v80 row_ror:2 row_mask:0xf bank_mask:0xf bound_ctrl:1
	v_add_f32_dpp v82, v82, v82 row_ror:2 row_mask:0xf bank_mask:0xf bound_ctrl:1
	s_nop 0
	v_mov_b32_dpp v81, v80 row_ror:1 row_mask:0xf bank_mask:0xf
	v_mov_b32_dpp v83, v82 row_ror:1 row_mask:0xf bank_mask:0xf
	s_and_saveexec_b64 s[8:9], s[40:41]
	v_add_f32_e32 v82, v82, v83
	v_add_f32_e32 v80, v80, v81
	ds_write2_b32 v186, v80, v82 offset0:32 offset1:48
	s_or_b64 exec, exec, s[8:9]
	s_waitcnt lgkmcnt(4)
	v_mul_f32 v189, v149, v116
	v_mul_f32 v116, v150, v116
	v_mul_f32 v191, v125, v117
	v_mul_f32 v117, v151, v117
	ds_read_b128 v[88:91], v134 offset:2816
	ds_read_b128 v[112:115], v134 offset:6912
	ds_read_b128 v[100:103], v134 offset:11008
	ds_read_b128 v[108:111], v134 offset:15104
	ds_read_b128 v[80:83], v134 offset:19200
	ds_read2_b32 v[120:121], v187 offset0:96 offset1:112
	v_fma_f32 v189, v127, v118, v189
	v_fma_f32 v116, v185, v118, v116
	v_fma_f32 v118, v141, v119, v191
	v_fma_f32 v117, v148, v119, v117
	v_add_f32_e32 v118, v189, v118
	v_add_f32_e32 v116, v116, v117
	s_nop 0
	v_add_f32_dpp v117, v118, v118 row_ror:8 row_mask:0xf bank_mask:0xf bound_ctrl:1
	v_add_f32_dpp v116, v116, v116 row_ror:8 row_mask:0xf bank_mask:0xf bound_ctrl:1
	s_waitcnt lgkmcnt(6)
	v_mul_f32 v118, v122, v104
	v_mul_f32 v104, v123, v104
	v_add_f32_dpp v117, v117, v117 row_ror:4 row_mask:0xf bank_mask:0xf bound_ctrl:1
	v_add_f32_dpp v116, v116, v116 row_ror:4 row_mask:0xf bank_mask:0xf bound_ctrl:1
	s_nop 0
	v_add_f32_dpp v117, v117, v117 row_ror:2 row_mask:0xf bank_mask:0xf bound_ctrl:1
	v_add_f32_dpp v116, v116, v116 row_ror:2 row_mask:0xf bank_mask:0xf bound_ctrl:1
	s_nop 0
	v_add_f32_dpp v117, v117, v117 row_ror:1 row_mask:0xf bank_mask:0xf bound_ctrl:1
	v_add_f32_dpp v116, v116, v116 row_ror:1 row_mask:0xf bank_mask:0xf bound_ctrl:1
	v_fma_f32 v118, v117, v96, v118
	v_fma_f32 v96, v116, v96, v104
	v_fma_f32 v149, v149, v92, v118
	v_fma_f32 v150, v150, v92, v96
	v_mul_f32 v92, v122, v105
	v_fma_f32 v92, v117, v97, v92
	v_fma_f32 v125, v125, v93, v92
	v_mul_f32 v92, v123, v105
	v_fma_f32 v92, v116, v97, v92
	v_fma_f32 v151, v151, v93, v92
	v_mul_f32 v92, v122, v106
	v_mul_f32 v93, v125, v85
	v_fma_f32 v92, v117, v98, v92
	v_mul_f32 v85, v151, v85
	v_fma_f32 v127, v127, v94, v92
	v_mul_f32 v92, v123, v106
	v_fma_f32 v92, v116, v98, v92
	v_fma_f32 v185, v185, v94, v92
	v_mul_f32 v92, v122, v107
	v_fma_f32 v92, v117, v99, v92
	v_fma_f32 v141, v141, v95, v92
	v_mul_f32 v92, v123, v107
	v_fma_f32 v92, v116, v99, v92
	v_fma_f32 v148, v148, v95, v92
	v_mul_f32 v92, v149, v84
	v_mul_f32 v84, v150, v84
	v_fma_f32 v92, v127, v86, v92
	v_fma_f32 v84, v185, v86, v84
	v_fma_f32 v86, v141, v87, v93
	v_fma_f32 v85, v148, v87, v85
	v_add_f32_e32 v86, v92, v86
	v_add_f32_e32 v87, v84, v85
	v_mov_b32_e32 v85, 0
	v_add_f32_dpp v84, v86, v86 row_ror:8 row_mask:0xf bank_mask:0xf bound_ctrl:1
	v_add_f32_dpp v86, v87, v87 row_ror:8 row_mask:0xf bank_mask:0xf bound_ctrl:1
	v_mov_b32_e32 v87, 0
	v_add_f32_dpp v84, v84, v84 row_ror:4 row_mask:0xf bank_mask:0xf bound_ctrl:1
	v_add_f32_dpp v86, v86, v86 row_ror:4 row_mask:0xf bank_mask:0xf bound_ctrl:1
	s_nop 0
	v_add_f32_dpp v84, v84, v84 row_ror:2 row_mask:0xf bank_mask:0xf bound_ctrl:1
	v_add_f32_dpp v86, v86, v86 row_ror:2 row_mask:0xf bank_mask:0xf bound_ctrl:1
	s_nop 0
	v_mov_b32_dpp v85, v84 row_ror:1 row_mask:0xf bank_mask:0xf
	v_mov_b32_dpp v87, v86 row_ror:1 row_mask:0xf bank_mask:0xf
	s_and_saveexec_b64 s[8:9], s[40:41]
	v_add_f32_e32 v86, v86, v87
	v_add_f32_e32 v84, v84, v85
	ds_write2_b32 v186, v84, v86 offset0:64 offset1:80
	s_or_b64 exec, exec, s[8:9]
	s_waitcnt lgkmcnt(4)
	v_mul_f32 v189, v149, v112
	v_mul_f32 v112, v150, v112
	v_mul_f32 v191, v125, v113
	v_mul_f32 v113, v151, v113
	ds_read_b128 v[92:95], v134 offset:3072
	ds_read_b128 v[116:119], v134 offset:7168
	ds_read_b128 v[96:99], v134 offset:11264
	ds_read_b128 v[104:107], v134 offset:15360
	ds_read_b128 v[84:87], v134 offset:19456
	ds_read2_b32 v[122:123], v187 offset0:128 offset1:144
	v_fma_f32 v189, v127, v114, v189
	v_fma_f32 v112, v185, v114, v112
	v_fma_f32 v114, v141, v115, v191
	v_fma_f32 v113, v148, v115, v113
	v_add_f32_e32 v114, v189, v114
	v_add_f32_e32 v112, v112, v113
	s_nop 0
	v_add_f32_dpp v113, v114, v114 row_ror:8 row_mask:0xf bank_mask:0xf bound_ctrl:1
	v_add_f32_dpp v112, v112, v112 row_ror:8 row_mask:0xf bank_mask:0xf bound_ctrl:1
	s_waitcnt lgkmcnt(6)
	v_mul_f32 v114, v120, v108
	v_mul_f32 v108, v121, v108
	v_add_f32_dpp v113, v113, v113 row_ror:4 row_mask:0xf bank_mask:0xf bound_ctrl:1
	v_add_f32_dpp v112, v112, v112 row_ror:4 row_mask:0xf bank_mask:0xf bound_ctrl:1
	s_nop 0
	v_add_f32_dpp v113, v113, v113 row_ror:2 row_mask:0xf bank_mask:0xf bound_ctrl:1
	v_add_f32_dpp v112, v112, v112 row_ror:2 row_mask:0xf bank_mask:0xf bound_ctrl:1
	s_nop 0
	v_add_f32_dpp v113, v113, v113 row_ror:1 row_mask:0xf bank_mask:0xf bound_ctrl:1
	v_add_f32_dpp v112, v112, v112 row_ror:1 row_mask:0xf bank_mask:0xf bound_ctrl:1
	v_fma_f32 v114, v113, v100, v114
	v_fma_f32 v100, v112, v100, v108
	v_fma_f32 v149, v149, v88, v114
	v_fma_f32 v150, v150, v88, v100
	v_mul_f32 v88, v120, v109
	v_fma_f32 v88, v113, v101, v88
	v_fma_f32 v125, v125, v89, v88
	v_mul_f32 v88, v121, v109
	v_fma_f32 v88, v112, v101, v88
	v_fma_f32 v151, v151, v89, v88
	v_mul_f32 v88, v120, v110
	v_mul_f32 v89, v125, v81
	v_fma_f32 v88, v113, v102, v88
	v_mul_f32 v81, v151, v81
	v_fma_f32 v127, v127, v90, v88
	v_mul_f32 v88, v121, v110
	v_fma_f32 v88, v112, v102, v88
	v_fma_f32 v185, v185, v90, v88
	v_mul_f32 v88, v120, v111
	v_fma_f32 v88, v113, v103, v88
	v_fma_f32 v141, v141, v91, v88
	v_mul_f32 v88, v121, v111
	v_fma_f32 v88, v112, v103, v88
	v_fma_f32 v148, v148, v91, v88
	v_mul_f32 v88, v149, v80
	v_mul_f32 v80, v150, v80
	v_fma_f32 v88, v127, v82, v88
	v_fma_f32 v80, v185, v82, v80
	v_fma_f32 v82, v141, v83, v89
	v_fma_f32 v81, v148, v83, v81
	v_add_f32_e32 v82, v88, v82
	v_add_f32_e32 v83, v80, v81
	v_mov_b32_e32 v81, 0
	v_add_f32_dpp v80, v82, v82 row_ror:8 row_mask:0xf bank_mask:0xf bound_ctrl:1
	v_add_f32_dpp v82, v83, v83 row_ror:8 row_mask:0xf bank_mask:0xf bound_ctrl:1
	v_mov_b32_e32 v83, 0
	v_add_f32_dpp v80, v80, v80 row_ror:4 row_mask:0xf bank_mask:0xf bound_ctrl:1
	v_add_f32_dpp v82, v82, v82 row_ror:4 row_mask:0xf bank_mask:0xf bound_ctrl:1
	s_nop 0
	v_add_f32_dpp v80, v80, v80 row_ror:2 row_mask:0xf bank_mask:0xf bound_ctrl:1
	v_add_f32_dpp v82, v82, v82 row_ror:2 row_mask:0xf bank_mask:0xf bound_ctrl:1
	s_nop 0
	v_mov_b32_dpp v81, v80 row_ror:1 row_mask:0xf bank_mask:0xf
	v_mov_b32_dpp v83, v82 row_ror:1 row_mask:0xf bank_mask:0xf
	s_and_saveexec_b64 s[8:9], s[40:41]
	v_add_f32_e32 v82, v82, v83
	v_add_f32_e32 v80, v80, v81
	ds_write2_b32 v186, v80, v82 offset0:96 offset1:112
	s_or_b64 exec, exec, s[8:9]
	s_waitcnt lgkmcnt(4)
	v_mul_f32 v189, v149, v116
	v_mul_f32 v116, v150, v116
	v_mul_f32 v191, v125, v117
	v_mul_f32 v117, v151, v117
	ds_read_b128 v[88:91], v134 offset:3328
	ds_read_b128 v[112:115], v134 offset:7424
	ds_read_b128 v[100:103], v134 offset:11520
	ds_read_b128 v[108:111], v134 offset:15616
	ds_read_b128 v[80:83], v134 offset:19712
	ds_read2_b32 v[120:121], v187 offset0:160 offset1:176
	v_fma_f32 v189, v127, v118, v189
	v_fma_f32 v116, v185, v118, v116
	v_fma_f32 v118, v141, v119, v191
	v_fma_f32 v117, v148, v119, v117
	v_add_f32_e32 v118, v189, v118
	v_add_f32_e32 v116, v116, v117
	s_nop 0
	v_add_f32_dpp v117, v118, v118 row_ror:8 row_mask:0xf bank_mask:0xf bound_ctrl:1
	v_add_f32_dpp v116, v116, v116 row_ror:8 row_mask:0xf bank_mask:0xf bound_ctrl:1
	s_waitcnt lgkmcnt(6)
	v_mul_f32 v118, v122, v104
	v_mul_f32 v104, v123, v104
	v_add_f32_dpp v117, v117, v117 row_ror:4 row_mask:0xf bank_mask:0xf bound_ctrl:1
	v_add_f32_dpp v116, v116, v116 row_ror:4 row_mask:0xf bank_mask:0xf bound_ctrl:1
	s_nop 0
	v_add_f32_dpp v117, v117, v117 row_ror:2 row_mask:0xf bank_mask:0xf bound_ctrl:1
	v_add_f32_dpp v116, v116, v116 row_ror:2 row_mask:0xf bank_mask:0xf bound_ctrl:1
	s_nop 0
	v_add_f32_dpp v117, v117, v117 row_ror:1 row_mask:0xf bank_mask:0xf bound_ctrl:1
	v_add_f32_dpp v116, v116, v116 row_ror:1 row_mask:0xf bank_mask:0xf bound_ctrl:1
	v_fma_f32 v118, v117, v96, v118
	v_fma_f32 v96, v116, v96, v104
	v_fma_f32 v149, v149, v92, v118
	v_fma_f32 v150, v150, v92, v96
	v_mul_f32 v92, v122, v105
	v_fma_f32 v92, v117, v97, v92
	v_fma_f32 v125, v125, v93, v92
	v_mul_f32 v92, v123, v105
	v_fma_f32 v92, v116, v97, v92
	v_fma_f32 v151, v151, v93, v92
	v_mul_f32 v92, v122, v106
	v_mul_f32 v93, v125, v85
	v_fma_f32 v92, v117, v98, v92
	v_mul_f32 v85, v151, v85
	v_fma_f32 v127, v127, v94, v92
	v_mul_f32 v92, v123, v106
	v_fma_f32 v92, v116, v98, v92
	v_fma_f32 v185, v185, v94, v92
	v_mul_f32 v92, v122, v107
	v_fma_f32 v92, v117, v99, v92
	v_fma_f32 v141, v141, v95, v92
	v_mul_f32 v92, v123, v107
	v_fma_f32 v92, v116, v99, v92
	v_fma_f32 v148, v148, v95, v92
	v_mul_f32 v92, v149, v84
	v_mul_f32 v84, v150, v84
	v_fma_f32 v92, v127, v86, v92
	v_fma_f32 v84, v185, v86, v84
	v_fma_f32 v86, v141, v87, v93
	v_fma_f32 v85, v148, v87, v85
	v_add_f32_e32 v86, v92, v86
	v_add_f32_e32 v87, v84, v85
	v_mov_b32_e32 v85, 0
	v_add_f32_dpp v84, v86, v86 row_ror:8 row_mask:0xf bank_mask:0xf bound_ctrl:1
	v_add_f32_dpp v86, v87, v87 row_ror:8 row_mask:0xf bank_mask:0xf bound_ctrl:1
	v_mov_b32_e32 v87, 0
	v_add_f32_dpp v84, v84, v84 row_ror:4 row_mask:0xf bank_mask:0xf bound_ctrl:1
	v_add_f32_dpp v86, v86, v86 row_ror:4 row_mask:0xf bank_mask:0xf bound_ctrl:1
	s_nop 0
	v_add_f32_dpp v84, v84, v84 row_ror:2 row_mask:0xf bank_mask:0xf bound_ctrl:1
	v_add_f32_dpp v86, v86, v86 row_ror:2 row_mask:0xf bank_mask:0xf bound_ctrl:1
	s_nop 0
	v_mov_b32_dpp v85, v84 row_ror:1 row_mask:0xf bank_mask:0xf
	v_mov_b32_dpp v87, v86 row_ror:1 row_mask:0xf bank_mask:0xf
	s_and_saveexec_b64 s[8:9], s[40:41]
	v_add_f32_e32 v86, v86, v87
	v_add_f32_e32 v84, v84, v85
	ds_write2_b32 v186, v84, v86 offset0:128 offset1:144
	s_or_b64 exec, exec, s[8:9]
	s_waitcnt lgkmcnt(4)
	v_mul_f32 v189, v149, v112
	v_mul_f32 v112, v150, v112
	v_mul_f32 v191, v125, v113
	v_mul_f32 v113, v151, v113
	ds_read_b128 v[92:95], v134 offset:3584
	ds_read_b128 v[116:119], v134 offset:7680
	ds_read_b128 v[96:99], v134 offset:11776
	ds_read_b128 v[104:107], v134 offset:15872
	ds_read_b128 v[84:87], v134 offset:19968
	ds_read2_b32 v[122:123], v187 offset0:192 offset1:208
	v_fma_f32 v189, v127, v114, v189
	v_fma_f32 v112, v185, v114, v112
	v_fma_f32 v114, v141, v115, v191
	v_fma_f32 v113, v148, v115, v113
	v_add_f32_e32 v114, v189, v114
	v_add_f32_e32 v112, v112, v113
	s_nop 0
	v_add_f32_dpp v113, v114, v114 row_ror:8 row_mask:0xf bank_mask:0xf bound_ctrl:1
	v_add_f32_dpp v112, v112, v112 row_ror:8 row_mask:0xf bank_mask:0xf bound_ctrl:1
	s_waitcnt lgkmcnt(6)
	v_mul_f32 v114, v120, v108
	v_mul_f32 v108, v121, v108
	v_add_f32_dpp v113, v113, v113 row_ror:4 row_mask:0xf bank_mask:0xf bound_ctrl:1
	v_add_f32_dpp v112, v112, v112 row_ror:4 row_mask:0xf bank_mask:0xf bound_ctrl:1
	s_nop 0
	v_add_f32_dpp v113, v113, v113 row_ror:2 row_mask:0xf bank_mask:0xf bound_ctrl:1
	v_add_f32_dpp v112, v112, v112 row_ror:2 row_mask:0xf bank_mask:0xf bound_ctrl:1
	s_nop 0
	v_add_f32_dpp v113, v113, v113 row_ror:1 row_mask:0xf bank_mask:0xf bound_ctrl:1
	v_add_f32_dpp v112, v112, v112 row_ror:1 row_mask:0xf bank_mask:0xf bound_ctrl:1
	v_fma_f32 v114, v113, v100, v114
	v_fma_f32 v100, v112, v100, v108
	v_fma_f32 v149, v149, v88, v114
	v_fma_f32 v150, v150, v88, v100
	v_mul_f32 v88, v120, v109
	v_fma_f32 v88, v113, v101, v88
	v_fma_f32 v125, v125, v89, v88
	v_mul_f32 v88, v121, v109
	v_fma_f32 v88, v112, v101, v88
	v_fma_f32 v151, v151, v89, v88
	v_mul_f32 v88, v120, v110
	v_mul_f32 v89, v125, v81
	v_fma_f32 v88, v113, v102, v88
	v_mul_f32 v81, v151, v81
	v_fma_f32 v127, v127, v90, v88
	v_mul_f32 v88, v121, v110
	v_fma_f32 v88, v112, v102, v88
	v_fma_f32 v185, v185, v90, v88
	v_mul_f32 v88, v120, v111
	v_fma_f32 v88, v113, v103, v88
	v_fma_f32 v141, v141, v91, v88
	v_mul_f32 v88, v121, v111
	v_fma_f32 v88, v112, v103, v88
	v_fma_f32 v148, v148, v91, v88
	v_mul_f32 v88, v149, v80
	v_mul_f32 v80, v150, v80
	v_fma_f32 v88, v127, v82, v88
	v_fma_f32 v80, v185, v82, v80
	v_fma_f32 v82, v141, v83, v89
	v_fma_f32 v81, v148, v83, v81
	v_add_f32_e32 v82, v88, v82
	v_add_f32_e32 v83, v80, v81
	v_mov_b32_e32 v81, 0
	v_add_f32_dpp v80, v82, v82 row_ror:8 row_mask:0xf bank_mask:0xf bound_ctrl:1
	v_add_f32_dpp v82, v83, v83 row_ror:8 row_mask:0xf bank_mask:0xf bound_ctrl:1
	v_mov_b32_e32 v83, 0
	v_add_f32_dpp v80, v80, v80 row_ror:4 row_mask:0xf bank_mask:0xf bound_ctrl:1
	v_add_f32_dpp v82, v82, v82 row_ror:4 row_mask:0xf bank_mask:0xf bound_ctrl:1
	s_nop 0
	v_add_f32_dpp v80, v80, v80 row_ror:2 row_mask:0xf bank_mask:0xf bound_ctrl:1
	v_add_f32_dpp v82, v82, v82 row_ror:2 row_mask:0xf bank_mask:0xf bound_ctrl:1
	s_nop 0
	v_mov_b32_dpp v81, v80 row_ror:1 row_mask:0xf bank_mask:0xf
	v_mov_b32_dpp v83, v82 row_ror:1 row_mask:0xf bank_mask:0xf
	s_and_saveexec_b64 s[8:9], s[40:41]
	v_add_f32_e32 v82, v82, v83
	v_add_f32_e32 v80, v80, v81
	ds_write2_b32 v186, v80, v82 offset0:160 offset1:176
	s_or_b64 exec, exec, s[8:9]
	ds_read_b128 v[88:91], v134 offset:3840
	ds_read_b128 v[112:115], v134 offset:7936
	ds_read_b128 v[100:103], v134 offset:12032
	ds_read_b128 v[108:111], v134 offset:16128
	ds_read_b128 v[80:83], v134 offset:20224
	ds_read2_b32 v[120:121], v187 offset0:224 offset1:240
	s_waitcnt lgkmcnt(10)
	v_mul_f32 v187, v149, v116
	v_mul_f32 v116, v150, v116
	v_mul_f32 v189, v125, v117
	v_mul_f32 v117, v151, v117
	v_fma_f32 v187, v127, v118, v187
	v_fma_f32 v116, v185, v118, v116
	v_fma_f32 v118, v141, v119, v189
	v_fma_f32 v117, v148, v119, v117
	v_add_f32_e32 v116, v116, v117
	v_add_f32_e32 v118, v187, v118
	s_nop 0
	v_add_f32_dpp v116, v116, v116 row_ror:8 row_mask:0xf bank_mask:0xf bound_ctrl:1
	v_add_f32_dpp v117, v118, v118 row_ror:8 row_mask:0xf bank_mask:0xf bound_ctrl:1
	s_nop 0
	v_add_f32_dpp v116, v116, v116 row_ror:4 row_mask:0xf bank_mask:0xf bound_ctrl:1
	v_add_f32_dpp v117, v117, v117 row_ror:4 row_mask:0xf bank_mask:0xf bound_ctrl:1
	s_nop 0
	v_add_f32_dpp v116, v116, v116 row_ror:2 row_mask:0xf bank_mask:0xf bound_ctrl:1
	v_add_f32_dpp v117, v117, v117 row_ror:2 row_mask:0xf bank_mask:0xf bound_ctrl:1
	s_nop 0
	v_add_f32_dpp v118, v116, v116 row_ror:1 row_mask:0xf bank_mask:0xf bound_ctrl:1
	s_waitcnt lgkmcnt(6)
	v_mul_f32 v116, v122, v104
	v_add_f32_dpp v117, v117, v117 row_ror:1 row_mask:0xf bank_mask:0xf bound_ctrl:1
	v_fma_f32 v116, v117, v96, v116
	v_mul_f32 v104, v123, v104
	v_fma_f32 v96, v118, v96, v104
	v_fma_f32 v116, v149, v92, v116
	v_mul_f32 v104, v123, v105
	v_fma_f32 v92, v150, v92, v96
	v_mul_f32 v96, v122, v105
	v_fma_f32 v96, v117, v97, v96
	v_fma_f32 v97, v118, v97, v104
	v_mul_f32 v104, v123, v106
	v_fma_f32 v96, v125, v93, v96
	v_fma_f32 v93, v151, v93, v97
	v_mul_f32 v97, v122, v106
	v_fma_f32 v97, v117, v98, v97
	v_fma_f32 v98, v118, v98, v104
	v_mul_f32 v104, v123, v107
	v_fma_f32 v97, v127, v94, v97
	v_fma_f32 v94, v185, v94, v98
	v_mul_f32 v98, v122, v107
	v_fma_f32 v98, v117, v99, v98
	v_fma_f32 v99, v118, v99, v104
	v_mul_f32 v104, v96, v85
	v_mul_f32 v85, v93, v85
	v_fma_f32 v98, v141, v95, v98
	v_fma_f32 v95, v148, v95, v99
	v_mul_f32 v99, v116, v84
	v_mul_f32 v84, v92, v84
	v_fma_f32 v99, v97, v86, v99
	v_fma_f32 v84, v94, v86, v84
	v_fma_f32 v86, v98, v87, v104
	v_fma_f32 v85, v95, v87, v85
	v_add_f32_e32 v86, v99, v86
	v_add_f32_e32 v87, v84, v85
	v_mov_b32_e32 v85, 0
	v_add_f32_dpp v84, v86, v86 row_ror:8 row_mask:0xf bank_mask:0xf bound_ctrl:1
	v_add_f32_dpp v86, v87, v87 row_ror:8 row_mask:0xf bank_mask:0xf bound_ctrl:1
	v_mov_b32_e32 v87, 0
	v_add_f32_dpp v84, v84, v84 row_ror:4 row_mask:0xf bank_mask:0xf bound_ctrl:1
	v_add_f32_dpp v86, v86, v86 row_ror:4 row_mask:0xf bank_mask:0xf bound_ctrl:1
	s_nop 0
	v_add_f32_dpp v84, v84, v84 row_ror:2 row_mask:0xf bank_mask:0xf bound_ctrl:1
	v_add_f32_dpp v86, v86, v86 row_ror:2 row_mask:0xf bank_mask:0xf bound_ctrl:1
	s_nop 0
	v_mov_b32_dpp v85, v84 row_ror:1 row_mask:0xf bank_mask:0xf
	v_mov_b32_dpp v87, v86 row_ror:1 row_mask:0xf bank_mask:0xf
	s_and_saveexec_b64 s[8:9], s[40:41]
	v_add_f32_e32 v86, v86, v87
	v_add_f32_e32 v84, v84, v85
	ds_write2_b32 v186, v84, v86 offset0:192 offset1:208
	s_or_b64 exec, exec, s[8:9]
	s_waitcnt lgkmcnt(4)
	v_mul_f32 v84, v116, v112
	v_mul_f32 v86, v96, v113
	v_mul_f32 v85, v92, v112
	v_mul_f32 v87, v93, v113
	v_fma_f32 v84, v97, v114, v84
	v_fma_f32 v86, v98, v115, v86
	v_fma_f32 v85, v94, v114, v85
	v_fma_f32 v87, v95, v115, v87
	v_add_f32_e32 v84, v84, v86
	v_add_f32_e32 v85, v85, v87
	s_nop 0
	v_add_f32_dpp v84, v84, v84 row_ror:8 row_mask:0xf bank_mask:0xf bound_ctrl:1
	s_waitcnt lgkmcnt(0)
	v_mul_f32 v86, v120, v109
	v_mul_f32 v87, v121, v109
	v_add_f32_dpp v84, v84, v84 row_ror:4 row_mask:0xf bank_mask:0xf bound_ctrl:1
	s_nop 1
	v_add_f32_dpp v84, v84, v84 row_ror:2 row_mask:0xf bank_mask:0xf bound_ctrl:1
	s_nop 1
	v_add_f32_dpp v99, v84, v84 row_ror:1 row_mask:0xf bank_mask:0xf bound_ctrl:1
	v_add_f32_dpp v84, v85, v85 row_ror:8 row_mask:0xf bank_mask:0xf bound_ctrl:1
	v_mul_f32 v85, v121, v108
	v_fma_f32 v86, v99, v101, v86
	v_fma_f32 v86, v96, v89, v86
	v_add_f32_dpp v84, v84, v84 row_ror:4 row_mask:0xf bank_mask:0xf bound_ctrl:1
	s_nop 1
	v_add_f32_dpp v84, v84, v84 row_ror:2 row_mask:0xf bank_mask:0xf bound_ctrl:1
	s_nop 1
	v_add_f32_dpp v104, v84, v84 row_ror:1 row_mask:0xf bank_mask:0xf bound_ctrl:1
	v_mul_f32 v84, v120, v108
	v_fma_f32 v85, v104, v100, v85
	v_fma_f32 v87, v104, v101, v87
	v_fma_f32 v84, v99, v100, v84
	v_fma_f32 v85, v92, v88, v85
	v_fma_f32 v87, v93, v89, v87
	v_mul_f32 v89, v86, v81
	v_fma_f32 v84, v116, v88, v84
	v_mul_f32 v88, v120, v110
	v_mul_f32 v81, v87, v81
	v_fma_f32 v88, v99, v102, v88
	v_fma_f32 v96, v97, v90, v88
	v_mul_f32 v88, v121, v110
	v_fma_f32 v88, v104, v102, v88
	v_fma_f32 v97, v94, v90, v88
	v_mul_f32 v88, v120, v111
	v_fma_f32 v88, v99, v103, v88
	v_fma_f32 v98, v98, v91, v88
	v_mul_f32 v88, v121, v111
	v_fma_f32 v88, v104, v103, v88
	v_fma_f32 v99, v95, v91, v88
	v_mul_f32 v88, v84, v80
	v_mul_f32 v80, v85, v80
	v_fma_f32 v88, v96, v82, v88
	v_fma_f32 v80, v97, v82, v80
	v_fma_f32 v82, v98, v83, v89
	v_fma_f32 v81, v99, v83, v81
	v_add_f32_e32 v82, v88, v82
	v_add_f32_e32 v83, v80, v81
	v_mov_b32_e32 v81, 0
	v_add_f32_dpp v80, v82, v82 row_ror:8 row_mask:0xf bank_mask:0xf bound_ctrl:1
	v_add_f32_dpp v82, v83, v83 row_ror:8 row_mask:0xf bank_mask:0xf bound_ctrl:1
	v_mov_b32_e32 v83, 0
	v_add_f32_dpp v80, v80, v80 row_ror:4 row_mask:0xf bank_mask:0xf bound_ctrl:1
	v_add_f32_dpp v82, v82, v82 row_ror:4 row_mask:0xf bank_mask:0xf bound_ctrl:1
	s_nop 0
	v_add_f32_dpp v80, v80, v80 row_ror:2 row_mask:0xf bank_mask:0xf bound_ctrl:1
	v_add_f32_dpp v82, v82, v82 row_ror:2 row_mask:0xf bank_mask:0xf bound_ctrl:1
	s_nop 0
	v_mov_b32_dpp v81, v80 row_ror:1 row_mask:0xf bank_mask:0xf
	v_mov_b32_dpp v83, v82 row_ror:1 row_mask:0xf bank_mask:0xf
	s_and_saveexec_b64 s[8:9], s[40:41]
	v_add_f32_e32 v82, v82, v83
	v_add_f32_e32 v80, v80, v81
	ds_write2_b32 v186, v80, v82 offset0:224 offset1:240
	s_or_b64 exec, exec, s[8:9]
	s_and_saveexec_b64 s[8:9], s[38:39]
	s_cbranch_execz .LBB0_453
	v_add_f32_e32 v88, v0, v76
	v_min_f32_e32 v92, 0, v88
	v_mul_f32_e64 v88, |v88|, s62
	v_exp_f32_e32 v88, v88
	v_add_f32_e32 v89, v1, v77
	v_add_f32_e32 v90, v2, v78
	v_add_f32_e32 v91, v3, v79
	v_add_f32_e32 v88, 1.0, v88
	v_cmp_gt_f32_e32 vcc, s5, v88
	s_mov_b32 s4, 0xf800000
	v_add_f32_e32 v80, v4, v72
	v_cndmask_b32_e64 v93, 0, 32, vcc
	v_ldexp_f32 v88, v88, v93
	v_log_f32_e32 v88, v88
	v_mul_f32_e32 v80, 0xbfb8aa3b, v80
	v_exp_f32_e32 v82, v80
	v_add_f32_e32 v80, v5, v73
	v_mul_f32_e32 v93, 0x3f317217, v88
	v_fma_f32 v93, v88, s76, -v93
	v_fmac_f32_e32 v93, 0x3377d1cf, v88
	v_fmac_f32_e32 v93, 0x3f317217, v88
	v_cmp_lt_f32_e64 s[42:43], |v88|, s77
	v_mul_f32_e32 v80, 0xbfb8aa3b, v80
	v_exp_f32_e32 v83, v80
	v_cndmask_b32_e64 v88, v88, v93, s[42:43]
	v_cndmask_b32_e32 v93, 0, v171, vcc
	v_sub_f32_e32 v88, v88, v93
	v_sub_f32_e32 v88, v92, v88
	v_min_f32_e32 v92, 0, v89
	v_mul_f32_e64 v89, |v89|, s62
	v_exp_f32_e32 v89, v89
	v_add_f32_e32 v88, -0.5, v88
	v_mul_f32_e32 v88, 0x3fb8aa3b, v88
	v_exp_f32_e32 v88, v88
	v_add_f32_e32 v89, 1.0, v89
	v_cmp_gt_f32_e32 vcc, s5, v89
	v_pk_add_f32 v[82:83], v[82:83], 1.0 op_sel_hi:[1,0]
	v_mul_f32_e32 v88, 0xbfb8aa3b, v88
	v_cndmask_b32_e64 v93, 0, 32, vcc
	v_ldexp_f32 v89, v89, v93
	v_log_f32_e32 v89, v89
	v_exp_f32_e32 v88, v88
	v_add_f32_e32 v80, v6, v74
	v_add_f32_e32 v81, v7, v75
	v_mul_f32_e32 v93, 0x3f317217, v89
	v_fma_f32 v93, v89, s76, -v93
	v_fmac_f32_e32 v93, 0x3377d1cf, v89
	v_fmac_f32_e32 v93, 0x3f317217, v89
	v_cmp_lt_f32_e64 s[42:43], |v89|, s77
	v_mul_f32_e32 v80, 0xbfb8aa3b, v80
	v_mul_f32_e32 v81, 0xbfb8aa3b, v81
	v_cndmask_b32_e64 v89, v89, v93, s[42:43]
	v_cndmask_b32_e32 v93, 0, v171, vcc
	v_sub_f32_e32 v89, v89, v93
	v_sub_f32_e32 v89, v92, v89
	v_min_f32_e32 v92, 0, v90
	v_mul_f32_e64 v90, |v90|, s62
	v_exp_f32_e32 v90, v90
	v_add_f32_e32 v89, -0.5, v89
	v_mul_f32_e32 v89, 0x3fb8aa3b, v89
	v_exp_f32_e32 v89, v89
	v_add_f32_e32 v90, 1.0, v90
	v_cmp_gt_f32_e32 vcc, s5, v90
	v_exp_f32_e32 v80, v80
	v_mul_f32_e32 v89, 0xbfb8aa3b, v89
	v_cndmask_b32_e64 v93, 0, 32, vcc
	v_ldexp_f32 v90, v90, v93
	v_log_f32_e32 v90, v90
	v_exp_f32_e32 v89, v89
	v_exp_f32_e32 v81, v81
	v_mul_f32_e32 v93, 0x3f317217, v90
	v_fma_f32 v93, v90, s76, -v93
	v_fmac_f32_e32 v93, 0x3377d1cf, v90
	v_fmac_f32_e32 v93, 0x3f317217, v90
	v_cmp_lt_f32_e64 s[42:43], |v90|, s77
	v_pk_add_f32 v[80:81], v[80:81], 1.0 op_sel_hi:[1,0]
	s_nop 0
	v_cndmask_b32_e64 v90, v90, v93, s[42:43]
	v_cndmask_b32_e32 v93, 0, v171, vcc
	v_sub_f32_e32 v90, v90, v93
	v_sub_f32_e32 v90, v92, v90
	v_min_f32_e32 v92, 0, v91
	v_mul_f32_e64 v91, |v91|, s62
	v_exp_f32_e32 v91, v91
	v_add_f32_e32 v90, -0.5, v90
	v_mul_f32_e32 v90, 0x3fb8aa3b, v90
	v_exp_f32_e32 v90, v90
	v_add_f32_e32 v91, 1.0, v91
	v_cmp_gt_f32_e32 vcc, s5, v91
	v_mul_f32_e32 v90, 0xbfb8aa3b, v90
	s_nop 0
	v_cndmask_b32_e64 v93, 0, 32, vcc
	v_ldexp_f32 v91, v91, v93
	v_log_f32_e32 v91, v91
	v_exp_f32_e32 v90, v90
	v_mul_f32_e32 v93, 0x3f317217, v91
	v_fma_f32 v93, v91, s76, -v93
	v_fmac_f32_e32 v93, 0x3377d1cf, v91
	v_fmac_f32_e32 v93, 0x3f317217, v91
	v_cmp_lt_f32_e64 s[42:43], |v91|, s77
	s_nop 1
	v_cndmask_b32_e64 v91, v91, v93, s[42:43]
	v_cndmask_b32_e32 v93, 0, v171, vcc
	v_sub_f32_e32 v91, v91, v93
	v_sub_f32_e32 v91, v92, v91
	v_add_f32_e32 v91, -0.5, v91
	v_mul_f32_e32 v91, 0x3fb8aa3b, v91
	v_exp_f32_e32 v91, v91
	v_pk_mul_f32 v[92:93], v[10:11], v[70:71]
	v_mul_f32_e32 v91, 0xbfb8aa3b, v91
	v_exp_f32_e32 v91, v91
	v_pk_mul_f32 v[94:95], v[92:93], v[92:93]
	ds_write_b128 v181, v[88:91] offset:22528
	v_pk_mul_f32 v[88:89], v[8:9], v[68:69]
	v_pk_mul_f32 v[90:91], v[88:89], v[88:89]
	v_add_f32_e32 v90, v91, v90
	v_add_f32_e32 v90, v94, v90
	v_add_f32_e32 v90, v95, v90
	s_nop 1
	v_add_f32_dpp v90, v90, v90 row_ror:8 row_mask:0xf bank_mask:0xf bound_ctrl:1
	s_nop 1
	v_add_f32_dpp v90, v90, v90 row_ror:4 row_mask:0xf bank_mask:0xf bound_ctrl:1
	s_nop 1
	v_add_f32_dpp v90, v90, v90 row_ror:2 row_mask:0xf bank_mask:0xf bound_ctrl:1
	s_nop 1
	v_add_f32_dpp v90, v90, v90 row_ror:1 row_mask:0xf bank_mask:0xf bound_ctrl:1
	v_cmp_gt_f32_e32 vcc, s4, v90
	v_mul_f32_e32 v91, 0x4f800000, v90
	s_nop 0
	v_cndmask_b32_e32 v90, v90, v91, vcc
	v_sqrt_f32_e32 v91, v90
	s_nop 0
	v_add_u32_e32 v94, -1, v91
	v_fma_f32 v95, -v94, v91, v90
	v_cmp_ge_f32_e64 s[42:43], 0, v95
	v_add_u32_e32 v95, 1, v91
	s_nop 0
	v_cndmask_b32_e64 v94, v91, v94, s[42:43]
	v_fma_f32 v91, -v95, v91, v90
	v_cmp_lt_f32_e64 s[42:43], 0, v91
	s_nop 1
	v_cndmask_b32_e64 v91, v94, v95, s[42:43]
	v_mul_f32_e32 v94, 0x37800000, v91
	v_cndmask_b32_e32 v91, v91, v94, vcc
	v_cmp_class_f32_e32 vcc, v90, v160
	s_nop 1
	v_cndmask_b32_e32 v90, v91, v90, vcc
	v_max_f32_e32 v90, 0x2b8cbccc, v90
	v_div_scale_f32 v91, s[22:23], v90, v90, 1.0
	v_rcp_f32_e32 v94, v91
	s_nop 0
	v_fma_f32 v95, -v91, v94, 1.0
	v_fmac_f32_e32 v94, v95, v94
	v_div_scale_f32 v95, vcc, 1.0, v90, 1.0
	v_mul_f32_e32 v100, v95, v94
	v_fma_f32 v101, -v91, v100, v95
	v_fmac_f32_e32 v100, v101, v94
	v_fma_f32 v91, -v91, v100, v95
	v_div_fmas_f32 v91, v91, v94, v100
	v_div_fixup_f32 v90, v91, v90, 1.0
	v_pk_mul_f32 v[94:95], v[88:89], v[90:91] op_sel_hi:[1,0]
	v_pk_mul_f32 v[92:93], v[92:93], v[90:91] op_sel_hi:[1,0]
	v_xor_b32_e32 v89, 0x80000000, v95
	v_xor_b32_e32 v88, 0x80000000, v94
	v_xor_b32_e32 v91, 0x80000000, v93
	v_xor_b32_e32 v90, 0x80000000, v92
	ds_write_b128 v181, v[88:91] offset:26624
	v_div_scale_f32 v88, s[22:23], v83, v83, 1.0
	v_rcp_f32_e32 v89, v88
	s_nop 0
	v_fma_f32 v90, -v88, v89, 1.0
	v_fmac_f32_e32 v89, v90, v89
	v_div_scale_f32 v90, vcc, 1.0, v83, 1.0
	v_mul_f32_e32 v91, v90, v89
	v_fma_f32 v100, -v88, v91, v90
	v_fmac_f32_e32 v91, v100, v89
	v_fma_f32 v88, -v88, v91, v90
	v_div_fmas_f32 v88, v88, v89, v91
	v_div_fixup_f32 v83, v88, v83, 1.0
	v_div_scale_f32 v88, s[22:23], v82, v82, 1.0
	v_rcp_f32_e32 v89, v88
	s_nop 0
	v_fma_f32 v90, -v88, v89, 1.0
	v_fmac_f32_e32 v89, v90, v89
	v_div_scale_f32 v90, vcc, 1.0, v82, 1.0
	v_mul_f32_e32 v91, v90, v89
	v_fma_f32 v100, -v88, v91, v90
	v_fmac_f32_e32 v91, v100, v89
	v_fma_f32 v88, -v88, v91, v90
	v_div_scale_f32 v90, s[22:23], v81, v81, 1.0
	v_div_fmas_f32 v88, v88, v89, v91
	v_rcp_f32_e32 v91, v90
	v_div_fixup_f32 v82, v88, v82, 1.0
	v_pk_mul_f32 v[88:89], v[82:83], v[94:95]
	v_fma_f32 v94, -v90, v91, 1.0
	v_fmac_f32_e32 v91, v94, v91
	v_div_scale_f32 v94, vcc, 1.0, v81, 1.0
	v_mul_f32_e32 v95, v94, v91
	v_fma_f32 v100, -v90, v95, v94
	v_fmac_f32_e32 v95, v100, v91
	v_fma_f32 v90, -v90, v95, v94
	v_div_fmas_f32 v90, v90, v91, v95
	v_div_fixup_f32 v95, v90, v81, 1.0
	v_div_scale_f32 v81, s[22:23], v80, v80, 1.0
	v_rcp_f32_e32 v90, v81
	s_nop 0
	v_fma_f32 v91, -v81, v90, 1.0
	v_fmac_f32_e32 v90, v91, v90
	v_div_scale_f32 v91, vcc, 1.0, v80, 1.0
	v_mul_f32_e32 v94, v91, v90
	v_fma_f32 v100, -v81, v94, v91
	v_fmac_f32_e32 v94, v100, v90
	v_fma_f32 v81, -v81, v94, v91
	v_div_fmas_f32 v81, v81, v90, v94
	v_div_fixup_f32 v94, v81, v80, 1.0
	v_pk_add_f32 v[80:81], v[82:83], -1.0 op_sel_hi:[1,0]
	v_pk_add_f32 v[82:83], v[94:95], -1.0 op_sel_hi:[1,0]
	v_pk_fma_f32 v[80:81], v[12:13], v[80:81], 1.0 op_sel_hi:[1,1,0]
	v_pk_fma_f32 v[82:83], v[14:15], v[82:83], 1.0 op_sel_hi:[1,1,0]
	v_pk_mul_f32 v[90:91], v[94:95], v[92:93]
	v_pk_mul_f32 v[80:81], v[68:69], v[80:81]
	v_pk_mul_f32 v[82:83], v[70:71], v[82:83]
	ds_write_b128 v181, v[88:91] offset:30720
	ds_write_b128 v181, v[80:83] offset:34816
	ds_write_b128 v181, v[48:51] offset:38912

.LBB0_457:
	ds_read2st64_b32 v[80:81], v179 offset0:176 offset1:180
	v_add_u32_e32 v82, 32, v126
	v_ashrrev_i32_e32 v83, 31, v82
	v_lshlrev_b64 v[82:83], 13, v[82:83]
	v_lshl_add_u64 v[82:83], v[144:145], 0, v[82:83]
	s_waitcnt lgkmcnt(0)
	global_store_dword v[82:83], v80, off
	v_add_u32_e32 v82, 32, v124
	v_ashrrev_i32_e32 v83, 31, v82
	v_lshlrev_b64 v[82:83], 13, v[82:83]
	v_lshl_add_u64 v[82:83], v[144:145], 0, v[82:83]
	global_store_dword v[82:83], v81, off
	ds_read_b128 v[104:107], v134 offset:22528
	ds_read_b128 v[88:91], v134 offset:22784
	ds_read_b128 v[108:111], v134 offset:26624
	ds_read_b128 v[112:115], v134 offset:26880
	ds_read_b128 v[116:119], v134 offset:30720
	ds_read_b128 v[92:95], v134 offset:30976
	ds_read_b128 v[148:151], v134 offset:34816
	ds_read_b128 v[100:103], v134 offset:35072
	ds_read_b128 v[192:195], v134 offset:38912
	ds_read_b128 v[80:83], v134 offset:39168
	ds_read2_b32 v[120:121], v190 offset0:32 offset1:48
	s_waitcnt lgkmcnt(8)
	v_mul_f32 v122, v84, v108
	v_mul_f32 v108, v85, v108
	v_mul_f32 v123, v86, v109
	v_mul_f32 v109, v87, v109
	v_fma_f32 v122, v96, v110, v122
	v_fma_f32 v108, v97, v110, v108
	v_fma_f32 v110, v98, v111, v123
	v_fma_f32 v109, v99, v111, v109
	v_add_f32_e32 v110, v122, v110
	v_add_f32_e32 v111, v108, v109
	s_nop 0
	v_add_f32_dpp v110, v110, v110 row_ror:8 row_mask:0xf bank_mask:0xf bound_ctrl:1
	ds_read2_b32 v[108:109], v190 offset1:16
	v_add_f32_dpp v111, v111, v111 row_ror:8 row_mask:0xf bank_mask:0xf bound_ctrl:1
	v_add_f32_dpp v110, v110, v110 row_ror:4 row_mask:0xf bank_mask:0xf bound_ctrl:1
	s_waitcnt lgkmcnt(0)
	v_mul_f32 v122, v108, v148
	v_add_f32_dpp v111, v111, v111 row_ror:4 row_mask:0xf bank_mask:0xf bound_ctrl:1
	v_add_f32_dpp v110, v110, v110 row_ror:2 row_mask:0xf bank_mask:0xf bound_ctrl:1
	s_nop 0
	v_add_f32_dpp v111, v111, v111 row_ror:2 row_mask:0xf bank_mask:0xf bound_ctrl:1
	v_add_f32_dpp v110, v110, v110 row_ror:1 row_mask:0xf bank_mask:0xf bound_ctrl:1
	v_fma_f32 v122, v110, v116, v122
	v_fma_f32 v122, v84, v104, v122
	v_mul_f32 v84, v109, v148
	v_add_f32_dpp v111, v111, v111 row_ror:1 row_mask:0xf bank_mask:0xf bound_ctrl:1
	v_fma_f32 v84, v111, v116, v84
	v_fma_f32 v123, v85, v104, v84
	v_mul_f32 v84, v108, v149
	v_fma_f32 v84, v110, v117, v84
	v_mul_f32 v85, v123, v192
	v_fma_f32 v126, v86, v105, v84
	v_mul_f32 v84, v109, v149
	v_fma_f32 v84, v111, v117, v84
	v_mul_f32 v86, v126, v193
	v_fma_f32 v127, v87, v105, v84
	v_mul_f32 v84, v108, v150
	v_fma_f32 v84, v110, v118, v84
	v_mul_f32 v87, v127, v193
	v_fma_f32 v141, v96, v106, v84
	v_mul_f32 v84, v109, v150
	v_fma_f32 v84, v111, v118, v84
	v_fma_f32 v148, v97, v106, v84
	v_mul_f32 v84, v108, v151
	v_fma_f32 v84, v110, v119, v84
	v_fma_f32 v85, v148, v194, v85
	v_fma_f32 v149, v98, v107, v84
	v_mul_f32 v84, v109, v151
	v_fma_f32 v84, v111, v119, v84
	v_fma_f32 v86, v149, v195, v86
	v_fma_f32 v150, v99, v107, v84
	v_mul_f32 v84, v122, v192
	v_fma_f32 v84, v141, v194, v84
	v_fma_f32 v87, v150, v195, v87
	v_add_f32_e32 v84, v84, v86
	v_add_f32_e32 v86, v85, v87
	v_mov_b32_e32 v85, 0
	v_add_f32_dpp v84, v84, v84 row_ror:8 row_mask:0xf bank_mask:0xf bound_ctrl:1
	v_add_f32_dpp v86, v86, v86 row_ror:8 row_mask:0xf bank_mask:0xf bound_ctrl:1
	v_mov_b32_e32 v87, 0
	v_add_f32_dpp v84, v84, v84 row_ror:4 row_mask:0xf bank_mask:0xf bound_ctrl:1
	v_add_f32_dpp v86, v86, v86 row_ror:4 row_mask:0xf bank_mask:0xf bound_ctrl:1
	s_nop 0
	v_add_f32_dpp v84, v84, v84 row_ror:2 row_mask:0xf bank_mask:0xf bound_ctrl:1
	v_add_f32_dpp v86, v86, v86 row_ror:2 row_mask:0xf bank_mask:0xf bound_ctrl:1
	s_nop 0
	v_mov_b32_dpp v85, v84 row_ror:1 row_mask:0xf bank_mask:0xf
	v_mov_b32_dpp v87, v86 row_ror:1 row_mask:0xf bank_mask:0xf
	s_and_saveexec_b64 s[8:9], s[40:41]
	v_add_f32_e32 v86, v86, v87
	v_add_f32_e32 v84, v84, v85
	ds_write2_b32 v188, v84, v86 offset1:16
	s_or_b64 exec, exec, s[8:9]
	v_mul_f32 v151, v122, v112
	v_mul_f32 v112, v123, v112
	v_mul_f32 v185, v126, v113
	v_mul_f32 v113, v127, v113
	ds_read_b128 v[96:99], v134 offset:23040
	ds_read_b128 v[116:119], v134 offset:27136
	ds_read_b128 v[104:107], v134 offset:31232
	ds_read_b128 v[108:111], v134 offset:35328
	ds_read_b128 v[84:87], v134 offset:39424
	ds_read2_b32 v[124:125], v190 offset0:64 offset1:80
	v_fma_f32 v151, v141, v114, v151
	v_fma_f32 v112, v148, v114, v112
	v_fma_f32 v114, v149, v115, v185
	v_fma_f32 v113, v150, v115, v113
	v_add_f32_e32 v114, v151, v114
	v_add_f32_e32 v112, v112, v113
	s_nop 0
	v_add_f32_dpp v113, v114, v114 row_ror:8 row_mask:0xf bank_mask:0xf bound_ctrl:1
	v_add_f32_dpp v112, v112, v112 row_ror:8 row_mask:0xf bank_mask:0xf bound_ctrl:1
	v_mul_f32 v114, v120, v100
	v_mul_f32 v100, v121, v100
	v_add_f32_dpp v113, v113, v113 row_ror:4 row_mask:0xf bank_mask:0xf bound_ctrl:1
	v_add_f32_dpp v112, v112, v112 row_ror:4 row_mask:0xf bank_mask:0xf bound_ctrl:1
	s_nop 0
	v_add_f32_dpp v113, v113, v113 row_ror:2 row_mask:0xf bank_mask:0xf bound_ctrl:1
	v_add_f32_dpp v112, v112, v112 row_ror:2 row_mask:0xf bank_mask:0xf bound_ctrl:1
	s_nop 0
	v_add_f32_dpp v113, v113, v113 row_ror:1 row_mask:0xf bank_mask:0xf bound_ctrl:1
	v_add_f32_dpp v112, v112, v112 row_ror:1 row_mask:0xf bank_mask:0xf bound_ctrl:1
	v_fma_f32 v114, v113, v92, v114
	v_fma_f32 v92, v112, v92, v100
	v_fma_f32 v151, v122, v88, v114
	v_fma_f32 v92, v123, v88, v92
	v_mul_f32 v88, v120, v101
	v_fma_f32 v88, v113, v93, v88
	v_fma_f32 v185, v126, v89, v88
	v_mul_f32 v88, v121, v101
	v_fma_f32 v88, v112, v93, v88
	v_fma_f32 v93, v127, v89, v88
	v_mul_f32 v88, v120, v102
	v_mul_f32 v89, v185, v81
	v_fma_f32 v88, v113, v94, v88
	v_mul_f32 v81, v93, v81
	v_fma_f32 v141, v141, v90, v88
	v_mul_f32 v88, v121, v102
	v_fma_f32 v88, v112, v94, v88
	v_fma_f32 v94, v148, v90, v88
	v_mul_f32 v88, v120, v103
	v_fma_f32 v88, v113, v95, v88
	v_fma_f32 v148, v149, v91, v88
	v_mul_f32 v88, v121, v103
	v_fma_f32 v88, v112, v95, v88
	v_fma_f32 v95, v150, v91, v88
	v_mul_f32 v88, v151, v80
	v_mul_f32 v80, v92, v80
	v_fma_f32 v88, v141, v82, v88
	v_fma_f32 v80, v94, v82, v80
	v_fma_f32 v82, v148, v83, v89
	v_fma_f32 v81, v95, v83, v81
	v_add_f32_e32 v82, v88, v82
	v_add_f32_e32 v83, v80, v81
	v_mov_b32_e32 v81, 0
	v_add_f32_dpp v80, v82, v82 row_ror:8 row_mask:0xf bank_mask:0xf bound_ctrl:1
	v_add_f32_dpp v82, v83, v83 row_ror:8 row_mask:0xf bank_mask:0xf bound_ctrl:1
	v_mov_b32_e32 v83, 0
	v_add_f32_dpp v80, v80, v80 row_ror:4 row_mask:0xf bank_mask:0xf bound_ctrl:1
	v_add_f32_dpp v82, v82, v82 row_ror:4 row_mask:0xf bank_mask:0xf bound_ctrl:1
	s_nop 0
	v_add_f32_dpp v80, v80, v80 row_ror:2 row_mask:0xf bank_mask:0xf bound_ctrl:1
	v_add_f32_dpp v82, v82, v82 row_ror:2 row_mask:0xf bank_mask:0xf bound_ctrl:1
	s_nop 0
	v_mov_b32_dpp v81, v80 row_ror:1 row_mask:0xf bank_mask:0xf
	v_mov_b32_dpp v83, v82 row_ror:1 row_mask:0xf bank_mask:0xf
	s_and_saveexec_b64 s[8:9], s[40:41]
	v_add_f32_e32 v82, v82, v83
	v_add_f32_e32 v80, v80, v81
	ds_write2_b32 v188, v80, v82 offset0:32 offset1:48
	s_or_b64 exec, exec, s[8:9]
	s_waitcnt lgkmcnt(4)
	v_mul_f32 v149, v151, v116
	v_mul_f32 v116, v92, v116
	v_mul_f32 v150, v185, v117
	v_mul_f32 v117, v93, v117
	ds_read_b128 v[88:91], v134 offset:23296
	ds_read_b128 v[120:123], v134 offset:27392
	ds_read_b128 v[100:103], v134 offset:31488
	ds_read_b128 v[112:115], v134 offset:35584
	ds_read_b128 v[80:83], v134 offset:39680
	ds_read2_b32 v[126:127], v190 offset0:96 offset1:112
	v_fma_f32 v149, v141, v118, v149
	v_fma_f32 v116, v94, v118, v116
	v_fma_f32 v118, v148, v119, v150
	v_fma_f32 v117, v95, v119, v117
	v_add_f32_e32 v118, v149, v118
	v_add_f32_e32 v116, v116, v117
	s_nop 0
	v_add_f32_dpp v117, v118, v118 row_ror:8 row_mask:0xf bank_mask:0xf bound_ctrl:1
	v_add_f32_dpp v116, v116, v116 row_ror:8 row_mask:0xf bank_mask:0xf bound_ctrl:1
	s_waitcnt lgkmcnt(6)
	v_mul_f32 v118, v124, v108
	v_mul_f32 v108, v125, v108
	v_add_f32_dpp v117, v117, v117 row_ror:4 row_mask:0xf bank_mask:0xf bound_ctrl:1
	v_add_f32_dpp v116, v116, v116 row_ror:4 row_mask:0xf bank_mask:0xf bound_ctrl:1
	s_nop 0
	v_add_f32_dpp v117, v117, v117 row_ror:2 row_mask:0xf bank_mask:0xf bound_ctrl:1
	v_add_f32_dpp v116, v116, v116 row_ror:2 row_mask:0xf bank_mask:0xf bound_ctrl:1
	s_nop 0
	v_add_f32_dpp v117, v117, v117 row_ror:1 row_mask:0xf bank_mask:0xf bound_ctrl:1
	v_add_f32_dpp v116, v116, v116 row_ror:1 row_mask:0xf bank_mask:0xf bound_ctrl:1
	v_fma_f32 v118, v117, v104, v118
	v_fma_f32 v104, v116, v104, v108
	v_fma_f32 v108, v92, v96, v104
	v_mul_f32 v92, v124, v109
	v_fma_f32 v149, v151, v96, v118
	v_fma_f32 v92, v117, v105, v92
	v_fma_f32 v150, v185, v97, v92
	v_mul_f32 v92, v125, v109
	v_fma_f32 v92, v116, v105, v92
	v_fma_f32 v109, v93, v97, v92
	v_mul_f32 v92, v124, v110
	v_mul_f32 v93, v150, v85
	v_fma_f32 v92, v117, v106, v92
	v_mul_f32 v85, v109, v85
	v_fma_f32 v141, v141, v98, v92
	v_mul_f32 v92, v125, v110
	v_fma_f32 v92, v116, v106, v92
	v_fma_f32 v110, v94, v98, v92
	v_mul_f32 v92, v124, v111
	v_fma_f32 v92, v117, v107, v92
	v_fma_f32 v148, v148, v99, v92
	v_mul_f32 v92, v125, v111
	v_fma_f32 v92, v116, v107, v92
	v_fma_f32 v111, v95, v99, v92
	v_mul_f32 v92, v149, v84
	v_mul_f32 v84, v108, v84
	v_fma_f32 v92, v141, v86, v92
	v_fma_f32 v84, v110, v86, v84
	v_fma_f32 v86, v148, v87, v93
	v_fma_f32 v85, v111, v87, v85
	v_add_f32_e32 v86, v92, v86
	v_add_f32_e32 v87, v84, v85
	v_mov_b32_e32 v85, 0
	v_add_f32_dpp v84, v86, v86 row_ror:8 row_mask:0xf bank_mask:0xf bound_ctrl:1
	v_add_f32_dpp v86, v87, v87 row_ror:8 row_mask:0xf bank_mask:0xf bound_ctrl:1
	v_mov_b32_e32 v87, 0
	v_add_f32_dpp v84, v84, v84 row_ror:4 row_mask:0xf bank_mask:0xf bound_ctrl:1
	v_add_f32_dpp v86, v86, v86 row_ror:4 row_mask:0xf bank_mask:0xf bound_ctrl:1
	s_nop 0
	v_add_f32_dpp v84, v84, v84 row_ror:2 row_mask:0xf bank_mask:0xf bound_ctrl:1
	v_add_f32_dpp v86, v86, v86 row_ror:2 row_mask:0xf bank_mask:0xf bound_ctrl:1
	s_nop 0
	v_mov_b32_dpp v85, v84 row_ror:1 row_mask:0xf bank_mask:0xf
	v_mov_b32_dpp v87, v86 row_ror:1 row_mask:0xf bank_mask:0xf
	s_and_saveexec_b64 s[8:9], s[40:41]
	v_add_f32_e32 v86, v86, v87
	v_add_f32_e32 v84, v84, v85
	ds_write2_b32 v188, v84, v86 offset0:64 offset1:80
	s_or_b64 exec, exec, s[8:9]
	s_waitcnt lgkmcnt(4)
	v_mul_f32 v151, v149, v120
	v_mul_f32 v120, v108, v120
	v_mul_f32 v185, v150, v121
	v_mul_f32 v121, v109, v121
	ds_read_b128 v[92:95], v134 offset:23552
	ds_read_b128 v[116:119], v134 offset:27648
	ds_read_b128 v[96:99], v134 offset:31744
	ds_read_b128 v[104:107], v134 offset:35840
	ds_read_b128 v[84:87], v134 offset:39936
	ds_read2_b32 v[124:125], v190 offset0:128 offset1:144
	v_fma_f32 v120, v110, v122, v120
	v_fma_f32 v151, v141, v122, v151
	v_fma_f32 v122, v148, v123, v185
	v_fma_f32 v121, v111, v123, v121
	v_add_f32_e32 v122, v151, v122
	v_add_f32_e32 v120, v120, v121
	s_nop 1
	v_add_f32_dpp v120, v120, v120 row_ror:8 row_mask:0xf bank_mask:0xf bound_ctrl:1
	v_add_f32_dpp v121, v122, v122 row_ror:8 row_mask:0xf bank_mask:0xf bound_ctrl:1
	s_nop 0
	v_add_f32_dpp v120, v120, v120 row_ror:4 row_mask:0xf bank_mask:0xf bound_ctrl:1
	v_add_f32_dpp v121, v121, v121 row_ror:4 row_mask:0xf bank_mask:0xf bound_ctrl:1
	s_nop 0
	v_add_f32_dpp v120, v120, v120 row_ror:2 row_mask:0xf bank_mask:0xf bound_ctrl:1
	v_add_f32_dpp v121, v121, v121 row_ror:2 row_mask:0xf bank_mask:0xf bound_ctrl:1
	s_nop 0
	v_add_f32_dpp v185, v120, v120 row_ror:1 row_mask:0xf bank_mask:0xf bound_ctrl:1
	s_waitcnt lgkmcnt(6)
	v_mul_f32 v120, v126, v112
	v_add_f32_dpp v151, v121, v121 row_ror:1 row_mask:0xf bank_mask:0xf bound_ctrl:1
	v_fma_f32 v120, v151, v100, v120
	v_mul_f32 v112, v127, v112
	v_fma_f32 v120, v149, v88, v120
	v_fma_f32 v100, v185, v100, v112
	v_fma_f32 v121, v108, v88, v100
	v_mul_f32 v88, v126, v113
	v_fma_f32 v88, v151, v101, v88
	v_fma_f32 v122, v150, v89, v88
	v_mul_f32 v88, v127, v113
	v_fma_f32 v88, v185, v101, v88
	v_fma_f32 v123, v109, v89, v88
	v_mul_f32 v88, v126, v114
	v_mul_f32 v89, v122, v81
	v_fma_f32 v88, v151, v102, v88
	v_mul_f32 v81, v123, v81
	v_fma_f32 v141, v141, v90, v88
	v_mul_f32 v88, v127, v114
	v_fma_f32 v88, v185, v102, v88
	v_fma_f32 v149, v110, v90, v88
	v_mul_f32 v88, v126, v115
	v_fma_f32 v88, v151, v103, v88
	v_fma_f32 v148, v148, v91, v88
	v_mul_f32 v88, v127, v115
	v_fma_f32 v88, v185, v103, v88
	v_fma_f32 v150, v111, v91, v88
	v_mul_f32 v88, v120, v80
	v_mul_f32 v80, v121, v80
	v_fma_f32 v88, v141, v82, v88
	v_fma_f32 v80, v149, v82, v80
	v_fma_f32 v82, v148, v83, v89
	v_fma_f32 v81, v150, v83, v81
	v_add_f32_e32 v82, v88, v82
	v_add_f32_e32 v83, v80, v81
	v_mov_b32_e32 v81, 0
	v_add_f32_dpp v80, v82, v82 row_ror:8 row_mask:0xf bank_mask:0xf bound_ctrl:1
	v_add_f32_dpp v82, v83, v83 row_ror:8 row_mask:0xf bank_mask:0xf bound_ctrl:1
	v_mov_b32_e32 v83, 0
	v_add_f32_dpp v80, v80, v80 row_ror:4 row_mask:0xf bank_mask:0xf bound_ctrl:1
	v_add_f32_dpp v82, v82, v82 row_ror:4 row_mask:0xf bank_mask:0xf bound_ctrl:1
	s_nop 0
	v_add_f32_dpp v80, v80, v80 row_ror:2 row_mask:0xf bank_mask:0xf bound_ctrl:1
	v_add_f32_dpp v82, v82, v82 row_ror:2 row_mask:0xf bank_mask:0xf bound_ctrl:1
	s_nop 0
	v_mov_b32_dpp v81, v80 row_ror:1 row_mask:0xf bank_mask:0xf
	v_mov_b32_dpp v83, v82 row_ror:1 row_mask:0xf bank_mask:0xf
	s_and_saveexec_b64 s[8:9], s[40:41]
	v_add_f32_e32 v82, v82, v83
	v_add_f32_e32 v80, v80, v81
	ds_write2_b32 v188, v80, v82 offset0:96 offset1:112
	s_or_b64 exec, exec, s[8:9]
	s_waitcnt lgkmcnt(4)
	v_mul_f32 v151, v120, v116
	v_mul_f32 v116, v121, v116
	v_mul_f32 v185, v122, v117
	v_mul_f32 v117, v123, v117
	ds_read_b128 v[88:91], v134 offset:23808
	ds_read_b128 v[112:115], v134 offset:27904
	ds_read_b128 v[100:103], v134 offset:32000
	ds_read_b128 v[108:111], v134 offset:36096
	ds_read_b128 v[80:83], v134 offset:40192
	ds_read2_b32 v[126:127], v190 offset0:160 offset1:176
	v_fma_f32 v116, v149, v118, v116
	v_fma_f32 v151, v141, v118, v151
	v_fma_f32 v118, v148, v119, v185
	v_fma_f32 v117, v150, v119, v117
	v_add_f32_e32 v118, v151, v118
	v_add_f32_e32 v116, v116, v117
	s_nop 1
	v_add_f32_dpp v116, v116, v116 row_ror:8 row_mask:0xf bank_mask:0xf bound_ctrl:1
	v_add_f32_dpp v117, v118, v118 row_ror:8 row_mask:0xf bank_mask:0xf bound_ctrl:1
	s_nop 0
	v_add_f32_dpp v116, v116, v116 row_ror:4 row_mask:0xf bank_mask:0xf bound_ctrl:1
	v_add_f32_dpp v117, v117, v117 row_ror:4 row_mask:0xf bank_mask:0xf bound_ctrl:1
	s_nop 0
	v_add_f32_dpp v116, v116, v116 row_ror:2 row_mask:0xf bank_mask:0xf bound_ctrl:1
	v_add_f32_dpp v117, v117, v117 row_ror:2 row_mask:0xf bank_mask:0xf bound_ctrl:1
	s_nop 0
	v_add_f32_dpp v186, v116, v116 row_ror:1 row_mask:0xf bank_mask:0xf bound_ctrl:1
	s_waitcnt lgkmcnt(6)
	v_mul_f32 v116, v124, v104
	v_add_f32_dpp v185, v117, v117 row_ror:1 row_mask:0xf bank_mask:0xf bound_ctrl:1
	v_fma_f32 v116, v185, v96, v116
	v_mul_f32 v104, v125, v104
	v_fma_f32 v116, v120, v92, v116
	v_fma_f32 v96, v186, v96, v104
	v_fma_f32 v117, v121, v92, v96
	v_mul_f32 v92, v124, v105
	v_fma_f32 v92, v185, v97, v92
	v_fma_f32 v118, v122, v93, v92
	v_mul_f32 v92, v125, v105
	v_fma_f32 v92, v186, v97, v92
	v_fma_f32 v119, v123, v93, v92
	v_mul_f32 v92, v124, v106
	v_mul_f32 v93, v118, v85
	v_fma_f32 v92, v185, v98, v92
	v_mul_f32 v85, v119, v85
	v_fma_f32 v141, v141, v94, v92
	v_mul_f32 v92, v125, v106
	v_fma_f32 v92, v186, v98, v92
	v_fma_f32 v151, v149, v94, v92
	v_mul_f32 v92, v124, v107
	v_fma_f32 v92, v185, v99, v92
	v_fma_f32 v124, v148, v95, v92
	v_mul_f32 v92, v125, v107
	v_fma_f32 v92, v186, v99, v92
	v_fma_f32 v125, v150, v95, v92
	v_mul_f32 v92, v116, v84
	v_mul_f32 v84, v117, v84
	v_fma_f32 v92, v141, v86, v92
	v_fma_f32 v84, v151, v86, v84
	v_fma_f32 v86, v124, v87, v93
	v_fma_f32 v85, v125, v87, v85
	v_add_f32_e32 v86, v92, v86
	v_add_f32_e32 v87, v84, v85
	v_mov_b32_e32 v85, 0
	v_add_f32_dpp v84, v86, v86 row_ror:8 row_mask:0xf bank_mask:0xf bound_ctrl:1
	v_add_f32_dpp v86, v87, v87 row_ror:8 row_mask:0xf bank_mask:0xf bound_ctrl:1
	v_mov_b32_e32 v87, 0
	v_add_f32_dpp v84, v84, v84 row_ror:4 row_mask:0xf bank_mask:0xf bound_ctrl:1
	v_add_f32_dpp v86, v86, v86 row_ror:4 row_mask:0xf bank_mask:0xf bound_ctrl:1
	s_nop 0
	v_add_f32_dpp v84, v84, v84 row_ror:2 row_mask:0xf bank_mask:0xf bound_ctrl:1
	v_add_f32_dpp v86, v86, v86 row_ror:2 row_mask:0xf bank_mask:0xf bound_ctrl:1
	s_nop 0
	v_mov_b32_dpp v85, v84 row_ror:1 row_mask:0xf bank_mask:0xf
	v_mov_b32_dpp v87, v86 row_ror:1 row_mask:0xf bank_mask:0xf
	s_and_saveexec_b64 s[8:9], s[40:41]
	v_add_f32_e32 v86, v86, v87
	v_add_f32_e32 v84, v84, v85
	ds_write2_b32 v188, v84, v86 offset0:128 offset1:144
	s_or_b64 exec, exec, s[8:9]
	s_waitcnt lgkmcnt(4)
	v_mul_f32 v150, v116, v112
	v_mul_f32 v112, v117, v112
	v_mul_f32 v185, v118, v113
	v_mul_f32 v113, v119, v113
	ds_read_b128 v[92:95], v134 offset:24064
	ds_read_b128 v[120:123], v134 offset:28160
	ds_read_b128 v[96:99], v134 offset:32256
	ds_read_b128 v[104:107], v134 offset:36352
	ds_read_b128 v[84:87], v134 offset:40448
	ds_read2_b32 v[148:149], v190 offset0:192 offset1:208
	v_fma_f32 v112, v151, v114, v112
	v_fma_f32 v150, v141, v114, v150
	v_fma_f32 v114, v124, v115, v185
	v_fma_f32 v113, v125, v115, v113
	v_add_f32_e32 v114, v150, v114
	v_add_f32_e32 v112, v112, v113
	s_nop 1
	v_add_f32_dpp v112, v112, v112 row_ror:8 row_mask:0xf bank_mask:0xf bound_ctrl:1
	v_add_f32_dpp v113, v114, v114 row_ror:8 row_mask:0xf bank_mask:0xf bound_ctrl:1
	s_nop 0
	v_add_f32_dpp v112, v112, v112 row_ror:4 row_mask:0xf bank_mask:0xf bound_ctrl:1
	v_add_f32_dpp v113, v113, v113 row_ror:4 row_mask:0xf bank_mask:0xf bound_ctrl:1
	s_nop 0
	v_add_f32_dpp v112, v112, v112 row_ror:2 row_mask:0xf bank_mask:0xf bound_ctrl:1
	v_add_f32_dpp v113, v113, v113 row_ror:2 row_mask:0xf bank_mask:0xf bound_ctrl:1
	s_nop 0
	v_add_f32_dpp v186, v112, v112 row_ror:1 row_mask:0xf bank_mask:0xf bound_ctrl:1
	s_waitcnt lgkmcnt(6)
	v_mul_f32 v112, v126, v108
	v_add_f32_dpp v185, v113, v113 row_ror:1 row_mask:0xf bank_mask:0xf bound_ctrl:1
	v_fma_f32 v112, v185, v100, v112
	v_mul_f32 v108, v127, v108
	v_fma_f32 v112, v116, v88, v112
	v_fma_f32 v100, v186, v100, v108
	v_fma_f32 v113, v117, v88, v100
	v_mul_f32 v88, v126, v109
	v_fma_f32 v88, v185, v101, v88
	v_fma_f32 v114, v118, v89, v88
	v_mul_f32 v88, v127, v109
	v_fma_f32 v88, v186, v101, v88
	v_fma_f32 v115, v119, v89, v88
	v_mul_f32 v88, v126, v110
	v_mul_f32 v89, v114, v81
	v_fma_f32 v88, v185, v102, v88
	v_mul_f32 v81, v115, v81
	v_fma_f32 v141, v141, v90, v88
	v_mul_f32 v88, v127, v110
	v_fma_f32 v88, v186, v102, v88
	v_fma_f32 v150, v151, v90, v88
	v_mul_f32 v88, v126, v111
	v_fma_f32 v88, v185, v103, v88
	v_fma_f32 v151, v124, v91, v88
	v_mul_f32 v88, v127, v111
	v_fma_f32 v88, v186, v103, v88
	v_fma_f32 v185, v125, v91, v88
	v_mul_f32 v88, v112, v80
	v_mul_f32 v80, v113, v80
	v_fma_f32 v88, v141, v82, v88
	v_fma_f32 v80, v150, v82, v80
	v_fma_f32 v82, v151, v83, v89
	v_fma_f32 v81, v185, v83, v81
	v_add_f32_e32 v82, v88, v82
	v_add_f32_e32 v83, v80, v81
	v_mov_b32_e32 v81, 0
	v_add_f32_dpp v80, v82, v82 row_ror:8 row_mask:0xf bank_mask:0xf bound_ctrl:1
	v_add_f32_dpp v82, v83, v83 row_ror:8 row_mask:0xf bank_mask:0xf bound_ctrl:1
	v_mov_b32_e32 v83, 0
	v_add_f32_dpp v80, v80, v80 row_ror:4 row_mask:0xf bank_mask:0xf bound_ctrl:1
	v_add_f32_dpp v82, v82, v82 row_ror:4 row_mask:0xf bank_mask:0xf bound_ctrl:1
	s_nop 0
	v_add_f32_dpp v80, v80, v80 row_ror:2 row_mask:0xf bank_mask:0xf bound_ctrl:1
	v_add_f32_dpp v82, v82, v82 row_ror:2 row_mask:0xf bank_mask:0xf bound_ctrl:1
	s_nop 0
	v_mov_b32_dpp v81, v80 row_ror:1 row_mask:0xf bank_mask:0xf
	v_mov_b32_dpp v83, v82 row_ror:1 row_mask:0xf bank_mask:0xf
	s_and_saveexec_b64 s[8:9], s[40:41]
	v_add_f32_e32 v82, v82, v83
	v_add_f32_e32 v80, v80, v81
	ds_write2_b32 v188, v80, v82 offset0:160 offset1:176
	s_or_b64 exec, exec, s[8:9]
	s_waitcnt lgkmcnt(4)
	v_mul_f32 v126, v112, v120
	v_mul_f32 v120, v113, v120
	v_mul_f32 v127, v114, v121
	v_mul_f32 v121, v115, v121
	ds_read_b128 v[88:91], v134 offset:24320
	ds_read_b128 v[116:119], v134 offset:28416
	ds_read_b128 v[100:103], v134 offset:32512
	ds_read_b128 v[108:111], v134 offset:36608
	ds_read_b128 v[80:83], v134 offset:40704
	ds_read2_b32 v[124:125], v190 offset0:224 offset1:240
	v_fma_f32 v126, v141, v122, v126
	v_fma_f32 v120, v150, v122, v120
	v_fma_f32 v122, v151, v123, v127
	v_fma_f32 v121, v185, v123, v121
	v_add_f32_e32 v122, v126, v122
	v_add_f32_e32 v120, v120, v121
	s_nop 0
	v_add_f32_dpp v121, v122, v122 row_ror:8 row_mask:0xf bank_mask:0xf bound_ctrl:1
	v_add_f32_dpp v120, v120, v120 row_ror:8 row_mask:0xf bank_mask:0xf bound_ctrl:1
	s_waitcnt lgkmcnt(6)
	v_mul_f32 v122, v148, v104
	v_mul_f32 v104, v149, v104
	v_add_f32_dpp v121, v121, v121 row_ror:4 row_mask:0xf bank_mask:0xf bound_ctrl:1
	v_add_f32_dpp v120, v120, v120 row_ror:4 row_mask:0xf bank_mask:0xf bound_ctrl:1
	s_nop 0
	v_add_f32_dpp v121, v121, v121 row_ror:2 row_mask:0xf bank_mask:0xf bound_ctrl:1
	v_add_f32_dpp v120, v120, v120 row_ror:2 row_mask:0xf bank_mask:0xf bound_ctrl:1
	s_nop 0
	v_add_f32_dpp v121, v121, v121 row_ror:1 row_mask:0xf bank_mask:0xf bound_ctrl:1
	v_fma_f32 v122, v121, v96, v122
	v_add_f32_dpp v120, v120, v120 row_ror:1 row_mask:0xf bank_mask:0xf bound_ctrl:1
	v_fma_f32 v122, v112, v92, v122
	v_fma_f32 v96, v120, v96, v104
	v_fma_f32 v123, v113, v92, v96
	v_mul_f32 v92, v148, v105
	v_fma_f32 v92, v121, v97, v92
	v_fma_f32 v126, v114, v93, v92
	v_mul_f32 v92, v149, v105
	v_fma_f32 v92, v120, v97, v92
	v_fma_f32 v127, v115, v93, v92
	v_mul_f32 v92, v148, v106
	v_mul_f32 v93, v126, v85
	v_fma_f32 v92, v121, v98, v92
	v_mul_f32 v85, v127, v85
	v_fma_f32 v141, v141, v94, v92
	v_mul_f32 v92, v149, v106
	v_fma_f32 v92, v120, v98, v92
	v_fma_f32 v150, v150, v94, v92
	v_mul_f32 v92, v148, v107
	v_fma_f32 v92, v121, v99, v92
	v_fma_f32 v148, v151, v95, v92
	v_mul_f32 v92, v149, v107
	v_fma_f32 v92, v120, v99, v92
	v_fma_f32 v149, v185, v95, v92
	v_mul_f32 v92, v122, v84
	v_mul_f32 v84, v123, v84
	v_fma_f32 v92, v141, v86, v92
	v_fma_f32 v84, v150, v86, v84
	v_fma_f32 v86, v148, v87, v93
	v_fma_f32 v85, v149, v87, v85
	v_add_f32_e32 v86, v92, v86
	v_add_f32_e32 v87, v84, v85
	v_mov_b32_e32 v85, 0
	v_add_f32_dpp v84, v86, v86 row_ror:8 row_mask:0xf bank_mask:0xf bound_ctrl:1
	v_add_f32_dpp v86, v87, v87 row_ror:8 row_mask:0xf bank_mask:0xf bound_ctrl:1
	v_mov_b32_e32 v87, 0
	v_add_f32_dpp v84, v84, v84 row_ror:4 row_mask:0xf bank_mask:0xf bound_ctrl:1
	v_add_f32_dpp v86, v86, v86 row_ror:4 row_mask:0xf bank_mask:0xf bound_ctrl:1
	s_nop 0
	v_add_f32_dpp v84, v84, v84 row_ror:2 row_mask:0xf bank_mask:0xf bound_ctrl:1
	v_add_f32_dpp v86, v86, v86 row_ror:2 row_mask:0xf bank_mask:0xf bound_ctrl:1
	s_nop 0
	v_mov_b32_dpp v85, v84 row_ror:1 row_mask:0xf bank_mask:0xf
	v_mov_b32_dpp v87, v86 row_ror:1 row_mask:0xf bank_mask:0xf
	s_and_saveexec_b64 s[8:9], s[40:41]
	v_add_f32_e32 v86, v86, v87
	v_add_f32_e32 v84, v84, v85
	ds_write2_b32 v188, v84, v86 offset0:192 offset1:208
	s_or_b64 exec, exec, s[8:9]
	s_waitcnt lgkmcnt(4)
	v_mul_f32 v151, v122, v116
	v_mul_f32 v116, v123, v116
	v_mul_f32 v185, v126, v117
	v_mul_f32 v117, v127, v117
	ds_read_b128 v[112:115], v134 offset:28672
	ds_read_b128 v[96:99], v134 offset:32768
	ds_read_b128 v[104:107], v134 offset:36864
	ds_read_b128 v[92:95], v134 offset:24576
	ds_read_b128 v[84:87], v134 offset:40960
	ds_read2_b32 v[120:121], v152 offset1:16
	v_fma_f32 v151, v141, v118, v151
	v_fma_f32 v116, v150, v118, v116
	v_fma_f32 v118, v148, v119, v185
	v_fma_f32 v117, v149, v119, v117
	v_add_f32_e32 v118, v151, v118
	v_add_f32_e32 v116, v116, v117
	s_nop 0
	v_add_f32_dpp v117, v118, v118 row_ror:8 row_mask:0xf bank_mask:0xf bound_ctrl:1
	v_add_f32_dpp v116, v116, v116 row_ror:8 row_mask:0xf bank_mask:0xf bound_ctrl:1
	s_waitcnt lgkmcnt(6)
	v_mul_f32 v118, v124, v108
	v_mul_f32 v108, v125, v108
	v_add_f32_dpp v117, v117, v117 row_ror:4 row_mask:0xf bank_mask:0xf bound_ctrl:1
	v_add_f32_dpp v116, v116, v116 row_ror:4 row_mask:0xf bank_mask:0xf bound_ctrl:1
	s_nop 0
	v_add_f32_dpp v117, v117, v117 row_ror:2 row_mask:0xf bank_mask:0xf bound_ctrl:1
	v_add_f32_dpp v116, v116, v116 row_ror:2 row_mask:0xf bank_mask:0xf bound_ctrl:1
	s_nop 0
	v_add_f32_dpp v117, v117, v117 row_ror:1 row_mask:0xf bank_mask:0xf bound_ctrl:1
	v_add_f32_dpp v116, v116, v116 row_ror:1 row_mask:0xf bank_mask:0xf bound_ctrl:1
	v_fma_f32 v118, v117, v100, v118
	v_fma_f32 v100, v116, v100, v108
	v_fma_f32 v151, v122, v88, v118
	v_fma_f32 v185, v123, v88, v100
	v_mul_f32 v88, v124, v109
	v_fma_f32 v88, v117, v101, v88
	v_fma_f32 v126, v126, v89, v88
	v_mul_f32 v88, v125, v109
	v_fma_f32 v88, v116, v101, v88
	v_fma_f32 v127, v127, v89, v88
	v_mul_f32 v88, v124, v110
	v_mul_f32 v89, v126, v81
	v_fma_f32 v88, v117, v102, v88
	v_mul_f32 v81, v127, v81
	v_fma_f32 v141, v141, v90, v88
	v_mul_f32 v88, v125, v110
	v_fma_f32 v88, v116, v102, v88
	v_fma_f32 v150, v150, v90, v88
	v_mul_f32 v88, v124, v111
	v_fma_f32 v88, v117, v103, v88
	v_fma_f32 v124, v148, v91, v88
	v_mul_f32 v88, v125, v111
	v_fma_f32 v88, v116, v103, v88
	v_fma_f32 v125, v149, v91, v88
	v_mul_f32 v88, v151, v80
	v_mul_f32 v80, v185, v80
	v_fma_f32 v88, v141, v82, v88
	v_fma_f32 v80, v150, v82, v80
	v_fma_f32 v82, v124, v83, v89
	v_fma_f32 v81, v125, v83, v81
	v_add_f32_e32 v82, v88, v82
	v_add_f32_e32 v83, v80, v81
	v_mov_b32_e32 v81, 0
	v_add_f32_dpp v80, v82, v82 row_ror:8 row_mask:0xf bank_mask:0xf bound_ctrl:1
	v_add_f32_dpp v82, v83, v83 row_ror:8 row_mask:0xf bank_mask:0xf bound_ctrl:1
	v_mov_b32_e32 v83, 0
	v_add_f32_dpp v80, v80, v80 row_ror:4 row_mask:0xf bank_mask:0xf bound_ctrl:1
	v_add_f32_dpp v82, v82, v82 row_ror:4 row_mask:0xf bank_mask:0xf bound_ctrl:1
	s_nop 0
	v_add_f32_dpp v80, v80, v80 row_ror:2 row_mask:0xf bank_mask:0xf bound_ctrl:1
	v_add_f32_dpp v82, v82, v82 row_ror:2 row_mask:0xf bank_mask:0xf bound_ctrl:1
	s_nop 0
	v_mov_b32_dpp v81, v80 row_ror:1 row_mask:0xf bank_mask:0xf
	v_mov_b32_dpp v83, v82 row_ror:1 row_mask:0xf bank_mask:0xf
	s_and_saveexec_b64 s[8:9], s[40:41]
	v_add_f32_e32 v82, v82, v83
	v_add_f32_e32 v80, v80, v81
	ds_write2_b32 v188, v80, v82 offset0:224 offset1:240
	s_or_b64 exec, exec, s[8:9]
	s_waitcnt lgkmcnt(5)
	v_mul_f32 v148, v151, v112
	v_mul_f32 v112, v185, v112
	v_mul_f32 v149, v126, v113
	v_mul_f32 v113, v127, v113
	ds_read_b128 v[116:119], v134 offset:28928
	ds_read_b128 v[100:103], v134 offset:33024
	ds_read_b128 v[108:111], v134 offset:37120
	ds_read_b128 v[88:91], v134 offset:24832
	ds_read_b128 v[80:83], v134 offset:41216
	ds_read2_b32 v[122:123], v152 offset0:32 offset1:48
	v_fma_f32 v148, v141, v114, v148
	v_fma_f32 v112, v150, v114, v112
	v_fma_f32 v114, v124, v115, v149
	v_fma_f32 v113, v125, v115, v113
	v_add_f32_e32 v114, v148, v114
	v_add_f32_e32 v112, v112, v113
	s_nop 0
	v_add_f32_dpp v113, v114, v114 row_ror:8 row_mask:0xf bank_mask:0xf bound_ctrl:1
	v_add_f32_dpp v112, v112, v112 row_ror:8 row_mask:0xf bank_mask:0xf bound_ctrl:1
	s_waitcnt lgkmcnt(6)
	v_mul_f32 v114, v120, v104
	v_mul_f32 v104, v121, v104
	v_add_f32_dpp v113, v113, v113 row_ror:4 row_mask:0xf bank_mask:0xf bound_ctrl:1
	v_add_f32_dpp v112, v112, v112 row_ror:4 row_mask:0xf bank_mask:0xf bound_ctrl:1
	s_nop 0
	v_add_f32_dpp v113, v113, v113 row_ror:2 row_mask:0xf bank_mask:0xf bound_ctrl:1
	v_add_f32_dpp v112, v112, v112 row_ror:2 row_mask:0xf bank_mask:0xf bound_ctrl:1
	s_nop 0
	v_add_f32_dpp v113, v113, v113 row_ror:1 row_mask:0xf bank_mask:0xf bound_ctrl:1
	v_add_f32_dpp v112, v112, v112 row_ror:1 row_mask:0xf bank_mask:0xf bound_ctrl:1
	v_fma_f32 v114, v113, v96, v114
	v_fma_f32 v96, v112, v96, v104
	v_fma_f32 v148, v151, v92, v114
	v_fma_f32 v149, v185, v92, v96
	v_mul_f32 v92, v120, v105
	v_fma_f32 v92, v113, v97, v92
	v_fma_f32 v126, v126, v93, v92
	v_mul_f32 v92, v121, v105
	v_fma_f32 v92, v112, v97, v92
	v_fma_f32 v127, v127, v93, v92
	v_mul_f32 v92, v120, v106
	v_mul_f32 v93, v126, v85
	v_fma_f32 v92, v113, v98, v92
	v_mul_f32 v85, v127, v85
	v_fma_f32 v141, v141, v94, v92
	v_mul_f32 v92, v121, v106
	v_fma_f32 v92, v112, v98, v92
	v_fma_f32 v150, v150, v94, v92
	v_mul_f32 v92, v120, v107
	v_fma_f32 v92, v113, v99, v92
	v_fma_f32 v124, v124, v95, v92
	v_mul_f32 v92, v121, v107
	v_fma_f32 v92, v112, v99, v92
	v_fma_f32 v125, v125, v95, v92
	v_mul_f32 v92, v148, v84
	v_mul_f32 v84, v149, v84
	v_fma_f32 v92, v141, v86, v92
	v_fma_f32 v84, v150, v86, v84
	v_fma_f32 v86, v124, v87, v93
	v_fma_f32 v85, v125, v87, v85
	v_add_f32_e32 v86, v92, v86
	v_add_f32_e32 v87, v84, v85
	v_mov_b32_e32 v85, 0
	v_add_f32_dpp v84, v86, v86 row_ror:8 row_mask:0xf bank_mask:0xf bound_ctrl:1
	v_add_f32_dpp v86, v87, v87 row_ror:8 row_mask:0xf bank_mask:0xf bound_ctrl:1
	v_mov_b32_e32 v87, 0
	v_add_f32_dpp v84, v84, v84 row_ror:4 row_mask:0xf bank_mask:0xf bound_ctrl:1
	v_add_f32_dpp v86, v86, v86 row_ror:4 row_mask:0xf bank_mask:0xf bound_ctrl:1
	s_nop 0
	v_add_f32_dpp v84, v84, v84 row_ror:2 row_mask:0xf bank_mask:0xf bound_ctrl:1
	v_add_f32_dpp v86, v86, v86 row_ror:2 row_mask:0xf bank_mask:0xf bound_ctrl:1
	s_nop 0
	v_mov_b32_dpp v85, v84 row_ror:1 row_mask:0xf bank_mask:0xf
	v_mov_b32_dpp v87, v86 row_ror:1 row_mask:0xf bank_mask:0xf
	s_and_saveexec_b64 s[8:9], s[40:41]
	v_add_f32_e32 v86, v86, v87
	v_add_f32_e32 v84, v84, v85
	ds_write2_b32 v153, v84, v86 offset1:16
	s_or_b64 exec, exec, s[8:9]
	s_waitcnt lgkmcnt(5)
	v_mul_f32 v151, v148, v116
	v_mul_f32 v116, v149, v116
	v_mul_f32 v185, v126, v117
	v_mul_f32 v117, v127, v117
	ds_read_b128 v[112:115], v134 offset:29184
	ds_read_b128 v[96:99], v134 offset:33280
	ds_read_b128 v[104:107], v134 offset:37376
	ds_read_b128 v[92:95], v134 offset:25088
	ds_read_b128 v[84:87], v134 offset:41472
	ds_read2_b32 v[120:121], v152 offset0:64 offset1:80
	v_fma_f32 v151, v141, v118, v151
	v_fma_f32 v116, v150, v118, v116
	v_fma_f32 v118, v124, v119, v185
	v_fma_f32 v117, v125, v119, v117
	v_add_f32_e32 v118, v151, v118
	v_add_f32_e32 v116, v116, v117
	s_nop 0
	v_add_f32_dpp v117, v118, v118 row_ror:8 row_mask:0xf bank_mask:0xf bound_ctrl:1
	v_add_f32_dpp v116, v116, v116 row_ror:8 row_mask:0xf bank_mask:0xf bound_ctrl:1
	s_waitcnt lgkmcnt(6)
	v_mul_f32 v118, v122, v108
	v_mul_f32 v108, v123, v108
	v_add_f32_dpp v117, v117, v117 row_ror:4 row_mask:0xf bank_mask:0xf bound_ctrl:1
	v_add_f32_dpp v116, v116, v116 row_ror:4 row_mask:0xf bank_mask:0xf bound_ctrl:1
	s_nop 0
	v_add_f32_dpp v117, v117, v117 row_ror:2 row_mask:0xf bank_mask:0xf bound_ctrl:1
	v_add_f32_dpp v116, v116, v116 row_ror:2 row_mask:0xf bank_mask:0xf bound_ctrl:1
	s_nop 0
	v_add_f32_dpp v117, v117, v117 row_ror:1 row_mask:0xf bank_mask:0xf bound_ctrl:1
	v_add_f32_dpp v116, v116, v116 row_ror:1 row_mask:0xf bank_mask:0xf bound_ctrl:1
	v_fma_f32 v118, v117, v100, v118
	v_fma_f32 v100, v116, v100, v108
	v_fma_f32 v148, v148, v88, v118
	v_fma_f32 v149, v149, v88, v100
	v_mul_f32 v88, v122, v109
	v_fma_f32 v88, v117, v101, v88
	v_fma_f32 v126, v126, v89, v88
	v_mul_f32 v88, v123, v109
	v_fma_f32 v88, v116, v101, v88
	v_fma_f32 v127, v127, v89, v88
	v_mul_f32 v88, v122, v110
	v_mul_f32 v89, v126, v81
	v_fma_f32 v88, v117, v102, v88
	v_mul_f32 v81, v127, v81
	v_fma_f32 v141, v141, v90, v88
	v_mul_f32 v88, v123, v110
	v_fma_f32 v88, v116, v102, v88
	v_fma_f32 v150, v150, v90, v88
	v_mul_f32 v88, v122, v111
	v_fma_f32 v88, v117, v103, v88
	v_fma_f32 v124, v124, v91, v88
	v_mul_f32 v88, v123, v111
	v_fma_f32 v88, v116, v103, v88
	v_fma_f32 v125, v125, v91, v88
	v_mul_f32 v88, v148, v80
	v_mul_f32 v80, v149, v80
	v_fma_f32 v88, v141, v82, v88
	v_fma_f32 v80, v150, v82, v80
	v_fma_f32 v82, v124, v83, v89
	v_fma_f32 v81, v125, v83, v81
	v_add_f32_e32 v82, v88, v82
	v_add_f32_e32 v83, v80, v81
	v_mov_b32_e32 v81, 0
	v_add_f32_dpp v80, v82, v82 row_ror:8 row_mask:0xf bank_mask:0xf bound_ctrl:1
	v_add_f32_dpp v82, v83, v83 row_ror:8 row_mask:0xf bank_mask:0xf bound_ctrl:1
	v_mov_b32_e32 v83, 0
	v_add_f32_dpp v80, v80, v80 row_ror:4 row_mask:0xf bank_mask:0xf bound_ctrl:1
	v_add_f32_dpp v82, v82, v82 row_ror:4 row_mask:0xf bank_mask:0xf bound_ctrl:1
	s_nop 0
	v_add_f32_dpp v80, v80, v80 row_ror:2 row_mask:0xf bank_mask:0xf bound_ctrl:1
	v_add_f32_dpp v82, v82, v82 row_ror:2 row_mask:0xf bank_mask:0xf bound_ctrl:1
	s_nop 0
	v_mov_b32_dpp v81, v80 row_ror:1 row_mask:0xf bank_mask:0xf
	v_mov_b32_dpp v83, v82 row_ror:1 row_mask:0xf bank_mask:0xf
	s_and_saveexec_b64 s[8:9], s[40:41]
	v_add_f32_e32 v82, v82, v83
	v_add_f32_e32 v80, v80, v81
	ds_write2_b32 v153, v80, v82 offset0:32 offset1:48
	s_or_b64 exec, exec, s[8:9]
	s_waitcnt lgkmcnt(5)
	v_mul_f32 v151, v148, v112
	v_mul_f32 v112, v149, v112
	v_mul_f32 v185, v126, v113
	v_mul_f32 v113, v127, v113
	ds_read_b128 v[116:119], v134 offset:29440
	ds_read_b128 v[100:103], v134 offset:33536
	ds_read_b128 v[108:111], v134 offset:37632
	ds_read_b128 v[88:91], v134 offset:25344
	ds_read_b128 v[80:83], v134 offset:41728
	ds_read2_b32 v[122:123], v152 offset0:96 offset1:112
	v_fma_f32 v151, v141, v114, v151
	v_fma_f32 v112, v150, v114, v112
	v_fma_f32 v114, v124, v115, v185
	v_fma_f32 v113, v125, v115, v113
	v_add_f32_e32 v114, v151, v114
	v_add_f32_e32 v112, v112, v113
	s_nop 0
	v_add_f32_dpp v113, v114, v114 row_ror:8 row_mask:0xf bank_mask:0xf bound_ctrl:1
	v_add_f32_dpp v112, v112, v112 row_ror:8 row_mask:0xf bank_mask:0xf bound_ctrl:1
	s_waitcnt lgkmcnt(6)
	v_mul_f32 v114, v120, v104
	v_mul_f32 v104, v121, v104
	v_add_f32_dpp v113, v113, v113 row_ror:4 row_mask:0xf bank_mask:0xf bound_ctrl:1
	v_add_f32_dpp v112, v112, v112 row_ror:4 row_mask:0xf bank_mask:0xf bound_ctrl:1
	s_nop 0
	v_add_f32_dpp v113, v113, v113 row_ror:2 row_mask:0xf bank_mask:0xf bound_ctrl:1
	v_add_f32_dpp v112, v112, v112 row_ror:2 row_mask:0xf bank_mask:0xf bound_ctrl:1
	s_nop 0
	v_add_f32_dpp v113, v113, v113 row_ror:1 row_mask:0xf bank_mask:0xf bound_ctrl:1
	v_add_f32_dpp v112, v112, v112 row_ror:1 row_mask:0xf bank_mask:0xf bound_ctrl:1
	v_fma_f32 v114, v113, v96, v114
	v_fma_f32 v96, v112, v96, v104
	v_fma_f32 v148, v148, v92, v114
	v_fma_f32 v149, v149, v92, v96
	v_mul_f32 v92, v120, v105
	v_fma_f32 v92, v113, v97, v92
	v_fma_f32 v126, v126, v93, v92
	v_mul_f32 v92, v121, v105
	v_fma_f32 v92, v112, v97, v92
	v_fma_f32 v127, v127, v93, v92
	v_mul_f32 v92, v120, v106
	v_mul_f32 v93, v126, v85
	v_fma_f32 v92, v113, v98, v92
	v_mul_f32 v85, v127, v85
	v_fma_f32 v141, v141, v94, v92
	v_mul_f32 v92, v121, v106
	v_fma_f32 v92, v112, v98, v92
	v_fma_f32 v150, v150, v94, v92
	v_mul_f32 v92, v120, v107
	v_fma_f32 v92, v113, v99, v92
	v_fma_f32 v124, v124, v95, v92
	v_mul_f32 v92, v121, v107
	v_fma_f32 v92, v112, v99, v92
	v_fma_f32 v125, v125, v95, v92
	v_mul_f32 v92, v148, v84
	v_mul_f32 v84, v149, v84
	v_fma_f32 v92, v141, v86, v92
	v_fma_f32 v84, v150, v86, v84
	v_fma_f32 v86, v124, v87, v93
	v_fma_f32 v85, v125, v87, v85
	v_add_f32_e32 v86, v92, v86
	v_add_f32_e32 v87, v84, v85
	v_mov_b32_e32 v85, 0
	v_add_f32_dpp v84, v86, v86 row_ror:8 row_mask:0xf bank_mask:0xf bound_ctrl:1
	v_add_f32_dpp v86, v87, v87 row_ror:8 row_mask:0xf bank_mask:0xf bound_ctrl:1
	v_mov_b32_e32 v87, 0
	v_add_f32_dpp v84, v84, v84 row_ror:4 row_mask:0xf bank_mask:0xf bound_ctrl:1
	v_add_f32_dpp v86, v86, v86 row_ror:4 row_mask:0xf bank_mask:0xf bound_ctrl:1
	s_nop 0
	v_add_f32_dpp v84, v84, v84 row_ror:2 row_mask:0xf bank_mask:0xf bound_ctrl:1
	v_add_f32_dpp v86, v86, v86 row_ror:2 row_mask:0xf bank_mask:0xf bound_ctrl:1
	s_nop 0
	v_mov_b32_dpp v85, v84 row_ror:1 row_mask:0xf bank_mask:0xf
	v_mov_b32_dpp v87, v86 row_ror:1 row_mask:0xf bank_mask:0xf
	s_and_saveexec_b64 s[8:9], s[40:41]
	v_add_f32_e32 v86, v86, v87
	v_add_f32_e32 v84, v84, v85
	ds_write2_b32 v153, v84, v86 offset0:64 offset1:80
	s_or_b64 exec, exec, s[8:9]
	s_waitcnt lgkmcnt(5)
	v_mul_f32 v151, v148, v116
	v_mul_f32 v116, v149, v116
	v_mul_f32 v185, v126, v117
	v_mul_f32 v117, v127, v117
	ds_read_b128 v[112:115], v134 offset:29696
	ds_read_b128 v[96:99], v134 offset:33792
	ds_read_b128 v[104:107], v134 offset:37888
	ds_read_b128 v[92:95], v134 offset:25600
	ds_read_b128 v[84:87], v134 offset:41984
	ds_read2_b32 v[120:121], v152 offset0:128 offset1:144
	v_fma_f32 v151, v141, v118, v151
	v_fma_f32 v116, v150, v118, v116
	v_fma_f32 v118, v124, v119, v185
	v_fma_f32 v117, v125, v119, v117
	v_add_f32_e32 v118, v151, v118
	v_add_f32_e32 v116, v116, v117
	s_nop 0
	v_add_f32_dpp v117, v118, v118 row_ror:8 row_mask:0xf bank_mask:0xf bound_ctrl:1
	v_add_f32_dpp v116, v116, v116 row_ror:8 row_mask:0xf bank_mask:0xf bound_ctrl:1
	s_waitcnt lgkmcnt(6)
	v_mul_f32 v118, v122, v108
	v_mul_f32 v108, v123, v108
	v_add_f32_dpp v117, v117, v117 row_ror:4 row_mask:0xf bank_mask:0xf bound_ctrl:1
	v_add_f32_dpp v116, v116, v116 row_ror:4 row_mask:0xf bank_mask:0xf bound_ctrl:1
	s_nop 0
	v_add_f32_dpp v117, v117, v117 row_ror:2 row_mask:0xf bank_mask:0xf bound_ctrl:1
	v_add_f32_dpp v116, v116, v116 row_ror:2 row_mask:0xf bank_mask:0xf bound_ctrl:1
	s_nop 0
	v_add_f32_dpp v117, v117, v117 row_ror:1 row_mask:0xf bank_mask:0xf bound_ctrl:1
	v_add_f32_dpp v116, v116, v116 row_ror:1 row_mask:0xf bank_mask:0xf bound_ctrl:1
	v_fma_f32 v118, v117, v100, v118
	v_fma_f32 v100, v116, v100, v108
	v_fma_f32 v148, v148, v88, v118
	v_fma_f32 v149, v149, v88, v100
	v_mul_f32 v88, v122, v109
	v_fma_f32 v88, v117, v101, v88
	v_fma_f32 v126, v126, v89, v88
	v_mul_f32 v88, v123, v109
	v_fma_f32 v88, v116, v101, v88
	v_fma_f32 v127, v127, v89, v88
	v_mul_f32 v88, v122, v110
	v_mul_f32 v89, v126, v81
	v_fma_f32 v88, v117, v102, v88
	v_mul_f32 v81, v127, v81
	v_fma_f32 v141, v141, v90, v88
	v_mul_f32 v88, v123, v110
	v_fma_f32 v88, v116, v102, v88
	v_fma_f32 v150, v150, v90, v88
	v_mul_f32 v88, v122, v111
	v_fma_f32 v88, v117, v103, v88
	v_fma_f32 v124, v124, v91, v88
	v_mul_f32 v88, v123, v111
	v_fma_f32 v88, v116, v103, v88
	v_fma_f32 v125, v125, v91, v88
	v_mul_f32 v88, v148, v80
	v_mul_f32 v80, v149, v80
	v_fma_f32 v88, v141, v82, v88
	v_fma_f32 v80, v150, v82, v80
	v_fma_f32 v82, v124, v83, v89
	v_fma_f32 v81, v125, v83, v81
	v_add_f32_e32 v82, v88, v82
	v_add_f32_e32 v83, v80, v81
	v_mov_b32_e32 v81, 0
	v_add_f32_dpp v80, v82, v82 row_ror:8 row_mask:0xf bank_mask:0xf bound_ctrl:1
	v_add_f32_dpp v82, v83, v83 row_ror:8 row_mask:0xf bank_mask:0xf bound_ctrl:1
	v_mov_b32_e32 v83, 0
	v_add_f32_dpp v80, v80, v80 row_ror:4 row_mask:0xf bank_mask:0xf bound_ctrl:1
	v_add_f32_dpp v82, v82, v82 row_ror:4 row_mask:0xf bank_mask:0xf bound_ctrl:1
	s_nop 0
	v_add_f32_dpp v80, v80, v80 row_ror:2 row_mask:0xf bank_mask:0xf bound_ctrl:1
	v_add_f32_dpp v82, v82, v82 row_ror:2 row_mask:0xf bank_mask:0xf bound_ctrl:1
	s_nop 0
	v_mov_b32_dpp v81, v80 row_ror:1 row_mask:0xf bank_mask:0xf
	v_mov_b32_dpp v83, v82 row_ror:1 row_mask:0xf bank_mask:0xf
	s_and_saveexec_b64 s[8:9], s[40:41]
	v_add_f32_e32 v82, v82, v83
	v_add_f32_e32 v80, v80, v81
	ds_write2_b32 v153, v80, v82 offset0:96 offset1:112
	s_or_b64 exec, exec, s[8:9]
	s_waitcnt lgkmcnt(5)
	v_mul_f32 v151, v148, v112
	v_mul_f32 v112, v149, v112
	v_mul_f32 v185, v126, v113
	v_mul_f32 v113, v127, v113
	ds_read_b128 v[116:119], v134 offset:29952
	ds_read_b128 v[100:103], v134 offset:34048
	ds_read_b128 v[108:111], v134 offset:38144
	ds_read_b128 v[88:91], v134 offset:25856
	ds_read_b128 v[80:83], v134 offset:42240
	ds_read2_b32 v[122:123], v152 offset0:160 offset1:176
	v_fma_f32 v151, v141, v114, v151
	v_fma_f32 v112, v150, v114, v112
	v_fma_f32 v114, v124, v115, v185
	v_fma_f32 v113, v125, v115, v113
	v_add_f32_e32 v114, v151, v114
	v_add_f32_e32 v112, v112, v113
	s_nop 0
	v_add_f32_dpp v113, v114, v114 row_ror:8 row_mask:0xf bank_mask:0xf bound_ctrl:1
	v_add_f32_dpp v112, v112, v112 row_ror:8 row_mask:0xf bank_mask:0xf bound_ctrl:1
	s_waitcnt lgkmcnt(6)
	v_mul_f32 v114, v120, v104
	v_mul_f32 v104, v121, v104
	v_add_f32_dpp v113, v113, v113 row_ror:4 row_mask:0xf bank_mask:0xf bound_ctrl:1
	v_add_f32_dpp v112, v112, v112 row_ror:4 row_mask:0xf bank_mask:0xf bound_ctrl:1
	s_nop 0
	v_add_f32_dpp v113, v113, v113 row_ror:2 row_mask:0xf bank_mask:0xf bound_ctrl:1
	v_add_f32_dpp v112, v112, v112 row_ror:2 row_mask:0xf bank_mask:0xf bound_ctrl:1
	s_nop 0
	v_add_f32_dpp v113, v113, v113 row_ror:1 row_mask:0xf bank_mask:0xf bound_ctrl:1
	v_add_f32_dpp v112, v112, v112 row_ror:1 row_mask:0xf bank_mask:0xf bound_ctrl:1
	v_fma_f32 v114, v113, v96, v114
	v_fma_f32 v96, v112, v96, v104
	v_fma_f32 v148, v148, v92, v114
	v_fma_f32 v149, v149, v92, v96
	v_mul_f32 v92, v120, v105
	v_fma_f32 v92, v113, v97, v92
	v_fma_f32 v126, v126, v93, v92
	v_mul_f32 v92, v121, v105
	v_fma_f32 v92, v112, v97, v92
	v_fma_f32 v127, v127, v93, v92
	v_mul_f32 v92, v120, v106
	v_mul_f32 v93, v126, v85
	v_fma_f32 v92, v113, v98, v92
	v_mul_f32 v85, v127, v85
	v_fma_f32 v141, v141, v94, v92
	v_mul_f32 v92, v121, v106
	v_fma_f32 v92, v112, v98, v92
	v_fma_f32 v150, v150, v94, v92
	v_mul_f32 v92, v120, v107
	v_fma_f32 v92, v113, v99, v92
	v_fma_f32 v124, v124, v95, v92
	v_mul_f32 v92, v121, v107
	v_fma_f32 v92, v112, v99, v92
	v_fma_f32 v125, v125, v95, v92
	v_mul_f32 v92, v148, v84
	v_mul_f32 v84, v149, v84
	v_fma_f32 v92, v141, v86, v92
	v_fma_f32 v84, v150, v86, v84
	v_fma_f32 v86, v124, v87, v93
	v_fma_f32 v85, v125, v87, v85
	v_add_f32_e32 v86, v92, v86
	v_add_f32_e32 v87, v84, v85
	v_mov_b32_e32 v85, 0
	v_add_f32_dpp v84, v86, v86 row_ror:8 row_mask:0xf bank_mask:0xf bound_ctrl:1
	v_add_f32_dpp v86, v87, v87 row_ror:8 row_mask:0xf bank_mask:0xf bound_ctrl:1
	v_mov_b32_e32 v87, 0
	v_add_f32_dpp v84, v84, v84 row_ror:4 row_mask:0xf bank_mask:0xf bound_ctrl:1
	v_add_f32_dpp v86, v86, v86 row_ror:4 row_mask:0xf bank_mask:0xf bound_ctrl:1
	s_nop 0
	v_add_f32_dpp v84, v84, v84 row_ror:2 row_mask:0xf bank_mask:0xf bound_ctrl:1
	v_add_f32_dpp v86, v86, v86 row_ror:2 row_mask:0xf bank_mask:0xf bound_ctrl:1
	s_nop 0
	v_mov_b32_dpp v85, v84 row_ror:1 row_mask:0xf bank_mask:0xf
	v_mov_b32_dpp v87, v86 row_ror:1 row_mask:0xf bank_mask:0xf
	s_and_saveexec_b64 s[8:9], s[40:41]
	v_add_f32_e32 v86, v86, v87
	v_add_f32_e32 v84, v84, v85
	ds_write2_b32 v153, v84, v86 offset0:128 offset1:144
	s_or_b64 exec, exec, s[8:9]
	s_waitcnt lgkmcnt(5)
	v_mul_f32 v151, v148, v116
	v_mul_f32 v116, v149, v116
	v_mul_f32 v185, v126, v117
	v_mul_f32 v117, v127, v117
	ds_read_b128 v[112:115], v134 offset:30208
	ds_read_b128 v[96:99], v134 offset:34304
	ds_read_b128 v[104:107], v134 offset:38400
	ds_read_b128 v[92:95], v134 offset:26112
	ds_read_b128 v[84:87], v134 offset:42496
	ds_read2_b32 v[120:121], v152 offset0:192 offset1:208
	v_fma_f32 v151, v141, v118, v151
	v_fma_f32 v116, v150, v118, v116
	v_fma_f32 v118, v124, v119, v185
	v_fma_f32 v117, v125, v119, v117
	v_add_f32_e32 v118, v151, v118
	v_add_f32_e32 v116, v116, v117
	s_nop 0
	v_add_f32_dpp v117, v118, v118 row_ror:8 row_mask:0xf bank_mask:0xf bound_ctrl:1
	v_add_f32_dpp v116, v116, v116 row_ror:8 row_mask:0xf bank_mask:0xf bound_ctrl:1
	s_waitcnt lgkmcnt(6)
	v_mul_f32 v118, v122, v108
	v_mul_f32 v108, v123, v108
	v_add_f32_dpp v117, v117, v117 row_ror:4 row_mask:0xf bank_mask:0xf bound_ctrl:1
	v_add_f32_dpp v116, v116, v116 row_ror:4 row_mask:0xf bank_mask:0xf bound_ctrl:1
	s_nop 0
	v_add_f32_dpp v117, v117, v117 row_ror:2 row_mask:0xf bank_mask:0xf bound_ctrl:1
	v_add_f32_dpp v116, v116, v116 row_ror:2 row_mask:0xf bank_mask:0xf bound_ctrl:1
	s_nop 0
	v_add_f32_dpp v117, v117, v117 row_ror:1 row_mask:0xf bank_mask:0xf bound_ctrl:1
	v_add_f32_dpp v116, v116, v116 row_ror:1 row_mask:0xf bank_mask:0xf bound_ctrl:1
	v_fma_f32 v118, v117, v100, v118
	v_fma_f32 v100, v116, v100, v108
	v_fma_f32 v148, v148, v88, v118
	v_fma_f32 v149, v149, v88, v100
	v_mul_f32 v88, v122, v109
	v_fma_f32 v88, v117, v101, v88
	v_fma_f32 v126, v126, v89, v88
	v_mul_f32 v88, v123, v109
	v_fma_f32 v88, v116, v101, v88
	v_fma_f32 v127, v127, v89, v88
	v_mul_f32 v88, v122, v110
	v_mul_f32 v89, v126, v81
	v_fma_f32 v88, v117, v102, v88
	v_mul_f32 v81, v127, v81
	v_fma_f32 v141, v141, v90, v88
	v_mul_f32 v88, v123, v110
	v_fma_f32 v88, v116, v102, v88
	v_fma_f32 v150, v150, v90, v88
	v_mul_f32 v88, v122, v111
	v_fma_f32 v88, v117, v103, v88
	v_fma_f32 v124, v124, v91, v88
	v_mul_f32 v88, v123, v111
	v_fma_f32 v88, v116, v103, v88
	v_fma_f32 v125, v125, v91, v88
	v_mul_f32 v88, v148, v80
	v_mul_f32 v80, v149, v80
	v_fma_f32 v88, v141, v82, v88
	v_fma_f32 v80, v150, v82, v80
	v_fma_f32 v82, v124, v83, v89
	v_fma_f32 v81, v125, v83, v81
	v_add_f32_e32 v82, v88, v82
	v_add_f32_e32 v83, v80, v81
	v_mov_b32_e32 v81, 0
	v_add_f32_dpp v80, v82, v82 row_ror:8 row_mask:0xf bank_mask:0xf bound_ctrl:1
	v_add_f32_dpp v82, v83, v83 row_ror:8 row_mask:0xf bank_mask:0xf bound_ctrl:1
	v_mov_b32_e32 v83, 0
	v_add_f32_dpp v80, v80, v80 row_ror:4 row_mask:0xf bank_mask:0xf bound_ctrl:1
	v_add_f32_dpp v82, v82, v82 row_ror:4 row_mask:0xf bank_mask:0xf bound_ctrl:1
	s_nop 0
	v_add_f32_dpp v80, v80, v80 row_ror:2 row_mask:0xf bank_mask:0xf bound_ctrl:1
	v_add_f32_dpp v82, v82, v82 row_ror:2 row_mask:0xf bank_mask:0xf bound_ctrl:1
	s_nop 0
	v_mov_b32_dpp v81, v80 row_ror:1 row_mask:0xf bank_mask:0xf
	v_mov_b32_dpp v83, v82 row_ror:1 row_mask:0xf bank_mask:0xf
	s_and_saveexec_b64 s[8:9], s[40:41]
	v_add_f32_e32 v82, v82, v83
	v_add_f32_e32 v80, v80, v81
	ds_write2_b32 v153, v80, v82 offset0:160 offset1:176
	s_or_b64 exec, exec, s[8:9]
	s_waitcnt lgkmcnt(5)
	v_mul_f32 v151, v148, v112
	v_mul_f32 v112, v149, v112
	ds_read_b128 v[116:119], v134 offset:30464
	ds_read_b128 v[100:103], v134 offset:34560
	ds_read_b128 v[108:111], v134 offset:38656
	ds_read_b128 v[80:83], v134 offset:26368
	ds_read_b128 v[88:91], v134 offset:42752
	ds_read2_b32 v[122:123], v152 offset0:224 offset1:240
	v_mul_f32 v152, v126, v113
	v_mul_f32 v113, v127, v113
	v_fma_f32 v112, v150, v114, v112
	v_fma_f32 v151, v141, v114, v151
	v_fma_f32 v114, v124, v115, v152
	v_fma_f32 v113, v125, v115, v113
	v_add_f32_e32 v112, v112, v113
	v_add_f32_e32 v114, v151, v114
	s_nop 0
	v_add_f32_dpp v112, v112, v112 row_ror:8 row_mask:0xf bank_mask:0xf bound_ctrl:1
	v_add_f32_dpp v113, v114, v114 row_ror:8 row_mask:0xf bank_mask:0xf bound_ctrl:1
	s_nop 0
	v_add_f32_dpp v112, v112, v112 row_ror:4 row_mask:0xf bank_mask:0xf bound_ctrl:1
	v_add_f32_dpp v113, v113, v113 row_ror:4 row_mask:0xf bank_mask:0xf bound_ctrl:1
	s_nop 0
	v_add_f32_dpp v112, v112, v112 row_ror:2 row_mask:0xf bank_mask:0xf bound_ctrl:1
	v_add_f32_dpp v113, v113, v113 row_ror:2 row_mask:0xf bank_mask:0xf bound_ctrl:1
	s_nop 0
	v_add_f32_dpp v114, v112, v112 row_ror:1 row_mask:0xf bank_mask:0xf bound_ctrl:1
	s_waitcnt lgkmcnt(6)
	v_mul_f32 v112, v120, v104
	v_add_f32_dpp v113, v113, v113 row_ror:1 row_mask:0xf bank_mask:0xf bound_ctrl:1
	v_fma_f32 v112, v113, v96, v112
	v_mul_f32 v104, v121, v104
	v_fma_f32 v96, v114, v96, v104
	v_fma_f32 v112, v148, v92, v112
	v_mul_f32 v104, v121, v105
	v_fma_f32 v92, v149, v92, v96
	v_mul_f32 v96, v120, v105
	v_fma_f32 v96, v113, v97, v96
	v_fma_f32 v97, v114, v97, v104
	v_mul_f32 v104, v121, v106
	v_fma_f32 v96, v126, v93, v96
	v_fma_f32 v93, v127, v93, v97
	v_mul_f32 v97, v120, v106
	v_fma_f32 v97, v113, v98, v97
	v_fma_f32 v98, v114, v98, v104
	v_mul_f32 v104, v121, v107
	v_fma_f32 v97, v141, v94, v97
	v_fma_f32 v94, v150, v94, v98
	v_mul_f32 v98, v120, v107
	v_fma_f32 v98, v113, v99, v98
	v_fma_f32 v99, v114, v99, v104
	v_mul_f32 v104, v96, v85
	v_mul_f32 v85, v93, v85
	v_fma_f32 v98, v124, v95, v98
	v_fma_f32 v95, v125, v95, v99
	v_mul_f32 v99, v112, v84
	v_mul_f32 v84, v92, v84
	v_fma_f32 v99, v97, v86, v99
	v_fma_f32 v84, v94, v86, v84
	v_fma_f32 v86, v98, v87, v104
	v_fma_f32 v85, v95, v87, v85
	v_add_f32_e32 v86, v99, v86
	v_add_f32_e32 v87, v84, v85
	v_mov_b32_e32 v85, 0
	v_add_f32_dpp v84, v86, v86 row_ror:8 row_mask:0xf bank_mask:0xf bound_ctrl:1
	v_add_f32_dpp v86, v87, v87 row_ror:8 row_mask:0xf bank_mask:0xf bound_ctrl:1
	v_mov_b32_e32 v87, 0
	v_add_f32_dpp v84, v84, v84 row_ror:4 row_mask:0xf bank_mask:0xf bound_ctrl:1
	v_add_f32_dpp v86, v86, v86 row_ror:4 row_mask:0xf bank_mask:0xf bound_ctrl:1
	s_nop 0
	v_add_f32_dpp v84, v84, v84 row_ror:2 row_mask:0xf bank_mask:0xf bound_ctrl:1
	v_add_f32_dpp v86, v86, v86 row_ror:2 row_mask:0xf bank_mask:0xf bound_ctrl:1
	s_nop 0
	v_mov_b32_dpp v85, v84 row_ror:1 row_mask:0xf bank_mask:0xf
	v_mov_b32_dpp v87, v86 row_ror:1 row_mask:0xf bank_mask:0xf
	s_and_saveexec_b64 s[8:9], s[40:41]
	v_add_f32_e32 v86, v86, v87
	v_add_f32_e32 v84, v84, v85
	ds_write2_b32 v153, v84, v86 offset0:192 offset1:208
	s_or_b64 exec, exec, s[8:9]
	s_waitcnt lgkmcnt(5)
	v_mul_f32 v84, v112, v116
	v_mul_f32 v86, v96, v117
	v_mul_f32 v85, v92, v116
	v_mul_f32 v87, v93, v117
	v_fma_f32 v84, v97, v118, v84
	v_fma_f32 v86, v98, v119, v86
	v_fma_f32 v85, v94, v118, v85
	v_fma_f32 v87, v95, v119, v87
	v_add_f32_e32 v84, v84, v86
	v_add_f32_e32 v85, v85, v87
	s_nop 0
	v_add_f32_dpp v84, v84, v84 row_ror:8 row_mask:0xf bank_mask:0xf bound_ctrl:1
	s_waitcnt lgkmcnt(0)
	v_mul_f32 v86, v123, v109
	v_add_f32_dpp v84, v84, v84 row_ror:4 row_mask:0xf bank_mask:0xf bound_ctrl:1
	s_nop 1
	v_add_f32_dpp v84, v84, v84 row_ror:2 row_mask:0xf bank_mask:0xf bound_ctrl:1
	s_nop 1
	v_add_f32_dpp v87, v84, v84 row_ror:1 row_mask:0xf bank_mask:0xf bound_ctrl:1
	v_add_f32_dpp v84, v85, v85 row_ror:8 row_mask:0xf bank_mask:0xf bound_ctrl:1
	v_mul_f32 v85, v123, v108
	s_nop 0
	v_add_f32_dpp v84, v84, v84 row_ror:4 row_mask:0xf bank_mask:0xf bound_ctrl:1
	s_nop 1
	v_add_f32_dpp v84, v84, v84 row_ror:2 row_mask:0xf bank_mask:0xf bound_ctrl:1
	s_nop 1
	v_add_f32_dpp v99, v84, v84 row_ror:1 row_mask:0xf bank_mask:0xf bound_ctrl:1
	v_mul_f32 v84, v122, v108
	v_fma_f32 v85, v99, v100, v85
	v_fma_f32 v86, v99, v101, v86
	v_fma_f32 v84, v87, v100, v84
	v_fma_f32 v84, v112, v80, v84
	v_fma_f32 v80, v92, v80, v85
	v_mul_f32 v85, v122, v109
	v_mul_f32 v92, v123, v110
	v_fma_f32 v85, v87, v101, v85
	v_fma_f32 v92, v99, v102, v92
	v_fma_f32 v85, v96, v81, v85
	v_fma_f32 v81, v93, v81, v86
	v_mul_f32 v86, v122, v110
	v_fma_f32 v86, v87, v102, v86
	v_mul_f32 v93, v85, v89
	v_mul_f32 v89, v81, v89
	v_fma_f32 v86, v97, v82, v86
	v_fma_f32 v82, v94, v82, v92
	v_mul_f32 v92, v122, v111
	v_fma_f32 v87, v87, v103, v92
	v_mul_f32 v92, v123, v111
	v_fma_f32 v92, v99, v103, v92
	v_fma_f32 v87, v98, v83, v87
	v_fma_f32 v83, v95, v83, v92
	v_mul_f32 v92, v84, v88
	v_mul_f32 v88, v80, v88
	v_fma_f32 v92, v86, v90, v92
	v_fma_f32 v88, v82, v90, v88
	v_fma_f32 v90, v87, v91, v93
	v_fma_f32 v89, v83, v91, v89
	v_add_f32_e32 v90, v92, v90
	v_add_f32_e32 v91, v88, v89
	v_mov_b32_e32 v89, 0
	v_add_f32_dpp v88, v90, v90 row_ror:8 row_mask:0xf bank_mask:0xf bound_ctrl:1
	v_add_f32_dpp v90, v91, v91 row_ror:8 row_mask:0xf bank_mask:0xf bound_ctrl:1
	v_mov_b32_e32 v91, 0
	v_add_f32_dpp v88, v88, v88 row_ror:4 row_mask:0xf bank_mask:0xf bound_ctrl:1
	v_add_f32_dpp v90, v90, v90 row_ror:4 row_mask:0xf bank_mask:0xf bound_ctrl:1
	s_nop 0
	v_add_f32_dpp v88, v88, v88 row_ror:2 row_mask:0xf bank_mask:0xf bound_ctrl:1
	v_add_f32_dpp v90, v90, v90 row_ror:2 row_mask:0xf bank_mask:0xf bound_ctrl:1
	s_nop 0
	v_mov_b32_dpp v89, v88 row_ror:1 row_mask:0xf bank_mask:0xf
	v_mov_b32_dpp v91, v90 row_ror:1 row_mask:0xf bank_mask:0xf
	s_and_saveexec_b64 s[8:9], s[40:41]
	s_cbranch_execz .LBB0_332
	v_add_f32_e32 v90, v90, v91
	v_add_f32_e32 v88, v88, v89
	ds_write2_b32 v153, v88, v90 offset0:224 offset1:240
	s_branch .LBB0_332

.LBB0_499:
	s_or_b64 exec, exec, s[8:9]
	v_ashrrev_i32_e32 v43, 5, v41
	s_waitcnt vmcnt(9)
	v_add_u32_e32 v48, s22, v43
	v_ashrrev_i32_e32 v49, 31, v48
	v_and_b32_e32 v43, 31, v41
	v_lshlrev_b64 v[50:51], 13, v[48:49]
	s_waitcnt vmcnt(8)
	v_lshl_add_u64 v[52:53], s[30:31], 0, v[50:51]
	v_lshlrev_b32_e32 v48, 2, v43
	v_mov_b32_e32 v49, v140
	v_lshl_add_u64 v[52:53], v[52:53], 0, v[48:49]
	s_lshl_b32 s94, s23, 2
	v_lshl_add_u64 v[52:53], v[52:53], 0, s[94:95]
	s_lshl_b32 s46, s15, 2
	s_mov_b32 s47, s95
	v_lshl_add_u64 v[52:53], v[52:53], 0, s[46:47]
	global_load_dword v43, v[52:53], off
	v_lshlrev_b32_e32 v46, 2, v46
	s_and_saveexec_b64 s[8:9], vcc
	s_cbranch_execz .LBB0_501
	s_waitcnt vmcnt(2)
	v_add_f32_e32 v23, v23, v35
	v_mul_f32_e64 v35, |v23|, s62
	v_exp_f32_e32 v35, v35
	s_waitcnt vmcnt(1)
	v_add_f32_e32 v29, v29, v37
	v_add_f32_e32 v22, v22, v34
	v_mul_f32_e64 v34, |v22|, s62
	v_add_f32_e32 v35, 1.0, v35
	v_cmp_gt_f32_e32 vcc, s5, v35
	v_add_f32_e32 v28, v28, v36
	v_exp_f32_e32 v34, v34
	v_cndmask_b32_e64 v37, 0, 32, vcc
	v_ldexp_f32 v35, v35, v37
	v_log_f32_e32 v35, v35
	v_add_f32_e32 v34, 1.0, v34
	v_min_f32_e32 v23, 0, v23
	v_add_f32_e32 v21, v21, v33
	v_mul_f32_e32 v36, 0x3f317217, v35
	v_fma_f32 v36, v35, s76, -v36
	v_fmac_f32_e32 v36, 0x3377d1cf, v35
	v_fmac_f32_e32 v36, 0x3f317217, v35
	v_cmp_lt_f32_e64 s[38:39], |v35|, s77
	v_mul_f32_e64 v33, |v21|, s62
	v_exp_f32_e32 v33, v33
	v_cndmask_b32_e64 v35, v35, v36, s[38:39]
	v_cndmask_b32_e32 v36, 0, v171, vcc
	v_sub_f32_e32 v35, v35, v36
	v_cmp_gt_f32_e32 vcc, s5, v34
	v_sub_f32_e32 v23, v23, v35
	v_add_f32_e32 v33, 1.0, v33
	v_cndmask_b32_e64 v35, 0, 32, vcc
	v_ldexp_f32 v34, v34, v35
	v_log_f32_e32 v34, v34
	v_min_f32_e32 v22, 0, v22
	v_add_f32_e32 v20, v20, v32
	v_mul_f32_e64 v32, |v20|, s62
	v_mul_f32_e32 v35, 0x3f317217, v34
	v_fma_f32 v35, v34, s76, -v35
	v_fmac_f32_e32 v35, 0x3377d1cf, v34
	v_fmac_f32_e32 v35, 0x3f317217, v34
	v_cmp_lt_f32_e64 s[38:39], |v34|, s77
	v_exp_f32_e32 v32, v32
	v_min_f32_e32 v21, 0, v21
	v_cndmask_b32_e64 v34, v34, v35, s[38:39]
	v_cndmask_b32_e32 v35, 0, v171, vcc
	v_sub_f32_e32 v34, v34, v35
	v_cmp_gt_f32_e32 vcc, s5, v33
	v_sub_f32_e32 v22, v22, v34
	v_add_f32_e32 v32, 1.0, v32
	v_cndmask_b32_e64 v34, 0, 32, vcc
	v_ldexp_f32 v33, v33, v34
	v_log_f32_e32 v33, v33
	v_min_f32_e32 v20, 0, v20
	v_pk_mul_f32 v[24:25], v[24:25], v[16:17]
	v_pk_mul_f32 v[26:27], v[26:27], v[18:19]
	v_mul_f32_e32 v34, 0x3f317217, v33
	v_fma_f32 v34, v33, s76, -v34
	v_fmac_f32_e32 v34, 0x3377d1cf, v33
	v_fmac_f32_e32 v34, 0x3f317217, v33
	v_cmp_lt_f32_e64 s[38:39], |v33|, s77
	s_mov_b32 s4, 0xf800000
	v_add_f32_e32 v23, -0.5, v23
	v_cndmask_b32_e64 v33, v33, v34, s[38:39]
	v_cndmask_b32_e32 v34, 0, v171, vcc
	v_sub_f32_e32 v33, v33, v34
	v_sub_f32_e32 v21, v21, v33
	v_cmp_gt_f32_e32 vcc, s5, v32
	v_add_f32_e32 v21, -0.5, v21
	v_mul_f32_e32 v21, 0x3fb8aa3b, v21
	v_cndmask_b32_e64 v33, 0, 32, vcc
	v_ldexp_f32 v32, v32, v33
	v_exp_f32_e32 v21, v21
	v_log_f32_e32 v32, v32
	v_add_f32_e32 v22, -0.5, v22
	v_mul_f32_e32 v29, 0xbfb8aa3b, v29
	v_mul_f32_e32 v34, 0xbfb8aa3b, v21
	v_mul_f32_e32 v21, 0x3f317217, v32
	v_fma_f32 v21, v32, s76, -v21
	v_fmac_f32_e32 v21, 0x3377d1cf, v32
	v_fmac_f32_e32 v21, 0x3f317217, v32
	v_cmp_lt_f32_e64 s[38:39], |v32|, s77
	v_mul_f32_e32 v28, 0xbfb8aa3b, v28
	v_mul_f32_e32 v23, 0x3fb8aa3b, v23
	v_cndmask_b32_e64 v21, v32, v21, s[38:39]
	v_cndmask_b32_e32 v32, 0, v171, vcc
	v_sub_f32_e32 v21, v21, v32
	v_sub_f32_e32 v35, v20, v21
	v_pk_mul_f32 v[20:21], v[24:25], v[24:25]
	v_pk_mul_f32 v[32:33], v[26:27], v[26:27]
	v_add_f32_e32 v20, v20, v21
	v_add_f32_e32 v20, v20, v32
	v_add_f32_e32 v20, v20, v33
	v_add_f32_e32 v32, -0.5, v35
	v_mul_f32_e32 v32, 0x3fb8aa3b, v32
	v_add_f32_dpp v20, v20, v20 row_ror:8 row_mask:0xf bank_mask:0xf bound_ctrl:1
	v_exp_f32_e32 v32, v32
	v_mul_f32_e32 v22, 0x3fb8aa3b, v22
	v_add_f32_dpp v20, v20, v20 row_ror:4 row_mask:0xf bank_mask:0xf bound_ctrl:1
	v_exp_f32_e32 v29, v29
	v_exp_f32_e32 v23, v23
	v_add_f32_dpp v20, v20, v20 row_ror:2 row_mask:0xf bank_mask:0xf bound_ctrl:1
	v_exp_f32_e32 v28, v28
	v_exp_f32_e32 v22, v22
	v_add_f32_dpp v20, v20, v20 row_ror:1 row_mask:0xf bank_mask:0xf bound_ctrl:1
	v_mul_f32_e32 v21, 0x4f800000, v20
	v_cmp_gt_f32_e32 vcc, s4, v20
	v_mul_f32_e32 v23, 0xbfb8aa3b, v23
	v_mul_f32_e32 v22, 0xbfb8aa3b, v22
	v_cndmask_b32_e32 v20, v20, v21, vcc
	v_sqrt_f32_e32 v21, v20
	v_pk_add_f32 v[28:29], v[28:29], 1.0 op_sel_hi:[1,0]
	v_exp_f32_e32 v23, v23
	v_exp_f32_e32 v22, v22
	v_add_u32_e32 v33, -1, v21
	v_fma_f32 v35, -v33, v21, v20
	v_cmp_ge_f32_e64 s[38:39], 0, v35
	v_add_u32_e32 v35, 1, v21
	v_lshl_or_b32 v47, v42, 8, v46
	v_cndmask_b32_e64 v33, v21, v33, s[38:39]
	v_fma_f32 v21, -v35, v21, v20
	v_cmp_lt_f32_e64 s[38:39], 0, v21
	v_add_f32_e32 v31, v31, v39
	v_add_f32_e32 v30, v30, v38
	v_cndmask_b32_e64 v21, v33, v35, s[38:39]
	v_mul_f32_e32 v33, 0x37800000, v21
	v_cndmask_b32_e32 v21, v21, v33, vcc
	v_cmp_class_f32_e32 vcc, v20, v160
	v_mul_f32_e32 v31, 0xbfb8aa3b, v31
	v_mul_f32_e32 v30, 0xbfb8aa3b, v30
	v_cndmask_b32_e32 v20, v21, v20, vcc
	v_max_f32_e32 v33, 0x2b8cbccc, v20
	v_div_scale_f32 v35, s[22:23], v33, v33, 1.0
	v_rcp_f32_e32 v36, v35
	v_mul_f32_e32 v20, 0xbfb8aa3b, v32
	v_exp_f32_e32 v21, v34
	v_exp_f32_e32 v20, v20
	v_fma_f32 v32, -v35, v36, 1.0
	v_fmac_f32_e32 v36, v32, v36
	v_div_scale_f32 v32, vcc, 1.0, v33, 1.0
	v_mul_f32_e32 v34, v32, v36
	v_fma_f32 v37, -v35, v34, v32
	v_fmac_f32_e32 v34, v37, v36
	v_fma_f32 v32, -v35, v34, v32
	v_div_fmas_f32 v32, v32, v36, v34
	v_div_fixup_f32 v32, v32, v33, 1.0
	v_pk_mul_f32 v[24:25], v[24:25], v[32:33] op_sel_hi:[1,0]
	v_pk_mul_f32 v[26:27], v[26:27], v[32:33] op_sel_hi:[1,0]
	v_div_scale_f32 v32, s[22:23], v29, v29, 1.0
	v_rcp_f32_e32 v33, v32
	ds_write_b128 v47, v[20:23]
	v_xor_b32_e32 v21, 0x80000000, v25
	v_xor_b32_e32 v20, 0x80000000, v24
	v_xor_b32_e32 v23, 0x80000000, v27
	v_xor_b32_e32 v22, 0x80000000, v26
	ds_write_b128 v47, v[20:23] offset:2048
	v_fma_f32 v20, -v32, v33, 1.0
	v_fmac_f32_e32 v33, v20, v33
	v_div_scale_f32 v20, vcc, 1.0, v29, 1.0
	v_mul_f32_e32 v21, v20, v33
	v_fma_f32 v22, -v32, v21, v20
	v_fmac_f32_e32 v21, v22, v33
	v_div_scale_f32 v22, s[22:23], v28, v28, 1.0
	v_fma_f32 v20, -v32, v21, v20
	v_rcp_f32_e32 v32, v22
	v_div_fmas_f32 v20, v20, v33, v21
	v_div_fixup_f32 v29, v20, v29, 1.0
	v_exp_f32_e32 v31, v31
	v_fma_f32 v20, -v22, v32, 1.0
	v_exp_f32_e32 v30, v30
	v_fmac_f32_e32 v32, v20, v32
	v_div_scale_f32 v20, vcc, 1.0, v28, 1.0
	v_mul_f32_e32 v21, v20, v32
	v_fma_f32 v23, -v22, v21, v20
	v_fmac_f32_e32 v21, v23, v32
	v_fma_f32 v20, -v22, v21, v20
	v_pk_add_f32 v[22:23], v[30:31], 1.0 op_sel_hi:[1,0]
	v_div_fmas_f32 v20, v20, v32, v21
	v_div_scale_f32 v30, s[22:23], v23, v23, 1.0
	v_rcp_f32_e32 v31, v30
	v_div_fixup_f32 v28, v20, v28, 1.0
	v_pk_mul_f32 v[20:21], v[28:29], v[24:25]
	v_fma_f32 v24, -v30, v31, 1.0
	v_fmac_f32_e32 v31, v24, v31
	v_div_scale_f32 v24, vcc, 1.0, v23, 1.0
	v_mul_f32_e32 v25, v24, v31
	v_fma_f32 v32, -v30, v25, v24
	v_fmac_f32_e32 v25, v32, v31
	v_fma_f32 v24, -v30, v25, v24
	v_div_scale_f32 v30, s[22:23], v22, v22, 1.0
	v_rcp_f32_e32 v32, v30
	v_div_fmas_f32 v24, v24, v31, v25
	v_div_fixup_f32 v25, v24, v23, 1.0
	v_fma_f32 v23, -v30, v32, 1.0
	v_fmac_f32_e32 v32, v23, v32
	v_div_scale_f32 v23, vcc, 1.0, v22, 1.0
	v_mul_f32_e32 v24, v23, v32
	v_fma_f32 v31, -v30, v24, v23
	v_fmac_f32_e32 v24, v31, v32
	v_fma_f32 v23, -v30, v24, v23
	v_div_fmas_f32 v23, v23, v32, v24
	v_div_fixup_f32 v24, v23, v22, 1.0
	v_pk_mul_f32 v[22:23], v[24:25], v[26:27]
	ds_write_b128 v47, v[20:23] offset:4096
	v_pk_add_f32 v[20:21], v[28:29], -1.0 op_sel_hi:[1,0]
	v_pk_fma_f32 v[8:9], v[8:9], v[20:21], 1.0 op_sel_hi:[1,1,0]
	v_pk_mul_f32 v[8:9], v[16:17], v[8:9]
	v_pk_add_f32 v[16:17], v[24:25], -1.0 op_sel_hi:[1,0]
	s_nop 0
	v_pk_fma_f32 v[10:11], v[10:11], v[16:17], 1.0 op_sel_hi:[1,1,0]
	s_nop 0
	v_pk_mul_f32 v[10:11], v[18:19], v[10:11]
	ds_write_b128 v47, v[8:11] offset:6144
	ds_write_b128 v47, v[12:15] offset:8192
.LBB0_501:
	s_or_b64 exec, exec, s[8:9]
	v_lshlrev_b32_e32 v47, 2, v41
	s_waitcnt vmcnt(0)
	ds_write_b32 v47, v43 offset:10240
	s_waitcnt lgkmcnt(0)
	s_barrier
	v_lshlrev_b32_e32 v49, 2, v42
	v_cmp_eq_u32_e32 vcc, 0, v40
	ds_read_b128 v[16:19], v46
	ds_read_b128 v[12:15], v46 offset:256
	ds_read_b128 v[24:27], v46 offset:2048
	ds_read_b128 v[36:39], v46 offset:2304
	ds_read_b128 v[32:35], v46 offset:4096
	ds_read_b128 v[20:23], v46 offset:4352
	ds_read_b128 v[40:43], v46 offset:6144
	ds_read_b128 v[28:31], v46 offset:6400
	ds_read_b128 v[62:65], v46 offset:8192
	ds_read_b128 v[8:11], v46 offset:8448
	s_waitcnt lgkmcnt(7)
	v_mul_f32 v52, v4, v24
	v_mul_f32 v24, v0, v24
	v_mul_f32 v53, v5, v25
	v_mul_f32 v25, v1, v25
	v_add_u32_e32 v56, 0x2800, v49
	v_fma_f32 v52, v6, v26, v52
	v_fma_f32 v24, v2, v26, v24
	v_fma_f32 v26, v7, v27, v53
	v_fma_f32 v25, v3, v27, v25
	ds_read2_b32 v[54:55], v56 offset0:32 offset1:48
	v_add_f32_e32 v26, v52, v26
	v_add_f32_e32 v27, v24, v25
	ds_read2_b32 v[24:25], v56 offset1:16
	v_add_f32_dpp v26, v26, v26 row_ror:8 row_mask:0xf bank_mask:0xf bound_ctrl:1
	v_add_f32_dpp v27, v27, v27 row_ror:8 row_mask:0xf bank_mask:0xf bound_ctrl:1
	s_waitcnt lgkmcnt(0)
	v_mul_f32 v52, v24, v40
	v_add_u32_e32 v49, 0x5800, v49
	v_add_f32_dpp v26, v26, v26 row_ror:4 row_mask:0xf bank_mask:0xf bound_ctrl:1
	v_add_f32_dpp v27, v27, v27 row_ror:4 row_mask:0xf bank_mask:0xf bound_ctrl:1
	s_nop 0
	v_add_f32_dpp v26, v26, v26 row_ror:2 row_mask:0xf bank_mask:0xf bound_ctrl:1
	v_add_f32_dpp v27, v27, v27 row_ror:2 row_mask:0xf bank_mask:0xf bound_ctrl:1
	s_nop 0
	v_add_f32_dpp v26, v26, v26 row_ror:1 row_mask:0xf bank_mask:0xf bound_ctrl:1
	v_fma_f32 v52, v26, v32, v52
	v_add_f32_dpp v27, v27, v27 row_ror:1 row_mask:0xf bank_mask:0xf bound_ctrl:1
	v_fma_f32 v57, v4, v16, v52
	v_mul_f32 v4, v25, v40
	v_fma_f32 v4, v27, v32, v4
	v_fma_f32 v4, v0, v16, v4
	v_mul_f32 v0, v24, v41
	v_fma_f32 v0, v26, v33, v0
	v_fma_f32 v5, v5, v17, v0
	v_mul_f32 v0, v25, v41
	v_fma_f32 v0, v27, v33, v0
	v_fma_f32 v58, v1, v17, v0
	v_mul_f32 v0, v24, v42
	v_mul_f32 v1, v4, v62
	v_fma_f32 v0, v26, v34, v0
	v_fma_f32 v6, v6, v18, v0
	v_mul_f32 v0, v25, v42
	v_fma_f32 v0, v27, v34, v0
	v_fma_f32 v59, v2, v18, v0
	v_mul_f32 v0, v24, v43
	v_mul_f32 v2, v5, v63
	v_fma_f32 v0, v26, v35, v0
	v_fma_f32 v1, v59, v64, v1
	v_fma_f32 v7, v7, v19, v0
	v_mul_f32 v0, v25, v43
	v_fma_f32 v0, v27, v35, v0
	v_fma_f32 v2, v7, v65, v2
	v_fma_f32 v60, v3, v19, v0
	v_mul_f32 v0, v57, v62
	v_mul_f32 v3, v58, v63
	v_fma_f32 v0, v6, v64, v0
	v_fma_f32 v3, v60, v65, v3
	v_add_f32_e32 v0, v0, v2
	v_add_f32_e32 v2, v1, v3
	v_mov_b32_e32 v1, v140
	v_add_f32_dpp v0, v0, v0 row_ror:8 row_mask:0xf bank_mask:0xf bound_ctrl:1
	v_add_f32_dpp v2, v2, v2 row_ror:8 row_mask:0xf bank_mask:0xf bound_ctrl:1
	v_mov_b32_e32 v3, v140
	v_add_f32_dpp v0, v0, v0 row_ror:4 row_mask:0xf bank_mask:0xf bound_ctrl:1
	v_add_f32_dpp v2, v2, v2 row_ror:4 row_mask:0xf bank_mask:0xf bound_ctrl:1
	s_nop 0
	v_add_f32_dpp v0, v0, v0 row_ror:2 row_mask:0xf bank_mask:0xf bound_ctrl:1
	v_add_f32_dpp v2, v2, v2 row_ror:2 row_mask:0xf bank_mask:0xf bound_ctrl:1
	s_nop 0
	v_mov_b32_dpp v1, v0 row_ror:1 row_mask:0xf bank_mask:0xf
	v_mov_b32_dpp v3, v2 row_ror:1 row_mask:0xf bank_mask:0xf
	s_and_saveexec_b64 s[8:9], vcc
	v_readlane_b32 s50, v219, 56
	s_movk_i32 s51, 0x2000
	v_add_f32_e32 v2, v2, v3
	v_add_f32_e32 v0, v0, v1
	ds_write2_b32 v49, v0, v2 offset1:16
	s_or_b64 exec, exec, s[8:9]
	v_mul_f32 v61, v57, v36
	v_mul_f32 v36, v4, v36
	v_mul_f32 v62, v5, v37
	v_mul_f32 v37, v58, v37
	ds_read_b128 v[16:19], v46 offset:512
	ds_read_b128 v[40:43], v46 offset:2560
	ds_read_b128 v[24:27], v46 offset:4608
	ds_read_b128 v[32:35], v46 offset:6656
	ds_read_b128 v[0:3], v46 offset:8704
	ds_read2_b32 v[52:53], v56 offset0:64 offset1:80
	v_fma_f32 v61, v6, v38, v61
	v_fma_f32 v36, v59, v38, v36
	v_fma_f32 v38, v7, v39, v62
	v_fma_f32 v37, v60, v39, v37
	v_add_f32_e32 v38, v61, v38
	v_add_f32_e32 v36, v36, v37
	s_nop 0
	v_add_f32_dpp v37, v38, v38 row_ror:8 row_mask:0xf bank_mask:0xf bound_ctrl:1
	v_add_f32_dpp v36, v36, v36 row_ror:8 row_mask:0xf bank_mask:0xf bound_ctrl:1
	v_mul_f32 v38, v54, v28
	v_mul_f32 v28, v55, v28
	v_add_f32_dpp v37, v37, v37 row_ror:4 row_mask:0xf bank_mask:0xf bound_ctrl:1
	v_add_f32_dpp v36, v36, v36 row_ror:4 row_mask:0xf bank_mask:0xf bound_ctrl:1
	s_nop 0
	v_add_f32_dpp v37, v37, v37 row_ror:2 row_mask:0xf bank_mask:0xf bound_ctrl:1
	v_add_f32_dpp v36, v36, v36 row_ror:2 row_mask:0xf bank_mask:0xf bound_ctrl:1
	s_nop 0
	v_add_f32_dpp v37, v37, v37 row_ror:1 row_mask:0xf bank_mask:0xf bound_ctrl:1
	v_add_f32_dpp v36, v36, v36 row_ror:1 row_mask:0xf bank_mask:0xf bound_ctrl:1
	v_fma_f32 v38, v37, v20, v38
	v_fma_f32 v20, v36, v20, v28
	v_fma_f32 v57, v57, v12, v38
	v_fma_f32 v12, v4, v12, v20
	v_mul_f32 v4, v54, v29
	v_fma_f32 v4, v37, v21, v4
	v_fma_f32 v61, v5, v13, v4
	v_mul_f32 v4, v55, v29
	v_mul_f32 v5, v12, v8
	v_fma_f32 v4, v36, v21, v4
	v_fma_f32 v13, v58, v13, v4
	v_mul_f32 v4, v54, v30
	v_fma_f32 v4, v37, v22, v4
	v_fma_f32 v58, v6, v14, v4
	v_mul_f32 v4, v55, v30
	v_mul_f32 v6, v61, v9
	v_fma_f32 v4, v36, v22, v4
	v_fma_f32 v14, v59, v14, v4
	v_mul_f32 v4, v54, v31
	v_fma_f32 v4, v37, v23, v4
	v_fma_f32 v5, v14, v10, v5
	v_fma_f32 v59, v7, v15, v4
	v_mul_f32 v4, v55, v31
	v_mul_f32 v7, v13, v9
	v_fma_f32 v4, v36, v23, v4
	v_fma_f32 v6, v59, v11, v6
	v_fma_f32 v15, v60, v15, v4
	v_mul_f32 v4, v57, v8
	v_fma_f32 v4, v58, v10, v4
	v_fma_f32 v7, v15, v11, v7
	v_add_f32_e32 v4, v4, v6
	v_add_f32_e32 v6, v5, v7
	v_mov_b32_e32 v5, v140
	v_add_f32_dpp v4, v4, v4 row_ror:8 row_mask:0xf bank_mask:0xf bound_ctrl:1
	v_add_f32_dpp v6, v6, v6 row_ror:8 row_mask:0xf bank_mask:0xf bound_ctrl:1
	v_mov_b32_e32 v7, v140
	v_add_f32_dpp v4, v4, v4 row_ror:4 row_mask:0xf bank_mask:0xf bound_ctrl:1
	v_add_f32_dpp v6, v6, v6 row_ror:4 row_mask:0xf bank_mask:0xf bound_ctrl:1
	s_nop 0
	v_add_f32_dpp v4, v4, v4 row_ror:2 row_mask:0xf bank_mask:0xf bound_ctrl:1
	v_add_f32_dpp v6, v6, v6 row_ror:2 row_mask:0xf bank_mask:0xf bound_ctrl:1
	s_nop 0
	v_mov_b32_dpp v5, v4 row_ror:1 row_mask:0xf bank_mask:0xf
	v_mov_b32_dpp v7, v6 row_ror:1 row_mask:0xf bank_mask:0xf
	s_and_saveexec_b64 s[8:9], vcc
	v_add_f32_e32 v6, v6, v7
	v_add_f32_e32 v4, v4, v5
	ds_write2_b32 v49, v4, v6 offset0:32 offset1:48
	s_or_b64 exec, exec, s[8:9]
	s_waitcnt lgkmcnt(4)
	v_mul_f32 v60, v57, v40
	v_mul_f32 v40, v12, v40
	v_mul_f32 v62, v61, v41
	v_mul_f32 v41, v13, v41
	ds_read_b128 v[8:11], v46 offset:768
	ds_read_b128 v[36:39], v46 offset:2816
	ds_read_b128 v[20:23], v46 offset:4864
	ds_read_b128 v[28:31], v46 offset:6912
	ds_read_b128 v[4:7], v46 offset:8960
	ds_read2_b32 v[54:55], v56 offset0:96 offset1:112
	v_fma_f32 v60, v58, v42, v60
	v_fma_f32 v40, v14, v42, v40
	v_fma_f32 v42, v59, v43, v62
	v_fma_f32 v41, v15, v43, v41
	v_add_f32_e32 v42, v60, v42
	v_add_f32_e32 v40, v40, v41
	s_nop 0
	v_add_f32_dpp v41, v42, v42 row_ror:8 row_mask:0xf bank_mask:0xf bound_ctrl:1
	v_add_f32_dpp v40, v40, v40 row_ror:8 row_mask:0xf bank_mask:0xf bound_ctrl:1
	s_waitcnt lgkmcnt(6)
	v_mul_f32 v42, v52, v32
	v_mul_f32 v32, v53, v32
	v_add_f32_dpp v41, v41, v41 row_ror:4 row_mask:0xf bank_mask:0xf bound_ctrl:1
	v_add_f32_dpp v40, v40, v40 row_ror:4 row_mask:0xf bank_mask:0xf bound_ctrl:1
	s_nop 0
	v_add_f32_dpp v41, v41, v41 row_ror:2 row_mask:0xf bank_mask:0xf bound_ctrl:1
	v_add_f32_dpp v40, v40, v40 row_ror:2 row_mask:0xf bank_mask:0xf bound_ctrl:1
	s_nop 0
	v_add_f32_dpp v41, v41, v41 row_ror:1 row_mask:0xf bank_mask:0xf bound_ctrl:1
	v_add_f32_dpp v40, v40, v40 row_ror:1 row_mask:0xf bank_mask:0xf bound_ctrl:1
	v_fma_f32 v42, v41, v24, v42
	v_fma_f32 v24, v40, v24, v32
	v_fma_f32 v43, v12, v16, v24
	v_mul_f32 v12, v52, v33
	v_fma_f32 v42, v57, v16, v42
	v_fma_f32 v12, v41, v25, v12
	v_fma_f32 v57, v61, v17, v12
	v_mul_f32 v12, v53, v33
	v_fma_f32 v12, v40, v25, v12
	v_fma_f32 v60, v13, v17, v12
	v_mul_f32 v12, v52, v34
	v_mul_f32 v13, v57, v1
	v_fma_f32 v12, v41, v26, v12
	v_mul_f32 v1, v60, v1
	v_fma_f32 v58, v58, v18, v12
	v_mul_f32 v12, v53, v34
	v_fma_f32 v12, v40, v26, v12
	v_fma_f32 v61, v14, v18, v12
	v_mul_f32 v12, v52, v35
	v_fma_f32 v12, v41, v27, v12
	v_fma_f32 v52, v59, v19, v12
	v_mul_f32 v12, v53, v35
	v_fma_f32 v12, v40, v27, v12
	v_fma_f32 v53, v15, v19, v12
	v_mul_f32 v12, v42, v0
	v_mul_f32 v0, v43, v0
	v_fma_f32 v12, v58, v2, v12
	v_fma_f32 v0, v61, v2, v0
	v_fma_f32 v2, v52, v3, v13
	v_fma_f32 v1, v53, v3, v1
	v_add_f32_e32 v2, v12, v2
	v_add_f32_e32 v3, v0, v1
	v_mov_b32_e32 v1, v140
	v_add_f32_dpp v0, v2, v2 row_ror:8 row_mask:0xf bank_mask:0xf bound_ctrl:1
	v_add_f32_dpp v2, v3, v3 row_ror:8 row_mask:0xf bank_mask:0xf bound_ctrl:1
	v_mov_b32_e32 v3, v140
	v_add_f32_dpp v0, v0, v0 row_ror:4 row_mask:0xf bank_mask:0xf bound_ctrl:1
	v_add_f32_dpp v2, v2, v2 row_ror:4 row_mask:0xf bank_mask:0xf bound_ctrl:1
	s_nop 0
	v_add_f32_dpp v0, v0, v0 row_ror:2 row_mask:0xf bank_mask:0xf bound_ctrl:1
	v_add_f32_dpp v2, v2, v2 row_ror:2 row_mask:0xf bank_mask:0xf bound_ctrl:1
	s_nop 0
	v_mov_b32_dpp v1, v0 row_ror:1 row_mask:0xf bank_mask:0xf
	v_mov_b32_dpp v3, v2 row_ror:1 row_mask:0xf bank_mask:0xf
	s_and_saveexec_b64 s[8:9], vcc
	v_add_f32_e32 v2, v2, v3
	v_add_f32_e32 v0, v0, v1
	ds_write2_b32 v49, v0, v2 offset0:64 offset1:80
	s_or_b64 exec, exec, s[8:9]
	s_waitcnt lgkmcnt(4)
	v_mul_f32 v59, v42, v36
	v_mul_f32 v36, v43, v36
	v_mul_f32 v62, v57, v37
	v_mul_f32 v37, v60, v37
	ds_read_b128 v[12:15], v46 offset:1024
	ds_read_b128 v[32:35], v46 offset:3072
	ds_read_b128 v[16:19], v46 offset:5120
	ds_read_b128 v[24:27], v46 offset:7168
	ds_read_b128 v[0:3], v46 offset:9216
	ds_read2_b32 v[40:41], v56 offset0:128 offset1:144
	v_fma_f32 v59, v58, v38, v59
	v_fma_f32 v36, v61, v38, v36
	v_fma_f32 v38, v52, v39, v62
	v_fma_f32 v37, v53, v39, v37
	v_add_f32_e32 v38, v59, v38
	v_add_f32_e32 v36, v36, v37
	s_nop 0
	v_add_f32_dpp v37, v38, v38 row_ror:8 row_mask:0xf bank_mask:0xf bound_ctrl:1
	v_add_f32_dpp v36, v36, v36 row_ror:8 row_mask:0xf bank_mask:0xf bound_ctrl:1
	s_waitcnt lgkmcnt(6)
	v_mul_f32 v38, v54, v28
	v_mul_f32 v28, v55, v28
	v_add_f32_dpp v37, v37, v37 row_ror:4 row_mask:0xf bank_mask:0xf bound_ctrl:1
	v_add_f32_dpp v36, v36, v36 row_ror:4 row_mask:0xf bank_mask:0xf bound_ctrl:1
	s_nop 0
	v_add_f32_dpp v37, v37, v37 row_ror:2 row_mask:0xf bank_mask:0xf bound_ctrl:1
	v_add_f32_dpp v36, v36, v36 row_ror:2 row_mask:0xf bank_mask:0xf bound_ctrl:1
	s_nop 0
	v_add_f32_dpp v37, v37, v37 row_ror:1 row_mask:0xf bank_mask:0xf bound_ctrl:1
	v_add_f32_dpp v36, v36, v36 row_ror:1 row_mask:0xf bank_mask:0xf bound_ctrl:1
	v_fma_f32 v38, v37, v20, v38
	v_fma_f32 v20, v36, v20, v28
	v_fma_f32 v59, v42, v8, v38
	v_fma_f32 v62, v43, v8, v20
	v_mul_f32 v8, v54, v29
	v_fma_f32 v8, v37, v21, v8
	v_fma_f32 v57, v57, v9, v8
	v_mul_f32 v8, v55, v29
	v_fma_f32 v8, v36, v21, v8
	v_fma_f32 v60, v60, v9, v8
	v_mul_f32 v8, v54, v30
	v_mul_f32 v9, v57, v5
	v_fma_f32 v8, v37, v22, v8
	v_mul_f32 v5, v60, v5
	v_fma_f32 v58, v58, v10, v8
	v_mul_f32 v8, v55, v30
	v_fma_f32 v8, v36, v22, v8
	v_fma_f32 v61, v61, v10, v8
	v_mul_f32 v8, v54, v31
	v_fma_f32 v8, v37, v23, v8
	v_fma_f32 v52, v52, v11, v8
	v_mul_f32 v8, v55, v31
	v_fma_f32 v8, v36, v23, v8
	v_fma_f32 v53, v53, v11, v8
	v_mul_f32 v8, v59, v4
	v_mul_f32 v4, v62, v4
	v_fma_f32 v8, v58, v6, v8
	v_fma_f32 v4, v61, v6, v4
	v_fma_f32 v6, v52, v7, v9
	v_fma_f32 v5, v53, v7, v5
	v_add_f32_e32 v6, v8, v6
	v_add_f32_e32 v7, v4, v5
	v_mov_b32_e32 v5, v140
	v_add_f32_dpp v4, v6, v6 row_ror:8 row_mask:0xf bank_mask:0xf bound_ctrl:1
	v_add_f32_dpp v6, v7, v7 row_ror:8 row_mask:0xf bank_mask:0xf bound_ctrl:1
	v_mov_b32_e32 v7, v140
	v_add_f32_dpp v4, v4, v4 row_ror:4 row_mask:0xf bank_mask:0xf bound_ctrl:1
	v_add_f32_dpp v6, v6, v6 row_ror:4 row_mask:0xf bank_mask:0xf bound_ctrl:1
	s_nop 0
	v_add_f32_dpp v4, v4, v4 row_ror:2 row_mask:0xf bank_mask:0xf bound_ctrl:1
	v_add_f32_dpp v6, v6, v6 row_ror:2 row_mask:0xf bank_mask:0xf bound_ctrl:1
	s_nop 0
	v_mov_b32_dpp v5, v4 row_ror:1 row_mask:0xf bank_mask:0xf
	v_mov_b32_dpp v7, v6 row_ror:1 row_mask:0xf bank_mask:0xf
	s_and_saveexec_b64 s[8:9], vcc
	v_add_f32_e32 v6, v6, v7
	v_add_f32_e32 v4, v4, v5
	ds_write2_b32 v49, v4, v6 offset0:96 offset1:112
	s_or_b64 exec, exec, s[8:9]
	s_waitcnt lgkmcnt(4)
	v_mul_f32 v54, v59, v32
	v_mul_f32 v32, v62, v32
	v_mul_f32 v55, v57, v33
	v_mul_f32 v33, v60, v33
	ds_read_b128 v[8:11], v46 offset:1280
	ds_read_b128 v[36:39], v46 offset:3328
	ds_read_b128 v[20:23], v46 offset:5376
	ds_read_b128 v[28:31], v46 offset:7424
	ds_read_b128 v[4:7], v46 offset:9472
	ds_read2_b32 v[42:43], v56 offset0:160 offset1:176
	v_fma_f32 v54, v58, v34, v54
	v_fma_f32 v32, v61, v34, v32
	v_fma_f32 v34, v52, v35, v55
	v_fma_f32 v33, v53, v35, v33
	v_add_f32_e32 v34, v54, v34
	v_add_f32_e32 v32, v32, v33
	s_nop 0
	v_add_f32_dpp v33, v34, v34 row_ror:8 row_mask:0xf bank_mask:0xf bound_ctrl:1
	v_add_f32_dpp v32, v32, v32 row_ror:8 row_mask:0xf bank_mask:0xf bound_ctrl:1
	s_waitcnt lgkmcnt(6)
	v_mul_f32 v34, v40, v24
	v_mul_f32 v24, v41, v24
	v_add_f32_dpp v33, v33, v33 row_ror:4 row_mask:0xf bank_mask:0xf bound_ctrl:1
	v_add_f32_dpp v32, v32, v32 row_ror:4 row_mask:0xf bank_mask:0xf bound_ctrl:1
	s_nop 0
	v_add_f32_dpp v33, v33, v33 row_ror:2 row_mask:0xf bank_mask:0xf bound_ctrl:1
	v_add_f32_dpp v32, v32, v32 row_ror:2 row_mask:0xf bank_mask:0xf bound_ctrl:1
	s_nop 0
	v_add_f32_dpp v33, v33, v33 row_ror:1 row_mask:0xf bank_mask:0xf bound_ctrl:1
	v_add_f32_dpp v32, v32, v32 row_ror:1 row_mask:0xf bank_mask:0xf bound_ctrl:1
	v_fma_f32 v34, v33, v16, v34
	v_fma_f32 v16, v32, v16, v24
	v_fma_f32 v54, v59, v12, v34
	v_fma_f32 v55, v62, v12, v16
	v_mul_f32 v12, v40, v25
	v_fma_f32 v12, v33, v17, v12
	v_fma_f32 v57, v57, v13, v12
	v_mul_f32 v12, v41, v25
	v_fma_f32 v12, v32, v17, v12
	v_fma_f32 v59, v60, v13, v12
	v_mul_f32 v12, v40, v26
	v_mul_f32 v13, v57, v1
	v_fma_f32 v12, v33, v18, v12
	v_mul_f32 v1, v59, v1
	v_fma_f32 v58, v58, v14, v12
	v_mul_f32 v12, v41, v26
	v_fma_f32 v12, v32, v18, v12
	v_fma_f32 v60, v61, v14, v12
	v_mul_f32 v12, v40, v27
	v_fma_f32 v12, v33, v19, v12
	v_fma_f32 v52, v52, v15, v12
	v_mul_f32 v12, v41, v27
	v_fma_f32 v12, v32, v19, v12
	v_fma_f32 v53, v53, v15, v12
	v_mul_f32 v12, v54, v0
	v_mul_f32 v0, v55, v0
	v_fma_f32 v12, v58, v2, v12
	v_fma_f32 v0, v60, v2, v0
	v_fma_f32 v2, v52, v3, v13
	v_fma_f32 v1, v53, v3, v1
	v_add_f32_e32 v2, v12, v2
	v_add_f32_e32 v3, v0, v1
	v_mov_b32_e32 v1, v140
	v_add_f32_dpp v0, v2, v2 row_ror:8 row_mask:0xf bank_mask:0xf bound_ctrl:1
	v_add_f32_dpp v2, v3, v3 row_ror:8 row_mask:0xf bank_mask:0xf bound_ctrl:1
	v_mov_b32_e32 v3, v140
	v_add_f32_dpp v0, v0, v0 row_ror:4 row_mask:0xf bank_mask:0xf bound_ctrl:1
	v_add_f32_dpp v2, v2, v2 row_ror:4 row_mask:0xf bank_mask:0xf bound_ctrl:1
	s_nop 0
	v_add_f32_dpp v0, v0, v0 row_ror:2 row_mask:0xf bank_mask:0xf bound_ctrl:1
	v_add_f32_dpp v2, v2, v2 row_ror:2 row_mask:0xf bank_mask:0xf bound_ctrl:1
	s_nop 0
	v_mov_b32_dpp v1, v0 row_ror:1 row_mask:0xf bank_mask:0xf
	v_mov_b32_dpp v3, v2 row_ror:1 row_mask:0xf bank_mask:0xf
	s_and_saveexec_b64 s[8:9], vcc
	v_add_f32_e32 v2, v2, v3
	v_add_f32_e32 v0, v0, v1
	ds_write2_b32 v49, v0, v2 offset0:128 offset1:144
	s_or_b64 exec, exec, s[8:9]
	s_waitcnt lgkmcnt(4)
	v_mul_f32 v61, v54, v36
	v_mul_f32 v36, v55, v36
	v_mul_f32 v62, v57, v37
	v_mul_f32 v37, v59, v37
	ds_read_b128 v[12:15], v46 offset:1536
	ds_read_b128 v[32:35], v46 offset:3584
	ds_read_b128 v[16:19], v46 offset:5632
	ds_read_b128 v[24:27], v46 offset:7680
	ds_read_b128 v[0:3], v46 offset:9728
	ds_read2_b32 v[40:41], v56 offset0:192 offset1:208
	v_fma_f32 v61, v58, v38, v61
	v_fma_f32 v36, v60, v38, v36
	v_fma_f32 v38, v52, v39, v62
	v_fma_f32 v37, v53, v39, v37
	v_add_f32_e32 v38, v61, v38
	v_add_f32_e32 v36, v36, v37
	s_nop 0
	v_add_f32_dpp v37, v38, v38 row_ror:8 row_mask:0xf bank_mask:0xf bound_ctrl:1
	v_add_f32_dpp v36, v36, v36 row_ror:8 row_mask:0xf bank_mask:0xf bound_ctrl:1
	s_waitcnt lgkmcnt(6)
	v_mul_f32 v38, v42, v28
	v_mul_f32 v28, v43, v28
	v_add_f32_dpp v37, v37, v37 row_ror:4 row_mask:0xf bank_mask:0xf bound_ctrl:1
	v_add_f32_dpp v36, v36, v36 row_ror:4 row_mask:0xf bank_mask:0xf bound_ctrl:1
	s_nop 0
	v_add_f32_dpp v37, v37, v37 row_ror:2 row_mask:0xf bank_mask:0xf bound_ctrl:1
	v_add_f32_dpp v36, v36, v36 row_ror:2 row_mask:0xf bank_mask:0xf bound_ctrl:1
	s_nop 0
	v_add_f32_dpp v37, v37, v37 row_ror:1 row_mask:0xf bank_mask:0xf bound_ctrl:1
	v_add_f32_dpp v36, v36, v36 row_ror:1 row_mask:0xf bank_mask:0xf bound_ctrl:1
	v_fma_f32 v38, v37, v20, v38
	v_fma_f32 v20, v36, v20, v28
	v_fma_f32 v54, v54, v8, v38
	v_fma_f32 v55, v55, v8, v20
	v_mul_f32 v8, v42, v29
	v_fma_f32 v8, v37, v21, v8
	v_fma_f32 v57, v57, v9, v8
	v_mul_f32 v8, v43, v29
	v_fma_f32 v8, v36, v21, v8
	v_fma_f32 v59, v59, v9, v8
	v_mul_f32 v8, v42, v30
	v_mul_f32 v9, v57, v5
	v_fma_f32 v8, v37, v22, v8
	v_mul_f32 v5, v59, v5
	v_fma_f32 v58, v58, v10, v8
	v_mul_f32 v8, v43, v30
	v_fma_f32 v8, v36, v22, v8
	v_fma_f32 v60, v60, v10, v8
	v_mul_f32 v8, v42, v31
	v_fma_f32 v8, v37, v23, v8
	v_fma_f32 v52, v52, v11, v8
	v_mul_f32 v8, v43, v31
	v_fma_f32 v8, v36, v23, v8
	v_fma_f32 v53, v53, v11, v8
	v_mul_f32 v8, v54, v4
	v_mul_f32 v4, v55, v4
	v_fma_f32 v8, v58, v6, v8
	v_fma_f32 v4, v60, v6, v4
	v_fma_f32 v6, v52, v7, v9
	v_fma_f32 v5, v53, v7, v5
	v_add_f32_e32 v6, v8, v6
	v_add_f32_e32 v7, v4, v5
	v_mov_b32_e32 v5, v140
	v_add_f32_dpp v4, v6, v6 row_ror:8 row_mask:0xf bank_mask:0xf bound_ctrl:1
	v_add_f32_dpp v6, v7, v7 row_ror:8 row_mask:0xf bank_mask:0xf bound_ctrl:1
	v_mov_b32_e32 v7, v140
	v_add_f32_dpp v4, v4, v4 row_ror:4 row_mask:0xf bank_mask:0xf bound_ctrl:1
	v_add_f32_dpp v6, v6, v6 row_ror:4 row_mask:0xf bank_mask:0xf bound_ctrl:1
	s_nop 0
	v_add_f32_dpp v4, v4, v4 row_ror:2 row_mask:0xf bank_mask:0xf bound_ctrl:1
	v_add_f32_dpp v6, v6, v6 row_ror:2 row_mask:0xf bank_mask:0xf bound_ctrl:1
	s_nop 0
	v_mov_b32_dpp v5, v4 row_ror:1 row_mask:0xf bank_mask:0xf
	v_mov_b32_dpp v7, v6 row_ror:1 row_mask:0xf bank_mask:0xf
	s_and_saveexec_b64 s[8:9], vcc
	v_add_f32_e32 v6, v6, v7
	v_add_f32_e32 v4, v4, v5
	ds_write2_b32 v49, v4, v6 offset0:160 offset1:176
	s_or_b64 exec, exec, s[8:9]
	ds_read_b128 v[8:11], v46 offset:1792
	ds_read_b128 v[36:39], v46 offset:3840
	ds_read_b128 v[20:23], v46 offset:5888
	ds_read_b128 v[28:31], v46 offset:7936
	ds_read_b128 v[4:7], v46 offset:9984
	ds_read2_b32 v[42:43], v56 offset0:224 offset1:240
	s_waitcnt lgkmcnt(10)
	v_mul_f32 v56, v54, v32
	v_mul_f32 v32, v55, v32
	v_mul_f32 v61, v57, v33
	v_mul_f32 v33, v59, v33
	v_fma_f32 v56, v58, v34, v56
	v_fma_f32 v32, v60, v34, v32
	v_fma_f32 v34, v52, v35, v61
	v_fma_f32 v33, v53, v35, v33
	v_add_f32_e32 v32, v32, v33
	v_add_f32_e32 v34, v56, v34
	s_nop 0
	v_add_f32_dpp v32, v32, v32 row_ror:8 row_mask:0xf bank_mask:0xf bound_ctrl:1
	v_add_f32_dpp v33, v34, v34 row_ror:8 row_mask:0xf bank_mask:0xf bound_ctrl:1
	s_nop 0
	v_add_f32_dpp v32, v32, v32 row_ror:4 row_mask:0xf bank_mask:0xf bound_ctrl:1
	v_add_f32_dpp v33, v33, v33 row_ror:4 row_mask:0xf bank_mask:0xf bound_ctrl:1
	s_nop 0
	v_add_f32_dpp v32, v32, v32 row_ror:2 row_mask:0xf bank_mask:0xf bound_ctrl:1
	v_add_f32_dpp v33, v33, v33 row_ror:2 row_mask:0xf bank_mask:0xf bound_ctrl:1
	s_nop 0
	v_add_f32_dpp v34, v32, v32 row_ror:1 row_mask:0xf bank_mask:0xf bound_ctrl:1
	s_waitcnt lgkmcnt(6)
	v_mul_f32 v32, v40, v24
	v_add_f32_dpp v33, v33, v33 row_ror:1 row_mask:0xf bank_mask:0xf bound_ctrl:1
	v_fma_f32 v32, v33, v16, v32
	v_mul_f32 v24, v41, v24
	v_fma_f32 v16, v34, v16, v24
	v_fma_f32 v32, v54, v12, v32
	v_fma_f32 v16, v55, v12, v16
	v_mul_f32 v12, v40, v25
	v_fma_f32 v12, v33, v17, v12
	v_fma_f32 v24, v57, v13, v12
	v_mul_f32 v12, v41, v25
	v_fma_f32 v12, v34, v17, v12
	v_fma_f32 v17, v59, v13, v12
	v_mul_f32 v12, v40, v26
	v_mul_f32 v13, v24, v1
	v_fma_f32 v12, v33, v18, v12
	v_mul_f32 v1, v17, v1
	v_fma_f32 v25, v58, v14, v12
	v_mul_f32 v12, v41, v26
	v_fma_f32 v12, v34, v18, v12
	v_fma_f32 v18, v60, v14, v12
	v_mul_f32 v12, v40, v27
	v_fma_f32 v12, v33, v19, v12
	v_fma_f32 v26, v52, v15, v12
	v_mul_f32 v12, v41, v27
	v_fma_f32 v12, v34, v19, v12
	v_fma_f32 v19, v53, v15, v12
	v_mul_f32 v12, v32, v0
	v_mul_f32 v0, v16, v0
	v_fma_f32 v12, v25, v2, v12
	v_fma_f32 v0, v18, v2, v0
	v_fma_f32 v2, v26, v3, v13
	v_fma_f32 v1, v19, v3, v1
	v_add_f32_e32 v2, v12, v2
	v_add_f32_e32 v3, v0, v1
	v_mov_b32_e32 v1, v140
	v_add_f32_dpp v0, v2, v2 row_ror:8 row_mask:0xf bank_mask:0xf bound_ctrl:1
	v_add_f32_dpp v2, v3, v3 row_ror:8 row_mask:0xf bank_mask:0xf bound_ctrl:1
	v_mov_b32_e32 v3, v140
	v_add_f32_dpp v0, v0, v0 row_ror:4 row_mask:0xf bank_mask:0xf bound_ctrl:1
	v_add_f32_dpp v2, v2, v2 row_ror:4 row_mask:0xf bank_mask:0xf bound_ctrl:1
	s_nop 0
	v_add_f32_dpp v0, v0, v0 row_ror:2 row_mask:0xf bank_mask:0xf bound_ctrl:1
	v_add_f32_dpp v2, v2, v2 row_ror:2 row_mask:0xf bank_mask:0xf bound_ctrl:1
	s_nop 0
	v_mov_b32_dpp v1, v0 row_ror:1 row_mask:0xf bank_mask:0xf
	v_mov_b32_dpp v3, v2 row_ror:1 row_mask:0xf bank_mask:0xf
	s_and_saveexec_b64 s[8:9], vcc
	v_add_f32_e32 v2, v2, v3
	v_add_f32_e32 v0, v0, v1
	ds_write2_b32 v49, v0, v2 offset0:192 offset1:208
	s_or_b64 exec, exec, s[8:9]
	s_waitcnt lgkmcnt(4)
	v_mul_f32 v0, v32, v36
	v_mul_f32 v2, v24, v37
	v_mul_f32 v1, v16, v36
	v_mul_f32 v3, v17, v37
	v_fma_f32 v0, v25, v38, v0
	v_fma_f32 v2, v26, v39, v2
	v_fma_f32 v1, v18, v38, v1
	v_fma_f32 v3, v19, v39, v3
	v_add_f32_e32 v0, v0, v2
	v_add_f32_e32 v1, v1, v3
	s_nop 0
	v_add_f32_dpp v0, v0, v0 row_ror:8 row_mask:0xf bank_mask:0xf bound_ctrl:1
	s_waitcnt lgkmcnt(0)
	v_mul_f32 v2, v42, v30
	v_add_f32_dpp v0, v0, v0 row_ror:4 row_mask:0xf bank_mask:0xf bound_ctrl:1
	s_nop 1
	v_add_f32_dpp v0, v0, v0 row_ror:2 row_mask:0xf bank_mask:0xf bound_ctrl:1
	s_nop 1
	v_add_f32_dpp v3, v0, v0 row_ror:1 row_mask:0xf bank_mask:0xf bound_ctrl:1
	v_add_f32_dpp v0, v1, v1 row_ror:8 row_mask:0xf bank_mask:0xf bound_ctrl:1
	v_mul_f32 v1, v42, v29
	v_fma_f32 v2, v3, v22, v2
	v_fma_f32 v1, v3, v21, v1
	v_fma_f32 v14, v25, v10, v2
	v_add_f32_dpp v0, v0, v0 row_ror:4 row_mask:0xf bank_mask:0xf bound_ctrl:1
	v_fma_f32 v13, v24, v9, v1
	v_mul_f32 v1, v43, v29
	v_mul_f32 v2, v43, v30
	v_add_f32_dpp v0, v0, v0 row_ror:2 row_mask:0xf bank_mask:0xf bound_ctrl:1
	s_nop 1
	v_add_f32_dpp v27, v0, v0 row_ror:1 row_mask:0xf bank_mask:0xf bound_ctrl:1
	v_mul_f32 v0, v42, v28
	v_fma_f32 v1, v27, v21, v1
	v_fma_f32 v2, v27, v22, v2
	v_fma_f32 v0, v3, v20, v0
	v_fma_f32 v1, v17, v9, v1
	v_fma_f32 v2, v18, v10, v2
	v_mul_f32 v9, v13, v5
	v_fma_f32 v12, v32, v8, v0
	v_mul_f32 v0, v43, v28
	v_mul_f32 v5, v1, v5
	v_fma_f32 v0, v27, v20, v0
	v_fma_f32 v0, v16, v8, v0
	v_mul_f32 v8, v42, v31
	v_fma_f32 v3, v3, v23, v8
	v_mul_f32 v8, v12, v4
	v_mul_f32 v4, v0, v4
	v_fma_f32 v15, v26, v11, v3
	v_mul_f32 v3, v43, v31
	v_fma_f32 v8, v14, v6, v8
	v_fma_f32 v4, v2, v6, v4
	v_fma_f32 v3, v27, v23, v3
	v_fma_f32 v6, v15, v7, v9
	v_fma_f32 v3, v19, v11, v3
	v_add_f32_e32 v6, v8, v6
	v_fma_f32 v5, v3, v7, v5
	v_add_f32_e32 v7, v4, v5
	v_add_f32_dpp v4, v6, v6 row_ror:8 row_mask:0xf bank_mask:0xf bound_ctrl:1
	v_mov_b32_e32 v5, v140
	v_add_f32_dpp v6, v7, v7 row_ror:8 row_mask:0xf bank_mask:0xf bound_ctrl:1
	v_add_f32_dpp v4, v4, v4 row_ror:4 row_mask:0xf bank_mask:0xf bound_ctrl:1
	v_mov_b32_e32 v7, v140
	v_add_f32_dpp v6, v6, v6 row_ror:4 row_mask:0xf bank_mask:0xf bound_ctrl:1
	v_add_f32_dpp v4, v4, v4 row_ror:2 row_mask:0xf bank_mask:0xf bound_ctrl:1
	s_nop 0
	v_add_f32_dpp v6, v6, v6 row_ror:2 row_mask:0xf bank_mask:0xf bound_ctrl:1
	v_mov_b32_dpp v5, v4 row_ror:1 row_mask:0xf bank_mask:0xf
	s_nop 0
	v_mov_b32_dpp v7, v6 row_ror:1 row_mask:0xf bank_mask:0xf
	s_and_saveexec_b64 s[8:9], vcc
	s_cbranch_execz .LBB0_490
	v_add_f32_e32 v6, v6, v7
	v_add_f32_e32 v4, v4, v5
	ds_write2_b32 v49, v4, v6 offset0:224 offset1:240
	s_branch .LBB0_490

.LBB0_1112:
	s_or_b64 exec, exec, s[8:9]
	s_load_dwordx2 s[8:9], s[0:1], 0x158
	s_lshl_b32 s4, s70, 2
	s_or_b32 s22, s4, s71
	s_ashr_i32 s23, s22, 31
	v_mad_u32_u24 v0, v146, s92, v190
	s_lshl_b64 s[22:23], s[22:23], 18
	v_add_u32_e32 v1, 0x8c00, v0
	ds_write2_b32 v1, v88, v89 offset0:40 offset1:57
	ds_write2_b32 v1, v90, v100 offset0:74 offset1:91
	v_add_u32_e32 v1, 0x9c00, v0
	s_waitcnt lgkmcnt(0)
	s_add_u32 s4, s8, s22
	ds_write2_b32 v1, v91, v101 offset0:104 offset1:121
	ds_write2_b32 v1, v102, v104 offset0:138 offset1:155
	v_add_u32_e32 v1, 0xac00, v0
	s_addc_u32 s9, s9, s23
	s_lshl_b32 s8, s84, 2
	ds_write2_b32 v1, v103, v105 offset0:168 offset1:185
	ds_write2_b32 v1, v106, v109 offset0:202 offset1:219
	v_add_u32_e32 v1, 0xbc00, v0
	v_add_u32_e32 v0, 0xc000, v0
	s_add_u32 s8, s4, s8
	ds_write2_b32 v0, v108, v111 offset0:10 offset1:27
	s_addc_u32 s9, s9, 0
	v_ashrrev_i32_e32 v0, 2, v141
	v_and_b32_e32 v2, 48, v188
	v_mov_b32_e32 v3, v140
	s_movk_i32 s4, 0x44
	ds_write2_b32 v1, v107, v110 offset0:232 offset1:249
	v_lshl_add_u64 v[4:5], s[8:9], 0, v[2:3]
	v_mad_u64_u32 v[6:7], s[8:9], v0, s4, v[2:3]
	v_ashrrev_i32_e32 v1, 31, v0
	v_add_u32_e32 v2, 0x8ca0, v6
	v_add_u32_e32 v3, 0x8ca8, v6
	v_lshlrev_b64 v[0:1], 10, v[0:1]
	s_waitcnt lgkmcnt(0)
	s_barrier
	v_lshl_add_u64 v[4:5], v[4:5], 0, v[0:1]
	ds_read2_b32 v[0:1], v2 offset1:1
	ds_read2_b32 v[2:3], v3 offset1:1
	s_mov_b32 s4, 0x4800000
	v_add_co_u32_e32 v8, vcc, s4, v4
	s_mov_b32 s4, 0x4810000
	s_nop 0
	v_addc_co_u32_e32 v9, vcc, 0, v5, vcc
	s_waitcnt lgkmcnt(0)
	global_store_dwordx4 v[8:9], v[0:3], off
	s_nop 1
	v_add_co_u32_e32 v8, vcc, s4, v4
	v_add_u32_e32 v0, 0x9da0, v6
	v_add_u32_e32 v2, 0x9da8, v6
	ds_read2_b32 v[0:1], v0 offset1:1
	ds_read2_b32 v[2:3], v2 offset1:1
	v_addc_co_u32_e32 v9, vcc, 0, v5, vcc
	s_mov_b32 s4, 0x4820000
	s_mov_b64 s[8:9], 0
	s_waitcnt lgkmcnt(0)
	global_store_dwordx4 v[8:9], v[0:3], off
	s_nop 1
	v_add_co_u32_e32 v8, vcc, s4, v4
	v_add_u32_e32 v0, 0xaea0, v6
	v_add_u32_e32 v2, 0xaea8, v6
	ds_read2_b32 v[0:1], v0 offset1:1
	ds_read2_b32 v[2:3], v2 offset1:1
	v_addc_co_u32_e32 v9, vcc, 0, v5, vcc
	v_add_co_u32_e32 v4, vcc, 0x4830000, v4
	s_waitcnt lgkmcnt(0)
	global_store_dwordx4 v[8:9], v[0:3], off
	v_addc_co_u32_e32 v5, vcc, 0, v5, vcc
	s_nop 0
	v_add_u32_e32 v0, 0xbfa0, v6
	v_add_u32_e32 v2, 0xbfa8, v6
	ds_read2_b32 v[0:1], v0 offset1:1
	ds_read2_b32 v[2:3], v2 offset1:1
	s_waitcnt lgkmcnt(0)
	global_store_dwordx4 v[4:5], v[0:3], off

.LBB0_1118:
	s_or_b64 exec, exec, s[8:9]
	s_waitcnt lgkmcnt(0)
	s_barrier
	ds_read_b32 v0, v159
	s_mov_b64 s[8:9], -1
	s_waitcnt lgkmcnt(0)
	v_cmp_lt_i32_e32 vcc, s89, v0
	v_readfirstlane_b32 s22, v0
	s_cbranch_vccnz .LBB0_1113
	v_mov_b32_e32 v141, v143
	v_cmp_eq_u32_e64 s[38:39], 0, v141
	s_and_saveexec_b64 s[8:9], s[38:39]
	ds_write_b32 v140, v140 offset:35328
	s_or_b64 exec, exec, s[8:9]
	s_load_dwordx2 s[40:41], s[0:1], 0x98
	s_ashr_i32 s70, s22, 6
	s_bfe_u32 s71, s22, 0x20004
	s_lshl_b32 s15, s70, 11
	s_waitcnt vmcnt(3)
	v_ashrrev_i32_e32 v48, 6, v141
	s_lshl_b32 s8, s71, 2
	v_add_u32_e32 v144, s15, v48
	s_waitcnt vmcnt(10)
	v_add_u32_e32 v69, 0x100, v141
	v_mov_b32_e32 v0, s8
	v_ashrrev_i32_e32 v145, 31, v144
	s_waitcnt vmcnt(1)
	v_ashrrev_i32_e32 v56, 6, v69
	s_waitcnt lgkmcnt(0)
	global_load_dword v147, v0, s[40:41]
	global_load_dword v178, v0, s[40:41] offset:16
	v_lshlrev_b64 v[0:1], 13, v[144:145]
	v_lshlrev_b32_e32 v145, 2, v141
	v_add_u32_e32 v148, s15, v56
	v_lshl_add_u64 v[0:1], s[36:37], 0, v[0:1]
	s_lshl_b32 s94, s71, 10
	v_and_b32_e32 v2, 0xfc, v145
	v_ashrrev_i32_e32 v149, 31, v148
	v_lshl_add_u64 v[0:1], v[0:1], 0, s[94:95]
	v_lshlrev_b32_e32 v64, 2, v2
	v_mov_b32_e32 v65, v140
	v_lshlrev_b64 v[8:9], 13, v[148:149]
	v_lshl_add_u64 v[0:1], v[0:1], 0, v[64:65]
	v_lshl_add_u64 v[8:9], s[36:37], 0, v[8:9]
	v_add_co_u32_e32 v4, vcc, s86, v0
	v_lshl_add_u64 v[8:9], v[8:9], 0, s[94:95]
	s_nop 0
	v_addc_co_u32_e32 v5, vcc, 0, v1, vcc
	v_lshl_add_u64 v[8:9], v[8:9], 0, v[64:65]
	v_add_co_u32_e32 v12, vcc, 0x1000, v8
	global_load_dwordx4 v[0:3], v[0:1], off
	s_nop 0
	global_load_dwordx4 v[4:7], v[4:5], off
	v_addc_co_u32_e32 v13, vcc, 0, v9, vcc
	global_load_dwordx4 v[8:11], v[8:9], off
	s_nop 0
	global_load_dwordx4 v[12:15], v[12:13], off
	s_lshl_b32 s4, s22, 4
	s_and_b32 s84, s4, 0xf0
	s_movk_i32 s4, 0x7f
	v_ashrrev_i32_e32 v68, 4, v141
	v_and_b32_e32 v146, 15, v141
	v_cmp_lt_i32_e64 s[56:57], s4, v141
	s_movk_i32 s4, 0x80
	s_lshl_b32 s22, s71, 8
	v_cmp_gt_i32_e64 s[40:41], s4, v141
	v_mov_b32_e32 v182, 0
	v_add_u32_e32 v149, s15, v68
	v_lshlrev_b32_e32 v66, 2, v146
	s_waitcnt vmcnt(14)
	v_mov_b32_e32 v180, 0
	s_and_saveexec_b64 s[42:43], s[40:41]
	s_cbranch_execz .LBB0_1123
	v_mov_b64_e32 v[16:17], s[30:31]
	v_mad_i64_i32 v[16:17], s[44:45], v149, s25, v[16:17]
	s_lshl_b32 s94, s22, 2
	v_lshl_add_u64 v[16:17], v[16:17], 0, s[94:95]
	s_lshl_b32 s94, s84, 2
	v_lshl_add_u64 v[16:17], v[16:17], 0, s[94:95]
	v_mov_b32_e32 v67, v140
	v_lshl_add_u64 v[16:17], v[16:17], 0, v[66:67]
	v_add_co_u32_e32 v16, vcc, 0x2000, v16
	s_nop 1
	v_addc_co_u32_e32 v17, vcc, 0, v17, vcc
	global_load_dword v180, v[16:17], off

.LBB0_1156:
	s_or_b64 exec, exec, s[8:9]
	s_waitcnt lgkmcnt(0)
	s_barrier
	v_add_u32_e64 v196, s83, 0
	ds_read_b128 v[72:75], v194
	ds_read_b128 v[80:83], v194 offset:256
	ds_read_b128 v[112:115], v194 offset:8192
	ds_read_b128 v[132:135], v194 offset:8448
	ds_read2_b64 v[92:95], v196 offset0:32 offset1:40
	v_add_u32_e32 v198, 0x4000, v190
	ds_read2_b32 v[64:65], v198 offset1:16
	ds_read_b128 v[206:209], v194 offset:512
	ds_read_b128 v[210:213], v194 offset:768
	ds_read_b128 v[154:157], v194 offset:8704
	ds_read_b128 v[200:203], v194 offset:8960
	ds_read_b128 v[96:99], v194 offset:1024
	ds_read_b128 v[84:87], v194 offset:1280
	ds_read_b128 v[128:131], v194 offset:9216
	ds_read_b128 v[120:123], v194 offset:9472
	ds_read_b128 v[76:79], v194 offset:1536
	ds_read_b128 v[68:71], v194 offset:1792
	ds_read_b128 v[124:127], v194 offset:9728
	ds_read_b128 v[116:119], v194 offset:9984
	s_waitcnt lgkmcnt(12)
	v_mul_f32_e32 v64, v94, v64
	v_mul_f32 v66, v112, v64
	v_mul_f32 v67, v113, v64
	v_mul_f32 v94, v114, v64
	v_mul_f32 v112, v115, v64
	v_mul_f32 v113, v132, v64
	v_mul_f32 v114, v133, v64
	v_mul_f32 v115, v134, v64
	v_mul_f32 v132, v135, v64
	s_waitcnt lgkmcnt(9)
	v_mul_f32 v133, v154, v64
	v_mul_f32 v134, v155, v64
	v_mul_f32 v135, v156, v64
	v_mul_f32 v154, v157, v64
	s_waitcnt lgkmcnt(8)
	v_mul_f32 v214, v200, v64
	v_mul_f32 v215, v201, v64
	v_mul_f32 v216, v202, v64
	v_mul_f32 v64, v203, v64
	v_fma_f32 v205, v92, v88, v66
	v_fma_f32 v204, v92, v89, v67
	v_fma_f32 v203, v92, v90, v94
	v_fma_f32 v202, v92, v100, v112
	v_fma_f32 v155, v92, v91, v113
	v_fma_f32 v157, v92, v101, v114
	v_fma_f32 v199, v92, v102, v115
	v_fma_f32 v201, v92, v104, v132
	v_fma_f32 v200, v92, v103, v133
	v_fma_f32 v197, v92, v105, v134
	v_fma_f32 v156, v92, v106, v135
	v_fma_f32 v154, v92, v109, v154
	v_fma_f32 v135, v92, v107, v214
	v_fma_f32 v134, v92, v110, v215
	v_fma_f32 v94, v92, v108, v216
	v_fma_f32 v92, v92, v111, v64
	v_fma_f32 v64, v72, v205, v140
	v_fma_f32 v66, v73, v204, v140
	v_fma_f32 v67, v74, v203, v140
	v_fma_f32 v72, v75, v202, v140
	v_fma_f32 v64, v80, v155, v64
	v_fma_f32 v66, v81, v157, v66
	v_fma_f32 v67, v82, v199, v67
	v_fma_f32 v72, v83, v201, v72
	v_fma_f32 v64, v206, v200, v64
	v_fma_f32 v66, v207, v197, v66
	v_fma_f32 v67, v208, v156, v67
	v_fma_f32 v72, v209, v154, v72
	v_fma_f32 v64, v210, v135, v64
	v_fma_f32 v66, v211, v134, v66
	v_fma_f32 v67, v212, v94, v67
	v_fma_f32 v72, v213, v92, v72
	v_add_f32_e32 v64, v64, v66
	v_add_f32_e32 v66, v67, v72
	v_add_f32_e32 v64, v64, v66
	v_mov_b32_e32 v66, 0
	s_nop 0
	v_add_f32_dpp v64, v64, v64 row_ror:8 row_mask:0xf bank_mask:0xf bound_ctrl:1
	s_nop 1
	v_add_f32_dpp v64, v64, v64 row_ror:4 row_mask:0xf bank_mask:0xf bound_ctrl:1
	s_nop 1
	v_add_f32_dpp v64, v64, v64 row_ror:2 row_mask:0xf bank_mask:0xf bound_ctrl:1
	s_nop 1
	v_mov_b32_dpp v66, v64 row_ror:1 row_mask:0xf bank_mask:0xf
	s_and_saveexec_b64 s[8:9], s[44:45]
	v_add_f32_e32 v64, v64, v66
	ds_write_b32 v190, v64 offset:34048
	s_or_b64 exec, exec, s[8:9]
	v_mul_f32_e32 v206, v95, v65
	ds_read_b128 v[88:91], v194 offset:2048
	ds_read_b128 v[80:83], v194 offset:2304
	ds_read_b128 v[112:115], v194 offset:10240
	ds_read_b128 v[104:107], v194 offset:10496
	ds_read_b128 v[72:75], v194 offset:2560
	ds_read_b128 v[64:67], v194 offset:2816
	ds_read_b128 v[108:111], v194 offset:10752
	ds_read_b128 v[100:103], v194 offset:11008
	ds_read2_b32 v[132:133], v196 offset0:66 offset1:82
	ds_read_b32 v95, v190 offset:16512
	s_waitcnt lgkmcnt(14)
	v_mul_f32 v128, v128, v206
	v_mul_f32 v129, v129, v206
	v_mul_f32 v130, v130, v206
	v_mul_f32 v131, v131, v206
	v_mul_f32 v120, v120, v206
	v_mul_f32 v121, v121, v206
	v_mul_f32 v122, v122, v206
	v_mul_f32 v123, v123, v206
	s_waitcnt lgkmcnt(11)
	v_mul_f32 v124, v124, v206
	v_mul_f32 v125, v125, v206
	v_mul_f32 v126, v126, v206
	v_mul_f32 v127, v127, v206
	s_waitcnt lgkmcnt(10)
	v_mul_f32 v116, v116, v206
	v_mul_f32 v117, v117, v206
	v_mul_f32 v118, v118, v206
	v_mul_f32 v119, v119, v206
	v_fma_f32 v128, v93, v205, v128
	v_fma_f32 v129, v93, v204, v129
	v_fma_f32 v130, v93, v203, v130
	v_fma_f32 v131, v93, v202, v131
	v_fma_f32 v155, v93, v155, v120
	v_fma_f32 v157, v93, v157, v121
	v_fma_f32 v199, v93, v199, v122
	v_fma_f32 v201, v93, v201, v123
	v_fma_f32 v200, v93, v200, v124
	v_fma_f32 v197, v93, v197, v125
	v_fma_f32 v156, v93, v156, v126
	v_fma_f32 v154, v93, v154, v127
	v_fma_f32 v202, v93, v135, v116
	v_fma_f32 v203, v93, v134, v117
	v_fma_f32 v204, v93, v94, v118
	v_fma_f32 v205, v93, v92, v119
	v_fma_f32 v92, v96, v128, v140
	v_fma_f32 v93, v97, v129, v140
	v_fma_f32 v94, v98, v130, v140
	v_fma_f32 v96, v99, v131, v140
	v_fma_f32 v84, v84, v155, v92
	v_fma_f32 v85, v85, v157, v93
	v_fma_f32 v86, v86, v199, v94
	v_fma_f32 v87, v87, v201, v96
	v_fma_f32 v76, v76, v200, v84
	v_fma_f32 v77, v77, v197, v85
	v_fma_f32 v78, v78, v156, v86
	v_fma_f32 v79, v79, v154, v87
	v_fma_f32 v68, v68, v202, v76
	v_fma_f32 v69, v69, v203, v77
	v_fma_f32 v70, v70, v204, v78
	v_fma_f32 v71, v71, v205, v79
	v_add_f32_e32 v68, v68, v69
	v_add_f32_e32 v69, v70, v71
	v_add_f32_e32 v68, v68, v69
	v_mov_b32_e32 v69, 0
	s_nop 0
	v_add_f32_dpp v68, v68, v68 row_ror:8 row_mask:0xf bank_mask:0xf bound_ctrl:1
	s_nop 1
	v_add_f32_dpp v68, v68, v68 row_ror:4 row_mask:0xf bank_mask:0xf bound_ctrl:1
	s_nop 1
	v_add_f32_dpp v68, v68, v68 row_ror:2 row_mask:0xf bank_mask:0xf bound_ctrl:1
	s_nop 1
	v_mov_b32_dpp v69, v68 row_ror:1 row_mask:0xf bank_mask:0xf
	s_and_saveexec_b64 s[8:9], s[44:45]
	v_add_f32_e32 v68, v68, v69
	ds_write_b32 v190, v68 offset:34112
	s_or_b64 exec, exec, s[8:9]
	s_waitcnt lgkmcnt(0)
	v_mul_f32_e32 v206, v133, v95
	ds_read_b128 v[92:95], v194 offset:3072
	ds_read_b128 v[84:87], v194 offset:3328
	ds_read_b128 v[124:127], v194 offset:11264
	ds_read_b128 v[116:119], v194 offset:11520
	ds_read_b128 v[76:79], v194 offset:3584
	ds_read_b128 v[68:71], v194 offset:3840
	ds_read_b128 v[120:123], v194 offset:11776
	ds_read_b128 v[96:99], v194 offset:12032
	ds_read2_b32 v[134:135], v196 offset0:67 offset1:83
	ds_read_b32 v133, v190 offset:16576
	v_mul_f32 v112, v112, v206
	v_mul_f32 v113, v113, v206
	v_mul_f32 v114, v114, v206
	v_mul_f32 v115, v115, v206
	v_mul_f32 v104, v104, v206
	v_mul_f32 v105, v105, v206
	v_mul_f32 v108, v108, v206
	v_mul_f32 v109, v109, v206
	v_mul_f32 v100, v100, v206
	v_mul_f32 v101, v101, v206
	v_fma_f32 v112, v132, v128, v112
	v_fma_f32 v113, v132, v129, v113
	v_fma_f32 v155, v132, v155, v104
	v_fma_f32 v157, v132, v157, v105
	v_fma_f32 v200, v132, v200, v108
	v_fma_f32 v197, v132, v197, v109
	v_fma_f32 v202, v132, v202, v100
	v_fma_f32 v203, v132, v203, v101
	v_fma_f32 v88, v88, v112, v140
	v_fma_f32 v89, v89, v113, v140
	v_mul_f32 v106, v106, v206
	v_mul_f32 v107, v107, v206
	v_mul_f32 v110, v110, v206
	v_mul_f32 v111, v111, v206
	v_fma_f32 v80, v80, v155, v88
	v_fma_f32 v81, v81, v157, v89
	v_mul_f32 v102, v102, v206
	v_mul_f32 v103, v103, v206
	v_fma_f32 v114, v132, v130, v114
	v_fma_f32 v115, v132, v131, v115
	v_fma_f32 v72, v72, v200, v80
	v_fma_f32 v73, v73, v197, v81
	v_fma_f32 v199, v132, v199, v106
	v_fma_f32 v201, v132, v201, v107
	v_fma_f32 v156, v132, v156, v110
	v_fma_f32 v154, v132, v154, v111
	v_fma_f32 v64, v64, v202, v72
	v_fma_f32 v65, v65, v203, v73
	v_fma_f32 v204, v132, v204, v102
	v_fma_f32 v205, v132, v205, v103
	v_fma_f32 v90, v90, v114, v140
	v_fma_f32 v91, v91, v115, v140
	v_add_f32_e32 v64, v64, v65
	v_fma_f32 v82, v82, v199, v90
	v_fma_f32 v83, v83, v201, v91
	v_fma_f32 v74, v74, v156, v82
	v_fma_f32 v75, v75, v154, v83
	v_fma_f32 v66, v66, v204, v74
	v_fma_f32 v67, v67, v205, v75
	v_add_f32_e32 v65, v66, v67
	v_add_f32_e32 v64, v64, v65
	v_mov_b32_e32 v65, 0
	s_nop 0
	v_add_f32_dpp v64, v64, v64 row_ror:8 row_mask:0xf bank_mask:0xf bound_ctrl:1
	s_nop 1
	v_add_f32_dpp v64, v64, v64 row_ror:4 row_mask:0xf bank_mask:0xf bound_ctrl:1
	s_nop 1
	v_add_f32_dpp v64, v64, v64 row_ror:2 row_mask:0xf bank_mask:0xf bound_ctrl:1
	s_nop 1
	v_mov_b32_dpp v65, v64 row_ror:1 row_mask:0xf bank_mask:0xf
	s_and_saveexec_b64 s[8:9], s[44:45]
	v_add_f32_e32 v64, v64, v65
	ds_write_b32 v190, v64 offset:34176
	s_or_b64 exec, exec, s[8:9]
	s_waitcnt lgkmcnt(0)
	v_mul_f32_e32 v206, v135, v133
	ds_read_b128 v[88:91], v194 offset:4096
	ds_read_b128 v[80:83], v194 offset:4352
	ds_read_b128 v[128:131], v194 offset:12288
	ds_read_b128 v[104:107], v194 offset:12544
	ds_read_b128 v[72:75], v194 offset:4608
	ds_read_b128 v[64:67], v194 offset:4864
	ds_read_b128 v[108:111], v194 offset:12800
	ds_read_b128 v[100:103], v194 offset:13056
	ds_read2_b32 v[132:133], v196 offset0:68 offset1:84
	ds_read_b32 v135, v190 offset:16640
	v_mul_f32 v124, v124, v206
	v_mul_f32 v125, v125, v206
	v_mul_f32 v126, v126, v206
	v_mul_f32 v127, v127, v206
	v_mul_f32 v116, v116, v206
	v_mul_f32 v117, v117, v206
	v_mul_f32 v120, v120, v206
	v_mul_f32 v121, v121, v206
	v_mul_f32 v96, v96, v206
	v_mul_f32 v97, v97, v206
	v_fma_f32 v124, v134, v112, v124
	v_fma_f32 v125, v134, v113, v125
	v_fma_f32 v155, v134, v155, v116
	v_fma_f32 v157, v134, v157, v117
	v_fma_f32 v200, v134, v200, v120
	v_fma_f32 v197, v134, v197, v121
	v_fma_f32 v202, v134, v202, v96
	v_fma_f32 v203, v134, v203, v97
	v_fma_f32 v92, v92, v124, v140
	v_fma_f32 v93, v93, v125, v140
	v_mul_f32 v118, v118, v206
	v_mul_f32 v119, v119, v206
	v_mul_f32 v122, v122, v206
	v_mul_f32 v123, v123, v206
	v_fma_f32 v84, v84, v155, v92
	v_fma_f32 v85, v85, v157, v93
	v_mul_f32 v98, v98, v206
	v_mul_f32 v99, v99, v206
	v_fma_f32 v126, v134, v114, v126
	v_fma_f32 v127, v134, v115, v127
	v_fma_f32 v76, v76, v200, v84
	v_fma_f32 v77, v77, v197, v85
	v_fma_f32 v199, v134, v199, v118
	v_fma_f32 v201, v134, v201, v119
	v_fma_f32 v156, v134, v156, v122
	v_fma_f32 v154, v134, v154, v123
	v_fma_f32 v68, v68, v202, v76
	v_fma_f32 v69, v69, v203, v77
	v_fma_f32 v204, v134, v204, v98
	v_fma_f32 v205, v134, v205, v99
	v_fma_f32 v94, v94, v126, v140
	v_fma_f32 v95, v95, v127, v140
	v_add_f32_e32 v68, v68, v69
	v_fma_f32 v86, v86, v199, v94
	v_fma_f32 v87, v87, v201, v95
	v_fma_f32 v78, v78, v156, v86
	v_fma_f32 v79, v79, v154, v87
	v_fma_f32 v70, v70, v204, v78
	v_fma_f32 v71, v71, v205, v79
	v_add_f32_e32 v69, v70, v71
	v_add_f32_e32 v68, v68, v69
	v_mov_b32_e32 v69, 0
	s_nop 0
	v_add_f32_dpp v68, v68, v68 row_ror:8 row_mask:0xf bank_mask:0xf bound_ctrl:1
	s_nop 1
	v_add_f32_dpp v68, v68, v68 row_ror:4 row_mask:0xf bank_mask:0xf bound_ctrl:1
	s_nop 1
	v_add_f32_dpp v68, v68, v68 row_ror:2 row_mask:0xf bank_mask:0xf bound_ctrl:1
	s_nop 1
	v_mov_b32_dpp v69, v68 row_ror:1 row_mask:0xf bank_mask:0xf
	s_and_saveexec_b64 s[8:9], s[44:45]
	v_add_f32_e32 v68, v68, v69
	ds_write_b32 v190, v68 offset:34240
	s_or_b64 exec, exec, s[8:9]
	s_waitcnt lgkmcnt(0)
	v_mul_f32_e32 v133, v133, v135
	ds_read_b128 v[92:95], v194 offset:5120
	ds_read_b128 v[84:87], v194 offset:5376
	ds_read_b128 v[120:123], v194 offset:13312
	ds_read_b128 v[112:115], v194 offset:13568
	ds_read_b128 v[76:79], v194 offset:5632
	ds_read_b128 v[68:71], v194 offset:5888
	ds_read_b128 v[116:119], v194 offset:13824
	ds_read_b128 v[96:99], v194 offset:14080
	ds_read2_b32 v[134:135], v196 offset0:69 offset1:85
	ds_read_b32 v207, v190 offset:16704
	v_mul_f32 v128, v128, v133
	v_mul_f32 v129, v129, v133
	v_mul_f32 v206, v130, v133
	v_mul_f32 v208, v131, v133
	v_mul_f32 v104, v104, v133
	v_mul_f32 v105, v105, v133
	v_mul_f32 v108, v108, v133
	v_mul_f32 v109, v109, v133
	v_mul_f32 v100, v100, v133
	v_mul_f32 v101, v101, v133
	v_fma_f32 v130, v132, v124, v128
	v_fma_f32 v131, v132, v125, v129
	v_fma_f32 v155, v132, v155, v104
	v_fma_f32 v157, v132, v157, v105
	v_fma_f32 v200, v132, v200, v108
	v_fma_f32 v197, v132, v197, v109
	v_fma_f32 v202, v132, v202, v100
	v_fma_f32 v203, v132, v203, v101
	v_fma_f32 v88, v88, v130, v140
	v_fma_f32 v89, v89, v131, v140
	v_mul_f32 v106, v106, v133
	v_mul_f32 v107, v107, v133
	v_mul_f32 v110, v110, v133
	v_mul_f32 v111, v111, v133
	v_fma_f32 v80, v80, v155, v88
	v_fma_f32 v81, v81, v157, v89
	v_mul_f32 v102, v102, v133
	v_mul_f32 v103, v103, v133
	v_fma_f32 v133, v132, v126, v206
	v_fma_f32 v206, v132, v127, v208
	v_fma_f32 v72, v72, v200, v80
	v_fma_f32 v73, v73, v197, v81
	v_fma_f32 v199, v132, v199, v106
	v_fma_f32 v201, v132, v201, v107
	v_fma_f32 v156, v132, v156, v110
	v_fma_f32 v154, v132, v154, v111
	v_fma_f32 v64, v64, v202, v72
	v_fma_f32 v65, v65, v203, v73
	v_fma_f32 v204, v132, v204, v102
	v_fma_f32 v132, v132, v205, v103
	v_fma_f32 v90, v90, v133, v140
	v_fma_f32 v91, v91, v206, v140
	v_add_f32_e32 v64, v64, v65
	v_fma_f32 v82, v82, v199, v90
	v_fma_f32 v83, v83, v201, v91
	v_fma_f32 v74, v74, v156, v82
	v_fma_f32 v75, v75, v154, v83
	v_fma_f32 v66, v66, v204, v74
	v_fma_f32 v67, v67, v132, v75
	v_add_f32_e32 v65, v66, v67
	v_add_f32_e32 v64, v64, v65
	v_mov_b32_e32 v65, 0
	s_nop 0
	v_add_f32_dpp v64, v64, v64 row_ror:8 row_mask:0xf bank_mask:0xf bound_ctrl:1
	s_nop 1
	v_add_f32_dpp v64, v64, v64 row_ror:4 row_mask:0xf bank_mask:0xf bound_ctrl:1
	s_nop 1
	v_add_f32_dpp v64, v64, v64 row_ror:2 row_mask:0xf bank_mask:0xf bound_ctrl:1
	s_nop 1
	v_mov_b32_dpp v65, v64 row_ror:1 row_mask:0xf bank_mask:0xf
	s_and_saveexec_b64 s[8:9], s[44:45]
	v_add_f32_e32 v64, v64, v65
	ds_write_b32 v190, v64 offset:34304
	s_or_b64 exec, exec, s[8:9]
	s_waitcnt lgkmcnt(0)
	v_mul_f32_e32 v135, v135, v207
	ds_read_b128 v[88:91], v194 offset:6144
	ds_read_b128 v[80:83], v194 offset:6400
	ds_read_b128 v[124:127], v194 offset:14336
	ds_read_b128 v[104:107], v194 offset:14592
	ds_read_b128 v[72:75], v194 offset:6656
	ds_read_b128 v[64:67], v194 offset:6912
	ds_read_b128 v[108:111], v194 offset:14848
	ds_read_b128 v[100:103], v194 offset:15104
	ds_read2_b32 v[128:129], v196 offset0:70 offset1:86
	ds_read_b32 v207, v190 offset:16768
	v_mul_f32 v120, v120, v135
	v_mul_f32 v121, v121, v135
	v_mul_f32 v122, v122, v135
	v_mul_f32 v123, v123, v135
	v_mul_f32 v112, v112, v135
	v_mul_f32 v113, v113, v135
	v_mul_f32 v114, v114, v135
	v_mul_f32 v115, v115, v135
	v_mul_f32 v116, v116, v135
	v_mul_f32 v117, v117, v135
	v_mul_f32 v118, v118, v135
	v_mul_f32 v119, v119, v135
	v_mul_f32 v96, v96, v135
	v_mul_f32 v97, v97, v135
	v_mul_f32 v98, v98, v135
	v_mul_f32 v99, v99, v135
	v_fma_f32 v135, v134, v130, v120
	v_fma_f32 v205, v134, v131, v121
	v_fma_f32 v155, v134, v155, v112
	v_fma_f32 v157, v134, v157, v113
	v_fma_f32 v200, v134, v200, v116
	v_fma_f32 v197, v134, v197, v117
	v_fma_f32 v202, v134, v202, v96
	v_fma_f32 v203, v134, v203, v97
	v_fma_f32 v92, v92, v135, v140
	v_fma_f32 v93, v93, v205, v140
	v_fma_f32 v133, v134, v133, v122
	v_fma_f32 v206, v134, v206, v123
	v_fma_f32 v199, v134, v199, v114
	v_fma_f32 v201, v134, v201, v115
	v_fma_f32 v84, v84, v155, v92
	v_fma_f32 v85, v85, v157, v93
	v_fma_f32 v156, v134, v156, v118
	v_fma_f32 v154, v134, v154, v119
	v_fma_f32 v204, v134, v204, v98
	v_fma_f32 v132, v134, v132, v99
	v_fma_f32 v76, v76, v200, v84
	v_fma_f32 v77, v77, v197, v85
	v_fma_f32 v94, v94, v133, v140
	v_fma_f32 v95, v95, v206, v140
	v_fma_f32 v68, v68, v202, v76
	v_fma_f32 v69, v69, v203, v77
	v_fma_f32 v86, v86, v199, v94
	v_fma_f32 v87, v87, v201, v95
	v_fma_f32 v78, v78, v156, v86
	v_fma_f32 v79, v79, v154, v87
	v_add_f32_e32 v68, v68, v69
	v_fma_f32 v70, v70, v204, v78
	v_fma_f32 v71, v71, v132, v79
	v_add_f32_e32 v69, v70, v71
	v_add_f32_e32 v68, v68, v69
	v_mov_b32_e32 v69, 0
	s_nop 0
	v_add_f32_dpp v68, v68, v68 row_ror:8 row_mask:0xf bank_mask:0xf bound_ctrl:1
	s_nop 1
	v_add_f32_dpp v68, v68, v68 row_ror:4 row_mask:0xf bank_mask:0xf bound_ctrl:1
	s_nop 1
	v_add_f32_dpp v68, v68, v68 row_ror:2 row_mask:0xf bank_mask:0xf bound_ctrl:1
	s_nop 1
	v_mov_b32_dpp v69, v68 row_ror:1 row_mask:0xf bank_mask:0xf
	s_and_saveexec_b64 s[8:9], s[44:45]
	v_add_f32_e32 v68, v68, v69
	ds_write_b32 v190, v68 offset:34368
	s_or_b64 exec, exec, s[8:9]
	s_waitcnt lgkmcnt(0)
	v_mul_f32_e32 v134, v129, v207
	ds_read_b128 v[92:95], v194 offset:7168
	ds_read_b128 v[84:87], v194 offset:7424
	ds_read_b128 v[120:123], v194 offset:15360
	ds_read_b128 v[112:115], v194 offset:15616
	ds_read_b128 v[76:79], v194 offset:7680
	ds_read_b128 v[68:71], v194 offset:7936
	ds_read_b128 v[116:119], v194 offset:15872
	ds_read_b128 v[96:99], v194 offset:16128
	ds_read2_b32 v[130:131], v196 offset0:71 offset1:87
	ds_read_b32 v129, v190 offset:16832
	v_mul_f32 v126, v126, v134
	v_mul_f32 v127, v127, v134
	v_mul_f32 v104, v104, v134
	v_mul_f32 v105, v105, v134
	v_mul_f32 v124, v124, v134
	v_mul_f32 v125, v125, v134
	v_mul_f32 v106, v106, v134
	v_mul_f32 v107, v107, v134
	v_mul_f32 v108, v108, v134
	v_mul_f32 v109, v109, v134
	v_mul_f32 v110, v110, v134
	v_mul_f32 v111, v111, v134
	v_mul_f32 v207, v100, v134
	v_mul_f32 v208, v101, v134
	v_mul_f32 v209, v102, v134
	v_mul_f32 v210, v103, v134
	v_fma_f32 v100, v128, v135, v124
	v_fma_f32 v101, v128, v205, v125
	v_fma_f32 v102, v128, v133, v126
	v_fma_f32 v103, v128, v206, v127
	v_fma_f32 v104, v128, v155, v104
	v_fma_f32 v105, v128, v157, v105
	v_fma_f32 v126, v128, v200, v108
	v_fma_f32 v127, v128, v197, v109
	v_fma_f32 v134, v128, v154, v111
	v_fma_f32 v135, v128, v202, v207
	v_fma_f32 v154, v128, v203, v208
	v_fma_f32 v88, v88, v100, v140
	v_fma_f32 v89, v89, v101, v140
	v_fma_f32 v124, v128, v199, v106
	v_fma_f32 v125, v128, v201, v107
	v_fma_f32 v133, v128, v156, v110
	v_fma_f32 v155, v128, v204, v209
	v_fma_f32 v80, v80, v104, v88
	v_fma_f32 v81, v81, v105, v89
	v_fma_f32 v128, v128, v132, v210
	v_fma_f32 v90, v90, v102, v140
	v_fma_f32 v91, v91, v103, v140
	v_fma_f32 v72, v72, v126, v80
	v_fma_f32 v73, v73, v127, v81
	v_fma_f32 v64, v64, v135, v72
	v_fma_f32 v65, v65, v154, v73
	v_fma_f32 v82, v82, v124, v90
	v_fma_f32 v83, v83, v125, v91
	v_fma_f32 v74, v74, v133, v82
	v_fma_f32 v75, v75, v134, v83
	v_add_f32_e32 v64, v64, v65
	v_fma_f32 v66, v66, v155, v74
	v_fma_f32 v67, v67, v128, v75
	v_add_f32_e32 v65, v66, v67
	v_add_f32_e32 v64, v64, v65
	v_mov_b32_e32 v65, 0
	s_nop 0
	v_add_f32_dpp v64, v64, v64 row_ror:8 row_mask:0xf bank_mask:0xf bound_ctrl:1
	s_nop 1
	v_add_f32_dpp v64, v64, v64 row_ror:4 row_mask:0xf bank_mask:0xf bound_ctrl:1
	s_nop 1
	v_add_f32_dpp v64, v64, v64 row_ror:2 row_mask:0xf bank_mask:0xf bound_ctrl:1
	s_nop 1
	v_mov_b32_dpp v65, v64 row_ror:1 row_mask:0xf bank_mask:0xf
	s_and_saveexec_b64 s[8:9], s[44:45]
	v_add_f32_e32 v64, v64, v65
	ds_write_b32 v190, v64 offset:34432
	s_or_b64 exec, exec, s[8:9]
	s_waitcnt lgkmcnt(0)
	v_mul_f32_e32 v64, v131, v129
	v_mul_f32 v65, v120, v64
	v_mul_f32 v66, v121, v64
	v_mul_f32 v67, v122, v64
	v_mul_f32 v72, v123, v64
	v_mul_f32 v73, v112, v64
	v_mul_f32 v74, v113, v64
	v_mul_f32 v75, v114, v64
	v_mul_f32 v80, v115, v64
	v_mul_f32 v81, v116, v64
	v_mul_f32 v82, v117, v64
	v_mul_f32 v83, v118, v64
	v_mul_f32 v88, v119, v64
	v_mul_f32 v89, v96, v64
	v_mul_f32 v90, v97, v64
	v_mul_f32 v112, v98, v64
	v_mul_f32 v64, v99, v64
	v_fma_f32 v111, v130, v100, v65
	v_fma_f32 v110, v130, v101, v66
	v_fma_f32 v96, v130, v134, v88
	v_fma_f32 v109, v130, v102, v67
	v_fma_f32 v108, v130, v103, v72
	v_fma_f32 v88, v130, v128, v64
	v_fma_f32 v64, v92, v111, v140
	v_fma_f32 v65, v93, v110, v140
	v_fma_f32 v107, v130, v104, v73
	v_fma_f32 v106, v130, v105, v74
	v_fma_f32 v66, v94, v109, v140
	v_fma_f32 v67, v95, v108, v140
	v_fma_f32 v105, v130, v124, v75
	v_fma_f32 v104, v130, v125, v80
	v_fma_f32 v64, v84, v107, v64
	v_fma_f32 v65, v85, v106, v65
	v_fma_f32 v99, v130, v126, v81
	v_fma_f32 v98, v130, v127, v82
	v_fma_f32 v66, v86, v105, v66
	v_fma_f32 v67, v87, v104, v67
	v_fma_f32 v97, v130, v133, v83
	v_fma_f32 v91, v130, v135, v89
	v_fma_f32 v64, v76, v99, v64
	v_fma_f32 v65, v77, v98, v65
	v_fma_f32 v90, v130, v154, v90
	v_fma_f32 v67, v79, v96, v67
	v_fma_f32 v66, v78, v97, v66
	v_fma_f32 v89, v130, v155, v112
	v_fma_f32 v64, v68, v91, v64
	v_fma_f32 v65, v69, v90, v65
	v_fma_f32 v67, v71, v88, v67
	v_fma_f32 v66, v70, v89, v66
	v_add_f32_e32 v64, v64, v65
	v_add_f32_e32 v65, v66, v67
	v_add_f32_e32 v64, v64, v65
	v_mov_b32_e32 v65, 0
	s_nop 0
	v_add_f32_dpp v64, v64, v64 row_ror:8 row_mask:0xf bank_mask:0xf bound_ctrl:1
	s_nop 1
	v_add_f32_dpp v64, v64, v64 row_ror:4 row_mask:0xf bank_mask:0xf bound_ctrl:1
	s_nop 1
	v_add_f32_dpp v64, v64, v64 row_ror:2 row_mask:0xf bank_mask:0xf bound_ctrl:1
	s_nop 1
	v_mov_b32_dpp v65, v64 row_ror:1 row_mask:0xf bank_mask:0xf
	s_and_saveexec_b64 s[8:9], s[44:45]
	v_add_f32_e32 v64, v64, v65
	ds_write_b32 v190, v64 offset:34496
	s_or_b64 exec, exec, s[8:9]
	s_waitcnt vmcnt(11)
	ds_write_b128 v188, v[16:19] offset:17024
	s_waitcnt vmcnt(9)
	ds_write_b128 v191, v[24:27] offset:17024
	ds_write_b128 v188, v[20:23] offset:25216
	s_waitcnt vmcnt(8)
	ds_write_b128 v191, v[28:31] offset:25216
	s_and_saveexec_b64 s[8:9], s[40:41]
	ds_write_b32 v145, v183 offset:33408
	s_or_b64 exec, exec, s[8:9]
	s_and_saveexec_b64 s[8:9], s[42:43]
	s_cbranch_execz .LBB0_1176
	v_add_f32_e32 v64, v178, v185
	v_mul_f32_e64 v65, |v64|, s62
	v_exp_f32_e32 v65, v65
	v_min_f32_e32 v64, 0, v64
	v_add_f32_e32 v65, 1.0, v65
	v_cmp_gt_f32_e32 vcc, s5, v65
	s_nop 1
	v_cndmask_b32_e64 v66, 0, 32, vcc
	v_ldexp_f32 v65, v65, v66
	v_log_f32_e32 v65, v65
	v_cndmask_b32_e32 v67, 0, v171, vcc
	v_add_f32_e32 v66, v147, v184
	v_mul_f32_e32 v68, 0x3f317217, v65
	v_fma_f32 v68, v65, s76, -v68
	v_fmac_f32_e32 v68, 0x3377d1cf, v65
	v_fmac_f32_e32 v68, 0x3f317217, v65
	v_cmp_lt_f32_e64 vcc, |v65|, s77
	s_nop 1
	v_cndmask_b32_e32 v65, v65, v68, vcc
	v_sub_f32_e32 v65, v65, v67
	v_sub_f32_e32 v64, v64, v65
	v_add_u32_e32 v65, 0x8400, v145
	ds_write2_b32 v65, v66, v64 offset0:32 offset1:48

.LBB0_1189:
	s_or_b64 exec, exec, s[8:9]
	s_waitcnt lgkmcnt(0)
	s_barrier
	ds_read_b128 v[92:95], v194 offset:17024
	ds_read_b128 v[112:115], v194 offset:17280
	ds_read_b128 v[124:127], v194 offset:25216
	ds_read_b128 v[132:135], v194 offset:25472
	ds_read2_b64 v[80:83], v196 offset0:32 offset1:40
	v_add_u32_e32 v197, 0x8000, v190
	ds_read2_b32 v[76:77], v197 offset0:160 offset1:176
	ds_read_b128 v[208:211], v194 offset:17536
	ds_read_b128 v[212:215], v194 offset:17792
	ds_read_b128 v[154:157], v194 offset:25728
	ds_read_b128 v[200:203], v194 offset:25984
	ds_read_b128 v[84:87], v194 offset:18048
	ds_read_b128 v[72:75], v194 offset:18304
	ds_read_b128 v[128:131], v194 offset:26240
	ds_read_b128 v[116:119], v194 offset:26496
	ds_read_b128 v[68:71], v194 offset:18560
	ds_read_b128 v[64:67], v194 offset:18816
	ds_read_b128 v[120:123], v194 offset:26752
	ds_read_b128 v[100:103], v194 offset:27008
	s_waitcnt lgkmcnt(12)
	v_mul_f32_e32 v76, v82, v76
	v_mul_f32 v78, v124, v76
	v_mul_f32 v79, v125, v76
	v_mul_f32 v124, v126, v76
	v_mul_f32 v125, v127, v76
	v_mul_f32 v126, v132, v76
	v_mul_f32 v127, v133, v76
	v_mul_f32 v199, v134, v76
	v_mul_f32 v204, v135, v76
	s_waitcnt lgkmcnt(9)
	v_mul_f32 v154, v154, v76
	v_mul_f32 v155, v155, v76
	v_mul_f32 v205, v156, v76
	v_mul_f32 v206, v157, v76
	s_waitcnt lgkmcnt(8)
	v_mul_f32 v207, v200, v76
	v_mul_f32 v216, v201, v76
	v_mul_f32 v217, v202, v76
	v_mul_f32 v76, v203, v76
	v_fma_f32 v82, v80, v111, v78
	v_fma_f32 v132, v80, v110, v79
	v_fma_f32 v133, v80, v109, v124
	v_fma_f32 v134, v80, v108, v125
	v_fma_f32 v135, v80, v107, v126
	v_fma_f32 v156, v80, v106, v127
	v_fma_f32 v157, v80, v105, v199
	v_fma_f32 v199, v80, v104, v204
	v_fma_f32 v200, v80, v99, v154
	v_fma_f32 v201, v80, v98, v155
	v_fma_f32 v202, v80, v97, v205
	v_fma_f32 v203, v80, v96, v206
	v_fma_f32 v204, v80, v91, v207
	v_fma_f32 v205, v80, v90, v216
	v_fma_f32 v206, v80, v89, v217
	v_fma_f32 v80, v80, v88, v76
	v_fma_f32 v76, v92, v82, v140
	v_fma_f32 v78, v93, v132, v140
	v_fma_f32 v79, v94, v133, v140
	v_fma_f32 v88, v95, v134, v140
	v_fma_f32 v76, v112, v135, v76
	v_fma_f32 v78, v113, v156, v78
	v_fma_f32 v79, v114, v157, v79
	v_fma_f32 v88, v115, v199, v88
	v_fma_f32 v76, v208, v200, v76
	v_fma_f32 v78, v209, v201, v78
	v_fma_f32 v79, v210, v202, v79
	v_fma_f32 v88, v211, v203, v88
	v_fma_f32 v76, v212, v204, v76
	v_fma_f32 v78, v213, v205, v78
	v_fma_f32 v79, v214, v206, v79
	v_fma_f32 v88, v215, v80, v88
	v_add_f32_e32 v76, v76, v78
	v_add_f32_e32 v78, v79, v88
	v_add_f32_e32 v76, v76, v78
	v_mov_b32_e32 v78, 0
	s_nop 0
	v_add_f32_dpp v76, v76, v76 row_ror:8 row_mask:0xf bank_mask:0xf bound_ctrl:1
	s_nop 1
	v_add_f32_dpp v76, v76, v76 row_ror:4 row_mask:0xf bank_mask:0xf bound_ctrl:1
	s_nop 1
	v_add_f32_dpp v76, v76, v76 row_ror:2 row_mask:0xf bank_mask:0xf bound_ctrl:1
	s_nop 1
	v_mov_b32_dpp v78, v76 row_ror:1 row_mask:0xf bank_mask:0xf
	s_and_saveexec_b64 s[8:9], s[44:45]
	v_add_f32_e32 v76, v76, v78
	ds_write_b32 v190, v76 offset:34560
	s_or_b64 exec, exec, s[8:9]
	v_mul_f32_e32 v207, v83, v77
	ds_read_b128 v[96:99], v194 offset:19072
	ds_read_b128 v[92:95], v194 offset:19328
	ds_read_b128 v[124:127], v194 offset:27264
	ds_read_b128 v[108:111], v194 offset:27520
	ds_read_b128 v[88:91], v194 offset:19584
	ds_read_b128 v[76:79], v194 offset:19840
	ds_read_b128 v[112:115], v194 offset:27776
	ds_read_b128 v[104:107], v194 offset:28032
	ds_read2_b32 v[154:155], v196 offset0:66 offset1:82
	ds_read_b32 v83, v190 offset:33536
	s_waitcnt lgkmcnt(14)
	v_mul_f32 v128, v128, v207
	v_mul_f32 v129, v129, v207
	v_mul_f32 v130, v130, v207
	v_mul_f32 v131, v131, v207
	v_mul_f32 v116, v116, v207
	v_mul_f32 v117, v117, v207
	v_mul_f32 v118, v118, v207
	v_mul_f32 v119, v119, v207
	s_waitcnt lgkmcnt(11)
	v_mul_f32 v120, v120, v207
	v_mul_f32 v121, v121, v207
	v_mul_f32 v122, v122, v207
	v_mul_f32 v123, v123, v207
	s_waitcnt lgkmcnt(10)
	v_mul_f32 v100, v100, v207
	v_mul_f32 v101, v101, v207
	v_mul_f32 v102, v102, v207
	v_mul_f32 v103, v103, v207
	v_fma_f32 v207, v81, v82, v128
	v_fma_f32 v208, v81, v132, v129
	v_fma_f32 v209, v81, v133, v130
	v_fma_f32 v210, v81, v134, v131
	v_fma_f32 v211, v81, v135, v116
	v_fma_f32 v212, v81, v156, v117
	v_fma_f32 v213, v81, v157, v118
	v_fma_f32 v199, v81, v199, v119
	v_fma_f32 v200, v81, v200, v120
	v_fma_f32 v201, v81, v201, v121
	v_fma_f32 v202, v81, v202, v122
	v_fma_f32 v203, v81, v203, v123
	v_fma_f32 v204, v81, v204, v100
	v_fma_f32 v205, v81, v205, v101
	v_fma_f32 v206, v81, v206, v102
	v_fma_f32 v214, v81, v80, v103
	v_fma_f32 v80, v84, v207, v140
	v_fma_f32 v81, v85, v208, v140
	v_fma_f32 v82, v86, v209, v140
	v_fma_f32 v84, v87, v210, v140
	v_fma_f32 v72, v72, v211, v80
	v_fma_f32 v73, v73, v212, v81
	v_fma_f32 v74, v74, v213, v82
	v_fma_f32 v75, v75, v199, v84
	v_fma_f32 v68, v68, v200, v72
	v_fma_f32 v69, v69, v201, v73
	v_fma_f32 v70, v70, v202, v74
	v_fma_f32 v71, v71, v203, v75
	v_fma_f32 v64, v64, v204, v68
	v_fma_f32 v65, v65, v205, v69
	v_fma_f32 v66, v66, v206, v70
	v_fma_f32 v67, v67, v214, v71
	v_add_f32_e32 v64, v64, v65
	v_add_f32_e32 v65, v66, v67
	v_add_f32_e32 v64, v64, v65
	v_mov_b32_e32 v65, 0
	s_nop 0
	v_add_f32_dpp v64, v64, v64 row_ror:8 row_mask:0xf bank_mask:0xf bound_ctrl:1
	s_nop 1
	v_add_f32_dpp v64, v64, v64 row_ror:4 row_mask:0xf bank_mask:0xf bound_ctrl:1
	s_nop 1
	v_add_f32_dpp v64, v64, v64 row_ror:2 row_mask:0xf bank_mask:0xf bound_ctrl:1
	s_nop 1
	v_mov_b32_dpp v65, v64 row_ror:1 row_mask:0xf bank_mask:0xf
	s_and_saveexec_b64 s[8:9], s[44:45]
	v_add_f32_e32 v64, v64, v65
	ds_write_b32 v190, v64 offset:34624
	s_or_b64 exec, exec, s[8:9]
	s_waitcnt lgkmcnt(0)
	v_mul_f32_e32 v69, v155, v83
	ds_read_b128 v[100:103], v194 offset:20096
	ds_read_b128 v[80:83], v194 offset:20352
	ds_read_b128 v[132:135], v194 offset:28288
	ds_read_b128 v[120:123], v194 offset:28544
	ds_read_b128 v[72:75], v194 offset:20608
	ds_read_b128 v[64:67], v194 offset:20864
	ds_read_b128 v[128:131], v194 offset:28800
	ds_read_b128 v[116:119], v194 offset:29056
	ds_read2_b32 v[156:157], v196 offset0:67 offset1:83
	ds_read_b32 v68, v190 offset:33600
	v_mul_f32 v70, v124, v69
	v_mul_f32 v71, v125, v69
	v_mul_f32 v84, v126, v69
	v_mul_f32 v85, v127, v69
	v_mul_f32 v86, v108, v69
	v_mul_f32 v87, v109, v69
	v_mul_f32 v108, v110, v69
	v_mul_f32 v109, v111, v69
	v_mul_f32 v110, v112, v69
	v_mul_f32 v111, v113, v69
	v_mul_f32 v124, v114, v69
	v_mul_f32 v125, v115, v69
	v_mul_f32 v104, v104, v69
	v_mul_f32 v105, v105, v69
	v_mul_f32 v106, v106, v69
	v_mul_f32 v69, v107, v69
	v_fma_f32 v112, v154, v207, v70
	v_fma_f32 v113, v154, v208, v71
	v_fma_f32 v115, v154, v210, v85
	v_fma_f32 v114, v154, v209, v84
	v_fma_f32 v207, v154, v211, v86
	v_fma_f32 v210, v154, v214, v69
	v_fma_f32 v69, v96, v112, v140
	v_fma_f32 v70, v97, v113, v140
	v_fma_f32 v208, v154, v212, v87
	v_fma_f32 v71, v98, v114, v140
	v_fma_f32 v209, v154, v213, v108
	v_fma_f32 v200, v154, v200, v110
	v_fma_f32 v69, v92, v207, v69
	v_fma_f32 v201, v154, v201, v111
	v_fma_f32 v70, v93, v208, v70
	v_fma_f32 v84, v99, v115, v140
	v_fma_f32 v71, v94, v209, v71
	v_fma_f32 v199, v154, v199, v109
	v_fma_f32 v69, v88, v200, v69
	v_fma_f32 v202, v154, v202, v124
	v_fma_f32 v70, v89, v201, v70
	v_fma_f32 v204, v154, v204, v104
	v_fma_f32 v205, v154, v205, v105
	v_fma_f32 v84, v95, v199, v84
	v_fma_f32 v203, v154, v203, v125
	v_fma_f32 v71, v90, v202, v71
	v_fma_f32 v206, v154, v206, v106
	v_fma_f32 v69, v76, v204, v69
	v_fma_f32 v70, v77, v205, v70
	v_fma_f32 v84, v91, v203, v84
	v_fma_f32 v71, v78, v206, v71
	v_fma_f32 v76, v79, v210, v84
	v_add_f32_e32 v69, v69, v70
	v_add_f32_e32 v70, v71, v76
	v_add_f32_e32 v69, v69, v70
	v_mov_b32_e32 v70, 0
	s_nop 0
	v_add_f32_dpp v69, v69, v69 row_ror:8 row_mask:0xf bank_mask:0xf bound_ctrl:1
	s_nop 1
	v_add_f32_dpp v69, v69, v69 row_ror:4 row_mask:0xf bank_mask:0xf bound_ctrl:1
	s_nop 1
	v_add_f32_dpp v69, v69, v69 row_ror:2 row_mask:0xf bank_mask:0xf bound_ctrl:1
	s_nop 1
	v_mov_b32_dpp v70, v69 row_ror:1 row_mask:0xf bank_mask:0xf
	s_and_saveexec_b64 s[8:9], s[44:45]
	v_add_f32_e32 v69, v69, v70
	ds_write_b32 v190, v69 offset:34688
	s_or_b64 exec, exec, s[8:9]
	s_waitcnt lgkmcnt(0)
	v_mul_f32_e32 v93, v157, v68
	ds_read_b128 v[88:91], v194 offset:21120
	ds_read_b128 v[84:87], v194 offset:21376
	ds_read_b128 v[124:127], v194 offset:29312
	ds_read_b128 v[104:107], v194 offset:29568
	ds_read_b128 v[76:79], v194 offset:21632
	ds_read_b128 v[68:71], v194 offset:21888
	ds_read_b128 v[108:111], v194 offset:29824
	ds_read_b128 v[96:99], v194 offset:30080
	ds_read2_b32 v[154:155], v196 offset0:68 offset1:84
	ds_read_b32 v92, v190 offset:33664
	v_mul_f32 v94, v132, v93
	v_mul_f32 v95, v133, v93
	v_mul_f32 v132, v134, v93
	v_mul_f32 v133, v135, v93
	v_mul_f32 v120, v120, v93
	v_mul_f32 v121, v121, v93
	v_mul_f32 v122, v122, v93
	v_mul_f32 v123, v123, v93
	v_mul_f32 v128, v128, v93
	v_mul_f32 v129, v129, v93
	v_mul_f32 v211, v130, v93
	v_mul_f32 v212, v131, v93
	v_mul_f32 v116, v116, v93
	v_mul_f32 v117, v117, v93
	v_mul_f32 v118, v118, v93
	v_mul_f32 v93, v119, v93
	v_fma_f32 v130, v156, v112, v94
	v_fma_f32 v131, v156, v113, v95
	v_fma_f32 v132, v156, v114, v132
	v_fma_f32 v133, v156, v115, v133
	v_fma_f32 v134, v156, v207, v120
	v_fma_f32 v135, v156, v208, v121
	v_fma_f32 v157, v156, v209, v122
	v_fma_f32 v199, v156, v199, v123
	v_fma_f32 v200, v156, v200, v128
	v_fma_f32 v201, v156, v201, v129
	v_fma_f32 v202, v156, v202, v211
	v_fma_f32 v203, v156, v203, v212
	v_fma_f32 v204, v156, v204, v116
	v_fma_f32 v205, v156, v205, v117
	v_fma_f32 v206, v156, v206, v118
	v_fma_f32 v156, v156, v210, v93
	v_fma_f32 v93, v100, v130, v140
	v_fma_f32 v94, v101, v131, v140
	v_fma_f32 v95, v102, v132, v140
	v_fma_f32 v100, v103, v133, v140
	v_fma_f32 v80, v80, v134, v93
	v_fma_f32 v81, v81, v135, v94
	v_fma_f32 v82, v82, v157, v95
	v_fma_f32 v83, v83, v199, v100
	v_fma_f32 v72, v72, v200, v80
	v_fma_f32 v73, v73, v201, v81
	v_fma_f32 v74, v74, v202, v82
	v_fma_f32 v75, v75, v203, v83
	v_fma_f32 v64, v64, v204, v72
	v_fma_f32 v65, v65, v205, v73
	v_fma_f32 v66, v66, v206, v74
	v_fma_f32 v67, v67, v156, v75
	v_add_f32_e32 v64, v64, v65
	v_add_f32_e32 v65, v66, v67
	v_add_f32_e32 v64, v64, v65
	v_mov_b32_e32 v65, 0
	s_nop 0
	v_add_f32_dpp v64, v64, v64 row_ror:8 row_mask:0xf bank_mask:0xf bound_ctrl:1
	s_nop 1
	v_add_f32_dpp v64, v64, v64 row_ror:4 row_mask:0xf bank_mask:0xf bound_ctrl:1
	s_nop 1
	v_add_f32_dpp v64, v64, v64 row_ror:2 row_mask:0xf bank_mask:0xf bound_ctrl:1
	s_nop 1
	v_mov_b32_dpp v65, v64 row_ror:1 row_mask:0xf bank_mask:0xf
	s_and_saveexec_b64 s[8:9], s[44:45]
	v_add_f32_e32 v64, v64, v65
	ds_write_b32 v190, v64 offset:34752
	s_or_b64 exec, exec, s[8:9]
	s_waitcnt lgkmcnt(0)
	v_mul_f32_e32 v155, v155, v92
	ds_read_b128 v[92:95], v194 offset:22144
	ds_read_b128 v[80:83], v194 offset:22400
	ds_read_b128 v[120:123], v194 offset:30336
	ds_read_b128 v[112:115], v194 offset:30592
	ds_read_b128 v[72:75], v194 offset:22656
	ds_read_b128 v[64:67], v194 offset:22912
	ds_read_b128 v[116:119], v194 offset:30848
	ds_read_b128 v[100:103], v194 offset:31104
	ds_read2_b32 v[128:129], v196 offset0:69 offset1:85
	ds_read_b32 v208, v190 offset:33728
	v_mul_f32 v124, v124, v155
	v_mul_f32 v125, v125, v155
	v_mul_f32 v126, v126, v155
	v_mul_f32 v127, v127, v155
	v_mul_f32 v104, v104, v155
	v_mul_f32 v105, v105, v155
	v_mul_f32 v106, v106, v155
	v_mul_f32 v107, v107, v155
	v_mul_f32 v108, v108, v155
	v_mul_f32 v109, v109, v155
	v_mul_f32 v110, v110, v155
	v_mul_f32 v111, v111, v155
	v_mul_f32 v96, v96, v155
	v_mul_f32 v97, v97, v155
	v_mul_f32 v98, v98, v155
	v_mul_f32 v99, v99, v155
	v_fma_f32 v155, v154, v130, v124
	v_fma_f32 v207, v154, v131, v125
	v_fma_f32 v134, v154, v134, v104
	v_fma_f32 v135, v154, v135, v105
	v_fma_f32 v200, v154, v200, v108
	v_fma_f32 v201, v154, v201, v109
	v_fma_f32 v204, v154, v204, v96
	v_fma_f32 v205, v154, v205, v97
	v_fma_f32 v88, v88, v155, v140
	v_fma_f32 v89, v89, v207, v140
	v_fma_f32 v132, v154, v132, v126
	v_fma_f32 v133, v154, v133, v127
	v_fma_f32 v157, v154, v157, v106
	v_fma_f32 v199, v154, v199, v107
	v_fma_f32 v84, v84, v134, v88
	v_fma_f32 v85, v85, v135, v89
	v_fma_f32 v202, v154, v202, v110
	v_fma_f32 v203, v154, v203, v111
	v_fma_f32 v206, v154, v206, v98
	v_fma_f32 v154, v154, v156, v99
	v_fma_f32 v76, v76, v200, v84
	v_fma_f32 v77, v77, v201, v85
	v_fma_f32 v90, v90, v132, v140
	v_fma_f32 v91, v91, v133, v140
	v_fma_f32 v68, v68, v204, v76
	v_fma_f32 v69, v69, v205, v77
	v_fma_f32 v86, v86, v157, v90
	v_fma_f32 v87, v87, v199, v91
	v_fma_f32 v78, v78, v202, v86
	v_fma_f32 v79, v79, v203, v87
	v_add_f32_e32 v68, v68, v69
	v_fma_f32 v70, v70, v206, v78
	v_fma_f32 v71, v71, v154, v79
	v_add_f32_e32 v69, v70, v71
	v_add_f32_e32 v68, v68, v69
	v_mov_b32_e32 v69, 0
	s_nop 0
	v_add_f32_dpp v68, v68, v68 row_ror:8 row_mask:0xf bank_mask:0xf bound_ctrl:1
	s_nop 1
	v_add_f32_dpp v68, v68, v68 row_ror:4 row_mask:0xf bank_mask:0xf bound_ctrl:1
	s_nop 1
	v_add_f32_dpp v68, v68, v68 row_ror:2 row_mask:0xf bank_mask:0xf bound_ctrl:1
	s_nop 1
	v_mov_b32_dpp v69, v68 row_ror:1 row_mask:0xf bank_mask:0xf
	s_and_saveexec_b64 s[8:9], s[44:45]
	v_add_f32_e32 v68, v68, v69
	ds_write_b32 v190, v68 offset:34816
	s_or_b64 exec, exec, s[8:9]
	s_waitcnt lgkmcnt(0)
	v_mul_f32_e32 v156, v129, v208
	ds_read_b128 v[88:91], v194 offset:23168
	ds_read_b128 v[84:87], v194 offset:23424
	ds_read_b128 v[124:127], v194 offset:31360
	ds_read_b128 v[104:107], v194 offset:31616
	ds_read_b128 v[76:79], v194 offset:23680
	ds_read_b128 v[68:71], v194 offset:23936
	ds_read_b128 v[108:111], v194 offset:31872
	ds_read_b128 v[96:99], v194 offset:32128
	ds_read2_b32 v[130:131], v196 offset0:70 offset1:86
	ds_read_b32 v129, v190 offset:33792
	v_mul_f32 v120, v120, v156
	v_mul_f32 v121, v121, v156
	v_mul_f32 v122, v122, v156
	v_mul_f32 v123, v123, v156
	v_mul_f32 v112, v112, v156
	v_mul_f32 v113, v113, v156
	v_mul_f32 v114, v114, v156
	v_mul_f32 v115, v115, v156
	v_mul_f32 v116, v116, v156
	v_mul_f32 v117, v117, v156
	v_mul_f32 v118, v118, v156
	v_mul_f32 v119, v119, v156
	v_mul_f32 v100, v100, v156
	v_mul_f32 v101, v101, v156
	v_mul_f32 v102, v102, v156
	v_mul_f32 v103, v103, v156
	v_fma_f32 v155, v128, v155, v120
	v_fma_f32 v156, v128, v207, v121
	v_fma_f32 v134, v128, v134, v112
	v_fma_f32 v135, v128, v135, v113
	v_fma_f32 v200, v128, v200, v116
	v_fma_f32 v201, v128, v201, v117
	v_fma_f32 v204, v128, v204, v100
	v_fma_f32 v205, v128, v205, v101
	v_fma_f32 v92, v92, v155, v140
	v_fma_f32 v93, v93, v156, v140
	v_fma_f32 v132, v128, v132, v122
	v_fma_f32 v133, v128, v133, v123
	v_fma_f32 v157, v128, v157, v114
	v_fma_f32 v199, v128, v199, v115
	v_fma_f32 v80, v80, v134, v92
	v_fma_f32 v81, v81, v135, v93
	v_fma_f32 v202, v128, v202, v118
	v_fma_f32 v203, v128, v203, v119
	v_fma_f32 v206, v128, v206, v102
	v_fma_f32 v154, v128, v154, v103
	v_fma_f32 v72, v72, v200, v80
	v_fma_f32 v73, v73, v201, v81
	v_fma_f32 v94, v94, v132, v140
	v_fma_f32 v95, v95, v133, v140
	v_fma_f32 v64, v64, v204, v72
	v_fma_f32 v65, v65, v205, v73
	v_fma_f32 v82, v82, v157, v94
	v_fma_f32 v83, v83, v199, v95
	v_fma_f32 v74, v74, v202, v82
	v_fma_f32 v75, v75, v203, v83
	v_add_f32_e32 v64, v64, v65
	v_fma_f32 v66, v66, v206, v74
	v_fma_f32 v67, v67, v154, v75
	v_add_f32_e32 v65, v66, v67
	v_add_f32_e32 v64, v64, v65
	v_mov_b32_e32 v65, 0
	s_nop 0
	v_add_f32_dpp v64, v64, v64 row_ror:8 row_mask:0xf bank_mask:0xf bound_ctrl:1
	s_nop 1
	v_add_f32_dpp v64, v64, v64 row_ror:4 row_mask:0xf bank_mask:0xf bound_ctrl:1
	s_nop 1
	v_add_f32_dpp v64, v64, v64 row_ror:2 row_mask:0xf bank_mask:0xf bound_ctrl:1
	s_nop 1
	v_mov_b32_dpp v65, v64 row_ror:1 row_mask:0xf bank_mask:0xf
	s_and_saveexec_b64 s[8:9], s[44:45]
	v_add_f32_e32 v64, v64, v65
	ds_write_b32 v190, v64 offset:34880
	s_or_b64 exec, exec, s[8:9]
	s_waitcnt lgkmcnt(0)
	v_mul_f32_e32 v207, v131, v129
	ds_read_b128 v[92:95], v194 offset:24192
	ds_read_b128 v[80:83], v194 offset:24448
	ds_read_b128 v[120:123], v194 offset:32384
	ds_read_b128 v[112:115], v194 offset:32640
	ds_read_b128 v[72:75], v194 offset:24704
	ds_read_b128 v[64:67], v194 offset:24960
	ds_read_b128 v[116:119], v194 offset:32896
	ds_read_b128 v[100:103], v194 offset:33152
	ds_read2_b32 v[128:129], v196 offset0:71 offset1:87
	ds_read_b32 v131, v190 offset:33856
	v_mul_f32 v125, v125, v207
	v_mul_f32 v126, v126, v207
	v_mul_f32 v104, v104, v207
	v_mul_f32 v124, v124, v207
	v_mul_f32 v127, v127, v207
	v_mul_f32 v105, v105, v207
	v_mul_f32 v106, v106, v207
	v_mul_f32 v107, v107, v207
	v_mul_f32 v108, v108, v207
	v_mul_f32 v109, v109, v207
	v_mul_f32 v208, v110, v207
	v_mul_f32 v209, v111, v207
	v_mul_f32 v210, v96, v207
	v_mul_f32 v211, v97, v207
	v_mul_f32 v212, v98, v207
	v_mul_f32 v207, v99, v207
	v_fma_f32 v96, v130, v155, v124
	v_fma_f32 v97, v130, v156, v125
	v_fma_f32 v98, v130, v132, v126
	v_fma_f32 v99, v130, v133, v127
	v_fma_f32 v104, v130, v134, v104
	v_fma_f32 v110, v130, v135, v105
	v_fma_f32 v125, v130, v200, v108
	v_fma_f32 v126, v130, v201, v109
	v_fma_f32 v133, v130, v204, v210
	v_fma_f32 v134, v130, v205, v211
	v_fma_f32 v88, v88, v96, v140
	v_fma_f32 v89, v89, v97, v140
	v_fma_f32 v111, v130, v157, v106
	v_fma_f32 v124, v130, v199, v107
	v_fma_f32 v127, v130, v202, v208
	v_fma_f32 v132, v130, v203, v209
	v_fma_f32 v84, v84, v104, v88
	v_fma_f32 v85, v85, v110, v89
	v_fma_f32 v135, v130, v206, v212
	v_fma_f32 v130, v130, v154, v207
	v_fma_f32 v90, v90, v98, v140
	v_fma_f32 v91, v91, v99, v140
	v_fma_f32 v76, v76, v125, v84
	v_fma_f32 v77, v77, v126, v85
	v_fma_f32 v68, v68, v133, v76
	v_fma_f32 v69, v69, v134, v77
	v_fma_f32 v86, v86, v111, v90
	v_fma_f32 v87, v87, v124, v91
	v_fma_f32 v78, v78, v127, v86
	v_fma_f32 v79, v79, v132, v87
	v_add_f32_e32 v68, v68, v69
	v_fma_f32 v70, v70, v135, v78
	v_fma_f32 v71, v71, v130, v79
	v_add_f32_e32 v69, v70, v71
	v_add_f32_e32 v68, v68, v69
	v_mov_b32_e32 v69, 0
	s_nop 0
	v_add_f32_dpp v68, v68, v68 row_ror:8 row_mask:0xf bank_mask:0xf bound_ctrl:1
	s_nop 1
	v_add_f32_dpp v68, v68, v68 row_ror:4 row_mask:0xf bank_mask:0xf bound_ctrl:1
	s_nop 1
	v_add_f32_dpp v68, v68, v68 row_ror:2 row_mask:0xf bank_mask:0xf bound_ctrl:1
	s_nop 1
	v_mov_b32_dpp v69, v68 row_ror:1 row_mask:0xf bank_mask:0xf
	s_and_saveexec_b64 s[8:9], s[44:45]
	v_add_f32_e32 v68, v68, v69
	ds_write_b32 v190, v68 offset:34944
	s_or_b64 exec, exec, s[8:9]
	s_waitcnt lgkmcnt(0)
	v_mul_f32_e32 v68, v129, v131
	v_mul_f32 v69, v120, v68
	v_mul_f32 v70, v121, v68
	v_mul_f32 v71, v122, v68
	v_mul_f32 v76, v123, v68
	v_mul_f32 v77, v112, v68
	v_mul_f32 v78, v113, v68
	v_mul_f32 v79, v114, v68
	v_mul_f32 v84, v115, v68
	v_mul_f32 v85, v116, v68
	v_mul_f32 v86, v117, v68
	v_mul_f32 v87, v118, v68
	v_mul_f32 v88, v119, v68
	v_mul_f32 v89, v100, v68
	v_mul_f32 v100, v101, v68
	v_mul_f32 v101, v102, v68
	v_mul_f32 v68, v103, v68
	v_fma_f32 v109, v128, v96, v69
	v_fma_f32 v108, v128, v97, v70
	v_fma_f32 v105, v128, v104, v77
	v_fma_f32 v104, v128, v110, v78
	v_fma_f32 v107, v128, v98, v71
	v_fma_f32 v78, v128, v130, v68
	v_fma_f32 v68, v92, v109, v140
	v_fma_f32 v69, v93, v108, v140
	v_fma_f32 v106, v128, v99, v76
	v_fma_f32 v99, v128, v111, v79
	v_fma_f32 v70, v94, v107, v140
	v_fma_f32 v98, v128, v124, v84
	v_fma_f32 v68, v80, v105, v68
	v_fma_f32 v69, v81, v104, v69
	v_fma_f32 v71, v95, v106, v140
	v_fma_f32 v97, v128, v125, v85
	v_fma_f32 v96, v128, v126, v86
	v_fma_f32 v90, v128, v132, v88
	v_fma_f32 v89, v128, v133, v89
	v_fma_f32 v88, v128, v134, v100
	v_fma_f32 v70, v82, v99, v70
	v_fma_f32 v71, v83, v98, v71
	v_fma_f32 v68, v72, v97, v68
	v_fma_f32 v69, v73, v96, v69
	v_fma_f32 v91, v128, v127, v87
	v_fma_f32 v79, v128, v135, v101
	v_fma_f32 v71, v75, v90, v71
	v_fma_f32 v64, v64, v89, v68
	v_fma_f32 v65, v65, v88, v69
	v_fma_f32 v70, v74, v91, v70
	v_fma_f32 v66, v66, v79, v70
	v_fma_f32 v67, v67, v78, v71
	v_add_f32_e32 v64, v64, v65
	v_add_f32_e32 v65, v66, v67
	v_add_f32_e32 v64, v64, v65
	v_mov_b32_e32 v65, 0
	s_nop 0
	v_add_f32_dpp v64, v64, v64 row_ror:8 row_mask:0xf bank_mask:0xf bound_ctrl:1
	s_nop 1
	v_add_f32_dpp v64, v64, v64 row_ror:4 row_mask:0xf bank_mask:0xf bound_ctrl:1
	s_nop 1
	v_add_f32_dpp v64, v64, v64 row_ror:2 row_mask:0xf bank_mask:0xf bound_ctrl:1
	s_nop 1
	v_mov_b32_dpp v65, v64 row_ror:1 row_mask:0xf bank_mask:0xf
	s_and_saveexec_b64 s[8:9], s[44:45]
	v_add_f32_e32 v64, v64, v65
	ds_write_b32 v190, v64 offset:35008
	s_or_b64 exec, exec, s[8:9]
	s_waitcnt vmcnt(7)
	ds_write_b128 v188, v[32:35]
	s_waitcnt vmcnt(5)
	ds_write_b128 v191, v[40:43]
	ds_write_b128 v188, v[36:39] offset:8192
	s_waitcnt vmcnt(4)
	ds_write_b128 v191, v[44:47] offset:8192
	s_and_saveexec_b64 s[8:9], s[40:41]
	ds_write_b32 v145, v186 offset:16384
	s_or_b64 exec, exec, s[8:9]
	s_and_saveexec_b64 s[8:9], s[42:43]
	s_cbranch_execz .LBB0_1209
	v_add_f32_e32 v64, v178, v189
	v_mul_f32_e64 v65, |v64|, s62
	v_exp_f32_e32 v65, v65
	v_min_f32_e32 v64, 0, v64
	v_add_f32_e32 v65, 1.0, v65
	v_cmp_gt_f32_e32 vcc, s5, v65
	s_nop 1
	v_cndmask_b32_e64 v66, 0, 32, vcc
	v_ldexp_f32 v65, v65, v66
	v_log_f32_e32 v65, v65
	v_cndmask_b32_e32 v67, 0, v171, vcc
	v_add_f32_e32 v66, v147, v187
	v_mul_f32_e32 v68, 0x3f317217, v65
	v_fma_f32 v68, v65, s76, -v68
	v_fmac_f32_e32 v68, 0x3377d1cf, v65
	v_fmac_f32_e32 v68, 0x3f317217, v65
	v_cmp_lt_f32_e64 vcc, |v65|, s77
	s_nop 1
	v_cndmask_b32_e32 v65, v65, v68, vcc
	v_sub_f32_e32 v65, v65, v67
	v_sub_f32_e32 v64, v64, v65
	v_add_u32_e32 v65, 0x4000, v145
	ds_write2_b32 v65, v66, v64 offset0:128 offset1:144

.LBB0_1222:
	s_or_b64 exec, exec, s[8:9]
	s_waitcnt lgkmcnt(0)
	s_barrier
	ds_read_b128 v[92:95], v194
	ds_read_b128 v[110:113], v194 offset:256
	ds_read_b128 v[124:127], v194 offset:8192
	ds_read_b128 v[132:135], v194 offset:8448
	ds_read2_b64 v[80:83], v196 offset0:32 offset1:40
	ds_read2_b32 v[76:77], v198 offset1:16
	ds_read_b128 v[206:209], v194 offset:512
	ds_read_b128 v[210:213], v194 offset:768
	ds_read_b128 v[154:157], v194 offset:8704
	ds_read_b128 v[198:201], v194 offset:8960
	s_waitcnt lgkmcnt(4)
	v_mul_f32_e32 v76, v82, v76
	v_mul_f32 v82, v124, v76
	v_mul_f32 v114, v125, v76
	v_mul_f32 v115, v126, v76
	v_mul_f32 v124, v127, v76
	v_mul_f32 v125, v132, v76
	v_mul_f32 v126, v133, v76
	v_mul_f32 v127, v134, v76
	v_mul_f32 v202, v135, v76
	s_waitcnt lgkmcnt(1)
	v_mul_f32 v154, v154, v76
	v_mul_f32 v155, v155, v76
	v_mul_f32 v203, v156, v76
	v_mul_f32 v204, v157, v76
	s_waitcnt lgkmcnt(0)
	v_mul_f32 v205, v198, v76
	v_mul_f32 v214, v199, v76
	v_mul_f32 v215, v200, v76
	v_mul_f32 v76, v201, v76
	ds_read_b128 v[84:87], v194 offset:1024
	ds_read_b128 v[72:75], v194 offset:1280
	ds_read_b128 v[128:131], v194 offset:9216
	ds_read_b128 v[116:119], v194 offset:9472
	ds_read_b128 v[68:71], v194 offset:1536
	ds_read_b128 v[64:67], v194 offset:1792
	ds_read_b128 v[120:123], v194 offset:9728
	ds_read_b128 v[100:103], v194 offset:9984
	v_fma_f32 v82, v80, v109, v82
	v_fma_f32 v132, v80, v108, v114
	v_fma_f32 v133, v80, v107, v115
	v_fma_f32 v134, v80, v106, v124
	v_fma_f32 v135, v80, v105, v125
	v_fma_f32 v156, v80, v104, v126
	v_fma_f32 v157, v80, v99, v127
	v_fma_f32 v198, v80, v98, v202
	v_fma_f32 v199, v80, v97, v154
	v_fma_f32 v200, v80, v96, v155
	v_fma_f32 v201, v80, v91, v203
	v_fma_f32 v202, v80, v90, v204
	v_fma_f32 v203, v80, v89, v205
	v_fma_f32 v204, v80, v88, v214
	v_fma_f32 v205, v80, v79, v215
	v_fma_f32 v80, v80, v78, v76
	v_fma_f32 v76, v92, v82, v140
	v_fma_f32 v78, v93, v132, v140
	v_fma_f32 v79, v94, v133, v140
	v_fma_f32 v88, v95, v134, v140
	v_fma_f32 v76, v110, v135, v76
	v_fma_f32 v78, v111, v156, v78
	v_fma_f32 v79, v112, v157, v79
	v_fma_f32 v88, v113, v198, v88
	v_fma_f32 v76, v206, v199, v76
	v_fma_f32 v78, v207, v200, v78
	v_fma_f32 v79, v208, v201, v79
	v_fma_f32 v88, v209, v202, v88
	v_fma_f32 v76, v210, v203, v76
	v_fma_f32 v78, v211, v204, v78
	v_fma_f32 v79, v212, v205, v79
	v_fma_f32 v88, v213, v80, v88
	v_add_f32_e32 v76, v76, v78
	v_add_f32_e32 v78, v79, v88
	v_add_f32_e32 v76, v76, v78
	v_mov_b32_e32 v78, 0
	s_nop 0
	v_add_f32_dpp v76, v76, v76 row_ror:8 row_mask:0xf bank_mask:0xf bound_ctrl:1
	s_nop 1
	v_add_f32_dpp v76, v76, v76 row_ror:4 row_mask:0xf bank_mask:0xf bound_ctrl:1
	s_nop 1
	v_add_f32_dpp v76, v76, v76 row_ror:2 row_mask:0xf bank_mask:0xf bound_ctrl:1
	s_nop 1
	v_mov_b32_dpp v78, v76 row_ror:1 row_mask:0xf bank_mask:0xf
	s_and_saveexec_b64 s[8:9], s[44:45]
	v_add_f32_e32 v76, v76, v78
	ds_write_b32 v190, v76 offset:34048
	s_or_b64 exec, exec, s[8:9]
	v_mul_f32_e32 v206, v83, v77
	ds_read_b128 v[96:99], v194 offset:2048
	ds_read_b128 v[92:95], v194 offset:2304
	ds_read_b128 v[124:127], v194 offset:10240
	ds_read_b128 v[108:111], v194 offset:10496
	ds_read_b128 v[88:91], v194 offset:2560
	ds_read_b128 v[76:79], v194 offset:2816
	ds_read_b128 v[112:115], v194 offset:10752
	ds_read_b128 v[104:107], v194 offset:11008
	ds_read2_b32 v[154:155], v196 offset0:66 offset1:82
	ds_read_b32 v83, v190 offset:16512
	s_waitcnt lgkmcnt(14)
	v_mul_f32 v128, v128, v206
	v_mul_f32 v129, v129, v206
	v_mul_f32 v130, v130, v206
	v_mul_f32 v131, v131, v206
	v_mul_f32 v116, v116, v206
	v_mul_f32 v117, v117, v206
	v_mul_f32 v118, v118, v206
	v_mul_f32 v119, v119, v206
	s_waitcnt lgkmcnt(11)
	v_mul_f32 v120, v120, v206
	v_mul_f32 v121, v121, v206
	v_mul_f32 v122, v122, v206
	v_mul_f32 v123, v123, v206
	s_waitcnt lgkmcnt(10)
	v_mul_f32 v100, v100, v206
	v_mul_f32 v101, v101, v206
	v_mul_f32 v102, v102, v206
	v_mul_f32 v103, v103, v206
	v_fma_f32 v206, v81, v82, v128
	v_fma_f32 v207, v81, v132, v129
	v_fma_f32 v208, v81, v133, v130
	v_fma_f32 v209, v81, v134, v131
	v_fma_f32 v210, v81, v135, v116
	v_fma_f32 v211, v81, v156, v117
	v_fma_f32 v212, v81, v157, v118
	v_fma_f32 v198, v81, v198, v119
	v_fma_f32 v199, v81, v199, v120
	v_fma_f32 v200, v81, v200, v121
	v_fma_f32 v201, v81, v201, v122
	v_fma_f32 v202, v81, v202, v123
	v_fma_f32 v203, v81, v203, v100
	v_fma_f32 v204, v81, v204, v101
	v_fma_f32 v205, v81, v205, v102
	v_fma_f32 v213, v81, v80, v103
	v_fma_f32 v80, v84, v206, v140
	v_fma_f32 v81, v85, v207, v140
	v_fma_f32 v82, v86, v208, v140
	v_fma_f32 v84, v87, v209, v140
	v_fma_f32 v72, v72, v210, v80
	v_fma_f32 v73, v73, v211, v81
	v_fma_f32 v74, v74, v212, v82
	v_fma_f32 v75, v75, v198, v84
	v_fma_f32 v68, v68, v199, v72
	v_fma_f32 v69, v69, v200, v73
	v_fma_f32 v70, v70, v201, v74
	v_fma_f32 v71, v71, v202, v75
	v_fma_f32 v64, v64, v203, v68
	v_fma_f32 v65, v65, v204, v69
	v_fma_f32 v66, v66, v205, v70
	v_fma_f32 v67, v67, v213, v71
	v_add_f32_e32 v64, v64, v65
	v_add_f32_e32 v65, v66, v67
	v_add_f32_e32 v64, v64, v65
	v_mov_b32_e32 v65, 0
	s_nop 0
	v_add_f32_dpp v64, v64, v64 row_ror:8 row_mask:0xf bank_mask:0xf bound_ctrl:1
	s_nop 1
	v_add_f32_dpp v64, v64, v64 row_ror:4 row_mask:0xf bank_mask:0xf bound_ctrl:1
	s_nop 1
	v_add_f32_dpp v64, v64, v64 row_ror:2 row_mask:0xf bank_mask:0xf bound_ctrl:1
	s_nop 1
	v_mov_b32_dpp v65, v64 row_ror:1 row_mask:0xf bank_mask:0xf
	s_and_saveexec_b64 s[8:9], s[44:45]
	v_add_f32_e32 v64, v64, v65
	ds_write_b32 v190, v64 offset:34112
	s_or_b64 exec, exec, s[8:9]
	s_waitcnt lgkmcnt(0)
	v_mul_f32_e32 v69, v155, v83
	ds_read_b128 v[100:103], v194 offset:3072
	ds_read_b128 v[80:83], v194 offset:3328
	ds_read_b128 v[132:135], v194 offset:11264
	ds_read_b128 v[120:123], v194 offset:11520
	ds_read_b128 v[72:75], v194 offset:3584
	ds_read_b128 v[64:67], v194 offset:3840
	ds_read_b128 v[128:131], v194 offset:11776
	ds_read_b128 v[116:119], v194 offset:12032
	ds_read2_b32 v[156:157], v196 offset0:67 offset1:83
	ds_read_b32 v68, v190 offset:16576
	v_mul_f32 v70, v124, v69
	v_mul_f32 v71, v125, v69
	v_mul_f32 v84, v126, v69
	v_mul_f32 v85, v127, v69
	v_mul_f32 v86, v108, v69
	v_mul_f32 v87, v109, v69
	v_mul_f32 v108, v110, v69
	v_mul_f32 v109, v111, v69
	v_mul_f32 v110, v112, v69
	v_mul_f32 v111, v113, v69
	v_mul_f32 v124, v114, v69
	v_mul_f32 v125, v115, v69
	v_mul_f32 v104, v104, v69
	v_mul_f32 v105, v105, v69
	v_mul_f32 v106, v106, v69
	v_mul_f32 v69, v107, v69
	v_fma_f32 v112, v154, v206, v70
	v_fma_f32 v113, v154, v207, v71
	v_fma_f32 v115, v154, v209, v85
	v_fma_f32 v114, v154, v208, v84
	v_fma_f32 v206, v154, v210, v86
	v_fma_f32 v209, v154, v213, v69
	v_fma_f32 v69, v96, v112, v140
	v_fma_f32 v70, v97, v113, v140
	v_fma_f32 v207, v154, v211, v87
	v_fma_f32 v71, v98, v114, v140
	v_fma_f32 v208, v154, v212, v108
	v_fma_f32 v199, v154, v199, v110
	v_fma_f32 v69, v92, v206, v69
	v_fma_f32 v200, v154, v200, v111
	v_fma_f32 v70, v93, v207, v70
	v_fma_f32 v84, v99, v115, v140
	v_fma_f32 v71, v94, v208, v71
	v_fma_f32 v198, v154, v198, v109
	v_fma_f32 v69, v88, v199, v69
	v_fma_f32 v201, v154, v201, v124
	v_fma_f32 v70, v89, v200, v70
	v_fma_f32 v203, v154, v203, v104
	v_fma_f32 v204, v154, v204, v105
	v_fma_f32 v84, v95, v198, v84
	v_fma_f32 v202, v154, v202, v125
	v_fma_f32 v71, v90, v201, v71
	v_fma_f32 v205, v154, v205, v106
	v_fma_f32 v69, v76, v203, v69
	v_fma_f32 v70, v77, v204, v70
	v_fma_f32 v84, v91, v202, v84
	v_fma_f32 v71, v78, v205, v71
	v_fma_f32 v76, v79, v209, v84
	v_add_f32_e32 v69, v69, v70
	v_add_f32_e32 v70, v71, v76
	v_add_f32_e32 v69, v69, v70
	v_mov_b32_e32 v70, 0
	s_nop 0
	v_add_f32_dpp v69, v69, v69 row_ror:8 row_mask:0xf bank_mask:0xf bound_ctrl:1
	s_nop 1
	v_add_f32_dpp v69, v69, v69 row_ror:4 row_mask:0xf bank_mask:0xf bound_ctrl:1
	s_nop 1
	v_add_f32_dpp v69, v69, v69 row_ror:2 row_mask:0xf bank_mask:0xf bound_ctrl:1
	s_nop 1
	v_mov_b32_dpp v70, v69 row_ror:1 row_mask:0xf bank_mask:0xf
	s_and_saveexec_b64 s[8:9], s[44:45]
	v_add_f32_e32 v69, v69, v70
	ds_write_b32 v190, v69 offset:34176
	s_or_b64 exec, exec, s[8:9]
	s_waitcnt lgkmcnt(0)
	v_mul_f32_e32 v93, v157, v68
	ds_read_b128 v[88:91], v194 offset:4096
	ds_read_b128 v[84:87], v194 offset:4352
	ds_read_b128 v[124:127], v194 offset:12288
	ds_read_b128 v[104:107], v194 offset:12544
	ds_read_b128 v[76:79], v194 offset:4608
	ds_read_b128 v[68:71], v194 offset:4864
	ds_read_b128 v[108:111], v194 offset:12800
	ds_read_b128 v[96:99], v194 offset:13056
	ds_read2_b32 v[154:155], v196 offset0:68 offset1:84
	ds_read_b32 v92, v190 offset:16640
	v_mul_f32 v94, v132, v93
	v_mul_f32 v95, v133, v93
	v_mul_f32 v132, v134, v93
	v_mul_f32 v133, v135, v93
	v_mul_f32 v120, v120, v93
	v_mul_f32 v121, v121, v93
	v_mul_f32 v122, v122, v93
	v_mul_f32 v123, v123, v93
	v_mul_f32 v128, v128, v93
	v_mul_f32 v129, v129, v93
	v_mul_f32 v210, v130, v93
	v_mul_f32 v211, v131, v93
	v_mul_f32 v116, v116, v93
	v_mul_f32 v117, v117, v93
	v_mul_f32 v118, v118, v93
	v_mul_f32 v93, v119, v93
	v_fma_f32 v130, v156, v112, v94
	v_fma_f32 v131, v156, v113, v95
	v_fma_f32 v132, v156, v114, v132
	v_fma_f32 v133, v156, v115, v133
	v_fma_f32 v134, v156, v206, v120
	v_fma_f32 v135, v156, v207, v121
	v_fma_f32 v157, v156, v208, v122
	v_fma_f32 v198, v156, v198, v123
	v_fma_f32 v199, v156, v199, v128
	v_fma_f32 v200, v156, v200, v129
	v_fma_f32 v201, v156, v201, v210
	v_fma_f32 v202, v156, v202, v211
	v_fma_f32 v203, v156, v203, v116
	v_fma_f32 v204, v156, v204, v117
	v_fma_f32 v205, v156, v205, v118
	v_fma_f32 v156, v156, v209, v93
	v_fma_f32 v93, v100, v130, v140
	v_fma_f32 v94, v101, v131, v140
	v_fma_f32 v95, v102, v132, v140
	v_fma_f32 v100, v103, v133, v140
	v_fma_f32 v80, v80, v134, v93
	v_fma_f32 v81, v81, v135, v94
	v_fma_f32 v82, v82, v157, v95
	v_fma_f32 v83, v83, v198, v100
	v_fma_f32 v72, v72, v199, v80
	v_fma_f32 v73, v73, v200, v81
	v_fma_f32 v74, v74, v201, v82
	v_fma_f32 v75, v75, v202, v83
	v_fma_f32 v64, v64, v203, v72
	v_fma_f32 v65, v65, v204, v73
	v_fma_f32 v66, v66, v205, v74
	v_fma_f32 v67, v67, v156, v75
	v_add_f32_e32 v64, v64, v65
	v_add_f32_e32 v65, v66, v67
	v_add_f32_e32 v64, v64, v65
	v_mov_b32_e32 v65, 0
	s_nop 0
	v_add_f32_dpp v64, v64, v64 row_ror:8 row_mask:0xf bank_mask:0xf bound_ctrl:1
	s_nop 1
	v_add_f32_dpp v64, v64, v64 row_ror:4 row_mask:0xf bank_mask:0xf bound_ctrl:1
	s_nop 1
	v_add_f32_dpp v64, v64, v64 row_ror:2 row_mask:0xf bank_mask:0xf bound_ctrl:1
	s_nop 1
	v_mov_b32_dpp v65, v64 row_ror:1 row_mask:0xf bank_mask:0xf
	s_and_saveexec_b64 s[8:9], s[44:45]
	v_add_f32_e32 v64, v64, v65
	ds_write_b32 v190, v64 offset:34240
	s_or_b64 exec, exec, s[8:9]
	s_waitcnt lgkmcnt(0)
	v_mul_f32_e32 v155, v155, v92
	ds_read_b128 v[92:95], v194 offset:5120
	ds_read_b128 v[80:83], v194 offset:5376
	ds_read_b128 v[120:123], v194 offset:13312
	ds_read_b128 v[112:115], v194 offset:13568
	ds_read_b128 v[72:75], v194 offset:5632
	ds_read_b128 v[64:67], v194 offset:5888
	ds_read_b128 v[116:119], v194 offset:13824
	ds_read_b128 v[100:103], v194 offset:14080
	ds_read2_b32 v[128:129], v196 offset0:69 offset1:85
	ds_read_b32 v207, v190 offset:16704
	v_mul_f32 v124, v124, v155
	v_mul_f32 v125, v125, v155
	v_mul_f32 v126, v126, v155
	v_mul_f32 v127, v127, v155
	v_mul_f32 v104, v104, v155
	v_mul_f32 v105, v105, v155
	v_mul_f32 v106, v106, v155
	v_mul_f32 v107, v107, v155
	v_mul_f32 v108, v108, v155
	v_mul_f32 v109, v109, v155
	v_mul_f32 v110, v110, v155
	v_mul_f32 v111, v111, v155
	v_mul_f32 v96, v96, v155
	v_mul_f32 v97, v97, v155
	v_mul_f32 v98, v98, v155
	v_mul_f32 v99, v99, v155
	v_fma_f32 v155, v154, v130, v124
	v_fma_f32 v206, v154, v131, v125
	v_fma_f32 v134, v154, v134, v104
	v_fma_f32 v135, v154, v135, v105
	v_fma_f32 v199, v154, v199, v108
	v_fma_f32 v200, v154, v200, v109
	v_fma_f32 v203, v154, v203, v96
	v_fma_f32 v204, v154, v204, v97
	v_fma_f32 v88, v88, v155, v140
	v_fma_f32 v89, v89, v206, v140
	v_fma_f32 v132, v154, v132, v126
	v_fma_f32 v133, v154, v133, v127
	v_fma_f32 v157, v154, v157, v106
	v_fma_f32 v198, v154, v198, v107
	v_fma_f32 v84, v84, v134, v88
	v_fma_f32 v85, v85, v135, v89
	v_fma_f32 v201, v154, v201, v110
	v_fma_f32 v202, v154, v202, v111
	v_fma_f32 v205, v154, v205, v98
	v_fma_f32 v154, v154, v156, v99
	v_fma_f32 v76, v76, v199, v84
	v_fma_f32 v77, v77, v200, v85
	v_fma_f32 v90, v90, v132, v140
	v_fma_f32 v91, v91, v133, v140
	v_fma_f32 v68, v68, v203, v76
	v_fma_f32 v69, v69, v204, v77
	v_fma_f32 v86, v86, v157, v90
	v_fma_f32 v87, v87, v198, v91
	v_fma_f32 v78, v78, v201, v86
	v_fma_f32 v79, v79, v202, v87
	v_add_f32_e32 v68, v68, v69
	v_fma_f32 v70, v70, v205, v78
	v_fma_f32 v71, v71, v154, v79
	v_add_f32_e32 v69, v70, v71
	v_add_f32_e32 v68, v68, v69
	v_mov_b32_e32 v69, 0
	s_nop 0
	v_add_f32_dpp v68, v68, v68 row_ror:8 row_mask:0xf bank_mask:0xf bound_ctrl:1
	s_nop 1
	v_add_f32_dpp v68, v68, v68 row_ror:4 row_mask:0xf bank_mask:0xf bound_ctrl:1
	s_nop 1
	v_add_f32_dpp v68, v68, v68 row_ror:2 row_mask:0xf bank_mask:0xf bound_ctrl:1
	s_nop 1
	v_mov_b32_dpp v69, v68 row_ror:1 row_mask:0xf bank_mask:0xf
	s_and_saveexec_b64 s[8:9], s[44:45]
	v_add_f32_e32 v68, v68, v69
	ds_write_b32 v190, v68 offset:34304
	s_or_b64 exec, exec, s[8:9]
	s_waitcnt lgkmcnt(0)
	v_mul_f32_e32 v156, v129, v207
	ds_read_b128 v[88:91], v194 offset:6144
	ds_read_b128 v[84:87], v194 offset:6400
	ds_read_b128 v[124:127], v194 offset:14336
	ds_read_b128 v[104:107], v194 offset:14592
	ds_read_b128 v[76:79], v194 offset:6656
	ds_read_b128 v[68:71], v194 offset:6912
	ds_read_b128 v[108:111], v194 offset:14848
	ds_read_b128 v[96:99], v194 offset:15104
	ds_read2_b32 v[130:131], v196 offset0:70 offset1:86
	ds_read_b32 v129, v190 offset:16768
	v_mul_f32 v120, v120, v156
	v_mul_f32 v121, v121, v156
	v_mul_f32 v122, v122, v156
	v_mul_f32 v123, v123, v156
	v_mul_f32 v112, v112, v156
	v_mul_f32 v113, v113, v156
	v_mul_f32 v114, v114, v156
	v_mul_f32 v115, v115, v156
	v_mul_f32 v116, v116, v156
	v_mul_f32 v117, v117, v156
	v_mul_f32 v118, v118, v156
	v_mul_f32 v119, v119, v156
	v_mul_f32 v100, v100, v156
	v_mul_f32 v101, v101, v156
	v_mul_f32 v102, v102, v156
	v_mul_f32 v103, v103, v156
	v_fma_f32 v155, v128, v155, v120
	v_fma_f32 v156, v128, v206, v121
	v_fma_f32 v134, v128, v134, v112
	v_fma_f32 v135, v128, v135, v113
	v_fma_f32 v199, v128, v199, v116
	v_fma_f32 v200, v128, v200, v117
	v_fma_f32 v203, v128, v203, v100
	v_fma_f32 v204, v128, v204, v101
	v_fma_f32 v92, v92, v155, v140
	v_fma_f32 v93, v93, v156, v140
	v_fma_f32 v132, v128, v132, v122
	v_fma_f32 v133, v128, v133, v123
	v_fma_f32 v157, v128, v157, v114
	v_fma_f32 v198, v128, v198, v115
	v_fma_f32 v80, v80, v134, v92
	v_fma_f32 v81, v81, v135, v93
	v_fma_f32 v201, v128, v201, v118
	v_fma_f32 v202, v128, v202, v119
	v_fma_f32 v205, v128, v205, v102
	v_fma_f32 v154, v128, v154, v103
	v_fma_f32 v72, v72, v199, v80
	v_fma_f32 v73, v73, v200, v81
	v_fma_f32 v94, v94, v132, v140
	v_fma_f32 v95, v95, v133, v140
	v_fma_f32 v64, v64, v203, v72
	v_fma_f32 v65, v65, v204, v73
	v_fma_f32 v82, v82, v157, v94
	v_fma_f32 v83, v83, v198, v95
	v_fma_f32 v74, v74, v201, v82
	v_fma_f32 v75, v75, v202, v83
	v_add_f32_e32 v64, v64, v65
	v_fma_f32 v66, v66, v205, v74
	v_fma_f32 v67, v67, v154, v75
	v_add_f32_e32 v65, v66, v67
	v_add_f32_e32 v64, v64, v65
	v_mov_b32_e32 v65, 0
	s_nop 0
	v_add_f32_dpp v64, v64, v64 row_ror:8 row_mask:0xf bank_mask:0xf bound_ctrl:1
	s_nop 1
	v_add_f32_dpp v64, v64, v64 row_ror:4 row_mask:0xf bank_mask:0xf bound_ctrl:1
	s_nop 1
	v_add_f32_dpp v64, v64, v64 row_ror:2 row_mask:0xf bank_mask:0xf bound_ctrl:1
	s_nop 1
	v_mov_b32_dpp v65, v64 row_ror:1 row_mask:0xf bank_mask:0xf
	s_and_saveexec_b64 s[8:9], s[44:45]
	v_add_f32_e32 v64, v64, v65
	ds_write_b32 v190, v64 offset:34368
	s_or_b64 exec, exec, s[8:9]
	s_waitcnt lgkmcnt(0)
	v_mul_f32_e32 v206, v131, v129
	ds_read_b128 v[92:95], v194 offset:7168
	ds_read_b128 v[80:83], v194 offset:7424
	ds_read_b128 v[120:123], v194 offset:15360
	ds_read_b128 v[112:115], v194 offset:15616
	ds_read_b128 v[72:75], v194 offset:7680
	ds_read_b128 v[64:67], v194 offset:7936
	ds_read_b128 v[116:119], v194 offset:15872
	ds_read_b128 v[100:103], v194 offset:16128
	ds_read2_b32 v[128:129], v196 offset0:71 offset1:87
	ds_read_b32 v131, v190 offset:16832
	v_mul_f32 v125, v125, v206
	v_mul_f32 v126, v126, v206
	v_mul_f32 v104, v104, v206
	v_mul_f32 v124, v124, v206
	v_mul_f32 v127, v127, v206
	v_mul_f32 v105, v105, v206
	v_mul_f32 v106, v106, v206
	v_mul_f32 v107, v107, v206
	v_mul_f32 v108, v108, v206
	v_mul_f32 v109, v109, v206
	v_mul_f32 v207, v110, v206
	v_mul_f32 v208, v111, v206
	v_mul_f32 v209, v96, v206
	v_mul_f32 v210, v97, v206
	v_mul_f32 v211, v98, v206
	v_mul_f32 v206, v99, v206
	v_fma_f32 v96, v130, v155, v124
	v_fma_f32 v97, v130, v156, v125
	v_fma_f32 v98, v130, v132, v126
	v_fma_f32 v99, v130, v133, v127
	v_fma_f32 v104, v130, v134, v104
	v_fma_f32 v110, v130, v135, v105
	v_fma_f32 v125, v130, v199, v108
	v_fma_f32 v126, v130, v200, v109
	v_fma_f32 v133, v130, v203, v209
	v_fma_f32 v134, v130, v204, v210
	v_fma_f32 v88, v88, v96, v140
	v_fma_f32 v89, v89, v97, v140
	v_fma_f32 v111, v130, v157, v106
	v_fma_f32 v124, v130, v198, v107
	v_fma_f32 v127, v130, v201, v207
	v_fma_f32 v132, v130, v202, v208
	v_fma_f32 v84, v84, v104, v88
	v_fma_f32 v85, v85, v110, v89
	v_fma_f32 v135, v130, v205, v211
	v_fma_f32 v130, v130, v154, v206
	v_fma_f32 v90, v90, v98, v140
	v_fma_f32 v91, v91, v99, v140
	v_fma_f32 v76, v76, v125, v84
	v_fma_f32 v77, v77, v126, v85
	v_fma_f32 v68, v68, v133, v76
	v_fma_f32 v69, v69, v134, v77
	v_fma_f32 v86, v86, v111, v90
	v_fma_f32 v87, v87, v124, v91
	v_fma_f32 v78, v78, v127, v86
	v_fma_f32 v79, v79, v132, v87
	v_add_f32_e32 v68, v68, v69
	v_fma_f32 v70, v70, v135, v78
	v_fma_f32 v71, v71, v130, v79
	v_add_f32_e32 v69, v70, v71
	v_add_f32_e32 v68, v68, v69
	v_mov_b32_e32 v69, 0
	s_nop 0
	v_add_f32_dpp v68, v68, v68 row_ror:8 row_mask:0xf bank_mask:0xf bound_ctrl:1
	s_nop 1
	v_add_f32_dpp v68, v68, v68 row_ror:4 row_mask:0xf bank_mask:0xf bound_ctrl:1
	s_nop 1
	v_add_f32_dpp v68, v68, v68 row_ror:2 row_mask:0xf bank_mask:0xf bound_ctrl:1
	s_nop 1
	v_mov_b32_dpp v69, v68 row_ror:1 row_mask:0xf bank_mask:0xf
	s_and_saveexec_b64 s[8:9], s[44:45]
	v_add_f32_e32 v68, v68, v69
	ds_write_b32 v190, v68 offset:34432
	s_or_b64 exec, exec, s[8:9]
	s_waitcnt lgkmcnt(0)
	v_mul_f32_e32 v68, v129, v131
	v_mul_f32 v69, v120, v68
	v_mul_f32 v70, v121, v68
	v_mul_f32 v71, v122, v68
	v_mul_f32 v76, v123, v68
	v_mul_f32 v77, v112, v68
	v_mul_f32 v78, v113, v68
	v_mul_f32 v79, v114, v68
	v_mul_f32 v84, v115, v68
	v_mul_f32 v85, v116, v68
	v_mul_f32 v86, v117, v68
	v_mul_f32 v87, v118, v68
	v_mul_f32 v88, v119, v68
	v_mul_f32 v89, v100, v68
	v_mul_f32 v100, v101, v68
	v_mul_f32 v101, v102, v68
	v_mul_f32 v68, v103, v68
	v_fma_f32 v109, v128, v96, v69
	v_fma_f32 v108, v128, v97, v70
	v_fma_f32 v105, v128, v104, v77
	v_fma_f32 v104, v128, v110, v78
	v_fma_f32 v107, v128, v98, v71
	v_fma_f32 v78, v128, v130, v68
	v_fma_f32 v68, v92, v109, v140
	v_fma_f32 v69, v93, v108, v140
	v_fma_f32 v106, v128, v99, v76
	v_fma_f32 v99, v128, v111, v79
	v_fma_f32 v70, v94, v107, v140
	v_fma_f32 v98, v128, v124, v84
	v_fma_f32 v68, v80, v105, v68
	v_fma_f32 v69, v81, v104, v69
	v_fma_f32 v71, v95, v106, v140
	v_fma_f32 v97, v128, v125, v85
	v_fma_f32 v96, v128, v126, v86
	v_fma_f32 v90, v128, v132, v88
	v_fma_f32 v89, v128, v133, v89
	v_fma_f32 v88, v128, v134, v100
	v_fma_f32 v70, v82, v99, v70
	v_fma_f32 v71, v83, v98, v71
	v_fma_f32 v68, v72, v97, v68
	v_fma_f32 v69, v73, v96, v69
	v_fma_f32 v91, v128, v127, v87
	v_fma_f32 v79, v128, v135, v101
	v_fma_f32 v71, v75, v90, v71
	v_fma_f32 v64, v64, v89, v68
	v_fma_f32 v65, v65, v88, v69
	v_fma_f32 v70, v74, v91, v70
	v_fma_f32 v66, v66, v79, v70
	v_fma_f32 v67, v67, v78, v71
	v_add_f32_e32 v64, v64, v65
	v_add_f32_e32 v65, v66, v67
	v_add_f32_e32 v64, v64, v65
	v_mov_b32_e32 v65, 0
	s_nop 0
	v_add_f32_dpp v64, v64, v64 row_ror:8 row_mask:0xf bank_mask:0xf bound_ctrl:1
	s_nop 1
	v_add_f32_dpp v64, v64, v64 row_ror:4 row_mask:0xf bank_mask:0xf bound_ctrl:1
	s_nop 1
	v_add_f32_dpp v64, v64, v64 row_ror:2 row_mask:0xf bank_mask:0xf bound_ctrl:1
	s_nop 1
	v_mov_b32_dpp v65, v64 row_ror:1 row_mask:0xf bank_mask:0xf
	s_and_saveexec_b64 s[8:9], s[44:45]
	v_add_f32_e32 v64, v64, v65
	ds_write_b32 v190, v64 offset:34496
	s_or_b64 exec, exec, s[8:9]
	s_waitcnt vmcnt(3)
	ds_write_b128 v188, v[48:51] offset:17024
	s_waitcnt vmcnt(1)
	ds_write_b128 v191, v[56:59] offset:17024
	ds_write_b128 v188, v[52:55] offset:25216
	s_waitcnt vmcnt(0)
	ds_write_b128 v191, v[60:63] offset:25216
	s_and_saveexec_b64 s[8:9], s[40:41]
	ds_write_b32 v145, v192 offset:33408
	s_or_b64 exec, exec, s[8:9]
	s_and_saveexec_b64 s[8:9], s[42:43]
	s_cbranch_execz .LBB0_1242
	v_add_f32_e32 v64, v178, v195
	v_mul_f32_e64 v65, |v64|, s62
	v_exp_f32_e32 v65, v65
	v_min_f32_e32 v64, 0, v64
	v_add_f32_e32 v65, 1.0, v65
	v_cmp_gt_f32_e32 vcc, s5, v65
	s_nop 1
	v_cndmask_b32_e64 v66, 0, 32, vcc
	v_ldexp_f32 v65, v65, v66
	v_log_f32_e32 v65, v65
	v_cndmask_b32_e32 v67, 0, v171, vcc
	v_add_f32_e32 v66, v147, v193
	v_mul_f32_e32 v68, 0x3f317217, v65
	v_fma_f32 v68, v65, s76, -v68
	v_fmac_f32_e32 v68, 0x3377d1cf, v65
	v_fmac_f32_e32 v68, 0x3f317217, v65
	v_cmp_lt_f32_e64 vcc, |v65|, s77
	s_nop 1
	v_cndmask_b32_e32 v65, v65, v68, vcc
	v_sub_f32_e32 v65, v65, v67
	v_sub_f32_e32 v64, v64, v65
	v_add_u32_e32 v65, 0x8400, v145
	ds_write2_b32 v65, v66, v64 offset0:32 offset1:48

.LBB0_1255:
	s_or_b64 exec, exec, s[8:9]
	s_waitcnt lgkmcnt(0)
	s_barrier
	ds_read_b128 v[92:95], v194 offset:17024
	ds_read_b128 v[110:113], v194 offset:17280
	ds_read_b128 v[124:127], v194 offset:25216
	ds_read_b128 v[132:135], v194 offset:25472
	ds_read2_b64 v[80:83], v196 offset0:32 offset1:40
	ds_read2_b32 v[76:77], v197 offset0:160 offset1:176
	ds_read_b128 v[206:209], v194 offset:17536
	ds_read_b128 v[210:213], v194 offset:17792
	ds_read_b128 v[154:157], v194 offset:25728
	ds_read_b128 v[198:201], v194 offset:25984
	s_waitcnt lgkmcnt(4)
	v_mul_f32_e32 v76, v82, v76
	v_mul_f32 v82, v124, v76
	v_mul_f32 v114, v125, v76
	v_mul_f32 v115, v126, v76
	v_mul_f32 v124, v127, v76
	v_mul_f32 v125, v132, v76
	v_mul_f32 v126, v133, v76
	v_mul_f32 v127, v134, v76
	v_mul_f32 v197, v135, v76
	s_waitcnt lgkmcnt(1)
	v_mul_f32 v154, v154, v76
	v_mul_f32 v155, v155, v76
	v_mul_f32 v202, v156, v76
	v_mul_f32 v203, v157, v76
	s_waitcnt lgkmcnt(0)
	v_mul_f32 v204, v198, v76
	v_mul_f32 v205, v199, v76
	v_mul_f32 v214, v200, v76
	v_mul_f32 v76, v201, v76
	ds_read_b128 v[84:87], v194 offset:18048
	ds_read_b128 v[72:75], v194 offset:18304
	ds_read_b128 v[128:131], v194 offset:26240
	ds_read_b128 v[116:119], v194 offset:26496
	ds_read_b128 v[68:71], v194 offset:18560
	ds_read_b128 v[64:67], v194 offset:18816
	ds_read_b128 v[120:123], v194 offset:26752
	ds_read_b128 v[100:103], v194 offset:27008
	v_fma_f32 v82, v80, v109, v82
	v_fma_f32 v132, v80, v108, v114
	v_fma_f32 v133, v80, v107, v115
	v_fma_f32 v134, v80, v106, v124
	v_fma_f32 v135, v80, v105, v125
	v_fma_f32 v156, v80, v104, v126
	v_fma_f32 v157, v80, v99, v127
	v_fma_f32 v197, v80, v98, v197
	v_fma_f32 v198, v80, v97, v154
	v_fma_f32 v199, v80, v96, v155
	v_fma_f32 v200, v80, v91, v202
	v_fma_f32 v201, v80, v90, v203
	v_fma_f32 v202, v80, v89, v204
	v_fma_f32 v203, v80, v88, v205
	v_fma_f32 v204, v80, v79, v214
	v_fma_f32 v80, v80, v78, v76
	v_fma_f32 v76, v92, v82, v140
	v_fma_f32 v78, v93, v132, v140
	v_fma_f32 v79, v94, v133, v140
	v_fma_f32 v88, v95, v134, v140
	v_fma_f32 v76, v110, v135, v76
	v_fma_f32 v78, v111, v156, v78
	v_fma_f32 v79, v112, v157, v79
	v_fma_f32 v88, v113, v197, v88
	v_fma_f32 v76, v206, v198, v76
	v_fma_f32 v78, v207, v199, v78
	v_fma_f32 v79, v208, v200, v79
	v_fma_f32 v88, v209, v201, v88
	v_fma_f32 v76, v210, v202, v76
	v_fma_f32 v78, v211, v203, v78
	v_fma_f32 v79, v212, v204, v79
	v_fma_f32 v88, v213, v80, v88
	v_add_f32_e32 v76, v76, v78
	v_add_f32_e32 v78, v79, v88
	v_add_f32_e32 v76, v76, v78
	v_mov_b32_e32 v78, 0
	s_nop 0
	v_add_f32_dpp v76, v76, v76 row_ror:8 row_mask:0xf bank_mask:0xf bound_ctrl:1
	s_nop 1
	v_add_f32_dpp v76, v76, v76 row_ror:4 row_mask:0xf bank_mask:0xf bound_ctrl:1
	s_nop 1
	v_add_f32_dpp v76, v76, v76 row_ror:2 row_mask:0xf bank_mask:0xf bound_ctrl:1
	s_nop 1
	v_mov_b32_dpp v78, v76 row_ror:1 row_mask:0xf bank_mask:0xf
	s_and_saveexec_b64 s[8:9], s[44:45]
	v_add_f32_e32 v76, v76, v78
	ds_write_b32 v190, v76 offset:34560
	s_or_b64 exec, exec, s[8:9]
	v_mul_f32_e32 v205, v83, v77
	ds_read_b128 v[96:99], v194 offset:19072
	ds_read_b128 v[92:95], v194 offset:19328
	ds_read_b128 v[124:127], v194 offset:27264
	ds_read_b128 v[108:111], v194 offset:27520
	ds_read_b128 v[88:91], v194 offset:19584
	ds_read_b128 v[76:79], v194 offset:19840
	ds_read_b128 v[112:115], v194 offset:27776
	ds_read_b128 v[104:107], v194 offset:28032
	ds_read2_b32 v[154:155], v196 offset0:66 offset1:82
	ds_read_b32 v83, v190 offset:33536
	s_waitcnt lgkmcnt(14)
	v_mul_f32 v128, v128, v205
	v_mul_f32 v129, v129, v205
	v_mul_f32 v130, v130, v205
	v_mul_f32 v131, v131, v205
	v_mul_f32 v116, v116, v205
	v_mul_f32 v117, v117, v205
	v_mul_f32 v118, v118, v205
	v_mul_f32 v119, v119, v205
	s_waitcnt lgkmcnt(11)
	v_mul_f32 v120, v120, v205
	v_mul_f32 v121, v121, v205
	v_mul_f32 v122, v122, v205
	v_mul_f32 v123, v123, v205
	s_waitcnt lgkmcnt(10)
	v_mul_f32 v100, v100, v205
	v_mul_f32 v101, v101, v205
	v_mul_f32 v102, v102, v205
	v_mul_f32 v103, v103, v205
	v_fma_f32 v205, v81, v82, v128
	v_fma_f32 v206, v81, v132, v129
	v_fma_f32 v207, v81, v133, v130
	v_fma_f32 v208, v81, v134, v131
	v_fma_f32 v209, v81, v135, v116
	v_fma_f32 v210, v81, v156, v117
	v_fma_f32 v211, v81, v157, v118
	v_fma_f32 v197, v81, v197, v119
	v_fma_f32 v198, v81, v198, v120
	v_fma_f32 v199, v81, v199, v121
	v_fma_f32 v200, v81, v200, v122
	v_fma_f32 v201, v81, v201, v123
	v_fma_f32 v202, v81, v202, v100
	v_fma_f32 v203, v81, v203, v101
	v_fma_f32 v204, v81, v204, v102
	v_fma_f32 v212, v81, v80, v103
	v_fma_f32 v80, v84, v205, v140
	v_fma_f32 v81, v85, v206, v140
	v_fma_f32 v82, v86, v207, v140
	v_fma_f32 v84, v87, v208, v140
	v_fma_f32 v72, v72, v209, v80
	v_fma_f32 v73, v73, v210, v81
	v_fma_f32 v74, v74, v211, v82
	v_fma_f32 v75, v75, v197, v84
	v_fma_f32 v68, v68, v198, v72
	v_fma_f32 v69, v69, v199, v73
	v_fma_f32 v70, v70, v200, v74
	v_fma_f32 v71, v71, v201, v75
	v_fma_f32 v64, v64, v202, v68
	v_fma_f32 v65, v65, v203, v69
	v_fma_f32 v66, v66, v204, v70
	v_fma_f32 v67, v67, v212, v71
	v_add_f32_e32 v64, v64, v65
	v_add_f32_e32 v65, v66, v67
	v_add_f32_e32 v64, v64, v65
	v_mov_b32_e32 v65, 0
	s_nop 0
	v_add_f32_dpp v64, v64, v64 row_ror:8 row_mask:0xf bank_mask:0xf bound_ctrl:1
	s_nop 1
	v_add_f32_dpp v64, v64, v64 row_ror:4 row_mask:0xf bank_mask:0xf bound_ctrl:1
	s_nop 1
	v_add_f32_dpp v64, v64, v64 row_ror:2 row_mask:0xf bank_mask:0xf bound_ctrl:1
	s_nop 1
	v_mov_b32_dpp v65, v64 row_ror:1 row_mask:0xf bank_mask:0xf
	s_and_saveexec_b64 s[8:9], s[44:45]
	v_add_f32_e32 v64, v64, v65
	ds_write_b32 v190, v64 offset:34624
	s_or_b64 exec, exec, s[8:9]
	s_waitcnt lgkmcnt(0)
	v_mul_f32_e32 v69, v155, v83
	ds_read_b128 v[100:103], v194 offset:20096
	ds_read_b128 v[80:83], v194 offset:20352
	ds_read_b128 v[132:135], v194 offset:28288
	ds_read_b128 v[120:123], v194 offset:28544
	ds_read_b128 v[72:75], v194 offset:20608
	ds_read_b128 v[64:67], v194 offset:20864
	ds_read_b128 v[128:131], v194 offset:28800
	ds_read_b128 v[116:119], v194 offset:29056
	ds_read2_b32 v[156:157], v196 offset0:67 offset1:83
	ds_read_b32 v68, v190 offset:33600
	v_mul_f32 v70, v124, v69
	v_mul_f32 v71, v125, v69
	v_mul_f32 v84, v126, v69
	v_mul_f32 v85, v127, v69
	v_mul_f32 v86, v108, v69
	v_mul_f32 v87, v109, v69
	v_mul_f32 v108, v110, v69
	v_mul_f32 v109, v111, v69
	v_mul_f32 v110, v112, v69
	v_mul_f32 v111, v113, v69
	v_mul_f32 v124, v114, v69
	v_mul_f32 v125, v115, v69
	v_mul_f32 v104, v104, v69
	v_mul_f32 v105, v105, v69
	v_mul_f32 v106, v106, v69
	v_mul_f32 v69, v107, v69
	v_fma_f32 v112, v154, v205, v70
	v_fma_f32 v113, v154, v206, v71
	v_fma_f32 v115, v154, v208, v85
	v_fma_f32 v114, v154, v207, v84
	v_fma_f32 v205, v154, v209, v86
	v_fma_f32 v208, v154, v212, v69
	v_fma_f32 v69, v96, v112, v140
	v_fma_f32 v70, v97, v113, v140
	v_fma_f32 v206, v154, v210, v87
	v_fma_f32 v71, v98, v114, v140
	v_fma_f32 v207, v154, v211, v108
	v_fma_f32 v198, v154, v198, v110
	v_fma_f32 v69, v92, v205, v69
	v_fma_f32 v199, v154, v199, v111
	v_fma_f32 v70, v93, v206, v70
	v_fma_f32 v84, v99, v115, v140
	v_fma_f32 v71, v94, v207, v71
	v_fma_f32 v197, v154, v197, v109
	v_fma_f32 v69, v88, v198, v69
	v_fma_f32 v200, v154, v200, v124
	v_fma_f32 v70, v89, v199, v70
	v_fma_f32 v202, v154, v202, v104
	v_fma_f32 v203, v154, v203, v105
	v_fma_f32 v84, v95, v197, v84
	v_fma_f32 v201, v154, v201, v125
	v_fma_f32 v71, v90, v200, v71
	v_fma_f32 v204, v154, v204, v106
	v_fma_f32 v69, v76, v202, v69
	v_fma_f32 v70, v77, v203, v70
	v_fma_f32 v84, v91, v201, v84
	v_fma_f32 v71, v78, v204, v71
	v_fma_f32 v76, v79, v208, v84
	v_add_f32_e32 v69, v69, v70
	v_add_f32_e32 v70, v71, v76
	v_add_f32_e32 v69, v69, v70
	v_mov_b32_e32 v70, 0
	s_nop 0
	v_add_f32_dpp v69, v69, v69 row_ror:8 row_mask:0xf bank_mask:0xf bound_ctrl:1
	s_nop 1
	v_add_f32_dpp v69, v69, v69 row_ror:4 row_mask:0xf bank_mask:0xf bound_ctrl:1
	s_nop 1
	v_add_f32_dpp v69, v69, v69 row_ror:2 row_mask:0xf bank_mask:0xf bound_ctrl:1
	s_nop 1
	v_mov_b32_dpp v70, v69 row_ror:1 row_mask:0xf bank_mask:0xf
	s_and_saveexec_b64 s[8:9], s[44:45]
	v_add_f32_e32 v69, v69, v70
	ds_write_b32 v190, v69 offset:34688
	s_or_b64 exec, exec, s[8:9]
	s_waitcnt lgkmcnt(0)
	v_mul_f32_e32 v93, v157, v68
	ds_read_b128 v[88:91], v194 offset:21120
	ds_read_b128 v[84:87], v194 offset:21376
	ds_read_b128 v[124:127], v194 offset:29312
	ds_read_b128 v[104:107], v194 offset:29568
	ds_read_b128 v[76:79], v194 offset:21632
	ds_read_b128 v[68:71], v194 offset:21888
	ds_read_b128 v[108:111], v194 offset:29824
	ds_read_b128 v[96:99], v194 offset:30080
	ds_read2_b32 v[154:155], v196 offset0:68 offset1:84
	ds_read_b32 v92, v190 offset:33664
	v_mul_f32 v94, v132, v93
	v_mul_f32 v95, v133, v93
	v_mul_f32 v132, v134, v93
	v_mul_f32 v133, v135, v93
	v_mul_f32 v120, v120, v93
	v_mul_f32 v121, v121, v93
	v_mul_f32 v122, v122, v93
	v_mul_f32 v123, v123, v93
	v_mul_f32 v128, v128, v93
	v_mul_f32 v129, v129, v93
	v_mul_f32 v209, v130, v93
	v_mul_f32 v210, v131, v93
	v_mul_f32 v116, v116, v93
	v_mul_f32 v117, v117, v93
	v_mul_f32 v118, v118, v93
	v_mul_f32 v93, v119, v93
	v_fma_f32 v130, v156, v112, v94
	v_fma_f32 v131, v156, v113, v95
	v_fma_f32 v132, v156, v114, v132
	v_fma_f32 v133, v156, v115, v133
	v_fma_f32 v134, v156, v205, v120
	v_fma_f32 v135, v156, v206, v121
	v_fma_f32 v157, v156, v207, v122
	v_fma_f32 v197, v156, v197, v123
	v_fma_f32 v198, v156, v198, v128
	v_fma_f32 v199, v156, v199, v129
	v_fma_f32 v200, v156, v200, v209
	v_fma_f32 v201, v156, v201, v210
	v_fma_f32 v202, v156, v202, v116
	v_fma_f32 v203, v156, v203, v117
	v_fma_f32 v204, v156, v204, v118
	v_fma_f32 v156, v156, v208, v93
	v_fma_f32 v93, v100, v130, v140
	v_fma_f32 v94, v101, v131, v140
	v_fma_f32 v95, v102, v132, v140
	v_fma_f32 v100, v103, v133, v140
	v_fma_f32 v80, v80, v134, v93
	v_fma_f32 v81, v81, v135, v94
	v_fma_f32 v82, v82, v157, v95
	v_fma_f32 v83, v83, v197, v100
	v_fma_f32 v72, v72, v198, v80
	v_fma_f32 v73, v73, v199, v81
	v_fma_f32 v74, v74, v200, v82
	v_fma_f32 v75, v75, v201, v83
	v_fma_f32 v64, v64, v202, v72
	v_fma_f32 v65, v65, v203, v73
	v_fma_f32 v66, v66, v204, v74
	v_fma_f32 v67, v67, v156, v75
	v_add_f32_e32 v64, v64, v65
	v_add_f32_e32 v65, v66, v67
	v_add_f32_e32 v64, v64, v65
	v_mov_b32_e32 v65, 0
	s_nop 0
	v_add_f32_dpp v64, v64, v64 row_ror:8 row_mask:0xf bank_mask:0xf bound_ctrl:1
	s_nop 1
	v_add_f32_dpp v64, v64, v64 row_ror:4 row_mask:0xf bank_mask:0xf bound_ctrl:1
	s_nop 1
	v_add_f32_dpp v64, v64, v64 row_ror:2 row_mask:0xf bank_mask:0xf bound_ctrl:1
	s_nop 1
	v_mov_b32_dpp v65, v64 row_ror:1 row_mask:0xf bank_mask:0xf
	s_and_saveexec_b64 s[8:9], s[44:45]
	v_add_f32_e32 v64, v64, v65
	ds_write_b32 v190, v64 offset:34752
	s_or_b64 exec, exec, s[8:9]
	s_waitcnt lgkmcnt(0)
	v_mul_f32_e32 v155, v155, v92
	ds_read_b128 v[92:95], v194 offset:22144
	ds_read_b128 v[80:83], v194 offset:22400
	ds_read_b128 v[120:123], v194 offset:30336
	ds_read_b128 v[112:115], v194 offset:30592
	ds_read_b128 v[72:75], v194 offset:22656
	ds_read_b128 v[64:67], v194 offset:22912
	ds_read_b128 v[116:119], v194 offset:30848
	ds_read_b128 v[100:103], v194 offset:31104
	ds_read2_b32 v[128:129], v196 offset0:69 offset1:85
	ds_read_b32 v206, v190 offset:33728
	v_mul_f32 v124, v124, v155
	v_mul_f32 v125, v125, v155
	v_mul_f32 v126, v126, v155
	v_mul_f32 v127, v127, v155
	v_mul_f32 v104, v104, v155
	v_mul_f32 v105, v105, v155
	v_mul_f32 v106, v106, v155
	v_mul_f32 v107, v107, v155
	v_mul_f32 v108, v108, v155
	v_mul_f32 v109, v109, v155
	v_mul_f32 v110, v110, v155
	v_mul_f32 v111, v111, v155
	v_mul_f32 v96, v96, v155
	v_mul_f32 v97, v97, v155
	v_mul_f32 v98, v98, v155
	v_mul_f32 v99, v99, v155
	v_fma_f32 v155, v154, v130, v124
	v_fma_f32 v205, v154, v131, v125
	v_fma_f32 v134, v154, v134, v104
	v_fma_f32 v135, v154, v135, v105
	v_fma_f32 v198, v154, v198, v108
	v_fma_f32 v199, v154, v199, v109
	v_fma_f32 v202, v154, v202, v96
	v_fma_f32 v203, v154, v203, v97
	v_fma_f32 v88, v88, v155, v140
	v_fma_f32 v89, v89, v205, v140
	v_fma_f32 v132, v154, v132, v126
	v_fma_f32 v133, v154, v133, v127
	v_fma_f32 v157, v154, v157, v106
	v_fma_f32 v197, v154, v197, v107
	v_fma_f32 v84, v84, v134, v88
	v_fma_f32 v85, v85, v135, v89
	v_fma_f32 v200, v154, v200, v110
	v_fma_f32 v201, v154, v201, v111
	v_fma_f32 v204, v154, v204, v98
	v_fma_f32 v154, v154, v156, v99
	v_fma_f32 v76, v76, v198, v84
	v_fma_f32 v77, v77, v199, v85
	v_fma_f32 v90, v90, v132, v140
	v_fma_f32 v91, v91, v133, v140
	v_fma_f32 v68, v68, v202, v76
	v_fma_f32 v69, v69, v203, v77
	v_fma_f32 v86, v86, v157, v90
	v_fma_f32 v87, v87, v197, v91
	v_fma_f32 v78, v78, v200, v86
	v_fma_f32 v79, v79, v201, v87
	v_add_f32_e32 v68, v68, v69
	v_fma_f32 v70, v70, v204, v78
	v_fma_f32 v71, v71, v154, v79
	v_add_f32_e32 v69, v70, v71
	v_add_f32_e32 v68, v68, v69
	v_mov_b32_e32 v69, 0
	s_nop 0
	v_add_f32_dpp v68, v68, v68 row_ror:8 row_mask:0xf bank_mask:0xf bound_ctrl:1
	s_nop 1
	v_add_f32_dpp v68, v68, v68 row_ror:4 row_mask:0xf bank_mask:0xf bound_ctrl:1
	s_nop 1
	v_add_f32_dpp v68, v68, v68 row_ror:2 row_mask:0xf bank_mask:0xf bound_ctrl:1
	s_nop 1
	v_mov_b32_dpp v69, v68 row_ror:1 row_mask:0xf bank_mask:0xf
	s_and_saveexec_b64 s[8:9], s[44:45]
	v_add_f32_e32 v68, v68, v69
	ds_write_b32 v190, v68 offset:34816
	s_or_b64 exec, exec, s[8:9]
	s_waitcnt lgkmcnt(0)
	v_mul_f32_e32 v156, v129, v206
	ds_read_b128 v[88:91], v194 offset:23168
	ds_read_b128 v[84:87], v194 offset:23424
	ds_read_b128 v[124:127], v194 offset:31360
	ds_read_b128 v[104:107], v194 offset:31616
	ds_read_b128 v[76:79], v194 offset:23680
	ds_read_b128 v[68:71], v194 offset:23936
	ds_read_b128 v[108:111], v194 offset:31872
	ds_read_b128 v[96:99], v194 offset:32128
	ds_read2_b32 v[130:131], v196 offset0:70 offset1:86
	ds_read_b32 v129, v190 offset:33792
	v_mul_f32 v120, v120, v156
	v_mul_f32 v121, v121, v156
	v_mul_f32 v122, v122, v156
	v_mul_f32 v123, v123, v156
	v_mul_f32 v112, v112, v156
	v_mul_f32 v113, v113, v156
	v_mul_f32 v114, v114, v156
	v_mul_f32 v115, v115, v156
	v_mul_f32 v116, v116, v156
	v_mul_f32 v117, v117, v156
	v_mul_f32 v118, v118, v156
	v_mul_f32 v119, v119, v156
	v_mul_f32 v100, v100, v156
	v_mul_f32 v101, v101, v156
	v_mul_f32 v102, v102, v156
	v_mul_f32 v103, v103, v156
	v_fma_f32 v155, v128, v155, v120
	v_fma_f32 v156, v128, v205, v121
	v_fma_f32 v134, v128, v134, v112
	v_fma_f32 v135, v128, v135, v113
	v_fma_f32 v198, v128, v198, v116
	v_fma_f32 v199, v128, v199, v117
	v_fma_f32 v202, v128, v202, v100
	v_fma_f32 v203, v128, v203, v101
	v_fma_f32 v92, v92, v155, v140
	v_fma_f32 v93, v93, v156, v140
	v_fma_f32 v132, v128, v132, v122
	v_fma_f32 v133, v128, v133, v123
	v_fma_f32 v157, v128, v157, v114
	v_fma_f32 v197, v128, v197, v115
	v_fma_f32 v80, v80, v134, v92
	v_fma_f32 v81, v81, v135, v93
	v_fma_f32 v200, v128, v200, v118
	v_fma_f32 v201, v128, v201, v119
	v_fma_f32 v204, v128, v204, v102
	v_fma_f32 v154, v128, v154, v103
	v_fma_f32 v72, v72, v198, v80
	v_fma_f32 v73, v73, v199, v81
	v_fma_f32 v94, v94, v132, v140
	v_fma_f32 v95, v95, v133, v140
	v_fma_f32 v64, v64, v202, v72
	v_fma_f32 v65, v65, v203, v73
	v_fma_f32 v82, v82, v157, v94
	v_fma_f32 v83, v83, v197, v95
	v_fma_f32 v74, v74, v200, v82
	v_fma_f32 v75, v75, v201, v83
	v_add_f32_e32 v64, v64, v65
	v_fma_f32 v66, v66, v204, v74
	v_fma_f32 v67, v67, v154, v75
	v_add_f32_e32 v65, v66, v67
	v_add_f32_e32 v64, v64, v65
	v_mov_b32_e32 v65, 0
	s_nop 0
	v_add_f32_dpp v64, v64, v64 row_ror:8 row_mask:0xf bank_mask:0xf bound_ctrl:1
	s_nop 1
	v_add_f32_dpp v64, v64, v64 row_ror:4 row_mask:0xf bank_mask:0xf bound_ctrl:1
	s_nop 1
	v_add_f32_dpp v64, v64, v64 row_ror:2 row_mask:0xf bank_mask:0xf bound_ctrl:1
	s_nop 1
	v_mov_b32_dpp v65, v64 row_ror:1 row_mask:0xf bank_mask:0xf
	s_and_saveexec_b64 s[8:9], s[44:45]
	v_add_f32_e32 v64, v64, v65
	ds_write_b32 v190, v64 offset:34880
	s_or_b64 exec, exec, s[8:9]
	s_waitcnt lgkmcnt(0)
	v_mul_f32_e32 v205, v131, v129
	ds_read_b128 v[92:95], v194 offset:24192
	ds_read_b128 v[80:83], v194 offset:24448
	ds_read_b128 v[120:123], v194 offset:32384
	ds_read_b128 v[112:115], v194 offset:32640
	ds_read_b128 v[72:75], v194 offset:24704
	ds_read_b128 v[64:67], v194 offset:24960
	ds_read_b128 v[116:119], v194 offset:32896
	ds_read_b128 v[100:103], v194 offset:33152
	ds_read2_b32 v[128:129], v196 offset0:71 offset1:87
	ds_read_b32 v131, v190 offset:33856
	v_mul_f32 v124, v124, v205
	v_mul_f32 v125, v125, v205
	v_mul_f32 v104, v104, v205
	v_mul_f32 v105, v105, v205
	v_mul_f32 v108, v108, v205
	v_mul_f32 v109, v109, v205
	v_mul_f32 v126, v126, v205
	v_mul_f32 v127, v127, v205
	v_mul_f32 v106, v106, v205
	v_mul_f32 v107, v107, v205
	v_mul_f32 v110, v110, v205
	v_mul_f32 v111, v111, v205
	v_mul_f32 v196, v96, v205
	v_mul_f32 v206, v97, v205
	v_fma_f32 v96, v130, v155, v124
	v_fma_f32 v97, v130, v156, v125
	v_fma_f32 v104, v130, v134, v104
	v_fma_f32 v105, v130, v135, v105
	v_fma_f32 v108, v130, v198, v108
	v_fma_f32 v109, v130, v199, v109
	v_fma_f32 v124, v130, v202, v196
	v_fma_f32 v125, v130, v203, v206
	v_fma_f32 v88, v88, v96, v140
	v_fma_f32 v89, v89, v97, v140
	v_mul_f32 v207, v98, v205
	v_mul_f32 v205, v99, v205
	v_fma_f32 v98, v130, v132, v126
	v_fma_f32 v99, v130, v133, v127
	v_fma_f32 v84, v84, v104, v88
	v_fma_f32 v85, v85, v105, v89
	v_fma_f32 v106, v130, v157, v106
	v_fma_f32 v107, v130, v197, v107
	v_fma_f32 v110, v130, v200, v110
	v_fma_f32 v111, v130, v201, v111
	v_fma_f32 v76, v76, v108, v84
	v_fma_f32 v77, v77, v109, v85
	v_fma_f32 v126, v130, v204, v207
	v_fma_f32 v127, v130, v154, v205
	v_fma_f32 v90, v90, v98, v140
	v_fma_f32 v91, v91, v99, v140
	v_fma_f32 v68, v68, v124, v76
	v_fma_f32 v69, v69, v125, v77
	v_fma_f32 v86, v86, v106, v90
	v_fma_f32 v87, v87, v107, v91
	v_add_f32_e32 v68, v68, v69
	v_fma_f32 v78, v78, v110, v86
	v_fma_f32 v79, v79, v111, v87
	v_fma_f32 v70, v70, v126, v78
	v_fma_f32 v71, v71, v127, v79
	v_add_f32_e32 v69, v70, v71
	v_add_f32_e32 v68, v68, v69
	v_mov_b32_e32 v69, 0
	s_nop 0
	v_add_f32_dpp v68, v68, v68 row_ror:8 row_mask:0xf bank_mask:0xf bound_ctrl:1
	s_nop 1
	v_add_f32_dpp v68, v68, v68 row_ror:4 row_mask:0xf bank_mask:0xf bound_ctrl:1
	s_nop 1
	v_add_f32_dpp v68, v68, v68 row_ror:2 row_mask:0xf bank_mask:0xf bound_ctrl:1
	s_nop 1
	v_mov_b32_dpp v69, v68 row_ror:1 row_mask:0xf bank_mask:0xf
	s_and_saveexec_b64 s[8:9], s[44:45]
	v_add_f32_e32 v68, v68, v69
	ds_write_b32 v190, v68 offset:34944
	s_or_b64 exec, exec, s[8:9]
	s_waitcnt lgkmcnt(0)
	v_mul_f32_e32 v68, v129, v131
	v_mul_f32 v69, v120, v68
	v_mul_f32 v70, v121, v68
	v_mul_f32 v71, v122, v68
	v_mul_f32 v76, v123, v68
	v_mul_f32 v77, v112, v68
	v_mul_f32 v78, v113, v68
	v_mul_f32 v79, v114, v68
	v_mul_f32 v84, v115, v68
	v_mul_f32 v85, v116, v68
	v_mul_f32 v86, v117, v68
	v_mul_f32 v87, v118, v68
	v_mul_f32 v112, v119, v68
	v_mul_f32 v113, v100, v68
	v_mul_f32 v114, v101, v68
	v_mul_f32 v115, v102, v68
	v_mul_f32 v68, v103, v68
	v_fma_f32 v88, v128, v96, v69
	v_fma_f32 v89, v128, v97, v70
	v_fma_f32 v101, v128, v105, v78
	v_fma_f32 v105, v128, v109, v86
	v_fma_f32 v109, v128, v111, v112
	v_fma_f32 v111, v128, v127, v68
	v_fma_f32 v68, v92, v88, v140
	v_fma_f32 v69, v93, v89, v140
	v_fma_f32 v90, v128, v98, v71
	v_fma_f32 v100, v128, v99, v76
	v_fma_f32 v91, v128, v104, v77
	v_fma_f32 v102, v128, v106, v79
	v_fma_f32 v104, v128, v107, v84
	v_fma_f32 v69, v81, v101, v69
	v_fma_f32 v70, v94, v90, v140
	v_fma_f32 v71, v95, v100, v140
	v_fma_f32 v68, v80, v91, v68
	v_fma_f32 v103, v128, v108, v85
	v_fma_f32 v106, v128, v110, v87
	v_fma_f32 v107, v128, v124, v113
	v_fma_f32 v110, v128, v125, v114
	v_fma_f32 v70, v82, v102, v70
	v_fma_f32 v71, v83, v104, v71
	v_fma_f32 v68, v72, v103, v68
	v_fma_f32 v69, v73, v105, v69
	v_fma_f32 v108, v128, v126, v115
	v_fma_f32 v70, v74, v106, v70
	v_fma_f32 v71, v75, v109, v71
	v_fma_f32 v64, v64, v107, v68
	v_fma_f32 v65, v65, v110, v69
	v_fma_f32 v66, v66, v108, v70
	v_fma_f32 v67, v67, v111, v71
	v_add_f32_e32 v64, v64, v65
	v_add_f32_e32 v65, v66, v67
	v_add_f32_e32 v64, v64, v65
	v_mov_b32_e32 v65, 0
	s_nop 0
	v_add_f32_dpp v64, v64, v64 row_ror:8 row_mask:0xf bank_mask:0xf bound_ctrl:1
	s_nop 1
	v_add_f32_dpp v64, v64, v64 row_ror:4 row_mask:0xf bank_mask:0xf bound_ctrl:1
	s_nop 1
	v_add_f32_dpp v64, v64, v64 row_ror:2 row_mask:0xf bank_mask:0xf bound_ctrl:1
	s_nop 1
	v_mov_b32_dpp v65, v64 row_ror:1 row_mask:0xf bank_mask:0xf
	s_and_saveexec_b64 s[8:9], s[44:45]
	s_cbranch_execz .LBB0_1138
	v_add_f32_e32 v64, v64, v65
	ds_write_b32 v190, v64 offset:35008
	s_branch .LBB0_1138

.LBB0_1281:
	s_or_b64 exec, exec, s[8:9]
	s_waitcnt lgkmcnt(0)
	s_barrier
	ds_read_b32 v0, v159
	s_movk_i32 s4, 0x8f
	s_mov_b64 s[8:9], -1
	s_waitcnt lgkmcnt(0)
	v_cmp_lt_i32_e32 vcc, s4, v0
	v_readfirstlane_b32 s72, v0
	s_cbranch_vccnz .LBB0_1276
	s_cmp_gt_i32 s72, 15
	s_cbranch_scc0 .LBB0_1426
	v_mov_b32_e32 v101, v143
	s_add_i32 s4, s72, -16
	s_load_dwordx2 s[8:9], s[0:1], 0xb0
	s_bfe_u32 s44, s4, 0x30002
	v_and_b32_e32 v100, 31, v101
	s_lshl_b32 s46, s44, 7
	v_lshlrev_b32_e32 v102, 2, v100
	v_or_b32_e32 v0, s46, v102
	v_lshlrev_b32_e32 v0, 2, v0
	v_mov_b32_e32 v1, v140
	s_waitcnt lgkmcnt(0)
	v_lshl_add_u64 v[4:5], s[8:9], 0, v[0:1]
	v_add_co_u32_e32 v4, vcc, s86, v4
	global_load_dwordx4 v[0:3], v0, s[8:9]
	s_nop 0
	v_addc_co_u32_e32 v5, vcc, 0, v5, vcc
	global_load_dwordx4 v[4:7], v[4:5], off
	s_lshr_b32 s43, s4, 5
	s_lshl_b32 s45, s43, 11
	s_waitcnt vmcnt(2)
	v_ashrrev_i32_e32 v123, 5, v101
	v_add_u32_e32 v124, s45, v123
	s_waitcnt vmcnt(7)
	v_mov_b64_e32 v[56:57], s[30:31]
	s_lshl_b32 s94, s44, 9
	v_lshlrev_b32_e32 v58, 4, v100
	v_mov_b32_e32 v59, v140
	s_lshl_b32 s4, s72, 5
	s_and_b32 s42, s4, 0x60
	s_movk_i32 s15, 0x5000
	s_lshl_b32 s38, s42, 2
	s_mov_b32 s39, s95
	v_mov_b32_e32 v103, v140
	v_add_u32_e32 v65, 0x100, v101
	v_ashrrev_i32_e32 v125, 5, v65
	v_add_u32_e32 v126, s45, v125
	s_or_b32 s4, s45, 16
	v_ashrrev_i32_e32 v64, 4, v101
	v_and_b32_e32 v122, 15, v101
	s_mov_b32 s47, 0
	v_lshlrev_b32_e32 v134, 2, v101
	v_lshlrev_b32_e32 v141, 4, v101
	v_lshlrev_b32_e32 v144, 4, v65
	v_lshlrev_b32_e32 v145, 4, v122
	v_mov_b32_e32 v118, 0
	s_mov_b32 s48, 0
	v_mov_b32_e32 v119, 0
	v_mov_b32_e32 v88, 0
	v_mov_b32_e32 v89, 0
	v_mov_b32_e32 v90, 0
	v_mov_b32_e32 v80, 0
	v_mov_b32_e32 v81, 0
	v_mov_b32_e32 v82, 0
	v_mov_b32_e32 v146, 0
	v_mov_b32_e32 v120, 0
	v_mov_b32_e32 v121, 0
	v_mov_b32_e32 v91, 0
	v_mov_b32_e32 v147, 0
	v_mov_b32_e32 v148, 0
	v_mov_b32_e32 v149, 0
	v_mov_b32_e32 v83, 0
	s_waitcnt vmcnt(0)
	v_sub_f32_e32 v0, v4, v0
	v_sub_f32_e32 v1, v5, v1
	v_mul_f32_e32 v0, 0x3fb8aa3b, v0
	v_mul_f32_e32 v1, 0x3fb8aa3b, v1
	v_exp_f32_e32 v0, v0
	v_exp_f32_e32 v1, v1
	s_nop 0
	v_pk_add_f32 v[0:1], v[0:1], 1.0 op_sel_hi:[1,0]
	v_div_scale_f32 v4, s[8:9], v1, v1, 1.0
	v_rcp_f32_e32 v5, v4
	s_nop 0
	v_fma_f32 v8, -v4, v5, 1.0
	v_fmac_f32_e32 v5, v8, v5
	v_div_scale_f32 v8, vcc, 1.0, v1, 1.0
	v_mul_f32_e32 v9, v8, v5
	v_fma_f32 v10, -v4, v9, v8
	v_fmac_f32_e32 v9, v10, v5
	v_fma_f32 v4, -v4, v9, v8
	v_div_fmas_f32 v4, v4, v5, v9
	v_div_fixup_f32 v105, v4, v1, 1.0
	v_div_scale_f32 v1, s[8:9], v0, v0, 1.0
	v_rcp_f32_e32 v4, v1
	s_nop 0
	v_fma_f32 v5, -v1, v4, 1.0
	v_fmac_f32_e32 v4, v5, v4
	v_div_scale_f32 v5, vcc, 1.0, v0, 1.0
	v_mul_f32_e32 v8, v5, v4
	v_fma_f32 v9, -v1, v8, v5
	v_fmac_f32_e32 v8, v9, v4
	v_fma_f32 v1, -v1, v8, v5
	v_div_fmas_f32 v1, v1, v4, v8
	v_div_fixup_f32 v104, v1, v0, 1.0
	v_sub_f32_e32 v0, v6, v2
	v_sub_f32_e32 v1, v7, v3
	v_mul_f32_e32 v0, 0x3fb8aa3b, v0
	v_mul_f32_e32 v1, 0x3fb8aa3b, v1
	v_exp_f32_e32 v0, v0
	v_exp_f32_e32 v1, v1
	v_pk_add_f32 v[110:111], v[104:105], 1.0 op_sel_hi:[1,0] neg_lo:[1,0] neg_hi:[1,0]
	v_pk_add_f32 v[0:1], v[0:1], 1.0 op_sel_hi:[1,0]
	v_div_scale_f32 v2, s[8:9], v1, v1, 1.0
	v_rcp_f32_e32 v3, v2
	s_nop 0
	v_fma_f32 v4, -v2, v3, 1.0
	v_fmac_f32_e32 v3, v4, v3
	v_div_scale_f32 v4, vcc, 1.0, v1, 1.0
	v_mul_f32_e32 v5, v4, v3
	v_fma_f32 v6, -v2, v5, v4
	v_fmac_f32_e32 v5, v6, v3
	v_fma_f32 v2, -v2, v5, v4
	v_div_fmas_f32 v2, v2, v3, v5
	v_div_fixup_f32 v107, v2, v1, 1.0
	v_div_scale_f32 v1, s[8:9], v0, v0, 1.0
	v_rcp_f32_e32 v2, v1
	s_nop 0
	v_fma_f32 v3, -v1, v2, 1.0
	v_fmac_f32_e32 v2, v3, v2
	v_div_scale_f32 v3, vcc, 1.0, v0, 1.0
	v_mul_f32_e32 v4, v3, v2
	v_fma_f32 v5, -v1, v4, v3
	v_fmac_f32_e32 v4, v5, v2
	v_fma_f32 v1, -v1, v4, v3
	v_div_fmas_f32 v1, v1, v2, v4
	v_div_fixup_f32 v106, v1, v0, 1.0
	v_mad_i64_i32 v[0:1], s[8:9], v124, s25, v[56:57]
	v_lshl_add_u64 v[8:9], v[0:1], 0, s[94:95]
	v_lshl_add_u64 v[4:5], v[8:9], 0, v[58:59]
	v_add_co_u32_e32 v0, vcc, s80, v4
	v_lshl_add_u64 v[8:9], v[8:9], 0, s[38:39]
	s_nop 0
	v_addc_co_u32_e32 v1, vcc, 0, v5, vcc
	v_add_co_u32_e32 v4, vcc, s15, v4
	v_lshl_add_u64 v[8:9], v[8:9], 0, v[102:103]
	s_nop 0
	v_addc_co_u32_e32 v5, vcc, 0, v5, vcc
	v_add_co_u32_e32 v8, vcc, s81, v8
	global_load_dwordx4 v[0:3], v[0:1], off offset:32
	s_nop 0
	v_addc_co_u32_e32 v9, vcc, 0, v9, vcc
	global_load_dword v127, v[8:9], off offset:32
	v_mad_i64_i32 v[8:9], s[8:9], v126, s25, v[56:57]
	v_lshl_add_u64 v[16:17], v[8:9], 0, s[94:95]
	v_lshl_add_u64 v[12:13], v[16:17], 0, v[58:59]
	v_add_co_u32_e32 v8, vcc, s80, v12
	v_lshl_add_u64 v[16:17], v[16:17], 0, s[38:39]
	s_nop 0
	v_addc_co_u32_e32 v9, vcc, 0, v13, vcc
	v_add_co_u32_e32 v12, vcc, s15, v12
	v_lshl_add_u64 v[16:17], v[16:17], 0, v[102:103]
	s_nop 0
	v_addc_co_u32_e32 v13, vcc, 0, v13, vcc
	v_add_co_u32_e32 v16, vcc, s81, v16
	global_load_dwordx4 v[4:7], v[4:5], off offset:32
	s_nop 0
	v_addc_co_u32_e32 v17, vcc, 0, v17, vcc
	global_load_dword v128, v[16:17], off offset:32
	v_add_u32_e32 v16, s4, v123
	v_mad_i64_i32 v[16:17], s[8:9], v16, s25, v[56:57]
	v_lshl_add_u64 v[24:25], v[16:17], 0, s[94:95]
	v_lshl_add_u64 v[20:21], v[24:25], 0, v[58:59]
	v_add_co_u32_e32 v16, vcc, s80, v20
	v_lshl_add_u64 v[24:25], v[24:25], 0, s[38:39]
	s_nop 0
	v_addc_co_u32_e32 v17, vcc, 0, v21, vcc
	v_add_co_u32_e32 v20, vcc, s15, v20
	v_lshl_add_u64 v[24:25], v[24:25], 0, v[102:103]
	s_nop 0
	v_addc_co_u32_e32 v21, vcc, 0, v21, vcc
	v_add_co_u32_e32 v24, vcc, s81, v24
	global_load_dwordx4 v[8:11], v[8:9], off offset:32
	s_nop 0
	v_addc_co_u32_e32 v25, vcc, 0, v25, vcc
	global_load_dword v129, v[24:25], off offset:32
	v_add_u32_e32 v24, s4, v125
	v_mad_i64_i32 v[24:25], s[8:9], v24, s25, v[56:57]
	v_lshl_add_u64 v[28:29], v[24:25], 0, s[94:95]
	v_lshl_add_u64 v[30:31], v[28:29], 0, v[58:59]
	v_add_co_u32_e32 v24, vcc, s80, v30
	v_lshl_add_u64 v[28:29], v[28:29], 0, s[38:39]
	s_nop 0
	v_addc_co_u32_e32 v25, vcc, 0, v31, vcc
	v_add_co_u32_e32 v30, vcc, s15, v30
	v_lshl_add_u64 v[28:29], v[28:29], 0, v[102:103]
	s_nop 0
	v_addc_co_u32_e32 v31, vcc, 0, v31, vcc
	v_add_co_u32_e32 v28, vcc, s81, v28
	s_or_b32 s4, s45, 32
	s_nop 0
	v_addc_co_u32_e32 v29, vcc, 0, v29, vcc
	global_load_dwordx4 v[24:27], v[24:25], off offset:32
	v_pk_add_f32 v[112:113], v[106:107], 1.0 op_sel_hi:[1,0] neg_lo:[1,0] neg_hi:[1,0]
	global_load_dword v130, v[28:29], off offset:32
	v_add_u32_e32 v28, s4, v123
	v_mad_i64_i32 v[28:29], s[8:9], v28, s25, v[56:57]
	v_lshl_add_u64 v[40:41], v[28:29], 0, s[94:95]
	v_lshl_add_u64 v[32:33], v[40:41], 0, v[58:59]
	v_add_co_u32_e32 v28, vcc, s80, v32
	v_lshl_add_u64 v[40:41], v[40:41], 0, s[38:39]
	s_nop 0
	v_addc_co_u32_e32 v29, vcc, 0, v33, vcc
	v_add_co_u32_e32 v32, vcc, s15, v32
	v_lshl_add_u64 v[40:41], v[40:41], 0, v[102:103]
	s_nop 0
	v_addc_co_u32_e32 v33, vcc, 0, v33, vcc
	v_add_co_u32_e32 v40, vcc, s81, v40
	global_load_dwordx4 v[36:39], v[30:31], off offset:32
	s_nop 0
	v_addc_co_u32_e32 v41, vcc, 0, v41, vcc
	global_load_dword v131, v[40:41], off offset:32
	v_add_u32_e32 v40, s4, v125
	v_mad_i64_i32 v[40:41], s[8:9], v40, s25, v[56:57]
	v_lshl_add_u64 v[44:45], v[40:41], 0, s[94:95]
	v_lshl_add_u64 v[46:47], v[44:45], 0, v[58:59]
	v_add_co_u32_e32 v40, vcc, s80, v46
	v_lshl_add_u64 v[44:45], v[44:45], 0, s[38:39]
	s_nop 0
	v_addc_co_u32_e32 v41, vcc, 0, v47, vcc
	v_add_co_u32_e32 v46, vcc, s15, v46
	v_lshl_add_u64 v[44:45], v[44:45], 0, v[102:103]
	s_nop 0
	v_addc_co_u32_e32 v47, vcc, 0, v47, vcc
	v_add_co_u32_e32 v44, vcc, s81, v44
	s_or_b32 s4, s45, 48
	s_nop 0
	v_addc_co_u32_e32 v45, vcc, 0, v45, vcc
	global_load_dwordx4 v[40:43], v[40:41], off offset:32
	s_nop 0
	global_load_dword v132, v[44:45], off offset:32
	v_add_u32_e32 v44, s4, v123
	v_mad_i64_i32 v[44:45], s[8:9], v44, s25, v[56:57]
	v_lshl_add_u64 v[60:61], v[44:45], 0, s[94:95]
	v_lshl_add_u64 v[48:49], v[60:61], 0, v[58:59]
	v_add_co_u32_e32 v44, vcc, s80, v48
	v_lshl_add_u64 v[60:61], v[60:61], 0, s[38:39]
	s_nop 0
	v_addc_co_u32_e32 v45, vcc, 0, v49, vcc
	v_add_co_u32_e32 v48, vcc, s15, v48
	v_lshl_add_u64 v[60:61], v[60:61], 0, v[102:103]
	s_nop 0
	v_addc_co_u32_e32 v49, vcc, 0, v49, vcc
	v_add_co_u32_e32 v60, vcc, s81, v60
	global_load_dwordx4 v[12:15], v[12:13], off offset:32
	s_nop 0
	v_addc_co_u32_e32 v61, vcc, 0, v61, vcc
	global_load_dword v133, v[60:61], off offset:32
	v_add_u32_e32 v60, s4, v125
	v_mad_i64_i32 v[56:57], s[8:9], v60, s25, v[56:57]
	v_lshl_add_u64 v[66:67], v[56:57], 0, s[94:95]
	v_lshl_add_u64 v[60:61], v[66:67], 0, v[58:59]
	v_add_co_u32_e32 v56, vcc, s80, v60
	v_lshl_add_u64 v[66:67], v[66:67], 0, s[38:39]
	s_nop 0
	v_addc_co_u32_e32 v57, vcc, 0, v61, vcc
	v_add_co_u32_e32 v60, vcc, s15, v60
	v_lshl_add_u64 v[66:67], v[66:67], 0, v[102:103]
	s_nop 0
	v_addc_co_u32_e32 v61, vcc, 0, v61, vcc
	v_add_co_u32_e32 v66, vcc, s81, v66
	global_load_dwordx4 v[16:19], v[16:17], off offset:32
	s_nop 0
	v_addc_co_u32_e32 v67, vcc, 0, v67, vcc
	global_load_dwordx4 v[20:23], v[20:21], off offset:32
	s_nop 0
	global_load_dwordx4 v[28:31], v[28:29], off offset:32
	s_nop 0
	global_load_dwordx4 v[32:35], v[32:33], off offset:32
	s_nop 0
	global_load_dwordx4 v[52:55], v[46:47], off offset:32
	global_load_dword v135, v[66:67], off offset:32
	v_lshl_add_u64 v[66:67], s[28:29], 0, v[102:103]
	global_load_dwordx4 v[48:51], v[48:49], off offset:32
	v_lshl_add_u64 v[66:67], v[66:67], 0, s[94:95]
	global_load_dwordx4 v[56:59], v[56:57], off offset:32
	v_lshl_add_u64 v[108:109], v[66:67], 0, s[38:39]
	global_load_dwordx4 v[44:47], v[44:45], off offset:32
	v_lshlrev_b32_e32 v103, 2, v64
	global_load_dwordx4 v[60:63], v[60:61], off offset:32
	v_cmp_eq_u32_e64 s[38:39], 0, v122
	s_branch .LBB0_1285

.LBB0_1285:
	s_waitcnt vmcnt(23)
	v_mul_f32_e32 v64, 0xbfb8aa3b, v0
	v_mul_f32_e32 v65, 0xbfb8aa3b, v1
	v_exp_f32_e32 v64, v64
	v_exp_f32_e32 v65, v65
	v_mul_f32_e32 v66, 0xbfb8aa3b, v2
	v_mul_f32_e32 v67, 0xbfb8aa3b, v3
	v_exp_f32_e32 v66, v66
	v_pk_add_f32 v[64:65], v[64:65], 1.0 op_sel_hi:[1,0]
	v_exp_f32_e32 v67, v67
	v_div_scale_f32 v72, s[8:9], v65, v65, v1
	v_rcp_f32_e32 v73, v72
	v_pk_add_f32 v[66:67], v[66:67], 1.0 op_sel_hi:[1,0]
	s_waitcnt vmcnt(21)
	v_mul_f32_e32 v68, 0xbfb8aa3b, v4
	v_mul_f32_e32 v69, 0xbfb8aa3b, v5
	v_fma_f32 v74, -v72, v73, 1.0
	v_fmac_f32_e32 v73, v74, v73
	v_div_scale_f32 v74, vcc, v1, v65, v1
	v_mul_f32_e32 v75, v74, v73
	v_fma_f32 v76, -v72, v75, v74
	v_fmac_f32_e32 v75, v76, v73
	v_fma_f32 v72, -v72, v75, v74
	v_div_fmas_f32 v72, v72, v73, v75
	v_div_fixup_f32 v65, v72, v65, v1
	v_div_scale_f32 v72, s[8:9], v64, v64, v0
	v_rcp_f32_e32 v73, v72
	v_exp_f32_e32 v68, v68
	v_exp_f32_e32 v69, v69
	v_mul_f32_e32 v70, 0xbfb8aa3b, v6
	v_fma_f32 v74, -v72, v73, 1.0
	v_fmac_f32_e32 v73, v74, v73
	v_div_scale_f32 v74, vcc, v0, v64, v0
	v_mul_f32_e32 v75, v74, v73
	v_fma_f32 v76, -v72, v75, v74
	v_fmac_f32_e32 v75, v76, v73
	v_fma_f32 v72, -v72, v75, v74
	v_div_fmas_f32 v72, v72, v73, v75
	v_div_fixup_f32 v64, v72, v64, v0
	v_div_scale_f32 v72, s[8:9], v67, v67, v3
	v_rcp_f32_e32 v73, v72
	v_pk_mul_f32 v[64:65], v[64:65], s[18:19] op_sel_hi:[1,0]
	v_mul_f32_e32 v71, 0xbfb8aa3b, v7
	v_exp_f32_e32 v70, v70
	v_fma_f32 v74, -v72, v73, 1.0
	v_fmac_f32_e32 v73, v74, v73
	v_div_scale_f32 v74, vcc, v3, v67, v3
	v_mul_f32_e32 v75, v74, v73
	v_fma_f32 v76, -v72, v75, v74
	v_fmac_f32_e32 v75, v76, v73
	v_fma_f32 v72, -v72, v75, v74
	v_div_fmas_f32 v72, v72, v73, v75
	v_div_fixup_f32 v67, v72, v67, v3
	v_div_scale_f32 v72, s[8:9], v66, v66, v2
	v_rcp_f32_e32 v73, v72
	v_exp_f32_e32 v71, v71
	s_cmpk_gt_u32 s48, 0x7b
	s_cselect_b64 s[40:41], -1, 0
	v_fma_f32 v74, -v72, v73, 1.0
	v_fmac_f32_e32 v73, v74, v73
	v_div_scale_f32 v74, vcc, v2, v66, v2
	v_mul_f32_e32 v75, v74, v73
	v_fma_f32 v76, -v72, v75, v74
	v_fmac_f32_e32 v75, v76, v73
	v_fma_f32 v72, -v72, v75, v74
	v_div_fmas_f32 v72, v72, v73, v75
	v_div_fixup_f32 v66, v72, v66, v2
	v_pk_mul_f32 v[66:67], v[66:67], s[18:19] op_sel_hi:[1,0]
	ds_write_b128 v141, v[64:67]
	v_pk_add_f32 v[64:65], v[68:69], 1.0 op_sel_hi:[1,0]
	v_lshlrev_b32_e32 v116, 2, v102
	v_div_scale_f32 v66, s[8:9], v65, v65, 1.0
	v_rcp_f32_e32 v67, v66
	v_lshlrev_b32_e32 v114, 2, v100
	v_fma_f32 v68, -v66, v67, 1.0
	v_fmac_f32_e32 v67, v68, v67
	v_div_scale_f32 v68, vcc, 1.0, v65, 1.0
	v_mul_f32_e32 v69, v68, v67
	v_fma_f32 v72, -v66, v69, v68
	v_fmac_f32_e32 v69, v72, v67
	v_fma_f32 v66, -v66, v69, v68
	v_div_fmas_f32 v66, v66, v67, v69
	v_div_fixup_f32 v65, v66, v65, 1.0
	v_div_scale_f32 v66, s[8:9], v64, v64, 1.0
	v_rcp_f32_e32 v67, v66
	s_nop 0
	v_fma_f32 v68, -v66, v67, 1.0
	v_fmac_f32_e32 v67, v68, v67
	v_div_scale_f32 v68, vcc, 1.0, v64, 1.0
	v_mul_f32_e32 v69, v68, v67
	v_fma_f32 v72, -v66, v69, v68
	v_fmac_f32_e32 v69, v72, v67
	v_fma_f32 v66, -v66, v69, v68
	v_div_fmas_f32 v66, v66, v67, v69
	v_div_fixup_f32 v64, v66, v64, 1.0
	v_pk_add_f32 v[66:67], v[70:71], 1.0 op_sel_hi:[1,0]
	v_pk_fma_f32 v[64:65], v[110:111], v[64:65], v[104:105]
	v_div_scale_f32 v68, s[8:9], v67, v67, 1.0
	v_rcp_f32_e32 v69, v68
	s_nop 0
	v_fma_f32 v70, -v68, v69, 1.0
	v_fmac_f32_e32 v69, v70, v69
	v_div_scale_f32 v70, vcc, 1.0, v67, 1.0
	v_mul_f32_e32 v71, v70, v69
	v_fma_f32 v72, -v68, v71, v70
	v_fmac_f32_e32 v71, v72, v69
	v_fma_f32 v68, -v68, v71, v70
	v_div_fmas_f32 v68, v68, v69, v71
	v_div_fixup_f32 v67, v68, v67, 1.0
	v_div_scale_f32 v68, s[8:9], v66, v66, 1.0
	v_rcp_f32_e32 v69, v68
	s_nop 0
	v_fma_f32 v70, -v68, v69, 1.0
	v_fmac_f32_e32 v69, v70, v69
	v_div_scale_f32 v70, vcc, 1.0, v66, 1.0
	v_mul_f32_e32 v71, v70, v69
	v_fma_f32 v72, -v68, v71, v70
	v_fmac_f32_e32 v71, v72, v69
	v_fma_f32 v68, -v68, v71, v70
	v_div_fmas_f32 v68, v68, v69, v71
	v_div_fixup_f32 v66, v68, v66, 1.0
	v_pk_fma_f32 v[66:67], v[112:113], v[66:67], v[106:107]
	ds_write_b128 v141, v[64:67] offset:8192
	ds_write_b32 v134, v127 offset:16384
	s_waitcnt vmcnt(19)
	v_mul_f32_e32 v64, 0xbfb8aa3b, v8
	v_mul_f32_e32 v65, 0xbfb8aa3b, v9
	v_exp_f32_e32 v64, v64
	v_exp_f32_e32 v65, v65
	v_mul_f32_e32 v66, 0xbfb8aa3b, v10
	v_mul_f32_e32 v67, 0xbfb8aa3b, v11
	v_exp_f32_e32 v66, v66
	v_pk_add_f32 v[64:65], v[64:65], 1.0 op_sel_hi:[1,0]
	v_exp_f32_e32 v67, v67
	v_div_scale_f32 v72, s[8:9], v65, v65, v9
	v_rcp_f32_e32 v73, v72
	v_pk_add_f32 v[66:67], v[66:67], 1.0 op_sel_hi:[1,0]
	s_waitcnt vmcnt(11)
	v_mul_f32_e32 v68, 0xbfb8aa3b, v12
	v_mul_f32_e32 v69, 0xbfb8aa3b, v13
	v_fma_f32 v74, -v72, v73, 1.0
	v_fmac_f32_e32 v73, v74, v73
	v_div_scale_f32 v74, vcc, v9, v65, v9
	v_mul_f32_e32 v75, v74, v73
	v_fma_f32 v76, -v72, v75, v74
	v_fmac_f32_e32 v75, v76, v73
	v_fma_f32 v72, -v72, v75, v74
	v_div_fmas_f32 v72, v72, v73, v75
	v_div_fixup_f32 v65, v72, v65, v9
	v_div_scale_f32 v72, s[8:9], v64, v64, v8
	v_rcp_f32_e32 v73, v72
	v_exp_f32_e32 v68, v68
	v_exp_f32_e32 v69, v69
	v_mul_f32_e32 v70, 0xbfb8aa3b, v14
	v_fma_f32 v74, -v72, v73, 1.0
	v_fmac_f32_e32 v73, v74, v73
	v_div_scale_f32 v74, vcc, v8, v64, v8
	v_mul_f32_e32 v75, v74, v73
	v_fma_f32 v76, -v72, v75, v74
	v_fmac_f32_e32 v75, v76, v73
	v_fma_f32 v72, -v72, v75, v74
	v_div_fmas_f32 v72, v72, v73, v75
	v_div_fixup_f32 v64, v72, v64, v8
	v_div_scale_f32 v72, s[8:9], v67, v67, v11
	v_rcp_f32_e32 v73, v72
	v_pk_mul_f32 v[64:65], v[64:65], s[18:19] op_sel_hi:[1,0]
	v_mul_f32_e32 v71, 0xbfb8aa3b, v15
	v_exp_f32_e32 v70, v70
	v_fma_f32 v74, -v72, v73, 1.0
	v_fmac_f32_e32 v73, v74, v73
	v_div_scale_f32 v74, vcc, v11, v67, v11
	v_mul_f32_e32 v75, v74, v73
	v_fma_f32 v76, -v72, v75, v74
	v_fmac_f32_e32 v75, v76, v73
	v_fma_f32 v72, -v72, v75, v74
	v_div_fmas_f32 v72, v72, v73, v75
	v_div_fixup_f32 v67, v72, v67, v11
	v_div_scale_f32 v72, s[8:9], v66, v66, v10
	v_rcp_f32_e32 v73, v72
	v_exp_f32_e32 v71, v71
	v_fma_f32 v74, -v72, v73, 1.0
	v_fmac_f32_e32 v73, v74, v73
	v_div_scale_f32 v74, vcc, v10, v66, v10
	v_mul_f32_e32 v75, v74, v73
	v_fma_f32 v76, -v72, v75, v74
	v_fmac_f32_e32 v75, v76, v73
	v_fma_f32 v72, -v72, v75, v74
	v_div_fmas_f32 v72, v72, v73, v75
	v_div_fixup_f32 v66, v72, v66, v10
	v_pk_mul_f32 v[66:67], v[66:67], s[18:19] op_sel_hi:[1,0]
	ds_write_b128 v144, v[64:67]
	v_pk_add_f32 v[64:65], v[68:69], 1.0 op_sel_hi:[1,0]
	v_div_scale_f32 v66, s[8:9], v65, v65, 1.0
	v_rcp_f32_e32 v67, v66
	s_nop 0
	v_fma_f32 v68, -v66, v67, 1.0
	v_fmac_f32_e32 v67, v68, v67
	v_div_scale_f32 v68, vcc, 1.0, v65, 1.0
	v_mul_f32_e32 v69, v68, v67
	v_fma_f32 v72, -v66, v69, v68
	v_fmac_f32_e32 v69, v72, v67
	v_fma_f32 v66, -v66, v69, v68
	v_div_fmas_f32 v66, v66, v67, v69
	v_div_fixup_f32 v65, v66, v65, 1.0
	v_div_scale_f32 v66, s[8:9], v64, v64, 1.0
	v_rcp_f32_e32 v67, v66
	s_nop 0
	v_fma_f32 v68, -v66, v67, 1.0
	v_fmac_f32_e32 v67, v68, v67
	v_div_scale_f32 v68, vcc, 1.0, v64, 1.0
	v_mul_f32_e32 v69, v68, v67
	v_fma_f32 v72, -v66, v69, v68
	v_fmac_f32_e32 v69, v72, v67
	v_fma_f32 v66, -v66, v69, v68
	v_div_fmas_f32 v66, v66, v67, v69
	v_div_fixup_f32 v64, v66, v64, 1.0
	v_pk_add_f32 v[66:67], v[70:71], 1.0 op_sel_hi:[1,0]
	v_pk_fma_f32 v[64:65], v[110:111], v[64:65], v[104:105]
	v_div_scale_f32 v68, s[8:9], v67, v67, 1.0
	v_rcp_f32_e32 v69, v68
	s_nop 0
	v_fma_f32 v70, -v68, v69, 1.0
	v_fmac_f32_e32 v69, v70, v69
	v_div_scale_f32 v70, vcc, 1.0, v67, 1.0
	v_mul_f32_e32 v71, v70, v69
	v_fma_f32 v72, -v68, v71, v70
	v_fmac_f32_e32 v71, v72, v69
	v_fma_f32 v68, -v68, v71, v70
	v_div_fmas_f32 v68, v68, v69, v71
	v_div_fixup_f32 v67, v68, v67, 1.0
	v_div_scale_f32 v68, s[8:9], v66, v66, 1.0
	v_rcp_f32_e32 v69, v68
	s_nop 0
	v_fma_f32 v70, -v68, v69, 1.0
	v_fmac_f32_e32 v69, v70, v69
	v_div_scale_f32 v70, vcc, 1.0, v66, 1.0
	v_mul_f32_e32 v71, v70, v69
	v_fma_f32 v72, -v68, v71, v70
	v_fmac_f32_e32 v71, v72, v69
	v_fma_f32 v68, -v68, v71, v70
	v_div_fmas_f32 v68, v68, v69, v71
	v_div_fixup_f32 v66, v68, v66, 1.0
	v_pk_fma_f32 v[66:67], v[112:113], v[66:67], v[106:107]
	ds_write_b128 v144, v[64:67] offset:8192
	ds_write_b32 v134, v128 offset:17408
	s_waitcnt lgkmcnt(0)
	s_barrier
	s_and_b64 vcc, exec, s[40:41]
	s_cbranch_vccnz .LBB0_1287
	v_add3_u32 v0, v124, s47, 64
	v_mov_b64_e32 v[8:9], s[30:31]
	v_mad_i64_i32 v[0:1], s[8:9], v0, s25, v[8:9]
	s_lshl_b32 s94, s46, 2
	v_lshl_add_u64 v[10:11], v[0:1], 0, s[94:95]
	v_mov_b32_e32 v117, v140
	v_lshl_add_u64 v[0:1], v[10:11], 0, v[116:117]
	v_add_co_u32_e32 v2, vcc, 0x4000, v0
	s_lshl_b32 s8, s42, 2
	s_nop 0
	v_addc_co_u32_e32 v3, vcc, 0, v1, vcc
	s_mov_b32 s9, s95
	v_add_co_u32_e32 v4, vcc, 0x5000, v0
	v_lshl_add_u64 v[10:11], v[10:11], 0, s[8:9]
	v_mov_b32_e32 v115, v140
	v_add3_u32 v12, v126, s47, 64
	v_addc_co_u32_e32 v5, vcc, 0, v1, vcc
	v_lshl_add_u64 v[10:11], v[10:11], 0, v[114:115]
	v_mad_i64_i32 v[8:9], s[22:23], v12, s25, v[8:9]
	v_add_co_u32_e32 v10, vcc, s81, v10
	v_lshl_add_u64 v[12:13], v[8:9], 0, s[94:95]
	s_nop 0
	v_addc_co_u32_e32 v11, vcc, 0, v11, vcc
	v_lshl_add_u64 v[14:15], v[12:13], 0, v[116:117]
	v_add_co_u32_e32 v8, vcc, s80, v14
	v_lshl_add_u64 v[12:13], v[12:13], 0, s[8:9]
	s_nop 0
	v_addc_co_u32_e32 v9, vcc, 0, v15, vcc
	v_add_co_u32_e32 v14, vcc, 0x5000, v14
	v_lshl_add_u64 v[12:13], v[12:13], 0, v[114:115]
	s_nop 0
	v_addc_co_u32_e32 v15, vcc, 0, v15, vcc
	v_add_co_u32_e32 v64, vcc, 0x6000, v12
	global_load_dwordx4 v[0:3], v[2:3], off offset:32
	s_nop 0
	global_load_dwordx4 v[4:7], v[4:5], off offset:32
	s_nop 0
	global_load_dword v127, v[10:11], off offset:32
	s_nop 0
	global_load_dwordx4 v[8:11], v[8:9], off offset:32
	v_addc_co_u32_e32 v65, vcc, 0, v13, vcc
	global_load_dwordx4 v[12:15], v[14:15], off offset:32
	s_nop 0
	global_load_dword v128, v[64:65], off offset:32

.LBB0_1289:
	ds_read_b128 v[64:67], v145
	ds_read_b128 v[72:75], v145 offset:256
	ds_read_b128 v[178:181], v145 offset:8192
	ds_read_b128 v[182:185], v145 offset:8448
	v_add_u32_e32 v152, 0x4000, v103
	ds_read2_b32 v[96:97], v152 offset1:16
	ds_read_b128 v[76:79], v145 offset:512
	ds_read_b128 v[68:71], v145 offset:768
	ds_read_b128 v[92:95], v145 offset:8704
	ds_read_b128 v[84:87], v145 offset:8960
	ds_read2_b32 v[98:99], v152 offset0:32 offset1:48
	s_waitcnt lgkmcnt(5)
	v_sub_f32 v115, v118, v96
	v_sub_f32 v118, v119, v96
	v_sub_f32 v119, v120, v97
	v_sub_f32 v120, v121, v97
	v_sub_f32 v80, v80, v96
	v_sub_f32 v81, v81, v96
	v_sub_f32 v82, v82, v96
	v_sub_f32 v117, v146, v97
	v_sub_f32 v88, v88, v96
	v_sub_f32 v121, v147, v97
	v_sub_f32 v83, v83, v97
	v_fma_f32 v157, v178, v115, v96
	v_fma_f32 v154, v179, v118, v96
	v_fma_f32 v156, v178, v117, v97
	v_fma_f32 v155, v179, v119, v97
	v_fma_f32 v151, v180, v88, v96
	v_fma_f32 v153, v180, v120, v97
	v_fma_f32 v120, v183, v80, v96
	v_fma_f32 v118, v184, v81, v96
	v_fma_f32 v115, v185, v82, v96
	v_fma_f32 v80, v64, v157, v140
	v_fma_f32 v64, v64, v156, v140
	v_fma_f32 v81, v65, v154, v140
	v_fma_f32 v65, v65, v155, v140
	v_fma_f32 v82, v66, v151, v140
	v_fma_f32 v66, v66, v153, v140
	v_sub_f32 v89, v89, v96
	v_sub_f32 v91, v91, v97
	v_sub_f32 v90, v90, v96
	v_sub_f32 v146, v148, v97
	v_sub_f32 v186, v149, v97
	v_fma_f32 v148, v182, v121, v97
	v_fma_f32 v149, v181, v89, v96
	v_fma_f32 v150, v181, v91, v97
	v_fma_f32 v147, v182, v90, v96
	v_fma_f32 v121, v183, v146, v97
	v_fma_f32 v119, v184, v186, v97
	v_fma_f32 v117, v185, v83, v97
	v_fma_f32 v83, v67, v149, v140
	v_fma_f32 v67, v67, v150, v140
	v_fma_f32 v80, v72, v147, v80
	v_fma_f32 v72, v72, v148, v64
	v_fma_f32 v64, v73, v120, v81
	v_fma_f32 v73, v73, v121, v65
	v_fma_f32 v65, v74, v118, v82
	v_fma_f32 v66, v74, v119, v66
	v_fma_f32 v74, v75, v115, v83
	v_fma_f32 v67, v75, v117, v67
	v_add_f32_e32 v64, v80, v64
	v_add_f32_e32 v65, v65, v74
	v_add_f32_e32 v72, v72, v73
	v_add_f32_e32 v66, v66, v67
	v_add_f32_e32 v64, v64, v65
	v_add_f32_e32 v66, v72, v66
	v_mov_b32_e32 v65, 0
	v_add_f32_dpp v64, v64, v64 row_ror:8 row_mask:0xf bank_mask:0xf bound_ctrl:1
	v_add_f32_dpp v66, v66, v66 row_ror:8 row_mask:0xf bank_mask:0xf bound_ctrl:1
	v_mov_b32_e32 v67, 0
	v_add_f32_dpp v64, v64, v64 row_ror:4 row_mask:0xf bank_mask:0xf bound_ctrl:1
	v_add_f32_dpp v66, v66, v66 row_ror:4 row_mask:0xf bank_mask:0xf bound_ctrl:1
	v_add_u32_e32 v146, 0x9000, v103
	v_add_f32_dpp v64, v64, v64 row_ror:2 row_mask:0xf bank_mask:0xf bound_ctrl:1
	v_add_f32_dpp v66, v66, v66 row_ror:2 row_mask:0xf bank_mask:0xf bound_ctrl:1
	s_nop 0
	v_mov_b32_dpp v65, v64 row_ror:1 row_mask:0xf bank_mask:0xf
	v_mov_b32_dpp v67, v66 row_ror:1 row_mask:0xf bank_mask:0xf
	s_and_saveexec_b64 s[8:9], s[38:39]
	v_add_f32_e32 v66, v66, v67
	v_add_f32_e32 v64, v64, v65
	ds_write2_b32 v146, v64, v66 offset1:16
	s_or_b64 exec, exec, s[8:9]
	s_waitcnt lgkmcnt(0)
	v_sub_f32 v157, v157, v98
	v_sub_f32 v156, v156, v99
	v_sub_f32 v154, v154, v98
	v_sub_f32 v155, v155, v99
	v_sub_f32 v147, v147, v98
	v_sub_f32 v148, v148, v99
	v_sub_f32 v120, v120, v98
	v_sub_f32 v121, v121, v99
	v_sub_f32 v151, v151, v98
	v_sub_f32 v153, v153, v99
	v_sub_f32 v118, v118, v98
	v_sub_f32 v119, v119, v99
	v_fma_f32 v157, v92, v157, v98
	v_fma_f32 v156, v92, v156, v99
	v_fma_f32 v154, v93, v154, v98
	v_fma_f32 v155, v93, v155, v99
	v_fma_f32 v147, v84, v147, v98
	v_fma_f32 v148, v84, v148, v99
	v_fma_f32 v120, v85, v120, v98
	v_fma_f32 v121, v85, v121, v99
	v_fma_f32 v84, v76, v157, v140
	v_fma_f32 v76, v76, v156, v140
	v_fma_f32 v85, v77, v154, v140
	v_fma_f32 v77, v77, v155, v140
	ds_read_b128 v[72:75], v145 offset:1024
	ds_read_b128 v[64:67], v145 offset:1280
	ds_read_b128 v[88:91], v145 offset:9216
	ds_read_b128 v[80:83], v145 offset:9472
	ds_read2_b32 v[96:97], v152 offset0:64 offset1:80
	v_sub_f32 v149, v149, v98
	v_sub_f32 v150, v150, v99
	v_sub_f32 v115, v115, v98
	v_sub_f32 v117, v117, v99
	v_fma_f32 v151, v94, v151, v98
	v_fma_f32 v153, v94, v153, v99
	v_fma_f32 v118, v86, v118, v98
	v_fma_f32 v119, v86, v119, v99
	v_fma_f32 v84, v68, v147, v84
	v_fma_f32 v76, v68, v148, v76
	v_fma_f32 v86, v78, v151, v140
	v_fma_f32 v78, v78, v153, v140
	v_fma_f32 v68, v69, v120, v85
	v_fma_f32 v77, v69, v121, v77
	v_fma_f32 v149, v95, v149, v98
	v_fma_f32 v150, v95, v150, v99
	v_fma_f32 v69, v70, v118, v86
	v_fma_f32 v70, v70, v119, v78
	v_fma_f32 v115, v87, v115, v98
	v_fma_f32 v117, v87, v117, v99
	v_fma_f32 v87, v79, v149, v140
	v_fma_f32 v79, v79, v150, v140
	v_add_f32_e32 v68, v84, v68
	v_fma_f32 v78, v71, v115, v87
	v_fma_f32 v71, v71, v117, v79
	v_add_f32_e32 v76, v76, v77
	v_add_f32_e32 v69, v69, v78
	v_add_f32_e32 v70, v70, v71
	v_add_f32_e32 v68, v68, v69
	v_add_f32_e32 v70, v76, v70
	v_mov_b32_e32 v69, 0
	v_add_f32_dpp v68, v68, v68 row_ror:8 row_mask:0xf bank_mask:0xf bound_ctrl:1
	v_add_f32_dpp v70, v70, v70 row_ror:8 row_mask:0xf bank_mask:0xf bound_ctrl:1
	v_mov_b32_e32 v71, 0
	v_add_f32_dpp v68, v68, v68 row_ror:4 row_mask:0xf bank_mask:0xf bound_ctrl:1
	v_add_f32_dpp v70, v70, v70 row_ror:4 row_mask:0xf bank_mask:0xf bound_ctrl:1
	s_nop 0
	v_add_f32_dpp v68, v68, v68 row_ror:2 row_mask:0xf bank_mask:0xf bound_ctrl:1
	v_add_f32_dpp v70, v70, v70 row_ror:2 row_mask:0xf bank_mask:0xf bound_ctrl:1
	s_nop 0
	v_mov_b32_dpp v69, v68 row_ror:1 row_mask:0xf bank_mask:0xf
	v_mov_b32_dpp v71, v70 row_ror:1 row_mask:0xf bank_mask:0xf
	s_and_saveexec_b64 s[8:9], s[38:39]
	v_add_f32_e32 v70, v70, v71
	v_add_f32_e32 v68, v68, v69
	ds_write2_b32 v146, v68, v70 offset0:32 offset1:48
	s_or_b64 exec, exec, s[8:9]
	s_waitcnt lgkmcnt(0)
	v_sub_f32 v157, v157, v96
	v_sub_f32 v156, v156, v97
	v_sub_f32 v154, v154, v96
	v_sub_f32 v155, v155, v97
	v_sub_f32 v147, v147, v96
	v_sub_f32 v148, v148, v97
	v_sub_f32 v120, v120, v96
	v_sub_f32 v121, v121, v97
	v_sub_f32 v151, v151, v96
	v_sub_f32 v153, v153, v97
	v_sub_f32 v118, v118, v96
	v_sub_f32 v119, v119, v97
	v_fma_f32 v157, v88, v157, v96
	v_fma_f32 v156, v88, v156, v97
	v_fma_f32 v154, v89, v154, v96
	v_fma_f32 v155, v89, v155, v97
	v_fma_f32 v147, v80, v147, v96
	v_fma_f32 v148, v80, v148, v97
	v_fma_f32 v120, v81, v120, v96
	v_fma_f32 v121, v81, v121, v97
	v_fma_f32 v80, v72, v157, v140
	v_fma_f32 v72, v72, v156, v140
	v_fma_f32 v81, v73, v154, v140
	v_fma_f32 v73, v73, v155, v140
	ds_read_b128 v[76:79], v145 offset:1536
	ds_read_b128 v[68:71], v145 offset:1792
	ds_read_b128 v[92:95], v145 offset:9728
	ds_read_b128 v[84:87], v145 offset:9984
	ds_read2_b32 v[98:99], v152 offset0:96 offset1:112
	v_sub_f32 v149, v149, v96
	v_sub_f32 v150, v150, v97
	v_sub_f32 v115, v115, v96
	v_sub_f32 v117, v117, v97
	v_fma_f32 v151, v90, v151, v96
	v_fma_f32 v153, v90, v153, v97
	v_fma_f32 v118, v82, v118, v96
	v_fma_f32 v119, v82, v119, v97
	v_fma_f32 v80, v64, v147, v80
	v_fma_f32 v72, v64, v148, v72
	v_fma_f32 v82, v74, v151, v140
	v_fma_f32 v74, v74, v153, v140
	v_fma_f32 v64, v65, v120, v81
	v_fma_f32 v73, v65, v121, v73
	v_fma_f32 v149, v91, v149, v96
	v_fma_f32 v150, v91, v150, v97
	v_fma_f32 v65, v66, v118, v82
	v_fma_f32 v66, v66, v119, v74
	v_fma_f32 v115, v83, v115, v96
	v_fma_f32 v117, v83, v117, v97
	v_fma_f32 v83, v75, v149, v140
	v_fma_f32 v75, v75, v150, v140
	v_add_f32_e32 v64, v80, v64
	v_fma_f32 v74, v67, v115, v83
	v_fma_f32 v67, v67, v117, v75
	v_add_f32_e32 v72, v72, v73
	v_add_f32_e32 v65, v65, v74
	v_add_f32_e32 v66, v66, v67
	v_add_f32_e32 v64, v64, v65
	v_add_f32_e32 v66, v72, v66
	v_mov_b32_e32 v65, 0
	v_add_f32_dpp v64, v64, v64 row_ror:8 row_mask:0xf bank_mask:0xf bound_ctrl:1
	v_add_f32_dpp v66, v66, v66 row_ror:8 row_mask:0xf bank_mask:0xf bound_ctrl:1
	v_mov_b32_e32 v67, 0
	v_add_f32_dpp v64, v64, v64 row_ror:4 row_mask:0xf bank_mask:0xf bound_ctrl:1
	v_add_f32_dpp v66, v66, v66 row_ror:4 row_mask:0xf bank_mask:0xf bound_ctrl:1
	s_nop 0
	v_add_f32_dpp v64, v64, v64 row_ror:2 row_mask:0xf bank_mask:0xf bound_ctrl:1
	v_add_f32_dpp v66, v66, v66 row_ror:2 row_mask:0xf bank_mask:0xf bound_ctrl:1
	s_nop 0
	v_mov_b32_dpp v65, v64 row_ror:1 row_mask:0xf bank_mask:0xf
	v_mov_b32_dpp v67, v66 row_ror:1 row_mask:0xf bank_mask:0xf
	s_and_saveexec_b64 s[8:9], s[38:39]
	v_add_f32_e32 v66, v66, v67
	v_add_f32_e32 v64, v64, v65
	ds_write2_b32 v146, v64, v66 offset0:64 offset1:80
	s_or_b64 exec, exec, s[8:9]
	s_waitcnt lgkmcnt(0)
	v_sub_f32 v157, v157, v98
	v_sub_f32 v156, v156, v99
	v_sub_f32 v154, v154, v98
	v_sub_f32 v155, v155, v99
	v_sub_f32 v147, v147, v98
	v_sub_f32 v148, v148, v99
	v_sub_f32 v120, v120, v98
	v_sub_f32 v121, v121, v99
	v_sub_f32 v151, v151, v98
	v_sub_f32 v153, v153, v99
	v_fma_f32 v157, v92, v157, v98
	v_fma_f32 v156, v92, v156, v99
	v_fma_f32 v154, v93, v154, v98
	v_fma_f32 v155, v93, v155, v99
	v_fma_f32 v147, v84, v147, v98
	v_fma_f32 v148, v84, v148, v99
	v_fma_f32 v120, v85, v120, v98
	v_fma_f32 v121, v85, v121, v99
	v_fma_f32 v84, v76, v157, v140
	v_fma_f32 v76, v76, v156, v140
	v_fma_f32 v85, v77, v154, v140
	v_fma_f32 v77, v77, v155, v140
	ds_read_b128 v[72:75], v145 offset:2048
	ds_read_b128 v[64:67], v145 offset:2304
	ds_read_b128 v[88:91], v145 offset:10240
	ds_read_b128 v[80:83], v145 offset:10496
	ds_read2_b32 v[96:97], v152 offset0:128 offset1:144
	v_sub_f32 v149, v149, v98
	v_sub_f32 v150, v150, v99
	v_sub_f32 v118, v118, v98
	v_sub_f32 v119, v119, v99
	v_sub_f32 v178, v115, v98
	v_sub_f32 v179, v117, v99
	v_fma_f32 v151, v94, v151, v98
	v_fma_f32 v153, v94, v153, v99
	v_fma_f32 v115, v86, v118, v98
	v_fma_f32 v117, v86, v119, v99
	v_fma_f32 v84, v68, v147, v84
	v_fma_f32 v76, v68, v148, v76
	v_fma_f32 v86, v78, v151, v140
	v_fma_f32 v78, v78, v153, v140
	v_fma_f32 v68, v69, v120, v85
	v_fma_f32 v77, v69, v121, v77
	v_fma_f32 v149, v95, v149, v98
	v_fma_f32 v150, v95, v150, v99
	v_fma_f32 v69, v70, v115, v86
	v_fma_f32 v70, v70, v117, v78
	v_fma_f32 v98, v87, v178, v98
	v_fma_f32 v99, v87, v179, v99
	v_fma_f32 v87, v79, v149, v140
	v_fma_f32 v79, v79, v150, v140
	v_add_f32_e32 v68, v84, v68
	v_fma_f32 v78, v71, v98, v87
	v_fma_f32 v71, v71, v99, v79
	v_add_f32_e32 v76, v76, v77
	v_add_f32_e32 v69, v69, v78
	v_add_f32_e32 v70, v70, v71
	v_add_f32_e32 v68, v68, v69
	v_add_f32_e32 v70, v76, v70
	v_mov_b32_e32 v69, 0
	v_add_f32_dpp v68, v68, v68 row_ror:8 row_mask:0xf bank_mask:0xf bound_ctrl:1
	v_add_f32_dpp v70, v70, v70 row_ror:8 row_mask:0xf bank_mask:0xf bound_ctrl:1
	v_mov_b32_e32 v71, 0
	v_add_f32_dpp v68, v68, v68 row_ror:4 row_mask:0xf bank_mask:0xf bound_ctrl:1
	v_add_f32_dpp v70, v70, v70 row_ror:4 row_mask:0xf bank_mask:0xf bound_ctrl:1
	s_nop 0
	v_add_f32_dpp v68, v68, v68 row_ror:2 row_mask:0xf bank_mask:0xf bound_ctrl:1
	v_add_f32_dpp v70, v70, v70 row_ror:2 row_mask:0xf bank_mask:0xf bound_ctrl:1
	s_nop 0
	v_mov_b32_dpp v69, v68 row_ror:1 row_mask:0xf bank_mask:0xf
	v_mov_b32_dpp v71, v70 row_ror:1 row_mask:0xf bank_mask:0xf
	s_and_saveexec_b64 s[8:9], s[38:39]
	v_add_f32_e32 v70, v70, v71
	v_add_f32_e32 v68, v68, v69
	ds_write2_b32 v146, v68, v70 offset0:96 offset1:112
	s_or_b64 exec, exec, s[8:9]
	s_waitcnt lgkmcnt(0)
	v_sub_f32 v157, v157, v96
	v_sub_f32 v156, v156, v97
	v_sub_f32 v154, v154, v96
	v_sub_f32 v155, v155, v97
	v_sub_f32 v151, v151, v96
	v_sub_f32 v153, v153, v97
	v_sub_f32 v149, v149, v96
	v_sub_f32 v150, v150, v97
	v_sub_f32 v147, v147, v96
	v_sub_f32 v148, v148, v97
	v_sub_f32 v120, v120, v96
	v_sub_f32 v121, v121, v97
	v_fma_f32 v181, v88, v157, v96
	v_fma_f32 v180, v88, v156, v97
	v_fma_f32 v178, v89, v154, v96
	v_fma_f32 v179, v89, v155, v97
	v_fma_f32 v156, v90, v151, v96
	v_fma_f32 v157, v90, v153, v97
	v_fma_f32 v154, v91, v149, v96
	v_fma_f32 v155, v91, v150, v97
	v_fma_f32 v151, v80, v147, v96
	v_fma_f32 v153, v80, v148, v97
	v_fma_f32 v149, v81, v120, v96
	v_fma_f32 v150, v81, v121, v97
	v_fma_f32 v80, v72, v181, v140
	v_fma_f32 v72, v72, v180, v140
	v_fma_f32 v81, v73, v178, v140
	v_fma_f32 v73, v73, v179, v140
	ds_read_b128 v[76:79], v145 offset:2560
	ds_read_b128 v[68:71], v145 offset:2816
	ds_read_b128 v[92:95], v145 offset:10752
	ds_read_b128 v[84:87], v145 offset:11008
	ds_read2_b32 v[118:119], v152 offset0:160 offset1:176
	v_sub_f32 v115, v115, v96
	v_sub_f32 v117, v117, v97
	v_fma_f32 v80, v64, v151, v80
	v_fma_f32 v72, v64, v153, v72
	v_fma_f32 v64, v65, v149, v81
	v_fma_f32 v73, v65, v150, v73
	v_fma_f32 v147, v82, v115, v96
	v_fma_f32 v148, v82, v117, v97
	v_fma_f32 v82, v74, v156, v140
	v_fma_f32 v74, v74, v157, v140
	v_sub_f32 v98, v98, v96
	v_sub_f32 v99, v99, v97
	v_add_f32_e32 v64, v80, v64
	v_fma_f32 v65, v66, v147, v82
	v_fma_f32 v66, v66, v148, v74
	v_fma_f32 v115, v83, v98, v96
	v_fma_f32 v117, v83, v99, v97
	v_fma_f32 v83, v75, v154, v140
	v_fma_f32 v75, v75, v155, v140
	v_add_f32_e32 v72, v72, v73
	v_fma_f32 v74, v67, v115, v83
	v_fma_f32 v67, v67, v117, v75
	v_add_f32_e32 v65, v65, v74
	v_add_f32_e32 v66, v66, v67
	v_add_f32_e32 v64, v64, v65
	v_add_f32_e32 v66, v72, v66
	v_mov_b32_e32 v65, 0
	v_add_f32_dpp v64, v64, v64 row_ror:8 row_mask:0xf bank_mask:0xf bound_ctrl:1
	v_add_f32_dpp v66, v66, v66 row_ror:8 row_mask:0xf bank_mask:0xf bound_ctrl:1
	v_mov_b32_e32 v67, 0
	v_add_f32_dpp v64, v64, v64 row_ror:4 row_mask:0xf bank_mask:0xf bound_ctrl:1
	v_add_f32_dpp v66, v66, v66 row_ror:4 row_mask:0xf bank_mask:0xf bound_ctrl:1
	s_nop 0
	v_add_f32_dpp v64, v64, v64 row_ror:2 row_mask:0xf bank_mask:0xf bound_ctrl:1
	v_add_f32_dpp v66, v66, v66 row_ror:2 row_mask:0xf bank_mask:0xf bound_ctrl:1
	s_nop 0
	v_mov_b32_dpp v65, v64 row_ror:1 row_mask:0xf bank_mask:0xf
	v_mov_b32_dpp v67, v66 row_ror:1 row_mask:0xf bank_mask:0xf
	s_and_saveexec_b64 s[8:9], s[38:39]
	v_add_f32_e32 v66, v66, v67
	v_add_f32_e32 v64, v64, v65
	ds_write2_b32 v146, v64, v66 offset0:128 offset1:144
	s_or_b64 exec, exec, s[8:9]
	s_waitcnt lgkmcnt(0)
	v_sub_f32 v64, v181, v118
	v_sub_f32 v65, v180, v119
	v_sub_f32 v66, v178, v118
	v_sub_f32 v67, v179, v119
	v_sub_f32 v156, v156, v118
	v_sub_f32 v151, v151, v118
	v_sub_f32 v153, v153, v119
	v_sub_f32 v149, v149, v118
	v_sub_f32 v150, v150, v119
	v_sub_f32 v147, v147, v118
	v_fma_f32 v181, v92, v64, v118
	v_fma_f32 v180, v92, v65, v119
	v_fma_f32 v178, v93, v66, v118
	v_fma_f32 v179, v93, v67, v119
	ds_read_b128 v[80:83], v145 offset:3072
	ds_read_b128 v[72:75], v145 offset:3328
	ds_read_b128 v[96:99], v145 offset:11264
	ds_read_b128 v[88:91], v145 offset:11520
	ds_read2_b32 v[120:121], v152 offset0:192 offset1:208
	v_fma_f32 v64, v76, v181, v140
	v_fma_f32 v65, v76, v180, v140
	v_fma_f32 v66, v77, v178, v140
	v_fma_f32 v67, v77, v179, v140
	v_sub_f32 v157, v157, v119
	v_sub_f32 v154, v154, v118
	v_sub_f32 v155, v155, v119
	v_sub_f32 v148, v148, v119
	v_sub_f32 v115, v115, v118
	v_sub_f32 v117, v117, v119
	v_fma_f32 v156, v94, v156, v118
	v_fma_f32 v151, v84, v151, v118
	v_fma_f32 v153, v84, v153, v119
	v_fma_f32 v149, v85, v149, v118
	v_fma_f32 v150, v85, v150, v119
	v_fma_f32 v147, v86, v147, v118
	v_fma_f32 v76, v78, v156, v140
	v_fma_f32 v64, v68, v151, v64
	v_fma_f32 v68, v68, v153, v65
	v_fma_f32 v65, v69, v149, v66
	v_fma_f32 v66, v69, v150, v67
	v_fma_f32 v157, v94, v157, v119
	v_fma_f32 v67, v70, v147, v76
	v_fma_f32 v154, v95, v154, v118
	v_fma_f32 v155, v95, v155, v119
	v_fma_f32 v148, v86, v148, v119
	v_fma_f32 v115, v87, v115, v118
	v_fma_f32 v117, v87, v117, v119
	v_fma_f32 v77, v78, v157, v140
	v_fma_f32 v78, v79, v154, v140
	v_fma_f32 v79, v79, v155, v140
	v_add_f32_e32 v64, v64, v65
	v_fma_f32 v69, v70, v148, v77
	v_fma_f32 v70, v71, v115, v78
	v_fma_f32 v71, v71, v117, v79
	v_add_f32_e32 v66, v68, v66
	v_add_f32_e32 v65, v67, v70
	v_add_f32_e32 v67, v69, v71
	v_add_f32_e32 v64, v64, v65
	v_add_f32_e32 v66, v66, v67
	v_mov_b32_e32 v65, 0
	v_add_f32_dpp v64, v64, v64 row_ror:8 row_mask:0xf bank_mask:0xf bound_ctrl:1
	v_add_f32_dpp v66, v66, v66 row_ror:8 row_mask:0xf bank_mask:0xf bound_ctrl:1
	v_mov_b32_e32 v67, 0
	v_add_f32_dpp v64, v64, v64 row_ror:4 row_mask:0xf bank_mask:0xf bound_ctrl:1
	v_add_f32_dpp v66, v66, v66 row_ror:4 row_mask:0xf bank_mask:0xf bound_ctrl:1
	s_nop 0
	v_add_f32_dpp v64, v64, v64 row_ror:2 row_mask:0xf bank_mask:0xf bound_ctrl:1
	v_add_f32_dpp v66, v66, v66 row_ror:2 row_mask:0xf bank_mask:0xf bound_ctrl:1
	s_nop 0
	v_mov_b32_dpp v65, v64 row_ror:1 row_mask:0xf bank_mask:0xf
	v_mov_b32_dpp v67, v66 row_ror:1 row_mask:0xf bank_mask:0xf
	s_and_saveexec_b64 s[8:9], s[38:39]
	v_add_f32_e32 v66, v66, v67
	v_add_f32_e32 v64, v64, v65
	ds_write2_b32 v146, v64, v66 offset0:160 offset1:176
	s_or_b64 exec, exec, s[8:9]
	s_waitcnt lgkmcnt(0)
	v_sub_f32 v68, v181, v120
	v_sub_f32 v69, v180, v121
	v_sub_f32 v70, v178, v120
	v_sub_f32 v71, v179, v121
	v_sub_f32 v181, v157, v121
	v_sub_f32 v151, v151, v120
	v_sub_f32 v149, v149, v120
	v_fma_f32 v180, v96, v68, v120
	v_fma_f32 v179, v96, v69, v121
	v_fma_f32 v157, v97, v70, v120
	v_fma_f32 v178, v97, v71, v121
	ds_read_b128 v[76:79], v145 offset:3584
	ds_read_b128 v[64:67], v145 offset:3840
	ds_read_b128 v[92:95], v145 offset:11776
	ds_read_b128 v[84:87], v145 offset:12032
	ds_read2_b32 v[118:119], v152 offset0:224 offset1:240
	v_fma_f32 v68, v80, v180, v140
	v_fma_f32 v69, v80, v179, v140
	v_fma_f32 v70, v81, v157, v140
	v_fma_f32 v71, v81, v178, v140
	v_sub_f32 v156, v156, v120
	v_sub_f32 v154, v154, v120
	v_sub_f32 v182, v155, v121
	v_sub_f32 v183, v153, v121
	v_sub_f32 v184, v150, v121
	v_sub_f32 v185, v147, v120
	v_sub_f32 v186, v115, v120
	v_fma_f32 v155, v98, v156, v120
	v_fma_f32 v150, v88, v151, v120
	v_fma_f32 v151, v88, v183, v121
	v_fma_f32 v147, v89, v149, v120
	v_fma_f32 v149, v89, v184, v121
	v_fma_f32 v115, v90, v185, v120
	v_fma_f32 v80, v82, v155, v140
	v_fma_f32 v68, v72, v150, v68
	v_fma_f32 v72, v72, v151, v69
	v_fma_f32 v69, v73, v147, v70
	v_fma_f32 v70, v73, v149, v71
	v_sub_f32 v148, v148, v121
	v_fma_f32 v71, v74, v115, v80
	v_sub_f32 v187, v117, v121
	v_fma_f32 v156, v98, v181, v121
	v_fma_f32 v153, v99, v154, v120
	v_fma_f32 v154, v99, v182, v121
	v_fma_f32 v117, v90, v148, v121
	v_fma_f32 v96, v91, v186, v120
	v_fma_f32 v97, v91, v187, v121
	v_fma_f32 v81, v82, v156, v140
	v_fma_f32 v82, v83, v153, v140
	v_fma_f32 v83, v83, v154, v140
	v_add_f32_e32 v68, v68, v69
	v_fma_f32 v73, v74, v117, v81
	v_fma_f32 v74, v75, v96, v82
	v_fma_f32 v75, v75, v97, v83
	v_add_f32_e32 v70, v72, v70
	v_add_f32_e32 v69, v71, v74
	v_add_f32_e32 v71, v73, v75
	v_add_f32_e32 v68, v68, v69
	v_add_f32_e32 v70, v70, v71
	v_mov_b32_e32 v69, 0
	v_add_f32_dpp v68, v68, v68 row_ror:8 row_mask:0xf bank_mask:0xf bound_ctrl:1
	v_add_f32_dpp v70, v70, v70 row_ror:8 row_mask:0xf bank_mask:0xf bound_ctrl:1
	v_mov_b32_e32 v71, 0
	v_add_f32_dpp v68, v68, v68 row_ror:4 row_mask:0xf bank_mask:0xf bound_ctrl:1
	v_add_f32_dpp v70, v70, v70 row_ror:4 row_mask:0xf bank_mask:0xf bound_ctrl:1
	s_nop 0
	v_add_f32_dpp v68, v68, v68 row_ror:2 row_mask:0xf bank_mask:0xf bound_ctrl:1
	v_add_f32_dpp v70, v70, v70 row_ror:2 row_mask:0xf bank_mask:0xf bound_ctrl:1
	s_nop 0
	v_mov_b32_dpp v69, v68 row_ror:1 row_mask:0xf bank_mask:0xf
	v_mov_b32_dpp v71, v70 row_ror:1 row_mask:0xf bank_mask:0xf
	s_and_saveexec_b64 s[8:9], s[38:39]
	v_add_f32_e32 v70, v70, v71
	v_add_f32_e32 v68, v68, v69
	ds_write2_b32 v146, v68, v70 offset0:192 offset1:208
	s_or_b64 exec, exec, s[8:9]
	s_waitcnt lgkmcnt(0)
	v_sub_f32 v157, v157, v118
	v_sub_f32 v178, v178, v119
	v_sub_f32 v150, v150, v118
	v_sub_f32 v151, v151, v119
	v_sub_f32 v147, v147, v118
	v_sub_f32 v149, v149, v119
	v_sub_f32 v120, v180, v118
	v_sub_f32 v121, v179, v119
	v_sub_f32 v155, v155, v118
	v_sub_f32 v156, v156, v119
	v_fma_f32 v157, v93, v157, v118
	v_fma_f32 v178, v93, v178, v119
	v_fma_f32 v180, v92, v120, v118
	v_fma_f32 v179, v92, v121, v119
	v_fma_f32 v150, v84, v150, v118
	v_fma_f32 v151, v84, v151, v119
	v_fma_f32 v147, v85, v147, v118
	v_fma_f32 v149, v85, v149, v119
	v_fma_f32 v84, v76, v180, v140
	v_fma_f32 v76, v76, v179, v140
	v_fma_f32 v85, v77, v157, v140
	v_fma_f32 v77, v77, v178, v140
	v_sub_f32 v153, v153, v118
	v_sub_f32 v154, v154, v119
	v_sub_f32 v115, v115, v118
	v_sub_f32 v117, v117, v119
	v_fma_f32 v155, v94, v155, v118
	v_fma_f32 v156, v94, v156, v119
	v_fma_f32 v84, v64, v150, v84
	v_fma_f32 v76, v64, v151, v76
	v_fma_f32 v120, v86, v115, v118
	v_fma_f32 v121, v86, v117, v119
	v_fma_f32 v86, v78, v155, v140
	v_fma_f32 v78, v78, v156, v140
	v_fma_f32 v64, v65, v147, v85
	v_fma_f32 v77, v65, v149, v77
	ds_read_b128 v[72:75], v145 offset:4096
	ds_read_b128 v[68:71], v145 offset:4352
	ds_read_b128 v[88:91], v145 offset:12288
	ds_read_b128 v[80:83], v145 offset:12544
	v_fma_f32 v65, v66, v120, v86
	v_fma_f32 v66, v66, v121, v78
	v_sub_f32 v96, v96, v118
	v_sub_f32 v97, v97, v119
	v_fma_f32 v153, v95, v153, v118
	v_fma_f32 v154, v95, v154, v119
	v_add_f32_e32 v64, v84, v64
	v_fma_f32 v115, v87, v96, v118
	v_fma_f32 v117, v87, v97, v119
	v_fma_f32 v87, v79, v153, v140
	v_fma_f32 v79, v79, v154, v140
	v_add_f32_e32 v76, v76, v77
	v_fma_f32 v78, v67, v115, v87
	v_fma_f32 v67, v67, v117, v79
	v_add_u32_e32 v148, 0x4400, v103
	v_add_f32_e32 v65, v65, v78
	v_add_f32_e32 v66, v66, v67
	v_add_f32_e32 v64, v64, v65
	v_add_f32_e32 v66, v76, v66
	ds_read2_b32 v[98:99], v148 offset1:16
	v_mov_b32_e32 v65, 0
	v_add_f32_dpp v64, v64, v64 row_ror:8 row_mask:0xf bank_mask:0xf bound_ctrl:1
	v_add_f32_dpp v66, v66, v66 row_ror:8 row_mask:0xf bank_mask:0xf bound_ctrl:1
	v_mov_b32_e32 v67, 0
	v_add_f32_dpp v64, v64, v64 row_ror:4 row_mask:0xf bank_mask:0xf bound_ctrl:1
	v_add_f32_dpp v66, v66, v66 row_ror:4 row_mask:0xf bank_mask:0xf bound_ctrl:1
	s_nop 0
	v_add_f32_dpp v64, v64, v64 row_ror:2 row_mask:0xf bank_mask:0xf bound_ctrl:1
	v_add_f32_dpp v66, v66, v66 row_ror:2 row_mask:0xf bank_mask:0xf bound_ctrl:1
	s_nop 0
	v_mov_b32_dpp v65, v64 row_ror:1 row_mask:0xf bank_mask:0xf
	v_mov_b32_dpp v67, v66 row_ror:1 row_mask:0xf bank_mask:0xf
	s_and_saveexec_b64 s[8:9], s[38:39]
	v_add_f32_e32 v66, v66, v67
	v_add_f32_e32 v64, v64, v65
	ds_write2_b32 v146, v64, v66 offset0:224 offset1:240
	s_or_b64 exec, exec, s[8:9]
	s_waitcnt lgkmcnt(0)
	v_sub_f32 v157, v157, v98
	v_sub_f32 v150, v150, v98
	v_sub_f32 v118, v180, v98
	v_sub_f32 v119, v179, v99
	v_sub_f32 v180, v178, v99
	v_sub_f32 v155, v155, v98
	v_sub_f32 v181, v156, v99
	v_sub_f32 v183, v151, v99
	v_sub_f32 v147, v147, v98
	v_sub_f32 v184, v149, v99
	v_sub_f32 v185, v120, v98
	v_sub_f32 v186, v121, v99
	v_fma_f32 v179, v88, v118, v98
	v_fma_f32 v178, v88, v119, v99
	v_fma_f32 v156, v89, v157, v98
	v_fma_f32 v157, v89, v180, v99
	v_fma_f32 v149, v80, v150, v98
	v_fma_f32 v150, v80, v183, v99
	v_fma_f32 v120, v81, v147, v98
	v_fma_f32 v121, v81, v184, v99
	v_fma_f32 v80, v72, v179, v140
	v_fma_f32 v72, v72, v178, v140
	v_fma_f32 v81, v73, v156, v140
	v_fma_f32 v73, v73, v157, v140
	ds_read_b128 v[76:79], v145 offset:4608
	ds_read_b128 v[64:67], v145 offset:4864
	ds_read_b128 v[92:95], v145 offset:12800
	ds_read_b128 v[84:87], v145 offset:13056
	ds_read2_b32 v[96:97], v148 offset0:32 offset1:48
	v_sub_f32 v153, v153, v98
	v_sub_f32 v182, v154, v99
	v_sub_f32 v115, v115, v98
	v_sub_f32 v117, v117, v99
	v_fma_f32 v154, v90, v155, v98
	v_fma_f32 v155, v90, v181, v99
	v_fma_f32 v118, v82, v185, v98
	v_fma_f32 v119, v82, v186, v99
	v_fma_f32 v80, v68, v149, v80
	v_fma_f32 v72, v68, v150, v72
	v_fma_f32 v82, v74, v154, v140
	v_fma_f32 v74, v74, v155, v140
	v_fma_f32 v68, v69, v120, v81
	v_fma_f32 v73, v69, v121, v73
	v_fma_f32 v151, v91, v153, v98
	v_fma_f32 v153, v91, v182, v99
	v_fma_f32 v69, v70, v118, v82
	v_fma_f32 v70, v70, v119, v74
	v_fma_f32 v115, v83, v115, v98
	v_fma_f32 v117, v83, v117, v99
	v_fma_f32 v83, v75, v151, v140
	v_fma_f32 v75, v75, v153, v140
	v_add_f32_e32 v68, v80, v68
	v_fma_f32 v74, v71, v115, v83
	v_fma_f32 v71, v71, v117, v75
	v_add_f32_e32 v72, v72, v73
	v_add_f32_e32 v69, v69, v74
	v_add_f32_e32 v70, v70, v71
	v_add_f32_e32 v68, v68, v69
	v_add_f32_e32 v70, v72, v70
	v_mov_b32_e32 v69, 0
	v_add_f32_dpp v68, v68, v68 row_ror:8 row_mask:0xf bank_mask:0xf bound_ctrl:1
	v_add_f32_dpp v70, v70, v70 row_ror:8 row_mask:0xf bank_mask:0xf bound_ctrl:1
	v_mov_b32_e32 v71, 0
	v_add_f32_dpp v68, v68, v68 row_ror:4 row_mask:0xf bank_mask:0xf bound_ctrl:1
	v_add_f32_dpp v70, v70, v70 row_ror:4 row_mask:0xf bank_mask:0xf bound_ctrl:1
	v_add_u32_e32 v147, 0x9400, v103
	v_add_f32_dpp v68, v68, v68 row_ror:2 row_mask:0xf bank_mask:0xf bound_ctrl:1
	v_add_f32_dpp v70, v70, v70 row_ror:2 row_mask:0xf bank_mask:0xf bound_ctrl:1
	s_nop 0
	v_mov_b32_dpp v69, v68 row_ror:1 row_mask:0xf bank_mask:0xf
	v_mov_b32_dpp v71, v70 row_ror:1 row_mask:0xf bank_mask:0xf
	s_and_saveexec_b64 s[8:9], s[38:39]
	v_add_f32_e32 v70, v70, v71
	v_add_f32_e32 v68, v68, v69
	ds_write2_b32 v147, v68, v70 offset1:16
	s_or_b64 exec, exec, s[8:9]
	s_waitcnt lgkmcnt(0)
	v_sub_f32 v179, v179, v96
	v_sub_f32 v178, v178, v97
	v_sub_f32 v156, v156, v96
	v_sub_f32 v157, v157, v97
	v_sub_f32 v149, v149, v96
	v_sub_f32 v150, v150, v97
	v_sub_f32 v120, v120, v96
	v_sub_f32 v121, v121, v97
	v_sub_f32 v154, v154, v96
	v_sub_f32 v155, v155, v97
	v_sub_f32 v118, v118, v96
	v_sub_f32 v119, v119, v97
	v_fma_f32 v179, v92, v179, v96
	v_fma_f32 v178, v92, v178, v97
	v_fma_f32 v156, v93, v156, v96
	v_fma_f32 v157, v93, v157, v97
	v_fma_f32 v149, v84, v149, v96
	v_fma_f32 v150, v84, v150, v97
	v_fma_f32 v120, v85, v120, v96
	v_fma_f32 v121, v85, v121, v97
	v_fma_f32 v84, v76, v179, v140
	v_fma_f32 v76, v76, v178, v140
	v_fma_f32 v85, v77, v156, v140
	v_fma_f32 v77, v77, v157, v140
	ds_read_b128 v[72:75], v145 offset:5120
	ds_read_b128 v[68:71], v145 offset:5376
	ds_read_b128 v[88:91], v145 offset:13312
	ds_read_b128 v[80:83], v145 offset:13568
	ds_read2_b32 v[98:99], v148 offset0:64 offset1:80
	v_sub_f32 v151, v151, v96
	v_sub_f32 v153, v153, v97
	v_sub_f32 v115, v115, v96
	v_sub_f32 v117, v117, v97
	v_fma_f32 v154, v94, v154, v96
	v_fma_f32 v155, v94, v155, v97
	v_fma_f32 v118, v86, v118, v96
	v_fma_f32 v119, v86, v119, v97
	v_fma_f32 v84, v64, v149, v84
	v_fma_f32 v76, v64, v150, v76
	v_fma_f32 v86, v78, v154, v140
	v_fma_f32 v78, v78, v155, v140
	v_fma_f32 v64, v65, v120, v85
	v_fma_f32 v77, v65, v121, v77
	v_fma_f32 v151, v95, v151, v96
	v_fma_f32 v153, v95, v153, v97
	v_fma_f32 v65, v66, v118, v86
	v_fma_f32 v66, v66, v119, v78
	v_fma_f32 v115, v87, v115, v96
	v_fma_f32 v117, v87, v117, v97
	v_fma_f32 v87, v79, v151, v140
	v_fma_f32 v79, v79, v153, v140
	v_add_f32_e32 v64, v84, v64
	v_fma_f32 v78, v67, v115, v87
	v_fma_f32 v67, v67, v117, v79
	v_add_f32_e32 v76, v76, v77
	v_add_f32_e32 v65, v65, v78
	v_add_f32_e32 v66, v66, v67
	v_add_f32_e32 v64, v64, v65
	v_add_f32_e32 v66, v76, v66
	v_mov_b32_e32 v65, 0
	v_add_f32_dpp v64, v64, v64 row_ror:8 row_mask:0xf bank_mask:0xf bound_ctrl:1
	v_add_f32_dpp v66, v66, v66 row_ror:8 row_mask:0xf bank_mask:0xf bound_ctrl:1
	v_mov_b32_e32 v67, 0
	v_add_f32_dpp v64, v64, v64 row_ror:4 row_mask:0xf bank_mask:0xf bound_ctrl:1
	v_add_f32_dpp v66, v66, v66 row_ror:4 row_mask:0xf bank_mask:0xf bound_ctrl:1
	s_nop 0
	v_add_f32_dpp v64, v64, v64 row_ror:2 row_mask:0xf bank_mask:0xf bound_ctrl:1
	v_add_f32_dpp v66, v66, v66 row_ror:2 row_mask:0xf bank_mask:0xf bound_ctrl:1
	s_nop 0
	v_mov_b32_dpp v65, v64 row_ror:1 row_mask:0xf bank_mask:0xf
	v_mov_b32_dpp v67, v66 row_ror:1 row_mask:0xf bank_mask:0xf
	s_and_saveexec_b64 s[8:9], s[38:39]
	v_add_f32_e32 v66, v66, v67
	v_add_f32_e32 v64, v64, v65
	ds_write2_b32 v147, v64, v66 offset0:32 offset1:48
	s_or_b64 exec, exec, s[8:9]
	s_waitcnt lgkmcnt(0)
	v_sub_f32 v179, v179, v98
	v_sub_f32 v178, v178, v99
	v_sub_f32 v156, v156, v98
	v_sub_f32 v157, v157, v99
	v_sub_f32 v149, v149, v98
	v_sub_f32 v150, v150, v99
	v_sub_f32 v120, v120, v98
	v_sub_f32 v121, v121, v99
	v_sub_f32 v154, v154, v98
	v_sub_f32 v155, v155, v99
	v_sub_f32 v118, v118, v98
	v_sub_f32 v119, v119, v99
	v_fma_f32 v179, v88, v179, v98
	v_fma_f32 v178, v88, v178, v99
	v_fma_f32 v156, v89, v156, v98
	v_fma_f32 v157, v89, v157, v99
	v_fma_f32 v149, v80, v149, v98
	v_fma_f32 v150, v80, v150, v99
	v_fma_f32 v120, v81, v120, v98
	v_fma_f32 v121, v81, v121, v99
	v_fma_f32 v80, v72, v179, v140
	v_fma_f32 v72, v72, v178, v140
	v_fma_f32 v81, v73, v156, v140
	v_fma_f32 v73, v73, v157, v140
	ds_read_b128 v[76:79], v145 offset:5632
	ds_read_b128 v[64:67], v145 offset:5888
	ds_read_b128 v[92:95], v145 offset:13824
	ds_read_b128 v[84:87], v145 offset:14080
	ds_read2_b32 v[96:97], v148 offset0:96 offset1:112
	v_sub_f32 v151, v151, v98
	v_sub_f32 v153, v153, v99
	v_sub_f32 v115, v115, v98
	v_sub_f32 v117, v117, v99
	v_fma_f32 v154, v90, v154, v98
	v_fma_f32 v155, v90, v155, v99
	v_fma_f32 v118, v82, v118, v98
	v_fma_f32 v119, v82, v119, v99
	v_fma_f32 v80, v68, v149, v80
	v_fma_f32 v72, v68, v150, v72
	v_fma_f32 v82, v74, v154, v140
	v_fma_f32 v74, v74, v155, v140
	v_fma_f32 v68, v69, v120, v81
	v_fma_f32 v73, v69, v121, v73
	v_fma_f32 v151, v91, v151, v98
	v_fma_f32 v153, v91, v153, v99
	v_fma_f32 v69, v70, v118, v82
	v_fma_f32 v70, v70, v119, v74
	v_fma_f32 v115, v83, v115, v98
	v_fma_f32 v117, v83, v117, v99
	v_fma_f32 v83, v75, v151, v140
	v_fma_f32 v75, v75, v153, v140
	v_add_f32_e32 v68, v80, v68
	v_fma_f32 v74, v71, v115, v83
	v_fma_f32 v71, v71, v117, v75
	v_add_f32_e32 v72, v72, v73
	v_add_f32_e32 v69, v69, v74
	v_add_f32_e32 v70, v70, v71
	v_add_f32_e32 v68, v68, v69
	v_add_f32_e32 v70, v72, v70
	v_mov_b32_e32 v69, 0
	v_add_f32_dpp v68, v68, v68 row_ror:8 row_mask:0xf bank_mask:0xf bound_ctrl:1
	v_add_f32_dpp v70, v70, v70 row_ror:8 row_mask:0xf bank_mask:0xf bound_ctrl:1
	v_mov_b32_e32 v71, 0
	v_add_f32_dpp v68, v68, v68 row_ror:4 row_mask:0xf bank_mask:0xf bound_ctrl:1
	v_add_f32_dpp v70, v70, v70 row_ror:4 row_mask:0xf bank_mask:0xf bound_ctrl:1
	s_nop 0
	v_add_f32_dpp v68, v68, v68 row_ror:2 row_mask:0xf bank_mask:0xf bound_ctrl:1
	v_add_f32_dpp v70, v70, v70 row_ror:2 row_mask:0xf bank_mask:0xf bound_ctrl:1
	s_nop 0
	v_mov_b32_dpp v69, v68 row_ror:1 row_mask:0xf bank_mask:0xf
	v_mov_b32_dpp v71, v70 row_ror:1 row_mask:0xf bank_mask:0xf
	s_and_saveexec_b64 s[8:9], s[38:39]
	v_add_f32_e32 v70, v70, v71
	v_add_f32_e32 v68, v68, v69
	ds_write2_b32 v147, v68, v70 offset0:64 offset1:80
	s_or_b64 exec, exec, s[8:9]
	s_waitcnt lgkmcnt(0)
	v_sub_f32 v179, v179, v96
	v_sub_f32 v178, v178, v97
	v_sub_f32 v156, v156, v96
	v_sub_f32 v157, v157, v97
	v_sub_f32 v149, v149, v96
	v_sub_f32 v150, v150, v97
	v_sub_f32 v120, v120, v96
	v_sub_f32 v121, v121, v97
	v_sub_f32 v154, v154, v96
	v_sub_f32 v155, v155, v97
	v_sub_f32 v118, v118, v96
	v_sub_f32 v119, v119, v97
	v_fma_f32 v179, v92, v179, v96
	v_fma_f32 v178, v92, v178, v97
	v_fma_f32 v156, v93, v156, v96
	v_fma_f32 v157, v93, v157, v97
	v_fma_f32 v149, v84, v149, v96
	v_fma_f32 v150, v84, v150, v97
	v_fma_f32 v120, v85, v120, v96
	v_fma_f32 v121, v85, v121, v97
	v_fma_f32 v84, v76, v179, v140
	v_fma_f32 v76, v76, v178, v140
	v_fma_f32 v85, v77, v156, v140
	v_fma_f32 v77, v77, v157, v140
	ds_read_b128 v[72:75], v145 offset:6144
	ds_read_b128 v[68:71], v145 offset:6400
	ds_read_b128 v[88:91], v145 offset:14336
	ds_read_b128 v[80:83], v145 offset:14592
	ds_read2_b32 v[98:99], v148 offset0:128 offset1:144
	v_sub_f32 v151, v151, v96
	v_sub_f32 v153, v153, v97
	v_sub_f32 v115, v115, v96
	v_sub_f32 v117, v117, v97
	v_fma_f32 v154, v94, v154, v96
	v_fma_f32 v155, v94, v155, v97
	v_fma_f32 v118, v86, v118, v96
	v_fma_f32 v119, v86, v119, v97
	v_fma_f32 v84, v64, v149, v84
	v_fma_f32 v76, v64, v150, v76
	v_fma_f32 v86, v78, v154, v140
	v_fma_f32 v78, v78, v155, v140
	v_fma_f32 v64, v65, v120, v85
	v_fma_f32 v77, v65, v121, v77
	v_fma_f32 v151, v95, v151, v96
	v_fma_f32 v153, v95, v153, v97
	v_fma_f32 v65, v66, v118, v86
	v_fma_f32 v66, v66, v119, v78
	v_fma_f32 v115, v87, v115, v96
	v_fma_f32 v117, v87, v117, v97
	v_fma_f32 v87, v79, v151, v140
	v_fma_f32 v79, v79, v153, v140
	v_add_f32_e32 v64, v84, v64
	v_fma_f32 v78, v67, v115, v87
	v_fma_f32 v67, v67, v117, v79
	v_add_f32_e32 v76, v76, v77
	v_add_f32_e32 v65, v65, v78
	v_add_f32_e32 v66, v66, v67
	v_add_f32_e32 v64, v64, v65
	v_add_f32_e32 v66, v76, v66
	v_mov_b32_e32 v65, 0
	v_add_f32_dpp v64, v64, v64 row_ror:8 row_mask:0xf bank_mask:0xf bound_ctrl:1
	v_add_f32_dpp v66, v66, v66 row_ror:8 row_mask:0xf bank_mask:0xf bound_ctrl:1
	v_mov_b32_e32 v67, 0
	v_add_f32_dpp v64, v64, v64 row_ror:4 row_mask:0xf bank_mask:0xf bound_ctrl:1
	v_add_f32_dpp v66, v66, v66 row_ror:4 row_mask:0xf bank_mask:0xf bound_ctrl:1
	s_nop 0
	v_add_f32_dpp v64, v64, v64 row_ror:2 row_mask:0xf bank_mask:0xf bound_ctrl:1
	v_add_f32_dpp v66, v66, v66 row_ror:2 row_mask:0xf bank_mask:0xf bound_ctrl:1
	s_nop 0
	v_mov_b32_dpp v65, v64 row_ror:1 row_mask:0xf bank_mask:0xf
	v_mov_b32_dpp v67, v66 row_ror:1 row_mask:0xf bank_mask:0xf
	s_and_saveexec_b64 s[8:9], s[38:39]
	v_add_f32_e32 v66, v66, v67
	v_add_f32_e32 v64, v64, v65
	ds_write2_b32 v147, v64, v66 offset0:96 offset1:112
	s_or_b64 exec, exec, s[8:9]
	s_waitcnt lgkmcnt(0)
	v_sub_f32 v179, v179, v98
	v_sub_f32 v178, v178, v99
	v_sub_f32 v156, v156, v98
	v_sub_f32 v157, v157, v99
	v_sub_f32 v149, v149, v98
	v_sub_f32 v150, v150, v99
	v_sub_f32 v120, v120, v98
	v_sub_f32 v121, v121, v99
	v_sub_f32 v154, v154, v98
	v_sub_f32 v155, v155, v99
	v_sub_f32 v118, v118, v98
	v_sub_f32 v119, v119, v99
	v_fma_f32 v179, v88, v179, v98
	v_fma_f32 v178, v88, v178, v99
	v_fma_f32 v156, v89, v156, v98
	v_fma_f32 v157, v89, v157, v99
	v_fma_f32 v149, v80, v149, v98
	v_fma_f32 v150, v80, v150, v99
	v_fma_f32 v120, v81, v120, v98
	v_fma_f32 v121, v81, v121, v99
	v_fma_f32 v80, v72, v179, v140
	v_fma_f32 v72, v72, v178, v140
	v_fma_f32 v81, v73, v156, v140
	v_fma_f32 v73, v73, v157, v140
	ds_read_b128 v[76:79], v145 offset:6656
	ds_read_b128 v[64:67], v145 offset:6912
	ds_read_b128 v[92:95], v145 offset:14848
	ds_read_b128 v[84:87], v145 offset:15104
	ds_read2_b32 v[96:97], v148 offset0:160 offset1:176
	v_sub_f32 v151, v151, v98
	v_sub_f32 v153, v153, v99
	v_sub_f32 v115, v115, v98
	v_sub_f32 v117, v117, v99
	v_fma_f32 v154, v90, v154, v98
	v_fma_f32 v155, v90, v155, v99
	v_fma_f32 v118, v82, v118, v98
	v_fma_f32 v119, v82, v119, v99
	v_fma_f32 v80, v68, v149, v80
	v_fma_f32 v72, v68, v150, v72
	v_fma_f32 v82, v74, v154, v140
	v_fma_f32 v74, v74, v155, v140
	v_fma_f32 v68, v69, v120, v81
	v_fma_f32 v73, v69, v121, v73
	v_fma_f32 v151, v91, v151, v98
	v_fma_f32 v153, v91, v153, v99
	v_fma_f32 v69, v70, v118, v82
	v_fma_f32 v70, v70, v119, v74
	v_fma_f32 v115, v83, v115, v98
	v_fma_f32 v117, v83, v117, v99
	v_fma_f32 v83, v75, v151, v140
	v_fma_f32 v75, v75, v153, v140
	v_add_f32_e32 v68, v80, v68
	v_fma_f32 v74, v71, v115, v83
	v_fma_f32 v71, v71, v117, v75
	v_add_f32_e32 v72, v72, v73
	v_add_f32_e32 v69, v69, v74
	v_add_f32_e32 v70, v70, v71
	v_add_f32_e32 v68, v68, v69
	v_add_f32_e32 v70, v72, v70
	v_mov_b32_e32 v69, 0
	v_add_f32_dpp v68, v68, v68 row_ror:8 row_mask:0xf bank_mask:0xf bound_ctrl:1
	v_add_f32_dpp v70, v70, v70 row_ror:8 row_mask:0xf bank_mask:0xf bound_ctrl:1
	v_mov_b32_e32 v71, 0
	v_add_f32_dpp v68, v68, v68 row_ror:4 row_mask:0xf bank_mask:0xf bound_ctrl:1
	v_add_f32_dpp v70, v70, v70 row_ror:4 row_mask:0xf bank_mask:0xf bound_ctrl:1
	s_nop 0
	v_add_f32_dpp v68, v68, v68 row_ror:2 row_mask:0xf bank_mask:0xf bound_ctrl:1
	v_add_f32_dpp v70, v70, v70 row_ror:2 row_mask:0xf bank_mask:0xf bound_ctrl:1
	s_nop 0
	v_mov_b32_dpp v69, v68 row_ror:1 row_mask:0xf bank_mask:0xf
	v_mov_b32_dpp v71, v70 row_ror:1 row_mask:0xf bank_mask:0xf
	s_and_saveexec_b64 s[8:9], s[38:39]
	v_add_f32_e32 v70, v70, v71
	v_add_f32_e32 v68, v68, v69
	ds_write2_b32 v147, v68, v70 offset0:128 offset1:144
	s_or_b64 exec, exec, s[8:9]
	s_waitcnt lgkmcnt(0)
	v_sub_f32 v179, v179, v96
	v_sub_f32 v178, v178, v97
	v_sub_f32 v156, v156, v96
	v_sub_f32 v157, v157, v97
	v_sub_f32 v149, v149, v96
	v_sub_f32 v150, v150, v97
	v_sub_f32 v120, v120, v96
	v_sub_f32 v121, v121, v97
	v_sub_f32 v154, v154, v96
	v_sub_f32 v155, v155, v97
	v_sub_f32 v118, v118, v96
	v_sub_f32 v119, v119, v97
	v_fma_f32 v179, v92, v179, v96
	v_fma_f32 v178, v92, v178, v97
	v_fma_f32 v156, v93, v156, v96
	v_fma_f32 v157, v93, v157, v97
	v_fma_f32 v149, v84, v149, v96
	v_fma_f32 v150, v84, v150, v97
	v_fma_f32 v120, v85, v120, v96
	v_fma_f32 v121, v85, v121, v97
	v_fma_f32 v84, v76, v179, v140
	v_fma_f32 v76, v76, v178, v140
	v_fma_f32 v85, v77, v156, v140
	v_fma_f32 v77, v77, v157, v140
	ds_read_b128 v[72:75], v145 offset:7168
	ds_read_b128 v[68:71], v145 offset:7424
	ds_read_b128 v[88:91], v145 offset:15360
	ds_read_b128 v[80:83], v145 offset:15616
	ds_read2_b32 v[98:99], v148 offset0:192 offset1:208
	v_sub_f32 v151, v151, v96
	v_sub_f32 v153, v153, v97
	v_sub_f32 v115, v115, v96
	v_sub_f32 v117, v117, v97
	v_fma_f32 v154, v94, v154, v96
	v_fma_f32 v155, v94, v155, v97
	v_fma_f32 v118, v86, v118, v96
	v_fma_f32 v119, v86, v119, v97
	v_fma_f32 v84, v64, v149, v84
	v_fma_f32 v76, v64, v150, v76
	v_fma_f32 v86, v78, v154, v140
	v_fma_f32 v78, v78, v155, v140
	v_fma_f32 v64, v65, v120, v85
	v_fma_f32 v77, v65, v121, v77
	v_fma_f32 v151, v95, v151, v96
	v_fma_f32 v153, v95, v153, v97
	v_fma_f32 v65, v66, v118, v86
	v_fma_f32 v66, v66, v119, v78
	v_fma_f32 v115, v87, v115, v96
	v_fma_f32 v117, v87, v117, v97
	v_fma_f32 v87, v79, v151, v140
	v_fma_f32 v79, v79, v153, v140
	v_add_f32_e32 v64, v84, v64
	v_fma_f32 v78, v67, v115, v87
	v_fma_f32 v67, v67, v117, v79
	v_add_f32_e32 v76, v76, v77
	v_add_f32_e32 v65, v65, v78
	v_add_f32_e32 v66, v66, v67
	v_add_f32_e32 v64, v64, v65
	v_add_f32_e32 v66, v76, v66
	v_mov_b32_e32 v65, 0
	v_add_f32_dpp v64, v64, v64 row_ror:8 row_mask:0xf bank_mask:0xf bound_ctrl:1
	v_add_f32_dpp v66, v66, v66 row_ror:8 row_mask:0xf bank_mask:0xf bound_ctrl:1
	v_mov_b32_e32 v67, 0
	v_add_f32_dpp v64, v64, v64 row_ror:4 row_mask:0xf bank_mask:0xf bound_ctrl:1
	v_add_f32_dpp v66, v66, v66 row_ror:4 row_mask:0xf bank_mask:0xf bound_ctrl:1
	s_nop 0
	v_add_f32_dpp v64, v64, v64 row_ror:2 row_mask:0xf bank_mask:0xf bound_ctrl:1
	v_add_f32_dpp v66, v66, v66 row_ror:2 row_mask:0xf bank_mask:0xf bound_ctrl:1
	s_nop 0
	v_mov_b32_dpp v65, v64 row_ror:1 row_mask:0xf bank_mask:0xf
	v_mov_b32_dpp v67, v66 row_ror:1 row_mask:0xf bank_mask:0xf
	s_and_saveexec_b64 s[8:9], s[38:39]
	v_add_f32_e32 v66, v66, v67
	v_add_f32_e32 v64, v64, v65
	ds_write2_b32 v147, v64, v66 offset0:160 offset1:176
	s_or_b64 exec, exec, s[8:9]
	s_waitcnt lgkmcnt(0)
	v_sub_f32 v179, v179, v98
	v_sub_f32 v178, v178, v99
	v_sub_f32 v156, v156, v98
	v_sub_f32 v157, v157, v99
	v_sub_f32 v154, v154, v98
	v_sub_f32 v155, v155, v99
	v_sub_f32 v180, v151, v98
	v_sub_f32 v153, v153, v99
	v_sub_f32 v181, v149, v98
	v_sub_f32 v182, v150, v99
	v_sub_f32 v183, v120, v98
	v_sub_f32 v184, v121, v99
	v_sub_f32 v185, v118, v98
	v_sub_f32 v186, v119, v99
	v_sub_f32 v187, v115, v98
	v_sub_f32 v188, v117, v99
	v_fma_f32 v151, v88, v179, v98
	v_fma_f32 v150, v88, v178, v99
	v_fma_f32 v121, v89, v156, v98
	v_fma_f32 v149, v89, v157, v99
	v_fma_f32 v119, v90, v154, v98
	v_fma_f32 v120, v90, v155, v99
	v_fma_f32 v117, v91, v180, v98
	v_fma_f32 v118, v91, v153, v99
	v_fma_f32 v91, v80, v181, v98
	v_fma_f32 v115, v80, v182, v99
	v_fma_f32 v89, v81, v183, v98
	v_fma_f32 v90, v81, v184, v99
	v_fma_f32 v88, v82, v185, v98
	v_fma_f32 v80, v83, v187, v98
	v_fma_f32 v81, v83, v188, v99
	v_fma_f32 v83, v72, v151, v140
	v_fma_f32 v72, v72, v150, v140
	v_fma_f32 v98, v73, v121, v140
	v_fma_f32 v73, v73, v149, v140
	ds_read_b128 v[76:79], v145 offset:7680
	ds_read_b128 v[64:67], v145 offset:7936
	ds_read_b128 v[92:95], v145 offset:15872
	ds_read_b128 v[84:87], v145 offset:16128
	ds_read2_b32 v[96:97], v148 offset0:224 offset1:240
	v_fma_f32 v82, v82, v186, v99
	v_fma_f32 v99, v74, v119, v140
	v_fma_f32 v74, v74, v120, v140
	v_fma_f32 v83, v68, v91, v83
	v_fma_f32 v72, v68, v115, v72
	v_fma_f32 v68, v69, v89, v98
	v_fma_f32 v73, v69, v90, v73
	v_fma_f32 v69, v70, v88, v99
	v_fma_f32 v70, v70, v82, v74
	v_fma_f32 v153, v75, v117, v140
	v_fma_f32 v75, v75, v118, v140
	v_add_f32_e32 v68, v83, v68
	v_fma_f32 v74, v71, v80, v153
	v_fma_f32 v71, v71, v81, v75
	v_add_f32_e32 v72, v72, v73
	v_add_f32_e32 v69, v69, v74
	v_add_f32_e32 v70, v70, v71
	v_add_f32_e32 v68, v68, v69
	v_add_f32_e32 v70, v72, v70
	v_mov_b32_e32 v69, 0
	v_add_f32_dpp v68, v68, v68 row_ror:8 row_mask:0xf bank_mask:0xf bound_ctrl:1
	v_add_f32_dpp v70, v70, v70 row_ror:8 row_mask:0xf bank_mask:0xf bound_ctrl:1
	v_mov_b32_e32 v71, 0
	v_add_f32_dpp v68, v68, v68 row_ror:4 row_mask:0xf bank_mask:0xf bound_ctrl:1
	v_add_f32_dpp v70, v70, v70 row_ror:4 row_mask:0xf bank_mask:0xf bound_ctrl:1
	s_nop 0
	v_add_f32_dpp v68, v68, v68 row_ror:2 row_mask:0xf bank_mask:0xf bound_ctrl:1
	v_add_f32_dpp v70, v70, v70 row_ror:2 row_mask:0xf bank_mask:0xf bound_ctrl:1
	s_nop 0
	v_mov_b32_dpp v69, v68 row_ror:1 row_mask:0xf bank_mask:0xf
	v_mov_b32_dpp v71, v70 row_ror:1 row_mask:0xf bank_mask:0xf
	s_and_saveexec_b64 s[8:9], s[38:39]
	v_add_f32_e32 v70, v70, v71
	v_add_f32_e32 v68, v68, v69
	ds_write2_b32 v147, v68, v70 offset0:192 offset1:208
	s_or_b64 exec, exec, s[8:9]
	s_waitcnt lgkmcnt(0)
	v_sub_f32 v72, v119, v96
	v_sub_f32 v73, v120, v97
	v_sub_f32 v74, v117, v96
	v_sub_f32 v68, v151, v96
	v_sub_f32 v69, v150, v97
	v_sub_f32 v70, v121, v96
	v_sub_f32 v71, v149, v97
	v_sub_f32 v75, v118, v97
	v_fma_f32 v120, v94, v72, v96
	v_fma_f32 v154, v92, v68, v96
	v_fma_f32 v151, v92, v69, v97
	v_fma_f32 v149, v93, v70, v96
	v_fma_f32 v121, v94, v73, v97
	v_fma_f32 v94, v95, v74, v96
	v_sub_f32 v83, v91, v96
	v_fma_f32 v72, v76, v154, v140
	v_fma_f32 v73, v76, v151, v140
	v_fma_f32 v74, v77, v149, v140
	v_sub_f32 v91, v115, v97
	v_sub_f32 v89, v89, v96
	v_sub_f32 v90, v90, v97
	v_sub_f32 v88, v88, v96
	v_sub_f32 v82, v82, v97
	v_fma_f32 v150, v93, v71, v97
	v_fma_f32 v95, v95, v75, v97
	v_fma_f32 v92, v84, v83, v96
	v_fma_f32 v93, v84, v91, v97
	v_fma_f32 v84, v85, v89, v96
	v_fma_f32 v85, v85, v90, v97
	v_fma_f32 v70, v86, v88, v96
	v_fma_f32 v71, v86, v82, v97
	v_fma_f32 v75, v77, v150, v140
	v_fma_f32 v76, v78, v120, v140
	v_fma_f32 v77, v78, v121, v140
	v_fma_f32 v72, v64, v92, v72
	v_fma_f32 v73, v64, v93, v73
	v_fma_f32 v64, v65, v84, v74
	v_fma_f32 v74, v65, v85, v75
	v_fma_f32 v65, v66, v70, v76
	v_fma_f32 v66, v66, v71, v77
	v_sub_f32 v80, v80, v96
	v_sub_f32 v81, v81, v97
	v_fma_f32 v78, v79, v94, v140
	v_fma_f32 v79, v79, v95, v140
	v_add_f32_e32 v64, v72, v64
	v_fma_f32 v68, v87, v80, v96
	v_fma_f32 v69, v87, v81, v97
	v_add_f32_e32 v72, v73, v74
	v_fma_f32 v75, v67, v68, v78
	v_fma_f32 v67, v67, v69, v79
	v_add_f32_e32 v65, v65, v75
	v_add_f32_e32 v66, v66, v67
	v_add_f32_e32 v64, v64, v65
	v_add_f32_e32 v66, v72, v66
	v_mov_b32_e32 v65, 0
	v_add_f32_dpp v64, v64, v64 row_ror:8 row_mask:0xf bank_mask:0xf bound_ctrl:1
	v_add_f32_dpp v66, v66, v66 row_ror:8 row_mask:0xf bank_mask:0xf bound_ctrl:1
	v_mov_b32_e32 v67, 0
	v_add_f32_dpp v64, v64, v64 row_ror:4 row_mask:0xf bank_mask:0xf bound_ctrl:1
	v_add_f32_dpp v66, v66, v66 row_ror:4 row_mask:0xf bank_mask:0xf bound_ctrl:1
	s_nop 0
	v_add_f32_dpp v64, v64, v64 row_ror:2 row_mask:0xf bank_mask:0xf bound_ctrl:1
	v_add_f32_dpp v66, v66, v66 row_ror:2 row_mask:0xf bank_mask:0xf bound_ctrl:1
	s_nop 0
	v_mov_b32_dpp v65, v64 row_ror:1 row_mask:0xf bank_mask:0xf
	v_mov_b32_dpp v67, v66 row_ror:1 row_mask:0xf bank_mask:0xf
	s_and_saveexec_b64 s[8:9], s[38:39]
	v_add_f32_e32 v66, v66, v67
	v_add_f32_e32 v64, v64, v65
	ds_write2_b32 v147, v64, v66 offset0:224 offset1:240
	s_or_b64 exec, exec, s[8:9]
	s_waitcnt vmcnt(9)
	v_mul_f32_e32 v64, 0xbfb8aa3b, v16
	v_mul_f32_e32 v65, 0xbfb8aa3b, v17
	v_exp_f32_e32 v64, v64
	v_exp_f32_e32 v65, v65
	v_mul_f32_e32 v66, 0xbfb8aa3b, v18
	v_mul_f32_e32 v67, 0xbfb8aa3b, v19
	v_exp_f32_e32 v66, v66
	v_pk_add_f32 v[64:65], v[64:65], 1.0 op_sel_hi:[1,0]
	v_exp_f32_e32 v67, v67
	v_div_scale_f32 v76, s[8:9], v65, v65, v17
	v_rcp_f32_e32 v77, v76
	v_pk_add_f32 v[66:67], v[66:67], 1.0 op_sel_hi:[1,0]
	s_waitcnt vmcnt(8)
	v_mul_f32_e32 v72, 0xbfb8aa3b, v20
	v_mul_f32_e32 v73, 0xbfb8aa3b, v21
	v_fma_f32 v78, -v76, v77, 1.0
	v_fmac_f32_e32 v77, v78, v77
	v_div_scale_f32 v78, vcc, v17, v65, v17
	v_mul_f32_e32 v79, v78, v77
	v_fma_f32 v80, -v76, v79, v78
	v_fmac_f32_e32 v79, v80, v77
	v_fma_f32 v76, -v76, v79, v78
	v_div_fmas_f32 v76, v76, v77, v79
	v_div_fixup_f32 v65, v76, v65, v17
	v_div_scale_f32 v76, s[8:9], v64, v64, v16
	v_rcp_f32_e32 v77, v76
	v_exp_f32_e32 v72, v72
	v_exp_f32_e32 v73, v73
	v_mul_f32_e32 v74, 0xbfb8aa3b, v22
	v_fma_f32 v78, -v76, v77, 1.0
	v_fmac_f32_e32 v77, v78, v77
	v_div_scale_f32 v78, vcc, v16, v64, v16
	v_mul_f32_e32 v79, v78, v77
	v_fma_f32 v80, -v76, v79, v78
	v_fmac_f32_e32 v79, v80, v77
	v_fma_f32 v76, -v76, v79, v78
	v_div_fmas_f32 v76, v76, v77, v79
	v_div_fixup_f32 v64, v76, v64, v16
	v_div_scale_f32 v76, s[8:9], v67, v67, v19
	v_rcp_f32_e32 v77, v76
	v_pk_mul_f32 v[64:65], v[64:65], s[18:19] op_sel_hi:[1,0]
	v_mul_f32_e32 v75, 0xbfb8aa3b, v23
	v_exp_f32_e32 v74, v74
	v_fma_f32 v78, -v76, v77, 1.0
	v_fmac_f32_e32 v77, v78, v77
	v_div_scale_f32 v78, vcc, v19, v67, v19
	v_mul_f32_e32 v79, v78, v77
	v_fma_f32 v80, -v76, v79, v78
	v_fmac_f32_e32 v79, v80, v77
	v_fma_f32 v76, -v76, v79, v78
	v_div_fmas_f32 v76, v76, v77, v79
	v_div_fixup_f32 v67, v76, v67, v19
	v_div_scale_f32 v76, s[8:9], v66, v66, v18
	v_rcp_f32_e32 v77, v76
	v_exp_f32_e32 v75, v75
	s_cmpk_lt_u32 s48, 0x7b
	v_fma_f32 v78, -v76, v77, 1.0
	v_fmac_f32_e32 v77, v78, v77
	v_div_scale_f32 v78, vcc, v18, v66, v18
	v_mul_f32_e32 v79, v78, v77
	v_fma_f32 v80, -v76, v79, v78
	v_fmac_f32_e32 v79, v80, v77
	v_fma_f32 v76, -v76, v79, v78
	v_div_fmas_f32 v76, v76, v77, v79
	v_div_fixup_f32 v66, v76, v66, v18
	v_pk_mul_f32 v[66:67], v[66:67], s[18:19] op_sel_hi:[1,0]
	ds_write_b128 v141, v[64:67] offset:18432
	v_pk_add_f32 v[64:65], v[72:73], 1.0 op_sel_hi:[1,0]
	v_div_scale_f32 v66, s[8:9], v65, v65, 1.0
	v_rcp_f32_e32 v67, v66
	s_nop 0
	v_fma_f32 v72, -v66, v67, 1.0
	v_fmac_f32_e32 v67, v72, v67
	v_div_scale_f32 v72, vcc, 1.0, v65, 1.0
	v_mul_f32_e32 v73, v72, v67
	v_fma_f32 v76, -v66, v73, v72
	v_fmac_f32_e32 v73, v76, v67
	v_fma_f32 v66, -v66, v73, v72
	v_div_fmas_f32 v66, v66, v67, v73
	v_div_fixup_f32 v65, v66, v65, 1.0
	v_div_scale_f32 v66, s[8:9], v64, v64, 1.0
	v_rcp_f32_e32 v67, v66
	s_nop 0
	v_fma_f32 v72, -v66, v67, 1.0
	v_fmac_f32_e32 v67, v72, v67
	v_div_scale_f32 v72, vcc, 1.0, v64, 1.0
	v_mul_f32_e32 v73, v72, v67
	v_fma_f32 v76, -v66, v73, v72
	v_fmac_f32_e32 v73, v76, v67
	v_fma_f32 v66, -v66, v73, v72
	v_div_fmas_f32 v66, v66, v67, v73
	v_div_fixup_f32 v64, v66, v64, 1.0
	v_pk_add_f32 v[66:67], v[74:75], 1.0 op_sel_hi:[1,0]
	v_pk_fma_f32 v[64:65], v[110:111], v[64:65], v[104:105]
	v_div_scale_f32 v72, s[8:9], v67, v67, 1.0
	v_rcp_f32_e32 v73, v72
	s_nop 0
	v_fma_f32 v74, -v72, v73, 1.0
	v_fmac_f32_e32 v73, v74, v73
	v_div_scale_f32 v74, vcc, 1.0, v67, 1.0
	v_mul_f32_e32 v75, v74, v73
	v_fma_f32 v76, -v72, v75, v74
	v_fmac_f32_e32 v75, v76, v73
	v_fma_f32 v72, -v72, v75, v74
	v_div_fmas_f32 v72, v72, v73, v75
	v_div_fixup_f32 v67, v72, v67, 1.0
	v_div_scale_f32 v72, s[8:9], v66, v66, 1.0
	v_rcp_f32_e32 v73, v72
	s_nop 0
	v_fma_f32 v74, -v72, v73, 1.0
	v_fmac_f32_e32 v73, v74, v73
	v_div_scale_f32 v74, vcc, 1.0, v66, 1.0
	v_mul_f32_e32 v75, v74, v73
	v_fma_f32 v76, -v72, v75, v74
	v_fmac_f32_e32 v75, v76, v73
	v_fma_f32 v72, -v72, v75, v74
	v_div_fmas_f32 v72, v72, v73, v75
	v_div_fixup_f32 v66, v72, v66, 1.0
	v_pk_fma_f32 v[66:67], v[112:113], v[66:67], v[106:107]
	ds_write_b128 v141, v[64:67] offset:26624
	ds_write_b32 v134, v129 offset:34816
	v_mul_f32_e32 v64, 0xbfb8aa3b, v24
	v_mul_f32_e32 v65, 0xbfb8aa3b, v25
	v_exp_f32_e32 v64, v64
	v_exp_f32_e32 v65, v65
	v_mul_f32_e32 v66, 0xbfb8aa3b, v26
	v_mul_f32_e32 v67, 0xbfb8aa3b, v27
	v_exp_f32_e32 v66, v66
	v_pk_add_f32 v[64:65], v[64:65], 1.0 op_sel_hi:[1,0]
	v_exp_f32_e32 v67, v67
	v_div_scale_f32 v76, s[8:9], v65, v65, v25
	v_rcp_f32_e32 v77, v76
	v_pk_add_f32 v[66:67], v[66:67], 1.0 op_sel_hi:[1,0]
	v_mul_f32_e32 v72, 0xbfb8aa3b, v36
	v_mul_f32_e32 v73, 0xbfb8aa3b, v37
	v_fma_f32 v78, -v76, v77, 1.0
	v_fmac_f32_e32 v77, v78, v77
	v_div_scale_f32 v78, vcc, v25, v65, v25
	v_mul_f32_e32 v79, v78, v77
	v_fma_f32 v80, -v76, v79, v78
	v_fmac_f32_e32 v79, v80, v77
	v_fma_f32 v76, -v76, v79, v78
	v_div_fmas_f32 v76, v76, v77, v79
	v_div_fixup_f32 v65, v76, v65, v25
	v_div_scale_f32 v76, s[8:9], v64, v64, v24
	v_rcp_f32_e32 v77, v76
	v_exp_f32_e32 v72, v72
	v_exp_f32_e32 v73, v73
	v_mul_f32_e32 v74, 0xbfb8aa3b, v38
	v_fma_f32 v78, -v76, v77, 1.0
	v_fmac_f32_e32 v77, v78, v77
	v_div_scale_f32 v78, vcc, v24, v64, v24
	v_mul_f32_e32 v79, v78, v77
	v_fma_f32 v80, -v76, v79, v78
	v_fmac_f32_e32 v79, v80, v77
	v_fma_f32 v76, -v76, v79, v78
	v_div_fmas_f32 v76, v76, v77, v79
	v_div_fixup_f32 v64, v76, v64, v24
	v_div_scale_f32 v76, s[8:9], v67, v67, v27
	v_rcp_f32_e32 v77, v76
	v_pk_mul_f32 v[64:65], v[64:65], s[18:19] op_sel_hi:[1,0]
	v_mul_f32_e32 v75, 0xbfb8aa3b, v39
	v_exp_f32_e32 v74, v74
	v_fma_f32 v78, -v76, v77, 1.0
	v_fmac_f32_e32 v77, v78, v77
	v_div_scale_f32 v78, vcc, v27, v67, v27
	v_mul_f32_e32 v79, v78, v77
	v_fma_f32 v80, -v76, v79, v78
	v_fmac_f32_e32 v79, v80, v77
	v_fma_f32 v76, -v76, v79, v78
	v_div_fmas_f32 v76, v76, v77, v79
	v_div_fixup_f32 v67, v76, v67, v27
	v_div_scale_f32 v76, s[8:9], v66, v66, v26
	v_rcp_f32_e32 v77, v76
	v_exp_f32_e32 v75, v75
	v_fma_f32 v78, -v76, v77, 1.0
	v_fmac_f32_e32 v77, v78, v77
	v_div_scale_f32 v78, vcc, v26, v66, v26
	v_mul_f32_e32 v79, v78, v77
	v_fma_f32 v80, -v76, v79, v78
	v_fmac_f32_e32 v79, v80, v77
	v_fma_f32 v76, -v76, v79, v78
	v_div_fmas_f32 v76, v76, v77, v79
	v_div_fixup_f32 v66, v76, v66, v26
	v_pk_mul_f32 v[66:67], v[66:67], s[18:19] op_sel_hi:[1,0]
	ds_write_b128 v144, v[64:67] offset:18432
	v_pk_add_f32 v[64:65], v[72:73], 1.0 op_sel_hi:[1,0]
	v_div_scale_f32 v66, s[8:9], v65, v65, 1.0
	v_rcp_f32_e32 v67, v66
	s_nop 0
	v_fma_f32 v72, -v66, v67, 1.0
	v_fmac_f32_e32 v67, v72, v67
	v_div_scale_f32 v72, vcc, 1.0, v65, 1.0
	v_mul_f32_e32 v73, v72, v67
	v_fma_f32 v76, -v66, v73, v72
	v_fmac_f32_e32 v73, v76, v67
	v_fma_f32 v66, -v66, v73, v72
	v_div_fmas_f32 v66, v66, v67, v73
	v_div_fixup_f32 v65, v66, v65, 1.0
	v_div_scale_f32 v66, s[8:9], v64, v64, 1.0
	v_rcp_f32_e32 v67, v66
	s_nop 0
	v_fma_f32 v72, -v66, v67, 1.0
	v_fmac_f32_e32 v67, v72, v67
	v_div_scale_f32 v72, vcc, 1.0, v64, 1.0
	v_mul_f32_e32 v73, v72, v67
	v_fma_f32 v76, -v66, v73, v72
	v_fmac_f32_e32 v73, v76, v67
	v_fma_f32 v66, -v66, v73, v72
	v_div_fmas_f32 v66, v66, v67, v73
	v_div_fixup_f32 v64, v66, v64, 1.0
	v_pk_add_f32 v[66:67], v[74:75], 1.0 op_sel_hi:[1,0]
	v_pk_fma_f32 v[64:65], v[110:111], v[64:65], v[104:105]
	v_div_scale_f32 v72, s[8:9], v67, v67, 1.0
	v_rcp_f32_e32 v73, v72
	s_nop 0
	v_fma_f32 v74, -v72, v73, 1.0
	v_fmac_f32_e32 v73, v74, v73
	v_div_scale_f32 v74, vcc, 1.0, v67, 1.0
	v_mul_f32_e32 v75, v74, v73
	v_fma_f32 v76, -v72, v75, v74
	v_fmac_f32_e32 v75, v76, v73
	v_fma_f32 v72, -v72, v75, v74
	v_div_fmas_f32 v72, v72, v73, v75
	v_div_fixup_f32 v67, v72, v67, 1.0
	v_div_scale_f32 v72, s[8:9], v66, v66, 1.0
	v_rcp_f32_e32 v73, v72
	s_mov_b64 s[8:9], -1
	v_fma_f32 v74, -v72, v73, 1.0
	v_fmac_f32_e32 v73, v74, v73
	v_div_scale_f32 v74, vcc, 1.0, v66, 1.0
	v_mul_f32_e32 v75, v74, v73
	v_fma_f32 v76, -v72, v75, v74
	v_fmac_f32_e32 v75, v76, v73
	v_fma_f32 v72, -v72, v75, v74
	v_div_fmas_f32 v72, v72, v73, v75
	v_div_fixup_f32 v66, v72, v66, 1.0
	v_pk_fma_f32 v[66:67], v[112:113], v[66:67], v[106:107]
	ds_write_b128 v144, v[64:67] offset:26624
	ds_write_b32 v134, v130 offset:35840
	s_waitcnt lgkmcnt(0)
	s_barrier
	v_add_u32_e32 v64, s47, v124
	v_add_u32_e32 v65, s47, v126
	s_cbranch_scc1 .LBB0_1323
	v_add_u32_e32 v98, s47, v124
	v_add_u32_e32 v96, s47, v126
	s_mov_b64 s[8:9], 0

.LBB0_1325:
	ds_read2st64_b32 v[64:65], v134 offset0:144 offset1:148
	v_ashrrev_i32_e32 v99, 31, v98
	v_lshlrev_b64 v[66:67], 12, v[98:99]
	v_ashrrev_i32_e32 v97, 31, v96
	v_lshl_add_u64 v[66:67], v[108:109], 0, v[66:67]
	s_waitcnt lgkmcnt(0)
	global_store_dword v[66:67], v64, off
	v_lshlrev_b64 v[66:67], 12, v[96:97]
	v_lshl_add_u64 v[66:67], v[108:109], 0, v[66:67]
	global_store_dword v[66:67], v65, off
	ds_read_b128 v[76:79], v145 offset:18432
	ds_read_b128 v[184:187], v145 offset:18688
	ds_read_b128 v[188:191], v145 offset:26624
	ds_read_b128 v[192:195], v145 offset:26880
	v_add_u32_e32 v153, 0x8800, v103
	ds_read2_b32 v[86:87], v153 offset1:16
	ds_read_b128 v[72:75], v145 offset:18944
	ds_read_b128 v[64:67], v145 offset:19200
	ds_read_b128 v[88:91], v145 offset:27136
	ds_read_b128 v[80:83], v145 offset:27392
	ds_read2_b32 v[118:119], v153 offset0:32 offset1:48
	s_waitcnt lgkmcnt(5)
	v_sub_f32 v97, v154, v86
	v_sub_f32 v99, v151, v87
	v_sub_f32 v115, v149, v86
	v_sub_f32 v117, v150, v87
	v_sub_f32 v70, v70, v86
	v_sub_f32 v71, v71, v87
	v_sub_f32 v68, v68, v86
	v_sub_f32 v69, v69, v87
	v_sub_f32 v84, v84, v86
	v_fma_f32 v183, v188, v97, v86
	v_fma_f32 v182, v188, v99, v87
	v_fma_f32 v180, v189, v115, v86
	v_fma_f32 v181, v189, v117, v87
	v_fma_f32 v115, v194, v70, v86
	v_fma_f32 v117, v194, v71, v87
	v_fma_f32 v97, v195, v68, v86
	v_fma_f32 v99, v195, v69, v87
	v_fma_f32 v68, v76, v183, v140
	v_fma_f32 v69, v76, v182, v140
	v_fma_f32 v70, v77, v180, v140
	v_fma_f32 v71, v77, v181, v140
	v_sub_f32 v120, v120, v86
	v_sub_f32 v121, v121, v87
	v_sub_f32 v94, v94, v86
	v_sub_f32 v92, v92, v86
	v_sub_f32 v93, v93, v87
	v_sub_f32 v85, v85, v87
	v_fma_f32 v178, v190, v120, v86
	v_fma_f32 v179, v190, v121, v87
	v_fma_f32 v156, v191, v94, v86
	v_fma_f32 v154, v192, v92, v86
	v_fma_f32 v155, v192, v93, v87
	v_fma_f32 v150, v193, v84, v86
	v_fma_f32 v151, v193, v85, v87
	v_fma_f32 v76, v78, v178, v140
	v_fma_f32 v77, v78, v179, v140
	v_fma_f32 v78, v79, v156, v140
	v_fma_f32 v68, v184, v154, v68
	v_fma_f32 v84, v184, v155, v69
	v_fma_f32 v69, v185, v150, v70
	v_fma_f32 v70, v185, v151, v71
	v_fma_f32 v71, v186, v115, v76
	v_sub_f32 v95, v95, v87
	v_fma_f32 v76, v186, v117, v77
	v_fma_f32 v77, v187, v97, v78
	v_add_f32_e32 v68, v68, v69
	v_fma_f32 v157, v191, v95, v87
	v_add_f32_e32 v69, v71, v77
	v_fma_f32 v79, v79, v157, v140
	v_add_f32_e32 v70, v84, v70
	v_fma_f32 v78, v187, v99, v79
	v_add_f32_e32 v68, v68, v69
	v_add_f32_e32 v71, v76, v78
	v_add_f32_e32 v70, v70, v71
	v_mov_b32_e32 v69, 0
	v_add_f32_dpp v68, v68, v68 row_ror:8 row_mask:0xf bank_mask:0xf bound_ctrl:1
	v_add_f32_dpp v70, v70, v70 row_ror:8 row_mask:0xf bank_mask:0xf bound_ctrl:1
	v_mov_b32_e32 v71, 0
	v_add_f32_dpp v68, v68, v68 row_ror:4 row_mask:0xf bank_mask:0xf bound_ctrl:1
	v_add_f32_dpp v70, v70, v70 row_ror:4 row_mask:0xf bank_mask:0xf bound_ctrl:1
	v_add_u32_e32 v149, 0x9800, v103
	v_add_f32_dpp v68, v68, v68 row_ror:2 row_mask:0xf bank_mask:0xf bound_ctrl:1
	v_add_f32_dpp v70, v70, v70 row_ror:2 row_mask:0xf bank_mask:0xf bound_ctrl:1
	s_nop 0
	v_mov_b32_dpp v69, v68 row_ror:1 row_mask:0xf bank_mask:0xf
	v_mov_b32_dpp v71, v70 row_ror:1 row_mask:0xf bank_mask:0xf
	s_and_saveexec_b64 s[8:9], s[38:39]
	v_add_f32_e32 v70, v70, v71
	v_add_f32_e32 v68, v68, v69
	ds_write2_b32 v149, v68, v70 offset1:16
	s_or_b64 exec, exec, s[8:9]
	s_waitcnt lgkmcnt(0)
	v_sub_f32 v183, v183, v118
	v_sub_f32 v182, v182, v119
	v_sub_f32 v180, v180, v118
	v_sub_f32 v181, v181, v119
	v_sub_f32 v154, v154, v118
	v_sub_f32 v155, v155, v119
	v_sub_f32 v150, v150, v118
	v_sub_f32 v151, v151, v119
	v_sub_f32 v178, v178, v118
	v_sub_f32 v179, v179, v119
	v_sub_f32 v115, v115, v118
	v_sub_f32 v117, v117, v119
	v_fma_f32 v183, v88, v183, v118
	v_fma_f32 v182, v88, v182, v119
	v_fma_f32 v180, v89, v180, v118
	v_fma_f32 v181, v89, v181, v119
	v_fma_f32 v154, v80, v154, v118
	v_fma_f32 v155, v80, v155, v119
	v_fma_f32 v150, v81, v150, v118
	v_fma_f32 v151, v81, v151, v119
	v_fma_f32 v80, v72, v183, v140
	v_fma_f32 v72, v72, v182, v140
	v_fma_f32 v81, v73, v180, v140
	v_fma_f32 v73, v73, v181, v140
	ds_read_b128 v[76:79], v145 offset:19456
	ds_read_b128 v[68:71], v145 offset:19712
	ds_read_b128 v[92:95], v145 offset:27648
	ds_read_b128 v[84:87], v145 offset:27904
	ds_read2_b32 v[120:121], v153 offset0:64 offset1:80
	v_sub_f32 v156, v156, v118
	v_sub_f32 v157, v157, v119
	v_sub_f32 v97, v97, v118
	v_sub_f32 v99, v99, v119
	v_fma_f32 v178, v90, v178, v118
	v_fma_f32 v179, v90, v179, v119
	v_fma_f32 v115, v82, v115, v118
	v_fma_f32 v117, v82, v117, v119
	v_fma_f32 v80, v64, v154, v80
	v_fma_f32 v72, v64, v155, v72
	v_fma_f32 v82, v74, v178, v140
	v_fma_f32 v74, v74, v179, v140
	v_fma_f32 v64, v65, v150, v81
	v_fma_f32 v73, v65, v151, v73
	v_fma_f32 v156, v91, v156, v118
	v_fma_f32 v157, v91, v157, v119
	v_fma_f32 v65, v66, v115, v82
	v_fma_f32 v66, v66, v117, v74
	v_fma_f32 v97, v83, v97, v118
	v_fma_f32 v99, v83, v99, v119
	v_fma_f32 v83, v75, v156, v140
	v_fma_f32 v75, v75, v157, v140
	v_add_f32_e32 v64, v80, v64
	v_fma_f32 v74, v67, v97, v83
	v_fma_f32 v67, v67, v99, v75
	v_add_f32_e32 v72, v72, v73
	v_add_f32_e32 v65, v65, v74
	v_add_f32_e32 v66, v66, v67
	v_add_f32_e32 v64, v64, v65
	v_add_f32_e32 v66, v72, v66
	v_mov_b32_e32 v65, 0
	v_add_f32_dpp v64, v64, v64 row_ror:8 row_mask:0xf bank_mask:0xf bound_ctrl:1
	v_add_f32_dpp v66, v66, v66 row_ror:8 row_mask:0xf bank_mask:0xf bound_ctrl:1
	v_mov_b32_e32 v67, 0
	v_add_f32_dpp v64, v64, v64 row_ror:4 row_mask:0xf bank_mask:0xf bound_ctrl:1
	v_add_f32_dpp v66, v66, v66 row_ror:4 row_mask:0xf bank_mask:0xf bound_ctrl:1
	s_nop 0
	v_add_f32_dpp v64, v64, v64 row_ror:2 row_mask:0xf bank_mask:0xf bound_ctrl:1
	v_add_f32_dpp v66, v66, v66 row_ror:2 row_mask:0xf bank_mask:0xf bound_ctrl:1
	s_nop 0
	v_mov_b32_dpp v65, v64 row_ror:1 row_mask:0xf bank_mask:0xf
	v_mov_b32_dpp v67, v66 row_ror:1 row_mask:0xf bank_mask:0xf
	s_and_saveexec_b64 s[8:9], s[38:39]
	v_add_f32_e32 v66, v66, v67
	v_add_f32_e32 v64, v64, v65
	ds_write2_b32 v149, v64, v66 offset0:32 offset1:48
	s_or_b64 exec, exec, s[8:9]
	s_waitcnt lgkmcnt(0)
	v_sub_f32 v183, v183, v120
	v_sub_f32 v182, v182, v121
	v_sub_f32 v180, v180, v120
	v_sub_f32 v181, v181, v121
	v_sub_f32 v154, v154, v120
	v_sub_f32 v155, v155, v121
	v_sub_f32 v150, v150, v120
	v_sub_f32 v151, v151, v121
	v_sub_f32 v178, v178, v120
	v_sub_f32 v179, v179, v121
	v_sub_f32 v115, v115, v120
	v_sub_f32 v117, v117, v121
	v_fma_f32 v183, v92, v183, v120
	v_fma_f32 v182, v92, v182, v121
	v_fma_f32 v180, v93, v180, v120
	v_fma_f32 v181, v93, v181, v121
	v_fma_f32 v154, v84, v154, v120
	v_fma_f32 v155, v84, v155, v121
	v_fma_f32 v150, v85, v150, v120
	v_fma_f32 v151, v85, v151, v121
	v_fma_f32 v84, v76, v183, v140
	v_fma_f32 v76, v76, v182, v140
	v_fma_f32 v85, v77, v180, v140
	v_fma_f32 v77, v77, v181, v140
	ds_read_b128 v[72:75], v145 offset:19968
	ds_read_b128 v[64:67], v145 offset:20224
	ds_read_b128 v[88:91], v145 offset:28160
	ds_read_b128 v[80:83], v145 offset:28416
	ds_read2_b32 v[118:119], v153 offset0:96 offset1:112
	v_sub_f32 v156, v156, v120
	v_sub_f32 v157, v157, v121
	v_sub_f32 v97, v97, v120
	v_sub_f32 v99, v99, v121
	v_fma_f32 v178, v94, v178, v120
	v_fma_f32 v179, v94, v179, v121
	v_fma_f32 v115, v86, v115, v120
	v_fma_f32 v117, v86, v117, v121
	v_fma_f32 v84, v68, v154, v84
	v_fma_f32 v76, v68, v155, v76
	v_fma_f32 v86, v78, v178, v140
	v_fma_f32 v78, v78, v179, v140
	v_fma_f32 v68, v69, v150, v85
	v_fma_f32 v77, v69, v151, v77
	v_fma_f32 v156, v95, v156, v120
	v_fma_f32 v157, v95, v157, v121
	v_fma_f32 v69, v70, v115, v86
	v_fma_f32 v70, v70, v117, v78
	v_fma_f32 v97, v87, v97, v120
	v_fma_f32 v99, v87, v99, v121
	v_fma_f32 v87, v79, v156, v140
	v_fma_f32 v79, v79, v157, v140
	v_add_f32_e32 v68, v84, v68
	v_fma_f32 v78, v71, v97, v87
	v_fma_f32 v71, v71, v99, v79
	v_add_f32_e32 v76, v76, v77
	v_add_f32_e32 v69, v69, v78
	v_add_f32_e32 v70, v70, v71
	v_add_f32_e32 v68, v68, v69
	v_add_f32_e32 v70, v76, v70
	v_mov_b32_e32 v69, 0
	v_add_f32_dpp v68, v68, v68 row_ror:8 row_mask:0xf bank_mask:0xf bound_ctrl:1
	v_add_f32_dpp v70, v70, v70 row_ror:8 row_mask:0xf bank_mask:0xf bound_ctrl:1
	v_mov_b32_e32 v71, 0
	v_add_f32_dpp v68, v68, v68 row_ror:4 row_mask:0xf bank_mask:0xf bound_ctrl:1
	v_add_f32_dpp v70, v70, v70 row_ror:4 row_mask:0xf bank_mask:0xf bound_ctrl:1
	s_nop 0
	v_add_f32_dpp v68, v68, v68 row_ror:2 row_mask:0xf bank_mask:0xf bound_ctrl:1
	v_add_f32_dpp v70, v70, v70 row_ror:2 row_mask:0xf bank_mask:0xf bound_ctrl:1
	s_nop 0
	v_mov_b32_dpp v69, v68 row_ror:1 row_mask:0xf bank_mask:0xf
	v_mov_b32_dpp v71, v70 row_ror:1 row_mask:0xf bank_mask:0xf
	s_and_saveexec_b64 s[8:9], s[38:39]
	v_add_f32_e32 v70, v70, v71
	v_add_f32_e32 v68, v68, v69
	ds_write2_b32 v149, v68, v70 offset0:64 offset1:80
	s_or_b64 exec, exec, s[8:9]
	s_waitcnt lgkmcnt(0)
	v_sub_f32 v183, v183, v118
	v_sub_f32 v182, v182, v119
	v_sub_f32 v180, v180, v118
	v_sub_f32 v181, v181, v119
	v_sub_f32 v154, v154, v118
	v_sub_f32 v155, v155, v119
	v_sub_f32 v150, v150, v118
	v_sub_f32 v151, v151, v119
	v_sub_f32 v178, v178, v118
	v_sub_f32 v179, v179, v119
	v_sub_f32 v115, v115, v118
	v_sub_f32 v117, v117, v119
	v_fma_f32 v183, v88, v183, v118
	v_fma_f32 v182, v88, v182, v119
	v_fma_f32 v180, v89, v180, v118
	v_fma_f32 v181, v89, v181, v119
	v_fma_f32 v154, v80, v154, v118
	v_fma_f32 v155, v80, v155, v119
	v_fma_f32 v150, v81, v150, v118
	v_fma_f32 v151, v81, v151, v119
	v_fma_f32 v80, v72, v183, v140
	v_fma_f32 v72, v72, v182, v140
	v_fma_f32 v81, v73, v180, v140
	v_fma_f32 v73, v73, v181, v140
	ds_read_b128 v[76:79], v145 offset:20480
	ds_read_b128 v[68:71], v145 offset:20736
	ds_read_b128 v[92:95], v145 offset:28672
	ds_read_b128 v[84:87], v145 offset:28928
	ds_read2_b32 v[120:121], v153 offset0:128 offset1:144
	v_sub_f32 v156, v156, v118
	v_sub_f32 v157, v157, v119
	v_sub_f32 v97, v97, v118
	v_sub_f32 v99, v99, v119
	v_fma_f32 v178, v90, v178, v118
	v_fma_f32 v179, v90, v179, v119
	v_fma_f32 v115, v82, v115, v118
	v_fma_f32 v117, v82, v117, v119
	v_fma_f32 v80, v64, v154, v80
	v_fma_f32 v72, v64, v155, v72
	v_fma_f32 v82, v74, v178, v140
	v_fma_f32 v74, v74, v179, v140
	v_fma_f32 v64, v65, v150, v81
	v_fma_f32 v73, v65, v151, v73
	v_fma_f32 v156, v91, v156, v118
	v_fma_f32 v157, v91, v157, v119
	v_fma_f32 v65, v66, v115, v82
	v_fma_f32 v66, v66, v117, v74
	v_fma_f32 v97, v83, v97, v118
	v_fma_f32 v99, v83, v99, v119
	v_fma_f32 v83, v75, v156, v140
	v_fma_f32 v75, v75, v157, v140
	v_add_f32_e32 v64, v80, v64
	v_fma_f32 v74, v67, v97, v83
	v_fma_f32 v67, v67, v99, v75
	v_add_f32_e32 v72, v72, v73
	v_add_f32_e32 v65, v65, v74
	v_add_f32_e32 v66, v66, v67
	v_add_f32_e32 v64, v64, v65
	v_add_f32_e32 v66, v72, v66
	v_mov_b32_e32 v65, 0
	v_add_f32_dpp v64, v64, v64 row_ror:8 row_mask:0xf bank_mask:0xf bound_ctrl:1
	v_add_f32_dpp v66, v66, v66 row_ror:8 row_mask:0xf bank_mask:0xf bound_ctrl:1
	v_mov_b32_e32 v67, 0
	v_add_f32_dpp v64, v64, v64 row_ror:4 row_mask:0xf bank_mask:0xf bound_ctrl:1
	v_add_f32_dpp v66, v66, v66 row_ror:4 row_mask:0xf bank_mask:0xf bound_ctrl:1
	s_nop 0
	v_add_f32_dpp v64, v64, v64 row_ror:2 row_mask:0xf bank_mask:0xf bound_ctrl:1
	v_add_f32_dpp v66, v66, v66 row_ror:2 row_mask:0xf bank_mask:0xf bound_ctrl:1
	s_nop 0
	v_mov_b32_dpp v65, v64 row_ror:1 row_mask:0xf bank_mask:0xf
	v_mov_b32_dpp v67, v66 row_ror:1 row_mask:0xf bank_mask:0xf
	s_and_saveexec_b64 s[8:9], s[38:39]
	v_add_f32_e32 v66, v66, v67
	v_add_f32_e32 v64, v64, v65
	ds_write2_b32 v149, v64, v66 offset0:96 offset1:112
	s_or_b64 exec, exec, s[8:9]
	s_waitcnt lgkmcnt(0)
	v_sub_f32 v183, v183, v120
	v_sub_f32 v182, v182, v121
	v_sub_f32 v180, v180, v120
	v_sub_f32 v181, v181, v121
	v_sub_f32 v154, v154, v120
	v_sub_f32 v155, v155, v121
	v_sub_f32 v150, v150, v120
	v_sub_f32 v151, v151, v121
	v_sub_f32 v178, v178, v120
	v_sub_f32 v179, v179, v121
	v_sub_f32 v115, v115, v120
	v_sub_f32 v117, v117, v121
	v_fma_f32 v183, v92, v183, v120
	v_fma_f32 v182, v92, v182, v121
	v_fma_f32 v180, v93, v180, v120
	v_fma_f32 v181, v93, v181, v121
	v_fma_f32 v154, v84, v154, v120
	v_fma_f32 v155, v84, v155, v121
	v_fma_f32 v150, v85, v150, v120
	v_fma_f32 v151, v85, v151, v121
	v_fma_f32 v84, v76, v183, v140
	v_fma_f32 v76, v76, v182, v140
	v_fma_f32 v85, v77, v180, v140
	v_fma_f32 v77, v77, v181, v140
	ds_read_b128 v[72:75], v145 offset:20992
	ds_read_b128 v[64:67], v145 offset:21248
	ds_read_b128 v[88:91], v145 offset:29184
	ds_read_b128 v[80:83], v145 offset:29440
	ds_read2_b32 v[118:119], v153 offset0:160 offset1:176
	v_sub_f32 v156, v156, v120
	v_sub_f32 v157, v157, v121
	v_sub_f32 v97, v97, v120
	v_sub_f32 v99, v99, v121
	v_fma_f32 v178, v94, v178, v120
	v_fma_f32 v179, v94, v179, v121
	v_fma_f32 v115, v86, v115, v120
	v_fma_f32 v117, v86, v117, v121
	v_fma_f32 v84, v68, v154, v84
	v_fma_f32 v76, v68, v155, v76
	v_fma_f32 v86, v78, v178, v140
	v_fma_f32 v78, v78, v179, v140
	v_fma_f32 v68, v69, v150, v85
	v_fma_f32 v77, v69, v151, v77
	v_fma_f32 v156, v95, v156, v120
	v_fma_f32 v157, v95, v157, v121
	v_fma_f32 v69, v70, v115, v86
	v_fma_f32 v70, v70, v117, v78
	v_fma_f32 v97, v87, v97, v120
	v_fma_f32 v99, v87, v99, v121
	v_fma_f32 v87, v79, v156, v140
	v_fma_f32 v79, v79, v157, v140
	v_add_f32_e32 v68, v84, v68
	v_fma_f32 v78, v71, v97, v87
	v_fma_f32 v71, v71, v99, v79
	v_add_f32_e32 v76, v76, v77
	v_add_f32_e32 v69, v69, v78
	v_add_f32_e32 v70, v70, v71
	v_add_f32_e32 v68, v68, v69
	v_add_f32_e32 v70, v76, v70
	v_mov_b32_e32 v69, 0
	v_add_f32_dpp v68, v68, v68 row_ror:8 row_mask:0xf bank_mask:0xf bound_ctrl:1
	v_add_f32_dpp v70, v70, v70 row_ror:8 row_mask:0xf bank_mask:0xf bound_ctrl:1
	v_mov_b32_e32 v71, 0
	v_add_f32_dpp v68, v68, v68 row_ror:4 row_mask:0xf bank_mask:0xf bound_ctrl:1
	v_add_f32_dpp v70, v70, v70 row_ror:4 row_mask:0xf bank_mask:0xf bound_ctrl:1
	s_nop 0
	v_add_f32_dpp v68, v68, v68 row_ror:2 row_mask:0xf bank_mask:0xf bound_ctrl:1
	v_add_f32_dpp v70, v70, v70 row_ror:2 row_mask:0xf bank_mask:0xf bound_ctrl:1
	s_nop 0
	v_mov_b32_dpp v69, v68 row_ror:1 row_mask:0xf bank_mask:0xf
	v_mov_b32_dpp v71, v70 row_ror:1 row_mask:0xf bank_mask:0xf
	s_and_saveexec_b64 s[8:9], s[38:39]
	v_add_f32_e32 v70, v70, v71
	v_add_f32_e32 v68, v68, v69
	ds_write2_b32 v149, v68, v70 offset0:128 offset1:144
	s_or_b64 exec, exec, s[8:9]
	s_waitcnt lgkmcnt(0)
	v_sub_f32 v183, v183, v118
	v_sub_f32 v182, v182, v119
	v_sub_f32 v180, v180, v118
	v_sub_f32 v181, v181, v119
	v_sub_f32 v154, v154, v118
	v_sub_f32 v155, v155, v119
	v_sub_f32 v150, v150, v118
	v_sub_f32 v151, v151, v119
	v_sub_f32 v178, v178, v118
	v_sub_f32 v179, v179, v119
	v_sub_f32 v115, v115, v118
	v_sub_f32 v117, v117, v119
	v_fma_f32 v183, v88, v183, v118
	v_fma_f32 v182, v88, v182, v119
	v_fma_f32 v180, v89, v180, v118
	v_fma_f32 v181, v89, v181, v119
	v_fma_f32 v154, v80, v154, v118
	v_fma_f32 v155, v80, v155, v119
	v_fma_f32 v150, v81, v150, v118
	v_fma_f32 v151, v81, v151, v119
	v_fma_f32 v80, v72, v183, v140
	v_fma_f32 v72, v72, v182, v140
	v_fma_f32 v81, v73, v180, v140
	v_fma_f32 v73, v73, v181, v140
	ds_read_b128 v[76:79], v145 offset:21504
	ds_read_b128 v[68:71], v145 offset:21760
	ds_read_b128 v[92:95], v145 offset:29696
	ds_read_b128 v[84:87], v145 offset:29952
	ds_read2_b32 v[120:121], v153 offset0:192 offset1:208
	v_sub_f32 v156, v156, v118
	v_sub_f32 v157, v157, v119
	v_sub_f32 v97, v97, v118
	v_sub_f32 v99, v99, v119
	v_fma_f32 v178, v90, v178, v118
	v_fma_f32 v179, v90, v179, v119
	v_fma_f32 v115, v82, v115, v118
	v_fma_f32 v117, v82, v117, v119
	v_fma_f32 v80, v64, v154, v80
	v_fma_f32 v72, v64, v155, v72
	v_fma_f32 v82, v74, v178, v140
	v_fma_f32 v74, v74, v179, v140
	v_fma_f32 v64, v65, v150, v81
	v_fma_f32 v73, v65, v151, v73
	v_fma_f32 v156, v91, v156, v118
	v_fma_f32 v157, v91, v157, v119
	v_fma_f32 v65, v66, v115, v82
	v_fma_f32 v66, v66, v117, v74
	v_fma_f32 v97, v83, v97, v118
	v_fma_f32 v99, v83, v99, v119
	v_fma_f32 v83, v75, v156, v140
	v_fma_f32 v75, v75, v157, v140
	v_add_f32_e32 v64, v80, v64
	v_fma_f32 v74, v67, v97, v83
	v_fma_f32 v67, v67, v99, v75
	v_add_f32_e32 v72, v72, v73
	v_add_f32_e32 v65, v65, v74
	v_add_f32_e32 v66, v66, v67
	v_add_f32_e32 v64, v64, v65
	v_add_f32_e32 v66, v72, v66
	v_mov_b32_e32 v65, 0
	v_add_f32_dpp v64, v64, v64 row_ror:8 row_mask:0xf bank_mask:0xf bound_ctrl:1
	v_add_f32_dpp v66, v66, v66 row_ror:8 row_mask:0xf bank_mask:0xf bound_ctrl:1
	v_mov_b32_e32 v67, 0
	v_add_f32_dpp v64, v64, v64 row_ror:4 row_mask:0xf bank_mask:0xf bound_ctrl:1
	v_add_f32_dpp v66, v66, v66 row_ror:4 row_mask:0xf bank_mask:0xf bound_ctrl:1
	s_nop 0
	v_add_f32_dpp v64, v64, v64 row_ror:2 row_mask:0xf bank_mask:0xf bound_ctrl:1
	v_add_f32_dpp v66, v66, v66 row_ror:2 row_mask:0xf bank_mask:0xf bound_ctrl:1
	s_nop 0
	v_mov_b32_dpp v65, v64 row_ror:1 row_mask:0xf bank_mask:0xf
	v_mov_b32_dpp v67, v66 row_ror:1 row_mask:0xf bank_mask:0xf
	s_and_saveexec_b64 s[8:9], s[38:39]
	v_add_f32_e32 v66, v66, v67
	v_add_f32_e32 v64, v64, v65
	ds_write2_b32 v149, v64, v66 offset0:160 offset1:176
	s_or_b64 exec, exec, s[8:9]
	s_waitcnt lgkmcnt(0)
	v_sub_f32 v183, v183, v120
	v_sub_f32 v182, v182, v121
	v_sub_f32 v156, v156, v120
	v_sub_f32 v154, v154, v120
	v_sub_f32 v150, v150, v120
	v_sub_f32 v180, v180, v120
	v_sub_f32 v185, v181, v121
	v_sub_f32 v187, v157, v121
	v_sub_f32 v188, v155, v121
	v_sub_f32 v151, v151, v121
	v_sub_f32 v115, v115, v120
	v_sub_f32 v117, v117, v121
	v_fma_f32 v184, v92, v183, v120
	v_fma_f32 v183, v92, v182, v121
	v_fma_f32 v181, v93, v180, v120
	v_fma_f32 v182, v93, v185, v121
	v_fma_f32 v157, v95, v156, v120
	v_fma_f32 v155, v84, v154, v120
	v_fma_f32 v156, v84, v188, v121
	v_fma_f32 v150, v85, v150, v120
	v_fma_f32 v154, v85, v151, v121
	v_fma_f32 v84, v76, v184, v140
	v_fma_f32 v76, v76, v183, v140
	v_fma_f32 v85, v77, v181, v140
	v_fma_f32 v77, v77, v182, v140
	ds_read_b128 v[72:75], v145 offset:22016
	ds_read_b128 v[64:67], v145 offset:22272
	ds_read_b128 v[88:91], v145 offset:30208
	ds_read_b128 v[80:83], v145 offset:30464
	ds_read2_b32 v[118:119], v153 offset0:224 offset1:240
	v_sub_f32 v178, v178, v120
	v_sub_f32 v186, v179, v121
	v_sub_f32 v97, v97, v120
	v_sub_f32 v99, v99, v121
	v_fma_f32 v115, v86, v115, v120
	v_fma_f32 v117, v86, v117, v121
	v_fma_f32 v179, v94, v178, v120
	v_fma_f32 v180, v94, v186, v121
	v_fma_f32 v84, v68, v155, v84
	v_fma_f32 v76, v68, v156, v76
	v_fma_f32 v68, v69, v150, v85
	v_fma_f32 v77, v69, v154, v77
	v_fma_f32 v86, v78, v179, v140
	v_fma_f32 v78, v78, v180, v140
	v_fma_f32 v178, v95, v187, v121
	v_fma_f32 v97, v87, v97, v120
	v_fma_f32 v99, v87, v99, v121
	v_fma_f32 v87, v79, v157, v140
	v_fma_f32 v69, v70, v115, v86
	v_fma_f32 v70, v70, v117, v78
	v_fma_f32 v79, v79, v178, v140
	v_add_f32_e32 v68, v84, v68
	v_fma_f32 v78, v71, v97, v87
	v_fma_f32 v71, v71, v99, v79
	v_add_f32_e32 v76, v76, v77
	v_add_f32_e32 v69, v69, v78
	v_add_f32_e32 v70, v70, v71
	v_add_f32_e32 v68, v68, v69
	v_add_f32_e32 v70, v76, v70
	v_mov_b32_e32 v69, 0
	v_add_f32_dpp v68, v68, v68 row_ror:8 row_mask:0xf bank_mask:0xf bound_ctrl:1
	v_add_f32_dpp v70, v70, v70 row_ror:8 row_mask:0xf bank_mask:0xf bound_ctrl:1
	v_mov_b32_e32 v71, 0
	v_add_f32_dpp v68, v68, v68 row_ror:4 row_mask:0xf bank_mask:0xf bound_ctrl:1
	v_add_f32_dpp v70, v70, v70 row_ror:4 row_mask:0xf bank_mask:0xf bound_ctrl:1
	s_nop 0
	v_add_f32_dpp v68, v68, v68 row_ror:2 row_mask:0xf bank_mask:0xf bound_ctrl:1
	v_add_f32_dpp v70, v70, v70 row_ror:2 row_mask:0xf bank_mask:0xf bound_ctrl:1
	s_nop 0
	v_mov_b32_dpp v69, v68 row_ror:1 row_mask:0xf bank_mask:0xf
	v_mov_b32_dpp v71, v70 row_ror:1 row_mask:0xf bank_mask:0xf
	s_and_saveexec_b64 s[8:9], s[38:39]
	v_add_f32_e32 v70, v70, v71
	v_add_f32_e32 v68, v68, v69
	ds_write2_b32 v149, v68, v70 offset0:192 offset1:208
	s_or_b64 exec, exec, s[8:9]
	s_waitcnt lgkmcnt(0)
	v_sub_f32 v184, v184, v118
	v_sub_f32 v183, v183, v119
	v_sub_f32 v181, v181, v118
	v_sub_f32 v182, v182, v119
	v_sub_f32 v155, v155, v118
	v_sub_f32 v156, v156, v119
	v_sub_f32 v150, v150, v118
	v_sub_f32 v154, v154, v119
	v_sub_f32 v179, v179, v118
	v_sub_f32 v180, v180, v119
	v_sub_f32 v115, v115, v118
	v_sub_f32 v117, v117, v119
	v_fma_f32 v184, v88, v184, v118
	v_fma_f32 v183, v88, v183, v119
	v_fma_f32 v181, v89, v181, v118
	v_fma_f32 v182, v89, v182, v119
	v_fma_f32 v155, v80, v155, v118
	v_fma_f32 v156, v80, v156, v119
	v_fma_f32 v150, v81, v150, v118
	v_fma_f32 v154, v81, v154, v119
	v_fma_f32 v80, v72, v184, v140
	v_fma_f32 v72, v72, v183, v140
	v_fma_f32 v81, v73, v181, v140
	v_fma_f32 v73, v73, v182, v140
	v_sub_f32 v157, v157, v118
	v_sub_f32 v178, v178, v119
	v_sub_f32 v97, v97, v118
	v_sub_f32 v99, v99, v119
	v_fma_f32 v179, v90, v179, v118
	v_fma_f32 v180, v90, v180, v119
	v_fma_f32 v115, v82, v115, v118
	v_fma_f32 v117, v82, v117, v119
	v_fma_f32 v80, v64, v155, v80
	v_fma_f32 v72, v64, v156, v72
	v_fma_f32 v82, v74, v179, v140
	v_fma_f32 v74, v74, v180, v140
	v_fma_f32 v64, v65, v150, v81
	v_fma_f32 v73, v65, v154, v73
	ds_read_b128 v[76:79], v145 offset:22528
	ds_read_b128 v[68:71], v145 offset:22784
	ds_read_b128 v[92:95], v145 offset:30720
	ds_read_b128 v[84:87], v145 offset:30976
	v_fma_f32 v65, v66, v115, v82
	v_fma_f32 v66, v66, v117, v74
	v_fma_f32 v157, v91, v157, v118
	v_fma_f32 v178, v91, v178, v119
	v_fma_f32 v97, v83, v97, v118
	v_fma_f32 v99, v83, v99, v119
	v_add_f32_e32 v64, v80, v64
	v_fma_f32 v83, v75, v157, v140
	v_fma_f32 v75, v75, v178, v140
	v_add_f32_e32 v72, v72, v73
	v_fma_f32 v74, v67, v97, v83
	v_fma_f32 v67, v67, v99, v75
	v_add_u32_e32 v151, 0x8c00, v103
	v_add_f32_e32 v65, v65, v74
	v_add_f32_e32 v66, v66, v67
	v_add_f32_e32 v64, v64, v65
	v_add_f32_e32 v66, v72, v66
	ds_read2_b32 v[120:121], v151 offset1:16
	v_mov_b32_e32 v65, 0
	v_add_f32_dpp v64, v64, v64 row_ror:8 row_mask:0xf bank_mask:0xf bound_ctrl:1
	v_add_f32_dpp v66, v66, v66 row_ror:8 row_mask:0xf bank_mask:0xf bound_ctrl:1
	v_mov_b32_e32 v67, 0
	v_add_f32_dpp v64, v64, v64 row_ror:4 row_mask:0xf bank_mask:0xf bound_ctrl:1
	v_add_f32_dpp v66, v66, v66 row_ror:4 row_mask:0xf bank_mask:0xf bound_ctrl:1
	s_nop 0
	v_add_f32_dpp v64, v64, v64 row_ror:2 row_mask:0xf bank_mask:0xf bound_ctrl:1
	v_add_f32_dpp v66, v66, v66 row_ror:2 row_mask:0xf bank_mask:0xf bound_ctrl:1
	s_nop 0
	v_mov_b32_dpp v65, v64 row_ror:1 row_mask:0xf bank_mask:0xf
	v_mov_b32_dpp v67, v66 row_ror:1 row_mask:0xf bank_mask:0xf
	s_and_saveexec_b64 s[8:9], s[38:39]
	v_add_f32_e32 v66, v66, v67
	v_add_f32_e32 v64, v64, v65
	ds_write2_b32 v149, v64, v66 offset0:224 offset1:240
	s_or_b64 exec, exec, s[8:9]
	s_waitcnt lgkmcnt(0)
	v_sub_f32 v184, v184, v120
	v_sub_f32 v183, v183, v121
	v_sub_f32 v157, v157, v120
	v_sub_f32 v155, v155, v120
	v_sub_f32 v181, v181, v120
	v_sub_f32 v186, v182, v121
	v_sub_f32 v188, v178, v121
	v_sub_f32 v189, v156, v121
	v_sub_f32 v150, v150, v120
	v_sub_f32 v190, v154, v121
	v_sub_f32 v115, v115, v120
	v_sub_f32 v117, v117, v121
	v_fma_f32 v185, v92, v184, v120
	v_fma_f32 v184, v92, v183, v121
	v_fma_f32 v182, v93, v181, v120
	v_fma_f32 v183, v93, v186, v121
	v_fma_f32 v178, v95, v157, v120
	v_fma_f32 v156, v84, v155, v120
	v_fma_f32 v157, v84, v189, v121
	v_fma_f32 v154, v85, v150, v120
	v_fma_f32 v155, v85, v190, v121
	v_fma_f32 v84, v76, v185, v140
	v_fma_f32 v76, v76, v184, v140
	v_fma_f32 v85, v77, v182, v140
	v_fma_f32 v77, v77, v183, v140
	ds_read_b128 v[72:75], v145 offset:23040
	ds_read_b128 v[64:67], v145 offset:23296
	ds_read_b128 v[88:91], v145 offset:31232
	ds_read_b128 v[80:83], v145 offset:31488
	ds_read2_b32 v[118:119], v151 offset0:32 offset1:48
	v_sub_f32 v179, v179, v120
	v_sub_f32 v187, v180, v121
	v_sub_f32 v97, v97, v120
	v_sub_f32 v99, v99, v121
	v_fma_f32 v115, v86, v115, v120
	v_fma_f32 v117, v86, v117, v121
	v_fma_f32 v180, v94, v179, v120
	v_fma_f32 v181, v94, v187, v121
	v_fma_f32 v84, v68, v156, v84
	v_fma_f32 v76, v68, v157, v76
	v_fma_f32 v68, v69, v154, v85
	v_fma_f32 v77, v69, v155, v77
	v_fma_f32 v86, v78, v180, v140
	v_fma_f32 v78, v78, v181, v140
	v_fma_f32 v179, v95, v188, v121
	v_fma_f32 v97, v87, v97, v120
	v_fma_f32 v99, v87, v99, v121
	v_fma_f32 v87, v79, v178, v140
	v_fma_f32 v69, v70, v115, v86
	v_fma_f32 v70, v70, v117, v78
	v_fma_f32 v79, v79, v179, v140
	v_add_f32_e32 v68, v84, v68
	v_fma_f32 v78, v71, v97, v87
	v_fma_f32 v71, v71, v99, v79
	v_add_f32_e32 v76, v76, v77
	v_add_f32_e32 v69, v69, v78
	v_add_f32_e32 v70, v70, v71
	v_add_f32_e32 v68, v68, v69
	v_add_f32_e32 v70, v76, v70
	v_mov_b32_e32 v69, 0
	v_add_f32_dpp v68, v68, v68 row_ror:8 row_mask:0xf bank_mask:0xf bound_ctrl:1
	v_add_f32_dpp v70, v70, v70 row_ror:8 row_mask:0xf bank_mask:0xf bound_ctrl:1
	v_mov_b32_e32 v71, 0
	v_add_f32_dpp v68, v68, v68 row_ror:4 row_mask:0xf bank_mask:0xf bound_ctrl:1
	v_add_f32_dpp v70, v70, v70 row_ror:4 row_mask:0xf bank_mask:0xf bound_ctrl:1
	v_add_u32_e32 v150, 0x9c00, v103
	v_add_f32_dpp v68, v68, v68 row_ror:2 row_mask:0xf bank_mask:0xf bound_ctrl:1
	v_add_f32_dpp v70, v70, v70 row_ror:2 row_mask:0xf bank_mask:0xf bound_ctrl:1
	s_nop 0
	v_mov_b32_dpp v69, v68 row_ror:1 row_mask:0xf bank_mask:0xf
	v_mov_b32_dpp v71, v70 row_ror:1 row_mask:0xf bank_mask:0xf
	s_and_saveexec_b64 s[8:9], s[38:39]
	v_add_f32_e32 v70, v70, v71
	v_add_f32_e32 v68, v68, v69
	ds_write2_b32 v150, v68, v70 offset1:16
	s_or_b64 exec, exec, s[8:9]
	s_waitcnt lgkmcnt(0)
	v_sub_f32 v185, v185, v118
	v_sub_f32 v184, v184, v119
	v_sub_f32 v182, v182, v118
	v_sub_f32 v183, v183, v119
	v_sub_f32 v156, v156, v118
	v_sub_f32 v157, v157, v119
	v_sub_f32 v154, v154, v118
	v_sub_f32 v155, v155, v119
	v_sub_f32 v180, v180, v118
	v_sub_f32 v181, v181, v119
	v_sub_f32 v115, v115, v118
	v_sub_f32 v117, v117, v119
	v_fma_f32 v185, v88, v185, v118
	v_fma_f32 v184, v88, v184, v119
	v_fma_f32 v182, v89, v182, v118
	v_fma_f32 v183, v89, v183, v119
	v_fma_f32 v156, v80, v156, v118
	v_fma_f32 v157, v80, v157, v119
	v_fma_f32 v154, v81, v154, v118
	v_fma_f32 v155, v81, v155, v119
	v_fma_f32 v80, v72, v185, v140
	v_fma_f32 v72, v72, v184, v140
	v_fma_f32 v81, v73, v182, v140
	v_fma_f32 v73, v73, v183, v140
	ds_read_b128 v[76:79], v145 offset:23552
	ds_read_b128 v[68:71], v145 offset:23808
	ds_read_b128 v[92:95], v145 offset:31744
	ds_read_b128 v[84:87], v145 offset:32000
	ds_read2_b32 v[120:121], v151 offset0:64 offset1:80
	v_sub_f32 v178, v178, v118
	v_sub_f32 v179, v179, v119
	v_sub_f32 v97, v97, v118
	v_sub_f32 v99, v99, v119
	v_fma_f32 v180, v90, v180, v118
	v_fma_f32 v181, v90, v181, v119
	v_fma_f32 v115, v82, v115, v118
	v_fma_f32 v117, v82, v117, v119
	v_fma_f32 v80, v64, v156, v80
	v_fma_f32 v72, v64, v157, v72
	v_fma_f32 v82, v74, v180, v140
	v_fma_f32 v74, v74, v181, v140
	v_fma_f32 v64, v65, v154, v81
	v_fma_f32 v73, v65, v155, v73
	v_fma_f32 v178, v91, v178, v118
	v_fma_f32 v179, v91, v179, v119
	v_fma_f32 v65, v66, v115, v82
	v_fma_f32 v66, v66, v117, v74
	v_fma_f32 v97, v83, v97, v118
	v_fma_f32 v99, v83, v99, v119
	v_fma_f32 v83, v75, v178, v140
	v_fma_f32 v75, v75, v179, v140
	v_add_f32_e32 v64, v80, v64
	v_fma_f32 v74, v67, v97, v83
	v_fma_f32 v67, v67, v99, v75
	v_add_f32_e32 v72, v72, v73
	v_add_f32_e32 v65, v65, v74
	v_add_f32_e32 v66, v66, v67
	v_add_f32_e32 v64, v64, v65
	v_add_f32_e32 v66, v72, v66
	v_mov_b32_e32 v65, 0
	v_add_f32_dpp v64, v64, v64 row_ror:8 row_mask:0xf bank_mask:0xf bound_ctrl:1
	v_add_f32_dpp v66, v66, v66 row_ror:8 row_mask:0xf bank_mask:0xf bound_ctrl:1
	v_mov_b32_e32 v67, 0
	v_add_f32_dpp v64, v64, v64 row_ror:4 row_mask:0xf bank_mask:0xf bound_ctrl:1
	v_add_f32_dpp v66, v66, v66 row_ror:4 row_mask:0xf bank_mask:0xf bound_ctrl:1
	s_nop 0
	v_add_f32_dpp v64, v64, v64 row_ror:2 row_mask:0xf bank_mask:0xf bound_ctrl:1
	v_add_f32_dpp v66, v66, v66 row_ror:2 row_mask:0xf bank_mask:0xf bound_ctrl:1
	s_nop 0
	v_mov_b32_dpp v65, v64 row_ror:1 row_mask:0xf bank_mask:0xf
	v_mov_b32_dpp v67, v66 row_ror:1 row_mask:0xf bank_mask:0xf
	s_and_saveexec_b64 s[8:9], s[38:39]
	v_add_f32_e32 v66, v66, v67
	v_add_f32_e32 v64, v64, v65
	ds_write2_b32 v150, v64, v66 offset0:32 offset1:48
	s_or_b64 exec, exec, s[8:9]
	s_waitcnt lgkmcnt(0)
	v_sub_f32 v185, v185, v120
	v_sub_f32 v184, v184, v121
	v_sub_f32 v182, v182, v120
	v_sub_f32 v183, v183, v121
	v_sub_f32 v156, v156, v120
	v_sub_f32 v157, v157, v121
	v_sub_f32 v154, v154, v120
	v_sub_f32 v155, v155, v121
	v_sub_f32 v180, v180, v120
	v_sub_f32 v181, v181, v121
	v_sub_f32 v115, v115, v120
	v_sub_f32 v117, v117, v121
	v_fma_f32 v185, v92, v185, v120
	v_fma_f32 v184, v92, v184, v121
	v_fma_f32 v182, v93, v182, v120
	v_fma_f32 v183, v93, v183, v121
	v_fma_f32 v156, v84, v156, v120
	v_fma_f32 v157, v84, v157, v121
	v_fma_f32 v154, v85, v154, v120
	v_fma_f32 v155, v85, v155, v121
	v_fma_f32 v84, v76, v185, v140
	v_fma_f32 v76, v76, v184, v140
	v_fma_f32 v85, v77, v182, v140
	v_fma_f32 v77, v77, v183, v140
	ds_read_b128 v[72:75], v145 offset:24064
	ds_read_b128 v[64:67], v145 offset:24320
	ds_read_b128 v[88:91], v145 offset:32256
	ds_read_b128 v[80:83], v145 offset:32512
	ds_read2_b32 v[118:119], v151 offset0:96 offset1:112
	v_sub_f32 v178, v178, v120
	v_sub_f32 v179, v179, v121
	v_sub_f32 v97, v97, v120
	v_sub_f32 v99, v99, v121
	v_fma_f32 v180, v94, v180, v120
	v_fma_f32 v181, v94, v181, v121
	v_fma_f32 v115, v86, v115, v120
	v_fma_f32 v117, v86, v117, v121
	v_fma_f32 v84, v68, v156, v84
	v_fma_f32 v76, v68, v157, v76
	v_fma_f32 v86, v78, v180, v140
	v_fma_f32 v78, v78, v181, v140
	v_fma_f32 v68, v69, v154, v85
	v_fma_f32 v77, v69, v155, v77
	v_fma_f32 v178, v95, v178, v120
	v_fma_f32 v179, v95, v179, v121
	v_fma_f32 v69, v70, v115, v86
	v_fma_f32 v70, v70, v117, v78
	v_fma_f32 v97, v87, v97, v120
	v_fma_f32 v99, v87, v99, v121
	v_fma_f32 v87, v79, v178, v140
	v_fma_f32 v79, v79, v179, v140
	v_add_f32_e32 v68, v84, v68
	v_fma_f32 v78, v71, v97, v87
	v_fma_f32 v71, v71, v99, v79
	v_add_f32_e32 v76, v76, v77
	v_add_f32_e32 v69, v69, v78
	v_add_f32_e32 v70, v70, v71
	v_add_f32_e32 v68, v68, v69
	v_add_f32_e32 v70, v76, v70
	v_mov_b32_e32 v69, 0
	v_add_f32_dpp v68, v68, v68 row_ror:8 row_mask:0xf bank_mask:0xf bound_ctrl:1
	v_add_f32_dpp v70, v70, v70 row_ror:8 row_mask:0xf bank_mask:0xf bound_ctrl:1
	v_mov_b32_e32 v71, 0
	v_add_f32_dpp v68, v68, v68 row_ror:4 row_mask:0xf bank_mask:0xf bound_ctrl:1
	v_add_f32_dpp v70, v70, v70 row_ror:4 row_mask:0xf bank_mask:0xf bound_ctrl:1
	s_nop 0
	v_add_f32_dpp v68, v68, v68 row_ror:2 row_mask:0xf bank_mask:0xf bound_ctrl:1
	v_add_f32_dpp v70, v70, v70 row_ror:2 row_mask:0xf bank_mask:0xf bound_ctrl:1
	s_nop 0
	v_mov_b32_dpp v69, v68 row_ror:1 row_mask:0xf bank_mask:0xf
	v_mov_b32_dpp v71, v70 row_ror:1 row_mask:0xf bank_mask:0xf
	s_and_saveexec_b64 s[8:9], s[38:39]
	v_add_f32_e32 v70, v70, v71
	v_add_f32_e32 v68, v68, v69
	ds_write2_b32 v150, v68, v70 offset0:64 offset1:80
	s_or_b64 exec, exec, s[8:9]
	s_waitcnt lgkmcnt(0)
	v_sub_f32 v185, v185, v118
	v_sub_f32 v184, v184, v119
	v_sub_f32 v182, v182, v118
	v_sub_f32 v183, v183, v119
	v_sub_f32 v156, v156, v118
	v_sub_f32 v157, v157, v119
	v_sub_f32 v154, v154, v118
	v_sub_f32 v155, v155, v119
	v_sub_f32 v180, v180, v118
	v_sub_f32 v181, v181, v119
	v_sub_f32 v115, v115, v118
	v_sub_f32 v117, v117, v119
	v_fma_f32 v185, v88, v185, v118
	v_fma_f32 v184, v88, v184, v119
	v_fma_f32 v182, v89, v182, v118
	v_fma_f32 v183, v89, v183, v119
	v_fma_f32 v156, v80, v156, v118
	v_fma_f32 v157, v80, v157, v119
	v_fma_f32 v154, v81, v154, v118
	v_fma_f32 v155, v81, v155, v119
	v_fma_f32 v80, v72, v185, v140
	v_fma_f32 v72, v72, v184, v140
	v_fma_f32 v81, v73, v182, v140
	v_fma_f32 v73, v73, v183, v140
	ds_read_b128 v[76:79], v145 offset:24576
	ds_read_b128 v[68:71], v145 offset:24832
	ds_read_b128 v[92:95], v145 offset:32768
	ds_read_b128 v[84:87], v145 offset:33024
	ds_read2_b32 v[120:121], v151 offset0:128 offset1:144
	v_sub_f32 v178, v178, v118
	v_sub_f32 v179, v179, v119
	v_sub_f32 v97, v97, v118
	v_sub_f32 v99, v99, v119
	v_fma_f32 v180, v90, v180, v118
	v_fma_f32 v181, v90, v181, v119
	v_fma_f32 v115, v82, v115, v118
	v_fma_f32 v117, v82, v117, v119
	v_fma_f32 v80, v64, v156, v80
	v_fma_f32 v72, v64, v157, v72
	v_fma_f32 v82, v74, v180, v140
	v_fma_f32 v74, v74, v181, v140
	v_fma_f32 v64, v65, v154, v81
	v_fma_f32 v73, v65, v155, v73
	v_fma_f32 v178, v91, v178, v118
	v_fma_f32 v179, v91, v179, v119
	v_fma_f32 v65, v66, v115, v82
	v_fma_f32 v66, v66, v117, v74
	v_fma_f32 v97, v83, v97, v118
	v_fma_f32 v99, v83, v99, v119
	v_fma_f32 v83, v75, v178, v140
	v_fma_f32 v75, v75, v179, v140
	v_add_f32_e32 v64, v80, v64
	v_fma_f32 v74, v67, v97, v83
	v_fma_f32 v67, v67, v99, v75
	v_add_f32_e32 v72, v72, v73
	v_add_f32_e32 v65, v65, v74
	v_add_f32_e32 v66, v66, v67
	v_add_f32_e32 v64, v64, v65
	v_add_f32_e32 v66, v72, v66
	v_mov_b32_e32 v65, 0
	v_add_f32_dpp v64, v64, v64 row_ror:8 row_mask:0xf bank_mask:0xf bound_ctrl:1
	v_add_f32_dpp v66, v66, v66 row_ror:8 row_mask:0xf bank_mask:0xf bound_ctrl:1
	v_mov_b32_e32 v67, 0
	v_add_f32_dpp v64, v64, v64 row_ror:4 row_mask:0xf bank_mask:0xf bound_ctrl:1
	v_add_f32_dpp v66, v66, v66 row_ror:4 row_mask:0xf bank_mask:0xf bound_ctrl:1
	s_nop 0
	v_add_f32_dpp v64, v64, v64 row_ror:2 row_mask:0xf bank_mask:0xf bound_ctrl:1
	v_add_f32_dpp v66, v66, v66 row_ror:2 row_mask:0xf bank_mask:0xf bound_ctrl:1
	s_nop 0
	v_mov_b32_dpp v65, v64 row_ror:1 row_mask:0xf bank_mask:0xf
	v_mov_b32_dpp v67, v66 row_ror:1 row_mask:0xf bank_mask:0xf
	s_and_saveexec_b64 s[8:9], s[38:39]
	v_add_f32_e32 v66, v66, v67
	v_add_f32_e32 v64, v64, v65
	ds_write2_b32 v150, v64, v66 offset0:96 offset1:112
	s_or_b64 exec, exec, s[8:9]
	s_waitcnt lgkmcnt(0)
	v_sub_f32 v185, v185, v120
	v_sub_f32 v184, v184, v121
	v_sub_f32 v182, v182, v120
	v_sub_f32 v183, v183, v121
	v_sub_f32 v156, v156, v120
	v_sub_f32 v157, v157, v121
	v_sub_f32 v154, v154, v120
	v_sub_f32 v155, v155, v121
	v_sub_f32 v180, v180, v120
	v_sub_f32 v181, v181, v121
	v_sub_f32 v115, v115, v120
	v_sub_f32 v117, v117, v121
	v_fma_f32 v185, v92, v185, v120
	v_fma_f32 v184, v92, v184, v121
	v_fma_f32 v182, v93, v182, v120
	v_fma_f32 v183, v93, v183, v121
	v_fma_f32 v156, v84, v156, v120
	v_fma_f32 v157, v84, v157, v121
	v_fma_f32 v154, v85, v154, v120
	v_fma_f32 v155, v85, v155, v121
	v_fma_f32 v84, v76, v185, v140
	v_fma_f32 v76, v76, v184, v140
	v_fma_f32 v85, v77, v182, v140
	v_fma_f32 v77, v77, v183, v140
	ds_read_b128 v[72:75], v145 offset:25088
	ds_read_b128 v[64:67], v145 offset:25344
	ds_read_b128 v[88:91], v145 offset:33280
	ds_read_b128 v[80:83], v145 offset:33536
	ds_read2_b32 v[118:119], v151 offset0:160 offset1:176
	v_sub_f32 v178, v178, v120
	v_sub_f32 v179, v179, v121
	v_sub_f32 v97, v97, v120
	v_sub_f32 v99, v99, v121
	v_fma_f32 v180, v94, v180, v120
	v_fma_f32 v181, v94, v181, v121
	v_fma_f32 v115, v86, v115, v120
	v_fma_f32 v117, v86, v117, v121
	v_fma_f32 v84, v68, v156, v84
	v_fma_f32 v76, v68, v157, v76
	v_fma_f32 v86, v78, v180, v140
	v_fma_f32 v78, v78, v181, v140
	v_fma_f32 v68, v69, v154, v85
	v_fma_f32 v77, v69, v155, v77
	v_fma_f32 v178, v95, v178, v120
	v_fma_f32 v179, v95, v179, v121
	v_fma_f32 v69, v70, v115, v86
	v_fma_f32 v70, v70, v117, v78
	v_fma_f32 v97, v87, v97, v120
	v_fma_f32 v99, v87, v99, v121
	v_fma_f32 v87, v79, v178, v140
	v_fma_f32 v79, v79, v179, v140
	v_add_f32_e32 v68, v84, v68
	v_fma_f32 v78, v71, v97, v87
	v_fma_f32 v71, v71, v99, v79
	v_add_f32_e32 v76, v76, v77
	v_add_f32_e32 v69, v69, v78
	v_add_f32_e32 v70, v70, v71
	v_add_f32_e32 v68, v68, v69
	v_add_f32_e32 v70, v76, v70
	v_mov_b32_e32 v69, 0
	v_add_f32_dpp v68, v68, v68 row_ror:8 row_mask:0xf bank_mask:0xf bound_ctrl:1
	v_add_f32_dpp v70, v70, v70 row_ror:8 row_mask:0xf bank_mask:0xf bound_ctrl:1
	v_mov_b32_e32 v71, 0
	v_add_f32_dpp v68, v68, v68 row_ror:4 row_mask:0xf bank_mask:0xf bound_ctrl:1
	v_add_f32_dpp v70, v70, v70 row_ror:4 row_mask:0xf bank_mask:0xf bound_ctrl:1
	s_nop 0
	v_add_f32_dpp v68, v68, v68 row_ror:2 row_mask:0xf bank_mask:0xf bound_ctrl:1
	v_add_f32_dpp v70, v70, v70 row_ror:2 row_mask:0xf bank_mask:0xf bound_ctrl:1
	s_nop 0
	v_mov_b32_dpp v69, v68 row_ror:1 row_mask:0xf bank_mask:0xf
	v_mov_b32_dpp v71, v70 row_ror:1 row_mask:0xf bank_mask:0xf
	s_and_saveexec_b64 s[8:9], s[38:39]
	v_add_f32_e32 v70, v70, v71
	v_add_f32_e32 v68, v68, v69
	ds_write2_b32 v150, v68, v70 offset0:128 offset1:144
	s_or_b64 exec, exec, s[8:9]
	s_waitcnt lgkmcnt(0)
	v_sub_f32 v185, v185, v118
	v_sub_f32 v184, v184, v119
	v_sub_f32 v182, v182, v118
	v_sub_f32 v183, v183, v119
	v_sub_f32 v156, v156, v118
	v_sub_f32 v157, v157, v119
	v_sub_f32 v154, v154, v118
	v_sub_f32 v155, v155, v119
	v_sub_f32 v180, v180, v118
	v_sub_f32 v181, v181, v119
	v_sub_f32 v115, v115, v118
	v_sub_f32 v117, v117, v119
	v_fma_f32 v185, v88, v185, v118
	v_fma_f32 v184, v88, v184, v119
	v_fma_f32 v182, v89, v182, v118
	v_fma_f32 v183, v89, v183, v119
	v_fma_f32 v156, v80, v156, v118
	v_fma_f32 v157, v80, v157, v119
	v_fma_f32 v154, v81, v154, v118
	v_fma_f32 v155, v81, v155, v119
	v_fma_f32 v80, v72, v185, v140
	v_fma_f32 v72, v72, v184, v140
	v_fma_f32 v81, v73, v182, v140
	v_fma_f32 v73, v73, v183, v140
	ds_read_b128 v[76:79], v145 offset:25600
	ds_read_b128 v[68:71], v145 offset:25856
	ds_read_b128 v[92:95], v145 offset:33792
	ds_read_b128 v[84:87], v145 offset:34048
	ds_read2_b32 v[120:121], v151 offset0:192 offset1:208
	v_sub_f32 v178, v178, v118
	v_sub_f32 v179, v179, v119
	v_sub_f32 v97, v97, v118
	v_sub_f32 v99, v99, v119
	v_fma_f32 v180, v90, v180, v118
	v_fma_f32 v181, v90, v181, v119
	v_fma_f32 v115, v82, v115, v118
	v_fma_f32 v117, v82, v117, v119
	v_fma_f32 v80, v64, v156, v80
	v_fma_f32 v72, v64, v157, v72
	v_fma_f32 v82, v74, v180, v140
	v_fma_f32 v74, v74, v181, v140
	v_fma_f32 v64, v65, v154, v81
	v_fma_f32 v73, v65, v155, v73
	v_fma_f32 v178, v91, v178, v118
	v_fma_f32 v179, v91, v179, v119
	v_fma_f32 v65, v66, v115, v82
	v_fma_f32 v66, v66, v117, v74
	v_fma_f32 v97, v83, v97, v118
	v_fma_f32 v99, v83, v99, v119
	v_fma_f32 v83, v75, v178, v140
	v_fma_f32 v75, v75, v179, v140
	v_add_f32_e32 v64, v80, v64
	v_fma_f32 v74, v67, v97, v83
	v_fma_f32 v67, v67, v99, v75
	v_add_f32_e32 v72, v72, v73
	v_add_f32_e32 v65, v65, v74
	v_add_f32_e32 v66, v66, v67
	v_add_f32_e32 v64, v64, v65
	v_add_f32_e32 v66, v72, v66
	v_mov_b32_e32 v65, 0
	v_add_f32_dpp v64, v64, v64 row_ror:8 row_mask:0xf bank_mask:0xf bound_ctrl:1
	v_add_f32_dpp v66, v66, v66 row_ror:8 row_mask:0xf bank_mask:0xf bound_ctrl:1
	v_mov_b32_e32 v67, 0
	v_add_f32_dpp v64, v64, v64 row_ror:4 row_mask:0xf bank_mask:0xf bound_ctrl:1
	v_add_f32_dpp v66, v66, v66 row_ror:4 row_mask:0xf bank_mask:0xf bound_ctrl:1
	s_nop 0
	v_add_f32_dpp v64, v64, v64 row_ror:2 row_mask:0xf bank_mask:0xf bound_ctrl:1
	v_add_f32_dpp v66, v66, v66 row_ror:2 row_mask:0xf bank_mask:0xf bound_ctrl:1
	s_nop 0
	v_mov_b32_dpp v65, v64 row_ror:1 row_mask:0xf bank_mask:0xf
	v_mov_b32_dpp v67, v66 row_ror:1 row_mask:0xf bank_mask:0xf
	s_and_saveexec_b64 s[8:9], s[38:39]
	v_add_f32_e32 v66, v66, v67
	v_add_f32_e32 v64, v64, v65
	ds_write2_b32 v150, v64, v66 offset0:160 offset1:176
	s_or_b64 exec, exec, s[8:9]
	s_waitcnt lgkmcnt(0)
	v_sub_f32 v185, v185, v120
	v_sub_f32 v184, v184, v121
	v_sub_f32 v182, v182, v120
	v_sub_f32 v183, v183, v121
	v_sub_f32 v180, v180, v120
	v_sub_f32 v181, v181, v121
	v_sub_f32 v186, v178, v120
	v_sub_f32 v179, v179, v121
	v_sub_f32 v187, v156, v120
	v_sub_f32 v188, v157, v121
	v_sub_f32 v189, v154, v120
	v_sub_f32 v190, v155, v121
	v_sub_f32 v191, v115, v120
	v_sub_f32 v192, v117, v121
	v_sub_f32 v193, v97, v120
	v_sub_f32 v194, v99, v121
	v_fma_f32 v178, v92, v185, v120
	v_fma_f32 v157, v92, v184, v121
	v_fma_f32 v155, v93, v182, v120
	v_fma_f32 v156, v93, v183, v121
	v_fma_f32 v117, v94, v180, v120
	v_fma_f32 v154, v94, v181, v121
	v_fma_f32 v99, v95, v186, v120
	v_fma_f32 v115, v95, v179, v121
	v_fma_f32 v95, v84, v187, v120
	v_fma_f32 v97, v84, v188, v121
	v_fma_f32 v93, v85, v189, v120
	v_fma_f32 v94, v85, v190, v121
	v_fma_f32 v92, v86, v191, v120
	v_fma_f32 v84, v87, v193, v120
	v_fma_f32 v85, v87, v194, v121
	v_fma_f32 v87, v76, v178, v140
	v_fma_f32 v76, v76, v157, v140
	v_fma_f32 v120, v77, v155, v140
	v_fma_f32 v77, v77, v156, v140
	ds_read_b128 v[72:75], v145 offset:26112
	ds_read_b128 v[64:67], v145 offset:26368
	ds_read_b128 v[88:91], v145 offset:34304
	ds_read_b128 v[80:83], v145 offset:34560
	ds_read2_b32 v[118:119], v151 offset0:224 offset1:240
	v_fma_f32 v86, v86, v192, v121
	v_fma_f32 v121, v78, v117, v140
	v_fma_f32 v78, v78, v154, v140
	v_fma_f32 v87, v68, v95, v87
	v_fma_f32 v76, v68, v97, v76
	v_fma_f32 v68, v69, v93, v120
	v_fma_f32 v77, v69, v94, v77
	v_fma_f32 v69, v70, v92, v121
	v_fma_f32 v70, v70, v86, v78
	v_fma_f32 v179, v79, v99, v140
	v_fma_f32 v79, v79, v115, v140
	v_add_f32_e32 v68, v87, v68
	v_fma_f32 v78, v71, v84, v179
	v_fma_f32 v71, v71, v85, v79
	v_add_f32_e32 v76, v76, v77
	v_add_f32_e32 v69, v69, v78
	v_add_f32_e32 v70, v70, v71
	v_add_f32_e32 v68, v68, v69
	v_add_f32_e32 v70, v76, v70
	v_mov_b32_e32 v69, 0
	v_add_f32_dpp v68, v68, v68 row_ror:8 row_mask:0xf bank_mask:0xf bound_ctrl:1
	v_add_f32_dpp v70, v70, v70 row_ror:8 row_mask:0xf bank_mask:0xf bound_ctrl:1
	v_mov_b32_e32 v71, 0
	v_add_f32_dpp v68, v68, v68 row_ror:4 row_mask:0xf bank_mask:0xf bound_ctrl:1
	v_add_f32_dpp v70, v70, v70 row_ror:4 row_mask:0xf bank_mask:0xf bound_ctrl:1
	s_nop 0
	v_add_f32_dpp v68, v68, v68 row_ror:2 row_mask:0xf bank_mask:0xf bound_ctrl:1
	v_add_f32_dpp v70, v70, v70 row_ror:2 row_mask:0xf bank_mask:0xf bound_ctrl:1
	s_nop 0
	v_mov_b32_dpp v69, v68 row_ror:1 row_mask:0xf bank_mask:0xf
	v_mov_b32_dpp v71, v70 row_ror:1 row_mask:0xf bank_mask:0xf
	s_and_saveexec_b64 s[8:9], s[38:39]
	v_add_f32_e32 v70, v70, v71
	v_add_f32_e32 v68, v68, v69
	ds_write2_b32 v150, v68, v70 offset0:192 offset1:208
	s_or_b64 exec, exec, s[8:9]
	s_waitcnt lgkmcnt(0)
	v_sub_f32 v76, v117, v118
	v_sub_f32 v77, v154, v119
	v_sub_f32 v78, v99, v118
	v_sub_f32 v79, v115, v119
	v_sub_f32 v68, v178, v118
	v_sub_f32 v69, v157, v119
	v_sub_f32 v70, v155, v118
	v_sub_f32 v71, v156, v119
	v_sub_f32 v99, v95, v118
	v_sub_f32 v97, v97, v119
	v_sub_f32 v115, v93, v118
	v_sub_f32 v117, v94, v119
	v_sub_f32 v120, v92, v118
	v_sub_f32 v121, v86, v119
	v_sub_f32 v154, v84, v118
	v_sub_f32 v155, v85, v119
	v_fma_f32 v95, v88, v68, v118
	v_fma_f32 v94, v88, v69, v119
	v_fma_f32 v92, v89, v70, v118
	v_fma_f32 v93, v89, v71, v119
	v_fma_f32 v86, v90, v76, v118
	v_fma_f32 v87, v90, v77, v119
	v_fma_f32 v84, v91, v78, v118
	v_fma_f32 v85, v91, v79, v119
	v_fma_f32 v78, v80, v99, v118
	v_fma_f32 v79, v80, v97, v119
	v_fma_f32 v76, v81, v115, v118
	v_fma_f32 v77, v81, v117, v119
	v_fma_f32 v80, v72, v95, v140
	v_fma_f32 v72, v72, v94, v140
	v_fma_f32 v81, v73, v92, v140
	v_fma_f32 v73, v73, v93, v140
	v_fma_f32 v70, v82, v120, v118
	v_fma_f32 v71, v82, v121, v119
	v_fma_f32 v82, v74, v86, v140
	v_fma_f32 v74, v74, v87, v140
	v_fma_f32 v80, v64, v78, v80
	v_fma_f32 v72, v64, v79, v72
	v_fma_f32 v64, v65, v76, v81
	v_fma_f32 v73, v65, v77, v73
	v_fma_f32 v65, v66, v70, v82
	v_fma_f32 v66, v66, v71, v74
	v_fma_f32 v68, v83, v154, v118
	v_fma_f32 v69, v83, v155, v119
	v_fma_f32 v83, v75, v84, v140
	v_fma_f32 v75, v75, v85, v140
	v_add_f32_e32 v64, v80, v64
	v_fma_f32 v74, v67, v68, v83
	v_fma_f32 v67, v67, v69, v75
	v_add_f32_e32 v72, v72, v73
	v_add_f32_e32 v65, v65, v74
	v_add_f32_e32 v66, v66, v67
	v_add_f32_e32 v64, v64, v65
	v_add_f32_e32 v66, v72, v66
	v_mov_b32_e32 v65, 0
	v_add_f32_dpp v64, v64, v64 row_ror:8 row_mask:0xf bank_mask:0xf bound_ctrl:1
	v_add_f32_dpp v66, v66, v66 row_ror:8 row_mask:0xf bank_mask:0xf bound_ctrl:1
	v_mov_b32_e32 v67, 0
	v_add_f32_dpp v64, v64, v64 row_ror:4 row_mask:0xf bank_mask:0xf bound_ctrl:1
	v_add_f32_dpp v66, v66, v66 row_ror:4 row_mask:0xf bank_mask:0xf bound_ctrl:1
	s_nop 0
	v_add_f32_dpp v64, v64, v64 row_ror:2 row_mask:0xf bank_mask:0xf bound_ctrl:1
	v_add_f32_dpp v66, v66, v66 row_ror:2 row_mask:0xf bank_mask:0xf bound_ctrl:1
	s_nop 0
	v_mov_b32_dpp v65, v64 row_ror:1 row_mask:0xf bank_mask:0xf
	v_mov_b32_dpp v67, v66 row_ror:1 row_mask:0xf bank_mask:0xf
	s_and_saveexec_b64 s[8:9], s[38:39]
	v_add_f32_e32 v66, v66, v67
	v_add_f32_e32 v64, v64, v65
	ds_write2_b32 v150, v64, v66 offset0:224 offset1:240
	s_or_b64 exec, exec, s[8:9]
	s_waitcnt vmcnt(9)
	v_mul_f32_e32 v64, 0xbfb8aa3b, v28
	v_mul_f32_e32 v65, 0xbfb8aa3b, v29
	v_exp_f32_e32 v64, v64
	v_exp_f32_e32 v65, v65
	v_mul_f32_e32 v66, 0xbfb8aa3b, v30
	v_mul_f32_e32 v67, 0xbfb8aa3b, v31
	v_exp_f32_e32 v66, v66
	v_pk_add_f32 v[64:65], v[64:65], 1.0 op_sel_hi:[1,0]
	v_exp_f32_e32 v67, v67
	v_div_scale_f32 v80, s[8:9], v65, v65, v29
	v_rcp_f32_e32 v81, v80
	v_pk_add_f32 v[66:67], v[66:67], 1.0 op_sel_hi:[1,0]
	s_waitcnt vmcnt(8)
	v_mul_f32_e32 v72, 0xbfb8aa3b, v32
	v_mul_f32_e32 v73, 0xbfb8aa3b, v33
	v_fma_f32 v82, -v80, v81, 1.0
	v_fmac_f32_e32 v81, v82, v81
	v_div_scale_f32 v82, vcc, v29, v65, v29
	v_mul_f32_e32 v83, v82, v81
	v_fma_f32 v88, -v80, v83, v82
	v_fmac_f32_e32 v83, v88, v81
	v_fma_f32 v80, -v80, v83, v82
	v_div_fmas_f32 v80, v80, v81, v83
	v_div_fixup_f32 v65, v80, v65, v29
	v_div_scale_f32 v80, s[8:9], v64, v64, v28
	v_rcp_f32_e32 v81, v80
	v_exp_f32_e32 v72, v72
	v_exp_f32_e32 v73, v73
	v_mul_f32_e32 v74, 0xbfb8aa3b, v34
	v_fma_f32 v82, -v80, v81, 1.0
	v_fmac_f32_e32 v81, v82, v81
	v_div_scale_f32 v82, vcc, v28, v64, v28
	v_mul_f32_e32 v83, v82, v81
	v_fma_f32 v88, -v80, v83, v82
	v_fmac_f32_e32 v83, v88, v81
	v_fma_f32 v80, -v80, v83, v82
	v_div_fmas_f32 v80, v80, v81, v83
	v_div_fixup_f32 v64, v80, v64, v28
	v_div_scale_f32 v80, s[8:9], v67, v67, v31
	v_rcp_f32_e32 v81, v80
	v_pk_mul_f32 v[64:65], v[64:65], s[18:19] op_sel_hi:[1,0]
	v_mul_f32_e32 v75, 0xbfb8aa3b, v35
	v_exp_f32_e32 v74, v74
	v_fma_f32 v82, -v80, v81, 1.0
	v_fmac_f32_e32 v81, v82, v81
	v_div_scale_f32 v82, vcc, v31, v67, v31
	v_mul_f32_e32 v83, v82, v81
	v_fma_f32 v88, -v80, v83, v82
	v_fmac_f32_e32 v83, v88, v81
	v_fma_f32 v80, -v80, v83, v82
	v_div_fmas_f32 v80, v80, v81, v83
	v_div_fixup_f32 v67, v80, v67, v31
	v_div_scale_f32 v80, s[8:9], v66, v66, v30
	v_rcp_f32_e32 v81, v80
	v_exp_f32_e32 v75, v75
	s_cmpk_gt_u32 s48, 0x79
	v_fma_f32 v82, -v80, v81, 1.0
	v_fmac_f32_e32 v81, v82, v81
	v_div_scale_f32 v82, vcc, v30, v66, v30
	v_mul_f32_e32 v83, v82, v81
	v_fma_f32 v88, -v80, v83, v82
	v_fmac_f32_e32 v83, v88, v81
	v_fma_f32 v80, -v80, v83, v82
	v_div_fmas_f32 v80, v80, v81, v83
	v_div_fixup_f32 v66, v80, v66, v30
	v_pk_mul_f32 v[66:67], v[66:67], s[18:19] op_sel_hi:[1,0]
	ds_write_b128 v141, v[64:67]
	v_pk_add_f32 v[64:65], v[72:73], 1.0 op_sel_hi:[1,0]
	v_div_scale_f32 v66, s[8:9], v65, v65, 1.0
	v_rcp_f32_e32 v67, v66
	s_nop 0
	v_fma_f32 v72, -v66, v67, 1.0
	v_fmac_f32_e32 v67, v72, v67
	v_div_scale_f32 v72, vcc, 1.0, v65, 1.0
	v_mul_f32_e32 v73, v72, v67
	v_fma_f32 v80, -v66, v73, v72
	v_fmac_f32_e32 v73, v80, v67
	v_fma_f32 v66, -v66, v73, v72
	v_div_fmas_f32 v66, v66, v67, v73
	v_div_fixup_f32 v65, v66, v65, 1.0
	v_div_scale_f32 v66, s[8:9], v64, v64, 1.0
	v_rcp_f32_e32 v67, v66
	s_nop 0
	v_fma_f32 v72, -v66, v67, 1.0
	v_fmac_f32_e32 v67, v72, v67
	v_div_scale_f32 v72, vcc, 1.0, v64, 1.0
	v_mul_f32_e32 v73, v72, v67
	v_fma_f32 v80, -v66, v73, v72
	v_fmac_f32_e32 v73, v80, v67
	v_fma_f32 v66, -v66, v73, v72
	v_div_fmas_f32 v66, v66, v67, v73
	v_div_fixup_f32 v64, v66, v64, 1.0
	v_pk_add_f32 v[66:67], v[74:75], 1.0 op_sel_hi:[1,0]
	v_pk_fma_f32 v[64:65], v[110:111], v[64:65], v[104:105]
	v_div_scale_f32 v72, s[8:9], v67, v67, 1.0
	v_rcp_f32_e32 v73, v72
	s_nop 0
	v_fma_f32 v74, -v72, v73, 1.0
	v_fmac_f32_e32 v73, v74, v73
	v_div_scale_f32 v74, vcc, 1.0, v67, 1.0
	v_mul_f32_e32 v75, v74, v73
	v_fma_f32 v80, -v72, v75, v74
	v_fmac_f32_e32 v75, v80, v73
	v_fma_f32 v72, -v72, v75, v74
	v_div_fmas_f32 v72, v72, v73, v75
	v_div_fixup_f32 v67, v72, v67, 1.0
	v_div_scale_f32 v72, s[8:9], v66, v66, 1.0
	v_rcp_f32_e32 v73, v72
	s_nop 0
	v_fma_f32 v74, -v72, v73, 1.0
	v_fmac_f32_e32 v73, v74, v73
	v_div_scale_f32 v74, vcc, 1.0, v66, 1.0
	v_mul_f32_e32 v75, v74, v73
	v_fma_f32 v80, -v72, v75, v74
	v_fmac_f32_e32 v75, v80, v73
	v_fma_f32 v72, -v72, v75, v74
	v_div_fmas_f32 v72, v72, v73, v75
	v_div_fixup_f32 v66, v72, v66, 1.0
	v_pk_fma_f32 v[66:67], v[112:113], v[66:67], v[106:107]
	ds_write_b128 v141, v[64:67] offset:8192
	ds_write_b32 v134, v131 offset:16384
	v_mul_f32_e32 v64, 0xbfb8aa3b, v40
	v_mul_f32_e32 v65, 0xbfb8aa3b, v41
	v_exp_f32_e32 v64, v64
	v_exp_f32_e32 v65, v65
	v_mul_f32_e32 v66, 0xbfb8aa3b, v42
	v_mul_f32_e32 v67, 0xbfb8aa3b, v43
	v_exp_f32_e32 v66, v66
	v_pk_add_f32 v[64:65], v[64:65], 1.0 op_sel_hi:[1,0]
	v_exp_f32_e32 v67, v67
	v_div_scale_f32 v80, s[8:9], v65, v65, v41
	v_rcp_f32_e32 v81, v80
	v_pk_add_f32 v[66:67], v[66:67], 1.0 op_sel_hi:[1,0]
	s_waitcnt vmcnt(7)
	v_mul_f32_e32 v72, 0xbfb8aa3b, v52
	v_mul_f32_e32 v73, 0xbfb8aa3b, v53
	v_fma_f32 v82, -v80, v81, 1.0
	v_fmac_f32_e32 v81, v82, v81
	v_div_scale_f32 v82, vcc, v41, v65, v41
	v_mul_f32_e32 v83, v82, v81
	v_fma_f32 v88, -v80, v83, v82
	v_fmac_f32_e32 v83, v88, v81
	v_fma_f32 v80, -v80, v83, v82
	v_div_fmas_f32 v80, v80, v81, v83
	v_div_fixup_f32 v65, v80, v65, v41
	v_div_scale_f32 v80, s[8:9], v64, v64, v40
	v_rcp_f32_e32 v81, v80
	v_exp_f32_e32 v72, v72
	v_exp_f32_e32 v73, v73
	v_mul_f32_e32 v74, 0xbfb8aa3b, v54
	v_fma_f32 v82, -v80, v81, 1.0
	v_fmac_f32_e32 v81, v82, v81
	v_div_scale_f32 v82, vcc, v40, v64, v40
	v_mul_f32_e32 v83, v82, v81
	v_fma_f32 v88, -v80, v83, v82
	v_fmac_f32_e32 v83, v88, v81
	v_fma_f32 v80, -v80, v83, v82
	v_div_fmas_f32 v80, v80, v81, v83
	v_div_fixup_f32 v64, v80, v64, v40
	v_div_scale_f32 v80, s[8:9], v67, v67, v43
	v_rcp_f32_e32 v81, v80
	v_pk_mul_f32 v[64:65], v[64:65], s[18:19] op_sel_hi:[1,0]
	v_mul_f32_e32 v75, 0xbfb8aa3b, v55
	v_exp_f32_e32 v74, v74
	v_fma_f32 v82, -v80, v81, 1.0
	v_fmac_f32_e32 v81, v82, v81
	v_div_scale_f32 v82, vcc, v43, v67, v43
	v_mul_f32_e32 v83, v82, v81
	v_fma_f32 v88, -v80, v83, v82
	v_fmac_f32_e32 v83, v88, v81
	v_fma_f32 v80, -v80, v83, v82
	v_div_fmas_f32 v80, v80, v81, v83
	v_div_fixup_f32 v67, v80, v67, v43
	v_div_scale_f32 v80, s[8:9], v66, v66, v42
	v_rcp_f32_e32 v81, v80
	v_exp_f32_e32 v75, v75
	v_fma_f32 v82, -v80, v81, 1.0
	v_fmac_f32_e32 v81, v82, v81
	v_div_scale_f32 v82, vcc, v42, v66, v42
	v_mul_f32_e32 v83, v82, v81
	v_fma_f32 v88, -v80, v83, v82
	v_fmac_f32_e32 v83, v88, v81
	v_fma_f32 v80, -v80, v83, v82
	v_div_fmas_f32 v80, v80, v81, v83
	v_div_fixup_f32 v66, v80, v66, v42
	v_pk_mul_f32 v[66:67], v[66:67], s[18:19] op_sel_hi:[1,0]
	ds_write_b128 v144, v[64:67]
	v_pk_add_f32 v[64:65], v[72:73], 1.0 op_sel_hi:[1,0]
	v_div_scale_f32 v66, s[8:9], v65, v65, 1.0
	v_rcp_f32_e32 v67, v66
	s_nop 0
	v_fma_f32 v72, -v66, v67, 1.0
	v_fmac_f32_e32 v67, v72, v67
	v_div_scale_f32 v72, vcc, 1.0, v65, 1.0
	v_mul_f32_e32 v73, v72, v67
	v_fma_f32 v80, -v66, v73, v72
	v_fmac_f32_e32 v73, v80, v67
	v_fma_f32 v66, -v66, v73, v72
	v_div_fmas_f32 v66, v66, v67, v73
	v_div_fixup_f32 v65, v66, v65, 1.0
	v_div_scale_f32 v66, s[8:9], v64, v64, 1.0
	v_rcp_f32_e32 v67, v66
	s_nop 0
	v_fma_f32 v72, -v66, v67, 1.0
	v_fmac_f32_e32 v67, v72, v67
	v_div_scale_f32 v72, vcc, 1.0, v64, 1.0
	v_mul_f32_e32 v73, v72, v67
	v_fma_f32 v80, -v66, v73, v72
	v_fmac_f32_e32 v73, v80, v67
	v_fma_f32 v66, -v66, v73, v72
	v_div_fmas_f32 v66, v66, v67, v73
	v_div_fixup_f32 v64, v66, v64, 1.0
	v_pk_add_f32 v[66:67], v[74:75], 1.0 op_sel_hi:[1,0]
	v_pk_fma_f32 v[64:65], v[110:111], v[64:65], v[104:105]
	v_div_scale_f32 v72, s[8:9], v67, v67, 1.0
	v_rcp_f32_e32 v73, v72
	s_nop 0
	v_fma_f32 v74, -v72, v73, 1.0
	v_fmac_f32_e32 v73, v74, v73
	v_div_scale_f32 v74, vcc, 1.0, v67, 1.0
	v_mul_f32_e32 v75, v74, v73
	v_fma_f32 v80, -v72, v75, v74
	v_fmac_f32_e32 v75, v80, v73
	v_fma_f32 v72, -v72, v75, v74
	v_div_fmas_f32 v72, v72, v73, v75
	v_div_fixup_f32 v67, v72, v67, 1.0
	v_div_scale_f32 v72, s[8:9], v66, v66, 1.0
	v_rcp_f32_e32 v73, v72
	s_nop 0
	v_fma_f32 v74, -v72, v73, 1.0
	v_fmac_f32_e32 v73, v74, v73
	v_div_scale_f32 v74, vcc, 1.0, v66, 1.0
	v_mul_f32_e32 v75, v74, v73
	v_fma_f32 v80, -v72, v75, v74
	v_fmac_f32_e32 v75, v80, v73
	v_fma_f32 v72, -v72, v75, v74
	v_div_fmas_f32 v72, v72, v73, v75
	v_div_fixup_f32 v66, v72, v66, 1.0
	v_pk_fma_f32 v[66:67], v[112:113], v[66:67], v[106:107]
	ds_write_b128 v144, v[64:67] offset:8192
	s_waitcnt vmcnt(6)
	ds_write_b32 v134, v132 offset:17408
	s_waitcnt lgkmcnt(0)
	s_barrier
	s_cbranch_scc1 .LBB0_1359
	v_add_u32_e32 v28, 0x60, v98
	v_mov_b64_e32 v[40:41], s[30:31]
	v_mad_i64_i32 v[28:29], s[8:9], v28, s25, v[40:41]
	s_lshl_b32 s94, s46, 2
	v_lshl_add_u64 v[42:43], v[28:29], 0, s[94:95]
	v_mov_b32_e32 v117, v140
	v_lshl_add_u64 v[28:29], v[42:43], 0, v[116:117]
	v_add_co_u32_e32 v30, vcc, 0x4000, v28
	s_lshl_b32 s8, s42, 2
	s_nop 0
	v_addc_co_u32_e32 v31, vcc, 0, v29, vcc
	s_mov_b32 s9, s95
	v_add_co_u32_e32 v32, vcc, 0x5000, v28
	v_lshl_add_u64 v[42:43], v[42:43], 0, s[8:9]
	v_mov_b32_e32 v115, v140
	v_add_u32_e32 v52, 0x60, v96
	v_addc_co_u32_e32 v33, vcc, 0, v29, vcc
	v_lshl_add_u64 v[42:43], v[42:43], 0, v[114:115]
	v_mad_i64_i32 v[40:41], s[22:23], v52, s25, v[40:41]
	v_add_co_u32_e32 v42, vcc, s81, v42
	v_lshl_add_u64 v[52:53], v[40:41], 0, s[94:95]
	s_nop 0
	v_addc_co_u32_e32 v43, vcc, 0, v43, vcc
	v_lshl_add_u64 v[54:55], v[52:53], 0, v[116:117]
	v_add_co_u32_e32 v40, vcc, s80, v54
	v_lshl_add_u64 v[52:53], v[52:53], 0, s[8:9]
	s_nop 0
	v_addc_co_u32_e32 v41, vcc, 0, v55, vcc
	v_add_co_u32_e32 v54, vcc, 0x5000, v54
	v_lshl_add_u64 v[52:53], v[52:53], 0, v[114:115]
	s_nop 0
	v_addc_co_u32_e32 v55, vcc, 0, v55, vcc
	v_add_co_u32_e32 v64, vcc, 0x6000, v52
	global_load_dwordx4 v[28:31], v[30:31], off offset:32
	s_nop 0
	global_load_dwordx4 v[32:35], v[32:33], off offset:32
	s_nop 0
	global_load_dword v131, v[42:43], off offset:32
	s_nop 0
	global_load_dwordx4 v[40:43], v[40:41], off offset:32
	v_addc_co_u32_e32 v65, vcc, 0, v53, vcc
	global_load_dwordx4 v[52:55], v[54:55], off offset:32
	s_nop 0
	global_load_dword v132, v[64:65], off offset:32
.LBB0_1359:
	ds_read2st64_b32 v[64:65], v134 offset0:152 offset1:156
	v_add_u32_e32 v66, 16, v98
	v_ashrrev_i32_e32 v67, 31, v66
	v_lshlrev_b64 v[66:67], 12, v[66:67]
	v_lshl_add_u64 v[66:67], v[108:109], 0, v[66:67]
	s_waitcnt lgkmcnt(0)
	global_store_dword v[66:67], v64, off
	v_add_u32_e32 v66, 16, v96
	v_ashrrev_i32_e32 v67, 31, v66
	v_lshlrev_b64 v[66:67], 12, v[66:67]
	v_lshl_add_u64 v[66:67], v[108:109], 0, v[66:67]
	global_store_dword v[66:67], v65, off
	ds_read_b128 v[186:189], v145
	ds_read_b128 v[190:193], v145 offset:256
	ds_read_b128 v[154:157], v145 offset:8192
	ds_read_b128 v[194:197], v145 offset:8448
	ds_read2_b32 v[120:121], v152 offset1:16
	ds_read_b128 v[72:75], v145 offset:512
	ds_read_b128 v[64:67], v145 offset:768
	ds_read_b128 v[88:91], v145 offset:8704
	ds_read_b128 v[80:83], v145 offset:8960
	ds_read2_b32 v[118:119], v152 offset0:32 offset1:48
	s_waitcnt lgkmcnt(5)
	v_sub_f32 v70, v70, v120
	v_sub_f32 v71, v71, v121
	v_sub_f32 v68, v68, v120
	v_sub_f32 v69, v69, v121
	v_sub_f32 v95, v95, v120
	v_sub_f32 v94, v94, v121
	v_sub_f32 v92, v92, v120
	v_sub_f32 v93, v93, v121
	v_sub_f32 v84, v84, v120
	v_sub_f32 v78, v78, v120
	v_sub_f32 v76, v76, v120
	v_sub_f32 v77, v77, v121
	v_fma_f32 v185, v154, v95, v120
	v_fma_f32 v184, v154, v94, v121
	v_fma_f32 v182, v155, v92, v120
	v_fma_f32 v183, v155, v93, v121
	v_fma_f32 v115, v196, v70, v120
	v_fma_f32 v117, v196, v71, v121
	v_fma_f32 v97, v197, v68, v120
	v_fma_f32 v99, v197, v69, v121
	v_fma_f32 v68, v186, v185, v140
	v_fma_f32 v69, v186, v184, v140
	v_fma_f32 v70, v187, v182, v140
	v_fma_f32 v71, v187, v183, v140
	v_sub_f32 v86, v86, v120
	v_sub_f32 v87, v87, v121
	v_sub_f32 v85, v85, v121
	v_sub_f32 v79, v79, v121
	v_fma_f32 v178, v157, v84, v120
	v_fma_f32 v154, v195, v76, v120
	v_fma_f32 v180, v156, v86, v120
	v_fma_f32 v181, v156, v87, v121
	v_fma_f32 v179, v157, v85, v121
	v_fma_f32 v156, v194, v78, v120
	v_fma_f32 v157, v194, v79, v121
	v_fma_f32 v155, v195, v77, v121
	v_fma_f32 v76, v188, v180, v140
	v_fma_f32 v77, v188, v181, v140
	v_fma_f32 v78, v189, v178, v140
	v_fma_f32 v68, v190, v156, v68
	v_fma_f32 v84, v190, v157, v69
	v_fma_f32 v69, v191, v154, v70
	v_fma_f32 v70, v191, v155, v71
	v_fma_f32 v71, v192, v115, v76
	v_fma_f32 v79, v189, v179, v140
	v_fma_f32 v76, v192, v117, v77
	v_fma_f32 v77, v193, v97, v78
	v_add_f32_e32 v68, v68, v69
	v_fma_f32 v78, v193, v99, v79
	v_add_f32_e32 v69, v71, v77
	v_add_f32_e32 v70, v84, v70
	v_add_f32_e32 v71, v76, v78
	v_add_f32_e32 v68, v68, v69
	v_add_f32_e32 v70, v70, v71
	v_mov_b32_e32 v69, 0
	v_add_f32_dpp v68, v68, v68 row_ror:8 row_mask:0xf bank_mask:0xf bound_ctrl:1
	v_add_f32_dpp v70, v70, v70 row_ror:8 row_mask:0xf bank_mask:0xf bound_ctrl:1
	v_mov_b32_e32 v71, 0
	v_add_f32_dpp v68, v68, v68 row_ror:4 row_mask:0xf bank_mask:0xf bound_ctrl:1
	v_add_f32_dpp v70, v70, v70 row_ror:4 row_mask:0xf bank_mask:0xf bound_ctrl:1
	s_nop 0
	v_add_f32_dpp v68, v68, v68 row_ror:2 row_mask:0xf bank_mask:0xf bound_ctrl:1
	v_add_f32_dpp v70, v70, v70 row_ror:2 row_mask:0xf bank_mask:0xf bound_ctrl:1
	s_nop 0
	v_mov_b32_dpp v69, v68 row_ror:1 row_mask:0xf bank_mask:0xf
	v_mov_b32_dpp v71, v70 row_ror:1 row_mask:0xf bank_mask:0xf
	s_and_saveexec_b64 s[8:9], s[38:39]
	v_add_f32_e32 v70, v70, v71
	v_add_f32_e32 v68, v68, v69
	ds_write2_b32 v146, v68, v70 offset1:16
	s_or_b64 exec, exec, s[8:9]
	s_waitcnt lgkmcnt(0)
	v_sub_f32 v185, v185, v118
	v_sub_f32 v184, v184, v119
	v_sub_f32 v182, v182, v118
	v_sub_f32 v183, v183, v119
	v_sub_f32 v156, v156, v118
	v_sub_f32 v157, v157, v119
	v_sub_f32 v154, v154, v118
	v_sub_f32 v155, v155, v119
	v_sub_f32 v180, v180, v118
	v_sub_f32 v181, v181, v119
	v_sub_f32 v115, v115, v118
	v_sub_f32 v117, v117, v119
	v_fma_f32 v185, v88, v185, v118
	v_fma_f32 v184, v88, v184, v119
	v_fma_f32 v182, v89, v182, v118
	v_fma_f32 v183, v89, v183, v119
	v_fma_f32 v156, v80, v156, v118
	v_fma_f32 v157, v80, v157, v119
	v_fma_f32 v154, v81, v154, v118
	v_fma_f32 v155, v81, v155, v119
	v_fma_f32 v80, v72, v185, v140
	v_fma_f32 v72, v72, v184, v140
	v_fma_f32 v81, v73, v182, v140
	v_fma_f32 v73, v73, v183, v140
	ds_read_b128 v[76:79], v145 offset:1024
	ds_read_b128 v[68:71], v145 offset:1280
	ds_read_b128 v[92:95], v145 offset:9216
	ds_read_b128 v[84:87], v145 offset:9472
	ds_read2_b32 v[120:121], v152 offset0:64 offset1:80
	v_sub_f32 v178, v178, v118
	v_sub_f32 v179, v179, v119
	v_sub_f32 v97, v97, v118
	v_sub_f32 v99, v99, v119
	v_fma_f32 v180, v90, v180, v118
	v_fma_f32 v181, v90, v181, v119
	v_fma_f32 v115, v82, v115, v118
	v_fma_f32 v117, v82, v117, v119
	v_fma_f32 v80, v64, v156, v80
	v_fma_f32 v72, v64, v157, v72
	v_fma_f32 v82, v74, v180, v140
	v_fma_f32 v74, v74, v181, v140
	v_fma_f32 v64, v65, v154, v81
	v_fma_f32 v73, v65, v155, v73
	v_fma_f32 v178, v91, v178, v118
	v_fma_f32 v179, v91, v179, v119
	v_fma_f32 v65, v66, v115, v82
	v_fma_f32 v66, v66, v117, v74
	v_fma_f32 v97, v83, v97, v118
	v_fma_f32 v99, v83, v99, v119
	v_fma_f32 v83, v75, v178, v140
	v_fma_f32 v75, v75, v179, v140
	v_add_f32_e32 v64, v80, v64
	v_fma_f32 v74, v67, v97, v83
	v_fma_f32 v67, v67, v99, v75
	v_add_f32_e32 v72, v72, v73
	v_add_f32_e32 v65, v65, v74
	v_add_f32_e32 v66, v66, v67
	v_add_f32_e32 v64, v64, v65
	v_add_f32_e32 v66, v72, v66
	v_mov_b32_e32 v65, 0
	v_add_f32_dpp v64, v64, v64 row_ror:8 row_mask:0xf bank_mask:0xf bound_ctrl:1
	v_add_f32_dpp v66, v66, v66 row_ror:8 row_mask:0xf bank_mask:0xf bound_ctrl:1
	v_mov_b32_e32 v67, 0
	v_add_f32_dpp v64, v64, v64 row_ror:4 row_mask:0xf bank_mask:0xf bound_ctrl:1
	v_add_f32_dpp v66, v66, v66 row_ror:4 row_mask:0xf bank_mask:0xf bound_ctrl:1
	s_nop 0
	v_add_f32_dpp v64, v64, v64 row_ror:2 row_mask:0xf bank_mask:0xf bound_ctrl:1
	v_add_f32_dpp v66, v66, v66 row_ror:2 row_mask:0xf bank_mask:0xf bound_ctrl:1
	s_nop 0
	v_mov_b32_dpp v65, v64 row_ror:1 row_mask:0xf bank_mask:0xf
	v_mov_b32_dpp v67, v66 row_ror:1 row_mask:0xf bank_mask:0xf
	s_and_saveexec_b64 s[8:9], s[38:39]
	v_add_f32_e32 v66, v66, v67
	v_add_f32_e32 v64, v64, v65
	ds_write2_b32 v146, v64, v66 offset0:32 offset1:48
	s_or_b64 exec, exec, s[8:9]
	s_waitcnt lgkmcnt(0)
	v_sub_f32 v185, v185, v120
	v_sub_f32 v184, v184, v121
	v_sub_f32 v182, v182, v120
	v_sub_f32 v183, v183, v121
	v_sub_f32 v156, v156, v120
	v_sub_f32 v157, v157, v121
	v_sub_f32 v154, v154, v120
	v_sub_f32 v155, v155, v121
	v_sub_f32 v180, v180, v120
	v_sub_f32 v181, v181, v121
	v_sub_f32 v115, v115, v120
	v_sub_f32 v117, v117, v121
	v_fma_f32 v185, v92, v185, v120
	v_fma_f32 v184, v92, v184, v121
	v_fma_f32 v182, v93, v182, v120
	v_fma_f32 v183, v93, v183, v121
	v_fma_f32 v156, v84, v156, v120
	v_fma_f32 v157, v84, v157, v121
	v_fma_f32 v154, v85, v154, v120
	v_fma_f32 v155, v85, v155, v121
	v_fma_f32 v84, v76, v185, v140
	v_fma_f32 v76, v76, v184, v140
	v_fma_f32 v85, v77, v182, v140
	v_fma_f32 v77, v77, v183, v140
	ds_read_b128 v[72:75], v145 offset:1536
	ds_read_b128 v[64:67], v145 offset:1792
	ds_read_b128 v[88:91], v145 offset:9728
	ds_read_b128 v[80:83], v145 offset:9984
	ds_read2_b32 v[118:119], v152 offset0:96 offset1:112
	v_sub_f32 v178, v178, v120
	v_sub_f32 v179, v179, v121
	v_sub_f32 v97, v97, v120
	v_sub_f32 v99, v99, v121
	v_fma_f32 v180, v94, v180, v120
	v_fma_f32 v181, v94, v181, v121
	v_fma_f32 v115, v86, v115, v120
	v_fma_f32 v117, v86, v117, v121
	v_fma_f32 v84, v68, v156, v84
	v_fma_f32 v76, v68, v157, v76
	v_fma_f32 v86, v78, v180, v140
	v_fma_f32 v78, v78, v181, v140
	v_fma_f32 v68, v69, v154, v85
	v_fma_f32 v77, v69, v155, v77
	v_fma_f32 v178, v95, v178, v120
	v_fma_f32 v179, v95, v179, v121
	v_fma_f32 v69, v70, v115, v86
	v_fma_f32 v70, v70, v117, v78
	v_fma_f32 v97, v87, v97, v120
	v_fma_f32 v99, v87, v99, v121
	v_fma_f32 v87, v79, v178, v140
	v_fma_f32 v79, v79, v179, v140
	v_add_f32_e32 v68, v84, v68
	v_fma_f32 v78, v71, v97, v87
	v_fma_f32 v71, v71, v99, v79
	v_add_f32_e32 v76, v76, v77
	v_add_f32_e32 v69, v69, v78
	v_add_f32_e32 v70, v70, v71
	v_add_f32_e32 v68, v68, v69
	v_add_f32_e32 v70, v76, v70
	v_mov_b32_e32 v69, 0
	v_add_f32_dpp v68, v68, v68 row_ror:8 row_mask:0xf bank_mask:0xf bound_ctrl:1
	v_add_f32_dpp v70, v70, v70 row_ror:8 row_mask:0xf bank_mask:0xf bound_ctrl:1
	v_mov_b32_e32 v71, 0
	v_add_f32_dpp v68, v68, v68 row_ror:4 row_mask:0xf bank_mask:0xf bound_ctrl:1
	v_add_f32_dpp v70, v70, v70 row_ror:4 row_mask:0xf bank_mask:0xf bound_ctrl:1
	s_nop 0
	v_add_f32_dpp v68, v68, v68 row_ror:2 row_mask:0xf bank_mask:0xf bound_ctrl:1
	v_add_f32_dpp v70, v70, v70 row_ror:2 row_mask:0xf bank_mask:0xf bound_ctrl:1
	s_nop 0
	v_mov_b32_dpp v69, v68 row_ror:1 row_mask:0xf bank_mask:0xf
	v_mov_b32_dpp v71, v70 row_ror:1 row_mask:0xf bank_mask:0xf
	s_and_saveexec_b64 s[8:9], s[38:39]
	v_add_f32_e32 v70, v70, v71
	v_add_f32_e32 v68, v68, v69
	ds_write2_b32 v146, v68, v70 offset0:64 offset1:80
	s_or_b64 exec, exec, s[8:9]
	s_waitcnt lgkmcnt(0)
	v_sub_f32 v185, v185, v118
	v_sub_f32 v184, v184, v119
	v_sub_f32 v182, v182, v118
	v_sub_f32 v183, v183, v119
	v_sub_f32 v156, v156, v118
	v_sub_f32 v157, v157, v119
	v_sub_f32 v154, v154, v118
	v_sub_f32 v155, v155, v119
	v_sub_f32 v180, v180, v118
	v_sub_f32 v181, v181, v119
	v_sub_f32 v115, v115, v118
	v_sub_f32 v117, v117, v119
	v_fma_f32 v185, v88, v185, v118
	v_fma_f32 v184, v88, v184, v119
	v_fma_f32 v182, v89, v182, v118
	v_fma_f32 v183, v89, v183, v119
	v_fma_f32 v156, v80, v156, v118
	v_fma_f32 v157, v80, v157, v119
	v_fma_f32 v154, v81, v154, v118
	v_fma_f32 v155, v81, v155, v119
	v_fma_f32 v80, v72, v185, v140
	v_fma_f32 v72, v72, v184, v140
	v_fma_f32 v81, v73, v182, v140
	v_fma_f32 v73, v73, v183, v140
	ds_read_b128 v[76:79], v145 offset:2048
	ds_read_b128 v[68:71], v145 offset:2304
	ds_read_b128 v[92:95], v145 offset:10240
	ds_read_b128 v[84:87], v145 offset:10496
	ds_read2_b32 v[120:121], v152 offset0:128 offset1:144
	v_sub_f32 v178, v178, v118
	v_sub_f32 v179, v179, v119
	v_sub_f32 v97, v97, v118
	v_sub_f32 v99, v99, v119
	v_fma_f32 v180, v90, v180, v118
	v_fma_f32 v181, v90, v181, v119
	v_fma_f32 v115, v82, v115, v118
	v_fma_f32 v117, v82, v117, v119
	v_fma_f32 v80, v64, v156, v80
	v_fma_f32 v72, v64, v157, v72
	v_fma_f32 v82, v74, v180, v140
	v_fma_f32 v74, v74, v181, v140
	v_fma_f32 v64, v65, v154, v81
	v_fma_f32 v73, v65, v155, v73
	v_fma_f32 v178, v91, v178, v118
	v_fma_f32 v179, v91, v179, v119
	v_fma_f32 v65, v66, v115, v82
	v_fma_f32 v66, v66, v117, v74
	v_fma_f32 v97, v83, v97, v118
	v_fma_f32 v99, v83, v99, v119
	v_fma_f32 v83, v75, v178, v140
	v_fma_f32 v75, v75, v179, v140
	v_add_f32_e32 v64, v80, v64
	v_fma_f32 v74, v67, v97, v83
	v_fma_f32 v67, v67, v99, v75
	v_add_f32_e32 v72, v72, v73
	v_add_f32_e32 v65, v65, v74
	v_add_f32_e32 v66, v66, v67
	v_add_f32_e32 v64, v64, v65
	v_add_f32_e32 v66, v72, v66
	v_mov_b32_e32 v65, 0
	v_add_f32_dpp v64, v64, v64 row_ror:8 row_mask:0xf bank_mask:0xf bound_ctrl:1
	v_add_f32_dpp v66, v66, v66 row_ror:8 row_mask:0xf bank_mask:0xf bound_ctrl:1
	v_mov_b32_e32 v67, 0
	v_add_f32_dpp v64, v64, v64 row_ror:4 row_mask:0xf bank_mask:0xf bound_ctrl:1
	v_add_f32_dpp v66, v66, v66 row_ror:4 row_mask:0xf bank_mask:0xf bound_ctrl:1
	s_nop 0
	v_add_f32_dpp v64, v64, v64 row_ror:2 row_mask:0xf bank_mask:0xf bound_ctrl:1
	v_add_f32_dpp v66, v66, v66 row_ror:2 row_mask:0xf bank_mask:0xf bound_ctrl:1
	s_nop 0
	v_mov_b32_dpp v65, v64 row_ror:1 row_mask:0xf bank_mask:0xf
	v_mov_b32_dpp v67, v66 row_ror:1 row_mask:0xf bank_mask:0xf
	s_and_saveexec_b64 s[8:9], s[38:39]
	v_add_f32_e32 v66, v66, v67
	v_add_f32_e32 v64, v64, v65
	ds_write2_b32 v146, v64, v66 offset0:96 offset1:112
	s_or_b64 exec, exec, s[8:9]
	s_waitcnt lgkmcnt(0)
	v_sub_f32 v185, v185, v120
	v_sub_f32 v184, v184, v121
	v_sub_f32 v182, v182, v120
	v_sub_f32 v183, v183, v121
	v_sub_f32 v156, v156, v120
	v_sub_f32 v157, v157, v121
	v_sub_f32 v154, v154, v120
	v_sub_f32 v155, v155, v121
	v_sub_f32 v180, v180, v120
	v_sub_f32 v181, v181, v121
	v_sub_f32 v115, v115, v120
	v_sub_f32 v117, v117, v121
	v_fma_f32 v185, v92, v185, v120
	v_fma_f32 v184, v92, v184, v121
	v_fma_f32 v182, v93, v182, v120
	v_fma_f32 v183, v93, v183, v121
	v_fma_f32 v156, v84, v156, v120
	v_fma_f32 v157, v84, v157, v121
	v_fma_f32 v154, v85, v154, v120
	v_fma_f32 v155, v85, v155, v121
	v_fma_f32 v84, v76, v185, v140
	v_fma_f32 v76, v76, v184, v140
	v_fma_f32 v85, v77, v182, v140
	v_fma_f32 v77, v77, v183, v140
	ds_read_b128 v[72:75], v145 offset:2560
	ds_read_b128 v[64:67], v145 offset:2816
	ds_read_b128 v[88:91], v145 offset:10752
	ds_read_b128 v[80:83], v145 offset:11008
	ds_read2_b32 v[118:119], v152 offset0:160 offset1:176
	v_sub_f32 v178, v178, v120
	v_sub_f32 v179, v179, v121
	v_sub_f32 v97, v97, v120
	v_sub_f32 v99, v99, v121
	v_fma_f32 v180, v94, v180, v120
	v_fma_f32 v181, v94, v181, v121
	v_fma_f32 v115, v86, v115, v120
	v_fma_f32 v117, v86, v117, v121
	v_fma_f32 v84, v68, v156, v84
	v_fma_f32 v76, v68, v157, v76
	v_fma_f32 v86, v78, v180, v140
	v_fma_f32 v78, v78, v181, v140
	v_fma_f32 v68, v69, v154, v85
	v_fma_f32 v77, v69, v155, v77
	v_fma_f32 v178, v95, v178, v120
	v_fma_f32 v179, v95, v179, v121
	v_fma_f32 v69, v70, v115, v86
	v_fma_f32 v70, v70, v117, v78
	v_fma_f32 v97, v87, v97, v120
	v_fma_f32 v99, v87, v99, v121
	v_fma_f32 v87, v79, v178, v140
	v_fma_f32 v79, v79, v179, v140
	v_add_f32_e32 v68, v84, v68
	v_fma_f32 v78, v71, v97, v87
	v_fma_f32 v71, v71, v99, v79
	v_add_f32_e32 v76, v76, v77
	v_add_f32_e32 v69, v69, v78
	v_add_f32_e32 v70, v70, v71
	v_add_f32_e32 v68, v68, v69
	v_add_f32_e32 v70, v76, v70
	v_mov_b32_e32 v69, 0
	v_add_f32_dpp v68, v68, v68 row_ror:8 row_mask:0xf bank_mask:0xf bound_ctrl:1
	v_add_f32_dpp v70, v70, v70 row_ror:8 row_mask:0xf bank_mask:0xf bound_ctrl:1
	v_mov_b32_e32 v71, 0
	v_add_f32_dpp v68, v68, v68 row_ror:4 row_mask:0xf bank_mask:0xf bound_ctrl:1
	v_add_f32_dpp v70, v70, v70 row_ror:4 row_mask:0xf bank_mask:0xf bound_ctrl:1
	s_nop 0
	v_add_f32_dpp v68, v68, v68 row_ror:2 row_mask:0xf bank_mask:0xf bound_ctrl:1
	v_add_f32_dpp v70, v70, v70 row_ror:2 row_mask:0xf bank_mask:0xf bound_ctrl:1
	s_nop 0
	v_mov_b32_dpp v69, v68 row_ror:1 row_mask:0xf bank_mask:0xf
	v_mov_b32_dpp v71, v70 row_ror:1 row_mask:0xf bank_mask:0xf
	s_and_saveexec_b64 s[8:9], s[38:39]
	v_add_f32_e32 v70, v70, v71
	v_add_f32_e32 v68, v68, v69
	ds_write2_b32 v146, v68, v70 offset0:128 offset1:144
	s_or_b64 exec, exec, s[8:9]
	s_waitcnt lgkmcnt(0)
	v_sub_f32 v185, v185, v118
	v_sub_f32 v184, v184, v119
	v_sub_f32 v182, v182, v118
	v_sub_f32 v183, v183, v119
	v_sub_f32 v156, v156, v118
	v_sub_f32 v157, v157, v119
	v_sub_f32 v154, v154, v118
	v_sub_f32 v155, v155, v119
	v_sub_f32 v180, v180, v118
	v_sub_f32 v181, v181, v119
	v_sub_f32 v115, v115, v118
	v_sub_f32 v117, v117, v119
	v_fma_f32 v185, v88, v185, v118
	v_fma_f32 v184, v88, v184, v119
	v_fma_f32 v182, v89, v182, v118
	v_fma_f32 v183, v89, v183, v119
	v_fma_f32 v156, v80, v156, v118
	v_fma_f32 v157, v80, v157, v119
	v_fma_f32 v154, v81, v154, v118
	v_fma_f32 v155, v81, v155, v119
	v_fma_f32 v80, v72, v185, v140
	v_fma_f32 v72, v72, v184, v140
	v_fma_f32 v81, v73, v182, v140
	v_fma_f32 v73, v73, v183, v140
	ds_read_b128 v[76:79], v145 offset:3072
	ds_read_b128 v[68:71], v145 offset:3328
	ds_read_b128 v[92:95], v145 offset:11264
	ds_read_b128 v[84:87], v145 offset:11520
	ds_read2_b32 v[120:121], v152 offset0:192 offset1:208
	v_sub_f32 v178, v178, v118
	v_sub_f32 v179, v179, v119
	v_sub_f32 v97, v97, v118
	v_sub_f32 v99, v99, v119
	v_fma_f32 v180, v90, v180, v118
	v_fma_f32 v181, v90, v181, v119
	v_fma_f32 v115, v82, v115, v118
	v_fma_f32 v117, v82, v117, v119
	v_fma_f32 v80, v64, v156, v80
	v_fma_f32 v72, v64, v157, v72
	v_fma_f32 v82, v74, v180, v140
	v_fma_f32 v74, v74, v181, v140
	v_fma_f32 v64, v65, v154, v81
	v_fma_f32 v73, v65, v155, v73
	v_fma_f32 v178, v91, v178, v118
	v_fma_f32 v179, v91, v179, v119
	v_fma_f32 v65, v66, v115, v82
	v_fma_f32 v66, v66, v117, v74
	v_fma_f32 v97, v83, v97, v118
	v_fma_f32 v99, v83, v99, v119
	v_fma_f32 v83, v75, v178, v140
	v_fma_f32 v75, v75, v179, v140
	v_add_f32_e32 v64, v80, v64
	v_fma_f32 v74, v67, v97, v83
	v_fma_f32 v67, v67, v99, v75
	v_add_f32_e32 v72, v72, v73
	v_add_f32_e32 v65, v65, v74
	v_add_f32_e32 v66, v66, v67
	v_add_f32_e32 v64, v64, v65
	v_add_f32_e32 v66, v72, v66
	v_mov_b32_e32 v65, 0
	v_add_f32_dpp v64, v64, v64 row_ror:8 row_mask:0xf bank_mask:0xf bound_ctrl:1
	v_add_f32_dpp v66, v66, v66 row_ror:8 row_mask:0xf bank_mask:0xf bound_ctrl:1
	v_mov_b32_e32 v67, 0
	v_add_f32_dpp v64, v64, v64 row_ror:4 row_mask:0xf bank_mask:0xf bound_ctrl:1
	v_add_f32_dpp v66, v66, v66 row_ror:4 row_mask:0xf bank_mask:0xf bound_ctrl:1
	s_nop 0
	v_add_f32_dpp v64, v64, v64 row_ror:2 row_mask:0xf bank_mask:0xf bound_ctrl:1
	v_add_f32_dpp v66, v66, v66 row_ror:2 row_mask:0xf bank_mask:0xf bound_ctrl:1
	s_nop 0
	v_mov_b32_dpp v65, v64 row_ror:1 row_mask:0xf bank_mask:0xf
	v_mov_b32_dpp v67, v66 row_ror:1 row_mask:0xf bank_mask:0xf
	s_and_saveexec_b64 s[8:9], s[38:39]
	v_add_f32_e32 v66, v66, v67
	v_add_f32_e32 v64, v64, v65
	ds_write2_b32 v146, v64, v66 offset0:160 offset1:176
	s_or_b64 exec, exec, s[8:9]
	ds_read_b128 v[72:75], v145 offset:3584
	ds_read_b128 v[64:67], v145 offset:3840
	ds_read_b128 v[88:91], v145 offset:11776
	ds_read_b128 v[80:83], v145 offset:12032
	ds_read2_b32 v[118:119], v152 offset0:224 offset1:240
	s_waitcnt lgkmcnt(5)
	v_sub_f32 v152, v185, v120
	v_sub_f32 v182, v182, v120
	v_sub_f32 v156, v156, v120
	v_sub_f32 v154, v154, v120
	v_sub_f32 v185, v184, v121
	v_sub_f32 v186, v183, v121
	v_sub_f32 v180, v180, v120
	v_sub_f32 v187, v181, v121
	v_sub_f32 v189, v157, v121
	v_sub_f32 v190, v155, v121
	v_sub_f32 v115, v115, v120
	v_sub_f32 v117, v117, v121
	v_fma_f32 v184, v92, v152, v120
	v_fma_f32 v183, v92, v185, v121
	v_fma_f32 v181, v93, v182, v120
	v_fma_f32 v182, v93, v186, v121
	v_fma_f32 v155, v84, v156, v120
	v_fma_f32 v156, v84, v189, v121
	v_fma_f32 v152, v85, v154, v120
	v_fma_f32 v154, v85, v190, v121
	v_fma_f32 v84, v76, v184, v140
	v_fma_f32 v76, v76, v183, v140
	v_fma_f32 v85, v77, v181, v140
	v_fma_f32 v77, v77, v182, v140
	v_sub_f32 v178, v178, v120
	v_sub_f32 v188, v179, v121
	v_sub_f32 v97, v97, v120
	v_sub_f32 v99, v99, v121
	v_fma_f32 v179, v94, v180, v120
	v_fma_f32 v180, v94, v187, v121
	v_fma_f32 v115, v86, v115, v120
	v_fma_f32 v117, v86, v117, v121
	v_fma_f32 v84, v68, v155, v84
	v_fma_f32 v76, v68, v156, v76
	v_fma_f32 v86, v78, v179, v140
	v_fma_f32 v78, v78, v180, v140
	v_fma_f32 v68, v69, v152, v85
	v_fma_f32 v77, v69, v154, v77
	v_fma_f32 v157, v95, v178, v120
	v_fma_f32 v178, v95, v188, v121
	v_fma_f32 v69, v70, v115, v86
	v_fma_f32 v70, v70, v117, v78
	v_fma_f32 v97, v87, v97, v120
	v_fma_f32 v99, v87, v99, v121
	v_fma_f32 v87, v79, v157, v140
	v_fma_f32 v79, v79, v178, v140
	v_add_f32_e32 v68, v84, v68
	v_fma_f32 v78, v71, v97, v87
	v_fma_f32 v71, v71, v99, v79
	v_add_f32_e32 v76, v76, v77
	v_add_f32_e32 v69, v69, v78
	v_add_f32_e32 v70, v70, v71
	v_add_f32_e32 v68, v68, v69
	v_add_f32_e32 v70, v76, v70
	v_mov_b32_e32 v69, 0
	v_add_f32_dpp v68, v68, v68 row_ror:8 row_mask:0xf bank_mask:0xf bound_ctrl:1
	v_add_f32_dpp v70, v70, v70 row_ror:8 row_mask:0xf bank_mask:0xf bound_ctrl:1
	v_mov_b32_e32 v71, 0
	v_add_f32_dpp v68, v68, v68 row_ror:4 row_mask:0xf bank_mask:0xf bound_ctrl:1
	v_add_f32_dpp v70, v70, v70 row_ror:4 row_mask:0xf bank_mask:0xf bound_ctrl:1
	s_nop 0
	v_add_f32_dpp v68, v68, v68 row_ror:2 row_mask:0xf bank_mask:0xf bound_ctrl:1
	v_add_f32_dpp v70, v70, v70 row_ror:2 row_mask:0xf bank_mask:0xf bound_ctrl:1
	s_nop 0
	v_mov_b32_dpp v69, v68 row_ror:1 row_mask:0xf bank_mask:0xf
	v_mov_b32_dpp v71, v70 row_ror:1 row_mask:0xf bank_mask:0xf
	s_and_saveexec_b64 s[8:9], s[38:39]
	v_add_f32_e32 v70, v70, v71
	v_add_f32_e32 v68, v68, v69
	ds_write2_b32 v146, v68, v70 offset0:192 offset1:208
	s_or_b64 exec, exec, s[8:9]
	s_waitcnt lgkmcnt(0)
	v_sub_f32 v184, v184, v118
	v_sub_f32 v183, v183, v119
	v_sub_f32 v181, v181, v118
	v_sub_f32 v182, v182, v119
	v_sub_f32 v155, v155, v118
	v_sub_f32 v156, v156, v119
	v_sub_f32 v152, v152, v118
	v_sub_f32 v154, v154, v119
	v_sub_f32 v179, v179, v118
	v_sub_f32 v180, v180, v119
	v_sub_f32 v115, v115, v118
	v_sub_f32 v117, v117, v119
	v_fma_f32 v184, v88, v184, v118
	v_fma_f32 v183, v88, v183, v119
	v_fma_f32 v181, v89, v181, v118
	v_fma_f32 v182, v89, v182, v119
	v_fma_f32 v155, v80, v155, v118
	v_fma_f32 v156, v80, v156, v119
	v_fma_f32 v152, v81, v152, v118
	v_fma_f32 v154, v81, v154, v119
	v_fma_f32 v80, v72, v184, v140
	v_fma_f32 v72, v72, v183, v140
	v_fma_f32 v81, v73, v181, v140
	v_fma_f32 v73, v73, v182, v140
	ds_read_b128 v[76:79], v145 offset:4096
	ds_read_b128 v[68:71], v145 offset:4352
	ds_read_b128 v[92:95], v145 offset:12288
	ds_read_b128 v[84:87], v145 offset:12544
	ds_read2_b32 v[120:121], v148 offset1:16
	v_sub_f32 v157, v157, v118
	v_sub_f32 v178, v178, v119
	v_sub_f32 v97, v97, v118
	v_sub_f32 v99, v99, v119
	v_fma_f32 v179, v90, v179, v118
	v_fma_f32 v180, v90, v180, v119
	v_fma_f32 v115, v82, v115, v118
	v_fma_f32 v117, v82, v117, v119
	v_fma_f32 v80, v64, v155, v80
	v_fma_f32 v72, v64, v156, v72
	v_fma_f32 v82, v74, v179, v140
	v_fma_f32 v74, v74, v180, v140
	v_fma_f32 v64, v65, v152, v81
	v_fma_f32 v73, v65, v154, v73
	v_fma_f32 v157, v91, v157, v118
	v_fma_f32 v178, v91, v178, v119
	v_fma_f32 v65, v66, v115, v82
	v_fma_f32 v66, v66, v117, v74
	v_fma_f32 v97, v83, v97, v118
	v_fma_f32 v99, v83, v99, v119
	v_fma_f32 v83, v75, v157, v140
	v_fma_f32 v75, v75, v178, v140
	v_add_f32_e32 v64, v80, v64
	v_fma_f32 v74, v67, v97, v83
	v_fma_f32 v67, v67, v99, v75
	v_add_f32_e32 v72, v72, v73
	v_add_f32_e32 v65, v65, v74
	v_add_f32_e32 v66, v66, v67
	v_add_f32_e32 v64, v64, v65
	v_add_f32_e32 v66, v72, v66
	v_mov_b32_e32 v65, 0
	v_add_f32_dpp v64, v64, v64 row_ror:8 row_mask:0xf bank_mask:0xf bound_ctrl:1
	v_add_f32_dpp v66, v66, v66 row_ror:8 row_mask:0xf bank_mask:0xf bound_ctrl:1
	v_mov_b32_e32 v67, 0
	v_add_f32_dpp v64, v64, v64 row_ror:4 row_mask:0xf bank_mask:0xf bound_ctrl:1
	v_add_f32_dpp v66, v66, v66 row_ror:4 row_mask:0xf bank_mask:0xf bound_ctrl:1
	s_nop 0
	v_add_f32_dpp v64, v64, v64 row_ror:2 row_mask:0xf bank_mask:0xf bound_ctrl:1
	v_add_f32_dpp v66, v66, v66 row_ror:2 row_mask:0xf bank_mask:0xf bound_ctrl:1
	s_nop 0
	v_mov_b32_dpp v65, v64 row_ror:1 row_mask:0xf bank_mask:0xf
	v_mov_b32_dpp v67, v66 row_ror:1 row_mask:0xf bank_mask:0xf
	s_and_saveexec_b64 s[8:9], s[38:39]
	v_add_f32_e32 v66, v66, v67
	v_add_f32_e32 v64, v64, v65
	ds_write2_b32 v146, v64, v66 offset0:224 offset1:240
	s_or_b64 exec, exec, s[8:9]
	s_waitcnt lgkmcnt(0)
	v_sub_f32 v146, v184, v120
	v_sub_f32 v181, v181, v120
	v_sub_f32 v155, v155, v120
	v_sub_f32 v152, v152, v120
	v_sub_f32 v184, v183, v121
	v_sub_f32 v185, v182, v121
	v_sub_f32 v179, v179, v120
	v_sub_f32 v186, v180, v121
	v_sub_f32 v188, v156, v121
	v_sub_f32 v189, v154, v121
	v_sub_f32 v115, v115, v120
	v_sub_f32 v117, v117, v121
	v_fma_f32 v183, v92, v146, v120
	v_fma_f32 v182, v92, v184, v121
	v_fma_f32 v180, v93, v181, v120
	v_fma_f32 v181, v93, v185, v121
	v_fma_f32 v154, v84, v155, v120
	v_fma_f32 v155, v84, v188, v121
	v_fma_f32 v146, v85, v152, v120
	v_fma_f32 v152, v85, v189, v121
	v_fma_f32 v84, v76, v183, v140
	v_fma_f32 v76, v76, v182, v140
	v_fma_f32 v85, v77, v180, v140
	v_fma_f32 v77, v77, v181, v140
	ds_read_b128 v[72:75], v145 offset:4608
	ds_read_b128 v[64:67], v145 offset:4864
	ds_read_b128 v[88:91], v145 offset:12800
	ds_read_b128 v[80:83], v145 offset:13056
	ds_read2_b32 v[118:119], v148 offset0:32 offset1:48
	v_sub_f32 v157, v157, v120
	v_sub_f32 v187, v178, v121
	v_sub_f32 v97, v97, v120
	v_sub_f32 v99, v99, v121
	v_fma_f32 v178, v94, v179, v120
	v_fma_f32 v179, v94, v186, v121
	v_fma_f32 v115, v86, v115, v120
	v_fma_f32 v117, v86, v117, v121
	v_fma_f32 v84, v68, v154, v84
	v_fma_f32 v76, v68, v155, v76
	v_fma_f32 v86, v78, v178, v140
	v_fma_f32 v78, v78, v179, v140
	v_fma_f32 v68, v69, v146, v85
	v_fma_f32 v77, v69, v152, v77
	v_fma_f32 v156, v95, v157, v120
	v_fma_f32 v157, v95, v187, v121
	v_fma_f32 v69, v70, v115, v86
	v_fma_f32 v70, v70, v117, v78
	v_fma_f32 v97, v87, v97, v120
	v_fma_f32 v99, v87, v99, v121
	v_fma_f32 v87, v79, v156, v140
	v_fma_f32 v79, v79, v157, v140
	v_add_f32_e32 v68, v84, v68
	v_fma_f32 v78, v71, v97, v87
	v_fma_f32 v71, v71, v99, v79
	v_add_f32_e32 v76, v76, v77
	v_add_f32_e32 v69, v69, v78
	v_add_f32_e32 v70, v70, v71
	v_add_f32_e32 v68, v68, v69
	v_add_f32_e32 v70, v76, v70
	v_mov_b32_e32 v69, 0
	v_add_f32_dpp v68, v68, v68 row_ror:8 row_mask:0xf bank_mask:0xf bound_ctrl:1
	v_add_f32_dpp v70, v70, v70 row_ror:8 row_mask:0xf bank_mask:0xf bound_ctrl:1
	v_mov_b32_e32 v71, 0
	v_add_f32_dpp v68, v68, v68 row_ror:4 row_mask:0xf bank_mask:0xf bound_ctrl:1
	v_add_f32_dpp v70, v70, v70 row_ror:4 row_mask:0xf bank_mask:0xf bound_ctrl:1
	s_nop 0
	v_add_f32_dpp v68, v68, v68 row_ror:2 row_mask:0xf bank_mask:0xf bound_ctrl:1
	v_add_f32_dpp v70, v70, v70 row_ror:2 row_mask:0xf bank_mask:0xf bound_ctrl:1
	s_nop 0
	v_mov_b32_dpp v69, v68 row_ror:1 row_mask:0xf bank_mask:0xf
	v_mov_b32_dpp v71, v70 row_ror:1 row_mask:0xf bank_mask:0xf
	s_and_saveexec_b64 s[8:9], s[38:39]
	v_add_f32_e32 v70, v70, v71
	v_add_f32_e32 v68, v68, v69
	ds_write2_b32 v147, v68, v70 offset1:16
	s_or_b64 exec, exec, s[8:9]
	s_waitcnt lgkmcnt(0)
	v_sub_f32 v183, v183, v118
	v_sub_f32 v182, v182, v119
	v_sub_f32 v180, v180, v118
	v_sub_f32 v181, v181, v119
	v_sub_f32 v154, v154, v118
	v_sub_f32 v155, v155, v119
	v_sub_f32 v146, v146, v118
	v_sub_f32 v152, v152, v119
	v_sub_f32 v178, v178, v118
	v_sub_f32 v179, v179, v119
	v_sub_f32 v115, v115, v118
	v_sub_f32 v117, v117, v119
	v_fma_f32 v183, v88, v183, v118
	v_fma_f32 v182, v88, v182, v119
	v_fma_f32 v180, v89, v180, v118
	v_fma_f32 v181, v89, v181, v119
	v_fma_f32 v154, v80, v154, v118
	v_fma_f32 v155, v80, v155, v119
	v_fma_f32 v146, v81, v146, v118
	v_fma_f32 v152, v81, v152, v119
	v_fma_f32 v80, v72, v183, v140
	v_fma_f32 v72, v72, v182, v140
	v_fma_f32 v81, v73, v180, v140
	v_fma_f32 v73, v73, v181, v140
	ds_read_b128 v[76:79], v145 offset:5120
	ds_read_b128 v[68:71], v145 offset:5376
	ds_read_b128 v[92:95], v145 offset:13312
	ds_read_b128 v[84:87], v145 offset:13568
	ds_read2_b32 v[120:121], v148 offset0:64 offset1:80
	v_sub_f32 v156, v156, v118
	v_sub_f32 v157, v157, v119
	v_sub_f32 v97, v97, v118
	v_sub_f32 v99, v99, v119
	v_fma_f32 v178, v90, v178, v118
	v_fma_f32 v179, v90, v179, v119
	v_fma_f32 v115, v82, v115, v118
	v_fma_f32 v117, v82, v117, v119
	v_fma_f32 v80, v64, v154, v80
	v_fma_f32 v72, v64, v155, v72
	v_fma_f32 v82, v74, v178, v140
	v_fma_f32 v74, v74, v179, v140
	v_fma_f32 v64, v65, v146, v81
	v_fma_f32 v73, v65, v152, v73
	v_fma_f32 v156, v91, v156, v118
	v_fma_f32 v157, v91, v157, v119
	v_fma_f32 v65, v66, v115, v82
	v_fma_f32 v66, v66, v117, v74
	v_fma_f32 v97, v83, v97, v118
	v_fma_f32 v99, v83, v99, v119
	v_fma_f32 v83, v75, v156, v140
	v_fma_f32 v75, v75, v157, v140
	v_add_f32_e32 v64, v80, v64
	v_fma_f32 v74, v67, v97, v83
	v_fma_f32 v67, v67, v99, v75
	v_add_f32_e32 v72, v72, v73
	v_add_f32_e32 v65, v65, v74
	v_add_f32_e32 v66, v66, v67
	v_add_f32_e32 v64, v64, v65
	v_add_f32_e32 v66, v72, v66
	v_mov_b32_e32 v65, 0
	v_add_f32_dpp v64, v64, v64 row_ror:8 row_mask:0xf bank_mask:0xf bound_ctrl:1
	v_add_f32_dpp v66, v66, v66 row_ror:8 row_mask:0xf bank_mask:0xf bound_ctrl:1
	v_mov_b32_e32 v67, 0
	v_add_f32_dpp v64, v64, v64 row_ror:4 row_mask:0xf bank_mask:0xf bound_ctrl:1
	v_add_f32_dpp v66, v66, v66 row_ror:4 row_mask:0xf bank_mask:0xf bound_ctrl:1
	s_nop 0
	v_add_f32_dpp v64, v64, v64 row_ror:2 row_mask:0xf bank_mask:0xf bound_ctrl:1
	v_add_f32_dpp v66, v66, v66 row_ror:2 row_mask:0xf bank_mask:0xf bound_ctrl:1
	s_nop 0
	v_mov_b32_dpp v65, v64 row_ror:1 row_mask:0xf bank_mask:0xf
	v_mov_b32_dpp v67, v66 row_ror:1 row_mask:0xf bank_mask:0xf
	s_and_saveexec_b64 s[8:9], s[38:39]
	v_add_f32_e32 v66, v66, v67
	v_add_f32_e32 v64, v64, v65
	ds_write2_b32 v147, v64, v66 offset0:32 offset1:48
	s_or_b64 exec, exec, s[8:9]
	s_waitcnt lgkmcnt(0)
	v_sub_f32 v183, v183, v120
	v_sub_f32 v182, v182, v121
	v_sub_f32 v180, v180, v120
	v_sub_f32 v181, v181, v121
	v_sub_f32 v154, v154, v120
	v_sub_f32 v155, v155, v121
	v_sub_f32 v146, v146, v120
	v_sub_f32 v152, v152, v121
	v_sub_f32 v178, v178, v120
	v_sub_f32 v179, v179, v121
	v_sub_f32 v115, v115, v120
	v_sub_f32 v117, v117, v121
	v_fma_f32 v183, v92, v183, v120
	v_fma_f32 v182, v92, v182, v121
	v_fma_f32 v180, v93, v180, v120
	v_fma_f32 v181, v93, v181, v121
	v_fma_f32 v154, v84, v154, v120
	v_fma_f32 v155, v84, v155, v121
	v_fma_f32 v146, v85, v146, v120
	v_fma_f32 v152, v85, v152, v121
	v_fma_f32 v84, v76, v183, v140
	v_fma_f32 v76, v76, v182, v140
	v_fma_f32 v85, v77, v180, v140
	v_fma_f32 v77, v77, v181, v140
	ds_read_b128 v[72:75], v145 offset:5632
	ds_read_b128 v[64:67], v145 offset:5888
	ds_read_b128 v[88:91], v145 offset:13824
	ds_read_b128 v[80:83], v145 offset:14080
	ds_read2_b32 v[118:119], v148 offset0:96 offset1:112
	v_sub_f32 v156, v156, v120
	v_sub_f32 v157, v157, v121
	v_sub_f32 v97, v97, v120
	v_sub_f32 v99, v99, v121
	v_fma_f32 v178, v94, v178, v120
	v_fma_f32 v179, v94, v179, v121
	v_fma_f32 v115, v86, v115, v120
	v_fma_f32 v117, v86, v117, v121
	v_fma_f32 v84, v68, v154, v84
	v_fma_f32 v76, v68, v155, v76
	v_fma_f32 v86, v78, v178, v140
	v_fma_f32 v78, v78, v179, v140
	v_fma_f32 v68, v69, v146, v85
	v_fma_f32 v77, v69, v152, v77
	v_fma_f32 v156, v95, v156, v120
	v_fma_f32 v157, v95, v157, v121
	v_fma_f32 v69, v70, v115, v86
	v_fma_f32 v70, v70, v117, v78
	v_fma_f32 v97, v87, v97, v120
	v_fma_f32 v99, v87, v99, v121
	v_fma_f32 v87, v79, v156, v140
	v_fma_f32 v79, v79, v157, v140
	v_add_f32_e32 v68, v84, v68
	v_fma_f32 v78, v71, v97, v87
	v_fma_f32 v71, v71, v99, v79
	v_add_f32_e32 v76, v76, v77
	v_add_f32_e32 v69, v69, v78
	v_add_f32_e32 v70, v70, v71
	v_add_f32_e32 v68, v68, v69
	v_add_f32_e32 v70, v76, v70
	v_mov_b32_e32 v69, 0
	v_add_f32_dpp v68, v68, v68 row_ror:8 row_mask:0xf bank_mask:0xf bound_ctrl:1
	v_add_f32_dpp v70, v70, v70 row_ror:8 row_mask:0xf bank_mask:0xf bound_ctrl:1
	v_mov_b32_e32 v71, 0
	v_add_f32_dpp v68, v68, v68 row_ror:4 row_mask:0xf bank_mask:0xf bound_ctrl:1
	v_add_f32_dpp v70, v70, v70 row_ror:4 row_mask:0xf bank_mask:0xf bound_ctrl:1
	s_nop 0
	v_add_f32_dpp v68, v68, v68 row_ror:2 row_mask:0xf bank_mask:0xf bound_ctrl:1
	v_add_f32_dpp v70, v70, v70 row_ror:2 row_mask:0xf bank_mask:0xf bound_ctrl:1
	s_nop 0
	v_mov_b32_dpp v69, v68 row_ror:1 row_mask:0xf bank_mask:0xf
	v_mov_b32_dpp v71, v70 row_ror:1 row_mask:0xf bank_mask:0xf
	s_and_saveexec_b64 s[8:9], s[38:39]
	v_add_f32_e32 v70, v70, v71
	v_add_f32_e32 v68, v68, v69
	ds_write2_b32 v147, v68, v70 offset0:64 offset1:80
	s_or_b64 exec, exec, s[8:9]
	s_waitcnt lgkmcnt(0)
	v_sub_f32 v183, v183, v118
	v_sub_f32 v182, v182, v119
	v_sub_f32 v180, v180, v118
	v_sub_f32 v181, v181, v119
	v_sub_f32 v154, v154, v118
	v_sub_f32 v155, v155, v119
	v_sub_f32 v146, v146, v118
	v_sub_f32 v152, v152, v119
	v_sub_f32 v178, v178, v118
	v_sub_f32 v179, v179, v119
	v_sub_f32 v115, v115, v118
	v_sub_f32 v117, v117, v119
	v_fma_f32 v183, v88, v183, v118
	v_fma_f32 v182, v88, v182, v119
	v_fma_f32 v180, v89, v180, v118
	v_fma_f32 v181, v89, v181, v119
	v_fma_f32 v154, v80, v154, v118
	v_fma_f32 v155, v80, v155, v119
	v_fma_f32 v146, v81, v146, v118
	v_fma_f32 v152, v81, v152, v119
	v_fma_f32 v80, v72, v183, v140
	v_fma_f32 v72, v72, v182, v140
	v_fma_f32 v81, v73, v180, v140
	v_fma_f32 v73, v73, v181, v140
	ds_read_b128 v[76:79], v145 offset:6144
	ds_read_b128 v[68:71], v145 offset:6400
	ds_read_b128 v[92:95], v145 offset:14336
	ds_read_b128 v[84:87], v145 offset:14592
	ds_read2_b32 v[120:121], v148 offset0:128 offset1:144
	v_sub_f32 v156, v156, v118
	v_sub_f32 v157, v157, v119
	v_sub_f32 v97, v97, v118
	v_sub_f32 v99, v99, v119
	v_fma_f32 v178, v90, v178, v118
	v_fma_f32 v179, v90, v179, v119
	v_fma_f32 v115, v82, v115, v118
	v_fma_f32 v117, v82, v117, v119
	v_fma_f32 v80, v64, v154, v80
	v_fma_f32 v72, v64, v155, v72
	v_fma_f32 v82, v74, v178, v140
	v_fma_f32 v74, v74, v179, v140
	v_fma_f32 v64, v65, v146, v81
	v_fma_f32 v73, v65, v152, v73
	v_fma_f32 v156, v91, v156, v118
	v_fma_f32 v157, v91, v157, v119
	v_fma_f32 v65, v66, v115, v82
	v_fma_f32 v66, v66, v117, v74
	v_fma_f32 v97, v83, v97, v118
	v_fma_f32 v99, v83, v99, v119
	v_fma_f32 v83, v75, v156, v140
	v_fma_f32 v75, v75, v157, v140
	v_add_f32_e32 v64, v80, v64
	v_fma_f32 v74, v67, v97, v83
	v_fma_f32 v67, v67, v99, v75
	v_add_f32_e32 v72, v72, v73
	v_add_f32_e32 v65, v65, v74
	v_add_f32_e32 v66, v66, v67
	v_add_f32_e32 v64, v64, v65
	v_add_f32_e32 v66, v72, v66
	v_mov_b32_e32 v65, 0
	v_add_f32_dpp v64, v64, v64 row_ror:8 row_mask:0xf bank_mask:0xf bound_ctrl:1
	v_add_f32_dpp v66, v66, v66 row_ror:8 row_mask:0xf bank_mask:0xf bound_ctrl:1
	v_mov_b32_e32 v67, 0
	v_add_f32_dpp v64, v64, v64 row_ror:4 row_mask:0xf bank_mask:0xf bound_ctrl:1
	v_add_f32_dpp v66, v66, v66 row_ror:4 row_mask:0xf bank_mask:0xf bound_ctrl:1
	s_nop 0
	v_add_f32_dpp v64, v64, v64 row_ror:2 row_mask:0xf bank_mask:0xf bound_ctrl:1
	v_add_f32_dpp v66, v66, v66 row_ror:2 row_mask:0xf bank_mask:0xf bound_ctrl:1
	s_nop 0
	v_mov_b32_dpp v65, v64 row_ror:1 row_mask:0xf bank_mask:0xf
	v_mov_b32_dpp v67, v66 row_ror:1 row_mask:0xf bank_mask:0xf
	s_and_saveexec_b64 s[8:9], s[38:39]
	v_add_f32_e32 v66, v66, v67
	v_add_f32_e32 v64, v64, v65
	ds_write2_b32 v147, v64, v66 offset0:96 offset1:112
	s_or_b64 exec, exec, s[8:9]
	s_waitcnt lgkmcnt(0)
	v_sub_f32 v183, v183, v120
	v_sub_f32 v182, v182, v121
	v_sub_f32 v180, v180, v120
	v_sub_f32 v181, v181, v121
	v_sub_f32 v154, v154, v120
	v_sub_f32 v155, v155, v121
	v_sub_f32 v146, v146, v120
	v_sub_f32 v152, v152, v121
	v_sub_f32 v178, v178, v120
	v_sub_f32 v179, v179, v121
	v_sub_f32 v115, v115, v120
	v_sub_f32 v117, v117, v121
	v_fma_f32 v183, v92, v183, v120
	v_fma_f32 v182, v92, v182, v121
	v_fma_f32 v180, v93, v180, v120
	v_fma_f32 v181, v93, v181, v121
	v_fma_f32 v154, v84, v154, v120
	v_fma_f32 v155, v84, v155, v121
	v_fma_f32 v146, v85, v146, v120
	v_fma_f32 v152, v85, v152, v121
	v_fma_f32 v84, v76, v183, v140
	v_fma_f32 v76, v76, v182, v140
	v_fma_f32 v85, v77, v180, v140
	v_fma_f32 v77, v77, v181, v140
	ds_read_b128 v[72:75], v145 offset:6656
	ds_read_b128 v[64:67], v145 offset:6912
	ds_read_b128 v[88:91], v145 offset:14848
	ds_read_b128 v[80:83], v145 offset:15104
	ds_read2_b32 v[118:119], v148 offset0:160 offset1:176
	v_sub_f32 v156, v156, v120
	v_sub_f32 v157, v157, v121
	v_sub_f32 v97, v97, v120
	v_sub_f32 v99, v99, v121
	v_fma_f32 v178, v94, v178, v120
	v_fma_f32 v179, v94, v179, v121
	v_fma_f32 v115, v86, v115, v120
	v_fma_f32 v117, v86, v117, v121
	v_fma_f32 v84, v68, v154, v84
	v_fma_f32 v76, v68, v155, v76
	v_fma_f32 v86, v78, v178, v140
	v_fma_f32 v78, v78, v179, v140
	v_fma_f32 v68, v69, v146, v85
	v_fma_f32 v77, v69, v152, v77
	v_fma_f32 v156, v95, v156, v120
	v_fma_f32 v157, v95, v157, v121
	v_fma_f32 v69, v70, v115, v86
	v_fma_f32 v70, v70, v117, v78
	v_fma_f32 v97, v87, v97, v120
	v_fma_f32 v99, v87, v99, v121
	v_fma_f32 v87, v79, v156, v140
	v_fma_f32 v79, v79, v157, v140
	v_add_f32_e32 v68, v84, v68
	v_fma_f32 v78, v71, v97, v87
	v_fma_f32 v71, v71, v99, v79
	v_add_f32_e32 v76, v76, v77
	v_add_f32_e32 v69, v69, v78
	v_add_f32_e32 v70, v70, v71
	v_add_f32_e32 v68, v68, v69
	v_add_f32_e32 v70, v76, v70
	v_mov_b32_e32 v69, 0
	v_add_f32_dpp v68, v68, v68 row_ror:8 row_mask:0xf bank_mask:0xf bound_ctrl:1
	v_add_f32_dpp v70, v70, v70 row_ror:8 row_mask:0xf bank_mask:0xf bound_ctrl:1
	v_mov_b32_e32 v71, 0
	v_add_f32_dpp v68, v68, v68 row_ror:4 row_mask:0xf bank_mask:0xf bound_ctrl:1
	v_add_f32_dpp v70, v70, v70 row_ror:4 row_mask:0xf bank_mask:0xf bound_ctrl:1
	s_nop 0
	v_add_f32_dpp v68, v68, v68 row_ror:2 row_mask:0xf bank_mask:0xf bound_ctrl:1
	v_add_f32_dpp v70, v70, v70 row_ror:2 row_mask:0xf bank_mask:0xf bound_ctrl:1
	s_nop 0
	v_mov_b32_dpp v69, v68 row_ror:1 row_mask:0xf bank_mask:0xf
	v_mov_b32_dpp v71, v70 row_ror:1 row_mask:0xf bank_mask:0xf
	s_and_saveexec_b64 s[8:9], s[38:39]
	v_add_f32_e32 v70, v70, v71
	v_add_f32_e32 v68, v68, v69
	ds_write2_b32 v147, v68, v70 offset0:128 offset1:144
	s_or_b64 exec, exec, s[8:9]
	s_waitcnt lgkmcnt(0)
	v_sub_f32 v183, v183, v118
	v_sub_f32 v182, v182, v119
	v_sub_f32 v180, v180, v118
	v_sub_f32 v181, v181, v119
	v_sub_f32 v154, v154, v118
	v_sub_f32 v155, v155, v119
	v_sub_f32 v146, v146, v118
	v_sub_f32 v152, v152, v119
	v_sub_f32 v178, v178, v118
	v_sub_f32 v179, v179, v119
	v_sub_f32 v115, v115, v118
	v_sub_f32 v117, v117, v119
	v_fma_f32 v183, v88, v183, v118
	v_fma_f32 v182, v88, v182, v119
	v_fma_f32 v180, v89, v180, v118
	v_fma_f32 v181, v89, v181, v119
	v_fma_f32 v154, v80, v154, v118
	v_fma_f32 v155, v80, v155, v119
	v_fma_f32 v146, v81, v146, v118
	v_fma_f32 v152, v81, v152, v119
	v_fma_f32 v80, v72, v183, v140
	v_fma_f32 v72, v72, v182, v140
	v_fma_f32 v81, v73, v180, v140
	v_fma_f32 v73, v73, v181, v140
	ds_read_b128 v[76:79], v145 offset:7168
	ds_read_b128 v[68:71], v145 offset:7424
	ds_read_b128 v[92:95], v145 offset:15360
	ds_read_b128 v[84:87], v145 offset:15616
	ds_read2_b32 v[120:121], v148 offset0:192 offset1:208
	v_sub_f32 v156, v156, v118
	v_sub_f32 v157, v157, v119
	v_sub_f32 v97, v97, v118
	v_sub_f32 v99, v99, v119
	v_fma_f32 v178, v90, v178, v118
	v_fma_f32 v179, v90, v179, v119
	v_fma_f32 v115, v82, v115, v118
	v_fma_f32 v117, v82, v117, v119
	v_fma_f32 v80, v64, v154, v80
	v_fma_f32 v72, v64, v155, v72
	v_fma_f32 v82, v74, v178, v140
	v_fma_f32 v74, v74, v179, v140
	v_fma_f32 v64, v65, v146, v81
	v_fma_f32 v73, v65, v152, v73
	v_fma_f32 v156, v91, v156, v118
	v_fma_f32 v157, v91, v157, v119
	v_fma_f32 v65, v66, v115, v82
	v_fma_f32 v66, v66, v117, v74
	v_fma_f32 v97, v83, v97, v118
	v_fma_f32 v99, v83, v99, v119
	v_fma_f32 v83, v75, v156, v140
	v_fma_f32 v75, v75, v157, v140
	v_add_f32_e32 v64, v80, v64
	v_fma_f32 v74, v67, v97, v83
	v_fma_f32 v67, v67, v99, v75
	v_add_f32_e32 v72, v72, v73
	v_add_f32_e32 v65, v65, v74
	v_add_f32_e32 v66, v66, v67
	v_add_f32_e32 v64, v64, v65
	v_add_f32_e32 v66, v72, v66
	v_mov_b32_e32 v65, 0
	v_add_f32_dpp v64, v64, v64 row_ror:8 row_mask:0xf bank_mask:0xf bound_ctrl:1
	v_add_f32_dpp v66, v66, v66 row_ror:8 row_mask:0xf bank_mask:0xf bound_ctrl:1
	v_mov_b32_e32 v67, 0
	v_add_f32_dpp v64, v64, v64 row_ror:4 row_mask:0xf bank_mask:0xf bound_ctrl:1
	v_add_f32_dpp v66, v66, v66 row_ror:4 row_mask:0xf bank_mask:0xf bound_ctrl:1
	s_nop 0
	v_add_f32_dpp v64, v64, v64 row_ror:2 row_mask:0xf bank_mask:0xf bound_ctrl:1
	v_add_f32_dpp v66, v66, v66 row_ror:2 row_mask:0xf bank_mask:0xf bound_ctrl:1
	s_nop 0
	v_mov_b32_dpp v65, v64 row_ror:1 row_mask:0xf bank_mask:0xf
	v_mov_b32_dpp v67, v66 row_ror:1 row_mask:0xf bank_mask:0xf
	s_and_saveexec_b64 s[8:9], s[38:39]
	v_add_f32_e32 v66, v66, v67
	v_add_f32_e32 v64, v64, v65
	ds_write2_b32 v147, v64, v66 offset0:160 offset1:176
	s_or_b64 exec, exec, s[8:9]
	ds_read_b128 v[72:75], v145 offset:7680
	ds_read_b128 v[64:67], v145 offset:7936
	ds_read_b128 v[88:91], v145 offset:15872
	ds_read_b128 v[80:83], v145 offset:16128
	ds_read2_b32 v[118:119], v148 offset0:224 offset1:240
	s_waitcnt lgkmcnt(5)
	v_sub_f32 v148, v183, v120
	v_sub_f32 v182, v182, v121
	v_sub_f32 v180, v180, v120
	v_sub_f32 v181, v181, v121
	v_sub_f32 v178, v178, v120
	v_sub_f32 v179, v179, v121
	v_sub_f32 v156, v156, v120
	v_sub_f32 v157, v157, v121
	v_sub_f32 v183, v154, v120
	v_sub_f32 v184, v155, v121
	v_sub_f32 v185, v146, v120
	v_sub_f32 v186, v152, v121
	v_sub_f32 v187, v115, v120
	v_sub_f32 v188, v117, v121
	v_sub_f32 v189, v97, v120
	v_sub_f32 v190, v99, v121
	v_fma_f32 v155, v92, v148, v120
	v_fma_f32 v154, v92, v182, v121
	v_fma_f32 v148, v93, v180, v120
	v_fma_f32 v152, v93, v181, v121
	v_fma_f32 v117, v94, v178, v120
	v_fma_f32 v146, v94, v179, v121
	v_fma_f32 v99, v95, v156, v120
	v_fma_f32 v115, v95, v157, v121
	v_fma_f32 v95, v84, v183, v120
	v_fma_f32 v97, v84, v184, v121
	v_fma_f32 v93, v85, v185, v120
	v_fma_f32 v94, v85, v186, v121
	v_fma_f32 v92, v86, v187, v120
	v_fma_f32 v84, v87, v189, v120
	v_fma_f32 v85, v87, v190, v121
	v_fma_f32 v87, v76, v155, v140
	v_fma_f32 v76, v76, v154, v140
	v_fma_f32 v120, v77, v148, v140
	v_fma_f32 v77, v77, v152, v140
	v_fma_f32 v86, v86, v188, v121
	v_fma_f32 v121, v78, v117, v140
	v_fma_f32 v78, v78, v146, v140
	v_fma_f32 v87, v68, v95, v87
	v_fma_f32 v76, v68, v97, v76
	v_fma_f32 v68, v69, v93, v120
	v_fma_f32 v77, v69, v94, v77
	v_fma_f32 v69, v70, v92, v121
	v_fma_f32 v70, v70, v86, v78
	v_fma_f32 v156, v79, v99, v140
	v_fma_f32 v79, v79, v115, v140
	v_add_f32_e32 v68, v87, v68
	v_fma_f32 v78, v71, v84, v156
	v_fma_f32 v71, v71, v85, v79
	v_add_f32_e32 v76, v76, v77
	v_add_f32_e32 v69, v69, v78
	v_add_f32_e32 v70, v70, v71
	v_add_f32_e32 v68, v68, v69
	v_add_f32_e32 v70, v76, v70
	v_mov_b32_e32 v69, 0
	v_add_f32_dpp v68, v68, v68 row_ror:8 row_mask:0xf bank_mask:0xf bound_ctrl:1
	v_add_f32_dpp v70, v70, v70 row_ror:8 row_mask:0xf bank_mask:0xf bound_ctrl:1
	v_mov_b32_e32 v71, 0
	v_add_f32_dpp v68, v68, v68 row_ror:4 row_mask:0xf bank_mask:0xf bound_ctrl:1
	v_add_f32_dpp v70, v70, v70 row_ror:4 row_mask:0xf bank_mask:0xf bound_ctrl:1
	s_nop 0
	v_add_f32_dpp v68, v68, v68 row_ror:2 row_mask:0xf bank_mask:0xf bound_ctrl:1
	v_add_f32_dpp v70, v70, v70 row_ror:2 row_mask:0xf bank_mask:0xf bound_ctrl:1
	s_nop 0
	v_mov_b32_dpp v69, v68 row_ror:1 row_mask:0xf bank_mask:0xf
	v_mov_b32_dpp v71, v70 row_ror:1 row_mask:0xf bank_mask:0xf
	s_and_saveexec_b64 s[8:9], s[38:39]
	v_add_f32_e32 v70, v70, v71
	v_add_f32_e32 v68, v68, v69
	ds_write2_b32 v147, v68, v70 offset0:192 offset1:208
	s_or_b64 exec, exec, s[8:9]
	s_waitcnt lgkmcnt(0)
	v_sub_f32 v76, v117, v118
	v_sub_f32 v77, v146, v119
	v_sub_f32 v78, v99, v118
	v_sub_f32 v79, v115, v119
	v_sub_f32 v68, v155, v118
	v_sub_f32 v69, v154, v119
	v_sub_f32 v70, v148, v118
	v_sub_f32 v71, v152, v119
	v_sub_f32 v99, v95, v118
	v_sub_f32 v97, v97, v119
	v_sub_f32 v115, v93, v118
	v_sub_f32 v117, v94, v119
	v_sub_f32 v120, v92, v118
	v_sub_f32 v121, v86, v119
	v_sub_f32 v146, v84, v118
	v_sub_f32 v148, v85, v119
	v_fma_f32 v95, v88, v68, v118
	v_fma_f32 v94, v88, v69, v119
	v_fma_f32 v92, v89, v70, v118
	v_fma_f32 v93, v89, v71, v119
	v_fma_f32 v86, v90, v76, v118
	v_fma_f32 v87, v90, v77, v119
	v_fma_f32 v84, v91, v78, v118
	v_fma_f32 v85, v91, v79, v119
	v_fma_f32 v78, v80, v99, v118
	v_fma_f32 v79, v80, v97, v119
	v_fma_f32 v76, v81, v115, v118
	v_fma_f32 v77, v81, v117, v119
	v_fma_f32 v80, v72, v95, v140
	v_fma_f32 v72, v72, v94, v140
	v_fma_f32 v81, v73, v92, v140
	v_fma_f32 v73, v73, v93, v140
	v_fma_f32 v70, v82, v120, v118
	v_fma_f32 v71, v82, v121, v119
	v_fma_f32 v82, v74, v86, v140
	v_fma_f32 v74, v74, v87, v140
	v_fma_f32 v80, v64, v78, v80
	v_fma_f32 v72, v64, v79, v72
	v_fma_f32 v64, v65, v76, v81
	v_fma_f32 v73, v65, v77, v73
	v_fma_f32 v65, v66, v70, v82
	v_fma_f32 v66, v66, v71, v74
	v_fma_f32 v68, v83, v146, v118
	v_fma_f32 v69, v83, v148, v119
	v_fma_f32 v83, v75, v84, v140
	v_fma_f32 v75, v75, v85, v140
	v_add_f32_e32 v64, v80, v64
	v_fma_f32 v74, v67, v68, v83
	v_fma_f32 v67, v67, v69, v75
	v_add_f32_e32 v72, v72, v73
	v_add_f32_e32 v65, v65, v74
	v_add_f32_e32 v66, v66, v67
	v_add_f32_e32 v64, v64, v65
	v_add_f32_e32 v66, v72, v66
	v_mov_b32_e32 v65, 0
	v_add_f32_dpp v64, v64, v64 row_ror:8 row_mask:0xf bank_mask:0xf bound_ctrl:1
	v_add_f32_dpp v66, v66, v66 row_ror:8 row_mask:0xf bank_mask:0xf bound_ctrl:1
	v_mov_b32_e32 v67, 0
	v_add_f32_dpp v64, v64, v64 row_ror:4 row_mask:0xf bank_mask:0xf bound_ctrl:1
	v_add_f32_dpp v66, v66, v66 row_ror:4 row_mask:0xf bank_mask:0xf bound_ctrl:1
	s_nop 0
	v_add_f32_dpp v64, v64, v64 row_ror:2 row_mask:0xf bank_mask:0xf bound_ctrl:1
	v_add_f32_dpp v66, v66, v66 row_ror:2 row_mask:0xf bank_mask:0xf bound_ctrl:1
	s_nop 0
	v_mov_b32_dpp v65, v64 row_ror:1 row_mask:0xf bank_mask:0xf
	v_mov_b32_dpp v67, v66 row_ror:1 row_mask:0xf bank_mask:0xf
	s_and_saveexec_b64 s[8:9], s[38:39]
	v_add_f32_e32 v66, v66, v67
	v_add_f32_e32 v64, v64, v65
	ds_write2_b32 v147, v64, v66 offset0:224 offset1:240
	s_or_b64 exec, exec, s[8:9]
	s_waitcnt vmcnt(5)
	v_mul_f32_e32 v64, 0xbfb8aa3b, v44
	v_mul_f32_e32 v65, 0xbfb8aa3b, v45
	v_exp_f32_e32 v64, v64
	v_exp_f32_e32 v65, v65
	v_mul_f32_e32 v66, 0xbfb8aa3b, v46
	v_mul_f32_e32 v67, 0xbfb8aa3b, v47
	v_exp_f32_e32 v66, v66
	v_pk_add_f32 v[64:65], v[64:65], 1.0 op_sel_hi:[1,0]
	v_exp_f32_e32 v67, v67
	v_div_scale_f32 v80, s[8:9], v65, v65, v45
	v_rcp_f32_e32 v81, v80
	v_pk_add_f32 v[66:67], v[66:67], 1.0 op_sel_hi:[1,0]
	v_mul_f32_e32 v72, 0xbfb8aa3b, v48
	v_mul_f32_e32 v73, 0xbfb8aa3b, v49
	v_fma_f32 v82, -v80, v81, 1.0
	v_fmac_f32_e32 v81, v82, v81
	v_div_scale_f32 v82, vcc, v45, v65, v45
	v_mul_f32_e32 v83, v82, v81
	v_fma_f32 v88, -v80, v83, v82
	v_fmac_f32_e32 v83, v88, v81
	v_fma_f32 v80, -v80, v83, v82
	v_div_fmas_f32 v80, v80, v81, v83
	v_div_fixup_f32 v65, v80, v65, v45
	v_div_scale_f32 v80, s[8:9], v64, v64, v44
	v_rcp_f32_e32 v81, v80
	v_exp_f32_e32 v72, v72
	v_exp_f32_e32 v73, v73
	v_mul_f32_e32 v74, 0xbfb8aa3b, v50
	v_fma_f32 v82, -v80, v81, 1.0
	v_fmac_f32_e32 v81, v82, v81
	v_div_scale_f32 v82, vcc, v44, v64, v44
	v_mul_f32_e32 v83, v82, v81
	v_fma_f32 v88, -v80, v83, v82
	v_fmac_f32_e32 v83, v88, v81
	v_fma_f32 v80, -v80, v83, v82
	v_div_fmas_f32 v80, v80, v81, v83
	v_div_fixup_f32 v64, v80, v64, v44
	v_div_scale_f32 v80, s[8:9], v67, v67, v47
	v_rcp_f32_e32 v81, v80
	v_pk_mul_f32 v[64:65], v[64:65], s[18:19] op_sel_hi:[1,0]
	v_mul_f32_e32 v75, 0xbfb8aa3b, v51
	v_exp_f32_e32 v74, v74
	v_fma_f32 v82, -v80, v81, 1.0
	v_fmac_f32_e32 v81, v82, v81
	v_div_scale_f32 v82, vcc, v47, v67, v47
	v_mul_f32_e32 v83, v82, v81
	v_fma_f32 v88, -v80, v83, v82
	v_fmac_f32_e32 v83, v88, v81
	v_fma_f32 v80, -v80, v83, v82
	v_div_fmas_f32 v80, v80, v81, v83
	v_div_fixup_f32 v67, v80, v67, v47
	v_div_scale_f32 v80, s[8:9], v66, v66, v46
	v_rcp_f32_e32 v81, v80
	v_exp_f32_e32 v75, v75
	s_cmpk_gt_u32 s48, 0x78
	v_fma_f32 v82, -v80, v81, 1.0
	v_fmac_f32_e32 v81, v82, v81
	v_div_scale_f32 v82, vcc, v46, v66, v46
	v_mul_f32_e32 v83, v82, v81
	v_fma_f32 v88, -v80, v83, v82
	v_fmac_f32_e32 v83, v88, v81
	v_fma_f32 v80, -v80, v83, v82
	v_div_fmas_f32 v80, v80, v81, v83
	v_div_fixup_f32 v66, v80, v66, v46
	v_pk_mul_f32 v[66:67], v[66:67], s[18:19] op_sel_hi:[1,0]
	ds_write_b128 v141, v[64:67] offset:18432
	v_pk_add_f32 v[64:65], v[72:73], 1.0 op_sel_hi:[1,0]
	v_div_scale_f32 v66, s[8:9], v65, v65, 1.0
	v_rcp_f32_e32 v67, v66
	s_nop 0
	v_fma_f32 v72, -v66, v67, 1.0
	v_fmac_f32_e32 v67, v72, v67
	v_div_scale_f32 v72, vcc, 1.0, v65, 1.0
	v_mul_f32_e32 v73, v72, v67
	v_fma_f32 v80, -v66, v73, v72
	v_fmac_f32_e32 v73, v80, v67
	v_fma_f32 v66, -v66, v73, v72
	v_div_fmas_f32 v66, v66, v67, v73
	v_div_fixup_f32 v65, v66, v65, 1.0
	v_div_scale_f32 v66, s[8:9], v64, v64, 1.0
	v_rcp_f32_e32 v67, v66
	s_nop 0
	v_fma_f32 v72, -v66, v67, 1.0
	v_fmac_f32_e32 v67, v72, v67
	v_div_scale_f32 v72, vcc, 1.0, v64, 1.0
	v_mul_f32_e32 v73, v72, v67
	v_fma_f32 v80, -v66, v73, v72
	v_fmac_f32_e32 v73, v80, v67
	v_fma_f32 v66, -v66, v73, v72
	v_div_fmas_f32 v66, v66, v67, v73
	v_div_fixup_f32 v64, v66, v64, 1.0
	v_pk_add_f32 v[66:67], v[74:75], 1.0 op_sel_hi:[1,0]
	v_pk_fma_f32 v[64:65], v[110:111], v[64:65], v[104:105]
	v_div_scale_f32 v72, s[8:9], v67, v67, 1.0
	v_rcp_f32_e32 v73, v72
	s_nop 0
	v_fma_f32 v74, -v72, v73, 1.0
	v_fmac_f32_e32 v73, v74, v73
	v_div_scale_f32 v74, vcc, 1.0, v67, 1.0
	v_mul_f32_e32 v75, v74, v73
	v_fma_f32 v80, -v72, v75, v74
	v_fmac_f32_e32 v75, v80, v73
	v_fma_f32 v72, -v72, v75, v74
	v_div_fmas_f32 v72, v72, v73, v75
	v_div_fixup_f32 v67, v72, v67, 1.0
	v_div_scale_f32 v72, s[8:9], v66, v66, 1.0
	v_rcp_f32_e32 v73, v72
	s_nop 0
	v_fma_f32 v74, -v72, v73, 1.0
	v_fmac_f32_e32 v73, v74, v73
	v_div_scale_f32 v74, vcc, 1.0, v66, 1.0
	v_mul_f32_e32 v75, v74, v73
	v_fma_f32 v80, -v72, v75, v74
	v_fmac_f32_e32 v75, v80, v73
	v_fma_f32 v72, -v72, v75, v74
	v_div_fmas_f32 v72, v72, v73, v75
	v_div_fixup_f32 v66, v72, v66, 1.0
	v_pk_fma_f32 v[66:67], v[112:113], v[66:67], v[106:107]
	ds_write_b128 v141, v[64:67] offset:26624
	ds_write_b32 v134, v133 offset:34816
	v_mul_f32_e32 v64, 0xbfb8aa3b, v56
	v_mul_f32_e32 v65, 0xbfb8aa3b, v57
	v_exp_f32_e32 v64, v64
	v_exp_f32_e32 v65, v65
	v_mul_f32_e32 v66, 0xbfb8aa3b, v58
	v_mul_f32_e32 v67, 0xbfb8aa3b, v59
	v_exp_f32_e32 v66, v66
	v_pk_add_f32 v[64:65], v[64:65], 1.0 op_sel_hi:[1,0]
	v_exp_f32_e32 v67, v67
	v_div_scale_f32 v80, s[8:9], v65, v65, v57
	v_rcp_f32_e32 v81, v80
	v_pk_add_f32 v[66:67], v[66:67], 1.0 op_sel_hi:[1,0]
	s_waitcnt vmcnt(4)
	v_mul_f32_e32 v72, 0xbfb8aa3b, v60
	v_mul_f32_e32 v73, 0xbfb8aa3b, v61
	v_fma_f32 v82, -v80, v81, 1.0
	v_fmac_f32_e32 v81, v82, v81
	v_div_scale_f32 v82, vcc, v57, v65, v57
	v_mul_f32_e32 v83, v82, v81
	v_fma_f32 v88, -v80, v83, v82
	v_fmac_f32_e32 v83, v88, v81
	v_fma_f32 v80, -v80, v83, v82
	v_div_fmas_f32 v80, v80, v81, v83
	v_div_fixup_f32 v65, v80, v65, v57
	v_div_scale_f32 v80, s[8:9], v64, v64, v56
	v_rcp_f32_e32 v81, v80
	v_exp_f32_e32 v72, v72
	v_exp_f32_e32 v73, v73
	v_mul_f32_e32 v74, 0xbfb8aa3b, v62
	v_fma_f32 v82, -v80, v81, 1.0
	v_fmac_f32_e32 v81, v82, v81
	v_div_scale_f32 v82, vcc, v56, v64, v56
	v_mul_f32_e32 v83, v82, v81
	v_fma_f32 v88, -v80, v83, v82
	v_fmac_f32_e32 v83, v88, v81
	v_fma_f32 v80, -v80, v83, v82
	v_div_fmas_f32 v80, v80, v81, v83
	v_div_fixup_f32 v64, v80, v64, v56
	v_div_scale_f32 v80, s[8:9], v67, v67, v59
	v_rcp_f32_e32 v81, v80
	v_pk_mul_f32 v[64:65], v[64:65], s[18:19] op_sel_hi:[1,0]
	v_mul_f32_e32 v75, 0xbfb8aa3b, v63
	v_exp_f32_e32 v74, v74
	v_fma_f32 v82, -v80, v81, 1.0
	v_fmac_f32_e32 v81, v82, v81
	v_div_scale_f32 v82, vcc, v59, v67, v59
	v_mul_f32_e32 v83, v82, v81
	v_fma_f32 v88, -v80, v83, v82
	v_fmac_f32_e32 v83, v88, v81
	v_fma_f32 v80, -v80, v83, v82
	v_div_fmas_f32 v80, v80, v81, v83
	v_div_fixup_f32 v67, v80, v67, v59
	v_div_scale_f32 v80, s[8:9], v66, v66, v58
	v_rcp_f32_e32 v81, v80
	v_exp_f32_e32 v75, v75
	v_fma_f32 v82, -v80, v81, 1.0
	v_fmac_f32_e32 v81, v82, v81
	v_div_scale_f32 v82, vcc, v58, v66, v58
	v_mul_f32_e32 v83, v82, v81
	v_fma_f32 v88, -v80, v83, v82
	v_fmac_f32_e32 v83, v88, v81
	v_fma_f32 v80, -v80, v83, v82
	v_div_fmas_f32 v80, v80, v81, v83
	v_div_fixup_f32 v66, v80, v66, v58
	v_pk_mul_f32 v[66:67], v[66:67], s[18:19] op_sel_hi:[1,0]
	ds_write_b128 v144, v[64:67] offset:18432
	v_pk_add_f32 v[64:65], v[72:73], 1.0 op_sel_hi:[1,0]
	v_div_scale_f32 v66, s[8:9], v65, v65, 1.0
	v_rcp_f32_e32 v67, v66
	s_nop 0
	v_fma_f32 v72, -v66, v67, 1.0
	v_fmac_f32_e32 v67, v72, v67
	v_div_scale_f32 v72, vcc, 1.0, v65, 1.0
	v_mul_f32_e32 v73, v72, v67
	v_fma_f32 v80, -v66, v73, v72
	v_fmac_f32_e32 v73, v80, v67
	v_fma_f32 v66, -v66, v73, v72
	v_div_fmas_f32 v66, v66, v67, v73
	v_div_fixup_f32 v65, v66, v65, 1.0
	v_div_scale_f32 v66, s[8:9], v64, v64, 1.0
	v_rcp_f32_e32 v67, v66
	s_nop 0
	v_fma_f32 v72, -v66, v67, 1.0
	v_fmac_f32_e32 v67, v72, v67
	v_div_scale_f32 v72, vcc, 1.0, v64, 1.0
	v_mul_f32_e32 v73, v72, v67
	v_fma_f32 v80, -v66, v73, v72
	v_fmac_f32_e32 v73, v80, v67
	v_fma_f32 v66, -v66, v73, v72
	v_div_fmas_f32 v66, v66, v67, v73
	v_div_fixup_f32 v64, v66, v64, 1.0
	v_pk_add_f32 v[66:67], v[74:75], 1.0 op_sel_hi:[1,0]
	v_pk_fma_f32 v[64:65], v[110:111], v[64:65], v[104:105]
	v_div_scale_f32 v72, s[8:9], v67, v67, 1.0
	v_rcp_f32_e32 v73, v72
	s_nop 0
	v_fma_f32 v74, -v72, v73, 1.0
	v_fmac_f32_e32 v73, v74, v73
	v_div_scale_f32 v74, vcc, 1.0, v67, 1.0
	v_mul_f32_e32 v75, v74, v73
	v_fma_f32 v80, -v72, v75, v74
	v_fmac_f32_e32 v75, v80, v73
	v_fma_f32 v72, -v72, v75, v74
	v_div_fmas_f32 v72, v72, v73, v75
	v_div_fixup_f32 v67, v72, v67, 1.0
	v_div_scale_f32 v72, s[8:9], v66, v66, 1.0
	v_rcp_f32_e32 v73, v72
	s_nop 0
	v_fma_f32 v74, -v72, v73, 1.0
	v_fmac_f32_e32 v73, v74, v73
	v_div_scale_f32 v74, vcc, 1.0, v66, 1.0
	v_mul_f32_e32 v75, v74, v73
	v_fma_f32 v80, -v72, v75, v74
	v_fmac_f32_e32 v75, v80, v73
	v_fma_f32 v72, -v72, v75, v74
	v_div_fmas_f32 v72, v72, v73, v75
	v_div_fixup_f32 v66, v72, v66, 1.0
	v_pk_fma_f32 v[66:67], v[112:113], v[66:67], v[106:107]
	ds_write_b128 v144, v[64:67] offset:26624
	ds_write_b32 v134, v135 offset:35840
	s_waitcnt lgkmcnt(0)
	s_barrier
	s_cbranch_scc1 .LBB0_1393
	v_add_u32_e32 v44, 0x70, v98
	v_mov_b64_e32 v[56:57], s[30:31]
	v_mad_i64_i32 v[44:45], s[8:9], v44, s25, v[56:57]
	s_lshl_b32 s94, s46, 2
	v_lshl_add_u64 v[58:59], v[44:45], 0, s[94:95]
	v_mov_b32_e32 v117, v140
	v_lshl_add_u64 v[44:45], v[58:59], 0, v[116:117]
	v_add_co_u32_e32 v46, vcc, 0x4000, v44
	s_lshl_b32 s8, s42, 2
	s_nop 0
	v_addc_co_u32_e32 v47, vcc, 0, v45, vcc
	s_mov_b32 s9, s95
	v_add_co_u32_e32 v48, vcc, 0x5000, v44
	v_lshl_add_u64 v[58:59], v[58:59], 0, s[8:9]
	v_mov_b32_e32 v115, v140
	v_add_u32_e32 v60, 0x70, v96
	v_addc_co_u32_e32 v49, vcc, 0, v45, vcc
	v_lshl_add_u64 v[58:59], v[58:59], 0, v[114:115]
	v_mad_i64_i32 v[56:57], s[22:23], v60, s25, v[56:57]
	v_add_co_u32_e32 v58, vcc, s81, v58
	v_lshl_add_u64 v[60:61], v[56:57], 0, s[94:95]
	s_nop 0
	v_addc_co_u32_e32 v59, vcc, 0, v59, vcc
	v_lshl_add_u64 v[62:63], v[60:61], 0, v[116:117]
	v_add_co_u32_e32 v56, vcc, s80, v62
	v_lshl_add_u64 v[60:61], v[60:61], 0, s[8:9]
	s_nop 0
	v_addc_co_u32_e32 v57, vcc, 0, v63, vcc
	v_add_co_u32_e32 v62, vcc, 0x5000, v62
	v_lshl_add_u64 v[60:61], v[60:61], 0, v[114:115]
	s_nop 0
	v_addc_co_u32_e32 v63, vcc, 0, v63, vcc
	v_add_co_u32_e32 v64, vcc, 0x6000, v60
	global_load_dwordx4 v[44:47], v[46:47], off offset:32
	s_nop 0
	global_load_dwordx4 v[48:51], v[48:49], off offset:32
	s_nop 0
	global_load_dword v133, v[58:59], off offset:32
	s_nop 0
	global_load_dwordx4 v[56:59], v[56:57], off offset:32
	v_addc_co_u32_e32 v65, vcc, 0, v61, vcc
	global_load_dwordx4 v[60:63], v[62:63], off offset:32
	s_nop 0
	global_load_dword v135, v[64:65], off offset:32
.LBB0_1393:
	ds_read2st64_b32 v[64:65], v134 offset0:144 offset1:148
	v_add_u32_e32 v66, 32, v98
	v_ashrrev_i32_e32 v67, 31, v66
	v_lshlrev_b64 v[66:67], 12, v[66:67]
	v_lshl_add_u64 v[66:67], v[108:109], 0, v[66:67]
	s_waitcnt lgkmcnt(0)
	global_store_dword v[66:67], v64, off
	v_add_u32_e32 v66, 32, v96
	v_ashrrev_i32_e32 v67, 31, v66
	v_lshlrev_b64 v[66:67], 12, v[66:67]
	v_lshl_add_u64 v[66:67], v[108:109], 0, v[66:67]
	global_store_dword v[66:67], v65, off
	ds_read_b128 v[178:181], v145 offset:18432
	ds_read_b128 v[182:185], v145 offset:18688
	ds_read_b128 v[114:117], v145 offset:26624
	ds_read_b128 v[186:189], v145 offset:26880
	ds_read2_b32 v[98:99], v153 offset1:16
	ds_read_b128 v[72:75], v145 offset:18944
	ds_read_b128 v[64:67], v145 offset:19200
	ds_read_b128 v[88:91], v145 offset:27136
	ds_read_b128 v[80:83], v145 offset:27392
	ds_read2_b32 v[96:97], v153 offset0:32 offset1:48
	s_waitcnt lgkmcnt(5)
	v_sub_f32 v70, v70, v98
	v_sub_f32 v71, v71, v99
	v_sub_f32 v68, v68, v98
	v_sub_f32 v69, v69, v99
	v_sub_f32 v95, v95, v98
	v_sub_f32 v94, v94, v99
	v_sub_f32 v92, v92, v98
	v_sub_f32 v93, v93, v99
	v_sub_f32 v86, v86, v98
	v_sub_f32 v87, v87, v99
	v_sub_f32 v84, v84, v98
	v_sub_f32 v85, v85, v99
	v_sub_f32 v78, v78, v98
	v_sub_f32 v76, v76, v98
	v_sub_f32 v77, v77, v99
	v_fma_f32 v157, v114, v95, v98
	v_fma_f32 v156, v114, v94, v99
	v_fma_f32 v154, v115, v92, v98
	v_fma_f32 v155, v115, v93, v99
	v_fma_f32 v148, v116, v86, v98
	v_fma_f32 v152, v116, v87, v99
	v_fma_f32 v146, v117, v84, v98
	v_fma_f32 v147, v117, v85, v99
	v_fma_f32 v116, v188, v70, v98
	v_fma_f32 v117, v188, v71, v99
	v_fma_f32 v114, v189, v68, v98
	v_fma_f32 v115, v189, v69, v99
	v_fma_f32 v68, v178, v157, v140
	v_fma_f32 v69, v178, v156, v140
	v_fma_f32 v70, v179, v154, v140
	v_fma_f32 v71, v179, v155, v140
	v_sub_f32 v79, v79, v99
	v_fma_f32 v120, v186, v78, v98
	v_fma_f32 v118, v187, v76, v98
	v_fma_f32 v119, v187, v77, v99
	v_fma_f32 v76, v180, v148, v140
	v_fma_f32 v77, v180, v152, v140
	v_fma_f32 v121, v186, v79, v99
	v_fma_f32 v78, v181, v146, v140
	v_fma_f32 v68, v182, v120, v68
	v_fma_f32 v79, v181, v147, v140
	v_fma_f32 v84, v182, v121, v69
	v_fma_f32 v69, v183, v118, v70
	v_fma_f32 v70, v183, v119, v71
	v_fma_f32 v71, v184, v116, v76
	v_fma_f32 v76, v184, v117, v77
	v_fma_f32 v77, v185, v114, v78
	v_fma_f32 v78, v185, v115, v79
	v_add_f32_e32 v68, v68, v69
	v_add_f32_e32 v69, v71, v77
	v_add_f32_e32 v70, v84, v70
	v_add_f32_e32 v71, v76, v78
	v_add_f32_e32 v68, v68, v69
	v_add_f32_e32 v70, v70, v71
	v_mov_b32_e32 v69, 0
	v_add_f32_dpp v68, v68, v68 row_ror:8 row_mask:0xf bank_mask:0xf bound_ctrl:1
	v_add_f32_dpp v70, v70, v70 row_ror:8 row_mask:0xf bank_mask:0xf bound_ctrl:1
	v_mov_b32_e32 v71, 0
	v_add_f32_dpp v68, v68, v68 row_ror:4 row_mask:0xf bank_mask:0xf bound_ctrl:1
	v_add_f32_dpp v70, v70, v70 row_ror:4 row_mask:0xf bank_mask:0xf bound_ctrl:1
	s_nop 0
	v_add_f32_dpp v68, v68, v68 row_ror:2 row_mask:0xf bank_mask:0xf bound_ctrl:1
	v_add_f32_dpp v70, v70, v70 row_ror:2 row_mask:0xf bank_mask:0xf bound_ctrl:1
	s_nop 0
	v_mov_b32_dpp v69, v68 row_ror:1 row_mask:0xf bank_mask:0xf
	v_mov_b32_dpp v71, v70 row_ror:1 row_mask:0xf bank_mask:0xf
	s_and_saveexec_b64 s[8:9], s[38:39]
	v_add_f32_e32 v70, v70, v71
	v_add_f32_e32 v68, v68, v69
	ds_write2_b32 v149, v68, v70 offset1:16
	s_or_b64 exec, exec, s[8:9]
	s_waitcnt lgkmcnt(0)
	v_sub_f32 v157, v157, v96
	v_sub_f32 v156, v156, v97
	v_sub_f32 v154, v154, v96
	v_sub_f32 v155, v155, v97
	v_sub_f32 v120, v120, v96
	v_sub_f32 v121, v121, v97
	v_sub_f32 v118, v118, v96
	v_sub_f32 v119, v119, v97
	v_sub_f32 v148, v148, v96
	v_sub_f32 v152, v152, v97
	v_sub_f32 v116, v116, v96
	v_sub_f32 v117, v117, v97
	v_fma_f32 v157, v88, v157, v96
	v_fma_f32 v156, v88, v156, v97
	v_fma_f32 v154, v89, v154, v96
	v_fma_f32 v155, v89, v155, v97
	v_fma_f32 v120, v80, v120, v96
	v_fma_f32 v121, v80, v121, v97
	v_fma_f32 v118, v81, v118, v96
	v_fma_f32 v119, v81, v119, v97
	v_fma_f32 v80, v72, v157, v140
	v_fma_f32 v72, v72, v156, v140
	v_fma_f32 v81, v73, v154, v140
	v_fma_f32 v73, v73, v155, v140
	ds_read_b128 v[76:79], v145 offset:19456
	ds_read_b128 v[68:71], v145 offset:19712
	ds_read_b128 v[92:95], v145 offset:27648
	ds_read_b128 v[84:87], v145 offset:27904
	ds_read2_b32 v[98:99], v153 offset0:64 offset1:80
	v_sub_f32 v146, v146, v96
	v_sub_f32 v147, v147, v97
	v_sub_f32 v114, v114, v96
	v_sub_f32 v115, v115, v97
	v_fma_f32 v148, v90, v148, v96
	v_fma_f32 v152, v90, v152, v97
	v_fma_f32 v116, v82, v116, v96
	v_fma_f32 v117, v82, v117, v97
	v_fma_f32 v80, v64, v120, v80
	v_fma_f32 v72, v64, v121, v72
	v_fma_f32 v82, v74, v148, v140
	v_fma_f32 v74, v74, v152, v140
	v_fma_f32 v64, v65, v118, v81
	v_fma_f32 v73, v65, v119, v73
	v_fma_f32 v146, v91, v146, v96
	v_fma_f32 v147, v91, v147, v97
	v_fma_f32 v65, v66, v116, v82
	v_fma_f32 v66, v66, v117, v74
	v_fma_f32 v114, v83, v114, v96
	v_fma_f32 v115, v83, v115, v97
	v_fma_f32 v83, v75, v146, v140
	v_fma_f32 v75, v75, v147, v140
	v_add_f32_e32 v64, v80, v64
	v_fma_f32 v74, v67, v114, v83
	v_fma_f32 v67, v67, v115, v75
	v_add_f32_e32 v72, v72, v73
	v_add_f32_e32 v65, v65, v74
	v_add_f32_e32 v66, v66, v67
	v_add_f32_e32 v64, v64, v65
	v_add_f32_e32 v66, v72, v66
	v_mov_b32_e32 v65, 0
	v_add_f32_dpp v64, v64, v64 row_ror:8 row_mask:0xf bank_mask:0xf bound_ctrl:1
	v_add_f32_dpp v66, v66, v66 row_ror:8 row_mask:0xf bank_mask:0xf bound_ctrl:1
	v_mov_b32_e32 v67, 0
	v_add_f32_dpp v64, v64, v64 row_ror:4 row_mask:0xf bank_mask:0xf bound_ctrl:1
	v_add_f32_dpp v66, v66, v66 row_ror:4 row_mask:0xf bank_mask:0xf bound_ctrl:1
	s_nop 0
	v_add_f32_dpp v64, v64, v64 row_ror:2 row_mask:0xf bank_mask:0xf bound_ctrl:1
	v_add_f32_dpp v66, v66, v66 row_ror:2 row_mask:0xf bank_mask:0xf bound_ctrl:1
	s_nop 0
	v_mov_b32_dpp v65, v64 row_ror:1 row_mask:0xf bank_mask:0xf
	v_mov_b32_dpp v67, v66 row_ror:1 row_mask:0xf bank_mask:0xf
	s_and_saveexec_b64 s[8:9], s[38:39]
	v_add_f32_e32 v66, v66, v67
	v_add_f32_e32 v64, v64, v65
	ds_write2_b32 v149, v64, v66 offset0:32 offset1:48
	s_or_b64 exec, exec, s[8:9]
	s_waitcnt lgkmcnt(0)
	v_sub_f32 v157, v157, v98
	v_sub_f32 v156, v156, v99
	v_sub_f32 v154, v154, v98
	v_sub_f32 v155, v155, v99
	v_sub_f32 v120, v120, v98
	v_sub_f32 v121, v121, v99
	v_sub_f32 v118, v118, v98
	v_sub_f32 v119, v119, v99
	v_sub_f32 v148, v148, v98
	v_sub_f32 v152, v152, v99
	v_sub_f32 v116, v116, v98
	v_sub_f32 v117, v117, v99
	v_fma_f32 v157, v92, v157, v98
	v_fma_f32 v156, v92, v156, v99
	v_fma_f32 v154, v93, v154, v98
	v_fma_f32 v155, v93, v155, v99
	v_fma_f32 v120, v84, v120, v98
	v_fma_f32 v121, v84, v121, v99
	v_fma_f32 v118, v85, v118, v98
	v_fma_f32 v119, v85, v119, v99
	v_fma_f32 v84, v76, v157, v140
	v_fma_f32 v76, v76, v156, v140
	v_fma_f32 v85, v77, v154, v140
	v_fma_f32 v77, v77, v155, v140
	ds_read_b128 v[72:75], v145 offset:19968
	ds_read_b128 v[64:67], v145 offset:20224
	ds_read_b128 v[88:91], v145 offset:28160
	ds_read_b128 v[80:83], v145 offset:28416
	ds_read2_b32 v[96:97], v153 offset0:96 offset1:112
	v_sub_f32 v146, v146, v98
	v_sub_f32 v147, v147, v99
	v_sub_f32 v114, v114, v98
	v_sub_f32 v115, v115, v99
	v_fma_f32 v148, v94, v148, v98
	v_fma_f32 v152, v94, v152, v99
	v_fma_f32 v116, v86, v116, v98
	v_fma_f32 v117, v86, v117, v99
	v_fma_f32 v84, v68, v120, v84
	v_fma_f32 v76, v68, v121, v76
	v_fma_f32 v86, v78, v148, v140
	v_fma_f32 v78, v78, v152, v140
	v_fma_f32 v68, v69, v118, v85
	v_fma_f32 v77, v69, v119, v77
	v_fma_f32 v146, v95, v146, v98
	v_fma_f32 v147, v95, v147, v99
	v_fma_f32 v69, v70, v116, v86
	v_fma_f32 v70, v70, v117, v78
	v_fma_f32 v114, v87, v114, v98
	v_fma_f32 v115, v87, v115, v99
	v_fma_f32 v87, v79, v146, v140
	v_fma_f32 v79, v79, v147, v140
	v_add_f32_e32 v68, v84, v68
	v_fma_f32 v78, v71, v114, v87
	v_fma_f32 v71, v71, v115, v79
	v_add_f32_e32 v76, v76, v77
	v_add_f32_e32 v69, v69, v78
	v_add_f32_e32 v70, v70, v71
	v_add_f32_e32 v68, v68, v69
	v_add_f32_e32 v70, v76, v70
	v_mov_b32_e32 v69, 0
	v_add_f32_dpp v68, v68, v68 row_ror:8 row_mask:0xf bank_mask:0xf bound_ctrl:1
	v_add_f32_dpp v70, v70, v70 row_ror:8 row_mask:0xf bank_mask:0xf bound_ctrl:1
	v_mov_b32_e32 v71, 0
	v_add_f32_dpp v68, v68, v68 row_ror:4 row_mask:0xf bank_mask:0xf bound_ctrl:1
	v_add_f32_dpp v70, v70, v70 row_ror:4 row_mask:0xf bank_mask:0xf bound_ctrl:1
	s_nop 0
	v_add_f32_dpp v68, v68, v68 row_ror:2 row_mask:0xf bank_mask:0xf bound_ctrl:1
	v_add_f32_dpp v70, v70, v70 row_ror:2 row_mask:0xf bank_mask:0xf bound_ctrl:1
	s_nop 0
	v_mov_b32_dpp v69, v68 row_ror:1 row_mask:0xf bank_mask:0xf
	v_mov_b32_dpp v71, v70 row_ror:1 row_mask:0xf bank_mask:0xf
	s_and_saveexec_b64 s[8:9], s[38:39]
	v_add_f32_e32 v70, v70, v71
	v_add_f32_e32 v68, v68, v69
	ds_write2_b32 v149, v68, v70 offset0:64 offset1:80
	s_or_b64 exec, exec, s[8:9]
	s_waitcnt lgkmcnt(0)
	v_sub_f32 v157, v157, v96
	v_sub_f32 v156, v156, v97
	v_sub_f32 v154, v154, v96
	v_sub_f32 v155, v155, v97
	v_sub_f32 v120, v120, v96
	v_sub_f32 v121, v121, v97
	v_sub_f32 v118, v118, v96
	v_sub_f32 v119, v119, v97
	v_sub_f32 v148, v148, v96
	v_sub_f32 v152, v152, v97
	v_sub_f32 v116, v116, v96
	v_sub_f32 v117, v117, v97
	v_fma_f32 v157, v88, v157, v96
	v_fma_f32 v156, v88, v156, v97
	v_fma_f32 v154, v89, v154, v96
	v_fma_f32 v155, v89, v155, v97
	v_fma_f32 v120, v80, v120, v96
	v_fma_f32 v121, v80, v121, v97
	v_fma_f32 v118, v81, v118, v96
	v_fma_f32 v119, v81, v119, v97
	v_fma_f32 v80, v72, v157, v140
	v_fma_f32 v72, v72, v156, v140
	v_fma_f32 v81, v73, v154, v140
	v_fma_f32 v73, v73, v155, v140
	ds_read_b128 v[76:79], v145 offset:20480
	ds_read_b128 v[68:71], v145 offset:20736
	ds_read_b128 v[92:95], v145 offset:28672
	ds_read_b128 v[84:87], v145 offset:28928
	ds_read2_b32 v[98:99], v153 offset0:128 offset1:144
	v_sub_f32 v146, v146, v96
	v_sub_f32 v147, v147, v97
	v_sub_f32 v114, v114, v96
	v_sub_f32 v115, v115, v97
	v_fma_f32 v148, v90, v148, v96
	v_fma_f32 v152, v90, v152, v97
	v_fma_f32 v116, v82, v116, v96
	v_fma_f32 v117, v82, v117, v97
	v_fma_f32 v80, v64, v120, v80
	v_fma_f32 v72, v64, v121, v72
	v_fma_f32 v82, v74, v148, v140
	v_fma_f32 v74, v74, v152, v140
	v_fma_f32 v64, v65, v118, v81
	v_fma_f32 v73, v65, v119, v73
	v_fma_f32 v146, v91, v146, v96
	v_fma_f32 v147, v91, v147, v97
	v_fma_f32 v65, v66, v116, v82
	v_fma_f32 v66, v66, v117, v74
	v_fma_f32 v114, v83, v114, v96
	v_fma_f32 v115, v83, v115, v97
	v_fma_f32 v83, v75, v146, v140
	v_fma_f32 v75, v75, v147, v140
	v_add_f32_e32 v64, v80, v64
	v_fma_f32 v74, v67, v114, v83
	v_fma_f32 v67, v67, v115, v75
	v_add_f32_e32 v72, v72, v73
	v_add_f32_e32 v65, v65, v74
	v_add_f32_e32 v66, v66, v67
	v_add_f32_e32 v64, v64, v65
	v_add_f32_e32 v66, v72, v66
	v_mov_b32_e32 v65, 0
	v_add_f32_dpp v64, v64, v64 row_ror:8 row_mask:0xf bank_mask:0xf bound_ctrl:1
	v_add_f32_dpp v66, v66, v66 row_ror:8 row_mask:0xf bank_mask:0xf bound_ctrl:1
	v_mov_b32_e32 v67, 0
	v_add_f32_dpp v64, v64, v64 row_ror:4 row_mask:0xf bank_mask:0xf bound_ctrl:1
	v_add_f32_dpp v66, v66, v66 row_ror:4 row_mask:0xf bank_mask:0xf bound_ctrl:1
	s_nop 0
	v_add_f32_dpp v64, v64, v64 row_ror:2 row_mask:0xf bank_mask:0xf bound_ctrl:1
	v_add_f32_dpp v66, v66, v66 row_ror:2 row_mask:0xf bank_mask:0xf bound_ctrl:1
	s_nop 0
	v_mov_b32_dpp v65, v64 row_ror:1 row_mask:0xf bank_mask:0xf
	v_mov_b32_dpp v67, v66 row_ror:1 row_mask:0xf bank_mask:0xf
	s_and_saveexec_b64 s[8:9], s[38:39]
	v_add_f32_e32 v66, v66, v67
	v_add_f32_e32 v64, v64, v65
	ds_write2_b32 v149, v64, v66 offset0:96 offset1:112
	s_or_b64 exec, exec, s[8:9]
	s_waitcnt lgkmcnt(0)
	v_sub_f32 v157, v157, v98
	v_sub_f32 v156, v156, v99
	v_sub_f32 v154, v154, v98
	v_sub_f32 v155, v155, v99
	v_sub_f32 v120, v120, v98
	v_sub_f32 v121, v121, v99
	v_sub_f32 v118, v118, v98
	v_sub_f32 v119, v119, v99
	v_sub_f32 v148, v148, v98
	v_sub_f32 v152, v152, v99
	v_sub_f32 v116, v116, v98
	v_sub_f32 v117, v117, v99
	v_fma_f32 v157, v92, v157, v98
	v_fma_f32 v156, v92, v156, v99
	v_fma_f32 v154, v93, v154, v98
	v_fma_f32 v155, v93, v155, v99
	v_fma_f32 v120, v84, v120, v98
	v_fma_f32 v121, v84, v121, v99
	v_fma_f32 v118, v85, v118, v98
	v_fma_f32 v119, v85, v119, v99
	v_fma_f32 v84, v76, v157, v140
	v_fma_f32 v76, v76, v156, v140
	v_fma_f32 v85, v77, v154, v140
	v_fma_f32 v77, v77, v155, v140
	ds_read_b128 v[72:75], v145 offset:20992
	ds_read_b128 v[64:67], v145 offset:21248
	ds_read_b128 v[88:91], v145 offset:29184
	ds_read_b128 v[80:83], v145 offset:29440
	ds_read2_b32 v[96:97], v153 offset0:160 offset1:176
	v_sub_f32 v146, v146, v98
	v_sub_f32 v147, v147, v99
	v_sub_f32 v114, v114, v98
	v_sub_f32 v115, v115, v99
	v_fma_f32 v148, v94, v148, v98
	v_fma_f32 v152, v94, v152, v99
	v_fma_f32 v116, v86, v116, v98
	v_fma_f32 v117, v86, v117, v99
	v_fma_f32 v84, v68, v120, v84
	v_fma_f32 v76, v68, v121, v76
	v_fma_f32 v86, v78, v148, v140
	v_fma_f32 v78, v78, v152, v140
	v_fma_f32 v68, v69, v118, v85
	v_fma_f32 v77, v69, v119, v77
	v_fma_f32 v146, v95, v146, v98
	v_fma_f32 v147, v95, v147, v99
	v_fma_f32 v69, v70, v116, v86
	v_fma_f32 v70, v70, v117, v78
	v_fma_f32 v114, v87, v114, v98
	v_fma_f32 v115, v87, v115, v99
	v_fma_f32 v87, v79, v146, v140
	v_fma_f32 v79, v79, v147, v140
	v_add_f32_e32 v68, v84, v68
	v_fma_f32 v78, v71, v114, v87
	v_fma_f32 v71, v71, v115, v79
	v_add_f32_e32 v76, v76, v77
	v_add_f32_e32 v69, v69, v78
	v_add_f32_e32 v70, v70, v71
	v_add_f32_e32 v68, v68, v69
	v_add_f32_e32 v70, v76, v70
	v_mov_b32_e32 v69, 0
	v_add_f32_dpp v68, v68, v68 row_ror:8 row_mask:0xf bank_mask:0xf bound_ctrl:1
	v_add_f32_dpp v70, v70, v70 row_ror:8 row_mask:0xf bank_mask:0xf bound_ctrl:1
	v_mov_b32_e32 v71, 0
	v_add_f32_dpp v68, v68, v68 row_ror:4 row_mask:0xf bank_mask:0xf bound_ctrl:1
	v_add_f32_dpp v70, v70, v70 row_ror:4 row_mask:0xf bank_mask:0xf bound_ctrl:1
	s_nop 0
	v_add_f32_dpp v68, v68, v68 row_ror:2 row_mask:0xf bank_mask:0xf bound_ctrl:1
	v_add_f32_dpp v70, v70, v70 row_ror:2 row_mask:0xf bank_mask:0xf bound_ctrl:1
	s_nop 0
	v_mov_b32_dpp v69, v68 row_ror:1 row_mask:0xf bank_mask:0xf
	v_mov_b32_dpp v71, v70 row_ror:1 row_mask:0xf bank_mask:0xf
	s_and_saveexec_b64 s[8:9], s[38:39]
	v_add_f32_e32 v70, v70, v71
	v_add_f32_e32 v68, v68, v69
	ds_write2_b32 v149, v68, v70 offset0:128 offset1:144
	s_or_b64 exec, exec, s[8:9]
	s_waitcnt lgkmcnt(0)
	v_sub_f32 v157, v157, v96
	v_sub_f32 v156, v156, v97
	v_sub_f32 v154, v154, v96
	v_sub_f32 v155, v155, v97
	v_sub_f32 v120, v120, v96
	v_sub_f32 v121, v121, v97
	v_sub_f32 v118, v118, v96
	v_sub_f32 v119, v119, v97
	v_sub_f32 v148, v148, v96
	v_sub_f32 v152, v152, v97
	v_sub_f32 v116, v116, v96
	v_sub_f32 v117, v117, v97
	v_fma_f32 v157, v88, v157, v96
	v_fma_f32 v156, v88, v156, v97
	v_fma_f32 v154, v89, v154, v96
	v_fma_f32 v155, v89, v155, v97
	v_fma_f32 v120, v80, v120, v96
	v_fma_f32 v121, v80, v121, v97
	v_fma_f32 v118, v81, v118, v96
	v_fma_f32 v119, v81, v119, v97
	v_fma_f32 v80, v72, v157, v140
	v_fma_f32 v72, v72, v156, v140
	v_fma_f32 v81, v73, v154, v140
	v_fma_f32 v73, v73, v155, v140
	ds_read_b128 v[76:79], v145 offset:21504
	ds_read_b128 v[68:71], v145 offset:21760
	ds_read_b128 v[92:95], v145 offset:29696
	ds_read_b128 v[84:87], v145 offset:29952
	ds_read2_b32 v[98:99], v153 offset0:192 offset1:208
	v_sub_f32 v146, v146, v96
	v_sub_f32 v147, v147, v97
	v_sub_f32 v114, v114, v96
	v_sub_f32 v115, v115, v97
	v_fma_f32 v148, v90, v148, v96
	v_fma_f32 v152, v90, v152, v97
	v_fma_f32 v116, v82, v116, v96
	v_fma_f32 v117, v82, v117, v97
	v_fma_f32 v80, v64, v120, v80
	v_fma_f32 v72, v64, v121, v72
	v_fma_f32 v82, v74, v148, v140
	v_fma_f32 v74, v74, v152, v140
	v_fma_f32 v64, v65, v118, v81
	v_fma_f32 v73, v65, v119, v73
	v_fma_f32 v146, v91, v146, v96
	v_fma_f32 v147, v91, v147, v97
	v_fma_f32 v65, v66, v116, v82
	v_fma_f32 v66, v66, v117, v74
	v_fma_f32 v114, v83, v114, v96
	v_fma_f32 v115, v83, v115, v97
	v_fma_f32 v83, v75, v146, v140
	v_fma_f32 v75, v75, v147, v140
	v_add_f32_e32 v64, v80, v64
	v_fma_f32 v74, v67, v114, v83
	v_fma_f32 v67, v67, v115, v75
	v_add_f32_e32 v72, v72, v73
	v_add_f32_e32 v65, v65, v74
	v_add_f32_e32 v66, v66, v67
	v_add_f32_e32 v64, v64, v65
	v_add_f32_e32 v66, v72, v66
	v_mov_b32_e32 v65, 0
	v_add_f32_dpp v64, v64, v64 row_ror:8 row_mask:0xf bank_mask:0xf bound_ctrl:1
	v_add_f32_dpp v66, v66, v66 row_ror:8 row_mask:0xf bank_mask:0xf bound_ctrl:1
	v_mov_b32_e32 v67, 0
	v_add_f32_dpp v64, v64, v64 row_ror:4 row_mask:0xf bank_mask:0xf bound_ctrl:1
	v_add_f32_dpp v66, v66, v66 row_ror:4 row_mask:0xf bank_mask:0xf bound_ctrl:1
	s_nop 0
	v_add_f32_dpp v64, v64, v64 row_ror:2 row_mask:0xf bank_mask:0xf bound_ctrl:1
	v_add_f32_dpp v66, v66, v66 row_ror:2 row_mask:0xf bank_mask:0xf bound_ctrl:1
	s_nop 0
	v_mov_b32_dpp v65, v64 row_ror:1 row_mask:0xf bank_mask:0xf
	v_mov_b32_dpp v67, v66 row_ror:1 row_mask:0xf bank_mask:0xf
	s_and_saveexec_b64 s[8:9], s[38:39]
	v_add_f32_e32 v66, v66, v67
	v_add_f32_e32 v64, v64, v65
	ds_write2_b32 v149, v64, v66 offset0:160 offset1:176
	s_or_b64 exec, exec, s[8:9]
	ds_read_b128 v[72:75], v145 offset:22016
	ds_read_b128 v[64:67], v145 offset:22272
	ds_read_b128 v[88:91], v145 offset:30208
	ds_read_b128 v[80:83], v145 offset:30464
	ds_read2_b32 v[96:97], v153 offset0:224 offset1:240
	s_waitcnt lgkmcnt(5)
	v_sub_f32 v153, v157, v98
	v_sub_f32 v154, v154, v98
	v_sub_f32 v120, v120, v98
	v_sub_f32 v121, v121, v99
	v_sub_f32 v118, v118, v98
	v_sub_f32 v119, v119, v99
	v_sub_f32 v157, v156, v99
	v_sub_f32 v178, v155, v99
	v_sub_f32 v148, v148, v98
	v_sub_f32 v152, v152, v99
	v_sub_f32 v116, v116, v98
	v_sub_f32 v117, v117, v99
	v_fma_f32 v156, v92, v153, v98
	v_fma_f32 v155, v92, v157, v99
	v_fma_f32 v153, v93, v154, v98
	v_fma_f32 v154, v93, v178, v99
	v_fma_f32 v120, v84, v120, v98
	v_fma_f32 v121, v84, v121, v99
	v_fma_f32 v118, v85, v118, v98
	v_fma_f32 v119, v85, v119, v99
	v_fma_f32 v84, v76, v156, v140
	v_fma_f32 v76, v76, v155, v140
	v_fma_f32 v85, v77, v153, v140
	v_fma_f32 v77, v77, v154, v140
	v_sub_f32 v146, v146, v98
	v_sub_f32 v147, v147, v99
	v_sub_f32 v114, v114, v98
	v_sub_f32 v115, v115, v99
	v_fma_f32 v148, v94, v148, v98
	v_fma_f32 v152, v94, v152, v99
	v_fma_f32 v116, v86, v116, v98
	v_fma_f32 v117, v86, v117, v99
	v_fma_f32 v84, v68, v120, v84
	v_fma_f32 v76, v68, v121, v76
	v_fma_f32 v86, v78, v148, v140
	v_fma_f32 v78, v78, v152, v140
	v_fma_f32 v68, v69, v118, v85
	v_fma_f32 v77, v69, v119, v77
	v_fma_f32 v146, v95, v146, v98
	v_fma_f32 v147, v95, v147, v99
	v_fma_f32 v69, v70, v116, v86
	v_fma_f32 v70, v70, v117, v78
	v_fma_f32 v114, v87, v114, v98
	v_fma_f32 v115, v87, v115, v99
	v_fma_f32 v87, v79, v146, v140
	v_fma_f32 v79, v79, v147, v140
	v_add_f32_e32 v68, v84, v68
	v_fma_f32 v78, v71, v114, v87
	v_fma_f32 v71, v71, v115, v79
	v_add_f32_e32 v76, v76, v77
	v_add_f32_e32 v69, v69, v78
	v_add_f32_e32 v70, v70, v71
	v_add_f32_e32 v68, v68, v69
	v_add_f32_e32 v70, v76, v70
	v_mov_b32_e32 v69, 0
	v_add_f32_dpp v68, v68, v68 row_ror:8 row_mask:0xf bank_mask:0xf bound_ctrl:1
	v_add_f32_dpp v70, v70, v70 row_ror:8 row_mask:0xf bank_mask:0xf bound_ctrl:1
	v_mov_b32_e32 v71, 0
	v_add_f32_dpp v68, v68, v68 row_ror:4 row_mask:0xf bank_mask:0xf bound_ctrl:1
	v_add_f32_dpp v70, v70, v70 row_ror:4 row_mask:0xf bank_mask:0xf bound_ctrl:1
	s_nop 0
	v_add_f32_dpp v68, v68, v68 row_ror:2 row_mask:0xf bank_mask:0xf bound_ctrl:1
	v_add_f32_dpp v70, v70, v70 row_ror:2 row_mask:0xf bank_mask:0xf bound_ctrl:1
	s_nop 0
	v_mov_b32_dpp v69, v68 row_ror:1 row_mask:0xf bank_mask:0xf
	v_mov_b32_dpp v71, v70 row_ror:1 row_mask:0xf bank_mask:0xf
	s_and_saveexec_b64 s[8:9], s[38:39]
	v_add_f32_e32 v70, v70, v71
	v_add_f32_e32 v68, v68, v69
	ds_write2_b32 v149, v68, v70 offset0:192 offset1:208
	s_or_b64 exec, exec, s[8:9]
	s_waitcnt lgkmcnt(0)
	v_sub_f32 v156, v156, v96
	v_sub_f32 v155, v155, v97
	v_sub_f32 v153, v153, v96
	v_sub_f32 v154, v154, v97
	v_sub_f32 v120, v120, v96
	v_sub_f32 v121, v121, v97
	v_sub_f32 v118, v118, v96
	v_sub_f32 v119, v119, v97
	v_sub_f32 v148, v148, v96
	v_sub_f32 v152, v152, v97
	v_sub_f32 v116, v116, v96
	v_sub_f32 v117, v117, v97
	v_fma_f32 v156, v88, v156, v96
	v_fma_f32 v155, v88, v155, v97
	v_fma_f32 v153, v89, v153, v96
	v_fma_f32 v154, v89, v154, v97
	v_fma_f32 v120, v80, v120, v96
	v_fma_f32 v121, v80, v121, v97
	v_fma_f32 v118, v81, v118, v96
	v_fma_f32 v119, v81, v119, v97
	v_fma_f32 v80, v72, v156, v140
	v_fma_f32 v72, v72, v155, v140
	v_fma_f32 v81, v73, v153, v140
	v_fma_f32 v73, v73, v154, v140
	ds_read_b128 v[76:79], v145 offset:22528
	ds_read_b128 v[68:71], v145 offset:22784
	ds_read_b128 v[92:95], v145 offset:30720
	ds_read_b128 v[84:87], v145 offset:30976
	ds_read2_b32 v[98:99], v151 offset1:16
	v_sub_f32 v146, v146, v96
	v_sub_f32 v147, v147, v97
	v_sub_f32 v114, v114, v96
	v_sub_f32 v115, v115, v97
	v_fma_f32 v148, v90, v148, v96
	v_fma_f32 v152, v90, v152, v97
	v_fma_f32 v116, v82, v116, v96
	v_fma_f32 v117, v82, v117, v97
	v_fma_f32 v80, v64, v120, v80
	v_fma_f32 v72, v64, v121, v72
	v_fma_f32 v82, v74, v148, v140
	v_fma_f32 v74, v74, v152, v140
	v_fma_f32 v64, v65, v118, v81
	v_fma_f32 v73, v65, v119, v73
	v_fma_f32 v146, v91, v146, v96
	v_fma_f32 v147, v91, v147, v97
	v_fma_f32 v65, v66, v116, v82
	v_fma_f32 v66, v66, v117, v74
	v_fma_f32 v114, v83, v114, v96
	v_fma_f32 v115, v83, v115, v97
	v_fma_f32 v83, v75, v146, v140
	v_fma_f32 v75, v75, v147, v140
	v_add_f32_e32 v64, v80, v64
	v_fma_f32 v74, v67, v114, v83
	v_fma_f32 v67, v67, v115, v75
	v_add_f32_e32 v72, v72, v73
	v_add_f32_e32 v65, v65, v74
	v_add_f32_e32 v66, v66, v67
	v_add_f32_e32 v64, v64, v65
	v_add_f32_e32 v66, v72, v66
	v_mov_b32_e32 v65, 0
	v_add_f32_dpp v64, v64, v64 row_ror:8 row_mask:0xf bank_mask:0xf bound_ctrl:1
	v_add_f32_dpp v66, v66, v66 row_ror:8 row_mask:0xf bank_mask:0xf bound_ctrl:1
	v_mov_b32_e32 v67, 0
	v_add_f32_dpp v64, v64, v64 row_ror:4 row_mask:0xf bank_mask:0xf bound_ctrl:1
	v_add_f32_dpp v66, v66, v66 row_ror:4 row_mask:0xf bank_mask:0xf bound_ctrl:1
	s_nop 0
	v_add_f32_dpp v64, v64, v64 row_ror:2 row_mask:0xf bank_mask:0xf bound_ctrl:1
	v_add_f32_dpp v66, v66, v66 row_ror:2 row_mask:0xf bank_mask:0xf bound_ctrl:1
	s_nop 0
	v_mov_b32_dpp v65, v64 row_ror:1 row_mask:0xf bank_mask:0xf
	v_mov_b32_dpp v67, v66 row_ror:1 row_mask:0xf bank_mask:0xf
	s_and_saveexec_b64 s[8:9], s[38:39]
	v_add_f32_e32 v66, v66, v67
	v_add_f32_e32 v64, v64, v65
	ds_write2_b32 v149, v64, v66 offset0:224 offset1:240
	s_or_b64 exec, exec, s[8:9]
	s_waitcnt lgkmcnt(0)
	v_sub_f32 v153, v153, v98
	v_sub_f32 v120, v120, v98
	v_sub_f32 v121, v121, v99
	v_sub_f32 v118, v118, v98
	v_sub_f32 v119, v119, v99
	v_sub_f32 v149, v156, v98
	v_sub_f32 v156, v155, v99
	v_sub_f32 v157, v154, v99
	v_sub_f32 v148, v148, v98
	v_sub_f32 v178, v152, v99
	v_sub_f32 v116, v116, v98
	v_sub_f32 v117, v117, v99
	v_fma_f32 v155, v92, v149, v98
	v_fma_f32 v154, v92, v156, v99
	v_fma_f32 v152, v93, v153, v98
	v_fma_f32 v153, v93, v157, v99
	v_fma_f32 v120, v84, v120, v98
	v_fma_f32 v121, v84, v121, v99
	v_fma_f32 v118, v85, v118, v98
	v_fma_f32 v119, v85, v119, v99
	v_fma_f32 v84, v76, v155, v140
	v_fma_f32 v76, v76, v154, v140
	v_fma_f32 v85, v77, v152, v140
	v_fma_f32 v77, v77, v153, v140
	ds_read_b128 v[72:75], v145 offset:23040
	ds_read_b128 v[64:67], v145 offset:23296
	ds_read_b128 v[88:91], v145 offset:31232
	ds_read_b128 v[80:83], v145 offset:31488
	ds_read2_b32 v[96:97], v151 offset0:32 offset1:48
	v_sub_f32 v146, v146, v98
	v_sub_f32 v147, v147, v99
	v_sub_f32 v114, v114, v98
	v_sub_f32 v115, v115, v99
	v_fma_f32 v148, v94, v148, v98
	v_fma_f32 v149, v94, v178, v99
	v_fma_f32 v116, v86, v116, v98
	v_fma_f32 v117, v86, v117, v99
	v_fma_f32 v84, v68, v120, v84
	v_fma_f32 v76, v68, v121, v76
	v_fma_f32 v86, v78, v148, v140
	v_fma_f32 v78, v78, v149, v140
	v_fma_f32 v68, v69, v118, v85
	v_fma_f32 v77, v69, v119, v77
	v_fma_f32 v146, v95, v146, v98
	v_fma_f32 v147, v95, v147, v99
	v_fma_f32 v69, v70, v116, v86
	v_fma_f32 v70, v70, v117, v78
	v_fma_f32 v114, v87, v114, v98
	v_fma_f32 v115, v87, v115, v99
	v_fma_f32 v87, v79, v146, v140
	v_fma_f32 v79, v79, v147, v140
	v_add_f32_e32 v68, v84, v68
	v_fma_f32 v78, v71, v114, v87
	v_fma_f32 v71, v71, v115, v79
	v_add_f32_e32 v76, v76, v77
	v_add_f32_e32 v69, v69, v78
	v_add_f32_e32 v70, v70, v71
	v_add_f32_e32 v68, v68, v69
	v_add_f32_e32 v70, v76, v70
	v_mov_b32_e32 v69, 0
	v_add_f32_dpp v68, v68, v68 row_ror:8 row_mask:0xf bank_mask:0xf bound_ctrl:1
	v_add_f32_dpp v70, v70, v70 row_ror:8 row_mask:0xf bank_mask:0xf bound_ctrl:1
	v_mov_b32_e32 v71, 0
	v_add_f32_dpp v68, v68, v68 row_ror:4 row_mask:0xf bank_mask:0xf bound_ctrl:1
	v_add_f32_dpp v70, v70, v70 row_ror:4 row_mask:0xf bank_mask:0xf bound_ctrl:1
	s_nop 0
	v_add_f32_dpp v68, v68, v68 row_ror:2 row_mask:0xf bank_mask:0xf bound_ctrl:1
	v_add_f32_dpp v70, v70, v70 row_ror:2 row_mask:0xf bank_mask:0xf bound_ctrl:1
	s_nop 0
	v_mov_b32_dpp v69, v68 row_ror:1 row_mask:0xf bank_mask:0xf
	v_mov_b32_dpp v71, v70 row_ror:1 row_mask:0xf bank_mask:0xf
	s_and_saveexec_b64 s[8:9], s[38:39]
	v_add_f32_e32 v70, v70, v71
	v_add_f32_e32 v68, v68, v69
	ds_write2_b32 v150, v68, v70 offset1:16
	s_or_b64 exec, exec, s[8:9]
	s_waitcnt lgkmcnt(0)
	v_sub_f32 v155, v155, v96
	v_sub_f32 v154, v154, v97
	v_sub_f32 v152, v152, v96
	v_sub_f32 v153, v153, v97
	v_sub_f32 v120, v120, v96
	v_sub_f32 v121, v121, v97
	v_sub_f32 v118, v118, v96
	v_sub_f32 v119, v119, v97
	v_sub_f32 v148, v148, v96
	v_sub_f32 v149, v149, v97
	v_sub_f32 v116, v116, v96
	v_sub_f32 v117, v117, v97
	v_fma_f32 v155, v88, v155, v96
	v_fma_f32 v154, v88, v154, v97
	v_fma_f32 v152, v89, v152, v96
	v_fma_f32 v153, v89, v153, v97
	v_fma_f32 v120, v80, v120, v96
	v_fma_f32 v121, v80, v121, v97
	v_fma_f32 v118, v81, v118, v96
	v_fma_f32 v119, v81, v119, v97
	v_fma_f32 v80, v72, v155, v140
	v_fma_f32 v72, v72, v154, v140
	v_fma_f32 v81, v73, v152, v140
	v_fma_f32 v73, v73, v153, v140
	ds_read_b128 v[76:79], v145 offset:23552
	ds_read_b128 v[68:71], v145 offset:23808
	ds_read_b128 v[92:95], v145 offset:31744
	ds_read_b128 v[84:87], v145 offset:32000
	ds_read2_b32 v[98:99], v151 offset0:64 offset1:80
	v_sub_f32 v146, v146, v96
	v_sub_f32 v147, v147, v97
	v_sub_f32 v114, v114, v96
	v_sub_f32 v115, v115, v97
	v_fma_f32 v148, v90, v148, v96
	v_fma_f32 v149, v90, v149, v97
	v_fma_f32 v116, v82, v116, v96
	v_fma_f32 v117, v82, v117, v97
	v_fma_f32 v80, v64, v120, v80
	v_fma_f32 v72, v64, v121, v72
	v_fma_f32 v82, v74, v148, v140
	v_fma_f32 v74, v74, v149, v140
	v_fma_f32 v64, v65, v118, v81
	v_fma_f32 v73, v65, v119, v73
	v_fma_f32 v146, v91, v146, v96
	v_fma_f32 v147, v91, v147, v97
	v_fma_f32 v65, v66, v116, v82
	v_fma_f32 v66, v66, v117, v74
	v_fma_f32 v114, v83, v114, v96
	v_fma_f32 v115, v83, v115, v97
	v_fma_f32 v83, v75, v146, v140
	v_fma_f32 v75, v75, v147, v140
	v_add_f32_e32 v64, v80, v64
	v_fma_f32 v74, v67, v114, v83
	v_fma_f32 v67, v67, v115, v75
	v_add_f32_e32 v72, v72, v73
	v_add_f32_e32 v65, v65, v74
	v_add_f32_e32 v66, v66, v67
	v_add_f32_e32 v64, v64, v65
	v_add_f32_e32 v66, v72, v66
	v_mov_b32_e32 v65, 0
	v_add_f32_dpp v64, v64, v64 row_ror:8 row_mask:0xf bank_mask:0xf bound_ctrl:1
	v_add_f32_dpp v66, v66, v66 row_ror:8 row_mask:0xf bank_mask:0xf bound_ctrl:1
	v_mov_b32_e32 v67, 0
	v_add_f32_dpp v64, v64, v64 row_ror:4 row_mask:0xf bank_mask:0xf bound_ctrl:1
	v_add_f32_dpp v66, v66, v66 row_ror:4 row_mask:0xf bank_mask:0xf bound_ctrl:1
	s_nop 0
	v_add_f32_dpp v64, v64, v64 row_ror:2 row_mask:0xf bank_mask:0xf bound_ctrl:1
	v_add_f32_dpp v66, v66, v66 row_ror:2 row_mask:0xf bank_mask:0xf bound_ctrl:1
	s_nop 0
	v_mov_b32_dpp v65, v64 row_ror:1 row_mask:0xf bank_mask:0xf
	v_mov_b32_dpp v67, v66 row_ror:1 row_mask:0xf bank_mask:0xf
	s_and_saveexec_b64 s[8:9], s[38:39]
	v_add_f32_e32 v66, v66, v67
	v_add_f32_e32 v64, v64, v65
	ds_write2_b32 v150, v64, v66 offset0:32 offset1:48
	s_or_b64 exec, exec, s[8:9]
	s_waitcnt lgkmcnt(0)
	v_sub_f32 v155, v155, v98
	v_sub_f32 v154, v154, v99
	v_sub_f32 v152, v152, v98
	v_sub_f32 v153, v153, v99
	v_sub_f32 v120, v120, v98
	v_sub_f32 v121, v121, v99
	v_sub_f32 v118, v118, v98
	v_sub_f32 v119, v119, v99
	v_sub_f32 v148, v148, v98
	v_sub_f32 v149, v149, v99
	v_sub_f32 v116, v116, v98
	v_sub_f32 v117, v117, v99
	v_fma_f32 v155, v92, v155, v98
	v_fma_f32 v154, v92, v154, v99
	v_fma_f32 v152, v93, v152, v98
	v_fma_f32 v153, v93, v153, v99
	v_fma_f32 v120, v84, v120, v98
	v_fma_f32 v121, v84, v121, v99
	v_fma_f32 v118, v85, v118, v98
	v_fma_f32 v119, v85, v119, v99
	v_fma_f32 v84, v76, v155, v140
	v_fma_f32 v76, v76, v154, v140
	v_fma_f32 v85, v77, v152, v140
	v_fma_f32 v77, v77, v153, v140
	ds_read_b128 v[72:75], v145 offset:24064
	ds_read_b128 v[64:67], v145 offset:24320
	ds_read_b128 v[88:91], v145 offset:32256
	ds_read_b128 v[80:83], v145 offset:32512
	ds_read2_b32 v[96:97], v151 offset0:96 offset1:112
	v_sub_f32 v146, v146, v98
	v_sub_f32 v147, v147, v99
	v_sub_f32 v114, v114, v98
	v_sub_f32 v115, v115, v99
	v_fma_f32 v148, v94, v148, v98
	v_fma_f32 v149, v94, v149, v99
	v_fma_f32 v116, v86, v116, v98
	v_fma_f32 v117, v86, v117, v99
	v_fma_f32 v84, v68, v120, v84
	v_fma_f32 v76, v68, v121, v76
	v_fma_f32 v86, v78, v148, v140
	v_fma_f32 v78, v78, v149, v140
	v_fma_f32 v68, v69, v118, v85
	v_fma_f32 v77, v69, v119, v77
	v_fma_f32 v146, v95, v146, v98
	v_fma_f32 v147, v95, v147, v99
	v_fma_f32 v69, v70, v116, v86
	v_fma_f32 v70, v70, v117, v78
	v_fma_f32 v114, v87, v114, v98
	v_fma_f32 v115, v87, v115, v99
	v_fma_f32 v87, v79, v146, v140
	v_fma_f32 v79, v79, v147, v140
	v_add_f32_e32 v68, v84, v68
	v_fma_f32 v78, v71, v114, v87
	v_fma_f32 v71, v71, v115, v79
	v_add_f32_e32 v76, v76, v77
	v_add_f32_e32 v69, v69, v78
	v_add_f32_e32 v70, v70, v71
	v_add_f32_e32 v68, v68, v69
	v_add_f32_e32 v70, v76, v70
	v_mov_b32_e32 v69, 0
	v_add_f32_dpp v68, v68, v68 row_ror:8 row_mask:0xf bank_mask:0xf bound_ctrl:1
	v_add_f32_dpp v70, v70, v70 row_ror:8 row_mask:0xf bank_mask:0xf bound_ctrl:1
	v_mov_b32_e32 v71, 0
	v_add_f32_dpp v68, v68, v68 row_ror:4 row_mask:0xf bank_mask:0xf bound_ctrl:1
	v_add_f32_dpp v70, v70, v70 row_ror:4 row_mask:0xf bank_mask:0xf bound_ctrl:1
	s_nop 0
	v_add_f32_dpp v68, v68, v68 row_ror:2 row_mask:0xf bank_mask:0xf bound_ctrl:1
	v_add_f32_dpp v70, v70, v70 row_ror:2 row_mask:0xf bank_mask:0xf bound_ctrl:1
	s_nop 0
	v_mov_b32_dpp v69, v68 row_ror:1 row_mask:0xf bank_mask:0xf
	v_mov_b32_dpp v71, v70 row_ror:1 row_mask:0xf bank_mask:0xf
	s_and_saveexec_b64 s[8:9], s[38:39]
	v_add_f32_e32 v70, v70, v71
	v_add_f32_e32 v68, v68, v69
	ds_write2_b32 v150, v68, v70 offset0:64 offset1:80
	s_or_b64 exec, exec, s[8:9]
	s_waitcnt lgkmcnt(0)
	v_sub_f32 v155, v155, v96
	v_sub_f32 v154, v154, v97
	v_sub_f32 v152, v152, v96
	v_sub_f32 v153, v153, v97
	v_sub_f32 v120, v120, v96
	v_sub_f32 v121, v121, v97
	v_sub_f32 v118, v118, v96
	v_sub_f32 v119, v119, v97
	v_sub_f32 v148, v148, v96
	v_sub_f32 v149, v149, v97
	v_sub_f32 v116, v116, v96
	v_sub_f32 v117, v117, v97
	v_fma_f32 v155, v88, v155, v96
	v_fma_f32 v154, v88, v154, v97
	v_fma_f32 v152, v89, v152, v96
	v_fma_f32 v153, v89, v153, v97
	v_fma_f32 v120, v80, v120, v96
	v_fma_f32 v121, v80, v121, v97
	v_fma_f32 v118, v81, v118, v96
	v_fma_f32 v119, v81, v119, v97
	v_fma_f32 v80, v72, v155, v140
	v_fma_f32 v72, v72, v154, v140
	v_fma_f32 v81, v73, v152, v140
	v_fma_f32 v73, v73, v153, v140
	ds_read_b128 v[76:79], v145 offset:24576
	ds_read_b128 v[68:71], v145 offset:24832
	ds_read_b128 v[92:95], v145 offset:32768
	ds_read_b128 v[84:87], v145 offset:33024
	ds_read2_b32 v[98:99], v151 offset0:128 offset1:144
	v_sub_f32 v146, v146, v96
	v_sub_f32 v147, v147, v97
	v_sub_f32 v114, v114, v96
	v_sub_f32 v115, v115, v97
	v_fma_f32 v148, v90, v148, v96
	v_fma_f32 v149, v90, v149, v97
	v_fma_f32 v116, v82, v116, v96
	v_fma_f32 v117, v82, v117, v97
	v_fma_f32 v80, v64, v120, v80
	v_fma_f32 v72, v64, v121, v72
	v_fma_f32 v82, v74, v148, v140
	v_fma_f32 v74, v74, v149, v140
	v_fma_f32 v64, v65, v118, v81
	v_fma_f32 v73, v65, v119, v73
	v_fma_f32 v146, v91, v146, v96
	v_fma_f32 v147, v91, v147, v97
	v_fma_f32 v65, v66, v116, v82
	v_fma_f32 v66, v66, v117, v74
	v_fma_f32 v114, v83, v114, v96
	v_fma_f32 v115, v83, v115, v97
	v_fma_f32 v83, v75, v146, v140
	v_fma_f32 v75, v75, v147, v140
	v_add_f32_e32 v64, v80, v64
	v_fma_f32 v74, v67, v114, v83
	v_fma_f32 v67, v67, v115, v75
	v_add_f32_e32 v72, v72, v73
	v_add_f32_e32 v65, v65, v74
	v_add_f32_e32 v66, v66, v67
	v_add_f32_e32 v64, v64, v65
	v_add_f32_e32 v66, v72, v66
	v_mov_b32_e32 v65, 0
	v_add_f32_dpp v64, v64, v64 row_ror:8 row_mask:0xf bank_mask:0xf bound_ctrl:1
	v_add_f32_dpp v66, v66, v66 row_ror:8 row_mask:0xf bank_mask:0xf bound_ctrl:1
	v_mov_b32_e32 v67, 0
	v_add_f32_dpp v64, v64, v64 row_ror:4 row_mask:0xf bank_mask:0xf bound_ctrl:1
	v_add_f32_dpp v66, v66, v66 row_ror:4 row_mask:0xf bank_mask:0xf bound_ctrl:1
	s_nop 0
	v_add_f32_dpp v64, v64, v64 row_ror:2 row_mask:0xf bank_mask:0xf bound_ctrl:1
	v_add_f32_dpp v66, v66, v66 row_ror:2 row_mask:0xf bank_mask:0xf bound_ctrl:1
	s_nop 0
	v_mov_b32_dpp v65, v64 row_ror:1 row_mask:0xf bank_mask:0xf
	v_mov_b32_dpp v67, v66 row_ror:1 row_mask:0xf bank_mask:0xf
	s_and_saveexec_b64 s[8:9], s[38:39]
	v_add_f32_e32 v66, v66, v67
	v_add_f32_e32 v64, v64, v65
	ds_write2_b32 v150, v64, v66 offset0:96 offset1:112
	s_or_b64 exec, exec, s[8:9]
	s_waitcnt lgkmcnt(0)
	v_sub_f32 v155, v155, v98
	v_sub_f32 v154, v154, v99
	v_sub_f32 v152, v152, v98
	v_sub_f32 v153, v153, v99
	v_sub_f32 v120, v120, v98
	v_sub_f32 v121, v121, v99
	v_sub_f32 v118, v118, v98
	v_sub_f32 v119, v119, v99
	v_sub_f32 v148, v148, v98
	v_sub_f32 v149, v149, v99
	v_sub_f32 v116, v116, v98
	v_sub_f32 v117, v117, v99
	v_fma_f32 v155, v92, v155, v98
	v_fma_f32 v154, v92, v154, v99
	v_fma_f32 v152, v93, v152, v98
	v_fma_f32 v153, v93, v153, v99
	v_fma_f32 v120, v84, v120, v98
	v_fma_f32 v121, v84, v121, v99
	v_fma_f32 v118, v85, v118, v98
	v_fma_f32 v119, v85, v119, v99
	v_fma_f32 v84, v76, v155, v140
	v_fma_f32 v76, v76, v154, v140
	v_fma_f32 v85, v77, v152, v140
	v_fma_f32 v77, v77, v153, v140
	ds_read_b128 v[72:75], v145 offset:25088
	ds_read_b128 v[64:67], v145 offset:25344
	ds_read_b128 v[88:91], v145 offset:33280
	ds_read_b128 v[80:83], v145 offset:33536
	ds_read2_b32 v[96:97], v151 offset0:160 offset1:176
	v_sub_f32 v146, v146, v98
	v_sub_f32 v147, v147, v99
	v_sub_f32 v114, v114, v98
	v_sub_f32 v115, v115, v99
	v_fma_f32 v148, v94, v148, v98
	v_fma_f32 v149, v94, v149, v99
	v_fma_f32 v116, v86, v116, v98
	v_fma_f32 v117, v86, v117, v99
	v_fma_f32 v84, v68, v120, v84
	v_fma_f32 v76, v68, v121, v76
	v_fma_f32 v86, v78, v148, v140
	v_fma_f32 v78, v78, v149, v140
	v_fma_f32 v68, v69, v118, v85
	v_fma_f32 v77, v69, v119, v77
	v_fma_f32 v146, v95, v146, v98
	v_fma_f32 v147, v95, v147, v99
	v_fma_f32 v69, v70, v116, v86
	v_fma_f32 v70, v70, v117, v78
	v_fma_f32 v114, v87, v114, v98
	v_fma_f32 v115, v87, v115, v99
	v_fma_f32 v87, v79, v146, v140
	v_fma_f32 v79, v79, v147, v140
	v_add_f32_e32 v68, v84, v68
	v_fma_f32 v78, v71, v114, v87
	v_fma_f32 v71, v71, v115, v79
	v_add_f32_e32 v76, v76, v77
	v_add_f32_e32 v69, v69, v78
	v_add_f32_e32 v70, v70, v71
	v_add_f32_e32 v68, v68, v69
	v_add_f32_e32 v70, v76, v70
	v_mov_b32_e32 v69, 0
	v_add_f32_dpp v68, v68, v68 row_ror:8 row_mask:0xf bank_mask:0xf bound_ctrl:1
	v_add_f32_dpp v70, v70, v70 row_ror:8 row_mask:0xf bank_mask:0xf bound_ctrl:1
	v_mov_b32_e32 v71, 0
	v_add_f32_dpp v68, v68, v68 row_ror:4 row_mask:0xf bank_mask:0xf bound_ctrl:1
	v_add_f32_dpp v70, v70, v70 row_ror:4 row_mask:0xf bank_mask:0xf bound_ctrl:1
	s_nop 0
	v_add_f32_dpp v68, v68, v68 row_ror:2 row_mask:0xf bank_mask:0xf bound_ctrl:1
	v_add_f32_dpp v70, v70, v70 row_ror:2 row_mask:0xf bank_mask:0xf bound_ctrl:1
	s_nop 0
	v_mov_b32_dpp v69, v68 row_ror:1 row_mask:0xf bank_mask:0xf
	v_mov_b32_dpp v71, v70 row_ror:1 row_mask:0xf bank_mask:0xf
	s_and_saveexec_b64 s[8:9], s[38:39]
	v_add_f32_e32 v70, v70, v71
	v_add_f32_e32 v68, v68, v69
	ds_write2_b32 v150, v68, v70 offset0:128 offset1:144
	s_or_b64 exec, exec, s[8:9]
	s_waitcnt lgkmcnt(0)
	v_sub_f32 v155, v155, v96
	v_sub_f32 v154, v154, v97
	v_sub_f32 v152, v152, v96
	v_sub_f32 v153, v153, v97
	v_sub_f32 v120, v120, v96
	v_sub_f32 v121, v121, v97
	v_sub_f32 v118, v118, v96
	v_sub_f32 v119, v119, v97
	v_sub_f32 v148, v148, v96
	v_sub_f32 v149, v149, v97
	v_sub_f32 v116, v116, v96
	v_sub_f32 v117, v117, v97
	v_fma_f32 v155, v88, v155, v96
	v_fma_f32 v154, v88, v154, v97
	v_fma_f32 v152, v89, v152, v96
	v_fma_f32 v153, v89, v153, v97
	v_fma_f32 v120, v80, v120, v96
	v_fma_f32 v121, v80, v121, v97
	v_fma_f32 v118, v81, v118, v96
	v_fma_f32 v119, v81, v119, v97
	v_fma_f32 v80, v72, v155, v140
	v_fma_f32 v72, v72, v154, v140
	v_fma_f32 v81, v73, v152, v140
	v_fma_f32 v73, v73, v153, v140
	ds_read_b128 v[76:79], v145 offset:25600
	ds_read_b128 v[68:71], v145 offset:25856
	ds_read_b128 v[92:95], v145 offset:33792
	ds_read_b128 v[84:87], v145 offset:34048
	ds_read2_b32 v[98:99], v151 offset0:192 offset1:208
	v_sub_f32 v146, v146, v96
	v_sub_f32 v147, v147, v97
	v_sub_f32 v114, v114, v96
	v_sub_f32 v115, v115, v97
	v_fma_f32 v148, v90, v148, v96
	v_fma_f32 v149, v90, v149, v97
	v_fma_f32 v116, v82, v116, v96
	v_fma_f32 v117, v82, v117, v97
	v_fma_f32 v80, v64, v120, v80
	v_fma_f32 v72, v64, v121, v72
	v_fma_f32 v82, v74, v148, v140
	v_fma_f32 v74, v74, v149, v140
	v_fma_f32 v64, v65, v118, v81
	v_fma_f32 v73, v65, v119, v73
	v_fma_f32 v146, v91, v146, v96
	v_fma_f32 v147, v91, v147, v97
	v_fma_f32 v65, v66, v116, v82
	v_fma_f32 v66, v66, v117, v74
	v_fma_f32 v114, v83, v114, v96
	v_fma_f32 v115, v83, v115, v97
	v_fma_f32 v83, v75, v146, v140
	v_fma_f32 v75, v75, v147, v140
	v_add_f32_e32 v64, v80, v64
	v_fma_f32 v74, v67, v114, v83
	v_fma_f32 v67, v67, v115, v75
	v_add_f32_e32 v72, v72, v73
	v_add_f32_e32 v65, v65, v74
	v_add_f32_e32 v66, v66, v67
	v_add_f32_e32 v64, v64, v65
	v_add_f32_e32 v66, v72, v66
	v_mov_b32_e32 v65, 0
	v_add_f32_dpp v64, v64, v64 row_ror:8 row_mask:0xf bank_mask:0xf bound_ctrl:1
	v_add_f32_dpp v66, v66, v66 row_ror:8 row_mask:0xf bank_mask:0xf bound_ctrl:1
	v_mov_b32_e32 v67, 0
	v_add_f32_dpp v64, v64, v64 row_ror:4 row_mask:0xf bank_mask:0xf bound_ctrl:1
	v_add_f32_dpp v66, v66, v66 row_ror:4 row_mask:0xf bank_mask:0xf bound_ctrl:1
	s_nop 0
	v_add_f32_dpp v64, v64, v64 row_ror:2 row_mask:0xf bank_mask:0xf bound_ctrl:1
	v_add_f32_dpp v66, v66, v66 row_ror:2 row_mask:0xf bank_mask:0xf bound_ctrl:1
	s_nop 0
	v_mov_b32_dpp v65, v64 row_ror:1 row_mask:0xf bank_mask:0xf
	v_mov_b32_dpp v67, v66 row_ror:1 row_mask:0xf bank_mask:0xf
	s_and_saveexec_b64 s[8:9], s[38:39]
	v_add_f32_e32 v66, v66, v67
	v_add_f32_e32 v64, v64, v65
	ds_write2_b32 v150, v64, v66 offset0:160 offset1:176
	s_or_b64 exec, exec, s[8:9]
	ds_read_b128 v[72:75], v145 offset:26112
	ds_read_b128 v[64:67], v145 offset:26368
	ds_read_b128 v[88:91], v145 offset:34304
	ds_read_b128 v[80:83], v145 offset:34560
	ds_read2_b32 v[96:97], v151 offset0:224 offset1:240
	s_waitcnt lgkmcnt(5)
	v_sub_f32 v151, v155, v98
	v_sub_f32 v154, v154, v99
	v_sub_f32 v152, v152, v98
	v_sub_f32 v153, v153, v99
	v_sub_f32 v148, v148, v98
	v_sub_f32 v149, v149, v99
	v_sub_f32 v155, v146, v98
	v_sub_f32 v147, v147, v99
	v_sub_f32 v156, v120, v98
	v_sub_f32 v157, v121, v99
	v_sub_f32 v178, v118, v98
	v_sub_f32 v179, v119, v99
	v_sub_f32 v180, v116, v98
	v_sub_f32 v181, v117, v99
	v_sub_f32 v182, v114, v98
	v_sub_f32 v183, v115, v99
	v_fma_f32 v146, v92, v151, v98
	v_fma_f32 v121, v92, v154, v99
	v_fma_f32 v119, v93, v152, v98
	v_fma_f32 v120, v93, v153, v99
	v_fma_f32 v117, v94, v148, v98
	v_fma_f32 v118, v94, v149, v99
	v_fma_f32 v115, v95, v155, v98
	v_fma_f32 v116, v95, v147, v99
	v_fma_f32 v95, v84, v156, v98
	v_fma_f32 v114, v84, v157, v99
	v_fma_f32 v93, v85, v178, v98
	v_fma_f32 v94, v85, v179, v99
	v_fma_f32 v92, v86, v180, v98
	v_fma_f32 v84, v87, v182, v98
	v_fma_f32 v85, v87, v183, v99
	v_fma_f32 v87, v76, v146, v140
	v_fma_f32 v76, v76, v121, v140
	v_fma_f32 v98, v77, v119, v140
	v_fma_f32 v77, v77, v120, v140
	v_fma_f32 v86, v86, v181, v99
	v_fma_f32 v99, v78, v117, v140
	v_fma_f32 v78, v78, v118, v140
	v_fma_f32 v87, v68, v95, v87
	v_fma_f32 v76, v68, v114, v76
	v_fma_f32 v68, v69, v93, v98
	v_fma_f32 v77, v69, v94, v77
	v_fma_f32 v69, v70, v92, v99
	v_fma_f32 v70, v70, v86, v78
	v_fma_f32 v147, v79, v115, v140
	v_fma_f32 v79, v79, v116, v140
	v_add_f32_e32 v68, v87, v68
	v_fma_f32 v78, v71, v84, v147
	v_fma_f32 v71, v71, v85, v79
	v_add_f32_e32 v76, v76, v77
	v_add_f32_e32 v69, v69, v78
	v_add_f32_e32 v70, v70, v71
	v_add_f32_e32 v68, v68, v69
	v_add_f32_e32 v70, v76, v70
	v_mov_b32_e32 v69, 0
	v_add_f32_dpp v68, v68, v68 row_ror:8 row_mask:0xf bank_mask:0xf bound_ctrl:1
	v_add_f32_dpp v70, v70, v70 row_ror:8 row_mask:0xf bank_mask:0xf bound_ctrl:1
	v_mov_b32_e32 v71, 0
	v_add_f32_dpp v68, v68, v68 row_ror:4 row_mask:0xf bank_mask:0xf bound_ctrl:1
	v_add_f32_dpp v70, v70, v70 row_ror:4 row_mask:0xf bank_mask:0xf bound_ctrl:1
	s_nop 0
	v_add_f32_dpp v68, v68, v68 row_ror:2 row_mask:0xf bank_mask:0xf bound_ctrl:1
	v_add_f32_dpp v70, v70, v70 row_ror:2 row_mask:0xf bank_mask:0xf bound_ctrl:1
	s_nop 0
	v_mov_b32_dpp v69, v68 row_ror:1 row_mask:0xf bank_mask:0xf
	v_mov_b32_dpp v71, v70 row_ror:1 row_mask:0xf bank_mask:0xf
	s_and_saveexec_b64 s[8:9], s[38:39]
	v_add_f32_e32 v70, v70, v71
	v_add_f32_e32 v68, v68, v69
	ds_write2_b32 v150, v68, v70 offset0:192 offset1:208
	s_or_b64 exec, exec, s[8:9]
	s_waitcnt lgkmcnt(0)
	v_sub_f32 v68, v146, v96
	v_sub_f32 v69, v121, v97
	v_sub_f32 v70, v119, v96
	v_sub_f32 v71, v120, v97
	v_sub_f32 v77, v118, v97
	v_sub_f32 v76, v117, v96
	v_fma_f32 v118, v88, v68, v96
	v_fma_f32 v146, v88, v69, v97
	v_fma_f32 v119, v89, v70, v96
	v_sub_f32 v87, v95, v96
	v_sub_f32 v95, v114, v97
	v_sub_f32 v93, v93, v96
	v_fma_f32 v68, v72, v118, v140
	v_fma_f32 v69, v72, v146, v140
	v_fma_f32 v70, v73, v119, v140
	v_sub_f32 v94, v94, v97
	v_sub_f32 v92, v92, v96
	v_sub_f32 v86, v86, v97
	v_fma_f32 v120, v89, v71, v97
	v_fma_f32 v88, v90, v76, v96
	v_fma_f32 v121, v90, v77, v97
	v_fma_f32 v90, v80, v87, v96
	v_fma_f32 v147, v80, v95, v97
	v_fma_f32 v80, v81, v93, v96
	v_fma_f32 v148, v81, v94, v97
	v_fma_f32 v81, v82, v92, v96
	v_fma_f32 v149, v82, v86, v97
	v_fma_f32 v71, v73, v120, v140
	v_fma_f32 v72, v74, v88, v140
	v_fma_f32 v73, v74, v121, v140
	v_fma_f32 v68, v64, v90, v68
	v_fma_f32 v69, v64, v147, v69
	v_fma_f32 v64, v65, v80, v70
	v_fma_f32 v70, v65, v148, v71
	v_fma_f32 v65, v66, v81, v72
	v_fma_f32 v66, v66, v149, v73
	v_sub_f32 v78, v115, v96
	v_sub_f32 v79, v116, v97
	v_sub_f32 v84, v84, v96
	v_sub_f32 v85, v85, v97
	v_add_f32_e32 v64, v68, v64
	v_fma_f32 v89, v91, v78, v96
	v_fma_f32 v91, v91, v79, v97
	v_fma_f32 v82, v83, v84, v96
	v_fma_f32 v83, v83, v85, v97
	v_add_f32_e32 v68, v69, v70
	v_fma_f32 v74, v75, v89, v140
	v_fma_f32 v75, v75, v91, v140
	v_fma_f32 v71, v67, v82, v74
	v_fma_f32 v67, v67, v83, v75
	v_add_f32_e32 v65, v65, v71
	v_add_f32_e32 v66, v66, v67
	v_add_f32_e32 v64, v64, v65
	v_add_f32_e32 v66, v68, v66
	v_mov_b32_e32 v65, 0
	v_add_f32_dpp v64, v64, v64 row_ror:8 row_mask:0xf bank_mask:0xf bound_ctrl:1
	v_add_f32_dpp v66, v66, v66 row_ror:8 row_mask:0xf bank_mask:0xf bound_ctrl:1
	v_mov_b32_e32 v67, 0
	v_add_f32_dpp v64, v64, v64 row_ror:4 row_mask:0xf bank_mask:0xf bound_ctrl:1
	v_add_f32_dpp v66, v66, v66 row_ror:4 row_mask:0xf bank_mask:0xf bound_ctrl:1
	s_nop 0
	v_add_f32_dpp v64, v64, v64 row_ror:2 row_mask:0xf bank_mask:0xf bound_ctrl:1
	v_add_f32_dpp v66, v66, v66 row_ror:2 row_mask:0xf bank_mask:0xf bound_ctrl:1
	s_nop 0
	v_mov_b32_dpp v65, v64 row_ror:1 row_mask:0xf bank_mask:0xf
	v_mov_b32_dpp v67, v66 row_ror:1 row_mask:0xf bank_mask:0xf
	s_and_saveexec_b64 s[8:9], s[38:39]
	s_cbranch_execz .LBB0_1284
	v_add_f32_e32 v66, v66, v67
	v_add_f32_e32 v64, v64, v65
	ds_write2_b32 v150, v64, v66 offset0:224 offset1:240
	s_branch .LBB0_1284
.LBB0_1425:
	s_waitcnt lgkmcnt(0)
	s_barrier
	s_or_b32 s4, s45, 0x7f0
	ds_read2st64_b32 v[0:1], v134 offset0:152 offset1:156
	v_add_u32_e32 v2, s4, v123
	v_ashrrev_i32_e32 v3, 31, v2
	v_lshlrev_b64 v[2:3], 12, v[2:3]
	s_load_dwordx2 s[8:9], s[0:1], 0x158
	v_lshl_add_u64 v[2:3], v[108:109], 0, v[2:3]
	s_waitcnt lgkmcnt(0)
	global_store_dword v[2:3], v0, off
	v_add_u32_e32 v2, s4, v125
	s_lshl_b32 s4, s43, 17
	s_lshl_b32 s15, s44, 14
	s_or_b32 s94, s15, s4
	v_ashrrev_i32_e32 v3, 31, v2
	s_lshl_b64 s[22:23], s[94:95], 2
	v_lshlrev_b64 v[2:3], 12, v[2:3]
	s_add_u32 s4, s8, s22
	s_movk_i32 s8, 0x210
	v_lshl_add_u64 v[2:3], v[108:109], 0, v[2:3]
	v_mad_u32_u24 v0, v122, s8, v103
	global_store_dword v[2:3], v1, off
	v_add_u32_e32 v1, 0xa400, v0
	s_addc_u32 s9, s9, s23
	ds_write2_b32 v1, v118, v146 offset0:204 offset1:220
	ds_write2_b32 v1, v119, v120 offset0:237 offset1:253
	v_add_u32_e32 v1, 0xa800, v0
	s_lshl_b32 s8, s42, 2
	ds_write2_b32 v1, v88, v121 offset0:14 offset1:30
	ds_write2_b32 v1, v89, v91 offset0:47 offset1:63
	v_add_u32_e32 v0, 0xc800, v0
	s_add_u32 s8, s4, s8
	v_lshlrev_b32_e32 v1, 2, v134
	ds_write2_b32 v0, v90, v147 offset0:12 offset1:28
	ds_write2_b32 v0, v80, v148 offset0:45 offset1:61
	ds_write2_b32 v0, v81, v149 offset0:78 offset1:94
	ds_write2_b32 v0, v82, v83 offset0:111 offset1:127
	s_addc_u32 s9, s9, 0
	v_ashrrev_i32_e32 v0, 3, v101
	v_and_b32_e32 v2, 0x70, v1
	v_mov_b32_e32 v3, v140
	v_lshl_add_u64 v[4:5], s[8:9], 0, v[2:3]
	v_mad_u64_u32 v[6:7], s[8:9], v0, s68, v[2:3]
	v_ashrrev_i32_e32 v1, 31, v0
	v_add_u32_e32 v2, 0xa730, v6
	v_add_u32_e32 v3, 0xa738, v6
	v_lshlrev_b64 v[0:1], 9, v[0:1]
	s_waitcnt lgkmcnt(0)
	s_barrier
	v_lshl_add_u64 v[4:5], v[4:5], 0, v[0:1]
	ds_read2_b32 v[0:1], v2 offset1:1
	ds_read2_b32 v[2:3], v3 offset1:1
	s_mov_b32 s4, 0x4c1c000
	v_add_co_u32_e32 v8, vcc, s4, v4
	s_mov_b32 s4, 0x4c20000
	s_nop 0
	v_addc_co_u32_e32 v9, vcc, 0, v5, vcc
	s_waitcnt lgkmcnt(0)
	global_store_dwordx4 v[8:9], v[0:3], off offset:64
	s_nop 1
	v_add_co_u32_e32 v8, vcc, s4, v4
	v_add_u32_e32 v0, 0xb7b0, v6
	v_add_u32_e32 v2, 0xb7b8, v6
	ds_read2_b32 v[0:1], v0 offset1:1
	ds_read2_b32 v[2:3], v2 offset1:1
	v_addc_co_u32_e32 v9, vcc, 0, v5, vcc
	s_mov_b32 s4, 0x4c24000
	s_mov_b64 s[8:9], 0
	s_waitcnt lgkmcnt(0)
	global_store_dwordx4 v[8:9], v[0:3], off offset:64
	s_nop 1
	v_add_co_u32_e32 v8, vcc, s4, v4
	v_add_u32_e32 v0, 0xc830, v6
	v_add_u32_e32 v2, 0xc838, v6
	ds_read2_b32 v[0:1], v0 offset1:1
	ds_read2_b32 v[2:3], v2 offset1:1
	v_addc_co_u32_e32 v9, vcc, 0, v5, vcc
	v_add_co_u32_e32 v4, vcc, 0x4c28000, v4
	s_waitcnt lgkmcnt(0)
	global_store_dwordx4 v[8:9], v[0:3], off offset:64
	v_addc_co_u32_e32 v5, vcc, 0, v5, vcc
	s_nop 0
	v_add_u32_e32 v0, 0xd8b0, v6
	v_add_u32_e32 v2, 0xd8b8, v6
	ds_read2_b32 v[0:1], v0 offset1:1
	ds_read2_b32 v[2:3], v2 offset1:1
	s_waitcnt lgkmcnt(0)
	global_store_dwordx4 v[4:5], v[0:3], off offset:64

.LBB0_1454:
	s_or_b64 exec, exec, s[8:9]
	s_waitcnt lgkmcnt(0)
	s_barrier
	v_add_u32_e64 v190, s83, 0
	ds_read_b128 v[104:107], v188
	ds_read_b128 v[108:111], v188 offset:256
	ds_read_b128 v[112:115], v188 offset:8192
	ds_read_b128 v[116:119], v188 offset:8448
	ds_read2_b64 v[96:99], v190 offset0:32 offset1:40
	v_add_u32_e32 v192, 0x4000, v189
	ds_read2_b32 v[92:93], v192 offset1:16
	ds_read_b128 v[202:205], v188 offset:512
	ds_read_b128 v[206:209], v188 offset:768
	ds_read_b128 v[152:155], v188 offset:8704
	ds_read_b128 v[194:197], v188 offset:8960
	ds_read_b128 v[100:103], v188 offset:1024
	ds_read_b128 v[88:91], v188 offset:1280
	ds_read_b128 v[132:135], v188 offset:9216
	ds_read_b128 v[124:127], v188 offset:9472
	ds_read_b128 v[84:87], v188 offset:1536
	ds_read_b128 v[80:83], v188 offset:1792
	ds_read_b128 v[128:131], v188 offset:9728
	ds_read_b128 v[120:123], v188 offset:9984
	s_waitcnt lgkmcnt(12)
	v_mul_f32_e32 v92, v98, v92
	v_mul_f32 v94, v112, v92
	v_mul_f32 v95, v113, v92
	v_mul_f32 v98, v114, v92
	v_mul_f32 v112, v115, v92
	v_mul_f32 v113, v116, v92
	v_mul_f32 v114, v117, v92
	v_fma_f32 v200, v96, v64, v94
	v_fma_f32 v199, v96, v65, v95
	v_mul_f32 v115, v118, v92
	v_mul_f32 v116, v119, v92
	s_waitcnt lgkmcnt(9)
	v_mul_f32 v117, v152, v92
	v_mul_f32 v118, v153, v92
	v_fma_f32 v64, v104, v200, v140
	v_fma_f32 v65, v105, v199, v140
	v_mul_f32 v119, v154, v92
	v_mul_f32 v152, v155, v92
	s_waitcnt lgkmcnt(8)
	v_mul_f32 v153, v194, v92
	v_mul_f32 v201, v195, v92
	v_mul_f32 v210, v196, v92
	v_mul_f32 v92, v197, v92
	v_fma_f32 v198, v96, v66, v98
	v_fma_f32 v197, v96, v67, v112
	v_fma_f32 v191, v96, v76, v113
	v_fma_f32 v193, v96, v77, v114
	v_fma_f32 v194, v96, v78, v115
	v_fma_f32 v196, v96, v79, v116
	v_fma_f32 v66, v106, v198, v140
	v_fma_f32 v67, v107, v197, v140
	v_fma_f32 v64, v108, v191, v64
	v_fma_f32 v65, v109, v193, v65
	v_fma_f32 v195, v96, v72, v117
	v_fma_f32 v155, v96, v73, v118
	v_fma_f32 v66, v110, v194, v66
	v_fma_f32 v67, v111, v196, v67
	v_fma_f32 v154, v96, v74, v119
	v_fma_f32 v98, v96, v75, v152
	v_fma_f32 v64, v202, v195, v64
	v_fma_f32 v65, v203, v155, v65
	v_fma_f32 v79, v96, v68, v153
	v_fma_f32 v78, v96, v69, v201
	v_fma_f32 v66, v204, v154, v66
	v_fma_f32 v67, v205, v98, v67
	v_fma_f32 v77, v96, v70, v210
	v_fma_f32 v76, v96, v71, v92
	v_fma_f32 v64, v206, v79, v64
	v_fma_f32 v65, v207, v78, v65
	v_fma_f32 v66, v208, v77, v66
	v_fma_f32 v67, v209, v76, v67
	v_add_f32_e32 v64, v64, v65
	v_add_f32_e32 v65, v66, v67
	v_add_f32_e32 v64, v64, v65
	v_mov_b32_e32 v65, 0
	s_nop 0
	v_add_f32_dpp v64, v64, v64 row_ror:8 row_mask:0xf bank_mask:0xf bound_ctrl:1
	s_nop 1
	v_add_f32_dpp v64, v64, v64 row_ror:4 row_mask:0xf bank_mask:0xf bound_ctrl:1
	s_nop 1
	v_add_f32_dpp v64, v64, v64 row_ror:2 row_mask:0xf bank_mask:0xf bound_ctrl:1
	s_nop 1
	v_mov_b32_dpp v65, v64 row_ror:1 row_mask:0xf bank_mask:0xf
	s_and_saveexec_b64 s[8:9], s[44:45]
	v_add_f32_e32 v64, v64, v65
	ds_write_b32 v189, v64 offset:34048
	s_or_b64 exec, exec, s[8:9]
	v_mul_f32_e32 v99, v99, v93
	ds_read_b128 v[92:95], v188 offset:2048
	ds_read_b128 v[72:75], v188 offset:2304
	ds_read_b128 v[116:119], v188 offset:10240
	ds_read_b128 v[108:111], v188 offset:10496
	ds_read_b128 v[68:71], v188 offset:2560
	ds_read_b128 v[64:67], v188 offset:2816
	ds_read_b128 v[112:115], v188 offset:10752
	ds_read_b128 v[104:107], v188 offset:11008
	ds_read2_b32 v[152:153], v190 offset0:66 offset1:82
	ds_read_b32 v96, v189 offset:16512
	s_waitcnt lgkmcnt(14)
	v_mul_f32 v132, v132, v99
	v_mul_f32 v133, v133, v99
	v_mul_f32 v134, v134, v99
	v_mul_f32 v135, v135, v99
	v_mul_f32 v124, v124, v99
	v_mul_f32 v125, v125, v99
	v_mul_f32 v126, v126, v99
	v_mul_f32 v127, v127, v99
	s_waitcnt lgkmcnt(11)
	v_mul_f32 v128, v128, v99
	v_mul_f32 v129, v129, v99
	v_mul_f32 v130, v130, v99
	v_mul_f32 v131, v131, v99
	s_waitcnt lgkmcnt(10)
	v_mul_f32 v120, v120, v99
	v_mul_f32 v121, v121, v99
	v_mul_f32 v122, v122, v99
	v_mul_f32 v99, v123, v99
	v_fma_f32 v132, v97, v200, v132
	v_fma_f32 v133, v97, v199, v133
	v_fma_f32 v134, v97, v198, v134
	v_fma_f32 v135, v97, v197, v135
	v_fma_f32 v202, v97, v77, v122
	v_fma_f32 v203, v97, v76, v99
	v_fma_f32 v76, v100, v132, v140
	v_fma_f32 v77, v101, v133, v140
	v_fma_f32 v191, v97, v191, v124
	v_fma_f32 v193, v97, v193, v125
	v_fma_f32 v200, v97, v79, v120
	v_fma_f32 v201, v97, v78, v121
	v_fma_f32 v78, v102, v134, v140
	v_fma_f32 v79, v103, v135, v140
	v_fma_f32 v76, v88, v191, v76
	v_fma_f32 v77, v89, v193, v77
	v_fma_f32 v194, v97, v194, v126
	v_fma_f32 v196, v97, v196, v127
	v_fma_f32 v195, v97, v195, v128
	v_fma_f32 v197, v97, v155, v129
	v_fma_f32 v198, v97, v154, v130
	v_fma_f32 v199, v97, v98, v131
	v_fma_f32 v78, v90, v194, v78
	v_fma_f32 v79, v91, v196, v79
	v_fma_f32 v76, v84, v195, v76
	v_fma_f32 v77, v85, v197, v77
	v_fma_f32 v78, v86, v198, v78
	v_fma_f32 v79, v87, v199, v79
	v_fma_f32 v76, v80, v200, v76
	v_fma_f32 v77, v81, v201, v77
	v_fma_f32 v78, v82, v202, v78
	v_fma_f32 v79, v83, v203, v79
	v_add_f32_e32 v76, v76, v77
	v_add_f32_e32 v77, v78, v79
	v_add_f32_e32 v76, v76, v77
	v_mov_b32_e32 v77, 0
	s_nop 0
	v_add_f32_dpp v76, v76, v76 row_ror:8 row_mask:0xf bank_mask:0xf bound_ctrl:1
	s_nop 1
	v_add_f32_dpp v76, v76, v76 row_ror:4 row_mask:0xf bank_mask:0xf bound_ctrl:1
	s_nop 1
	v_add_f32_dpp v76, v76, v76 row_ror:2 row_mask:0xf bank_mask:0xf bound_ctrl:1
	s_nop 1
	v_mov_b32_dpp v77, v76 row_ror:1 row_mask:0xf bank_mask:0xf
	s_and_saveexec_b64 s[8:9], s[44:45]
	v_add_f32_e32 v76, v76, v77
	ds_write_b32 v189, v76 offset:34112
	s_or_b64 exec, exec, s[8:9]
	s_waitcnt lgkmcnt(0)
	v_mul_f32_e32 v89, v153, v96
	ds_read_b128 v[96:99], v188 offset:3072
	ds_read_b128 v[84:87], v188 offset:3328
	ds_read_b128 v[128:131], v188 offset:11264
	ds_read_b128 v[120:123], v188 offset:11520
	ds_read_b128 v[80:83], v188 offset:3584
	ds_read_b128 v[76:79], v188 offset:3840
	ds_read_b128 v[124:127], v188 offset:11776
	ds_read_b128 v[100:103], v188 offset:12032
	ds_read2_b32 v[154:155], v190 offset0:67 offset1:83
	ds_read_b32 v88, v189 offset:16576
	v_mul_f32 v90, v116, v89
	v_mul_f32 v91, v117, v89
	v_mul_f32 v118, v118, v89
	v_mul_f32 v119, v119, v89
	v_mul_f32 v108, v108, v89
	v_mul_f32 v109, v109, v89
	v_mul_f32 v110, v110, v89
	v_mul_f32 v111, v111, v89
	v_mul_f32 v112, v112, v89
	v_mul_f32 v113, v113, v89
	v_mul_f32 v114, v114, v89
	v_mul_f32 v115, v115, v89
	v_mul_f32 v104, v104, v89
	v_mul_f32 v105, v105, v89
	v_mul_f32 v106, v106, v89
	v_mul_f32 v89, v107, v89
	v_fma_f32 v116, v152, v132, v90
	v_fma_f32 v117, v152, v133, v91
	v_fma_f32 v191, v152, v191, v108
	v_fma_f32 v193, v152, v193, v109
	v_fma_f32 v195, v152, v195, v112
	v_fma_f32 v197, v152, v197, v113
	v_fma_f32 v200, v152, v200, v104
	v_fma_f32 v201, v152, v201, v105
	v_fma_f32 v203, v152, v203, v89
	v_fma_f32 v89, v92, v116, v140
	v_fma_f32 v90, v93, v117, v140
	v_fma_f32 v118, v152, v134, v118
	v_fma_f32 v119, v152, v135, v119
	v_fma_f32 v194, v152, v194, v110
	v_fma_f32 v196, v152, v196, v111
	v_fma_f32 v72, v72, v191, v89
	v_fma_f32 v73, v73, v193, v90
	v_fma_f32 v198, v152, v198, v114
	v_fma_f32 v199, v152, v199, v115
	v_fma_f32 v202, v152, v202, v106
	v_fma_f32 v91, v94, v118, v140
	v_fma_f32 v68, v68, v195, v72
	v_fma_f32 v69, v69, v197, v73
	v_fma_f32 v92, v95, v119, v140
	v_fma_f32 v64, v64, v200, v68
	v_fma_f32 v65, v65, v201, v69
	v_fma_f32 v74, v74, v194, v91
	v_fma_f32 v75, v75, v196, v92
	v_fma_f32 v70, v70, v198, v74
	v_fma_f32 v71, v71, v199, v75
	v_add_f32_e32 v64, v64, v65
	v_fma_f32 v66, v66, v202, v70
	v_fma_f32 v67, v67, v203, v71
	v_add_f32_e32 v65, v66, v67
	v_add_f32_e32 v64, v64, v65
	v_mov_b32_e32 v65, 0
	s_nop 0
	v_add_f32_dpp v64, v64, v64 row_ror:8 row_mask:0xf bank_mask:0xf bound_ctrl:1
	s_nop 1
	v_add_f32_dpp v64, v64, v64 row_ror:4 row_mask:0xf bank_mask:0xf bound_ctrl:1
	s_nop 1
	v_add_f32_dpp v64, v64, v64 row_ror:2 row_mask:0xf bank_mask:0xf bound_ctrl:1
	s_nop 1
	v_mov_b32_dpp v65, v64 row_ror:1 row_mask:0xf bank_mask:0xf
	s_and_saveexec_b64 s[8:9], s[44:45]
	v_add_f32_e32 v64, v64, v65
	ds_write_b32 v189, v64 offset:34176
	s_or_b64 exec, exec, s[8:9]
	s_waitcnt lgkmcnt(0)
	v_mul_f32_e32 v69, v155, v88
	ds_read_b128 v[92:95], v188 offset:4096
	ds_read_b128 v[88:91], v188 offset:4352
	ds_read_b128 v[132:135], v188 offset:12288
	ds_read_b128 v[108:111], v188 offset:12544
	ds_read_b128 v[72:75], v188 offset:4608
	ds_read_b128 v[64:67], v188 offset:4864
	ds_read_b128 v[112:115], v188 offset:12800
	ds_read_b128 v[104:107], v188 offset:13056
	ds_read2_b32 v[152:153], v190 offset0:68 offset1:84
	ds_read_b32 v68, v189 offset:16640
	v_mul_f32 v70, v128, v69
	v_mul_f32 v71, v129, v69
	v_mul_f32 v130, v130, v69
	v_mul_f32 v131, v131, v69
	v_mul_f32 v120, v120, v69
	v_mul_f32 v121, v121, v69
	v_mul_f32 v122, v122, v69
	v_mul_f32 v123, v123, v69
	v_mul_f32 v124, v124, v69
	v_mul_f32 v125, v125, v69
	v_mul_f32 v126, v126, v69
	v_mul_f32 v127, v127, v69
	v_mul_f32 v100, v100, v69
	v_mul_f32 v101, v101, v69
	v_mul_f32 v102, v102, v69
	v_mul_f32 v69, v103, v69
	v_fma_f32 v128, v154, v116, v70
	v_fma_f32 v129, v154, v117, v71
	v_fma_f32 v130, v154, v118, v130
	v_fma_f32 v191, v154, v191, v120
	v_fma_f32 v193, v154, v193, v121
	v_fma_f32 v203, v154, v203, v69
	v_fma_f32 v69, v96, v128, v140
	v_fma_f32 v70, v97, v129, v140
	v_fma_f32 v71, v98, v130, v140
	v_fma_f32 v194, v154, v194, v122
	v_fma_f32 v195, v154, v195, v124
	v_fma_f32 v197, v154, v197, v125
	v_fma_f32 v69, v84, v191, v69
	v_fma_f32 v70, v85, v193, v70
	v_fma_f32 v198, v154, v198, v126
	v_fma_f32 v71, v86, v194, v71
	v_fma_f32 v200, v154, v200, v100
	v_fma_f32 v201, v154, v201, v101
	v_fma_f32 v69, v80, v195, v69
	v_fma_f32 v70, v81, v197, v70
	v_fma_f32 v131, v154, v119, v131
	v_fma_f32 v71, v82, v198, v71
	v_fma_f32 v196, v154, v196, v123
	v_fma_f32 v199, v154, v199, v127
	v_fma_f32 v69, v76, v200, v69
	v_fma_f32 v70, v77, v201, v70
	v_fma_f32 v202, v154, v202, v102
	v_fma_f32 v96, v99, v131, v140
	v_fma_f32 v84, v87, v196, v96
	v_fma_f32 v71, v78, v202, v71
	v_add_f32_e32 v69, v69, v70
	v_fma_f32 v80, v83, v199, v84
	v_fma_f32 v76, v79, v203, v80
	v_add_f32_e32 v70, v71, v76
	v_add_f32_e32 v69, v69, v70
	v_mov_b32_e32 v70, 0
	s_nop 0
	v_add_f32_dpp v69, v69, v69 row_ror:8 row_mask:0xf bank_mask:0xf bound_ctrl:1
	s_nop 1
	v_add_f32_dpp v69, v69, v69 row_ror:4 row_mask:0xf bank_mask:0xf bound_ctrl:1
	s_nop 1
	v_add_f32_dpp v69, v69, v69 row_ror:2 row_mask:0xf bank_mask:0xf bound_ctrl:1
	s_nop 1
	v_mov_b32_dpp v70, v69 row_ror:1 row_mask:0xf bank_mask:0xf
	s_and_saveexec_b64 s[8:9], s[44:45]
	v_add_f32_e32 v69, v69, v70
	ds_write_b32 v189, v69 offset:34240
	s_or_b64 exec, exec, s[8:9]
	s_waitcnt lgkmcnt(0)
	v_mul_f32_e32 v85, v153, v68
	ds_read_b128 v[96:99], v188 offset:5120
	ds_read_b128 v[80:83], v188 offset:5376
	ds_read_b128 v[124:127], v188 offset:13312
	ds_read_b128 v[116:119], v188 offset:13568
	ds_read_b128 v[76:79], v188 offset:5632
	ds_read_b128 v[68:71], v188 offset:5888
	ds_read_b128 v[120:123], v188 offset:13824
	ds_read_b128 v[100:103], v188 offset:14080
	ds_read2_b32 v[154:155], v190 offset0:69 offset1:85
	ds_read_b32 v84, v189 offset:16704
	v_mul_f32 v86, v132, v85
	v_mul_f32 v87, v133, v85
	v_mul_f32 v132, v134, v85
	v_mul_f32 v133, v135, v85
	v_mul_f32 v108, v108, v85
	v_mul_f32 v109, v109, v85
	v_mul_f32 v110, v110, v85
	v_mul_f32 v111, v111, v85
	v_mul_f32 v112, v112, v85
	v_mul_f32 v113, v113, v85
	v_mul_f32 v114, v114, v85
	v_mul_f32 v115, v115, v85
	v_mul_f32 v104, v104, v85
	v_mul_f32 v105, v105, v85
	v_mul_f32 v106, v106, v85
	v_mul_f32 v85, v107, v85
	v_fma_f32 v134, v152, v128, v86
	v_fma_f32 v135, v152, v129, v87
	v_fma_f32 v153, v152, v130, v132
	v_fma_f32 v204, v152, v131, v133
	v_fma_f32 v191, v152, v191, v108
	v_fma_f32 v193, v152, v193, v109
	v_fma_f32 v194, v152, v194, v110
	v_fma_f32 v196, v152, v196, v111
	v_fma_f32 v195, v152, v195, v112
	v_fma_f32 v197, v152, v197, v113
	v_fma_f32 v198, v152, v198, v114
	v_fma_f32 v199, v152, v199, v115
	v_fma_f32 v200, v152, v200, v104
	v_fma_f32 v201, v152, v201, v105
	v_fma_f32 v202, v152, v202, v106
	v_fma_f32 v152, v152, v203, v85
	v_fma_f32 v85, v92, v134, v140
	v_fma_f32 v86, v93, v135, v140
	v_fma_f32 v87, v94, v153, v140
	v_fma_f32 v92, v95, v204, v140
	v_fma_f32 v85, v88, v191, v85
	v_fma_f32 v86, v89, v193, v86
	v_fma_f32 v87, v90, v194, v87
	v_fma_f32 v88, v91, v196, v92
	v_fma_f32 v72, v72, v195, v85
	v_fma_f32 v73, v73, v197, v86
	v_fma_f32 v74, v74, v198, v87
	v_fma_f32 v75, v75, v199, v88
	v_fma_f32 v64, v64, v200, v72
	v_fma_f32 v65, v65, v201, v73
	v_fma_f32 v66, v66, v202, v74
	v_fma_f32 v67, v67, v152, v75
	v_add_f32_e32 v64, v64, v65
	v_add_f32_e32 v65, v66, v67
	v_add_f32_e32 v64, v64, v65
	v_mov_b32_e32 v65, 0
	s_nop 0
	v_add_f32_dpp v64, v64, v64 row_ror:8 row_mask:0xf bank_mask:0xf bound_ctrl:1
	s_nop 1
	v_add_f32_dpp v64, v64, v64 row_ror:4 row_mask:0xf bank_mask:0xf bound_ctrl:1
	s_nop 1
	v_add_f32_dpp v64, v64, v64 row_ror:2 row_mask:0xf bank_mask:0xf bound_ctrl:1
	s_nop 1
	v_mov_b32_dpp v65, v64 row_ror:1 row_mask:0xf bank_mask:0xf
	s_and_saveexec_b64 s[8:9], s[44:45]
	v_add_f32_e32 v64, v64, v65
	ds_write_b32 v189, v64 offset:34304
	s_or_b64 exec, exec, s[8:9]
	s_waitcnt lgkmcnt(0)
	v_mul_f32_e32 v93, v155, v84
	ds_read_b128 v[88:91], v188 offset:6144
	ds_read_b128 v[84:87], v188 offset:6400
	ds_read_b128 v[128:131], v188 offset:14336
	ds_read_b128 v[108:111], v188 offset:14592
	ds_read_b128 v[72:75], v188 offset:6656
	ds_read_b128 v[64:67], v188 offset:6912
	ds_read_b128 v[112:115], v188 offset:14848
	ds_read_b128 v[104:107], v188 offset:15104
	ds_read2_b32 v[132:133], v190 offset0:70 offset1:86
	ds_read_b32 v92, v189 offset:16768
	v_mul_f32 v94, v124, v93
	v_mul_f32 v95, v125, v93
	v_mul_f32 v124, v126, v93
	v_mul_f32 v125, v127, v93
	v_mul_f32 v116, v116, v93
	v_mul_f32 v117, v117, v93
	v_mul_f32 v118, v118, v93
	v_mul_f32 v119, v119, v93
	v_mul_f32 v120, v120, v93
	v_mul_f32 v121, v121, v93
	v_mul_f32 v122, v122, v93
	v_mul_f32 v123, v123, v93
	v_mul_f32 v100, v100, v93
	v_mul_f32 v101, v101, v93
	v_mul_f32 v102, v102, v93
	v_mul_f32 v93, v103, v93
	v_fma_f32 v126, v154, v134, v94
	v_fma_f32 v127, v154, v135, v95
	v_fma_f32 v134, v154, v153, v124
	v_fma_f32 v153, v154, v191, v116
	v_fma_f32 v155, v154, v193, v117
	v_fma_f32 v191, v154, v194, v118
	v_fma_f32 v193, v154, v196, v119
	v_fma_f32 v194, v154, v195, v120
	v_fma_f32 v195, v154, v197, v121
	v_fma_f32 v196, v154, v198, v122
	v_fma_f32 v197, v154, v199, v123
	v_fma_f32 v198, v154, v200, v100
	v_fma_f32 v199, v154, v201, v101
	v_fma_f32 v152, v154, v152, v93
	v_fma_f32 v93, v96, v126, v140
	v_fma_f32 v94, v97, v127, v140
	v_fma_f32 v135, v154, v204, v125
	v_fma_f32 v200, v154, v202, v102
	v_fma_f32 v95, v98, v134, v140
	v_fma_f32 v80, v80, v153, v93
	v_fma_f32 v81, v81, v155, v94
	v_fma_f32 v96, v99, v135, v140
	v_fma_f32 v76, v76, v194, v80
	v_fma_f32 v77, v77, v195, v81
	v_fma_f32 v82, v82, v191, v95
	v_fma_f32 v83, v83, v193, v96
	v_fma_f32 v68, v68, v198, v76
	v_fma_f32 v69, v69, v199, v77
	v_fma_f32 v78, v78, v196, v82
	v_fma_f32 v79, v79, v197, v83
	v_fma_f32 v70, v70, v200, v78
	v_fma_f32 v71, v71, v152, v79
	v_add_f32_e32 v68, v68, v69
	v_add_f32_e32 v69, v70, v71
	v_add_f32_e32 v68, v68, v69
	v_mov_b32_e32 v69, 0
	s_nop 0
	v_add_f32_dpp v68, v68, v68 row_ror:8 row_mask:0xf bank_mask:0xf bound_ctrl:1
	s_nop 1
	v_add_f32_dpp v68, v68, v68 row_ror:4 row_mask:0xf bank_mask:0xf bound_ctrl:1
	s_nop 1
	v_add_f32_dpp v68, v68, v68 row_ror:2 row_mask:0xf bank_mask:0xf bound_ctrl:1
	s_nop 1
	v_mov_b32_dpp v69, v68 row_ror:1 row_mask:0xf bank_mask:0xf
	s_and_saveexec_b64 s[8:9], s[44:45]
	v_add_f32_e32 v68, v68, v69
	ds_write_b32 v189, v68 offset:34368
	s_or_b64 exec, exec, s[8:9]
	s_waitcnt lgkmcnt(0)
	v_mul_f32_e32 v154, v133, v92
	ds_read_b128 v[92:95], v188 offset:7168
	ds_read_b128 v[80:83], v188 offset:7424
	ds_read_b128 v[120:123], v188 offset:15360
	ds_read_b128 v[100:103], v188 offset:15616
	ds_read_b128 v[76:79], v188 offset:7680
	ds_read_b128 v[68:71], v188 offset:7936
	ds_read_b128 v[116:119], v188 offset:15872
	ds_read_b128 v[96:99], v188 offset:16128
	ds_read2_b32 v[124:125], v190 offset0:71 offset1:87
	ds_read_b32 v133, v189 offset:16832
	v_mul_f32 v130, v130, v154
	v_mul_f32 v131, v131, v154
	v_mul_f32 v128, v128, v154
	v_mul_f32 v129, v129, v154
	v_mul_f32 v108, v108, v154
	v_mul_f32 v109, v109, v154
	v_mul_f32 v110, v110, v154
	v_mul_f32 v111, v111, v154
	v_mul_f32 v201, v112, v154
	v_mul_f32 v202, v113, v154
	v_mul_f32 v203, v114, v154
	v_mul_f32 v204, v115, v154
	v_mul_f32 v205, v104, v154
	v_mul_f32 v206, v105, v154
	v_mul_f32 v207, v106, v154
	v_mul_f32 v154, v107, v154
	v_fma_f32 v104, v132, v126, v128
	v_fma_f32 v105, v132, v127, v129
	v_fma_f32 v106, v132, v134, v130
	v_fma_f32 v107, v132, v135, v131
	v_fma_f32 v112, v132, v153, v108
	v_fma_f32 v113, v132, v155, v109
	v_fma_f32 v126, v132, v194, v201
	v_fma_f32 v127, v132, v195, v202
	v_fma_f32 v130, v132, v198, v205
	v_fma_f32 v131, v132, v199, v206
	v_fma_f32 v88, v88, v104, v140
	v_fma_f32 v89, v89, v105, v140
	v_fma_f32 v114, v132, v191, v110
	v_fma_f32 v115, v132, v193, v111
	v_fma_f32 v128, v132, v196, v203
	v_fma_f32 v129, v132, v197, v204
	v_fma_f32 v84, v84, v112, v88
	v_fma_f32 v85, v85, v113, v89
	v_fma_f32 v134, v132, v200, v207
	v_fma_f32 v132, v132, v152, v154
	v_fma_f32 v90, v90, v106, v140
	v_fma_f32 v91, v91, v107, v140
	v_fma_f32 v72, v72, v126, v84
	v_fma_f32 v73, v73, v127, v85
	v_fma_f32 v64, v64, v130, v72
	v_fma_f32 v65, v65, v131, v73
	v_fma_f32 v86, v86, v114, v90
	v_fma_f32 v87, v87, v115, v91
	v_fma_f32 v74, v74, v128, v86
	v_fma_f32 v75, v75, v129, v87
	v_add_f32_e32 v64, v64, v65
	v_fma_f32 v66, v66, v134, v74
	v_fma_f32 v67, v67, v132, v75
	v_add_f32_e32 v65, v66, v67
	v_add_f32_e32 v64, v64, v65
	v_mov_b32_e32 v65, 0
	s_nop 0
	v_add_f32_dpp v64, v64, v64 row_ror:8 row_mask:0xf bank_mask:0xf bound_ctrl:1
	s_nop 1
	v_add_f32_dpp v64, v64, v64 row_ror:4 row_mask:0xf bank_mask:0xf bound_ctrl:1
	s_nop 1
	v_add_f32_dpp v64, v64, v64 row_ror:2 row_mask:0xf bank_mask:0xf bound_ctrl:1
	s_nop 1
	v_mov_b32_dpp v65, v64 row_ror:1 row_mask:0xf bank_mask:0xf
	s_and_saveexec_b64 s[8:9], s[44:45]
	v_add_f32_e32 v64, v64, v65
	ds_write_b32 v189, v64 offset:34432
	s_or_b64 exec, exec, s[8:9]
	s_waitcnt lgkmcnt(0)
	v_mul_f32_e32 v64, v125, v133
	v_mul_f32 v65, v120, v64
	v_mul_f32 v66, v121, v64
	v_mul_f32 v67, v122, v64
	v_mul_f32 v72, v123, v64
	v_mul_f32 v73, v100, v64
	v_mul_f32 v74, v101, v64
	v_mul_f32 v75, v102, v64
	v_mul_f32 v84, v103, v64
	v_mul_f32 v85, v116, v64
	v_mul_f32 v86, v117, v64
	v_mul_f32 v87, v118, v64
	v_mul_f32 v88, v119, v64
	v_mul_f32 v89, v96, v64
	v_mul_f32 v90, v97, v64
	v_mul_f32 v100, v98, v64
	v_mul_f32 v64, v99, v64
	v_fma_f32 v111, v124, v104, v65
	v_fma_f32 v110, v124, v105, v66
	v_fma_f32 v96, v124, v129, v88
	v_fma_f32 v109, v124, v106, v67
	v_fma_f32 v108, v124, v107, v72
	v_fma_f32 v88, v124, v132, v64
	v_fma_f32 v64, v92, v111, v140
	v_fma_f32 v65, v93, v110, v140
	v_fma_f32 v107, v124, v112, v73
	v_fma_f32 v106, v124, v113, v74
	v_fma_f32 v66, v94, v109, v140
	v_fma_f32 v67, v95, v108, v140
	v_fma_f32 v105, v124, v114, v75
	v_fma_f32 v104, v124, v115, v84
	v_fma_f32 v64, v80, v107, v64
	v_fma_f32 v65, v81, v106, v65
	v_fma_f32 v99, v124, v126, v85
	v_fma_f32 v98, v124, v127, v86
	v_fma_f32 v66, v82, v105, v66
	v_fma_f32 v67, v83, v104, v67
	v_fma_f32 v97, v124, v128, v87
	v_fma_f32 v91, v124, v130, v89
	v_fma_f32 v64, v76, v99, v64
	v_fma_f32 v65, v77, v98, v65
	v_fma_f32 v90, v124, v131, v90
	v_fma_f32 v67, v79, v96, v67
	v_fma_f32 v66, v78, v97, v66
	v_fma_f32 v89, v124, v134, v100
	v_fma_f32 v64, v68, v91, v64
	v_fma_f32 v65, v69, v90, v65
	v_fma_f32 v67, v71, v88, v67
	v_fma_f32 v66, v70, v89, v66
	v_add_f32_e32 v64, v64, v65
	v_add_f32_e32 v65, v66, v67
	v_add_f32_e32 v64, v64, v65
	v_mov_b32_e32 v65, 0
	s_nop 0
	v_add_f32_dpp v64, v64, v64 row_ror:8 row_mask:0xf bank_mask:0xf bound_ctrl:1
	s_nop 1
	v_add_f32_dpp v64, v64, v64 row_ror:4 row_mask:0xf bank_mask:0xf bound_ctrl:1
	s_nop 1
	v_add_f32_dpp v64, v64, v64 row_ror:2 row_mask:0xf bank_mask:0xf bound_ctrl:1
	s_nop 1
	v_mov_b32_dpp v65, v64 row_ror:1 row_mask:0xf bank_mask:0xf
	s_and_saveexec_b64 s[8:9], s[44:45]
	v_add_f32_e32 v64, v64, v65
	ds_write_b32 v189, v64 offset:34496
	s_or_b64 exec, exec, s[8:9]
	s_waitcnt vmcnt(11)
	ds_write_b128 v185, v[16:19] offset:17024
	s_waitcnt vmcnt(9)
	ds_write_b128 v186, v[24:27] offset:17024
	ds_write_b128 v185, v[20:23] offset:25216
	s_waitcnt vmcnt(8)
	ds_write_b128 v186, v[28:31] offset:25216
	s_and_saveexec_b64 s[8:9], s[42:43]
	ds_write_b32 v144, v184 offset:33408
	s_or_b64 exec, exec, s[8:9]
	s_and_saveexec_b64 s[8:9], s[40:41]
	s_cbranch_execz .LBB0_1474
	v_add_f32_e32 v64, v156, v157
	v_mul_f32_e64 v65, |v64|, s62
	v_exp_f32_e32 v65, v65
	v_min_f32_e32 v64, 0, v64
	v_add_f32_e32 v65, 1.0, v65
	v_cmp_gt_f32_e32 vcc, s5, v65
	s_nop 1
	v_cndmask_b32_e64 v66, 0, 32, vcc
	v_ldexp_f32 v65, v65, v66
	v_log_f32_e32 v65, v65
	v_cndmask_b32_e32 v67, 0, v171, vcc
	v_add_f32_e32 v66, v145, v179
	v_mul_f32_e32 v68, 0x3f317217, v65
	v_fma_f32 v68, v65, s76, -v68
	v_fmac_f32_e32 v68, 0x3377d1cf, v65
	v_fmac_f32_e32 v68, 0x3f317217, v65
	v_cmp_lt_f32_e64 vcc, |v65|, s77
	s_nop 1
	v_cndmask_b32_e32 v65, v65, v68, vcc
	v_sub_f32_e32 v65, v65, v67
	v_sub_f32_e32 v64, v64, v65
	v_add_u32_e32 v65, 0x8400, v144
	ds_write2_b32 v65, v66, v64 offset0:32 offset1:48

.LBB0_1485:
	s_or_b64 exec, exec, s[8:9]
	s_waitcnt lgkmcnt(0)
	s_barrier
	ds_read_b128 v[92:95], v188 offset:17024
	ds_read_b128 v[112:115], v188 offset:17280
	ds_read_b128 v[124:127], v188 offset:25216
	ds_read_b128 v[132:135], v188 offset:25472
	ds_read2_b64 v[80:83], v190 offset0:32 offset1:40
	v_add_u32_e32 v191, 0x8000, v189
	ds_read2_b32 v[76:77], v191 offset0:160 offset1:176
	ds_read_b128 v[202:205], v188 offset:17536
	ds_read_b128 v[206:209], v188 offset:17792
	ds_read_b128 v[152:155], v188 offset:25728
	ds_read_b128 v[194:197], v188 offset:25984
	ds_read_b128 v[84:87], v188 offset:18048
	ds_read_b128 v[72:75], v188 offset:18304
	ds_read_b128 v[128:131], v188 offset:26240
	ds_read_b128 v[116:119], v188 offset:26496
	ds_read_b128 v[68:71], v188 offset:18560
	ds_read_b128 v[64:67], v188 offset:18816
	ds_read_b128 v[120:123], v188 offset:26752
	ds_read_b128 v[100:103], v188 offset:27008
	s_waitcnt lgkmcnt(12)
	v_mul_f32_e32 v76, v82, v76
	v_mul_f32 v78, v124, v76
	v_mul_f32 v79, v125, v76
	v_mul_f32 v124, v126, v76
	v_mul_f32 v125, v127, v76
	v_mul_f32 v126, v132, v76
	v_mul_f32 v127, v133, v76
	v_mul_f32 v193, v134, v76
	v_mul_f32 v198, v135, v76
	s_waitcnt lgkmcnt(9)
	v_mul_f32 v152, v152, v76
	v_mul_f32 v153, v153, v76
	v_mul_f32 v199, v154, v76
	v_mul_f32 v200, v155, v76
	s_waitcnt lgkmcnt(8)
	v_mul_f32 v201, v194, v76
	v_mul_f32 v210, v195, v76
	v_mul_f32 v211, v196, v76
	v_mul_f32 v76, v197, v76
	v_fma_f32 v82, v80, v111, v78
	v_fma_f32 v132, v80, v110, v79
	v_fma_f32 v133, v80, v109, v124
	v_fma_f32 v134, v80, v108, v125
	v_fma_f32 v135, v80, v107, v126
	v_fma_f32 v154, v80, v106, v127
	v_fma_f32 v155, v80, v105, v193
	v_fma_f32 v193, v80, v104, v198
	v_fma_f32 v194, v80, v99, v152
	v_fma_f32 v195, v80, v98, v153
	v_fma_f32 v196, v80, v97, v199
	v_fma_f32 v197, v80, v96, v200
	v_fma_f32 v198, v80, v91, v201
	v_fma_f32 v199, v80, v90, v210
	v_fma_f32 v200, v80, v89, v211
	v_fma_f32 v80, v80, v88, v76
	v_fma_f32 v76, v92, v82, v140
	v_fma_f32 v78, v93, v132, v140
	v_fma_f32 v79, v94, v133, v140
	v_fma_f32 v88, v95, v134, v140
	v_fma_f32 v76, v112, v135, v76
	v_fma_f32 v78, v113, v154, v78
	v_fma_f32 v79, v114, v155, v79
	v_fma_f32 v88, v115, v193, v88
	v_fma_f32 v76, v202, v194, v76
	v_fma_f32 v78, v203, v195, v78
	v_fma_f32 v79, v204, v196, v79
	v_fma_f32 v88, v205, v197, v88
	v_fma_f32 v76, v206, v198, v76
	v_fma_f32 v78, v207, v199, v78
	v_fma_f32 v79, v208, v200, v79
	v_fma_f32 v88, v209, v80, v88
	v_add_f32_e32 v76, v76, v78
	v_add_f32_e32 v78, v79, v88
	v_add_f32_e32 v76, v76, v78
	v_mov_b32_e32 v78, 0
	s_nop 0
	v_add_f32_dpp v76, v76, v76 row_ror:8 row_mask:0xf bank_mask:0xf bound_ctrl:1
	s_nop 1
	v_add_f32_dpp v76, v76, v76 row_ror:4 row_mask:0xf bank_mask:0xf bound_ctrl:1
	s_nop 1
	v_add_f32_dpp v76, v76, v76 row_ror:2 row_mask:0xf bank_mask:0xf bound_ctrl:1
	s_nop 1
	v_mov_b32_dpp v78, v76 row_ror:1 row_mask:0xf bank_mask:0xf
	s_and_saveexec_b64 s[8:9], s[44:45]
	v_add_f32_e32 v76, v76, v78
	ds_write_b32 v189, v76 offset:34560
	s_or_b64 exec, exec, s[8:9]
	v_mul_f32_e32 v201, v83, v77
	ds_read_b128 v[96:99], v188 offset:19072
	ds_read_b128 v[92:95], v188 offset:19328
	ds_read_b128 v[124:127], v188 offset:27264
	ds_read_b128 v[108:111], v188 offset:27520
	ds_read_b128 v[88:91], v188 offset:19584
	ds_read_b128 v[76:79], v188 offset:19840
	ds_read_b128 v[112:115], v188 offset:27776
	ds_read_b128 v[104:107], v188 offset:28032
	ds_read2_b32 v[152:153], v190 offset0:66 offset1:82
	ds_read_b32 v83, v189 offset:33536
	s_waitcnt lgkmcnt(14)
	v_mul_f32 v128, v128, v201
	v_mul_f32 v129, v129, v201
	v_mul_f32 v130, v130, v201
	v_mul_f32 v131, v131, v201
	v_mul_f32 v116, v116, v201
	v_mul_f32 v117, v117, v201
	v_mul_f32 v118, v118, v201
	v_mul_f32 v119, v119, v201
	s_waitcnt lgkmcnt(11)
	v_mul_f32 v120, v120, v201
	v_mul_f32 v121, v121, v201
	v_mul_f32 v122, v122, v201
	v_mul_f32 v123, v123, v201
	s_waitcnt lgkmcnt(10)
	v_mul_f32 v100, v100, v201
	v_mul_f32 v101, v101, v201
	v_mul_f32 v102, v102, v201
	v_mul_f32 v103, v103, v201
	v_fma_f32 v201, v81, v82, v128
	v_fma_f32 v202, v81, v132, v129
	v_fma_f32 v203, v81, v133, v130
	v_fma_f32 v204, v81, v134, v131
	v_fma_f32 v205, v81, v135, v116
	v_fma_f32 v206, v81, v154, v117
	v_fma_f32 v207, v81, v155, v118
	v_fma_f32 v193, v81, v193, v119
	v_fma_f32 v194, v81, v194, v120
	v_fma_f32 v195, v81, v195, v121
	v_fma_f32 v196, v81, v196, v122
	v_fma_f32 v197, v81, v197, v123
	v_fma_f32 v198, v81, v198, v100
	v_fma_f32 v199, v81, v199, v101
	v_fma_f32 v200, v81, v200, v102
	v_fma_f32 v208, v81, v80, v103
	v_fma_f32 v80, v84, v201, v140
	v_fma_f32 v81, v85, v202, v140
	v_fma_f32 v82, v86, v203, v140
	v_fma_f32 v84, v87, v204, v140
	v_fma_f32 v72, v72, v205, v80
	v_fma_f32 v73, v73, v206, v81
	v_fma_f32 v74, v74, v207, v82
	v_fma_f32 v75, v75, v193, v84
	v_fma_f32 v68, v68, v194, v72
	v_fma_f32 v69, v69, v195, v73
	v_fma_f32 v70, v70, v196, v74
	v_fma_f32 v71, v71, v197, v75
	v_fma_f32 v64, v64, v198, v68
	v_fma_f32 v65, v65, v199, v69
	v_fma_f32 v66, v66, v200, v70
	v_fma_f32 v67, v67, v208, v71
	v_add_f32_e32 v64, v64, v65
	v_add_f32_e32 v65, v66, v67
	v_add_f32_e32 v64, v64, v65
	v_mov_b32_e32 v65, 0
	s_nop 0
	v_add_f32_dpp v64, v64, v64 row_ror:8 row_mask:0xf bank_mask:0xf bound_ctrl:1
	s_nop 1
	v_add_f32_dpp v64, v64, v64 row_ror:4 row_mask:0xf bank_mask:0xf bound_ctrl:1
	s_nop 1
	v_add_f32_dpp v64, v64, v64 row_ror:2 row_mask:0xf bank_mask:0xf bound_ctrl:1
	s_nop 1
	v_mov_b32_dpp v65, v64 row_ror:1 row_mask:0xf bank_mask:0xf
	s_and_saveexec_b64 s[8:9], s[44:45]
	v_add_f32_e32 v64, v64, v65
	ds_write_b32 v189, v64 offset:34624
	s_or_b64 exec, exec, s[8:9]
	s_waitcnt lgkmcnt(0)
	v_mul_f32_e32 v69, v153, v83
	ds_read_b128 v[100:103], v188 offset:20096
	ds_read_b128 v[80:83], v188 offset:20352
	ds_read_b128 v[132:135], v188 offset:28288
	ds_read_b128 v[120:123], v188 offset:28544
	ds_read_b128 v[72:75], v188 offset:20608
	ds_read_b128 v[64:67], v188 offset:20864
	ds_read_b128 v[128:131], v188 offset:28800
	ds_read_b128 v[116:119], v188 offset:29056
	ds_read2_b32 v[154:155], v190 offset0:67 offset1:83
	ds_read_b32 v68, v189 offset:33600
	v_mul_f32 v70, v124, v69
	v_mul_f32 v71, v125, v69
	v_mul_f32 v84, v126, v69
	v_mul_f32 v85, v127, v69
	v_mul_f32 v86, v108, v69
	v_mul_f32 v87, v109, v69
	v_mul_f32 v108, v110, v69
	v_mul_f32 v109, v111, v69
	v_mul_f32 v110, v112, v69
	v_mul_f32 v111, v113, v69
	v_mul_f32 v124, v114, v69
	v_mul_f32 v125, v115, v69
	v_mul_f32 v104, v104, v69
	v_mul_f32 v105, v105, v69
	v_mul_f32 v106, v106, v69
	v_mul_f32 v69, v107, v69
	v_fma_f32 v112, v152, v201, v70
	v_fma_f32 v113, v152, v202, v71
	v_fma_f32 v115, v152, v204, v85
	v_fma_f32 v114, v152, v203, v84
	v_fma_f32 v201, v152, v205, v86
	v_fma_f32 v204, v152, v208, v69
	v_fma_f32 v69, v96, v112, v140
	v_fma_f32 v70, v97, v113, v140
	v_fma_f32 v202, v152, v206, v87
	v_fma_f32 v71, v98, v114, v140
	v_fma_f32 v203, v152, v207, v108
	v_fma_f32 v194, v152, v194, v110
	v_fma_f32 v69, v92, v201, v69
	v_fma_f32 v195, v152, v195, v111
	v_fma_f32 v70, v93, v202, v70
	v_fma_f32 v84, v99, v115, v140
	v_fma_f32 v71, v94, v203, v71
	v_fma_f32 v193, v152, v193, v109
	v_fma_f32 v69, v88, v194, v69
	v_fma_f32 v196, v152, v196, v124
	v_fma_f32 v70, v89, v195, v70
	v_fma_f32 v198, v152, v198, v104
	v_fma_f32 v199, v152, v199, v105
	v_fma_f32 v84, v95, v193, v84
	v_fma_f32 v197, v152, v197, v125
	v_fma_f32 v71, v90, v196, v71
	v_fma_f32 v200, v152, v200, v106
	v_fma_f32 v69, v76, v198, v69
	v_fma_f32 v70, v77, v199, v70
	v_fma_f32 v84, v91, v197, v84
	v_fma_f32 v71, v78, v200, v71
	v_fma_f32 v76, v79, v204, v84
	v_add_f32_e32 v69, v69, v70
	v_add_f32_e32 v70, v71, v76
	v_add_f32_e32 v69, v69, v70
	v_mov_b32_e32 v70, 0
	s_nop 0
	v_add_f32_dpp v69, v69, v69 row_ror:8 row_mask:0xf bank_mask:0xf bound_ctrl:1
	s_nop 1
	v_add_f32_dpp v69, v69, v69 row_ror:4 row_mask:0xf bank_mask:0xf bound_ctrl:1
	s_nop 1
	v_add_f32_dpp v69, v69, v69 row_ror:2 row_mask:0xf bank_mask:0xf bound_ctrl:1
	s_nop 1
	v_mov_b32_dpp v70, v69 row_ror:1 row_mask:0xf bank_mask:0xf
	s_and_saveexec_b64 s[8:9], s[44:45]
	v_add_f32_e32 v69, v69, v70
	ds_write_b32 v189, v69 offset:34688
	s_or_b64 exec, exec, s[8:9]
	s_waitcnt lgkmcnt(0)
	v_mul_f32_e32 v93, v155, v68
	ds_read_b128 v[88:91], v188 offset:21120
	ds_read_b128 v[84:87], v188 offset:21376
	ds_read_b128 v[124:127], v188 offset:29312
	ds_read_b128 v[104:107], v188 offset:29568
	ds_read_b128 v[76:79], v188 offset:21632
	ds_read_b128 v[68:71], v188 offset:21888
	ds_read_b128 v[108:111], v188 offset:29824
	ds_read_b128 v[96:99], v188 offset:30080
	ds_read2_b32 v[152:153], v190 offset0:68 offset1:84
	ds_read_b32 v92, v189 offset:33664
	v_mul_f32 v94, v132, v93
	v_mul_f32 v95, v133, v93
	v_mul_f32 v132, v134, v93
	v_mul_f32 v133, v135, v93
	v_mul_f32 v120, v120, v93
	v_mul_f32 v121, v121, v93
	v_mul_f32 v122, v122, v93
	v_mul_f32 v123, v123, v93
	v_mul_f32 v128, v128, v93
	v_mul_f32 v129, v129, v93
	v_mul_f32 v205, v130, v93
	v_mul_f32 v206, v131, v93
	v_mul_f32 v116, v116, v93
	v_mul_f32 v117, v117, v93
	v_mul_f32 v118, v118, v93
	v_mul_f32 v93, v119, v93
	v_fma_f32 v130, v154, v112, v94
	v_fma_f32 v131, v154, v113, v95
	v_fma_f32 v132, v154, v114, v132
	v_fma_f32 v133, v154, v115, v133
	v_fma_f32 v134, v154, v201, v120
	v_fma_f32 v135, v154, v202, v121
	v_fma_f32 v155, v154, v203, v122
	v_fma_f32 v193, v154, v193, v123
	v_fma_f32 v194, v154, v194, v128
	v_fma_f32 v195, v154, v195, v129
	v_fma_f32 v196, v154, v196, v205
	v_fma_f32 v197, v154, v197, v206
	v_fma_f32 v198, v154, v198, v116
	v_fma_f32 v199, v154, v199, v117
	v_fma_f32 v200, v154, v200, v118
	v_fma_f32 v154, v154, v204, v93
	v_fma_f32 v93, v100, v130, v140
	v_fma_f32 v94, v101, v131, v140
	v_fma_f32 v95, v102, v132, v140
	v_fma_f32 v100, v103, v133, v140
	v_fma_f32 v80, v80, v134, v93
	v_fma_f32 v81, v81, v135, v94
	v_fma_f32 v82, v82, v155, v95
	v_fma_f32 v83, v83, v193, v100
	v_fma_f32 v72, v72, v194, v80
	v_fma_f32 v73, v73, v195, v81
	v_fma_f32 v74, v74, v196, v82
	v_fma_f32 v75, v75, v197, v83
	v_fma_f32 v64, v64, v198, v72
	v_fma_f32 v65, v65, v199, v73
	v_fma_f32 v66, v66, v200, v74
	v_fma_f32 v67, v67, v154, v75
	v_add_f32_e32 v64, v64, v65
	v_add_f32_e32 v65, v66, v67
	v_add_f32_e32 v64, v64, v65
	v_mov_b32_e32 v65, 0
	s_nop 0
	v_add_f32_dpp v64, v64, v64 row_ror:8 row_mask:0xf bank_mask:0xf bound_ctrl:1
	s_nop 1
	v_add_f32_dpp v64, v64, v64 row_ror:4 row_mask:0xf bank_mask:0xf bound_ctrl:1
	s_nop 1
	v_add_f32_dpp v64, v64, v64 row_ror:2 row_mask:0xf bank_mask:0xf bound_ctrl:1
	s_nop 1
	v_mov_b32_dpp v65, v64 row_ror:1 row_mask:0xf bank_mask:0xf
	s_and_saveexec_b64 s[8:9], s[44:45]
	v_add_f32_e32 v64, v64, v65
	ds_write_b32 v189, v64 offset:34752
	s_or_b64 exec, exec, s[8:9]
	s_waitcnt lgkmcnt(0)
	v_mul_f32_e32 v153, v153, v92
	ds_read_b128 v[92:95], v188 offset:22144
	ds_read_b128 v[80:83], v188 offset:22400
	ds_read_b128 v[120:123], v188 offset:30336
	ds_read_b128 v[112:115], v188 offset:30592
	ds_read_b128 v[72:75], v188 offset:22656
	ds_read_b128 v[64:67], v188 offset:22912
	ds_read_b128 v[116:119], v188 offset:30848
	ds_read_b128 v[100:103], v188 offset:31104
	ds_read2_b32 v[128:129], v190 offset0:69 offset1:85
	ds_read_b32 v202, v189 offset:33728
	v_mul_f32 v124, v124, v153
	v_mul_f32 v125, v125, v153
	v_mul_f32 v126, v126, v153
	v_mul_f32 v127, v127, v153
	v_mul_f32 v104, v104, v153
	v_mul_f32 v105, v105, v153
	v_mul_f32 v106, v106, v153
	v_mul_f32 v107, v107, v153
	v_mul_f32 v108, v108, v153
	v_mul_f32 v109, v109, v153
	v_mul_f32 v110, v110, v153
	v_mul_f32 v111, v111, v153
	v_mul_f32 v96, v96, v153
	v_mul_f32 v97, v97, v153
	v_mul_f32 v98, v98, v153
	v_mul_f32 v99, v99, v153
	v_fma_f32 v153, v152, v130, v124
	v_fma_f32 v201, v152, v131, v125
	v_fma_f32 v134, v152, v134, v104
	v_fma_f32 v135, v152, v135, v105
	v_fma_f32 v194, v152, v194, v108
	v_fma_f32 v195, v152, v195, v109
	v_fma_f32 v198, v152, v198, v96
	v_fma_f32 v199, v152, v199, v97
	v_fma_f32 v88, v88, v153, v140
	v_fma_f32 v89, v89, v201, v140
	v_fma_f32 v132, v152, v132, v126
	v_fma_f32 v133, v152, v133, v127
	v_fma_f32 v155, v152, v155, v106
	v_fma_f32 v193, v152, v193, v107
	v_fma_f32 v84, v84, v134, v88
	v_fma_f32 v85, v85, v135, v89
	v_fma_f32 v196, v152, v196, v110
	v_fma_f32 v197, v152, v197, v111
	v_fma_f32 v200, v152, v200, v98
	v_fma_f32 v152, v152, v154, v99
	v_fma_f32 v76, v76, v194, v84
	v_fma_f32 v77, v77, v195, v85
	v_fma_f32 v90, v90, v132, v140
	v_fma_f32 v91, v91, v133, v140
	v_fma_f32 v68, v68, v198, v76
	v_fma_f32 v69, v69, v199, v77
	v_fma_f32 v86, v86, v155, v90
	v_fma_f32 v87, v87, v193, v91
	v_fma_f32 v78, v78, v196, v86
	v_fma_f32 v79, v79, v197, v87
	v_add_f32_e32 v68, v68, v69
	v_fma_f32 v70, v70, v200, v78
	v_fma_f32 v71, v71, v152, v79
	v_add_f32_e32 v69, v70, v71
	v_add_f32_e32 v68, v68, v69
	v_mov_b32_e32 v69, 0
	s_nop 0
	v_add_f32_dpp v68, v68, v68 row_ror:8 row_mask:0xf bank_mask:0xf bound_ctrl:1
	s_nop 1
	v_add_f32_dpp v68, v68, v68 row_ror:4 row_mask:0xf bank_mask:0xf bound_ctrl:1
	s_nop 1
	v_add_f32_dpp v68, v68, v68 row_ror:2 row_mask:0xf bank_mask:0xf bound_ctrl:1
	s_nop 1
	v_mov_b32_dpp v69, v68 row_ror:1 row_mask:0xf bank_mask:0xf
	s_and_saveexec_b64 s[8:9], s[44:45]
	v_add_f32_e32 v68, v68, v69
	ds_write_b32 v189, v68 offset:34816
	s_or_b64 exec, exec, s[8:9]
	s_waitcnt lgkmcnt(0)
	v_mul_f32_e32 v154, v129, v202
	ds_read_b128 v[88:91], v188 offset:23168
	ds_read_b128 v[84:87], v188 offset:23424
	ds_read_b128 v[124:127], v188 offset:31360
	ds_read_b128 v[104:107], v188 offset:31616
	ds_read_b128 v[76:79], v188 offset:23680
	ds_read_b128 v[68:71], v188 offset:23936
	ds_read_b128 v[108:111], v188 offset:31872
	ds_read_b128 v[96:99], v188 offset:32128
	ds_read2_b32 v[130:131], v190 offset0:70 offset1:86
	ds_read_b32 v129, v189 offset:33792
	v_mul_f32 v120, v120, v154
	v_mul_f32 v121, v121, v154
	v_mul_f32 v122, v122, v154
	v_mul_f32 v123, v123, v154
	v_mul_f32 v112, v112, v154
	v_mul_f32 v113, v113, v154
	v_mul_f32 v114, v114, v154
	v_mul_f32 v115, v115, v154
	v_mul_f32 v116, v116, v154
	v_mul_f32 v117, v117, v154
	v_mul_f32 v118, v118, v154
	v_mul_f32 v119, v119, v154
	v_mul_f32 v100, v100, v154
	v_mul_f32 v101, v101, v154
	v_mul_f32 v102, v102, v154
	v_mul_f32 v103, v103, v154
	v_fma_f32 v153, v128, v153, v120
	v_fma_f32 v154, v128, v201, v121
	v_fma_f32 v134, v128, v134, v112
	v_fma_f32 v135, v128, v135, v113
	v_fma_f32 v194, v128, v194, v116
	v_fma_f32 v195, v128, v195, v117
	v_fma_f32 v198, v128, v198, v100
	v_fma_f32 v199, v128, v199, v101
	v_fma_f32 v92, v92, v153, v140
	v_fma_f32 v93, v93, v154, v140
	v_fma_f32 v132, v128, v132, v122
	v_fma_f32 v133, v128, v133, v123
	v_fma_f32 v155, v128, v155, v114
	v_fma_f32 v193, v128, v193, v115
	v_fma_f32 v80, v80, v134, v92
	v_fma_f32 v81, v81, v135, v93
	v_fma_f32 v196, v128, v196, v118
	v_fma_f32 v197, v128, v197, v119
	v_fma_f32 v200, v128, v200, v102
	v_fma_f32 v152, v128, v152, v103
	v_fma_f32 v72, v72, v194, v80
	v_fma_f32 v73, v73, v195, v81
	v_fma_f32 v94, v94, v132, v140
	v_fma_f32 v95, v95, v133, v140
	v_fma_f32 v64, v64, v198, v72
	v_fma_f32 v65, v65, v199, v73
	v_fma_f32 v82, v82, v155, v94
	v_fma_f32 v83, v83, v193, v95
	v_fma_f32 v74, v74, v196, v82
	v_fma_f32 v75, v75, v197, v83
	v_add_f32_e32 v64, v64, v65
	v_fma_f32 v66, v66, v200, v74
	v_fma_f32 v67, v67, v152, v75
	v_add_f32_e32 v65, v66, v67
	v_add_f32_e32 v64, v64, v65
	v_mov_b32_e32 v65, 0
	s_nop 0
	v_add_f32_dpp v64, v64, v64 row_ror:8 row_mask:0xf bank_mask:0xf bound_ctrl:1
	s_nop 1
	v_add_f32_dpp v64, v64, v64 row_ror:4 row_mask:0xf bank_mask:0xf bound_ctrl:1
	s_nop 1
	v_add_f32_dpp v64, v64, v64 row_ror:2 row_mask:0xf bank_mask:0xf bound_ctrl:1
	s_nop 1
	v_mov_b32_dpp v65, v64 row_ror:1 row_mask:0xf bank_mask:0xf
	s_and_saveexec_b64 s[8:9], s[44:45]
	v_add_f32_e32 v64, v64, v65
	ds_write_b32 v189, v64 offset:34880
	s_or_b64 exec, exec, s[8:9]
	s_waitcnt lgkmcnt(0)
	v_mul_f32_e32 v201, v131, v129
	ds_read_b128 v[92:95], v188 offset:24192
	ds_read_b128 v[80:83], v188 offset:24448
	ds_read_b128 v[120:123], v188 offset:32384
	ds_read_b128 v[112:115], v188 offset:32640
	ds_read_b128 v[72:75], v188 offset:24704
	ds_read_b128 v[64:67], v188 offset:24960
	ds_read_b128 v[116:119], v188 offset:32896
	ds_read_b128 v[100:103], v188 offset:33152
	ds_read2_b32 v[128:129], v190 offset0:71 offset1:87
	ds_read_b32 v131, v189 offset:33856
	v_mul_f32 v125, v125, v201
	v_mul_f32 v126, v126, v201
	v_mul_f32 v104, v104, v201
	v_mul_f32 v124, v124, v201
	v_mul_f32 v127, v127, v201
	v_mul_f32 v105, v105, v201
	v_mul_f32 v106, v106, v201
	v_mul_f32 v107, v107, v201
	v_mul_f32 v108, v108, v201
	v_mul_f32 v109, v109, v201
	v_mul_f32 v202, v110, v201
	v_mul_f32 v203, v111, v201
	v_mul_f32 v204, v96, v201
	v_mul_f32 v205, v97, v201
	v_mul_f32 v206, v98, v201
	v_mul_f32 v201, v99, v201
	v_fma_f32 v96, v130, v153, v124
	v_fma_f32 v97, v130, v154, v125
	v_fma_f32 v98, v130, v132, v126
	v_fma_f32 v99, v130, v133, v127
	v_fma_f32 v104, v130, v134, v104
	v_fma_f32 v110, v130, v135, v105
	v_fma_f32 v125, v130, v194, v108
	v_fma_f32 v126, v130, v195, v109
	v_fma_f32 v133, v130, v198, v204
	v_fma_f32 v134, v130, v199, v205
	v_fma_f32 v88, v88, v96, v140
	v_fma_f32 v89, v89, v97, v140
	v_fma_f32 v111, v130, v155, v106
	v_fma_f32 v124, v130, v193, v107
	v_fma_f32 v127, v130, v196, v202
	v_fma_f32 v132, v130, v197, v203
	v_fma_f32 v84, v84, v104, v88
	v_fma_f32 v85, v85, v110, v89
	v_fma_f32 v135, v130, v200, v206
	v_fma_f32 v130, v130, v152, v201
	v_fma_f32 v90, v90, v98, v140
	v_fma_f32 v91, v91, v99, v140
	v_fma_f32 v76, v76, v125, v84
	v_fma_f32 v77, v77, v126, v85
	v_fma_f32 v68, v68, v133, v76
	v_fma_f32 v69, v69, v134, v77
	v_fma_f32 v86, v86, v111, v90
	v_fma_f32 v87, v87, v124, v91
	v_fma_f32 v78, v78, v127, v86
	v_fma_f32 v79, v79, v132, v87
	v_add_f32_e32 v68, v68, v69
	v_fma_f32 v70, v70, v135, v78
	v_fma_f32 v71, v71, v130, v79
	v_add_f32_e32 v69, v70, v71
	v_add_f32_e32 v68, v68, v69
	v_mov_b32_e32 v69, 0
	s_nop 0
	v_add_f32_dpp v68, v68, v68 row_ror:8 row_mask:0xf bank_mask:0xf bound_ctrl:1
	s_nop 1
	v_add_f32_dpp v68, v68, v68 row_ror:4 row_mask:0xf bank_mask:0xf bound_ctrl:1
	s_nop 1
	v_add_f32_dpp v68, v68, v68 row_ror:2 row_mask:0xf bank_mask:0xf bound_ctrl:1
	s_nop 1
	v_mov_b32_dpp v69, v68 row_ror:1 row_mask:0xf bank_mask:0xf
	s_and_saveexec_b64 s[8:9], s[44:45]
	v_add_f32_e32 v68, v68, v69
	ds_write_b32 v189, v68 offset:34944
	s_or_b64 exec, exec, s[8:9]
	s_waitcnt lgkmcnt(0)
	v_mul_f32_e32 v68, v129, v131
	v_mul_f32 v69, v120, v68
	v_mul_f32 v70, v121, v68
	v_mul_f32 v71, v122, v68
	v_mul_f32 v76, v123, v68
	v_mul_f32 v77, v112, v68
	v_mul_f32 v78, v113, v68
	v_mul_f32 v79, v114, v68
	v_mul_f32 v84, v115, v68
	v_mul_f32 v85, v116, v68
	v_mul_f32 v86, v117, v68
	v_mul_f32 v87, v118, v68
	v_mul_f32 v88, v119, v68
	v_mul_f32 v89, v100, v68
	v_mul_f32 v100, v101, v68
	v_mul_f32 v101, v102, v68
	v_mul_f32 v68, v103, v68
	v_fma_f32 v109, v128, v96, v69
	v_fma_f32 v108, v128, v97, v70
	v_fma_f32 v105, v128, v104, v77
	v_fma_f32 v104, v128, v110, v78
	v_fma_f32 v107, v128, v98, v71
	v_fma_f32 v78, v128, v130, v68
	v_fma_f32 v68, v92, v109, v140
	v_fma_f32 v69, v93, v108, v140
	v_fma_f32 v106, v128, v99, v76
	v_fma_f32 v99, v128, v111, v79
	v_fma_f32 v70, v94, v107, v140
	v_fma_f32 v98, v128, v124, v84
	v_fma_f32 v68, v80, v105, v68
	v_fma_f32 v69, v81, v104, v69
	v_fma_f32 v71, v95, v106, v140
	v_fma_f32 v97, v128, v125, v85
	v_fma_f32 v96, v128, v126, v86
	v_fma_f32 v90, v128, v132, v88
	v_fma_f32 v89, v128, v133, v89
	v_fma_f32 v88, v128, v134, v100
	v_fma_f32 v70, v82, v99, v70
	v_fma_f32 v71, v83, v98, v71
	v_fma_f32 v68, v72, v97, v68
	v_fma_f32 v69, v73, v96, v69
	v_fma_f32 v91, v128, v127, v87
	v_fma_f32 v79, v128, v135, v101
	v_fma_f32 v71, v75, v90, v71
	v_fma_f32 v64, v64, v89, v68
	v_fma_f32 v65, v65, v88, v69
	v_fma_f32 v70, v74, v91, v70
	v_fma_f32 v66, v66, v79, v70
	v_fma_f32 v67, v67, v78, v71
	v_add_f32_e32 v64, v64, v65
	v_add_f32_e32 v65, v66, v67
	v_add_f32_e32 v64, v64, v65
	v_mov_b32_e32 v65, 0
	s_nop 0
	v_add_f32_dpp v64, v64, v64 row_ror:8 row_mask:0xf bank_mask:0xf bound_ctrl:1
	s_nop 1
	v_add_f32_dpp v64, v64, v64 row_ror:4 row_mask:0xf bank_mask:0xf bound_ctrl:1
	s_nop 1
	v_add_f32_dpp v64, v64, v64 row_ror:2 row_mask:0xf bank_mask:0xf bound_ctrl:1
	s_nop 1
	v_mov_b32_dpp v65, v64 row_ror:1 row_mask:0xf bank_mask:0xf
	s_and_saveexec_b64 s[8:9], s[44:45]
	v_add_f32_e32 v64, v64, v65
	ds_write_b32 v189, v64 offset:35008
	s_or_b64 exec, exec, s[8:9]
	s_waitcnt vmcnt(7)
	ds_write_b128 v185, v[32:35]
	s_waitcnt vmcnt(5)
	ds_write_b128 v186, v[40:43]
	ds_write_b128 v185, v[36:39] offset:8192
	s_waitcnt vmcnt(4)
	ds_write_b128 v186, v[44:47] offset:8192
	s_and_saveexec_b64 s[8:9], s[42:43]
	ds_write_b32 v144, v184 offset:16384
	s_or_b64 exec, exec, s[8:9]
	s_and_saveexec_b64 s[8:9], s[40:41]
	s_cbranch_execz .LBB0_1505
	v_add_f32_e32 v64, v156, v182
	v_mul_f32_e64 v65, |v64|, s62
	v_exp_f32_e32 v65, v65
	v_min_f32_e32 v64, 0, v64
	v_add_f32_e32 v65, 1.0, v65
	v_cmp_gt_f32_e32 vcc, s5, v65
	s_nop 1
	v_cndmask_b32_e64 v66, 0, 32, vcc
	v_ldexp_f32 v65, v65, v66
	v_log_f32_e32 v65, v65
	v_cndmask_b32_e32 v67, 0, v171, vcc
	v_add_f32_e32 v66, v145, v180
	v_mul_f32_e32 v68, 0x3f317217, v65
	v_fma_f32 v68, v65, s76, -v68
	v_fmac_f32_e32 v68, 0x3377d1cf, v65
	v_fmac_f32_e32 v68, 0x3f317217, v65
	v_cmp_lt_f32_e64 vcc, |v65|, s77
	s_nop 1
	v_cndmask_b32_e32 v65, v65, v68, vcc
	v_sub_f32_e32 v65, v65, v67
	v_sub_f32_e32 v64, v64, v65
	v_add_u32_e32 v65, 0x4000, v144
	ds_write2_b32 v65, v66, v64 offset0:128 offset1:144

.LBB0_1516:
	s_or_b64 exec, exec, s[8:9]
	s_waitcnt lgkmcnt(0)
	s_barrier
	ds_read_b128 v[92:95], v188
	ds_read_b128 v[110:113], v188 offset:256
	ds_read_b128 v[124:127], v188 offset:8192
	ds_read_b128 v[132:135], v188 offset:8448
	ds_read2_b64 v[80:83], v190 offset0:32 offset1:40
	ds_read2_b32 v[76:77], v192 offset1:16
	ds_read_b128 v[200:203], v188 offset:512
	ds_read_b128 v[204:207], v188 offset:768
	ds_read_b128 v[152:155], v188 offset:8704
	ds_read_b128 v[192:195], v188 offset:8960
	s_waitcnt lgkmcnt(4)
	v_mul_f32_e32 v76, v82, v76
	v_mul_f32 v82, v124, v76
	v_mul_f32 v114, v125, v76
	v_mul_f32 v115, v126, v76
	v_mul_f32 v124, v127, v76
	v_mul_f32 v125, v132, v76
	v_mul_f32 v126, v133, v76
	v_mul_f32 v127, v134, v76
	v_mul_f32 v196, v135, v76
	s_waitcnt lgkmcnt(1)
	v_mul_f32 v152, v152, v76
	v_mul_f32 v153, v153, v76
	v_mul_f32 v197, v154, v76
	v_mul_f32 v198, v155, v76
	s_waitcnt lgkmcnt(0)
	v_mul_f32 v199, v192, v76
	v_mul_f32 v208, v193, v76
	v_mul_f32 v209, v194, v76
	v_mul_f32 v76, v195, v76
	ds_read_b128 v[84:87], v188 offset:1024
	ds_read_b128 v[72:75], v188 offset:1280
	ds_read_b128 v[128:131], v188 offset:9216
	ds_read_b128 v[116:119], v188 offset:9472
	ds_read_b128 v[68:71], v188 offset:1536
	ds_read_b128 v[64:67], v188 offset:1792
	ds_read_b128 v[120:123], v188 offset:9728
	ds_read_b128 v[100:103], v188 offset:9984
	v_fma_f32 v82, v80, v109, v82
	v_fma_f32 v132, v80, v108, v114
	v_fma_f32 v133, v80, v107, v115
	v_fma_f32 v134, v80, v106, v124
	v_fma_f32 v135, v80, v105, v125
	v_fma_f32 v154, v80, v104, v126
	v_fma_f32 v155, v80, v99, v127
	v_fma_f32 v192, v80, v98, v196
	v_fma_f32 v193, v80, v97, v152
	v_fma_f32 v194, v80, v96, v153
	v_fma_f32 v195, v80, v91, v197
	v_fma_f32 v196, v80, v90, v198
	v_fma_f32 v197, v80, v89, v199
	v_fma_f32 v198, v80, v88, v208
	v_fma_f32 v199, v80, v79, v209
	v_fma_f32 v80, v80, v78, v76
	v_fma_f32 v76, v92, v82, v140
	v_fma_f32 v78, v93, v132, v140
	v_fma_f32 v79, v94, v133, v140
	v_fma_f32 v88, v95, v134, v140
	v_fma_f32 v76, v110, v135, v76
	v_fma_f32 v78, v111, v154, v78
	v_fma_f32 v79, v112, v155, v79
	v_fma_f32 v88, v113, v192, v88
	v_fma_f32 v76, v200, v193, v76
	v_fma_f32 v78, v201, v194, v78
	v_fma_f32 v79, v202, v195, v79
	v_fma_f32 v88, v203, v196, v88
	v_fma_f32 v76, v204, v197, v76
	v_fma_f32 v78, v205, v198, v78
	v_fma_f32 v79, v206, v199, v79
	v_fma_f32 v88, v207, v80, v88
	v_add_f32_e32 v76, v76, v78
	v_add_f32_e32 v78, v79, v88
	v_add_f32_e32 v76, v76, v78
	v_mov_b32_e32 v78, 0
	s_nop 0
	v_add_f32_dpp v76, v76, v76 row_ror:8 row_mask:0xf bank_mask:0xf bound_ctrl:1
	s_nop 1
	v_add_f32_dpp v76, v76, v76 row_ror:4 row_mask:0xf bank_mask:0xf bound_ctrl:1
	s_nop 1
	v_add_f32_dpp v76, v76, v76 row_ror:2 row_mask:0xf bank_mask:0xf bound_ctrl:1
	s_nop 1
	v_mov_b32_dpp v78, v76 row_ror:1 row_mask:0xf bank_mask:0xf
	s_and_saveexec_b64 s[8:9], s[44:45]
	v_add_f32_e32 v76, v76, v78
	ds_write_b32 v189, v76 offset:34048
	s_or_b64 exec, exec, s[8:9]
	v_mul_f32_e32 v200, v83, v77
	ds_read_b128 v[96:99], v188 offset:2048
	ds_read_b128 v[92:95], v188 offset:2304
	ds_read_b128 v[124:127], v188 offset:10240
	ds_read_b128 v[108:111], v188 offset:10496
	ds_read_b128 v[88:91], v188 offset:2560
	ds_read_b128 v[76:79], v188 offset:2816
	ds_read_b128 v[112:115], v188 offset:10752
	ds_read_b128 v[104:107], v188 offset:11008
	ds_read2_b32 v[152:153], v190 offset0:66 offset1:82
	ds_read_b32 v83, v189 offset:16512
	s_waitcnt lgkmcnt(14)
	v_mul_f32 v128, v128, v200
	v_mul_f32 v129, v129, v200
	v_mul_f32 v130, v130, v200
	v_mul_f32 v131, v131, v200
	v_mul_f32 v116, v116, v200
	v_mul_f32 v117, v117, v200
	v_mul_f32 v118, v118, v200
	v_mul_f32 v119, v119, v200
	s_waitcnt lgkmcnt(11)
	v_mul_f32 v120, v120, v200
	v_mul_f32 v121, v121, v200
	v_mul_f32 v122, v122, v200
	v_mul_f32 v123, v123, v200
	s_waitcnt lgkmcnt(10)
	v_mul_f32 v100, v100, v200
	v_mul_f32 v101, v101, v200
	v_mul_f32 v102, v102, v200
	v_mul_f32 v103, v103, v200
	v_fma_f32 v200, v81, v82, v128
	v_fma_f32 v201, v81, v132, v129
	v_fma_f32 v202, v81, v133, v130
	v_fma_f32 v203, v81, v134, v131
	v_fma_f32 v204, v81, v135, v116
	v_fma_f32 v205, v81, v154, v117
	v_fma_f32 v206, v81, v155, v118
	v_fma_f32 v192, v81, v192, v119
	v_fma_f32 v193, v81, v193, v120
	v_fma_f32 v194, v81, v194, v121
	v_fma_f32 v195, v81, v195, v122
	v_fma_f32 v196, v81, v196, v123
	v_fma_f32 v197, v81, v197, v100
	v_fma_f32 v198, v81, v198, v101
	v_fma_f32 v199, v81, v199, v102
	v_fma_f32 v207, v81, v80, v103
	v_fma_f32 v80, v84, v200, v140
	v_fma_f32 v81, v85, v201, v140
	v_fma_f32 v82, v86, v202, v140
	v_fma_f32 v84, v87, v203, v140
	v_fma_f32 v72, v72, v204, v80
	v_fma_f32 v73, v73, v205, v81
	v_fma_f32 v74, v74, v206, v82
	v_fma_f32 v75, v75, v192, v84
	v_fma_f32 v68, v68, v193, v72
	v_fma_f32 v69, v69, v194, v73
	v_fma_f32 v70, v70, v195, v74
	v_fma_f32 v71, v71, v196, v75
	v_fma_f32 v64, v64, v197, v68
	v_fma_f32 v65, v65, v198, v69
	v_fma_f32 v66, v66, v199, v70
	v_fma_f32 v67, v67, v207, v71
	v_add_f32_e32 v64, v64, v65
	v_add_f32_e32 v65, v66, v67
	v_add_f32_e32 v64, v64, v65
	v_mov_b32_e32 v65, 0
	s_nop 0
	v_add_f32_dpp v64, v64, v64 row_ror:8 row_mask:0xf bank_mask:0xf bound_ctrl:1
	s_nop 1
	v_add_f32_dpp v64, v64, v64 row_ror:4 row_mask:0xf bank_mask:0xf bound_ctrl:1
	s_nop 1
	v_add_f32_dpp v64, v64, v64 row_ror:2 row_mask:0xf bank_mask:0xf bound_ctrl:1
	s_nop 1
	v_mov_b32_dpp v65, v64 row_ror:1 row_mask:0xf bank_mask:0xf
	s_and_saveexec_b64 s[8:9], s[44:45]
	v_add_f32_e32 v64, v64, v65
	ds_write_b32 v189, v64 offset:34112
	s_or_b64 exec, exec, s[8:9]
	s_waitcnt lgkmcnt(0)
	v_mul_f32_e32 v69, v153, v83
	ds_read_b128 v[100:103], v188 offset:3072
	ds_read_b128 v[80:83], v188 offset:3328
	ds_read_b128 v[132:135], v188 offset:11264
	ds_read_b128 v[120:123], v188 offset:11520
	ds_read_b128 v[72:75], v188 offset:3584
	ds_read_b128 v[64:67], v188 offset:3840
	ds_read_b128 v[128:131], v188 offset:11776
	ds_read_b128 v[116:119], v188 offset:12032
	ds_read2_b32 v[154:155], v190 offset0:67 offset1:83
	ds_read_b32 v68, v189 offset:16576
	v_mul_f32 v70, v124, v69
	v_mul_f32 v71, v125, v69
	v_mul_f32 v84, v126, v69
	v_mul_f32 v85, v127, v69
	v_mul_f32 v86, v108, v69
	v_mul_f32 v87, v109, v69
	v_mul_f32 v108, v110, v69
	v_mul_f32 v109, v111, v69
	v_mul_f32 v110, v112, v69
	v_mul_f32 v111, v113, v69
	v_mul_f32 v124, v114, v69
	v_mul_f32 v125, v115, v69
	v_mul_f32 v104, v104, v69
	v_mul_f32 v105, v105, v69
	v_mul_f32 v106, v106, v69
	v_mul_f32 v69, v107, v69
	v_fma_f32 v112, v152, v200, v70
	v_fma_f32 v113, v152, v201, v71
	v_fma_f32 v115, v152, v203, v85
	v_fma_f32 v114, v152, v202, v84
	v_fma_f32 v200, v152, v204, v86
	v_fma_f32 v203, v152, v207, v69
	v_fma_f32 v69, v96, v112, v140
	v_fma_f32 v70, v97, v113, v140
	v_fma_f32 v201, v152, v205, v87
	v_fma_f32 v71, v98, v114, v140
	v_fma_f32 v202, v152, v206, v108
	v_fma_f32 v193, v152, v193, v110
	v_fma_f32 v69, v92, v200, v69
	v_fma_f32 v194, v152, v194, v111
	v_fma_f32 v70, v93, v201, v70
	v_fma_f32 v84, v99, v115, v140
	v_fma_f32 v71, v94, v202, v71
	v_fma_f32 v192, v152, v192, v109
	v_fma_f32 v69, v88, v193, v69
	v_fma_f32 v195, v152, v195, v124
	v_fma_f32 v70, v89, v194, v70
	v_fma_f32 v197, v152, v197, v104
	v_fma_f32 v198, v152, v198, v105
	v_fma_f32 v84, v95, v192, v84
	v_fma_f32 v196, v152, v196, v125
	v_fma_f32 v71, v90, v195, v71
	v_fma_f32 v199, v152, v199, v106
	v_fma_f32 v69, v76, v197, v69
	v_fma_f32 v70, v77, v198, v70
	v_fma_f32 v84, v91, v196, v84
	v_fma_f32 v71, v78, v199, v71
	v_fma_f32 v76, v79, v203, v84
	v_add_f32_e32 v69, v69, v70
	v_add_f32_e32 v70, v71, v76
	v_add_f32_e32 v69, v69, v70
	v_mov_b32_e32 v70, 0
	s_nop 0
	v_add_f32_dpp v69, v69, v69 row_ror:8 row_mask:0xf bank_mask:0xf bound_ctrl:1
	s_nop 1
	v_add_f32_dpp v69, v69, v69 row_ror:4 row_mask:0xf bank_mask:0xf bound_ctrl:1
	s_nop 1
	v_add_f32_dpp v69, v69, v69 row_ror:2 row_mask:0xf bank_mask:0xf bound_ctrl:1
	s_nop 1
	v_mov_b32_dpp v70, v69 row_ror:1 row_mask:0xf bank_mask:0xf
	s_and_saveexec_b64 s[8:9], s[44:45]
	v_add_f32_e32 v69, v69, v70
	ds_write_b32 v189, v69 offset:34176
	s_or_b64 exec, exec, s[8:9]
	s_waitcnt lgkmcnt(0)
	v_mul_f32_e32 v93, v155, v68
	ds_read_b128 v[88:91], v188 offset:4096
	ds_read_b128 v[84:87], v188 offset:4352
	ds_read_b128 v[124:127], v188 offset:12288
	ds_read_b128 v[104:107], v188 offset:12544
	ds_read_b128 v[76:79], v188 offset:4608
	ds_read_b128 v[68:71], v188 offset:4864
	ds_read_b128 v[108:111], v188 offset:12800
	ds_read_b128 v[96:99], v188 offset:13056
	ds_read2_b32 v[152:153], v190 offset0:68 offset1:84
	ds_read_b32 v92, v189 offset:16640
	v_mul_f32 v94, v132, v93
	v_mul_f32 v95, v133, v93
	v_mul_f32 v132, v134, v93
	v_mul_f32 v133, v135, v93
	v_mul_f32 v120, v120, v93
	v_mul_f32 v121, v121, v93
	v_mul_f32 v122, v122, v93
	v_mul_f32 v123, v123, v93
	v_mul_f32 v128, v128, v93
	v_mul_f32 v129, v129, v93
	v_mul_f32 v204, v130, v93
	v_mul_f32 v205, v131, v93
	v_mul_f32 v116, v116, v93
	v_mul_f32 v117, v117, v93
	v_mul_f32 v118, v118, v93
	v_mul_f32 v93, v119, v93
	v_fma_f32 v130, v154, v112, v94
	v_fma_f32 v131, v154, v113, v95
	v_fma_f32 v132, v154, v114, v132
	v_fma_f32 v133, v154, v115, v133
	v_fma_f32 v134, v154, v200, v120
	v_fma_f32 v135, v154, v201, v121
	v_fma_f32 v155, v154, v202, v122
	v_fma_f32 v192, v154, v192, v123
	v_fma_f32 v193, v154, v193, v128
	v_fma_f32 v194, v154, v194, v129
	v_fma_f32 v195, v154, v195, v204
	v_fma_f32 v196, v154, v196, v205
	v_fma_f32 v197, v154, v197, v116
	v_fma_f32 v198, v154, v198, v117
	v_fma_f32 v199, v154, v199, v118
	v_fma_f32 v154, v154, v203, v93
	v_fma_f32 v93, v100, v130, v140
	v_fma_f32 v94, v101, v131, v140
	v_fma_f32 v95, v102, v132, v140
	v_fma_f32 v100, v103, v133, v140
	v_fma_f32 v80, v80, v134, v93
	v_fma_f32 v81, v81, v135, v94
	v_fma_f32 v82, v82, v155, v95
	v_fma_f32 v83, v83, v192, v100
	v_fma_f32 v72, v72, v193, v80
	v_fma_f32 v73, v73, v194, v81
	v_fma_f32 v74, v74, v195, v82
	v_fma_f32 v75, v75, v196, v83
	v_fma_f32 v64, v64, v197, v72
	v_fma_f32 v65, v65, v198, v73
	v_fma_f32 v66, v66, v199, v74
	v_fma_f32 v67, v67, v154, v75
	v_add_f32_e32 v64, v64, v65
	v_add_f32_e32 v65, v66, v67
	v_add_f32_e32 v64, v64, v65
	v_mov_b32_e32 v65, 0
	s_nop 0
	v_add_f32_dpp v64, v64, v64 row_ror:8 row_mask:0xf bank_mask:0xf bound_ctrl:1
	s_nop 1
	v_add_f32_dpp v64, v64, v64 row_ror:4 row_mask:0xf bank_mask:0xf bound_ctrl:1
	s_nop 1
	v_add_f32_dpp v64, v64, v64 row_ror:2 row_mask:0xf bank_mask:0xf bound_ctrl:1
	s_nop 1
	v_mov_b32_dpp v65, v64 row_ror:1 row_mask:0xf bank_mask:0xf
	s_and_saveexec_b64 s[8:9], s[44:45]
	v_add_f32_e32 v64, v64, v65
	ds_write_b32 v189, v64 offset:34240
	s_or_b64 exec, exec, s[8:9]
	s_waitcnt lgkmcnt(0)
	v_mul_f32_e32 v153, v153, v92
	ds_read_b128 v[92:95], v188 offset:5120
	ds_read_b128 v[80:83], v188 offset:5376
	ds_read_b128 v[120:123], v188 offset:13312
	ds_read_b128 v[112:115], v188 offset:13568
	ds_read_b128 v[72:75], v188 offset:5632
	ds_read_b128 v[64:67], v188 offset:5888
	ds_read_b128 v[116:119], v188 offset:13824
	ds_read_b128 v[100:103], v188 offset:14080
	ds_read2_b32 v[128:129], v190 offset0:69 offset1:85
	ds_read_b32 v201, v189 offset:16704
	v_mul_f32 v124, v124, v153
	v_mul_f32 v125, v125, v153
	v_mul_f32 v126, v126, v153
	v_mul_f32 v127, v127, v153
	v_mul_f32 v104, v104, v153
	v_mul_f32 v105, v105, v153
	v_mul_f32 v106, v106, v153
	v_mul_f32 v107, v107, v153
	v_mul_f32 v108, v108, v153
	v_mul_f32 v109, v109, v153
	v_mul_f32 v110, v110, v153
	v_mul_f32 v111, v111, v153
	v_mul_f32 v96, v96, v153
	v_mul_f32 v97, v97, v153
	v_mul_f32 v98, v98, v153
	v_mul_f32 v99, v99, v153
	v_fma_f32 v153, v152, v130, v124
	v_fma_f32 v200, v152, v131, v125
	v_fma_f32 v134, v152, v134, v104
	v_fma_f32 v135, v152, v135, v105
	v_fma_f32 v193, v152, v193, v108
	v_fma_f32 v194, v152, v194, v109
	v_fma_f32 v197, v152, v197, v96
	v_fma_f32 v198, v152, v198, v97
	v_fma_f32 v88, v88, v153, v140
	v_fma_f32 v89, v89, v200, v140
	v_fma_f32 v132, v152, v132, v126
	v_fma_f32 v133, v152, v133, v127
	v_fma_f32 v155, v152, v155, v106
	v_fma_f32 v192, v152, v192, v107
	v_fma_f32 v84, v84, v134, v88
	v_fma_f32 v85, v85, v135, v89
	v_fma_f32 v195, v152, v195, v110
	v_fma_f32 v196, v152, v196, v111
	v_fma_f32 v199, v152, v199, v98
	v_fma_f32 v152, v152, v154, v99
	v_fma_f32 v76, v76, v193, v84
	v_fma_f32 v77, v77, v194, v85
	v_fma_f32 v90, v90, v132, v140
	v_fma_f32 v91, v91, v133, v140
	v_fma_f32 v68, v68, v197, v76
	v_fma_f32 v69, v69, v198, v77
	v_fma_f32 v86, v86, v155, v90
	v_fma_f32 v87, v87, v192, v91
	v_fma_f32 v78, v78, v195, v86
	v_fma_f32 v79, v79, v196, v87
	v_add_f32_e32 v68, v68, v69
	v_fma_f32 v70, v70, v199, v78
	v_fma_f32 v71, v71, v152, v79
	v_add_f32_e32 v69, v70, v71
	v_add_f32_e32 v68, v68, v69
	v_mov_b32_e32 v69, 0
	s_nop 0
	v_add_f32_dpp v68, v68, v68 row_ror:8 row_mask:0xf bank_mask:0xf bound_ctrl:1
	s_nop 1
	v_add_f32_dpp v68, v68, v68 row_ror:4 row_mask:0xf bank_mask:0xf bound_ctrl:1
	s_nop 1
	v_add_f32_dpp v68, v68, v68 row_ror:2 row_mask:0xf bank_mask:0xf bound_ctrl:1
	s_nop 1
	v_mov_b32_dpp v69, v68 row_ror:1 row_mask:0xf bank_mask:0xf
	s_and_saveexec_b64 s[8:9], s[44:45]
	v_add_f32_e32 v68, v68, v69
	ds_write_b32 v189, v68 offset:34304
	s_or_b64 exec, exec, s[8:9]
	s_waitcnt lgkmcnt(0)
	v_mul_f32_e32 v154, v129, v201
	ds_read_b128 v[88:91], v188 offset:6144
	ds_read_b128 v[84:87], v188 offset:6400
	ds_read_b128 v[124:127], v188 offset:14336
	ds_read_b128 v[104:107], v188 offset:14592
	ds_read_b128 v[76:79], v188 offset:6656
	ds_read_b128 v[68:71], v188 offset:6912
	ds_read_b128 v[108:111], v188 offset:14848
	ds_read_b128 v[96:99], v188 offset:15104
	ds_read2_b32 v[130:131], v190 offset0:70 offset1:86
	ds_read_b32 v129, v189 offset:16768
	v_mul_f32 v120, v120, v154
	v_mul_f32 v121, v121, v154
	v_mul_f32 v122, v122, v154
	v_mul_f32 v123, v123, v154
	v_mul_f32 v112, v112, v154
	v_mul_f32 v113, v113, v154
	v_mul_f32 v114, v114, v154
	v_mul_f32 v115, v115, v154
	v_mul_f32 v116, v116, v154
	v_mul_f32 v117, v117, v154
	v_mul_f32 v118, v118, v154
	v_mul_f32 v119, v119, v154
	v_mul_f32 v100, v100, v154
	v_mul_f32 v101, v101, v154
	v_mul_f32 v102, v102, v154
	v_mul_f32 v103, v103, v154
	v_fma_f32 v153, v128, v153, v120
	v_fma_f32 v154, v128, v200, v121
	v_fma_f32 v134, v128, v134, v112
	v_fma_f32 v135, v128, v135, v113
	v_fma_f32 v193, v128, v193, v116
	v_fma_f32 v194, v128, v194, v117
	v_fma_f32 v197, v128, v197, v100
	v_fma_f32 v198, v128, v198, v101
	v_fma_f32 v92, v92, v153, v140
	v_fma_f32 v93, v93, v154, v140
	v_fma_f32 v132, v128, v132, v122
	v_fma_f32 v133, v128, v133, v123
	v_fma_f32 v155, v128, v155, v114
	v_fma_f32 v192, v128, v192, v115
	v_fma_f32 v80, v80, v134, v92
	v_fma_f32 v81, v81, v135, v93
	v_fma_f32 v195, v128, v195, v118
	v_fma_f32 v196, v128, v196, v119
	v_fma_f32 v199, v128, v199, v102
	v_fma_f32 v152, v128, v152, v103
	v_fma_f32 v72, v72, v193, v80
	v_fma_f32 v73, v73, v194, v81
	v_fma_f32 v94, v94, v132, v140
	v_fma_f32 v95, v95, v133, v140
	v_fma_f32 v64, v64, v197, v72
	v_fma_f32 v65, v65, v198, v73
	v_fma_f32 v82, v82, v155, v94
	v_fma_f32 v83, v83, v192, v95
	v_fma_f32 v74, v74, v195, v82
	v_fma_f32 v75, v75, v196, v83
	v_add_f32_e32 v64, v64, v65
	v_fma_f32 v66, v66, v199, v74
	v_fma_f32 v67, v67, v152, v75
	v_add_f32_e32 v65, v66, v67
	v_add_f32_e32 v64, v64, v65
	v_mov_b32_e32 v65, 0
	s_nop 0
	v_add_f32_dpp v64, v64, v64 row_ror:8 row_mask:0xf bank_mask:0xf bound_ctrl:1
	s_nop 1
	v_add_f32_dpp v64, v64, v64 row_ror:4 row_mask:0xf bank_mask:0xf bound_ctrl:1
	s_nop 1
	v_add_f32_dpp v64, v64, v64 row_ror:2 row_mask:0xf bank_mask:0xf bound_ctrl:1
	s_nop 1
	v_mov_b32_dpp v65, v64 row_ror:1 row_mask:0xf bank_mask:0xf
	s_and_saveexec_b64 s[8:9], s[44:45]
	v_add_f32_e32 v64, v64, v65
	ds_write_b32 v189, v64 offset:34368
	s_or_b64 exec, exec, s[8:9]
	s_waitcnt lgkmcnt(0)
	v_mul_f32_e32 v200, v131, v129
	ds_read_b128 v[92:95], v188 offset:7168
	ds_read_b128 v[80:83], v188 offset:7424
	ds_read_b128 v[120:123], v188 offset:15360
	ds_read_b128 v[112:115], v188 offset:15616
	ds_read_b128 v[72:75], v188 offset:7680
	ds_read_b128 v[64:67], v188 offset:7936
	ds_read_b128 v[116:119], v188 offset:15872
	ds_read_b128 v[100:103], v188 offset:16128
	ds_read2_b32 v[128:129], v190 offset0:71 offset1:87
	ds_read_b32 v131, v189 offset:16832
	v_mul_f32 v125, v125, v200
	v_mul_f32 v126, v126, v200
	v_mul_f32 v104, v104, v200
	v_mul_f32 v124, v124, v200
	v_mul_f32 v127, v127, v200
	v_mul_f32 v105, v105, v200
	v_mul_f32 v106, v106, v200
	v_mul_f32 v107, v107, v200
	v_mul_f32 v108, v108, v200
	v_mul_f32 v109, v109, v200
	v_mul_f32 v201, v110, v200
	v_mul_f32 v202, v111, v200
	v_mul_f32 v203, v96, v200
	v_mul_f32 v204, v97, v200
	v_mul_f32 v205, v98, v200
	v_mul_f32 v200, v99, v200
	v_fma_f32 v96, v130, v153, v124
	v_fma_f32 v97, v130, v154, v125
	v_fma_f32 v98, v130, v132, v126
	v_fma_f32 v99, v130, v133, v127
	v_fma_f32 v104, v130, v134, v104
	v_fma_f32 v110, v130, v135, v105
	v_fma_f32 v125, v130, v193, v108
	v_fma_f32 v126, v130, v194, v109
	v_fma_f32 v133, v130, v197, v203
	v_fma_f32 v134, v130, v198, v204
	v_fma_f32 v88, v88, v96, v140
	v_fma_f32 v89, v89, v97, v140
	v_fma_f32 v111, v130, v155, v106
	v_fma_f32 v124, v130, v192, v107
	v_fma_f32 v127, v130, v195, v201
	v_fma_f32 v132, v130, v196, v202
	v_fma_f32 v84, v84, v104, v88
	v_fma_f32 v85, v85, v110, v89
	v_fma_f32 v135, v130, v199, v205
	v_fma_f32 v130, v130, v152, v200
	v_fma_f32 v90, v90, v98, v140
	v_fma_f32 v91, v91, v99, v140
	v_fma_f32 v76, v76, v125, v84
	v_fma_f32 v77, v77, v126, v85
	v_fma_f32 v68, v68, v133, v76
	v_fma_f32 v69, v69, v134, v77
	v_fma_f32 v86, v86, v111, v90
	v_fma_f32 v87, v87, v124, v91
	v_fma_f32 v78, v78, v127, v86
	v_fma_f32 v79, v79, v132, v87
	v_add_f32_e32 v68, v68, v69
	v_fma_f32 v70, v70, v135, v78
	v_fma_f32 v71, v71, v130, v79
	v_add_f32_e32 v69, v70, v71
	v_add_f32_e32 v68, v68, v69
	v_mov_b32_e32 v69, 0
	s_nop 0
	v_add_f32_dpp v68, v68, v68 row_ror:8 row_mask:0xf bank_mask:0xf bound_ctrl:1
	s_nop 1
	v_add_f32_dpp v68, v68, v68 row_ror:4 row_mask:0xf bank_mask:0xf bound_ctrl:1
	s_nop 1
	v_add_f32_dpp v68, v68, v68 row_ror:2 row_mask:0xf bank_mask:0xf bound_ctrl:1
	s_nop 1
	v_mov_b32_dpp v69, v68 row_ror:1 row_mask:0xf bank_mask:0xf
	s_and_saveexec_b64 s[8:9], s[44:45]
	v_add_f32_e32 v68, v68, v69
	ds_write_b32 v189, v68 offset:34432
	s_or_b64 exec, exec, s[8:9]
	s_waitcnt lgkmcnt(0)
	v_mul_f32_e32 v68, v129, v131
	v_mul_f32 v69, v120, v68
	v_mul_f32 v70, v121, v68
	v_mul_f32 v71, v122, v68
	v_mul_f32 v76, v123, v68
	v_mul_f32 v77, v112, v68
	v_mul_f32 v78, v113, v68
	v_mul_f32 v79, v114, v68
	v_mul_f32 v84, v115, v68
	v_mul_f32 v85, v116, v68
	v_mul_f32 v86, v117, v68
	v_mul_f32 v87, v118, v68
	v_mul_f32 v88, v119, v68
	v_mul_f32 v89, v100, v68
	v_mul_f32 v100, v101, v68
	v_mul_f32 v101, v102, v68
	v_mul_f32 v68, v103, v68
	v_fma_f32 v109, v128, v96, v69
	v_fma_f32 v108, v128, v97, v70
	v_fma_f32 v105, v128, v104, v77
	v_fma_f32 v104, v128, v110, v78
	v_fma_f32 v107, v128, v98, v71
	v_fma_f32 v78, v128, v130, v68
	v_fma_f32 v68, v92, v109, v140
	v_fma_f32 v69, v93, v108, v140
	v_fma_f32 v106, v128, v99, v76
	v_fma_f32 v99, v128, v111, v79
	v_fma_f32 v70, v94, v107, v140
	v_fma_f32 v98, v128, v124, v84
	v_fma_f32 v68, v80, v105, v68
	v_fma_f32 v69, v81, v104, v69
	v_fma_f32 v71, v95, v106, v140
	v_fma_f32 v97, v128, v125, v85
	v_fma_f32 v96, v128, v126, v86
	v_fma_f32 v90, v128, v132, v88
	v_fma_f32 v89, v128, v133, v89
	v_fma_f32 v88, v128, v134, v100
	v_fma_f32 v70, v82, v99, v70
	v_fma_f32 v71, v83, v98, v71
	v_fma_f32 v68, v72, v97, v68
	v_fma_f32 v69, v73, v96, v69
	v_fma_f32 v91, v128, v127, v87
	v_fma_f32 v79, v128, v135, v101
	v_fma_f32 v71, v75, v90, v71
	v_fma_f32 v64, v64, v89, v68
	v_fma_f32 v65, v65, v88, v69
	v_fma_f32 v70, v74, v91, v70
	v_fma_f32 v66, v66, v79, v70
	v_fma_f32 v67, v67, v78, v71
	v_add_f32_e32 v64, v64, v65
	v_add_f32_e32 v65, v66, v67
	v_add_f32_e32 v64, v64, v65
	v_mov_b32_e32 v65, 0
	s_nop 0
	v_add_f32_dpp v64, v64, v64 row_ror:8 row_mask:0xf bank_mask:0xf bound_ctrl:1
	s_nop 1
	v_add_f32_dpp v64, v64, v64 row_ror:4 row_mask:0xf bank_mask:0xf bound_ctrl:1
	s_nop 1
	v_add_f32_dpp v64, v64, v64 row_ror:2 row_mask:0xf bank_mask:0xf bound_ctrl:1
	s_nop 1
	v_mov_b32_dpp v65, v64 row_ror:1 row_mask:0xf bank_mask:0xf
	s_and_saveexec_b64 s[8:9], s[44:45]
	v_add_f32_e32 v64, v64, v65
	ds_write_b32 v189, v64 offset:34496
	s_or_b64 exec, exec, s[8:9]
	s_waitcnt vmcnt(3)
	ds_write_b128 v185, v[48:51] offset:17024
	s_waitcnt vmcnt(1)
	ds_write_b128 v186, v[56:59] offset:17024
	ds_write_b128 v185, v[52:55] offset:25216
	s_waitcnt vmcnt(0)
	ds_write_b128 v186, v[60:63] offset:25216
	s_and_saveexec_b64 s[8:9], s[42:43]
	ds_write_b32 v144, v184 offset:33408
	s_or_b64 exec, exec, s[8:9]
	s_and_saveexec_b64 s[8:9], s[40:41]
	s_cbranch_execz .LBB0_1536
	v_add_f32_e32 v64, v156, v181
	v_mul_f32_e64 v65, |v64|, s62
	v_exp_f32_e32 v65, v65
	v_min_f32_e32 v64, 0, v64
	v_add_f32_e32 v65, 1.0, v65
	v_cmp_gt_f32_e32 vcc, s5, v65
	s_nop 1
	v_cndmask_b32_e64 v66, 0, 32, vcc
	v_ldexp_f32 v65, v65, v66
	v_log_f32_e32 v65, v65
	v_cndmask_b32_e32 v67, 0, v171, vcc
	v_add_f32_e32 v66, v145, v187
	v_mul_f32_e32 v68, 0x3f317217, v65
	v_fma_f32 v68, v65, s76, -v68
	v_fmac_f32_e32 v68, 0x3377d1cf, v65
	v_fmac_f32_e32 v68, 0x3f317217, v65
	v_cmp_lt_f32_e64 vcc, |v65|, s77
	s_nop 1
	v_cndmask_b32_e32 v65, v65, v68, vcc
	v_sub_f32_e32 v65, v65, v67
	v_sub_f32_e32 v64, v64, v65
	v_add_u32_e32 v65, 0x8400, v144
	ds_write2_b32 v65, v66, v64 offset0:32 offset1:48

.LBB0_1547:
	s_or_b64 exec, exec, s[8:9]
	s_waitcnt lgkmcnt(0)
	s_barrier
	ds_read_b128 v[92:95], v188 offset:17024
	ds_read_b128 v[110:113], v188 offset:17280
	ds_read_b128 v[124:127], v188 offset:25216
	ds_read_b128 v[132:135], v188 offset:25472
	ds_read2_b64 v[80:83], v190 offset0:32 offset1:40
	ds_read2_b32 v[76:77], v191 offset0:160 offset1:176
	ds_read_b128 v[200:203], v188 offset:17536
	ds_read_b128 v[204:207], v188 offset:17792
	ds_read_b128 v[152:155], v188 offset:25728
	ds_read_b128 v[192:195], v188 offset:25984
	s_waitcnt lgkmcnt(4)
	v_mul_f32_e32 v76, v82, v76
	v_mul_f32 v82, v124, v76
	v_mul_f32 v114, v125, v76
	v_mul_f32 v115, v126, v76
	v_mul_f32 v124, v127, v76
	v_mul_f32 v125, v132, v76
	v_mul_f32 v126, v133, v76
	v_mul_f32 v127, v134, v76
	v_mul_f32 v191, v135, v76
	s_waitcnt lgkmcnt(1)
	v_mul_f32 v152, v152, v76
	v_mul_f32 v153, v153, v76
	v_mul_f32 v196, v154, v76
	v_mul_f32 v197, v155, v76
	s_waitcnt lgkmcnt(0)
	v_mul_f32 v198, v192, v76
	v_mul_f32 v199, v193, v76
	v_mul_f32 v208, v194, v76
	v_mul_f32 v76, v195, v76
	ds_read_b128 v[84:87], v188 offset:18048
	ds_read_b128 v[72:75], v188 offset:18304
	ds_read_b128 v[128:131], v188 offset:26240
	ds_read_b128 v[116:119], v188 offset:26496
	ds_read_b128 v[68:71], v188 offset:18560
	ds_read_b128 v[64:67], v188 offset:18816
	ds_read_b128 v[120:123], v188 offset:26752
	ds_read_b128 v[100:103], v188 offset:27008
	v_fma_f32 v82, v80, v109, v82
	v_fma_f32 v132, v80, v108, v114
	v_fma_f32 v133, v80, v107, v115
	v_fma_f32 v134, v80, v106, v124
	v_fma_f32 v135, v80, v105, v125
	v_fma_f32 v154, v80, v104, v126
	v_fma_f32 v155, v80, v99, v127
	v_fma_f32 v191, v80, v98, v191
	v_fma_f32 v192, v80, v97, v152
	v_fma_f32 v193, v80, v96, v153
	v_fma_f32 v194, v80, v91, v196
	v_fma_f32 v195, v80, v90, v197
	v_fma_f32 v196, v80, v89, v198
	v_fma_f32 v197, v80, v88, v199
	v_fma_f32 v198, v80, v79, v208
	v_fma_f32 v80, v80, v78, v76
	v_fma_f32 v76, v92, v82, v140
	v_fma_f32 v78, v93, v132, v140
	v_fma_f32 v79, v94, v133, v140
	v_fma_f32 v88, v95, v134, v140
	v_fma_f32 v76, v110, v135, v76
	v_fma_f32 v78, v111, v154, v78
	v_fma_f32 v79, v112, v155, v79
	v_fma_f32 v88, v113, v191, v88
	v_fma_f32 v76, v200, v192, v76
	v_fma_f32 v78, v201, v193, v78
	v_fma_f32 v79, v202, v194, v79
	v_fma_f32 v88, v203, v195, v88
	v_fma_f32 v76, v204, v196, v76
	v_fma_f32 v78, v205, v197, v78
	v_fma_f32 v79, v206, v198, v79
	v_fma_f32 v88, v207, v80, v88
	v_add_f32_e32 v76, v76, v78
	v_add_f32_e32 v78, v79, v88
	v_add_f32_e32 v76, v76, v78
	v_mov_b32_e32 v78, 0
	s_nop 0
	v_add_f32_dpp v76, v76, v76 row_ror:8 row_mask:0xf bank_mask:0xf bound_ctrl:1
	s_nop 1
	v_add_f32_dpp v76, v76, v76 row_ror:4 row_mask:0xf bank_mask:0xf bound_ctrl:1
	s_nop 1
	v_add_f32_dpp v76, v76, v76 row_ror:2 row_mask:0xf bank_mask:0xf bound_ctrl:1
	s_nop 1
	v_mov_b32_dpp v78, v76 row_ror:1 row_mask:0xf bank_mask:0xf
	s_and_saveexec_b64 s[8:9], s[44:45]
	v_add_f32_e32 v76, v76, v78
	ds_write_b32 v189, v76 offset:34560
	s_or_b64 exec, exec, s[8:9]
	v_mul_f32_e32 v199, v83, v77
	ds_read_b128 v[96:99], v188 offset:19072
	ds_read_b128 v[92:95], v188 offset:19328
	ds_read_b128 v[124:127], v188 offset:27264
	ds_read_b128 v[108:111], v188 offset:27520
	ds_read_b128 v[88:91], v188 offset:19584
	ds_read_b128 v[76:79], v188 offset:19840
	ds_read_b128 v[112:115], v188 offset:27776
	ds_read_b128 v[104:107], v188 offset:28032
	ds_read2_b32 v[152:153], v190 offset0:66 offset1:82
	ds_read_b32 v83, v189 offset:33536
	s_waitcnt lgkmcnt(14)
	v_mul_f32 v128, v128, v199
	v_mul_f32 v129, v129, v199
	v_mul_f32 v130, v130, v199
	v_mul_f32 v131, v131, v199
	v_mul_f32 v116, v116, v199
	v_mul_f32 v117, v117, v199
	v_mul_f32 v118, v118, v199
	v_mul_f32 v119, v119, v199
	s_waitcnt lgkmcnt(11)
	v_mul_f32 v120, v120, v199
	v_mul_f32 v121, v121, v199
	v_mul_f32 v122, v122, v199
	v_mul_f32 v123, v123, v199
	s_waitcnt lgkmcnt(10)
	v_mul_f32 v100, v100, v199
	v_mul_f32 v101, v101, v199
	v_mul_f32 v102, v102, v199
	v_mul_f32 v103, v103, v199
	v_fma_f32 v199, v81, v82, v128
	v_fma_f32 v200, v81, v132, v129
	v_fma_f32 v201, v81, v133, v130
	v_fma_f32 v202, v81, v134, v131
	v_fma_f32 v203, v81, v135, v116
	v_fma_f32 v204, v81, v154, v117
	v_fma_f32 v205, v81, v155, v118
	v_fma_f32 v191, v81, v191, v119
	v_fma_f32 v192, v81, v192, v120
	v_fma_f32 v193, v81, v193, v121
	v_fma_f32 v194, v81, v194, v122
	v_fma_f32 v195, v81, v195, v123
	v_fma_f32 v196, v81, v196, v100
	v_fma_f32 v197, v81, v197, v101
	v_fma_f32 v198, v81, v198, v102
	v_fma_f32 v206, v81, v80, v103
	v_fma_f32 v80, v84, v199, v140
	v_fma_f32 v81, v85, v200, v140
	v_fma_f32 v82, v86, v201, v140
	v_fma_f32 v84, v87, v202, v140
	v_fma_f32 v72, v72, v203, v80
	v_fma_f32 v73, v73, v204, v81
	v_fma_f32 v74, v74, v205, v82
	v_fma_f32 v75, v75, v191, v84
	v_fma_f32 v68, v68, v192, v72
	v_fma_f32 v69, v69, v193, v73
	v_fma_f32 v70, v70, v194, v74
	v_fma_f32 v71, v71, v195, v75
	v_fma_f32 v64, v64, v196, v68
	v_fma_f32 v65, v65, v197, v69
	v_fma_f32 v66, v66, v198, v70
	v_fma_f32 v67, v67, v206, v71
	v_add_f32_e32 v64, v64, v65
	v_add_f32_e32 v65, v66, v67
	v_add_f32_e32 v64, v64, v65
	v_mov_b32_e32 v65, 0
	s_nop 0
	v_add_f32_dpp v64, v64, v64 row_ror:8 row_mask:0xf bank_mask:0xf bound_ctrl:1
	s_nop 1
	v_add_f32_dpp v64, v64, v64 row_ror:4 row_mask:0xf bank_mask:0xf bound_ctrl:1
	s_nop 1
	v_add_f32_dpp v64, v64, v64 row_ror:2 row_mask:0xf bank_mask:0xf bound_ctrl:1
	s_nop 1
	v_mov_b32_dpp v65, v64 row_ror:1 row_mask:0xf bank_mask:0xf
	s_and_saveexec_b64 s[8:9], s[44:45]
	v_add_f32_e32 v64, v64, v65
	ds_write_b32 v189, v64 offset:34624
	s_or_b64 exec, exec, s[8:9]
	s_waitcnt lgkmcnt(0)
	v_mul_f32_e32 v69, v153, v83
	ds_read_b128 v[100:103], v188 offset:20096
	ds_read_b128 v[80:83], v188 offset:20352
	ds_read_b128 v[132:135], v188 offset:28288
	ds_read_b128 v[120:123], v188 offset:28544
	ds_read_b128 v[72:75], v188 offset:20608
	ds_read_b128 v[64:67], v188 offset:20864
	ds_read_b128 v[128:131], v188 offset:28800
	ds_read_b128 v[116:119], v188 offset:29056
	ds_read2_b32 v[154:155], v190 offset0:67 offset1:83
	ds_read_b32 v68, v189 offset:33600
	v_mul_f32 v70, v124, v69
	v_mul_f32 v71, v125, v69
	v_mul_f32 v84, v126, v69
	v_mul_f32 v85, v127, v69
	v_mul_f32 v86, v108, v69
	v_mul_f32 v87, v109, v69
	v_mul_f32 v108, v110, v69
	v_mul_f32 v109, v111, v69
	v_mul_f32 v110, v112, v69
	v_mul_f32 v111, v113, v69
	v_mul_f32 v124, v114, v69
	v_mul_f32 v125, v115, v69
	v_mul_f32 v104, v104, v69
	v_mul_f32 v105, v105, v69
	v_mul_f32 v106, v106, v69
	v_mul_f32 v69, v107, v69
	v_fma_f32 v112, v152, v199, v70
	v_fma_f32 v113, v152, v200, v71
	v_fma_f32 v115, v152, v202, v85
	v_fma_f32 v114, v152, v201, v84
	v_fma_f32 v199, v152, v203, v86
	v_fma_f32 v202, v152, v206, v69
	v_fma_f32 v69, v96, v112, v140
	v_fma_f32 v70, v97, v113, v140
	v_fma_f32 v200, v152, v204, v87
	v_fma_f32 v71, v98, v114, v140
	v_fma_f32 v201, v152, v205, v108
	v_fma_f32 v192, v152, v192, v110
	v_fma_f32 v69, v92, v199, v69
	v_fma_f32 v193, v152, v193, v111
	v_fma_f32 v70, v93, v200, v70
	v_fma_f32 v84, v99, v115, v140
	v_fma_f32 v71, v94, v201, v71
	v_fma_f32 v191, v152, v191, v109
	v_fma_f32 v69, v88, v192, v69
	v_fma_f32 v194, v152, v194, v124
	v_fma_f32 v70, v89, v193, v70
	v_fma_f32 v196, v152, v196, v104
	v_fma_f32 v197, v152, v197, v105
	v_fma_f32 v84, v95, v191, v84
	v_fma_f32 v195, v152, v195, v125
	v_fma_f32 v71, v90, v194, v71
	v_fma_f32 v198, v152, v198, v106
	v_fma_f32 v69, v76, v196, v69
	v_fma_f32 v70, v77, v197, v70
	v_fma_f32 v84, v91, v195, v84
	v_fma_f32 v71, v78, v198, v71
	v_fma_f32 v76, v79, v202, v84
	v_add_f32_e32 v69, v69, v70
	v_add_f32_e32 v70, v71, v76
	v_add_f32_e32 v69, v69, v70
	v_mov_b32_e32 v70, 0
	s_nop 0
	v_add_f32_dpp v69, v69, v69 row_ror:8 row_mask:0xf bank_mask:0xf bound_ctrl:1
	s_nop 1
	v_add_f32_dpp v69, v69, v69 row_ror:4 row_mask:0xf bank_mask:0xf bound_ctrl:1
	s_nop 1
	v_add_f32_dpp v69, v69, v69 row_ror:2 row_mask:0xf bank_mask:0xf bound_ctrl:1
	s_nop 1
	v_mov_b32_dpp v70, v69 row_ror:1 row_mask:0xf bank_mask:0xf
	s_and_saveexec_b64 s[8:9], s[44:45]
	v_add_f32_e32 v69, v69, v70
	ds_write_b32 v189, v69 offset:34688
	s_or_b64 exec, exec, s[8:9]
	s_waitcnt lgkmcnt(0)
	v_mul_f32_e32 v93, v155, v68
	ds_read_b128 v[88:91], v188 offset:21120
	ds_read_b128 v[84:87], v188 offset:21376
	ds_read_b128 v[124:127], v188 offset:29312
	ds_read_b128 v[104:107], v188 offset:29568
	ds_read_b128 v[76:79], v188 offset:21632
	ds_read_b128 v[68:71], v188 offset:21888
	ds_read_b128 v[108:111], v188 offset:29824
	ds_read_b128 v[96:99], v188 offset:30080
	ds_read2_b32 v[152:153], v190 offset0:68 offset1:84
	ds_read_b32 v92, v189 offset:33664
	v_mul_f32 v94, v132, v93
	v_mul_f32 v95, v133, v93
	v_mul_f32 v132, v134, v93
	v_mul_f32 v133, v135, v93
	v_mul_f32 v134, v120, v93
	v_mul_f32 v135, v121, v93
	v_mul_f32 v155, v122, v93
	v_mul_f32 v203, v123, v93
	v_mul_f32 v128, v128, v93
	v_mul_f32 v129, v129, v93
	v_mul_f32 v130, v130, v93
	v_mul_f32 v131, v131, v93
	v_mul_f32 v116, v116, v93
	v_mul_f32 v117, v117, v93
	v_mul_f32 v118, v118, v93
	v_mul_f32 v93, v119, v93
	v_fma_f32 v120, v154, v112, v94
	v_fma_f32 v121, v154, v113, v95
	v_fma_f32 v122, v154, v114, v132
	v_fma_f32 v123, v154, v115, v133
	v_fma_f32 v134, v154, v199, v134
	v_fma_f32 v135, v154, v200, v135
	v_fma_f32 v155, v154, v201, v155
	v_fma_f32 v191, v154, v191, v203
	v_fma_f32 v192, v154, v192, v128
	v_fma_f32 v193, v154, v193, v129
	v_fma_f32 v194, v154, v194, v130
	v_fma_f32 v195, v154, v195, v131
	v_fma_f32 v196, v154, v196, v116
	v_fma_f32 v197, v154, v197, v117
	v_fma_f32 v198, v154, v198, v118
	v_fma_f32 v154, v154, v202, v93
	v_fma_f32 v93, v100, v120, v140
	v_fma_f32 v94, v101, v121, v140
	v_fma_f32 v95, v102, v122, v140
	v_fma_f32 v100, v103, v123, v140
	v_fma_f32 v80, v80, v134, v93
	v_fma_f32 v81, v81, v135, v94
	v_fma_f32 v82, v82, v155, v95
	v_fma_f32 v83, v83, v191, v100
	v_fma_f32 v72, v72, v192, v80
	v_fma_f32 v73, v73, v193, v81
	v_fma_f32 v74, v74, v194, v82
	v_fma_f32 v75, v75, v195, v83
	v_fma_f32 v64, v64, v196, v72
	v_fma_f32 v65, v65, v197, v73
	v_fma_f32 v66, v66, v198, v74
	v_fma_f32 v67, v67, v154, v75
	v_add_f32_e32 v64, v64, v65
	v_add_f32_e32 v65, v66, v67
	v_add_f32_e32 v64, v64, v65
	v_mov_b32_e32 v65, 0
	s_nop 0
	v_add_f32_dpp v64, v64, v64 row_ror:8 row_mask:0xf bank_mask:0xf bound_ctrl:1
	s_nop 1
	v_add_f32_dpp v64, v64, v64 row_ror:4 row_mask:0xf bank_mask:0xf bound_ctrl:1
	s_nop 1
	v_add_f32_dpp v64, v64, v64 row_ror:2 row_mask:0xf bank_mask:0xf bound_ctrl:1
	s_nop 1
	v_mov_b32_dpp v65, v64 row_ror:1 row_mask:0xf bank_mask:0xf
	s_and_saveexec_b64 s[8:9], s[44:45]
	v_add_f32_e32 v64, v64, v65
	ds_write_b32 v189, v64 offset:34752
	s_or_b64 exec, exec, s[8:9]
	s_waitcnt lgkmcnt(0)
	v_mul_f32_e32 v153, v153, v92
	ds_read_b128 v[92:95], v188 offset:22144
	ds_read_b128 v[80:83], v188 offset:22400
	ds_read_b128 v[128:131], v188 offset:30336
	ds_read_b128 v[112:115], v188 offset:30592
	ds_read_b128 v[72:75], v188 offset:22656
	ds_read_b128 v[64:67], v188 offset:22912
	ds_read_b128 v[116:119], v188 offset:30848
	ds_read_b128 v[100:103], v188 offset:31104
	ds_read2_b32 v[132:133], v190 offset0:69 offset1:85
	ds_read_b32 v200, v189 offset:33728
	v_mul_f32 v124, v124, v153
	v_mul_f32 v125, v125, v153
	v_mul_f32 v126, v126, v153
	v_mul_f32 v127, v127, v153
	v_mul_f32 v104, v104, v153
	v_mul_f32 v105, v105, v153
	v_mul_f32 v106, v106, v153
	v_mul_f32 v107, v107, v153
	v_mul_f32 v108, v108, v153
	v_mul_f32 v109, v109, v153
	v_mul_f32 v110, v110, v153
	v_mul_f32 v111, v111, v153
	v_mul_f32 v201, v96, v153
	v_mul_f32 v202, v97, v153
	v_mul_f32 v203, v98, v153
	v_mul_f32 v204, v99, v153
	v_fma_f32 v96, v152, v120, v124
	v_fma_f32 v97, v152, v121, v125
	v_fma_f32 v153, v152, v134, v104
	v_fma_f32 v199, v152, v135, v105
	v_fma_f32 v192, v152, v192, v108
	v_fma_f32 v193, v152, v193, v109
	v_fma_f32 v196, v152, v196, v201
	v_fma_f32 v197, v152, v197, v202
	v_fma_f32 v88, v88, v96, v140
	v_fma_f32 v89, v89, v97, v140
	v_fma_f32 v98, v152, v122, v126
	v_fma_f32 v99, v152, v123, v127
	v_fma_f32 v155, v152, v155, v106
	v_fma_f32 v191, v152, v191, v107
	v_fma_f32 v84, v84, v153, v88
	v_fma_f32 v85, v85, v199, v89
	v_fma_f32 v194, v152, v194, v110
	v_fma_f32 v195, v152, v195, v111
	v_fma_f32 v198, v152, v198, v203
	v_fma_f32 v152, v152, v154, v204
	v_fma_f32 v76, v76, v192, v84
	v_fma_f32 v77, v77, v193, v85
	v_fma_f32 v90, v90, v98, v140
	v_fma_f32 v91, v91, v99, v140
	v_fma_f32 v68, v68, v196, v76
	v_fma_f32 v69, v69, v197, v77
	v_fma_f32 v86, v86, v155, v90
	v_fma_f32 v87, v87, v191, v91
	v_fma_f32 v78, v78, v194, v86
	v_fma_f32 v79, v79, v195, v87
	v_add_f32_e32 v68, v68, v69
	v_fma_f32 v70, v70, v198, v78
	v_fma_f32 v71, v71, v152, v79
	v_add_f32_e32 v69, v70, v71
	v_add_f32_e32 v68, v68, v69
	v_mov_b32_e32 v69, 0
	s_nop 0
	v_add_f32_dpp v68, v68, v68 row_ror:8 row_mask:0xf bank_mask:0xf bound_ctrl:1
	s_nop 1
	v_add_f32_dpp v68, v68, v68 row_ror:4 row_mask:0xf bank_mask:0xf bound_ctrl:1
	s_nop 1
	v_add_f32_dpp v68, v68, v68 row_ror:2 row_mask:0xf bank_mask:0xf bound_ctrl:1
	s_nop 1
	v_mov_b32_dpp v69, v68 row_ror:1 row_mask:0xf bank_mask:0xf
	s_and_saveexec_b64 s[8:9], s[44:45]
	v_add_f32_e32 v68, v68, v69
	ds_write_b32 v189, v68 offset:34816
	s_or_b64 exec, exec, s[8:9]
	s_waitcnt lgkmcnt(0)
	v_mul_f32_e32 v133, v133, v200
	ds_read_b128 v[88:91], v188 offset:23168
	ds_read_b128 v[84:87], v188 offset:23424
	ds_read_b128 v[124:127], v188 offset:31360
	ds_read_b128 v[108:111], v188 offset:31616
	ds_read_b128 v[76:79], v188 offset:23680
	ds_read_b128 v[68:71], v188 offset:23936
	ds_read_b128 v[120:123], v188 offset:31872
	ds_read_b128 v[104:107], v188 offset:32128
	ds_read2_b32 v[134:135], v190 offset0:70 offset1:86
	ds_read_b32 v200, v189 offset:33792
	v_mul_f32 v128, v128, v133
	v_mul_f32 v129, v129, v133
	v_mul_f32 v154, v130, v133
	v_mul_f32 v201, v131, v133
	v_mul_f32 v112, v112, v133
	v_mul_f32 v113, v113, v133
	v_mul_f32 v116, v116, v133
	v_mul_f32 v117, v117, v133
	v_mul_f32 v100, v100, v133
	v_mul_f32 v101, v101, v133
	v_fma_f32 v130, v132, v96, v128
	v_fma_f32 v131, v132, v97, v129
	v_fma_f32 v153, v132, v153, v112
	v_fma_f32 v199, v132, v199, v113
	v_fma_f32 v192, v132, v192, v116
	v_fma_f32 v193, v132, v193, v117
	v_fma_f32 v196, v132, v196, v100
	v_fma_f32 v197, v132, v197, v101
	v_fma_f32 v92, v92, v130, v140
	v_fma_f32 v93, v93, v131, v140
	v_mul_f32 v114, v114, v133
	v_mul_f32 v115, v115, v133
	v_mul_f32 v118, v118, v133
	v_mul_f32 v119, v119, v133
	v_fma_f32 v80, v80, v153, v92
	v_fma_f32 v81, v81, v199, v93
	v_mul_f32 v102, v102, v133
	v_mul_f32 v103, v103, v133
	v_fma_f32 v133, v132, v98, v154
	v_fma_f32 v154, v132, v99, v201
	v_fma_f32 v72, v72, v192, v80
	v_fma_f32 v73, v73, v193, v81
	v_fma_f32 v155, v132, v155, v114
	v_fma_f32 v191, v132, v191, v115
	v_fma_f32 v194, v132, v194, v118
	v_fma_f32 v195, v132, v195, v119
	v_fma_f32 v64, v64, v196, v72
	v_fma_f32 v65, v65, v197, v73
	v_fma_f32 v198, v132, v198, v102
	v_fma_f32 v132, v132, v152, v103
	v_fma_f32 v94, v94, v133, v140
	v_fma_f32 v95, v95, v154, v140
	v_add_f32_e32 v64, v64, v65
	v_fma_f32 v82, v82, v155, v94
	v_fma_f32 v83, v83, v191, v95
	v_fma_f32 v74, v74, v194, v82
	v_fma_f32 v75, v75, v195, v83
	v_fma_f32 v66, v66, v198, v74
	v_fma_f32 v67, v67, v132, v75
	v_add_f32_e32 v65, v66, v67
	v_add_f32_e32 v64, v64, v65
	v_mov_b32_e32 v65, 0
	s_nop 0
	v_add_f32_dpp v64, v64, v64 row_ror:8 row_mask:0xf bank_mask:0xf bound_ctrl:1
	s_nop 1
	v_add_f32_dpp v64, v64, v64 row_ror:4 row_mask:0xf bank_mask:0xf bound_ctrl:1
	s_nop 1
	v_add_f32_dpp v64, v64, v64 row_ror:2 row_mask:0xf bank_mask:0xf bound_ctrl:1
	s_nop 1
	v_mov_b32_dpp v65, v64 row_ror:1 row_mask:0xf bank_mask:0xf
	s_and_saveexec_b64 s[8:9], s[44:45]
	v_add_f32_e32 v64, v64, v65
	ds_write_b32 v189, v64 offset:34880
	s_or_b64 exec, exec, s[8:9]
	s_waitcnt lgkmcnt(0)
	v_mul_f32_e32 v152, v135, v200
	ds_read_b128 v[100:103], v188 offset:24192
	ds_read_b128 v[96:99], v188 offset:24448
	ds_read_b128 v[116:119], v188 offset:32384
	ds_read_b128 v[72:75], v188 offset:32640
	ds_read_b128 v[92:95], v188 offset:24704
	ds_read_b128 v[80:83], v188 offset:24960
	ds_read_b128 v[112:115], v188 offset:32896
	ds_read_b128 v[64:67], v188 offset:33152
	ds_read2_b32 v[128:129], v190 offset0:71 offset1:87
	ds_read_b32 v135, v189 offset:33856
	v_mul_f32 v124, v124, v152
	v_mul_f32 v125, v125, v152
	v_mul_f32 v108, v108, v152
	v_mul_f32 v109, v109, v152
	v_mul_f32 v120, v120, v152
	v_mul_f32 v121, v121, v152
	v_mul_f32 v126, v126, v152
	v_mul_f32 v127, v127, v152
	v_mul_f32 v110, v110, v152
	v_mul_f32 v111, v111, v152
	v_mul_f32 v122, v122, v152
	v_mul_f32 v123, v123, v152
	v_mul_f32 v190, v104, v152
	v_mul_f32 v200, v105, v152
	v_fma_f32 v104, v134, v130, v124
	v_fma_f32 v105, v134, v131, v125
	v_fma_f32 v108, v134, v153, v108
	v_fma_f32 v109, v134, v199, v109
	v_fma_f32 v120, v134, v192, v120
	v_fma_f32 v121, v134, v193, v121
	v_fma_f32 v124, v134, v196, v190
	v_fma_f32 v125, v134, v197, v200
	v_fma_f32 v88, v88, v104, v140
	v_fma_f32 v89, v89, v105, v140
	v_mul_f32 v201, v106, v152
	v_mul_f32 v152, v107, v152
	v_fma_f32 v106, v134, v133, v126
	v_fma_f32 v107, v134, v154, v127
	v_fma_f32 v84, v84, v108, v88
	v_fma_f32 v85, v85, v109, v89
	v_fma_f32 v110, v134, v155, v110
	v_fma_f32 v111, v134, v191, v111
	v_fma_f32 v122, v134, v194, v122
	v_fma_f32 v123, v134, v195, v123
	v_fma_f32 v76, v76, v120, v84
	v_fma_f32 v77, v77, v121, v85
	v_fma_f32 v126, v134, v198, v201
	v_fma_f32 v127, v134, v132, v152
	v_fma_f32 v90, v90, v106, v140
	v_fma_f32 v91, v91, v107, v140
	v_fma_f32 v68, v68, v124, v76
	v_fma_f32 v69, v69, v125, v77
	v_fma_f32 v86, v86, v110, v90
	v_fma_f32 v87, v87, v111, v91
	v_add_f32_e32 v68, v68, v69
	v_fma_f32 v78, v78, v122, v86
	v_fma_f32 v79, v79, v123, v87
	v_fma_f32 v70, v70, v126, v78
	v_fma_f32 v71, v71, v127, v79
	v_add_f32_e32 v69, v70, v71
	v_add_f32_e32 v68, v68, v69
	v_mov_b32_e32 v69, 0
	s_nop 0
	v_add_f32_dpp v68, v68, v68 row_ror:8 row_mask:0xf bank_mask:0xf bound_ctrl:1
	s_nop 1
	v_add_f32_dpp v68, v68, v68 row_ror:4 row_mask:0xf bank_mask:0xf bound_ctrl:1
	s_nop 1
	v_add_f32_dpp v68, v68, v68 row_ror:2 row_mask:0xf bank_mask:0xf bound_ctrl:1
	s_nop 1
	v_mov_b32_dpp v69, v68 row_ror:1 row_mask:0xf bank_mask:0xf
	s_and_saveexec_b64 s[8:9], s[44:45]
	v_add_f32_e32 v68, v68, v69
	ds_write_b32 v189, v68 offset:34944
	s_or_b64 exec, exec, s[8:9]
	s_waitcnt lgkmcnt(0)
	v_mul_f32_e32 v68, v129, v135
	v_mul_f32 v76, v119, v68
	v_mul_f32 v72, v72, v68
	v_mul_f32 v73, v73, v68
	v_mul_f32 v84, v112, v68
	v_mul_f32 v85, v113, v68
	v_mul_f32 v69, v116, v68
	v_mul_f32 v70, v117, v68
	v_mul_f32 v74, v74, v68
	v_mul_f32 v75, v75, v68
	v_mul_f32 v86, v114, v68
	v_mul_f32 v87, v115, v68
	v_mul_f32 v88, v64, v68
	v_mul_f32 v89, v65, v68
	v_mul_f32 v91, v67, v68
	v_fma_f32 v64, v128, v104, v69
	v_fma_f32 v65, v128, v105, v70
	v_fma_f32 v67, v128, v107, v76
	v_fma_f32 v76, v128, v108, v72
	v_fma_f32 v77, v128, v109, v73
	v_fma_f32 v72, v128, v120, v84
	v_fma_f32 v73, v128, v121, v85
	v_fma_f32 v84, v100, v64, v140
	v_fma_f32 v85, v101, v65, v140
	v_mul_f32 v71, v118, v68
	v_mul_f32 v90, v66, v68
	v_fma_f32 v78, v128, v110, v74
	v_fma_f32 v79, v128, v111, v75
	v_fma_f32 v74, v128, v122, v86
	v_fma_f32 v75, v128, v123, v87
	v_fma_f32 v66, v128, v106, v71
	v_fma_f32 v87, v103, v67, v140
	v_fma_f32 v84, v96, v76, v84
	v_fma_f32 v85, v97, v77, v85
	v_fma_f32 v68, v128, v124, v88
	v_fma_f32 v69, v128, v125, v89
	v_fma_f32 v86, v102, v66, v140
	v_fma_f32 v87, v99, v79, v87
	v_fma_f32 v84, v92, v72, v84
	v_fma_f32 v85, v93, v73, v85
	v_fma_f32 v70, v128, v126, v90
	v_fma_f32 v71, v128, v127, v91
	v_fma_f32 v86, v98, v78, v86
	v_fma_f32 v87, v95, v75, v87
	v_fma_f32 v80, v80, v68, v84
	v_fma_f32 v81, v81, v69, v85
	v_fma_f32 v86, v94, v74, v86
	v_fma_f32 v83, v83, v71, v87
	v_add_f32_e32 v80, v80, v81
	v_fma_f32 v82, v82, v70, v86
	v_add_f32_e32 v81, v82, v83
	v_add_f32_e32 v80, v80, v81
	v_mov_b32_e32 v81, 0
	s_nop 0
	v_add_f32_dpp v80, v80, v80 row_ror:8 row_mask:0xf bank_mask:0xf bound_ctrl:1
	s_nop 1
	v_add_f32_dpp v80, v80, v80 row_ror:4 row_mask:0xf bank_mask:0xf bound_ctrl:1
	s_nop 1
	v_add_f32_dpp v80, v80, v80 row_ror:2 row_mask:0xf bank_mask:0xf bound_ctrl:1
	s_nop 1
	v_mov_b32_dpp v81, v80 row_ror:1 row_mask:0xf bank_mask:0xf
	s_and_saveexec_b64 s[8:9], s[44:45]
	s_cbranch_execz .LBB0_1438
	v_add_f32_e32 v80, v80, v81
	ds_write_b32 v189, v80 offset:35008
	s_branch .LBB0_1438

.LBB0_1567:
	s_load_dwordx2 s[22:23], s[0:1], 0x158
	s_ashr_i32 s73, s72, 31
	s_lshl_b64 s[40:41], s[72:73], 10
	v_mov_b32_e32 v145, v140
	s_waitcnt lgkmcnt(0)
	s_add_u32 s22, s22, s40
	s_addc_u32 s23, s23, s41
	v_lshl_add_u64 v[0:1], v[144:145], 2, s[22:23]
	s_mov_b64 s[22:23], 0x4c00000
	v_lshl_add_u64 v[2:3], v[0:1], 0, s[22:23]
	v_add_co_u32_e32 v0, vcc, 0x4c00000, v0
	s_nop 1
	v_addc_co_u32_e32 v1, vcc, 0, v1, vcc
	global_store_dwordx4 v[0:1], v[64:67], off
	global_store_dwordx4 v[2:3], v[76:79], off offset:256
	s_nop 1
	global_store_dwordx4 v[2:3], v[72:75], off offset:512
	s_nop 1
	global_store_dwordx4 v[2:3], v[68:71], off offset:768
	s_or_b64 exec, exec, s[8:9]
	s_and_saveexec_b64 s[8:9], s[38:39]
	s_xor_b64 s[8:9], exec, s[8:9]
	s_cbranch_execz .LBB0_1274

.LBB0_1576:
	s_or_b64 exec, exec, s[8:9]
	s_waitcnt lgkmcnt(0)
	s_barrier
	ds_read_b32 v0, v159
	s_movk_i32 s4, 0x31ff
	s_mov_b64 s[8:9], -1
	s_waitcnt lgkmcnt(0)
	v_cmp_lt_i32_e32 vcc, s4, v0
	v_readfirstlane_b32 s42, v0
	s_cbranch_vccnz .LBB0_1571
	s_cmpk_gt_i32 s42, 0x21ff
	s_cbranch_scc0 .LBB0_1595
	v_mov_b32_e32 v14, v143
	s_add_i32 s4, s42, 0xffffde00
	s_load_dwordx2 s[22:23], s[0:1], 0x40
	s_lshr_b32 s4, s4, 2
	s_bfe_u32 s8, s42, 0x30002
	s_and_b32 s4, s4, 0x3ffffff8
	s_lshl_b32 s9, s42, 5
	s_or_b32 s94, s4, s8
	s_and_b32 s9, s9, 0x60
	s_lshl_b64 s[38:39], s[94:95], 16
	s_waitcnt lgkmcnt(0)
	s_add_u32 s15, s22, s38
	s_addc_u32 s23, s23, s39
	s_lshl_b32 s40, s9, 2
	s_waitcnt vmcnt(0)
	v_lshlrev_b32_e32 v62, 2, v14
	s_add_u32 s22, s15, s40
	v_ashrrev_i32_e32 v0, 3, v14
	v_and_b32_e32 v1, 28, v62
	s_addc_u32 s23, s23, 0
	v_lshlrev_b32_e32 v42, 2, v1
	v_mov_b32_e32 v43, v140
	v_ashrrev_i32_e32 v1, 31, v0
	v_lshl_add_u64 v[2:3], s[22:23], 0, v[42:43]
	v_lshlrev_b64 v[44:45], 9, v[0:1]
	s_mov_b64 s[22:23], 0x4000
	v_lshl_add_u64 v[40:41], v[44:45], 0, s[22:23]
	s_mov_b64 s[22:23], 0x8000
	v_lshl_add_u64 v[38:39], v[44:45], 0, s[22:23]
	s_mov_b64 s[22:23], 0xc000
	v_lshl_add_u64 v[4:5], v[2:3], 0, v[44:45]
	v_lshl_add_u64 v[36:37], v[44:45], 0, s[22:23]
	v_mul_lo_u32 v0, v0, s68
	v_lshl_add_u64 v[6:7], v[2:3], 0, v[40:41]
	v_lshl_add_u64 v[8:9], v[2:3], 0, v[38:39]
	v_lshl_add_u64 v[10:11], v[2:3], 0, v[36:37]
	v_add_u32_e32 v12, v42, v0
	global_load_dwordx4 v[0:3], v[4:5], off
	v_add_u32_e32 v54, 0x5140, v12
	v_add_u32_e32 v58, 0x5148, v12
	v_add_u32_e32 v55, 0x61c0, v12
	v_add_u32_e32 v59, 0x61c8, v12
	v_add_u32_e32 v56, 0x7240, v12
	v_add_u32_e32 v60, 0x7248, v12
	v_add_u32_e32 v57, 0x82c0, v12
	v_add_u32_e32 v61, 0x82c8, v12
	s_lshl_b32 s43, s8, 7
	s_addk_i32 s4, 0x2000
	v_and_b32_e32 v49, 15, v14
	s_movk_i32 s9, 0x210
	s_lshl_b32 s8, s8, 9
	s_mov_b32 s41, s95
	v_mov_b32_e32 v47, v140
	v_lshlrev_b32_e32 v17, 4, v14
	v_cmp_eq_u32_e64 s[38:39], 0, v49
	s_waitcnt vmcnt(0)
	ds_write2_b32 v54, v0, v1 offset1:1
	ds_write2_b32 v58, v2, v3 offset1:1
	global_load_dwordx4 v[0:3], v[6:7], off
	s_waitcnt vmcnt(0)
	ds_write2_b32 v55, v0, v1 offset1:1
	ds_write2_b32 v59, v2, v3 offset1:1
	global_load_dwordx4 v[0:3], v[8:9], off
	s_waitcnt vmcnt(0)
	ds_write2_b32 v56, v0, v1 offset1:1
	ds_write2_b32 v60, v2, v3 offset1:1
	global_load_dwordx4 v[0:3], v[10:11], off
	v_and_b32_e32 v10, 31, v14
	v_lshlrev_b32_e32 v46, 2, v10
	s_waitcnt vmcnt(0)
	ds_write2_b32 v57, v0, v1 offset1:1
	ds_write2_b32 v61, v2, v3 offset1:1
	s_waitcnt lgkmcnt(0)
	s_barrier
	s_load_dwordx2 s[22:23], s[0:1], 0xb0
	v_ashrrev_i32_e32 v0, 4, v14
	v_lshlrev_b32_e32 v43, 2, v0
	v_or_b32_e32 v0, s43, v46
	v_lshlrev_b32_e32 v0, 2, v0
	v_mov_b32_e32 v1, v140
	s_waitcnt lgkmcnt(0)
	v_lshl_add_u64 v[4:5], s[22:23], 0, v[0:1]
	v_add_co_u32_e32 v4, vcc, s86, v4
	global_load_dwordx4 v[0:3], v0, s[22:23]
	s_nop 0
	v_addc_co_u32_e32 v5, vcc, 0, v5, vcc
	global_load_dwordx4 v[6:9], v[4:5], off
	v_mad_u32_u24 v18, v49, s9, v43
	s_mov_b32 s9, s95
	v_add_u32_e32 v64, 0x2000, v43
	s_waitcnt vmcnt(0)
	v_sub_f32_e32 v0, v6, v0
	v_mul_f32_e32 v0, 0x3fb8aa3b, v0
	v_exp_f32_e32 v6, v0
	v_sub_f32_e32 v0, v7, v1
	v_mul_f32_e32 v0, 0x3fb8aa3b, v0
	v_exp_f32_e32 v7, v0
	v_sub_f32_e32 v0, v8, v2
	v_mul_f32_e32 v0, 0x3fb8aa3b, v0
	v_exp_f32_e32 v4, v0
	v_sub_f32_e32 v0, v9, v3
	v_mul_f32_e32 v0, 0x3fb8aa3b, v0
	v_exp_f32_e32 v5, v0
	v_ashrrev_i32_e32 v0, 5, v14
	v_add_u32_e32 v48, s4, v0
	v_mov_b64_e32 v[0:1], s[30:31]
	v_mad_i64_i32 v[0:1], s[22:23], v48, s25, v[0:1]
	v_lshl_add_u64 v[8:9], v[0:1], 0, s[8:9]
	v_lshlrev_b32_e32 v0, 4, v10
	v_mov_b32_e32 v1, v140
	v_lshl_add_u64 v[12:13], v[8:9], 0, v[0:1]
	s_movk_i32 s4, 0x5000
	v_add_co_u32_e32 v0, vcc, s4, v12
	v_lshl_add_u64 v[8:9], v[8:9], 0, s[40:41]
	s_nop 0
	v_addc_co_u32_e32 v1, vcc, 0, v13, vcc
	global_load_dwordx4 v[0:3], v[0:1], off offset:32
	v_lshl_add_u64 v[8:9], v[8:9], 0, v[46:47]
	v_add_co_u32_e32 v8, vcc, s81, v8
	v_lshlrev_b32_e32 v47, 4, v49
	s_nop 0
	v_addc_co_u32_e32 v9, vcc, 0, v9, vcc
	global_load_dword v16, v[8:9], off offset:32
	s_waitcnt vmcnt(1)
	v_mul_f32_e32 v0, 0xbfb8aa3b, v0
	v_exp_f32_e32 v10, v0
	v_mul_f32_e32 v0, 0xbfb8aa3b, v1
	v_exp_f32_e32 v11, v0
	v_mul_f32_e32 v0, 0xbfb8aa3b, v2
	v_exp_f32_e32 v8, v0
	v_mul_f32_e32 v0, 0xbfb8aa3b, v3
	v_exp_f32_e32 v9, v0
	v_add_co_u32_e32 v0, vcc, s80, v12
	s_nop 1
	v_addc_co_u32_e32 v1, vcc, 0, v13, vcc
	global_load_dwordx4 v[0:3], v[0:1], off offset:32
	s_waitcnt vmcnt(0)
	v_mul_f32_e32 v12, 0xbfb8aa3b, v0
	v_mul_f32_e32 v13, 0xbfb8aa3b, v1
	v_exp_f32_e32 v12, v12
	v_exp_f32_e32 v13, v13
	s_nop 0
	v_pk_add_f32 v[12:13], v[12:13], 1.0 op_sel_hi:[1,0]
	v_div_scale_f32 v14, s[8:9], v13, v13, v1
	v_rcp_f32_e32 v15, v14
	s_nop 0
	v_fma_f32 v19, -v14, v15, 1.0
	v_fmac_f32_e32 v15, v19, v15
	v_div_scale_f32 v19, vcc, v1, v13, v1
	v_mul_f32_e32 v20, v19, v15
	v_fma_f32 v21, -v14, v20, v19
	v_fmac_f32_e32 v20, v21, v15
	v_fma_f32 v14, -v14, v20, v19
	v_div_fmas_f32 v14, v14, v15, v20
	v_div_fixup_f32 v1, v14, v13, v1
	v_div_scale_f32 v13, s[8:9], v12, v12, v0
	v_rcp_f32_e32 v14, v13
	s_nop 0
	v_fma_f32 v15, -v13, v14, 1.0
	v_fmac_f32_e32 v14, v15, v14
	v_div_scale_f32 v15, vcc, v0, v12, v0
	v_mul_f32_e32 v19, v15, v14
	v_fma_f32 v20, -v13, v19, v15
	v_fmac_f32_e32 v19, v20, v14
	v_fma_f32 v13, -v13, v19, v15
	v_div_fmas_f32 v13, v13, v14, v19
	v_div_fixup_f32 v0, v13, v12, v0
	v_mul_f32_e32 v12, 0xbfb8aa3b, v2
	v_mul_f32_e32 v13, 0xbfb8aa3b, v3
	v_exp_f32_e32 v12, v12
	v_exp_f32_e32 v13, v13
	v_pk_mul_f32 v[0:1], v[0:1], s[18:19] op_sel_hi:[1,0]
	v_pk_add_f32 v[12:13], v[12:13], 1.0 op_sel_hi:[1,0]
	v_div_scale_f32 v14, s[8:9], v13, v13, v3
	v_rcp_f32_e32 v15, v14
	s_nop 0
	v_fma_f32 v19, -v14, v15, 1.0
	v_fmac_f32_e32 v15, v19, v15
	v_div_scale_f32 v19, vcc, v3, v13, v3
	v_mul_f32_e32 v20, v19, v15
	v_fma_f32 v21, -v14, v20, v19
	v_fmac_f32_e32 v20, v21, v15
	v_fma_f32 v14, -v14, v20, v19
	v_div_fmas_f32 v14, v14, v15, v20
	v_div_fixup_f32 v3, v14, v13, v3
	v_div_scale_f32 v13, s[8:9], v12, v12, v2
	v_rcp_f32_e32 v14, v13
	s_nop 0
	v_fma_f32 v15, -v13, v14, 1.0
	v_fmac_f32_e32 v14, v15, v14
	v_div_scale_f32 v15, vcc, v2, v12, v2
	v_mul_f32_e32 v19, v15, v14
	v_fma_f32 v20, -v13, v19, v15
	v_fmac_f32_e32 v19, v20, v14
	v_fma_f32 v13, -v13, v19, v15
	v_div_fmas_f32 v13, v13, v14, v19
	v_div_fixup_f32 v2, v13, v12, v2
	v_add_u32_e32 v19, 0x5000, v18
	v_pk_mul_f32 v[2:3], v[2:3], s[18:19] op_sel_hi:[1,0]
	ds_read2_b32 v[14:15], v19 offset0:80 offset1:96
	ds_read2_b32 v[12:13], v19 offset0:113 offset1:129
	ds_read2_b32 v[24:25], v19 offset0:146 offset1:162
	ds_read2_b32 v[26:27], v19 offset0:179 offset1:195
	v_add_u32_e32 v19, 0x7000, v18
	v_add_u32_e32 v18, 0x7200, v18
	ds_read2_b32 v[28:29], v19 offset0:144 offset1:160
	ds_read2_b32 v[30:31], v19 offset0:177 offset1:193
	ds_read2_b32 v[32:33], v19 offset0:210 offset1:226
	ds_read2_b32 v[34:35], v18 offset0:115 offset1:131
	ds_write_b128 v17, v[0:3]
	v_pk_add_f32 v[0:1], v[6:7], 1.0 op_sel_hi:[1,0]
	v_div_scale_f32 v2, s[8:9], v1, v1, 1.0
	v_rcp_f32_e32 v3, v2
	s_nop 0
	v_fma_f32 v6, -v2, v3, 1.0
	v_fmac_f32_e32 v3, v6, v3
	v_div_scale_f32 v6, vcc, 1.0, v1, 1.0
	v_mul_f32_e32 v7, v6, v3
	v_fma_f32 v18, -v2, v7, v6
	v_fmac_f32_e32 v7, v18, v3
	v_fma_f32 v2, -v2, v7, v6
	v_div_fmas_f32 v2, v2, v3, v7
	v_div_fixup_f32 v1, v2, v1, 1.0
	v_div_scale_f32 v2, s[8:9], v0, v0, 1.0
	v_rcp_f32_e32 v3, v2
	s_nop 0
	v_fma_f32 v6, -v2, v3, 1.0
	v_fmac_f32_e32 v3, v6, v3
	v_div_scale_f32 v6, vcc, 1.0, v0, 1.0
	v_mul_f32_e32 v7, v6, v3
	v_fma_f32 v18, -v2, v7, v6
	v_fmac_f32_e32 v7, v18, v3
	v_fma_f32 v2, -v2, v7, v6
	v_div_fmas_f32 v2, v2, v3, v7
	v_pk_add_f32 v[6:7], v[10:11], 1.0 op_sel_hi:[1,0]
	v_div_fixup_f32 v0, v2, v0, 1.0
	v_div_scale_f32 v10, s[8:9], v7, v7, 1.0
	v_rcp_f32_e32 v11, v10
	v_pk_add_f32 v[2:3], v[0:1], 1.0 op_sel_hi:[1,0] neg_lo:[1,0] neg_hi:[1,0]
	v_fma_f32 v18, -v10, v11, 1.0
	v_fmac_f32_e32 v11, v18, v11
	v_div_scale_f32 v18, vcc, 1.0, v7, 1.0
	v_mul_f32_e32 v19, v18, v11
	v_fma_f32 v20, -v10, v19, v18
	v_fmac_f32_e32 v19, v20, v11
	v_fma_f32 v10, -v10, v19, v18
	v_div_fmas_f32 v10, v10, v11, v19
	v_div_fixup_f32 v7, v10, v7, 1.0
	v_div_scale_f32 v10, s[8:9], v6, v6, 1.0
	v_rcp_f32_e32 v11, v10
	s_nop 0
	v_fma_f32 v18, -v10, v11, 1.0
	v_fmac_f32_e32 v11, v18, v11
	v_div_scale_f32 v18, vcc, 1.0, v6, 1.0
	v_mul_f32_e32 v19, v18, v11
	v_fma_f32 v20, -v10, v19, v18
	v_fmac_f32_e32 v19, v20, v11
	v_fma_f32 v10, -v10, v19, v18
	v_div_fmas_f32 v10, v10, v11, v19
	v_div_fixup_f32 v6, v10, v6, 1.0
	v_pk_fma_f32 v[0:1], v[2:3], v[6:7], v[0:1]
	v_pk_add_f32 v[2:3], v[4:5], 1.0 op_sel_hi:[1,0]
	v_div_scale_f32 v4, s[8:9], v3, v3, 1.0
	v_rcp_f32_e32 v5, v4
	s_nop 0
	v_fma_f32 v6, -v4, v5, 1.0
	v_fmac_f32_e32 v5, v6, v5
	v_div_scale_f32 v6, vcc, 1.0, v3, 1.0
	v_mul_f32_e32 v7, v6, v5
	v_fma_f32 v10, -v4, v7, v6
	v_fmac_f32_e32 v7, v10, v5
	v_fma_f32 v4, -v4, v7, v6
	v_div_fmas_f32 v4, v4, v5, v7
	v_div_fixup_f32 v3, v4, v3, 1.0
	v_div_scale_f32 v4, s[8:9], v2, v2, 1.0
	v_rcp_f32_e32 v5, v4
	s_nop 0
	v_fma_f32 v6, -v4, v5, 1.0
	v_fmac_f32_e32 v5, v6, v5
	v_div_scale_f32 v6, vcc, 1.0, v2, 1.0
	v_mul_f32_e32 v7, v6, v5
	v_fma_f32 v10, -v4, v7, v6
	v_fmac_f32_e32 v7, v10, v5
	v_fma_f32 v4, -v4, v7, v6
	v_div_fmas_f32 v4, v4, v5, v7
	v_pk_add_f32 v[6:7], v[8:9], 1.0 op_sel_hi:[1,0]
	v_div_fixup_f32 v2, v4, v2, 1.0
	v_div_scale_f32 v8, s[8:9], v7, v7, 1.0
	v_rcp_f32_e32 v9, v8
	v_pk_add_f32 v[4:5], v[2:3], 1.0 op_sel_hi:[1,0] neg_lo:[1,0] neg_hi:[1,0]
	v_fma_f32 v10, -v8, v9, 1.0
	v_fmac_f32_e32 v9, v10, v9
	v_div_scale_f32 v10, vcc, 1.0, v7, 1.0
	v_mul_f32_e32 v11, v10, v9
	v_fma_f32 v18, -v8, v11, v10
	v_fmac_f32_e32 v11, v18, v9
	v_fma_f32 v8, -v8, v11, v10
	v_div_fmas_f32 v8, v8, v9, v11
	v_div_fixup_f32 v7, v8, v7, 1.0
	v_div_scale_f32 v8, s[8:9], v6, v6, 1.0
	v_rcp_f32_e32 v9, v8
	s_nop 0
	v_fma_f32 v10, -v8, v9, 1.0
	v_fmac_f32_e32 v9, v10, v9
	v_div_scale_f32 v10, vcc, 1.0, v6, 1.0
	v_mul_f32_e32 v11, v10, v9
	v_fma_f32 v18, -v8, v11, v10
	v_fmac_f32_e32 v11, v18, v9
	v_fma_f32 v8, -v8, v11, v10
	v_div_fmas_f32 v8, v8, v9, v11
	v_div_fixup_f32 v6, v8, v6, 1.0
	v_pk_fma_f32 v[2:3], v[4:5], v[6:7], v[2:3]
	ds_write_b128 v17, v[0:3] offset:4096
	ds_write_b32 v62, v16 offset:8192
	s_waitcnt lgkmcnt(0)
	s_barrier
	ds_read_b128 v[8:11], v47
	ds_read_b128 v[78:81], v47 offset:256
	ds_read_b128 v[82:85], v47 offset:4096
	ds_read_b128 v[86:89], v47 offset:4352
	ds_read_b128 v[4:7], v47 offset:512
	ds_read_b128 v[0:3], v47 offset:768
	ds_read_b128 v[20:23], v47 offset:4608
	ds_read_b128 v[16:19], v47 offset:4864
	ds_read2_b32 v[50:51], v64 offset0:32 offset1:48
	ds_read2_b32 v[52:53], v64 offset1:16
	s_waitcnt lgkmcnt(0)
	v_sub_f32 v14, v14, v52
	v_sub_f32 v12, v12, v52
	v_sub_f32 v13, v13, v53
	v_sub_f32 v15, v15, v53
	v_sub_f32 v24, v24, v52
	v_sub_f32 v25, v25, v53
	v_fma_f32 v76, v82, v14, v52
	v_fma_f32 v73, v83, v12, v52
	v_fma_f32 v74, v83, v13, v53
	v_fma_f32 v75, v82, v15, v53
	v_fma_f32 v71, v84, v24, v52
	v_fma_f32 v72, v84, v25, v53
	v_fma_f32 v12, v8, v76, v140
	v_fma_f32 v13, v9, v73, v140
	v_fma_f32 v9, v9, v74, v140
	v_fma_f32 v8, v8, v75, v140
	v_fma_f32 v14, v10, v71, v140
	v_fma_f32 v10, v10, v72, v140
	v_sub_f32 v26, v26, v52
	v_sub_f32 v27, v27, v53
	v_sub_f32 v28, v28, v52
	v_sub_f32 v29, v29, v53
	v_sub_f32 v30, v30, v52
	v_sub_f32 v31, v31, v53
	v_sub_f32 v32, v32, v52
	v_sub_f32 v33, v33, v53
	v_sub_f32 v63, v34, v52
	v_sub_f32 v77, v35, v53
	v_fma_f32 v69, v85, v26, v52
	v_fma_f32 v70, v85, v27, v53
	v_fma_f32 v67, v86, v28, v52
	v_fma_f32 v68, v86, v29, v53
	v_fma_f32 v65, v87, v30, v52
	v_fma_f32 v66, v87, v31, v53
	v_fma_f32 v34, v88, v32, v52
	v_fma_f32 v35, v88, v33, v53
	v_fma_f32 v15, v11, v69, v140
	v_fma_f32 v11, v11, v70, v140
	v_fma_f32 v12, v78, v67, v12
	v_fma_f32 v24, v78, v68, v8
	v_fma_f32 v8, v79, v65, v13
	v_fma_f32 v13, v79, v66, v9
	v_fma_f32 v9, v80, v34, v14
	v_fma_f32 v10, v80, v35, v10
	v_fma_f32 v32, v89, v63, v52
	v_fma_f32 v33, v89, v77, v53
	v_add_f32_e32 v8, v12, v8
	v_fma_f32 v14, v81, v32, v15
	v_fma_f32 v11, v81, v33, v11
	v_add_f32_e32 v12, v24, v13
	v_add_f32_e32 v9, v9, v14
	v_add_f32_e32 v10, v10, v11
	v_add_f32_e32 v8, v8, v9
	v_add_f32_e32 v10, v12, v10
	v_mov_b32_e32 v9, v140
	v_add_f32_dpp v8, v8, v8 row_ror:8 row_mask:0xf bank_mask:0xf bound_ctrl:1
	v_add_f32_dpp v10, v10, v10 row_ror:8 row_mask:0xf bank_mask:0xf bound_ctrl:1
	v_mov_b32_e32 v11, v140
	v_add_f32_dpp v8, v8, v8 row_ror:4 row_mask:0xf bank_mask:0xf bound_ctrl:1
	v_add_f32_dpp v10, v10, v10 row_ror:4 row_mask:0xf bank_mask:0xf bound_ctrl:1
	v_add_u32_e32 v63, 0x4800, v43
	v_add_f32_dpp v8, v8, v8 row_ror:2 row_mask:0xf bank_mask:0xf bound_ctrl:1
	v_add_f32_dpp v10, v10, v10 row_ror:2 row_mask:0xf bank_mask:0xf bound_ctrl:1
	s_nop 0
	v_mov_b32_dpp v9, v8 row_ror:1 row_mask:0xf bank_mask:0xf
	v_mov_b32_dpp v11, v10 row_ror:1 row_mask:0xf bank_mask:0xf
	s_and_saveexec_b64 s[8:9], s[38:39]
	v_add_f32_e32 v10, v10, v11
	v_add_f32_e32 v8, v8, v9
	ds_write2_b32 v63, v8, v10 offset1:16
	s_or_b64 exec, exec, s[8:9]
	v_sub_f32 v76, v76, v50
	v_sub_f32 v75, v75, v51
	v_sub_f32 v73, v73, v50
	v_sub_f32 v74, v74, v51
	v_sub_f32 v71, v71, v50
	v_sub_f32 v72, v72, v51
	v_sub_f32 v69, v69, v50
	v_sub_f32 v70, v70, v51
	v_sub_f32 v67, v67, v50
	v_sub_f32 v68, v68, v51
	v_sub_f32 v65, v65, v50
	v_sub_f32 v66, v66, v51
	v_fma_f32 v80, v20, v76, v50
	v_fma_f32 v79, v20, v75, v51
	v_fma_f32 v77, v21, v73, v50
	v_fma_f32 v78, v21, v74, v51
	v_fma_f32 v75, v22, v71, v50
	v_fma_f32 v76, v22, v72, v51
	v_fma_f32 v73, v23, v69, v50
	v_fma_f32 v74, v23, v70, v51
	v_fma_f32 v71, v16, v67, v50
	v_fma_f32 v72, v16, v68, v51
	v_fma_f32 v69, v17, v65, v50
	v_fma_f32 v70, v17, v66, v51
	v_fma_f32 v16, v4, v80, v140
	v_fma_f32 v4, v4, v79, v140
	v_fma_f32 v17, v5, v77, v140
	v_fma_f32 v5, v5, v78, v140
	ds_read_b128 v[12:15], v47 offset:1024
	ds_read_b128 v[8:11], v47 offset:1280
	ds_read_b128 v[28:31], v47 offset:5120
	ds_read_b128 v[24:27], v47 offset:5376
	ds_read2_b32 v[52:53], v64 offset0:64 offset1:80
	v_sub_f32 v34, v34, v50
	v_sub_f32 v35, v35, v51
	v_fma_f32 v16, v0, v71, v16
	v_fma_f32 v4, v0, v72, v4
	v_fma_f32 v0, v1, v69, v17
	v_fma_f32 v5, v1, v70, v5
	v_fma_f32 v67, v18, v34, v50
	v_fma_f32 v68, v18, v35, v51
	v_fma_f32 v18, v6, v75, v140
	v_fma_f32 v6, v6, v76, v140
	v_sub_f32 v32, v32, v50
	v_sub_f32 v33, v33, v51
	v_add_f32_e32 v0, v16, v0
	v_fma_f32 v1, v2, v67, v18
	v_fma_f32 v2, v2, v68, v6
	v_fma_f32 v65, v19, v32, v50
	v_fma_f32 v66, v19, v33, v51
	v_fma_f32 v19, v7, v73, v140
	v_fma_f32 v7, v7, v74, v140
	v_add_f32_e32 v4, v4, v5
	v_fma_f32 v6, v3, v65, v19
	v_fma_f32 v3, v3, v66, v7
	v_add_f32_e32 v1, v1, v6
	v_add_f32_e32 v2, v2, v3
	v_add_f32_e32 v0, v0, v1
	v_add_f32_e32 v2, v4, v2
	v_mov_b32_e32 v1, v140
	v_add_f32_dpp v0, v0, v0 row_ror:8 row_mask:0xf bank_mask:0xf bound_ctrl:1
	v_add_f32_dpp v2, v2, v2 row_ror:8 row_mask:0xf bank_mask:0xf bound_ctrl:1
	v_mov_b32_e32 v3, v140
	v_add_f32_dpp v0, v0, v0 row_ror:4 row_mask:0xf bank_mask:0xf bound_ctrl:1
	v_add_f32_dpp v2, v2, v2 row_ror:4 row_mask:0xf bank_mask:0xf bound_ctrl:1
	s_nop 0
	v_add_f32_dpp v0, v0, v0 row_ror:2 row_mask:0xf bank_mask:0xf bound_ctrl:1
	v_add_f32_dpp v2, v2, v2 row_ror:2 row_mask:0xf bank_mask:0xf bound_ctrl:1
	s_nop 0
	v_mov_b32_dpp v1, v0 row_ror:1 row_mask:0xf bank_mask:0xf
	v_mov_b32_dpp v3, v2 row_ror:1 row_mask:0xf bank_mask:0xf
	s_and_saveexec_b64 s[8:9], s[38:39]
	v_add_f32_e32 v2, v2, v3
	v_add_f32_e32 v0, v0, v1
	ds_write2_b32 v63, v0, v2 offset0:32 offset1:48
	s_or_b64 exec, exec, s[8:9]
	s_waitcnt lgkmcnt(0)
	v_sub_f32 v4, v80, v52
	v_sub_f32 v5, v79, v53
	v_sub_f32 v6, v77, v52
	v_sub_f32 v7, v78, v53
	v_sub_f32 v75, v75, v52
	v_sub_f32 v71, v71, v52
	v_sub_f32 v72, v72, v53
	v_sub_f32 v69, v69, v52
	v_sub_f32 v70, v70, v53
	v_sub_f32 v67, v67, v52
	v_fma_f32 v80, v28, v4, v52
	v_fma_f32 v79, v28, v5, v53
	v_fma_f32 v77, v29, v6, v52
	v_fma_f32 v78, v29, v7, v53
	ds_read_b128 v[16:19], v47 offset:1536
	ds_read_b128 v[0:3], v47 offset:1792
	ds_read_b128 v[32:35], v47 offset:5632
	ds_read_b128 v[20:23], v47 offset:5888
	ds_read2_b32 v[50:51], v64 offset0:96 offset1:112
	v_fma_f32 v4, v12, v80, v140
	v_fma_f32 v5, v12, v79, v140
	v_fma_f32 v6, v13, v77, v140
	v_fma_f32 v7, v13, v78, v140
	v_sub_f32 v76, v76, v53
	v_sub_f32 v73, v73, v52
	v_sub_f32 v74, v74, v53
	v_sub_f32 v68, v68, v53
	v_sub_f32 v65, v65, v52
	v_sub_f32 v66, v66, v53
	v_fma_f32 v75, v30, v75, v52
	v_fma_f32 v71, v24, v71, v52
	v_fma_f32 v72, v24, v72, v53
	v_fma_f32 v69, v25, v69, v52
	v_fma_f32 v70, v25, v70, v53
	v_fma_f32 v67, v26, v67, v52
	v_fma_f32 v12, v14, v75, v140
	v_fma_f32 v4, v8, v71, v4
	v_fma_f32 v8, v8, v72, v5
	v_fma_f32 v5, v9, v69, v6
	v_fma_f32 v6, v9, v70, v7
	v_fma_f32 v76, v30, v76, v53
	v_fma_f32 v7, v10, v67, v12
	v_fma_f32 v73, v31, v73, v52
	v_fma_f32 v74, v31, v74, v53
	v_fma_f32 v68, v26, v68, v53
	v_fma_f32 v65, v27, v65, v52
	v_fma_f32 v66, v27, v66, v53
	v_fma_f32 v13, v14, v76, v140
	v_fma_f32 v14, v15, v73, v140
	v_fma_f32 v15, v15, v74, v140
	v_add_f32_e32 v4, v4, v5
	v_fma_f32 v9, v10, v68, v13
	v_fma_f32 v10, v11, v65, v14
	v_fma_f32 v11, v11, v66, v15
	v_add_f32_e32 v6, v8, v6
	v_add_f32_e32 v5, v7, v10
	v_add_f32_e32 v7, v9, v11
	v_add_f32_e32 v4, v4, v5
	v_add_f32_e32 v6, v6, v7
	v_mov_b32_e32 v5, v140
	v_add_f32_dpp v4, v4, v4 row_ror:8 row_mask:0xf bank_mask:0xf bound_ctrl:1
	v_add_f32_dpp v6, v6, v6 row_ror:8 row_mask:0xf bank_mask:0xf bound_ctrl:1
	v_mov_b32_e32 v7, v140
	v_add_f32_dpp v4, v4, v4 row_ror:4 row_mask:0xf bank_mask:0xf bound_ctrl:1
	v_add_f32_dpp v6, v6, v6 row_ror:4 row_mask:0xf bank_mask:0xf bound_ctrl:1
	s_nop 0
	v_add_f32_dpp v4, v4, v4 row_ror:2 row_mask:0xf bank_mask:0xf bound_ctrl:1
	v_add_f32_dpp v6, v6, v6 row_ror:2 row_mask:0xf bank_mask:0xf bound_ctrl:1
	s_nop 0
	v_mov_b32_dpp v5, v4 row_ror:1 row_mask:0xf bank_mask:0xf
	v_mov_b32_dpp v7, v6 row_ror:1 row_mask:0xf bank_mask:0xf
	s_and_saveexec_b64 s[8:9], s[38:39]
	v_add_f32_e32 v6, v6, v7
	v_add_f32_e32 v4, v4, v5
	ds_write2_b32 v63, v4, v6 offset0:64 offset1:80
	s_or_b64 exec, exec, s[8:9]
	s_waitcnt lgkmcnt(0)
	v_sub_f32 v12, v80, v50
	v_sub_f32 v13, v79, v51
	v_sub_f32 v14, v77, v50
	v_sub_f32 v15, v78, v51
	v_sub_f32 v79, v76, v51
	v_sub_f32 v81, v74, v51
	v_fma_f32 v77, v32, v12, v50
	v_fma_f32 v76, v32, v13, v51
	v_fma_f32 v74, v33, v14, v50
	ds_read_b128 v[8:11], v47 offset:2048
	ds_read_b128 v[4:7], v47 offset:2304
	ds_read_b128 v[28:31], v47 offset:6144
	ds_read_b128 v[24:27], v47 offset:6400
	ds_read2_b32 v[52:53], v64 offset0:128 offset1:144
	v_fma_f32 v12, v16, v77, v140
	v_fma_f32 v13, v16, v76, v140
	v_fma_f32 v14, v17, v74, v140
	v_sub_f32 v78, v75, v50
	v_sub_f32 v80, v73, v50
	v_sub_f32 v82, v71, v50
	v_sub_f32 v83, v72, v51
	v_sub_f32 v84, v69, v50
	v_sub_f32 v85, v70, v51
	v_sub_f32 v86, v67, v50
	v_sub_f32 v87, v68, v51
	v_sub_f32 v88, v65, v50
	v_sub_f32 v89, v66, v51
	v_fma_f32 v75, v33, v15, v51
	v_fma_f32 v72, v34, v78, v50
	v_fma_f32 v73, v34, v79, v51
	v_fma_f32 v68, v20, v82, v50
	v_fma_f32 v69, v20, v83, v51
	v_fma_f32 v66, v21, v84, v50
	v_fma_f32 v67, v21, v85, v51
	v_fma_f32 v65, v22, v86, v50
	v_fma_f32 v22, v22, v87, v51
	v_fma_f32 v15, v17, v75, v140
	v_fma_f32 v16, v18, v72, v140
	v_fma_f32 v17, v18, v73, v140
	v_fma_f32 v12, v0, v68, v12
	v_fma_f32 v13, v0, v69, v13
	v_fma_f32 v0, v1, v66, v14
	v_fma_f32 v14, v1, v67, v15
	v_fma_f32 v1, v2, v65, v16
	v_fma_f32 v2, v2, v22, v17
	v_fma_f32 v70, v35, v80, v50
	v_fma_f32 v71, v35, v81, v51
	v_fma_f32 v20, v23, v88, v50
	v_fma_f32 v21, v23, v89, v51
	v_add_f32_e32 v0, v12, v0
	v_fma_f32 v18, v19, v70, v140
	v_fma_f32 v19, v19, v71, v140
	v_add_f32_e32 v12, v13, v14
	v_fma_f32 v15, v3, v20, v18
	v_fma_f32 v3, v3, v21, v19
	v_add_f32_e32 v1, v1, v15
	v_add_f32_e32 v2, v2, v3
	v_add_f32_e32 v0, v0, v1
	v_add_f32_e32 v2, v12, v2
	v_mov_b32_e32 v1, v140
	v_add_f32_dpp v0, v0, v0 row_ror:8 row_mask:0xf bank_mask:0xf bound_ctrl:1
	v_add_f32_dpp v2, v2, v2 row_ror:8 row_mask:0xf bank_mask:0xf bound_ctrl:1
	v_mov_b32_e32 v3, v140
	v_add_f32_dpp v0, v0, v0 row_ror:4 row_mask:0xf bank_mask:0xf bound_ctrl:1
	v_add_f32_dpp v2, v2, v2 row_ror:4 row_mask:0xf bank_mask:0xf bound_ctrl:1
	s_nop 0
	v_add_f32_dpp v0, v0, v0 row_ror:2 row_mask:0xf bank_mask:0xf bound_ctrl:1
	v_add_f32_dpp v2, v2, v2 row_ror:2 row_mask:0xf bank_mask:0xf bound_ctrl:1
	s_nop 0
	v_mov_b32_dpp v1, v0 row_ror:1 row_mask:0xf bank_mask:0xf
	v_mov_b32_dpp v3, v2 row_ror:1 row_mask:0xf bank_mask:0xf
	s_and_saveexec_b64 s[8:9], s[38:39]
	v_add_f32_e32 v2, v2, v3
	v_add_f32_e32 v0, v0, v1
	ds_write2_b32 v63, v0, v2 offset0:96 offset1:112
	s_or_b64 exec, exec, s[8:9]
	s_waitcnt lgkmcnt(0)
	v_sub_f32 v74, v74, v52
	v_sub_f32 v20, v20, v52
	v_sub_f32 v21, v21, v53
	v_sub_f32 v23, v77, v52
	v_sub_f32 v77, v76, v53
	v_sub_f32 v78, v75, v53
	v_sub_f32 v72, v72, v52
	v_sub_f32 v79, v73, v53
	v_sub_f32 v70, v70, v52
	v_sub_f32 v68, v68, v52
	v_sub_f32 v66, v66, v52
	v_sub_f32 v22, v22, v53
	v_fma_f32 v76, v28, v23, v52
	v_fma_f32 v75, v28, v77, v53
	v_fma_f32 v73, v29, v74, v52
	v_fma_f32 v74, v29, v78, v53
	v_fma_f32 v28, v27, v20, v52
	v_fma_f32 v29, v27, v21, v53
	v_fma_f32 v20, v8, v76, v140
	v_fma_f32 v8, v8, v75, v140
	v_fma_f32 v21, v9, v73, v140
	v_fma_f32 v9, v9, v74, v140
	ds_read_b128 v[12:15], v47 offset:2560
	ds_read_b128 v[0:3], v47 offset:2816
	ds_read_b128 v[32:35], v47 offset:6656
	ds_read_b128 v[16:19], v47 offset:6912
	ds_read2_b32 v[50:51], v64 offset0:160 offset1:176
	v_sub_f32 v80, v71, v53
	v_sub_f32 v81, v69, v53
	v_sub_f32 v82, v67, v53
	v_sub_f32 v83, v65, v52
	v_fma_f32 v71, v30, v72, v52
	v_fma_f32 v72, v30, v79, v53
	v_fma_f32 v69, v31, v70, v52
	v_fma_f32 v70, v31, v80, v53
	v_fma_f32 v67, v24, v68, v52
	v_fma_f32 v68, v24, v81, v53
	v_fma_f32 v65, v25, v66, v52
	v_fma_f32 v66, v25, v82, v53
	v_fma_f32 v30, v26, v83, v52
	v_fma_f32 v31, v26, v22, v53
	v_fma_f32 v22, v10, v71, v140
	v_fma_f32 v10, v10, v72, v140
	v_fma_f32 v20, v4, v67, v20
	v_fma_f32 v8, v4, v68, v8
	v_fma_f32 v4, v5, v65, v21
	v_fma_f32 v9, v5, v66, v9
	v_fma_f32 v5, v6, v30, v22
	v_fma_f32 v6, v6, v31, v10
	v_fma_f32 v23, v11, v69, v140
	v_fma_f32 v11, v11, v70, v140
	v_add_f32_e32 v4, v20, v4
	v_fma_f32 v10, v7, v28, v23
	v_fma_f32 v7, v7, v29, v11
	v_add_f32_e32 v8, v8, v9
	v_add_f32_e32 v5, v5, v10
	v_add_f32_e32 v6, v6, v7
	v_add_f32_e32 v4, v4, v5
	v_add_f32_e32 v6, v8, v6
	v_mov_b32_e32 v5, v140
	v_add_f32_dpp v4, v4, v4 row_ror:8 row_mask:0xf bank_mask:0xf bound_ctrl:1
	v_add_f32_dpp v6, v6, v6 row_ror:8 row_mask:0xf bank_mask:0xf bound_ctrl:1
	v_mov_b32_e32 v7, v140
	v_add_f32_dpp v4, v4, v4 row_ror:4 row_mask:0xf bank_mask:0xf bound_ctrl:1
	v_add_f32_dpp v6, v6, v6 row_ror:4 row_mask:0xf bank_mask:0xf bound_ctrl:1
	s_nop 0
	v_add_f32_dpp v4, v4, v4 row_ror:2 row_mask:0xf bank_mask:0xf bound_ctrl:1
	v_add_f32_dpp v6, v6, v6 row_ror:2 row_mask:0xf bank_mask:0xf bound_ctrl:1
	s_nop 0
	v_mov_b32_dpp v5, v4 row_ror:1 row_mask:0xf bank_mask:0xf
	v_mov_b32_dpp v7, v6 row_ror:1 row_mask:0xf bank_mask:0xf
	s_and_saveexec_b64 s[8:9], s[38:39]
	v_add_f32_e32 v6, v6, v7
	v_add_f32_e32 v4, v4, v5
	ds_write2_b32 v63, v4, v6 offset0:128 offset1:144
	s_or_b64 exec, exec, s[8:9]
	s_waitcnt lgkmcnt(0)
	v_sub_f32 v76, v76, v50
	v_sub_f32 v75, v75, v51
	v_sub_f32 v73, v73, v50
	v_sub_f32 v74, v74, v51
	v_sub_f32 v71, v71, v50
	v_sub_f32 v72, v72, v51
	v_sub_f32 v69, v69, v50
	v_sub_f32 v70, v70, v51
	v_sub_f32 v67, v67, v50
	v_sub_f32 v68, v68, v51
	v_sub_f32 v65, v65, v50
	v_sub_f32 v66, v66, v51
	v_fma_f32 v78, v32, v76, v50
	v_fma_f32 v77, v32, v75, v51
	v_fma_f32 v75, v33, v73, v50
	v_fma_f32 v76, v33, v74, v51
	v_fma_f32 v73, v34, v71, v50
	v_fma_f32 v74, v34, v72, v51
	v_fma_f32 v71, v35, v69, v50
	v_fma_f32 v72, v35, v70, v51
	v_fma_f32 v69, v16, v67, v50
	v_fma_f32 v70, v16, v68, v51
	v_fma_f32 v67, v17, v65, v50
	v_fma_f32 v68, v17, v66, v51
	v_fma_f32 v16, v12, v78, v140
	v_fma_f32 v12, v12, v77, v140
	v_fma_f32 v17, v13, v75, v140
	v_fma_f32 v13, v13, v76, v140
	ds_read_b128 v[8:11], v47 offset:3072
	ds_read_b128 v[4:7], v47 offset:3328
	ds_read_b128 v[24:27], v47 offset:7168
	ds_read_b128 v[20:23], v47 offset:7424
	ds_read2_b32 v[52:53], v64 offset0:192 offset1:208
	v_sub_f32 v30, v30, v50
	v_sub_f32 v31, v31, v51
	v_fma_f32 v16, v0, v69, v16
	v_fma_f32 v12, v0, v70, v12
	v_fma_f32 v0, v1, v67, v17
	v_fma_f32 v13, v1, v68, v13
	v_fma_f32 v65, v18, v30, v50
	v_fma_f32 v66, v18, v31, v51
	v_fma_f32 v18, v14, v73, v140
	v_fma_f32 v14, v14, v74, v140
	v_sub_f32 v28, v28, v50
	v_sub_f32 v29, v29, v51
	v_add_f32_e32 v0, v16, v0
	v_fma_f32 v1, v2, v65, v18
	v_fma_f32 v2, v2, v66, v14
	v_fma_f32 v34, v19, v28, v50
	v_fma_f32 v35, v19, v29, v51
	v_fma_f32 v19, v15, v71, v140
	v_fma_f32 v15, v15, v72, v140
	v_add_f32_e32 v12, v12, v13
	v_fma_f32 v14, v3, v34, v19
	v_fma_f32 v3, v3, v35, v15
	v_add_f32_e32 v1, v1, v14
	v_add_f32_e32 v2, v2, v3
	v_add_f32_e32 v0, v0, v1
	v_add_f32_e32 v2, v12, v2
	v_mov_b32_e32 v1, v140
	v_add_f32_dpp v0, v0, v0 row_ror:8 row_mask:0xf bank_mask:0xf bound_ctrl:1
	v_add_f32_dpp v2, v2, v2 row_ror:8 row_mask:0xf bank_mask:0xf bound_ctrl:1
	v_mov_b32_e32 v3, v140
	v_add_f32_dpp v0, v0, v0 row_ror:4 row_mask:0xf bank_mask:0xf bound_ctrl:1
	v_add_f32_dpp v2, v2, v2 row_ror:4 row_mask:0xf bank_mask:0xf bound_ctrl:1
	s_nop 0
	v_add_f32_dpp v0, v0, v0 row_ror:2 row_mask:0xf bank_mask:0xf bound_ctrl:1
	v_add_f32_dpp v2, v2, v2 row_ror:2 row_mask:0xf bank_mask:0xf bound_ctrl:1
	s_nop 0
	v_mov_b32_dpp v1, v0 row_ror:1 row_mask:0xf bank_mask:0xf
	v_mov_b32_dpp v3, v2 row_ror:1 row_mask:0xf bank_mask:0xf
	s_and_saveexec_b64 s[8:9], s[38:39]
	v_add_f32_e32 v2, v2, v3
	v_add_f32_e32 v0, v0, v1
	ds_write2_b32 v63, v0, v2 offset0:160 offset1:176
	s_or_b64 exec, exec, s[8:9]
	ds_read_b128 v[12:15], v47 offset:3584
	ds_read_b128 v[0:3], v47 offset:3840
	ds_read_b128 v[28:31], v47 offset:7680
	ds_read_b128 v[16:19], v47 offset:7936
	ds_read2_b32 v[32:33], v64 offset0:224 offset1:240
	s_waitcnt lgkmcnt(5)
	v_sub_f32 v47, v78, v52
	v_sub_f32 v50, v77, v53
	v_sub_f32 v51, v75, v52
	v_sub_f32 v75, v76, v53
	v_sub_f32 v73, v73, v52
	v_sub_f32 v74, v74, v53
	v_sub_f32 v71, v71, v52
	v_sub_f32 v72, v72, v53
	v_sub_f32 v69, v69, v52
	v_sub_f32 v70, v70, v53
	v_sub_f32 v76, v67, v52
	v_sub_f32 v68, v68, v53
	v_sub_f32 v77, v65, v52
	v_sub_f32 v78, v66, v53
	v_sub_f32 v79, v34, v52
	v_sub_f32 v80, v35, v53
	v_fma_f32 v67, v24, v47, v52
	v_fma_f32 v66, v24, v50, v53
	v_fma_f32 v64, v25, v51, v52
	v_fma_f32 v65, v25, v75, v53
	v_fma_f32 v50, v26, v73, v52
	v_fma_f32 v51, v26, v74, v53
	v_fma_f32 v35, v27, v71, v52
	v_fma_f32 v47, v27, v72, v53
	v_fma_f32 v27, v20, v69, v52
	v_fma_f32 v34, v20, v70, v53
	v_fma_f32 v25, v21, v76, v52
	v_fma_f32 v26, v21, v68, v53
	v_fma_f32 v24, v22, v77, v52
	v_fma_f32 v20, v23, v79, v52
	v_fma_f32 v21, v23, v80, v53
	v_fma_f32 v23, v8, v67, v140
	v_fma_f32 v8, v8, v66, v140
	v_fma_f32 v52, v9, v64, v140
	v_fma_f32 v9, v9, v65, v140
	v_fma_f32 v22, v22, v78, v53
	v_fma_f32 v53, v10, v50, v140
	v_fma_f32 v10, v10, v51, v140
	v_fma_f32 v23, v4, v27, v23
	v_fma_f32 v8, v4, v34, v8
	v_fma_f32 v4, v5, v25, v52
	v_fma_f32 v9, v5, v26, v9
	v_fma_f32 v5, v6, v24, v53
	v_fma_f32 v6, v6, v22, v10
	v_fma_f32 v68, v11, v35, v140
	v_fma_f32 v11, v11, v47, v140
	v_add_f32_e32 v4, v23, v4
	v_fma_f32 v10, v7, v20, v68
	v_fma_f32 v7, v7, v21, v11
	v_add_f32_e32 v8, v8, v9
	v_add_f32_e32 v5, v5, v10
	v_add_f32_e32 v6, v6, v7
	v_add_f32_e32 v4, v4, v5
	v_add_f32_e32 v6, v8, v6
	v_mov_b32_e32 v5, v140
	v_add_f32_dpp v4, v4, v4 row_ror:8 row_mask:0xf bank_mask:0xf bound_ctrl:1
	v_add_f32_dpp v6, v6, v6 row_ror:8 row_mask:0xf bank_mask:0xf bound_ctrl:1
	v_mov_b32_e32 v7, v140
	v_add_f32_dpp v4, v4, v4 row_ror:4 row_mask:0xf bank_mask:0xf bound_ctrl:1
	v_add_f32_dpp v6, v6, v6 row_ror:4 row_mask:0xf bank_mask:0xf bound_ctrl:1
	s_nop 0
	v_add_f32_dpp v4, v4, v4 row_ror:2 row_mask:0xf bank_mask:0xf bound_ctrl:1
	v_add_f32_dpp v6, v6, v6 row_ror:2 row_mask:0xf bank_mask:0xf bound_ctrl:1
	s_nop 0
	v_mov_b32_dpp v5, v4 row_ror:1 row_mask:0xf bank_mask:0xf
	v_mov_b32_dpp v7, v6 row_ror:1 row_mask:0xf bank_mask:0xf
	s_and_saveexec_b64 s[8:9], s[38:39]
	v_add_f32_e32 v6, v6, v7
	v_add_f32_e32 v4, v4, v5
	ds_write2_b32 v63, v4, v6 offset0:192 offset1:208
	s_or_b64 exec, exec, s[8:9]
	s_waitcnt lgkmcnt(0)
	v_sub_f32 v4, v67, v32
	v_sub_f32 v5, v66, v33
	v_sub_f32 v6, v64, v32
	v_sub_f32 v7, v65, v33
	v_sub_f32 v25, v25, v32
	v_sub_f32 v24, v24, v32
	v_sub_f32 v8, v50, v32
	v_sub_f32 v9, v51, v33
	v_sub_f32 v11, v47, v33
	v_sub_f32 v23, v27, v32
	v_sub_f32 v27, v34, v33
	v_sub_f32 v26, v26, v33
	v_sub_f32 v34, v22, v33
	v_sub_f32 v47, v21, v33
	v_fma_f32 v4, v28, v4, v32
	v_fma_f32 v5, v28, v5, v33
	v_fma_f32 v6, v29, v6, v32
	v_fma_f32 v7, v29, v7, v33
	v_fma_f32 v21, v17, v25, v32
	v_fma_f32 v22, v18, v24, v32
	v_fma_f32 v24, v12, v4, v140
	v_fma_f32 v12, v12, v5, v140
	v_fma_f32 v25, v13, v6, v140
	v_fma_f32 v13, v13, v7, v140
	v_sub_f32 v10, v35, v32
	v_sub_f32 v35, v20, v32
	v_fma_f32 v8, v30, v8, v32
	v_fma_f32 v9, v30, v9, v33
	v_fma_f32 v20, v31, v11, v33
	v_fma_f32 v11, v16, v23, v32
	v_fma_f32 v16, v16, v27, v33
	v_fma_f32 v17, v17, v26, v33
	v_fma_f32 v23, v18, v34, v33
	v_fma_f32 v26, v14, v8, v140
	v_fma_f32 v14, v14, v9, v140
	v_fma_f32 v24, v0, v11, v24
	v_fma_f32 v12, v0, v16, v12
	v_fma_f32 v0, v1, v21, v25
	v_fma_f32 v13, v1, v17, v13
	v_fma_f32 v1, v2, v22, v26
	v_fma_f32 v2, v2, v23, v14
	v_fma_f32 v10, v31, v10, v32
	v_fma_f32 v18, v19, v35, v32
	v_fma_f32 v19, v19, v47, v33
	v_add_f32_e32 v0, v24, v0
	v_fma_f32 v27, v15, v10, v140
	v_fma_f32 v15, v15, v20, v140
	v_add_f32_e32 v12, v12, v13
	v_fma_f32 v14, v3, v18, v27
	v_fma_f32 v3, v3, v19, v15
	v_add_f32_e32 v1, v1, v14
	v_add_f32_e32 v2, v2, v3
	v_add_f32_e32 v0, v0, v1
	v_add_f32_e32 v2, v12, v2
	v_mov_b32_e32 v1, v140
	v_add_f32_dpp v0, v0, v0 row_ror:8 row_mask:0xf bank_mask:0xf bound_ctrl:1
	v_add_f32_dpp v2, v2, v2 row_ror:8 row_mask:0xf bank_mask:0xf bound_ctrl:1
	v_mov_b32_e32 v3, v140
	v_add_f32_dpp v0, v0, v0 row_ror:4 row_mask:0xf bank_mask:0xf bound_ctrl:1
	v_add_f32_dpp v2, v2, v2 row_ror:4 row_mask:0xf bank_mask:0xf bound_ctrl:1
	s_nop 0
	v_add_f32_dpp v0, v0, v0 row_ror:2 row_mask:0xf bank_mask:0xf bound_ctrl:1
	v_add_f32_dpp v2, v2, v2 row_ror:2 row_mask:0xf bank_mask:0xf bound_ctrl:1
	s_nop 0
	v_mov_b32_dpp v1, v0 row_ror:1 row_mask:0xf bank_mask:0xf
	v_mov_b32_dpp v3, v2 row_ror:1 row_mask:0xf bank_mask:0xf
	s_and_saveexec_b64 s[8:9], s[38:39]
	v_add_f32_e32 v2, v2, v3
	v_add_f32_e32 v0, v0, v1
	ds_write2_b32 v63, v0, v2 offset0:224 offset1:240
	s_or_b64 exec, exec, s[8:9]
	s_waitcnt lgkmcnt(0)
	s_barrier
	s_load_dwordx2 s[22:23], s[0:1], 0x158
	v_mov_b32_e32 v47, v140
	ds_read_b32 v13, v62 offset:18432
	s_lshl_b64 s[8:9], s[94:95], 14
	v_lshl_add_u64 v[0:1], s[28:29], 0, v[46:47]
	s_lshl_b32 s94, s43, 2
	v_mul_u32_u24_e32 v12, 0x210, v49
	v_ashrrev_i32_e32 v49, 31, v48
	v_lshl_add_u64 v[0:1], v[0:1], 0, s[94:95]
	s_mov_b32 s41, s95
	v_lshl_add_u64 v[0:1], v[0:1], 0, s[40:41]
	v_lshlrev_b64 v[2:3], 12, v[48:49]
	s_lshl_b64 s[8:9], s[8:9], 2
	v_lshl_add_u64 v[0:1], v[0:1], 0, v[2:3]
	s_waitcnt lgkmcnt(0)
	s_add_u32 s4, s22, s8
	global_store_dword v[0:1], v13, off
	s_addc_u32 s9, s23, s9
	v_add_u32_e32 v0, v43, v12
	v_add_u32_e32 v1, 0x5000, v0
	s_add_u32 s8, s4, s40
	ds_write2_b32 v1, v4, v5 offset0:80 offset1:96
	ds_write2_b32 v1, v6, v7 offset0:113 offset1:129
	ds_write2_b32 v1, v8, v9 offset0:146 offset1:162
	ds_write2_b32 v1, v10, v20 offset0:179 offset1:195
	v_add_u32_e32 v1, 0x7000, v0
	v_add_u32_e32 v0, 0x7200, v0
	s_addc_u32 s9, s9, 0
	v_mov_b32_e32 v43, v140
	ds_write2_b32 v1, v11, v16 offset0:144 offset1:160
	ds_write2_b32 v1, v21, v17 offset0:177 offset1:193
	ds_write2_b32 v1, v22, v23 offset0:210 offset1:226
	ds_write2_b32 v0, v18, v19 offset0:115 offset1:131
	v_lshl_add_u64 v[0:1], s[8:9], 0, v[42:43]
	s_mov_b64 s[8:9], 0xd3a4840
	s_waitcnt lgkmcnt(0)
	s_barrier
	v_lshl_add_u64 v[4:5], v[0:1], 0, s[8:9]
	ds_read2_b32 v[0:1], v54 offset1:1
	ds_read2_b32 v[2:3], v58 offset1:1
	v_lshl_add_u64 v[6:7], v[4:5], 0, v[44:45]
	s_mov_b64 s[8:9], 0
	s_waitcnt lgkmcnt(0)
	global_store_dwordx4 v[6:7], v[0:3], off
	s_nop 1
	ds_read2_b32 v[0:1], v55 offset1:1
	ds_read2_b32 v[2:3], v59 offset1:1
	v_lshl_add_u64 v[6:7], v[4:5], 0, v[40:41]
	s_waitcnt lgkmcnt(0)
	global_store_dwordx4 v[6:7], v[0:3], off
	s_nop 1
	ds_read2_b32 v[0:1], v56 offset1:1
	ds_read2_b32 v[2:3], v60 offset1:1
	v_lshl_add_u64 v[6:7], v[4:5], 0, v[38:39]
	v_lshl_add_u64 v[4:5], v[4:5], 0, v[36:37]
	s_waitcnt lgkmcnt(0)
	global_store_dwordx4 v[6:7], v[0:3], off
	s_nop 1
	ds_read2_b32 v[0:1], v57 offset1:1
	ds_read2_b32 v[2:3], v61 offset1:1
	s_waitcnt lgkmcnt(0)
	global_store_dwordx4 v[4:5], v[0:3], off

.LBB0_1650:
	s_or_b64 exec, exec, s[8:9]
	v_lshlrev_b32_e32 v80, 4, v77
	v_lshlrev_b32_e32 v79, 2, v69
	s_waitcnt lgkmcnt(0)
	s_barrier
	v_add_u32_e64 v81, s83, 0
	ds_read_b128 v[8:11], v80
	ds_read_b128 v[44:47], v80 offset:256
	ds_read_b128 v[48:51], v80 offset:8192
	ds_read_b128 v[72:75], v80 offset:8448
	ds_read2_b64 v[28:31], v81 offset0:32 offset1:40
	v_add_u32_e32 v0, 0x4000, v79
	ds_read2_b32 v[0:1], v0 offset1:16
	ds_read_b128 v[94:97], v80 offset:512
	ds_read_b128 v[98:101], v80 offset:768
	ds_read_b128 v[82:85], v80 offset:8704
	ds_read_b128 v[86:89], v80 offset:8960
	ds_read_b128 v[32:35], v80 offset:1024
	ds_read_b128 v[20:23], v80 offset:1280
	ds_read_b128 v[64:67], v80 offset:9216
	ds_read_b128 v[56:59], v80 offset:9472
	ds_read_b128 v[12:15], v80 offset:1536
	ds_read_b128 v[4:7], v80 offset:1792
	ds_read_b128 v[60:63], v80 offset:9728
	ds_read_b128 v[52:55], v80 offset:9984
	v_cmp_eq_u32_e32 vcc, 0, v77
	s_waitcnt lgkmcnt(12)
	v_mul_f32_e32 v0, v30, v0
	v_mul_f32 v2, v48, v0
	v_mul_f32 v3, v49, v0
	v_mul_f32 v30, v50, v0
	v_mul_f32 v48, v51, v0
	v_mul_f32 v49, v72, v0
	v_mul_f32 v50, v73, v0
	v_mul_f32 v51, v74, v0
	v_mul_f32 v72, v75, v0
	s_waitcnt lgkmcnt(9)
	v_mul_f32 v73, v82, v0
	v_mul_f32 v74, v83, v0
	v_mul_f32 v75, v84, v0
	v_mul_f32 v82, v85, v0
	s_waitcnt lgkmcnt(8)
	v_mul_f32 v102, v86, v0
	v_mul_f32 v103, v87, v0
	v_mul_f32 v104, v88, v0
	v_mul_f32 v0, v89, v0
	v_fma_f32 v93, v28, v16, v2
	v_fma_f32 v92, v28, v17, v3
	v_fma_f32 v91, v28, v18, v30
	v_fma_f32 v90, v28, v19, v48
	v_fma_f32 v83, v28, v24, v49
	v_fma_f32 v85, v28, v25, v50
	v_fma_f32 v87, v28, v26, v51
	v_fma_f32 v89, v28, v27, v72
	v_fma_f32 v88, v28, v36, v73
	v_fma_f32 v86, v28, v37, v74
	v_fma_f32 v84, v28, v38, v75
	v_fma_f32 v82, v28, v39, v82
	v_fma_f32 v75, v28, v40, v102
	v_fma_f32 v74, v28, v41, v103
	v_fma_f32 v30, v28, v42, v104
	v_fma_f32 v28, v28, v43, v0
	v_fma_f32 v0, v8, v93, v140
	v_fma_f32 v2, v9, v92, v140
	v_fma_f32 v3, v10, v91, v140
	v_fma_f32 v8, v11, v90, v140
	v_fma_f32 v0, v44, v83, v0
	v_fma_f32 v2, v45, v85, v2
	v_fma_f32 v3, v46, v87, v3
	v_fma_f32 v8, v47, v89, v8
	v_fma_f32 v0, v94, v88, v0
	v_fma_f32 v2, v95, v86, v2
	v_fma_f32 v3, v96, v84, v3
	v_fma_f32 v8, v97, v82, v8
	v_fma_f32 v0, v98, v75, v0
	v_fma_f32 v2, v99, v74, v2
	v_fma_f32 v3, v100, v30, v3
	v_fma_f32 v8, v101, v28, v8
	v_add_f32_e32 v0, v0, v2
	v_add_f32_e32 v2, v3, v8
	v_add_f32_e32 v0, v0, v2
	v_mov_b32_e32 v2, v140
	s_nop 0
	v_add_f32_dpp v0, v0, v0 row_ror:8 row_mask:0xf bank_mask:0xf bound_ctrl:1
	s_nop 1
	v_add_f32_dpp v0, v0, v0 row_ror:4 row_mask:0xf bank_mask:0xf bound_ctrl:1
	s_nop 1
	v_add_f32_dpp v0, v0, v0 row_ror:2 row_mask:0xf bank_mask:0xf bound_ctrl:1
	s_nop 1
	v_mov_b32_dpp v2, v0 row_ror:1 row_mask:0xf bank_mask:0xf
	s_and_saveexec_b64 s[8:9], vcc
	v_add_f32_e32 v0, v0, v2
	ds_write_b32 v79, v0 offset:34048
	s_or_b64 exec, exec, s[8:9]
	v_mul_f32_e32 v94, v31, v1
	ds_read_b128 v[24:27], v80 offset:2048
	ds_read_b128 v[16:19], v80 offset:2304
	ds_read_b128 v[48:51], v80 offset:10240
	ds_read_b128 v[40:43], v80 offset:10496
	ds_read_b128 v[8:11], v80 offset:2560
	ds_read_b128 v[0:3], v80 offset:2816
	ds_read_b128 v[44:47], v80 offset:10752
	ds_read_b128 v[36:39], v80 offset:11008
	ds_read2_b32 v[72:73], v81 offset0:66 offset1:82
	ds_read_b32 v31, v79 offset:16512
	s_waitcnt lgkmcnt(14)
	v_mul_f32 v64, v64, v94
	v_mul_f32 v65, v65, v94
	v_mul_f32 v66, v66, v94
	v_mul_f32 v67, v67, v94
	v_mul_f32 v56, v56, v94
	v_mul_f32 v57, v57, v94
	v_mul_f32 v58, v58, v94
	v_mul_f32 v59, v59, v94
	s_waitcnt lgkmcnt(11)
	v_mul_f32 v60, v60, v94
	v_mul_f32 v61, v61, v94
	v_mul_f32 v62, v62, v94
	v_mul_f32 v63, v63, v94
	s_waitcnt lgkmcnt(10)
	v_mul_f32 v52, v52, v94
	v_mul_f32 v53, v53, v94
	v_mul_f32 v54, v54, v94
	v_mul_f32 v55, v55, v94
	v_fma_f32 v64, v29, v93, v64
	v_fma_f32 v65, v29, v92, v65
	v_fma_f32 v66, v29, v91, v66
	v_fma_f32 v67, v29, v90, v67
	v_fma_f32 v83, v29, v83, v56
	v_fma_f32 v85, v29, v85, v57
	v_fma_f32 v87, v29, v87, v58
	v_fma_f32 v89, v29, v89, v59
	v_fma_f32 v88, v29, v88, v60
	v_fma_f32 v86, v29, v86, v61
	v_fma_f32 v84, v29, v84, v62
	v_fma_f32 v82, v29, v82, v63
	v_fma_f32 v90, v29, v75, v52
	v_fma_f32 v91, v29, v74, v53
	v_fma_f32 v92, v29, v30, v54
	v_fma_f32 v93, v29, v28, v55
	v_fma_f32 v28, v32, v64, v140
	v_fma_f32 v29, v33, v65, v140
	v_fma_f32 v30, v34, v66, v140
	v_fma_f32 v32, v35, v67, v140
	v_fma_f32 v20, v20, v83, v28
	v_fma_f32 v21, v21, v85, v29
	v_fma_f32 v22, v22, v87, v30
	v_fma_f32 v23, v23, v89, v32
	v_fma_f32 v12, v12, v88, v20
	v_fma_f32 v13, v13, v86, v21
	v_fma_f32 v14, v14, v84, v22
	v_fma_f32 v15, v15, v82, v23
	v_fma_f32 v4, v4, v90, v12
	v_fma_f32 v5, v5, v91, v13
	v_fma_f32 v6, v6, v92, v14
	v_fma_f32 v7, v7, v93, v15
	v_add_f32_e32 v4, v4, v5
	v_add_f32_e32 v5, v6, v7
	v_add_f32_e32 v4, v4, v5
	v_mov_b32_e32 v5, v140
	s_nop 0
	v_add_f32_dpp v4, v4, v4 row_ror:8 row_mask:0xf bank_mask:0xf bound_ctrl:1
	s_nop 1
	v_add_f32_dpp v4, v4, v4 row_ror:4 row_mask:0xf bank_mask:0xf bound_ctrl:1
	s_nop 1
	v_add_f32_dpp v4, v4, v4 row_ror:2 row_mask:0xf bank_mask:0xf bound_ctrl:1
	s_nop 1
	v_mov_b32_dpp v5, v4 row_ror:1 row_mask:0xf bank_mask:0xf
	s_and_saveexec_b64 s[8:9], vcc
	v_add_f32_e32 v4, v4, v5
	ds_write_b32 v79, v4 offset:34112
	s_or_b64 exec, exec, s[8:9]
	s_waitcnt lgkmcnt(0)
	v_mul_f32_e32 v94, v73, v31
	ds_read_b128 v[28:31], v80 offset:3072
	ds_read_b128 v[20:23], v80 offset:3328
	ds_read_b128 v[60:63], v80 offset:11264
	ds_read_b128 v[52:55], v80 offset:11520
	ds_read_b128 v[12:15], v80 offset:3584
	ds_read_b128 v[4:7], v80 offset:3840
	ds_read_b128 v[56:59], v80 offset:11776
	ds_read_b128 v[32:35], v80 offset:12032
	ds_read2_b32 v[74:75], v81 offset0:67 offset1:83
	ds_read_b32 v73, v79 offset:16576
	v_mul_f32 v48, v48, v94
	v_mul_f32 v49, v49, v94
	v_mul_f32 v50, v50, v94
	v_mul_f32 v51, v51, v94
	v_mul_f32 v40, v40, v94
	v_mul_f32 v41, v41, v94
	v_mul_f32 v44, v44, v94
	v_mul_f32 v45, v45, v94
	v_mul_f32 v36, v36, v94
	v_mul_f32 v37, v37, v94
	v_fma_f32 v48, v72, v64, v48
	v_fma_f32 v49, v72, v65, v49
	v_fma_f32 v83, v72, v83, v40
	v_fma_f32 v85, v72, v85, v41
	v_fma_f32 v88, v72, v88, v44
	v_fma_f32 v86, v72, v86, v45
	v_fma_f32 v90, v72, v90, v36
	v_fma_f32 v91, v72, v91, v37
	v_fma_f32 v24, v24, v48, v140
	v_fma_f32 v25, v25, v49, v140
	v_mul_f32 v42, v42, v94
	v_mul_f32 v43, v43, v94
	v_mul_f32 v46, v46, v94
	v_mul_f32 v47, v47, v94
	v_fma_f32 v16, v16, v83, v24
	v_fma_f32 v17, v17, v85, v25
	v_mul_f32 v38, v38, v94
	v_mul_f32 v39, v39, v94
	v_fma_f32 v50, v72, v66, v50
	v_fma_f32 v51, v72, v67, v51
	v_fma_f32 v8, v8, v88, v16
	v_fma_f32 v9, v9, v86, v17
	v_fma_f32 v87, v72, v87, v42
	v_fma_f32 v89, v72, v89, v43
	v_fma_f32 v84, v72, v84, v46
	v_fma_f32 v82, v72, v82, v47
	v_fma_f32 v0, v0, v90, v8
	v_fma_f32 v1, v1, v91, v9
	v_fma_f32 v92, v72, v92, v38
	v_fma_f32 v93, v72, v93, v39
	v_fma_f32 v26, v26, v50, v140
	v_fma_f32 v27, v27, v51, v140
	v_add_f32_e32 v0, v0, v1
	v_fma_f32 v18, v18, v87, v26
	v_fma_f32 v19, v19, v89, v27
	v_fma_f32 v10, v10, v84, v18
	v_fma_f32 v11, v11, v82, v19
	v_fma_f32 v2, v2, v92, v10
	v_fma_f32 v3, v3, v93, v11
	v_add_f32_e32 v1, v2, v3
	v_add_f32_e32 v0, v0, v1
	v_mov_b32_e32 v1, v140
	s_nop 0
	v_add_f32_dpp v0, v0, v0 row_ror:8 row_mask:0xf bank_mask:0xf bound_ctrl:1
	s_nop 1
	v_add_f32_dpp v0, v0, v0 row_ror:4 row_mask:0xf bank_mask:0xf bound_ctrl:1
	s_nop 1
	v_add_f32_dpp v0, v0, v0 row_ror:2 row_mask:0xf bank_mask:0xf bound_ctrl:1
	s_nop 1
	v_mov_b32_dpp v1, v0 row_ror:1 row_mask:0xf bank_mask:0xf
	s_and_saveexec_b64 s[8:9], vcc
	v_add_f32_e32 v0, v0, v1
	ds_write_b32 v79, v0 offset:34176
	s_or_b64 exec, exec, s[8:9]
	s_waitcnt lgkmcnt(0)
	v_mul_f32_e32 v94, v75, v73
	ds_read_b128 v[24:27], v80 offset:4096
	ds_read_b128 v[16:19], v80 offset:4352
	ds_read_b128 v[64:67], v80 offset:12288
	ds_read_b128 v[40:43], v80 offset:12544
	ds_read_b128 v[8:11], v80 offset:4608
	ds_read_b128 v[0:3], v80 offset:4864
	ds_read_b128 v[44:47], v80 offset:12800
	ds_read_b128 v[36:39], v80 offset:13056
	ds_read2_b32 v[72:73], v81 offset0:68 offset1:84
	ds_read_b32 v75, v79 offset:16640
	v_mul_f32 v60, v60, v94
	v_mul_f32 v61, v61, v94
	v_mul_f32 v52, v52, v94
	v_mul_f32 v53, v53, v94
	v_mul_f32 v95, v56, v94
	v_mul_f32 v96, v57, v94
	v_mul_f32 v32, v32, v94
	v_mul_f32 v33, v33, v94
	v_fma_f32 v56, v74, v48, v60
	v_fma_f32 v57, v74, v49, v61
	v_fma_f32 v83, v74, v83, v52
	v_fma_f32 v85, v74, v85, v53
	v_fma_f32 v88, v74, v88, v95
	v_fma_f32 v86, v74, v86, v96
	v_fma_f32 v90, v74, v90, v32
	v_fma_f32 v91, v74, v91, v33
	v_fma_f32 v28, v28, v56, v140
	v_fma_f32 v29, v29, v57, v140
	v_mul_f32 v62, v62, v94
	v_mul_f32 v63, v63, v94
	v_mul_f32 v54, v54, v94
	v_mul_f32 v55, v55, v94
	v_fma_f32 v20, v20, v83, v28
	v_fma_f32 v21, v21, v85, v29
	v_mul_f32 v97, v58, v94
	v_mul_f32 v98, v59, v94
	v_mul_f32 v34, v34, v94
	v_mul_f32 v35, v35, v94
	v_fma_f32 v12, v12, v88, v20
	v_fma_f32 v13, v13, v86, v21
	v_fma_f32 v58, v74, v50, v62
	v_fma_f32 v59, v74, v51, v63
	v_fma_f32 v87, v74, v87, v54
	v_fma_f32 v89, v74, v89, v55
	v_fma_f32 v4, v4, v90, v12
	v_fma_f32 v5, v5, v91, v13
	v_fma_f32 v84, v74, v84, v97
	v_fma_f32 v82, v74, v82, v98
	v_fma_f32 v92, v74, v92, v34
	v_fma_f32 v93, v74, v93, v35
	v_fma_f32 v30, v30, v58, v140
	v_fma_f32 v31, v31, v59, v140
	v_add_f32_e32 v4, v4, v5
	v_fma_f32 v22, v22, v87, v30
	v_fma_f32 v23, v23, v89, v31
	v_fma_f32 v14, v14, v84, v22
	v_fma_f32 v15, v15, v82, v23
	v_fma_f32 v6, v6, v92, v14
	v_fma_f32 v7, v7, v93, v15
	v_add_f32_e32 v5, v6, v7
	v_add_f32_e32 v4, v4, v5
	v_mov_b32_e32 v5, v140
	s_nop 0
	v_add_f32_dpp v4, v4, v4 row_ror:8 row_mask:0xf bank_mask:0xf bound_ctrl:1
	s_nop 1
	v_add_f32_dpp v4, v4, v4 row_ror:4 row_mask:0xf bank_mask:0xf bound_ctrl:1
	s_nop 1
	v_add_f32_dpp v4, v4, v4 row_ror:2 row_mask:0xf bank_mask:0xf bound_ctrl:1
	s_nop 1
	v_mov_b32_dpp v5, v4 row_ror:1 row_mask:0xf bank_mask:0xf
	s_and_saveexec_b64 s[8:9], vcc
	v_add_f32_e32 v4, v4, v5
	ds_write_b32 v79, v4 offset:34240
	s_or_b64 exec, exec, s[8:9]
	s_waitcnt lgkmcnt(0)
	v_mul_f32_e32 v94, v73, v75
	ds_read_b128 v[28:31], v80 offset:5120
	ds_read_b128 v[20:23], v80 offset:5376
	ds_read_b128 v[60:63], v80 offset:13312
	ds_read_b128 v[48:51], v80 offset:13568
	ds_read_b128 v[12:15], v80 offset:5632
	ds_read_b128 v[4:7], v80 offset:5888
	ds_read_b128 v[52:55], v80 offset:13824
	ds_read_b128 v[32:35], v80 offset:14080
	ds_read2_b32 v[74:75], v81 offset0:69 offset1:85
	ds_read_b32 v73, v79 offset:16704
	v_mul_f32 v64, v64, v94
	v_mul_f32 v65, v65, v94
	v_mul_f32 v40, v40, v94
	v_mul_f32 v41, v41, v94
	v_mul_f32 v44, v44, v94
	v_mul_f32 v45, v45, v94
	v_mul_f32 v95, v36, v94
	v_mul_f32 v96, v37, v94
	v_fma_f32 v36, v72, v56, v64
	v_fma_f32 v37, v72, v57, v65
	v_fma_f32 v83, v72, v83, v40
	v_fma_f32 v85, v72, v85, v41
	v_fma_f32 v88, v72, v88, v44
	v_fma_f32 v86, v72, v86, v45
	v_fma_f32 v90, v72, v90, v95
	v_fma_f32 v91, v72, v91, v96
	v_fma_f32 v24, v24, v36, v140
	v_fma_f32 v25, v25, v37, v140
	v_mul_f32 v66, v66, v94
	v_mul_f32 v67, v67, v94
	v_mul_f32 v42, v42, v94
	v_mul_f32 v43, v43, v94
	v_fma_f32 v16, v16, v83, v24
	v_fma_f32 v17, v17, v85, v25
	v_mul_f32 v46, v46, v94
	v_mul_f32 v47, v47, v94
	v_mul_f32 v97, v38, v94
	v_mul_f32 v94, v39, v94
	v_fma_f32 v8, v8, v88, v16
	v_fma_f32 v9, v9, v86, v17
	v_fma_f32 v38, v72, v58, v66
	v_fma_f32 v39, v72, v59, v67
	v_fma_f32 v87, v72, v87, v42
	v_fma_f32 v89, v72, v89, v43
	v_fma_f32 v0, v0, v90, v8
	v_fma_f32 v1, v1, v91, v9
	v_fma_f32 v84, v72, v84, v46
	v_fma_f32 v82, v72, v82, v47
	v_fma_f32 v92, v72, v92, v97
	v_fma_f32 v93, v72, v93, v94
	v_fma_f32 v26, v26, v38, v140
	v_fma_f32 v27, v27, v39, v140
	v_add_f32_e32 v0, v0, v1
	v_fma_f32 v18, v18, v87, v26
	v_fma_f32 v19, v19, v89, v27
	v_fma_f32 v10, v10, v84, v18
	v_fma_f32 v11, v11, v82, v19
	v_fma_f32 v2, v2, v92, v10
	v_fma_f32 v3, v3, v93, v11
	v_add_f32_e32 v1, v2, v3
	v_add_f32_e32 v0, v0, v1
	v_mov_b32_e32 v1, v140
	s_nop 0
	v_add_f32_dpp v0, v0, v0 row_ror:8 row_mask:0xf bank_mask:0xf bound_ctrl:1
	s_nop 1
	v_add_f32_dpp v0, v0, v0 row_ror:4 row_mask:0xf bank_mask:0xf bound_ctrl:1
	s_nop 1
	v_add_f32_dpp v0, v0, v0 row_ror:2 row_mask:0xf bank_mask:0xf bound_ctrl:1
	s_nop 1
	v_mov_b32_dpp v1, v0 row_ror:1 row_mask:0xf bank_mask:0xf
	s_and_saveexec_b64 s[8:9], vcc
	v_add_f32_e32 v0, v0, v1
	ds_write_b32 v79, v0 offset:34304
	s_or_b64 exec, exec, s[8:9]
	s_waitcnt lgkmcnt(0)
	v_mul_f32_e32 v75, v75, v73
	ds_read_b128 v[24:27], v80 offset:6144
	ds_read_b128 v[16:19], v80 offset:6400
	ds_read_b128 v[64:67], v80 offset:14336
	ds_read_b128 v[44:47], v80 offset:14592
	ds_read_b128 v[8:11], v80 offset:6656
	ds_read_b128 v[0:3], v80 offset:6912
	ds_read_b128 v[56:59], v80 offset:14848
	ds_read_b128 v[40:43], v80 offset:15104
	ds_read2_b32 v[72:73], v81 offset0:70 offset1:86
	ds_read_b32 v95, v79 offset:16768
	v_mul_f32 v60, v60, v75
	v_mul_f32 v61, v61, v75
	v_mul_f32 v94, v62, v75
	v_mul_f32 v96, v63, v75
	v_mul_f32 v48, v48, v75
	v_mul_f32 v49, v49, v75
	v_mul_f32 v52, v52, v75
	v_mul_f32 v53, v53, v75
	v_mul_f32 v32, v32, v75
	v_mul_f32 v33, v33, v75
	v_fma_f32 v62, v74, v36, v60
	v_fma_f32 v63, v74, v37, v61
	v_fma_f32 v83, v74, v83, v48
	v_fma_f32 v85, v74, v85, v49
	v_fma_f32 v88, v74, v88, v52
	v_fma_f32 v86, v74, v86, v53
	v_fma_f32 v90, v74, v90, v32
	v_fma_f32 v91, v74, v91, v33
	v_fma_f32 v28, v28, v62, v140
	v_fma_f32 v29, v29, v63, v140
	v_mul_f32 v50, v50, v75
	v_mul_f32 v51, v51, v75
	v_mul_f32 v54, v54, v75
	v_mul_f32 v55, v55, v75
	v_fma_f32 v20, v20, v83, v28
	v_fma_f32 v21, v21, v85, v29
	v_mul_f32 v34, v34, v75
	v_mul_f32 v35, v35, v75
	v_fma_f32 v75, v74, v38, v94
	v_fma_f32 v94, v74, v39, v96
	v_fma_f32 v12, v12, v88, v20
	v_fma_f32 v13, v13, v86, v21
	v_fma_f32 v87, v74, v87, v50
	v_fma_f32 v89, v74, v89, v51
	v_fma_f32 v84, v74, v84, v54
	v_fma_f32 v82, v74, v82, v55
	v_fma_f32 v4, v4, v90, v12
	v_fma_f32 v5, v5, v91, v13
	v_fma_f32 v92, v74, v92, v34
	v_fma_f32 v74, v74, v93, v35
	v_fma_f32 v30, v30, v75, v140
	v_fma_f32 v31, v31, v94, v140
	v_add_f32_e32 v4, v4, v5
	v_fma_f32 v22, v22, v87, v30
	v_fma_f32 v23, v23, v89, v31
	v_fma_f32 v14, v14, v84, v22
	v_fma_f32 v15, v15, v82, v23
	v_fma_f32 v6, v6, v92, v14
	v_fma_f32 v7, v7, v74, v15
	v_add_f32_e32 v5, v6, v7
	v_add_f32_e32 v4, v4, v5
	v_mov_b32_e32 v5, v140
	s_nop 0
	v_add_f32_dpp v4, v4, v4 row_ror:8 row_mask:0xf bank_mask:0xf bound_ctrl:1
	s_nop 1
	v_add_f32_dpp v4, v4, v4 row_ror:4 row_mask:0xf bank_mask:0xf bound_ctrl:1
	s_nop 1
	v_add_f32_dpp v4, v4, v4 row_ror:2 row_mask:0xf bank_mask:0xf bound_ctrl:1
	s_nop 1
	v_mov_b32_dpp v5, v4 row_ror:1 row_mask:0xf bank_mask:0xf
	s_and_saveexec_b64 s[8:9], vcc
	v_add_f32_e32 v4, v4, v5
	ds_write_b32 v79, v4 offset:34368
	s_or_b64 exec, exec, s[8:9]
	s_waitcnt lgkmcnt(0)
	v_mul_f32_e32 v93, v73, v95
	ds_read_b128 v[36:39], v80 offset:7168
	ds_read_b128 v[32:35], v80 offset:7424
	ds_read_b128 v[52:55], v80 offset:15360
	ds_read_b128 v[12:15], v80 offset:15616
	ds_read_b128 v[28:31], v80 offset:7680
	ds_read_b128 v[20:23], v80 offset:7936
	ds_read_b128 v[48:51], v80 offset:15872
	ds_read_b128 v[4:7], v80 offset:16128
	ds_read2_b32 v[60:61], v81 offset0:71 offset1:87
	ds_read_b32 v73, v79 offset:16832
	v_mul_f32 v44, v44, v93
	v_mul_f32 v45, v45, v93
	v_mul_f32 v56, v56, v93
	v_mul_f32 v57, v57, v93
	v_mul_f32 v64, v64, v93
	v_mul_f32 v65, v65, v93
	v_mul_f32 v46, v46, v93
	v_mul_f32 v47, v47, v93
	v_mul_f32 v58, v58, v93
	v_mul_f32 v59, v59, v93
	v_mul_f32 v80, v40, v93
	v_mul_f32 v81, v41, v93
	v_fma_f32 v40, v72, v62, v64
	v_fma_f32 v41, v72, v63, v65
	v_fma_f32 v44, v72, v83, v44
	v_fma_f32 v45, v72, v85, v45
	v_fma_f32 v56, v72, v88, v56
	v_fma_f32 v57, v72, v86, v57
	v_fma_f32 v62, v72, v90, v80
	v_fma_f32 v63, v72, v91, v81
	v_fma_f32 v24, v24, v40, v140
	v_fma_f32 v25, v25, v41, v140
	v_mul_f32 v66, v66, v93
	v_mul_f32 v67, v67, v93
	v_mul_f32 v95, v42, v93
	v_mul_f32 v93, v43, v93
	v_fma_f32 v16, v16, v44, v24
	v_fma_f32 v17, v17, v45, v25
	v_fma_f32 v42, v72, v75, v66
	v_fma_f32 v43, v72, v94, v67
	v_fma_f32 v46, v72, v87, v46
	v_fma_f32 v47, v72, v89, v47
	v_fma_f32 v8, v8, v56, v16
	v_fma_f32 v9, v9, v57, v17
	v_fma_f32 v58, v72, v84, v58
	v_fma_f32 v59, v72, v82, v59
	v_fma_f32 v64, v72, v92, v95
	v_fma_f32 v65, v72, v74, v93
	v_fma_f32 v0, v0, v62, v8
	v_fma_f32 v1, v1, v63, v9
	v_fma_f32 v26, v26, v42, v140
	v_fma_f32 v27, v27, v43, v140
	v_fma_f32 v18, v18, v46, v26
	v_fma_f32 v19, v19, v47, v27
	v_add_f32_e32 v0, v0, v1
	v_fma_f32 v10, v10, v58, v18
	v_fma_f32 v11, v11, v59, v19
	v_fma_f32 v2, v2, v64, v10
	v_fma_f32 v3, v3, v65, v11
	v_add_f32_e32 v1, v2, v3
	v_add_f32_e32 v0, v0, v1
	v_mov_b32_e32 v1, v140
	s_nop 0
	v_add_f32_dpp v0, v0, v0 row_ror:8 row_mask:0xf bank_mask:0xf bound_ctrl:1
	s_nop 1
	v_add_f32_dpp v0, v0, v0 row_ror:4 row_mask:0xf bank_mask:0xf bound_ctrl:1
	s_nop 1
	v_add_f32_dpp v0, v0, v0 row_ror:2 row_mask:0xf bank_mask:0xf bound_ctrl:1
	s_nop 1
	v_mov_b32_dpp v1, v0 row_ror:1 row_mask:0xf bank_mask:0xf
	s_and_saveexec_b64 s[8:9], vcc
	v_add_f32_e32 v0, v0, v1
	ds_write_b32 v79, v0 offset:34432
	s_or_b64 exec, exec, s[8:9]
	s_waitcnt lgkmcnt(0)
	v_mul_f32_e32 v0, v61, v73
	v_mul_f32 v1, v52, v0
	v_mul_f32 v9, v12, v0
	v_mul_f32 v11, v14, v0
	v_mul_f32 v12, v15, v0
	v_mul_f32 v16, v51, v0
	v_mul_f32 v17, v4, v0
	v_mul_f32 v2, v53, v0
	v_mul_f32 v3, v54, v0
	v_mul_f32 v8, v55, v0
	v_mul_f32 v10, v13, v0
	v_mul_f32 v13, v48, v0
	v_mul_f32 v14, v49, v0
	v_mul_f32 v15, v50, v0
	v_mul_f32 v18, v5, v0
	v_mul_f32 v19, v6, v0
	v_mul_f32 v24, v7, v0
	v_fma_f32 v0, v60, v40, v1
	v_fma_f32 v1, v60, v41, v2
	v_fma_f32 v6, v60, v46, v11
	v_fma_f32 v7, v60, v47, v12
	v_fma_f32 v11, v60, v59, v16
	v_fma_f32 v12, v60, v62, v17
	v_fma_f32 v16, v36, v0, v140
	v_fma_f32 v17, v37, v1, v140
	v_fma_f32 v2, v60, v42, v3
	v_fma_f32 v3, v60, v43, v8
	v_fma_f32 v4, v60, v44, v9
	v_fma_f32 v5, v60, v45, v10
	v_fma_f32 v8, v60, v56, v13
	v_fma_f32 v9, v60, v57, v14
	v_fma_f32 v13, v60, v63, v18
	v_fma_f32 v14, v60, v64, v19
	v_fma_f32 v18, v38, v2, v140
	v_fma_f32 v19, v39, v3, v140
	v_fma_f32 v16, v32, v4, v16
	v_fma_f32 v17, v33, v5, v17
	v_fma_f32 v10, v60, v58, v15
	v_fma_f32 v15, v60, v65, v24
	v_fma_f32 v18, v34, v6, v18
	v_fma_f32 v19, v35, v7, v19
	v_fma_f32 v16, v28, v8, v16
	v_fma_f32 v17, v29, v9, v17
	v_fma_f32 v18, v30, v10, v18
	v_fma_f32 v19, v31, v11, v19
	v_fma_f32 v16, v20, v12, v16
	v_fma_f32 v17, v21, v13, v17
	v_fma_f32 v18, v22, v14, v18
	v_fma_f32 v19, v23, v15, v19
	v_add_f32_e32 v16, v16, v17
	v_add_f32_e32 v17, v18, v19
	v_add_f32_e32 v16, v16, v17
	v_mov_b32_e32 v17, v140
	s_nop 0
	v_add_f32_dpp v16, v16, v16 row_ror:8 row_mask:0xf bank_mask:0xf bound_ctrl:1
	s_nop 1
	v_add_f32_dpp v16, v16, v16 row_ror:4 row_mask:0xf bank_mask:0xf bound_ctrl:1
	s_nop 1
	v_add_f32_dpp v16, v16, v16 row_ror:2 row_mask:0xf bank_mask:0xf bound_ctrl:1
	s_nop 1
	v_mov_b32_dpp v17, v16 row_ror:1 row_mask:0xf bank_mask:0xf
	s_and_saveexec_b64 s[8:9], vcc
	v_add_f32_e32 v16, v16, v17
	ds_write_b32 v79, v16 offset:34496
	s_or_b64 exec, exec, s[8:9]
	s_mov_b64 s[8:9], -1
	s_and_b64 vcc, exec, s[50:51]
	s_waitcnt lgkmcnt(0)
	s_barrier
	s_cbranch_vccnz .LBB0_1670
	s_andn2_b64 vcc, exec, s[8:9]
	s_cbranch_vccz .LBB0_1673

.LBB0_1676:
	v_cmp_gt_u32_e32 vcc, 16, v76
	s_and_saveexec_b64 s[8:9], vcc
	s_cbranch_execz .LBB0_1678
	s_load_dwordx2 s[22:23], s[0:1], 0x158
	s_lshl_b64 s[40:41], s[46:47], 10
	v_mov_b32_e32 v69, v140
	s_waitcnt lgkmcnt(0)
	s_add_u32 s22, s22, s40
	s_addc_u32 s23, s23, s41
	v_lshl_add_u64 v[16:17], v[68:69], 2, s[22:23]
	s_mov_b64 s[22:23], 0xd024040
	v_lshl_add_u64 v[18:19], v[16:17], 0, s[22:23]
	v_add_co_u32_e32 v16, vcc, 0xd024000, v16
	s_nop 1
	v_addc_co_u32_e32 v17, vcc, 0, v17, vcc
	global_store_dwordx4 v[16:17], v[0:3], off offset:64
	global_store_dwordx4 v[18:19], v[4:7], off offset:256
	s_nop 1
	global_store_dwordx4 v[18:19], v[8:11], off offset:512
	s_nop 1
	global_store_dwordx4 v[18:19], v[12:15], off offset:768

.LBB0_1681:
	s_load_dwordx2 s[8:9], s[0:1], 0x158
	s_movk_i32 s4, 0x110
	v_mad_u32_u24 v16, v77, s4, v79
	v_add_u32_e32 v17, 0x8c00, v16
	s_lshl_b64 s[22:23], s[46:47], 18
	s_ashr_i32 s55, s54, 31
	ds_write2_b32 v17, v0, v1 offset0:40 offset1:57
	ds_write2_b32 v17, v2, v3 offset0:74 offset1:91
	v_add_u32_e32 v0, 0x9c00, v16
	ds_write2_b32 v0, v4, v5 offset0:104 offset1:121
	ds_write2_b32 v0, v6, v7 offset0:138 offset1:155
	v_add_u32_e32 v0, 0xac00, v16
	s_waitcnt lgkmcnt(0)
	s_add_u32 s4, s8, s22
	ds_write2_b32 v0, v8, v9 offset0:168 offset1:185
	ds_write2_b32 v0, v10, v11 offset0:202 offset1:219
	v_add_u32_e32 v0, 0xbc00, v16
	s_addc_u32 s15, s9, s23
	s_lshl_b64 s[8:9], s[54:55], 2
	ds_write2_b32 v0, v12, v13 offset0:232 offset1:249
	v_add_u32_e32 v0, 0xc000, v16
	s_add_u32 s8, s4, s8
	ds_write2_b32 v0, v14, v15 offset0:10 offset1:27
	s_addc_u32 s9, s15, s9
	v_and_b32_e32 v0, 48, v78
	v_mov_b32_e32 v1, v140
	s_movk_i32 s4, 0x44
	v_lshl_add_u64 v[2:3], s[8:9], 0, v[0:1]
	v_mad_u64_u32 v[8:9], s[8:9], v70, s4, v[0:1]
	v_add_u32_e32 v4, 0x8ca0, v8
	v_lshlrev_b64 v[0:1], 10, v[70:71]
	s_waitcnt lgkmcnt(0)
	s_barrier
	v_add_u32_e32 v5, 0x8ca8, v8
	v_lshl_add_u64 v[10:11], v[2:3], 0, v[0:1]
	ds_read2_b32 v[0:1], v4 offset1:1
	ds_read2_b32 v[2:3], v5 offset1:1
	v_add_u32_e32 v4, 0x9da0, v8
	v_add_u32_e32 v6, 0x9da8, v8
	s_mov_b32 s4, 0x5024000
	ds_read2_b32 v[4:5], v4 offset1:1
	ds_read2_b32 v[6:7], v6 offset1:1
	v_add_co_u32_e32 v12, vcc, s4, v10
	s_mov_b32 s4, 0x5034000
	s_nop 0
	v_addc_co_u32_e32 v13, vcc, 0, v11, vcc
	s_waitcnt lgkmcnt(2)
	global_store_dwordx4 v[12:13], v[0:3], off offset:64
	s_nop 1
	v_add_co_u32_e32 v0, vcc, s4, v10
	v_add_u32_e32 v2, 0xaea8, v8
	s_nop 0
	v_addc_co_u32_e32 v1, vcc, 0, v11, vcc
	s_waitcnt lgkmcnt(0)
	global_store_dwordx4 v[0:1], v[4:7], off offset:64
	s_nop 1
	v_add_u32_e32 v0, 0xaea0, v8
	ds_read2_b32 v[0:1], v0 offset1:1
	ds_read2_b32 v[2:3], v2 offset1:1
	v_add_u32_e32 v4, 0xbfa0, v8
	v_add_u32_e32 v6, 0xbfa8, v8
	ds_read2_b32 v[4:5], v4 offset1:1
	ds_read2_b32 v[6:7], v6 offset1:1
	v_add_co_u32_e32 v12, vcc, 0x5044000, v10
	s_nop 1
	v_addc_co_u32_e32 v13, vcc, 0, v11, vcc
	s_waitcnt lgkmcnt(2)
	global_store_dwordx4 v[12:13], v[0:3], off offset:64
	s_nop 1
	v_add_co_u32_e32 v0, vcc, 0x5054000, v10
	s_nop 1
	v_addc_co_u32_e32 v1, vcc, 0, v11, vcc
	s_waitcnt lgkmcnt(0)
	global_store_dwordx4 v[0:1], v[4:7], off offset:64
	s_branch .LBB0_1570
